# peephole: adjacent 32-bit register move pairs (epilogue prefetch copies, zero fills) merged into 64-bit moves
# speedup vs baseline: 1.0151x; 1.0021x over previous
; __device__ __forceinline__ f32x4 cv_bf4(const u32x2 w) { return (f32x4){bflo(w.x), bfhi(w.x), bflo(w.y), bfhi(w.y)}; }
; __device__ __forceinline__ void scan_finish(const ScanPtrs& Q, int J, int ci, unsigned char* buf, int ltid, const LStage& L, int toff) {
;     ...
;     if (tt < jb.nsteps) {
;         const int tok = jb.tok0 + tt; const int tseq = jb.is_s ? tt : ci * SC_CH + tt;
;         const int gc = jb.h * 64 + c;
;         f32x4 r = cv_bf4(L.r), k0 = cv_bf4(L.k), v = cv_bf4(L.v), rp, kp, vp;
;         if (tseq > 0) { rp = cv_bf4(L.rp); kp = cv_bf4(L.kp); vp = cv_bf4(L.vp); }
;         else if (jb.is_s) { rp = L.fr; kp = L.fk; vp = L.fv; }
;         else { rp = (f32x4){0.f, 0.f, 0.f, 0.f}; kp = rp; vp = rp; }
.LBB0_444:
	s_or_b64 exec, exec, s[72:73]
	v_cndmask_b32_e64 v18, 64, 1, s[14:15]
	s_and_saveexec_b64 s[20:21], s[70:71]
	s_cbranch_execz .LBB0_410
	v_cmp_gt_i32_e32 vcc, v102, v94
	v_mov_b64_e32 v[44:45], 0
	v_mov_b64_e32 v[46:47], 0
	v_mov_b32_e32 v48, 0
	v_mov_b32_e32 v50, 0
	v_mov_b32_e32 v49, 0
	v_mov_b32_e32 v51, 0
	v_mov_b32_e32 v40, 0
	v_mov_b32_e32 v41, 0
	v_mov_b32_e32 v42, 0
	v_mov_b32_e32 v43, 0
	s_and_saveexec_b64 s[14:15], vcc
	s_cbranch_execz .LBB0_447
	s_waitcnt vmcnt(4)
	v_lshlrev_b32_e32 v40, 16, v54
	v_and_b32_e32 v41, 0xffff0000, v54
	v_lshlrev_b32_e32 v42, 16, v55
	v_and_b32_e32 v43, 0xffff0000, v55
	s_waitcnt vmcnt(3)
	v_lshlrev_b32_e32 v48, 16, v58
	v_and_b32_e32 v50, 0xffff0000, v58
	v_lshlrev_b32_e32 v49, 16, v59
	v_and_b32_e32 v51, 0xffff0000, v59
	s_waitcnt vmcnt(2)
	v_lshlrev_b32_e32 v44, 16, v66
	v_and_b32_e32 v45, 0xffff0000, v66
	v_lshlrev_b32_e32 v46, 16, v67
	v_and_b32_e32 v47, 0xffff0000, v67

; __device__ __forceinline__ f32x4 cv_bf4(const u32x2 w) { return (f32x4){bflo(w.x), bfhi(w.x), bflo(w.y), bfhi(w.y)}; }
; __device__ __forceinline__ void scan_finish(const ScanPtrs& Q, int J, int ci, unsigned char* buf, int ltid, const LStage& L, int toff) {
;     ...
;     if (tt < jb.nsteps) {
;         const int tok = jb.tok0 + tt; const int tseq = jb.is_s ? tt : ci * SC_CH + tt;
;         const int gc = jb.h * 64 + c;
;         f32x4 r = cv_bf4(L.r), k0 = cv_bf4(L.k), v = cv_bf4(L.v), rp, kp, vp;
;         if (tseq > 0) { rp = cv_bf4(L.rp); kp = cv_bf4(L.kp); vp = cv_bf4(L.vp); }
;         else if (jb.is_s) { rp = L.fr; kp = L.fk; vp = L.fv; }
;         else { rp = (f32x4){0.f, 0.f, 0.f, 0.f}; kp = rp; vp = rp; }
.LBB0_492:
	s_or_b64 exec, exec, s[74:75]
	s_nor_b64 s[8:9], s[16:17], s[12:13]
	v_cndmask_b32_e64 v18, 64, 1, s[16:17]
	s_and_saveexec_b64 s[22:23], s[8:9]
	s_cbranch_execz .LBB0_500
	v_cmp_gt_i32_e32 vcc, v120, v104
	s_andn2_b64 s[100:101], exec, vcc
	s_cbranch_scc0 .Lzs_0
	v_mov_b64_e32 v[48:49], 0
	v_mov_b64_e32 v[50:51], 0
	v_mov_b32_e32 v52, 0
	v_mov_b32_e32 v92, 0
	v_mov_b32_e32 v53, 0
	v_mov_b32_e32 v93, 0
	v_mov_b32_e32 v44, 0
	v_mov_b32_e32 v45, 0
	v_mov_b32_e32 v46, 0
	v_mov_b32_e32 v47, 0

; #define PG8_STAGE(bufoff, gbase, voff) do { _Pragma("unroll") for (int _i = 0; _i < 2; ++_i) \
;         __builtin_amdgcn_global_load_lds((const unsigned*)((const char*)(gbase) + (voff)[_i]), (LAS unsigned*)(lds + (bufoff) + ldsw + _i * 8192), 16, 0, 0); } while (0)
; #define PG8_LDA(dst, b, h) do { _Pragma("unroll") for (int m = 0; m < 4; ++m) _Pragma("unroll") for (int k = 0; k < 2; ++k) dst[m][k] = *(const LAS bf16x8*)(lds + PG8_SA(b, h) + aoff + m * 2048 + k * 1024); } while (0)
; #define PG8_LDB(dst, b, h) do { _Pragma("unroll") for (int n = 0; n < 2; ++n) _Pragma("unroll") for (int k = 0; k < 2; ++k) dst[n][k] = *(const LAS bf16x8*)(lds + PG8_SB(b, h) + boff + n * 2048 + k * 1024); } while (0)
; #define PG8_MMA(ai, bj, At, Bt) do { __builtin_amdgcn_s_setprio(1); _Pragma("unroll") for (int m = 0; m < 4; ++m) _Pragma("unroll") for (int n = 0; n < 2; ++n) _Pragma("unroll") for (int k = 0; k < 2; ++k) \
;         acc[ai][bj][m][n] = __builtin_amdgcn_mfma_f32_16x16x32_bf16(Bt[n][k], At[m][k], acc[ai][bj][m][n], 0, 0, 0); __builtin_amdgcn_s_setprio(0); } while (0)
; #define PG8_WAIT_L(n) asm volatile("s_waitcnt lgkmcnt(" #n ")" ::: "memory")
; #define PG8_BAR __builtin_amdgcn_s_barrier()
; #define PG8_SCHED __builtin_amdgcn_sched_barrier(0)
;     ...
;             PG8_LDB(B0, 0, 0); PG8_SCHED; PG8_LDA(At, 0, 0); PG8_STAGE(PG8_SA(1, 1), a1 + hA, voffA);
;             PG8_WAIT_L(8); PG8_BAR; PG8_WAIT_L(0); PG8_MMA(0, 0, At, B0); PG8_BAR; PG8_SCHED;
;             PG8_LDB(B1, 0, 1); PG8_STAGE(PG8_SB(0, 0), b2, voffB);
;             PG8_BAR; PG8_WAIT_L(0); PG8_MMA(0, 1, At, B1); PG8_BAR;
;             PG8_LDA(At, 0, 1); PG8_STAGE(PG8_SA(0, 0), a2, voffA);
;             PG8_BAR; PG8_WAIT_L(0); PG8_MMA(1, 0, At, B0); PG8_BAR; PG8_SCHED;
.LBB0_627:
	ds_read_b128 v[146:149], v157
	ds_read_b128 v[150:153], v157 offset:1024
	ds_read_b128 v[160:163], v157 offset:2048
	ds_read_b128 v[170:173], v157 offset:3072
	s_add_u32 s12, s14, 0x100
	s_addc_u32 s13, s15, 0
	s_cmp_eq_u32 s42, 4
	s_cselect_b32 s19, s31, s13
	s_cselect_b32 s18, s30, s12
	s_cselect_b32 s17, s8, s33
	s_cselect_b32 s16, s9, s29
	v_lshl_add_u64 v[164:165], s[14:15], 0, v[138:139]
	s_add_i32 m0, s39, 0xc000
	ds_read_b128 v[174:177], v158
	ds_read_b128 v[178:181], v158 offset:1024
	ds_read_b128 v[182:185], v158 offset:2048
	ds_read_b128 v[186:189], v158 offset:3072
	ds_read_b128 v[190:193], v158 offset:4096
	ds_read_b128 v[194:197], v158 offset:5120
	ds_read_b128 v[198:201], v158 offset:6144
	ds_read_b128 v[202:205], v158 offset:7168
	global_load_lds_dwordx4 v[164:165], off
	v_lshl_add_u64 v[164:165], s[14:15], 0, v[136:137]
	s_add_i32 m0, s39, 0xe000
	s_nop 0
	global_load_lds_dwordx4 v[164:165], off
	s_waitcnt lgkmcnt(8)
	s_barrier
	s_waitcnt lgkmcnt(0)
	s_setprio 1
	s_waitcnt lgkmcnt(0)
	v_mfma_f32_16x16x32_bf16 v[124:127], v[146:149], v[174:177], v[124:127]
	v_mfma_f32_16x16x32_bf16 v[120:123], v[160:163], v[174:177], v[120:123]
	v_mfma_f32_16x16x32_bf16 v[108:111], v[146:149], v[182:185], v[108:111]
	v_mfma_f32_16x16x32_bf16 v[104:107], v[160:163], v[182:185], v[104:107]
	v_mfma_f32_16x16x32_bf16 v[92:95], v[146:149], v[190:193], v[92:95]
	v_mfma_f32_16x16x32_bf16 v[88:91], v[160:163], v[190:193], v[88:91]
	v_mfma_f32_16x16x32_bf16 v[76:79], v[146:149], v[198:201], v[76:79]
	v_mfma_f32_16x16x32_bf16 v[72:75], v[160:163], v[198:201], v[72:75]
	v_mfma_f32_16x16x32_bf16 v[124:127], v[150:153], v[178:181], v[124:127]
	v_mfma_f32_16x16x32_bf16 v[120:123], v[170:173], v[178:181], v[120:123]
	v_mfma_f32_16x16x32_bf16 v[108:111], v[150:153], v[186:189], v[108:111]
	v_mfma_f32_16x16x32_bf16 v[104:107], v[170:173], v[186:189], v[104:107]
	v_mfma_f32_16x16x32_bf16 v[92:95], v[150:153], v[194:197], v[92:95]
	v_mfma_f32_16x16x32_bf16 v[88:91], v[170:173], v[194:197], v[88:91]
	v_mfma_f32_16x16x32_bf16 v[76:79], v[150:153], v[202:205], v[76:79]
	v_mfma_f32_16x16x32_bf16 v[72:75], v[170:173], v[202:205], v[72:75]
	s_setprio 0
	s_barrier
	s_add_i32 s14, s59, s37
	v_lshl_add_u64 v[164:165], s[16:17], 0, v[132:133]
	s_mov_b32 m0, s14
	ds_read_b128 v[206:209], v159
	ds_read_b128 v[210:213], v159 offset:1024
	ds_read_b128 v[214:217], v159 offset:2048
	ds_read_b128 v[218:221], v159 offset:3072
	global_load_lds_dwordx4 v[164:165], off
	v_lshl_add_u64 v[222:223], s[16:17], 0, v[128:129]
	s_add_i32 m0, s14, 0x2000
	s_nop 0
	global_load_lds_dwordx4 v[222:223], off
	s_barrier
	s_waitcnt lgkmcnt(0)
	s_setprio 1
	s_waitcnt lgkmcnt(0)
	v_mfma_f32_16x16x32_bf16 v[116:119], v[206:209], v[174:177], v[116:119]
	v_mfma_f32_16x16x32_bf16 v[112:115], v[214:217], v[174:177], v[112:115]
	v_mfma_f32_16x16x32_bf16 v[100:103], v[206:209], v[182:185], v[100:103]
	v_mfma_f32_16x16x32_bf16 v[96:99], v[214:217], v[182:185], v[96:99]
	v_mfma_f32_16x16x32_bf16 v[84:87], v[206:209], v[190:193], v[84:87]
	v_mfma_f32_16x16x32_bf16 v[80:83], v[214:217], v[190:193], v[80:83]
	v_mfma_f32_16x16x32_bf16 v[68:71], v[206:209], v[198:201], v[68:71]
	v_mfma_f32_16x16x32_bf16 v[64:67], v[214:217], v[198:201], v[64:67]
	v_mfma_f32_16x16x32_bf16 v[116:119], v[210:213], v[178:181], v[116:119]
	v_mfma_f32_16x16x32_bf16 v[112:115], v[218:221], v[178:181], v[112:115]
	v_mfma_f32_16x16x32_bf16 v[100:103], v[210:213], v[186:189], v[100:103]
	v_mfma_f32_16x16x32_bf16 v[96:99], v[218:221], v[186:189], v[96:99]
	v_mfma_f32_16x16x32_bf16 v[84:87], v[210:213], v[194:197], v[84:87]
	v_mfma_f32_16x16x32_bf16 v[80:83], v[218:221], v[194:197], v[80:83]
	v_mfma_f32_16x16x32_bf16 v[68:71], v[210:213], v[202:205], v[68:71]
	v_mfma_f32_16x16x32_bf16 v[64:67], v[218:221], v[202:205], v[64:67]
	s_setprio 0
	s_mov_b32 m0, s39
	v_lshl_add_u64 v[224:225], s[18:19], 0, v[134:135]
	s_barrier
	ds_read_b128 v[174:177], v158 offset:16384
	ds_read_b128 v[178:181], v158 offset:17408
	ds_read_b128 v[182:185], v158 offset:18432
	ds_read_b128 v[186:189], v158 offset:19456
	ds_read_b128 v[190:193], v158 offset:20480
	ds_read_b128 v[194:197], v158 offset:21504
	ds_read_b128 v[198:201], v158 offset:22528
	ds_read_b128 v[202:205], v158 offset:23552
	global_load_lds_dwordx4 v[224:225], off
	v_lshl_add_u64 v[226:227], s[18:19], 0, v[130:131]
	s_mov_b32 m0, s51
	s_nop 0
	global_load_lds_dwordx4 v[226:227], off
	s_barrier
	s_waitcnt lgkmcnt(0)
	s_setprio 1
	s_waitcnt lgkmcnt(0)
	v_mfma_f32_16x16x32_bf16 v[60:63], v[146:149], v[174:177], v[60:63]
	v_mfma_f32_16x16x32_bf16 v[56:59], v[160:163], v[174:177], v[56:59]
	v_mfma_f32_16x16x32_bf16 v[44:47], v[146:149], v[182:185], v[44:47]
	v_mfma_f32_16x16x32_bf16 v[40:43], v[160:163], v[182:185], v[40:43]
	v_mfma_f32_16x16x32_bf16 v[28:31], v[146:149], v[190:193], v[28:31]
	v_mfma_f32_16x16x32_bf16 v[24:27], v[160:163], v[190:193], v[24:27]
	v_mfma_f32_16x16x32_bf16 v[12:15], v[146:149], v[198:201], v[12:15]
	v_mfma_f32_16x16x32_bf16 v[8:11], v[160:163], v[198:201], v[8:11]
	v_mfma_f32_16x16x32_bf16 v[60:63], v[150:153], v[178:181], v[60:63]
	v_mfma_f32_16x16x32_bf16 v[56:59], v[170:173], v[178:181], v[56:59]
	v_mfma_f32_16x16x32_bf16 v[44:47], v[150:153], v[186:189], v[44:47]
	v_mfma_f32_16x16x32_bf16 v[40:43], v[170:173], v[186:189], v[40:43]
	v_mfma_f32_16x16x32_bf16 v[28:31], v[150:153], v[194:197], v[28:31]
	v_mfma_f32_16x16x32_bf16 v[24:27], v[170:173], v[194:197], v[24:27]
	v_mfma_f32_16x16x32_bf16 v[12:15], v[150:153], v[202:205], v[12:15]
	v_mfma_f32_16x16x32_bf16 v[8:11], v[170:173], v[202:205], v[8:11]
	s_setprio 0
	s_barrier
; #define PG8_STAGE(bufoff, gbase, voff) do { _Pragma("unroll") for (int _i = 0; _i < 2; ++_i) \
;         __builtin_amdgcn_global_load_lds((const unsigned*)((const char*)(gbase) + (voff)[_i]), (LAS unsigned*)(lds + (bufoff) + ldsw + _i * 8192), 16, 0, 0); } while (0)
; #define PG8_LDA(dst, b, h) do { _Pragma("unroll") for (int m = 0; m < 4; ++m) _Pragma("unroll") for (int k = 0; k < 2; ++k) dst[m][k] = *(const LAS bf16x8*)(lds + PG8_SA(b, h) + aoff + m * 2048 + k * 1024); } while (0)
; #define PG8_LDB(dst, b, h) do { _Pragma("unroll") for (int n = 0; n < 2; ++n) _Pragma("unroll") for (int k = 0; k < 2; ++k) dst[n][k] = *(const LAS bf16x8*)(lds + PG8_SB(b, h) + boff + n * 2048 + k * 1024); } while (0)
; #define PG8_MMA(ai, bj, At, Bt) do { __builtin_amdgcn_s_setprio(1); _Pragma("unroll") for (int m = 0; m < 4; ++m) _Pragma("unroll") for (int n = 0; n < 2; ++n) _Pragma("unroll") for (int k = 0; k < 2; ++k) \
;         acc[ai][bj][m][n] = __builtin_amdgcn_mfma_f32_16x16x32_bf16(Bt[n][k], At[m][k], acc[ai][bj][m][n], 0, 0, 0); __builtin_amdgcn_s_setprio(0); } while (0)
; #define PG8_WAIT_V(n) asm volatile("s_waitcnt vmcnt(" #n ")" ::: "memory")
; #define PG8_WAIT_L(n) asm volatile("s_waitcnt lgkmcnt(" #n ")" ::: "memory")
; #define PG8_BAR __builtin_amdgcn_s_barrier()
; #define PG8_SCHED __builtin_amdgcn_sched_barrier(0)
;     ...
;             PG8_STAGE(PG8_SB(0, 1), b2 + hB, voffB);
;             PG8_WAIT_V(6); PG8_BAR; PG8_MMA(1, 1, At, B1); PG8_BAR;
;             PG8_LDB(B0, 1, 0); PG8_SCHED; PG8_LDA(At, 1, 0); PG8_STAGE(PG8_SA(0, 1), a2 + hA, voffA);
;             PG8_WAIT_L(8); PG8_BAR; PG8_WAIT_L(0); PG8_MMA(0, 0, At, B0); PG8_BAR; PG8_SCHED;
;             PG8_LDB(B1, 1, 1); PG8_STAGE(PG8_SB(1, 0), b3, voffB);
;             PG8_BAR; PG8_WAIT_L(0); PG8_MMA(0, 1, At, B1); PG8_BAR;
;             PG8_LDA(At, 1, 1); PG8_STAGE(PG8_SA(1, 0), a3, voffA);
;             PG8_BAR; PG8_WAIT_L(0); PG8_MMA(1, 0, At, B0); PG8_BAR; PG8_SCHED;
	s_add_u32 s14, s16, 0x20000
	s_addc_u32 s15, s17, 0
	s_add_i32 s43, s60, s37
	v_lshl_add_u64 v[146:147], s[14:15], 0, v[132:133]
	s_mov_b32 m0, s43
	s_nop 0
	global_load_lds_dwordx4 v[146:147], off
	v_lshl_add_u64 v[146:147], s[14:15], 0, v[128:129]
	s_add_i32 m0, s43, 0x2000
	s_nop 0
	global_load_lds_dwordx4 v[146:147], off
	s_waitcnt vmcnt(6)
	s_barrier
	s_setprio 1
	v_mfma_f32_16x16x32_bf16 v[52:55], v[206:209], v[174:177], v[52:55]
	v_mfma_f32_16x16x32_bf16 v[48:51], v[214:217], v[174:177], v[48:51]
	v_mfma_f32_16x16x32_bf16 v[36:39], v[206:209], v[182:185], v[36:39]
	v_mfma_f32_16x16x32_bf16 v[32:35], v[214:217], v[182:185], v[32:35]
	v_mfma_f32_16x16x32_bf16 v[20:23], v[206:209], v[190:193], v[20:23]
	v_mfma_f32_16x16x32_bf16 v[16:19], v[214:217], v[190:193], v[16:19]
	v_mfma_f32_16x16x32_bf16 v[4:7], v[206:209], v[198:201], v[4:7]
	v_mfma_f32_16x16x32_bf16 v[0:3], v[214:217], v[198:201], v[0:3]
	v_mfma_f32_16x16x32_bf16 v[52:55], v[210:213], v[178:181], v[52:55]
	v_mfma_f32_16x16x32_bf16 v[48:51], v[218:221], v[178:181], v[48:51]
	v_mfma_f32_16x16x32_bf16 v[36:39], v[210:213], v[186:189], v[36:39]
	v_mfma_f32_16x16x32_bf16 v[32:35], v[218:221], v[186:189], v[32:35]
	v_mfma_f32_16x16x32_bf16 v[20:23], v[210:213], v[194:197], v[20:23]
	v_mfma_f32_16x16x32_bf16 v[16:19], v[218:221], v[194:197], v[16:19]
	v_mfma_f32_16x16x32_bf16 v[4:7], v[210:213], v[202:205], v[4:7]
	v_mfma_f32_16x16x32_bf16 v[0:3], v[218:221], v[202:205], v[0:3]
	s_setprio 0
	s_add_i32 s43, 0, 0x18000
	v_add_u32_e32 v170, s43, v155
	s_barrier
	ds_read_b128 v[146:149], v170
	ds_read_b128 v[150:153], v170 offset:1024
	ds_read_b128 v[160:163], v170 offset:2048
	ds_read_b128 v[170:173], v170 offset:3072
	s_add_u32 s14, s18, 0x110000
	s_addc_u32 s15, s19, 0
	s_mov_b32 m0, s53
	v_lshl_add_u64 v[206:207], s[14:15], 0, v[134:135]
	ds_read_b128 v[174:177], v158 offset:32768
	ds_read_b128 v[178:181], v158 offset:33792
	ds_read_b128 v[182:185], v158 offset:34816
	ds_read_b128 v[186:189], v158 offset:35840
	ds_read_b128 v[190:193], v158 offset:36864
	ds_read_b128 v[194:197], v158 offset:37888
	ds_read_b128 v[198:201], v158 offset:38912
	ds_read_b128 v[202:205], v158 offset:39936
	global_load_lds_dwordx4 v[206:207], off
	v_lshl_add_u64 v[206:207], s[14:15], 0, v[130:131]
	s_mov_b32 m0, s54
	s_nop 0
	global_load_lds_dwordx4 v[206:207], off
	s_waitcnt lgkmcnt(8)
	s_barrier
	s_waitcnt lgkmcnt(0)
	s_setprio 1
	s_waitcnt lgkmcnt(0)
	v_mfma_f32_16x16x32_bf16 v[124:127], v[146:149], v[174:177], v[124:127]
	v_mfma_f32_16x16x32_bf16 v[120:123], v[160:163], v[174:177], v[120:123]
	v_mfma_f32_16x16x32_bf16 v[108:111], v[146:149], v[182:185], v[108:111]
	v_mfma_f32_16x16x32_bf16 v[104:107], v[160:163], v[182:185], v[104:107]
	v_mfma_f32_16x16x32_bf16 v[92:95], v[146:149], v[190:193], v[92:95]
	v_mfma_f32_16x16x32_bf16 v[88:91], v[160:163], v[190:193], v[88:91]
	v_mfma_f32_16x16x32_bf16 v[76:79], v[146:149], v[198:201], v[76:79]
	v_mfma_f32_16x16x32_bf16 v[72:75], v[160:163], v[198:201], v[72:75]
	v_mfma_f32_16x16x32_bf16 v[124:127], v[150:153], v[178:181], v[124:127]
	v_mfma_f32_16x16x32_bf16 v[120:123], v[170:173], v[178:181], v[120:123]
	v_mfma_f32_16x16x32_bf16 v[108:111], v[150:153], v[186:189], v[108:111]
	v_mfma_f32_16x16x32_bf16 v[104:107], v[170:173], v[186:189], v[104:107]
	v_mfma_f32_16x16x32_bf16 v[92:95], v[150:153], v[194:197], v[92:95]
	v_mfma_f32_16x16x32_bf16 v[88:91], v[170:173], v[194:197], v[88:91]
	v_mfma_f32_16x16x32_bf16 v[76:79], v[150:153], v[202:205], v[76:79]
	v_mfma_f32_16x16x32_bf16 v[72:75], v[170:173], v[202:205], v[72:75]
	s_setprio 0
	s_barrier
	s_add_i32 s18, 0, 0x1c000
	s_add_i32 s14, s43, s37
	v_add_u32_e32 v218, s18, v155
	v_lshl_add_u64 v[164:165], v[164:165], 0, s[26:27]
	s_mov_b32 m0, s14
	ds_read_b128 v[206:209], v218
	ds_read_b128 v[210:213], v218 offset:1024
	ds_read_b128 v[214:217], v218 offset:2048
	ds_read_b128 v[218:221], v218 offset:3072
	global_load_lds_dwordx4 v[164:165], off
	v_lshl_add_u64 v[164:165], v[222:223], 0, s[26:27]
	s_add_i32 m0, s14, 0x2000
	s_nop 0
	global_load_lds_dwordx4 v[164:165], off
	s_barrier
	s_waitcnt lgkmcnt(0)
	s_setprio 1
	s_waitcnt lgkmcnt(0)
	v_mfma_f32_16x16x32_bf16 v[116:119], v[206:209], v[174:177], v[116:119]
	v_mfma_f32_16x16x32_bf16 v[112:115], v[214:217], v[174:177], v[112:115]
	v_mfma_f32_16x16x32_bf16 v[100:103], v[206:209], v[182:185], v[100:103]
	v_mfma_f32_16x16x32_bf16 v[96:99], v[214:217], v[182:185], v[96:99]
	v_mfma_f32_16x16x32_bf16 v[84:87], v[206:209], v[190:193], v[84:87]
	v_mfma_f32_16x16x32_bf16 v[80:83], v[214:217], v[190:193], v[80:83]
	v_mfma_f32_16x16x32_bf16 v[68:71], v[206:209], v[198:201], v[68:71]
	v_mfma_f32_16x16x32_bf16 v[64:67], v[214:217], v[198:201], v[64:67]
	v_mfma_f32_16x16x32_bf16 v[116:119], v[210:213], v[178:181], v[116:119]
	v_mfma_f32_16x16x32_bf16 v[112:115], v[218:221], v[178:181], v[112:115]
	v_mfma_f32_16x16x32_bf16 v[100:103], v[210:213], v[186:189], v[100:103]
	v_mfma_f32_16x16x32_bf16 v[96:99], v[218:221], v[186:189], v[96:99]
	v_mfma_f32_16x16x32_bf16 v[84:87], v[210:213], v[194:197], v[84:87]
	v_mfma_f32_16x16x32_bf16 v[80:83], v[218:221], v[194:197], v[80:83]
	v_mfma_f32_16x16x32_bf16 v[68:71], v[210:213], v[202:205], v[68:71]
	v_mfma_f32_16x16x32_bf16 v[64:67], v[218:221], v[202:205], v[64:67]
	s_setprio 0
	s_mov_b32 m0, s56
	v_lshl_add_u64 v[164:165], v[224:225], 0, s[26:27]
	s_barrier
	ds_read_b128 v[174:177], v158 offset:49152
	ds_read_b128 v[178:181], v158 offset:50176
	ds_read_b128 v[182:185], v158 offset:51200
	ds_read_b128 v[186:189], v158 offset:52224
	ds_read_b128 v[190:193], v158 offset:53248
	ds_read_b128 v[194:197], v158 offset:54272
	ds_read_b128 v[198:201], v158 offset:55296
	ds_read_b128 v[202:205], v158 offset:56320
	global_load_lds_dwordx4 v[164:165], off
	v_lshl_add_u64 v[164:165], v[226:227], 0, s[26:27]
	s_mov_b32 m0, s57
	s_nop 0
	global_load_lds_dwordx4 v[164:165], off
	s_barrier
; __device__ __forceinline__ float sigmoidf_(float x) { return 1.0f / (1.0f + __expf(-x)); }
; #define PG8_STAGE(bufoff, gbase, voff) do { _Pragma("unroll") for (int _i = 0; _i < 2; ++_i) \
;         __builtin_amdgcn_global_load_lds((const unsigned*)((const char*)(gbase) + (voff)[_i]), (LAS unsigned*)(lds + (bufoff) + ldsw + _i * 8192), 16, 0, 0); } while (0)
; #define PG8_MMA(ai, bj, At, Bt) do { __builtin_amdgcn_s_setprio(1); _Pragma("unroll") for (int m = 0; m < 4; ++m) _Pragma("unroll") for (int n = 0; n < 2; ++n) _Pragma("unroll") for (int k = 0; k < 2; ++k) \
;         acc[ai][bj][m][n] = __builtin_amdgcn_mfma_f32_16x16x32_bf16(Bt[n][k], At[m][k], acc[ai][bj][m][n], 0, 0, 0); __builtin_amdgcn_s_setprio(0); } while (0)
; #define PG8_WAIT_V(n) asm volatile("s_waitcnt vmcnt(" #n ")" ::: "memory")
; #define PG8_WAIT_L(n) asm volatile("s_waitcnt lgkmcnt(" #n ")" ::: "memory")
; #define PG8_BAR __builtin_amdgcn_s_barrier()
; #define PG8_SCHED __builtin_amdgcn_sched_barrier(0)
; __device__ __forceinline__ void unpack8(const u32x4 w, f32x4& v0, f32x4& v1) { v0 = (f32x4){bflo(w.x), bfhi(w.x), bflo(w.y), bfhi(w.y)}; v1 = (f32x4){bflo(w.z), bfhi(w.z), bflo(w.w), bfhi(w.w)}; }
;     ...
;             PG8_BAR; PG8_WAIT_L(0); PG8_MMA(1, 0, At, B0); PG8_BAR; PG8_SCHED;
;             PG8_STAGE(PG8_SB(1, 1), b3 + hB, voffB);
;             PG8_WAIT_V(6); PG8_BAR; PG8_MMA(1, 1, At, B1); PG8_BAR;
;     __device__ __forceinline__ void operator()(const f32x4 (&acc)[2][2][4][2], const Unit& u, int wr, int wc, int fr, int fq) const {
;     ...
; #pragma unroll
;         for (int ai = 0; ai < 2; ++ai)
; #pragma unroll
;             for (int m = 0; m < 4; ++m) {
;                 bf16_t* rowp = z + (size_t)(row0 + ai * 128 + m * 16) * DIN + col0;
; #pragma unroll
;                 for (int bj = 0; bj < 2; ++bj) {
;                     const u32x4 gw = *(const u32x4*)(rowp + (MODE == 0 ? O_GB : O_GA) + bj * 128);
;                     f32x4 g0, g1; unpack8(gw, g0, g1);
;                     f32x4 v0, v1;
; #pragma unroll
;                     for (int j = 0; j < 4; ++j) { v0[j] = sigmoidf_(g0[j]) * acc[ai][bj][m][0][j]; v1[j] = sigmoidf_(g1[j]) * acc[ai][bj][m][1][j]; }
	s_waitcnt lgkmcnt(0)
	s_setprio 1
	s_waitcnt lgkmcnt(0)
	v_mfma_f32_16x16x32_bf16 v[60:63], v[146:149], v[174:177], v[60:63]
	v_mfma_f32_16x16x32_bf16 v[56:59], v[160:163], v[174:177], v[56:59]
	v_mfma_f32_16x16x32_bf16 v[44:47], v[146:149], v[182:185], v[44:47]
	v_mfma_f32_16x16x32_bf16 v[40:43], v[160:163], v[182:185], v[40:43]
	v_mfma_f32_16x16x32_bf16 v[28:31], v[146:149], v[190:193], v[28:31]
	v_mfma_f32_16x16x32_bf16 v[24:27], v[160:163], v[190:193], v[24:27]
	v_mfma_f32_16x16x32_bf16 v[12:15], v[146:149], v[198:201], v[12:15]
	v_mfma_f32_16x16x32_bf16 v[8:11], v[160:163], v[198:201], v[8:11]
	v_mfma_f32_16x16x32_bf16 v[60:63], v[150:153], v[178:181], v[60:63]
	v_mfma_f32_16x16x32_bf16 v[56:59], v[170:173], v[178:181], v[56:59]
	v_mfma_f32_16x16x32_bf16 v[44:47], v[150:153], v[186:189], v[44:47]
	v_mfma_f32_16x16x32_bf16 v[40:43], v[170:173], v[186:189], v[40:43]
	v_mfma_f32_16x16x32_bf16 v[28:31], v[150:153], v[194:197], v[28:31]
	v_mfma_f32_16x16x32_bf16 v[24:27], v[170:173], v[194:197], v[24:27]
	v_mfma_f32_16x16x32_bf16 v[12:15], v[150:153], v[202:205], v[12:15]
	v_mfma_f32_16x16x32_bf16 v[8:11], v[170:173], v[202:205], v[8:11]
	s_setprio 0
	s_barrier
	s_add_u32 s14, s16, 0x20080
	s_addc_u32 s15, s17, 0
	s_add_i32 s16, s18, s37
	v_lshl_add_u64 v[146:147], s[14:15], 0, v[132:133]
	s_mov_b32 m0, s16
	s_nop 0
	global_load_lds_dwordx4 v[146:147], off
	v_lshl_add_u64 v[146:147], s[14:15], 0, v[128:129]
	s_add_i32 m0, s16, 0x2000
	s_nop 0
	global_load_lds_dwordx4 v[146:147], off
	s_waitcnt vmcnt(6)
	s_barrier
	s_setprio 1
	v_mfma_f32_16x16x32_bf16 v[52:55], v[206:209], v[174:177], v[52:55]
	v_mfma_f32_16x16x32_bf16 v[48:51], v[214:217], v[174:177], v[48:51]
	v_mfma_f32_16x16x32_bf16 v[36:39], v[206:209], v[182:185], v[36:39]
	v_mfma_f32_16x16x32_bf16 v[32:35], v[214:217], v[182:185], v[32:35]
	v_mfma_f32_16x16x32_bf16 v[20:23], v[206:209], v[190:193], v[20:23]
	v_mfma_f32_16x16x32_bf16 v[16:19], v[214:217], v[190:193], v[16:19]
	v_mfma_f32_16x16x32_bf16 v[4:7], v[206:209], v[198:201], v[4:7]
	v_mfma_f32_16x16x32_bf16 v[0:3], v[214:217], v[198:201], v[0:3]
	v_mfma_f32_16x16x32_bf16 v[52:55], v[210:213], v[178:181], v[52:55]
	v_mfma_f32_16x16x32_bf16 v[48:51], v[218:221], v[178:181], v[48:51]
	v_mfma_f32_16x16x32_bf16 v[36:39], v[210:213], v[186:189], v[36:39]
	v_mfma_f32_16x16x32_bf16 v[32:35], v[218:221], v[186:189], v[32:35]
	v_mfma_f32_16x16x32_bf16 v[20:23], v[210:213], v[194:197], v[20:23]
	v_mfma_f32_16x16x32_bf16 v[16:19], v[218:221], v[194:197], v[16:19]
	v_mfma_f32_16x16x32_bf16 v[4:7], v[210:213], v[202:205], v[4:7]
	v_mfma_f32_16x16x32_bf16 v[0:3], v[218:221], v[202:205], v[0:3]
	s_setprio 0
	s_add_i32 s42, s42, 2
	s_add_u32 s29, s29, 0x100
	s_addc_u32 s33, s33, 0
	s_cmp_gt_u32 s42, 5
	s_mov_b64 s[14:15], s[12:13]
	s_barrier
	s_cbranch_scc0 .LBB0_627
	v_lshl_or_b32 v148, s7, 8, v156
	v_lshl_add_u32 v160, s6, 8, v154
	v_ashrrev_i32_e32 v149, 31, v148
	v_mov_b64_e32 v[146:147], s[24:25]
	v_mad_i64_i32 v[150:151], s[6:7], v160, s61, v[146:147]
	v_lshlrev_b64 v[148:149], 1, v[148:149]
	v_lshl_add_u64 v[150:151], v[150:151], 0, v[148:149]
	v_add_co_u32_e32 v152, vcc, 0x1000, v150
	s_nop 1
	v_addc_co_u32_e32 v153, vcc, 0, v151, vcc
	v_subrev_u32_e32 v198, s24, v150
	v_add_u32_e32 v199, 0x1a00, v198
	global_load_dwordx4 v[200:203], v199, s[24:25]
	v_add_u32_e32 v199, 0x1b00, v198
	global_load_dwordx4 v[204:207], v199, s[24:25]
	v_add_u32_e32 v199, 0x23a00, v198
	global_load_dwordx4 v[208:211], v199, s[24:25]
	v_add_u32_e32 v199, 0x23b00, v198
	global_load_dwordx4 v[212:215], v199, s[24:25]
	v_add_u32_e32 v199, 0x45a00, v198
	global_load_dwordx4 v[216:219], v199, s[24:25]
	v_add_u32_e32 v199, 0x45b00, v198
	global_load_dwordx4 v[232:235], v199, s[24:25]
	s_waitcnt vmcnt(5)
	v_mov_b64_e32 v[162:163], v[200:201]
	v_mov_b64_e32 v[164:165], v[202:203]
	v_add_u32_e32 v199, 0x67a00, v198
	global_load_dwordx4 v[200:203], v199, s[24:25]
	s_mov_b32 s100, 0xbfb8aa3b
	v_lshlrev_b32_e32 v236, 16, v162
	v_and_b32_e32 v237, 0xffff0000, v162
	v_lshlrev_b32_e32 v238, 16, v164
	v_and_b32_e32 v239, 0xffff0000, v164
	v_lshlrev_b32_e32 v240, 16, v163
	v_and_b32_e32 v241, 0xffff0000, v163
	v_lshlrev_b32_e32 v242, 16, v165
	v_and_b32_e32 v243, 0xffff0000, v165
	v_pk_mul_f32 v[236:237], v[236:237], s[100:101] op_sel_hi:[1,0]
	v_pk_mul_f32 v[238:239], v[238:239], s[100:101] op_sel_hi:[1,0]
	v_pk_mul_f32 v[240:241], v[240:241], s[100:101] op_sel_hi:[1,0]
	v_pk_mul_f32 v[242:243], v[242:243], s[100:101] op_sel_hi:[1,0]
	v_exp_f32_e32 v236, v236
	v_exp_f32_e32 v237, v237
	v_exp_f32_e32 v238, v238
	v_exp_f32_e32 v239, v239
	v_exp_f32_e32 v240, v240
	v_exp_f32_e32 v241, v241
	v_exp_f32_e32 v242, v242
	v_exp_f32_e32 v243, v243
	s_nop 0
	v_pk_add_f32 v[236:237], v[236:237], 1.0 op_sel_hi:[1,0]
	v_pk_add_f32 v[238:239], v[238:239], 1.0 op_sel_hi:[1,0]
	v_pk_add_f32 v[240:241], v[240:241], 1.0 op_sel_hi:[1,0]
	v_pk_add_f32 v[242:243], v[242:243], 1.0 op_sel_hi:[1,0]
	v_rcp_f32_e32 v244, v236
	v_rcp_f32_e32 v245, v237
	v_rcp_f32_e32 v250, v238
	v_rcp_f32_e32 v251, v239
	v_pk_fma_f32 v[246:247], v[236:237], v[244:245], 1.0 op_sel_hi:[1,1,0] neg_lo:[1,0,0] neg_hi:[1,0,0]
	v_pk_fma_f32 v[252:253], v[238:239], v[250:251], 1.0 op_sel_hi:[1,1,0] neg_lo:[1,0,0] neg_hi:[1,0,0]
	v_pk_fma_f32 v[244:245], v[246:247], v[244:245], v[244:245]
	v_pk_fma_f32 v[250:251], v[252:253], v[250:251], v[250:251]
	v_pk_fma_f32 v[246:247], v[236:237], v[244:245], 1.0 op_sel_hi:[1,1,0] neg_lo:[1,0,0] neg_hi:[1,0,0]
	v_pk_fma_f32 v[252:253], v[238:239], v[250:251], 1.0 op_sel_hi:[1,1,0] neg_lo:[1,0,0] neg_hi:[1,0,0]
	v_pk_fma_f32 v[248:249], v[246:247], v[244:245], v[244:245]
; __device__ __forceinline__ float sigmoidf_(float x) { return 1.0f / (1.0f + __expf(-x)); }
; __device__ __forceinline__ u32x4 pack8(const f32x4 v0, const f32x4 v1) { u32x4 w; w.x = pk2(v0[0], v0[1]); w.y = pk2(v0[2], v0[3]); w.z = pk2(v1[0], v1[1]); w.w = pk2(v1[2], v1[3]); return w; }
; __device__ __forceinline__ void unpack8(const u32x4 w, f32x4& v0, f32x4& v1) { v0 = (f32x4){bflo(w.x), bfhi(w.x), bflo(w.y), bfhi(w.y)}; v1 = (f32x4){bflo(w.z), bfhi(w.z), bflo(w.w), bfhi(w.w)}; }
;     __device__ __forceinline__ void operator()(const f32x4 (&acc)[2][2][4][2], const Unit& u, int wr, int wc, int fr, int fq) const {
;     ...
; #pragma unroll
;         for (int ai = 0; ai < 2; ++ai)
; #pragma unroll
;             for (int m = 0; m < 4; ++m) {
;                 bf16_t* rowp = z + (size_t)(row0 + ai * 128 + m * 16) * DIN + col0;
; #pragma unroll
;                 for (int bj = 0; bj < 2; ++bj) {
;                     const u32x4 gw = *(const u32x4*)(rowp + (MODE == 0 ? O_GB : O_GA) + bj * 128);
;                     f32x4 g0, g1; unpack8(gw, g0, g1);
;                     f32x4 v0, v1;
; #pragma unroll
;                     for (int j = 0; j < 4; ++j) { v0[j] = sigmoidf_(g0[j]) * acc[ai][bj][m][0][j]; v1[j] = sigmoidf_(g1[j]) * acc[ai][bj][m][1][j]; }
;                     if (MODE == 1) { const u32x4 mw = *(const u32x4*)(rowp + bj * 128); f32x4 m0, m1; unpack8(mw, m0, m1); v0 += m0; v1 += m1; }
;                     *(u32x4*)(rowp + bj * 128) = pack8(v0, v1); }
	v_pk_fma_f32 v[254:255], v[252:253], v[250:251], v[250:251]
	v_pk_fma_f32 v[246:247], v[236:237], v[248:249], 1.0 op_sel_hi:[1,1,0] neg_lo:[1,0,0] neg_hi:[1,0,0]
	v_pk_fma_f32 v[252:253], v[238:239], v[254:255], 1.0 op_sel_hi:[1,1,0] neg_lo:[1,0,0] neg_hi:[1,0,0]
	v_pk_fma_f32 v[248:249], v[246:247], v[244:245], v[248:249]
	v_pk_fma_f32 v[254:255], v[252:253], v[250:251], v[254:255]
	v_div_fixup_f32 v236, v248, v236, 1.0
	v_div_fixup_f32 v237, v249, v237, 1.0
	v_div_fixup_f32 v238, v254, v238, 1.0
	v_div_fixup_f32 v239, v255, v239, 1.0
	v_rcp_f32_e32 v244, v240
	v_rcp_f32_e32 v245, v241
	v_rcp_f32_e32 v250, v242
	v_rcp_f32_e32 v251, v243
	v_pk_fma_f32 v[246:247], v[240:241], v[244:245], 1.0 op_sel_hi:[1,1,0] neg_lo:[1,0,0] neg_hi:[1,0,0]
	v_pk_fma_f32 v[252:253], v[242:243], v[250:251], 1.0 op_sel_hi:[1,1,0] neg_lo:[1,0,0] neg_hi:[1,0,0]
	v_pk_fma_f32 v[244:245], v[246:247], v[244:245], v[244:245]
	v_pk_fma_f32 v[250:251], v[252:253], v[250:251], v[250:251]
	v_pk_fma_f32 v[246:247], v[240:241], v[244:245], 1.0 op_sel_hi:[1,1,0] neg_lo:[1,0,0] neg_hi:[1,0,0]
	v_pk_fma_f32 v[252:253], v[242:243], v[250:251], 1.0 op_sel_hi:[1,1,0] neg_lo:[1,0,0] neg_hi:[1,0,0]
	v_pk_fma_f32 v[248:249], v[246:247], v[244:245], v[244:245]
	v_pk_fma_f32 v[254:255], v[252:253], v[250:251], v[250:251]
	v_pk_fma_f32 v[246:247], v[240:241], v[248:249], 1.0 op_sel_hi:[1,1,0] neg_lo:[1,0,0] neg_hi:[1,0,0]
	v_pk_fma_f32 v[252:253], v[242:243], v[254:255], 1.0 op_sel_hi:[1,1,0] neg_lo:[1,0,0] neg_hi:[1,0,0]
	v_pk_fma_f32 v[248:249], v[246:247], v[244:245], v[248:249]
	v_pk_fma_f32 v[254:255], v[252:253], v[250:251], v[254:255]
	v_div_fixup_f32 v240, v248, v240, 1.0
	v_div_fixup_f32 v241, v249, v241, 1.0
	v_div_fixup_f32 v242, v254, v242, 1.0
	v_div_fixup_f32 v243, v255, v243, 1.0
	s_mov_b64 vcc, s[12:13]
	s_mov_b64 vcc, s[14:15]
	v_mul_f32_e32 v124, v124, v236
	s_mov_b64 vcc, s[16:17]
	v_mul_f32_e32 v161, v120, v238
	v_mul_f32_e32 v120, v125, v237
	v_mul_f32_e32 v125, v121, v239
	s_mov_b64 vcc, s[18:19]
	v_mul_f32_e32 v126, v126, v240
	v_mul_f32_e32 v162, v122, v242
	v_mul_f32_e32 v121, v127, v241
	v_mul_f32_e32 v123, v123, v243
	v_cvt_pk_bf16_f32 v120, v124, v120
	v_cvt_pk_bf16_f32 v121, v126, v121
	v_cvt_pk_bf16_f32 v122, v161, v125
	v_cvt_pk_bf16_f32 v123, v162, v123
	s_mov_b64 s[16:17], s[34:35]
	global_store_dwordx4 v[150:151], v[120:123], off
	s_mov_b64 s[14:15], s[30:31]
	s_waitcnt vmcnt(6)
	v_mov_b64_e32 v[124:125], v[204:205]
	v_mov_b64_e32 v[126:127], v[206:207]
	v_add_u32_e32 v199, 0x67b00, v198
	global_load_dwordx4 v[204:207], v199, s[24:25]
	s_mov_b32 s100, 0xbfb8aa3b
	v_lshlrev_b32_e32 v236, 16, v124
	v_and_b32_e32 v237, 0xffff0000, v124
	v_lshlrev_b32_e32 v238, 16, v126
	v_and_b32_e32 v239, 0xffff0000, v126
	v_lshlrev_b32_e32 v240, 16, v125
	v_and_b32_e32 v241, 0xffff0000, v125
	v_lshlrev_b32_e32 v242, 16, v127
	v_and_b32_e32 v243, 0xffff0000, v127
	v_pk_mul_f32 v[236:237], v[236:237], s[100:101] op_sel_hi:[1,0]
	v_pk_mul_f32 v[238:239], v[238:239], s[100:101] op_sel_hi:[1,0]
	v_pk_mul_f32 v[240:241], v[240:241], s[100:101] op_sel_hi:[1,0]
	v_pk_mul_f32 v[242:243], v[242:243], s[100:101] op_sel_hi:[1,0]
	v_exp_f32_e32 v236, v236
	v_exp_f32_e32 v237, v237
	v_exp_f32_e32 v238, v238
	v_exp_f32_e32 v239, v239
	v_exp_f32_e32 v240, v240
	v_exp_f32_e32 v241, v241
	v_exp_f32_e32 v242, v242
	v_exp_f32_e32 v243, v243
	s_nop 0
	v_pk_add_f32 v[236:237], v[236:237], 1.0 op_sel_hi:[1,0]
	v_pk_add_f32 v[238:239], v[238:239], 1.0 op_sel_hi:[1,0]
	v_pk_add_f32 v[240:241], v[240:241], 1.0 op_sel_hi:[1,0]
	v_pk_add_f32 v[242:243], v[242:243], 1.0 op_sel_hi:[1,0]
	v_rcp_f32_e32 v244, v236
	v_rcp_f32_e32 v245, v237
	v_rcp_f32_e32 v250, v238
	v_rcp_f32_e32 v251, v239
	v_pk_fma_f32 v[246:247], v[236:237], v[244:245], 1.0 op_sel_hi:[1,1,0] neg_lo:[1,0,0] neg_hi:[1,0,0]
	v_pk_fma_f32 v[252:253], v[238:239], v[250:251], 1.0 op_sel_hi:[1,1,0] neg_lo:[1,0,0] neg_hi:[1,0,0]
	v_pk_fma_f32 v[244:245], v[246:247], v[244:245], v[244:245]
	v_pk_fma_f32 v[250:251], v[252:253], v[250:251], v[250:251]
	v_pk_fma_f32 v[246:247], v[236:237], v[244:245], 1.0 op_sel_hi:[1,1,0] neg_lo:[1,0,0] neg_hi:[1,0,0]
	v_pk_fma_f32 v[252:253], v[238:239], v[250:251], 1.0 op_sel_hi:[1,1,0] neg_lo:[1,0,0] neg_hi:[1,0,0]
	v_pk_fma_f32 v[248:249], v[246:247], v[244:245], v[244:245]
	v_pk_fma_f32 v[254:255], v[252:253], v[250:251], v[250:251]
	v_pk_fma_f32 v[246:247], v[236:237], v[248:249], 1.0 op_sel_hi:[1,1,0] neg_lo:[1,0,0] neg_hi:[1,0,0]
	v_pk_fma_f32 v[252:253], v[238:239], v[254:255], 1.0 op_sel_hi:[1,1,0] neg_lo:[1,0,0] neg_hi:[1,0,0]
	v_pk_fma_f32 v[248:249], v[246:247], v[244:245], v[248:249]
	v_pk_fma_f32 v[254:255], v[252:253], v[250:251], v[254:255]
	v_div_fixup_f32 v236, v248, v236, 1.0
	v_div_fixup_f32 v237, v249, v237, 1.0
	v_div_fixup_f32 v238, v254, v238, 1.0
	v_div_fixup_f32 v239, v255, v239, 1.0
	v_rcp_f32_e32 v244, v240
	v_rcp_f32_e32 v245, v241
	v_rcp_f32_e32 v250, v242
	v_rcp_f32_e32 v251, v243
	v_pk_fma_f32 v[246:247], v[240:241], v[244:245], 1.0 op_sel_hi:[1,1,0] neg_lo:[1,0,0] neg_hi:[1,0,0]
	v_pk_fma_f32 v[252:253], v[242:243], v[250:251], 1.0 op_sel_hi:[1,1,0] neg_lo:[1,0,0] neg_hi:[1,0,0]
	v_pk_fma_f32 v[244:245], v[246:247], v[244:245], v[244:245]
	v_pk_fma_f32 v[250:251], v[252:253], v[250:251], v[250:251]
	v_pk_fma_f32 v[246:247], v[240:241], v[244:245], 1.0 op_sel_hi:[1,1,0] neg_lo:[1,0,0] neg_hi:[1,0,0]
	v_pk_fma_f32 v[252:253], v[242:243], v[250:251], 1.0 op_sel_hi:[1,1,0] neg_lo:[1,0,0] neg_hi:[1,0,0]
	v_pk_fma_f32 v[248:249], v[246:247], v[244:245], v[244:245]
	v_pk_fma_f32 v[254:255], v[252:253], v[250:251], v[250:251]
	v_pk_fma_f32 v[246:247], v[240:241], v[248:249], 1.0 op_sel_hi:[1,1,0] neg_lo:[1,0,0] neg_hi:[1,0,0]
	v_pk_fma_f32 v[252:253], v[242:243], v[254:255], 1.0 op_sel_hi:[1,1,0] neg_lo:[1,0,0] neg_hi:[1,0,0]
	v_pk_fma_f32 v[248:249], v[246:247], v[244:245], v[248:249]
	v_pk_fma_f32 v[254:255], v[252:253], v[250:251], v[254:255]
	v_div_fixup_f32 v240, v248, v240, 1.0
	v_div_fixup_f32 v241, v249, v241, 1.0
	v_div_fixup_f32 v242, v254, v242, 1.0
	v_div_fixup_f32 v243, v255, v243, 1.0
	s_mov_b64 vcc, s[12:13]
	v_pk_mul_f32 v[116:117], v[116:117], v[236:237]
	v_pk_mul_f32 v[112:113], v[112:113], v[238:239]
	v_pk_mul_f32 v[118:119], v[118:119], v[240:241]
	v_pk_mul_f32 v[120:121], v[114:115], v[242:243]
	v_cvt_pk_bf16_f32 v114, v116, v117
	v_cvt_pk_bf16_f32 v115, v118, v119
	v_cvt_pk_bf16_f32 v116, v112, v113
	v_or_b32_e32 v112, 16, v160
	v_mad_i64_i32 v[112:113], s[6:7], v112, s61, v[146:147]
	v_lshl_add_u64 v[112:113], v[112:113], 0, v[148:149]
	v_add_co_u32_e32 v122, vcc, s62, v112
	v_cvt_pk_bf16_f32 v117, v120, v121
	global_store_dwordx4 v[150:151], v[114:117], off offset:256
	s_nop 0
	v_addc_co_u32_e32 v123, vcc, 0, v113, vcc
	s_waitcnt vmcnt(7)
; __device__ __forceinline__ float sigmoidf_(float x) { return 1.0f / (1.0f + __expf(-x)); }
; __device__ __forceinline__ u32x4 pack8(const f32x4 v0, const f32x4 v1) { u32x4 w; w.x = pk2(v0[0], v0[1]); w.y = pk2(v0[2], v0[3]); w.z = pk2(v1[0], v1[1]); w.w = pk2(v1[2], v1[3]); return w; }
; __device__ __forceinline__ void unpack8(const u32x4 w, f32x4& v0, f32x4& v1) { v0 = (f32x4){bflo(w.x), bfhi(w.x), bflo(w.y), bfhi(w.y)}; v1 = (f32x4){bflo(w.z), bfhi(w.z), bflo(w.w), bfhi(w.w)}; }
;     __device__ __forceinline__ void operator()(const f32x4 (&acc)[2][2][4][2], const Unit& u, int wr, int wc, int fr, int fq) const {
;     ...
; #pragma unroll
;         for (int ai = 0; ai < 2; ++ai)
; #pragma unroll
;             for (int m = 0; m < 4; ++m) {
;                 bf16_t* rowp = z + (size_t)(row0 + ai * 128 + m * 16) * DIN + col0;
; #pragma unroll
;                 for (int bj = 0; bj < 2; ++bj) {
;                     const u32x4 gw = *(const u32x4*)(rowp + (MODE == 0 ? O_GB : O_GA) + bj * 128);
;                     f32x4 g0, g1; unpack8(gw, g0, g1);
;                     f32x4 v0, v1;
; #pragma unroll
;                     for (int j = 0; j < 4; ++j) { v0[j] = sigmoidf_(g0[j]) * acc[ai][bj][m][0][j]; v1[j] = sigmoidf_(g1[j]) * acc[ai][bj][m][1][j]; }
;                     if (MODE == 1) { const u32x4 mw = *(const u32x4*)(rowp + bj * 128); f32x4 m0, m1; unpack8(mw, m0, m1); v0 += m0; v1 += m1; }
;                     *(u32x4*)(rowp + bj * 128) = pack8(v0, v1); }
	v_mov_b64_e32 v[118:119], v[208:209]
	v_mov_b64_e32 v[120:121], v[210:211]
	v_add_u32_e32 v199, 0x111a00, v198
	global_load_dwordx4 v[208:211], v199, s[24:25]
	s_mov_b32 s100, 0xbfb8aa3b
	v_lshlrev_b32_e32 v236, 16, v118
	v_and_b32_e32 v237, 0xffff0000, v118
	v_lshlrev_b32_e32 v238, 16, v120
	v_and_b32_e32 v239, 0xffff0000, v120
	v_lshlrev_b32_e32 v240, 16, v119
	v_and_b32_e32 v241, 0xffff0000, v119
	v_lshlrev_b32_e32 v242, 16, v121
	v_and_b32_e32 v243, 0xffff0000, v121
	v_pk_mul_f32 v[236:237], v[236:237], s[100:101] op_sel_hi:[1,0]
	v_pk_mul_f32 v[238:239], v[238:239], s[100:101] op_sel_hi:[1,0]
	v_pk_mul_f32 v[240:241], v[240:241], s[100:101] op_sel_hi:[1,0]
	v_pk_mul_f32 v[242:243], v[242:243], s[100:101] op_sel_hi:[1,0]
	v_exp_f32_e32 v236, v236
	v_exp_f32_e32 v237, v237
	v_exp_f32_e32 v238, v238
	v_exp_f32_e32 v239, v239
	v_exp_f32_e32 v240, v240
	v_exp_f32_e32 v241, v241
	v_exp_f32_e32 v242, v242
	v_exp_f32_e32 v243, v243
	s_nop 0
	v_pk_add_f32 v[236:237], v[236:237], 1.0 op_sel_hi:[1,0]
	v_pk_add_f32 v[238:239], v[238:239], 1.0 op_sel_hi:[1,0]
	v_pk_add_f32 v[240:241], v[240:241], 1.0 op_sel_hi:[1,0]
	v_pk_add_f32 v[242:243], v[242:243], 1.0 op_sel_hi:[1,0]
	v_rcp_f32_e32 v244, v236
	v_rcp_f32_e32 v245, v237
	v_rcp_f32_e32 v250, v238
	v_rcp_f32_e32 v251, v239
	v_pk_fma_f32 v[246:247], v[236:237], v[244:245], 1.0 op_sel_hi:[1,1,0] neg_lo:[1,0,0] neg_hi:[1,0,0]
	v_pk_fma_f32 v[252:253], v[238:239], v[250:251], 1.0 op_sel_hi:[1,1,0] neg_lo:[1,0,0] neg_hi:[1,0,0]
	v_pk_fma_f32 v[244:245], v[246:247], v[244:245], v[244:245]
	v_pk_fma_f32 v[250:251], v[252:253], v[250:251], v[250:251]
	v_pk_fma_f32 v[246:247], v[236:237], v[244:245], 1.0 op_sel_hi:[1,1,0] neg_lo:[1,0,0] neg_hi:[1,0,0]
	v_pk_fma_f32 v[252:253], v[238:239], v[250:251], 1.0 op_sel_hi:[1,1,0] neg_lo:[1,0,0] neg_hi:[1,0,0]
	v_pk_fma_f32 v[248:249], v[246:247], v[244:245], v[244:245]
	v_pk_fma_f32 v[254:255], v[252:253], v[250:251], v[250:251]
	v_pk_fma_f32 v[246:247], v[236:237], v[248:249], 1.0 op_sel_hi:[1,1,0] neg_lo:[1,0,0] neg_hi:[1,0,0]
	v_pk_fma_f32 v[252:253], v[238:239], v[254:255], 1.0 op_sel_hi:[1,1,0] neg_lo:[1,0,0] neg_hi:[1,0,0]
	v_pk_fma_f32 v[248:249], v[246:247], v[244:245], v[248:249]
	v_pk_fma_f32 v[254:255], v[252:253], v[250:251], v[254:255]
	v_div_fixup_f32 v236, v248, v236, 1.0
	v_div_fixup_f32 v237, v249, v237, 1.0
	v_div_fixup_f32 v238, v254, v238, 1.0
	v_div_fixup_f32 v239, v255, v239, 1.0
	v_rcp_f32_e32 v244, v240
	v_rcp_f32_e32 v245, v241
	v_rcp_f32_e32 v250, v242
	v_rcp_f32_e32 v251, v243
	v_pk_fma_f32 v[246:247], v[240:241], v[244:245], 1.0 op_sel_hi:[1,1,0] neg_lo:[1,0,0] neg_hi:[1,0,0]
	v_pk_fma_f32 v[252:253], v[242:243], v[250:251], 1.0 op_sel_hi:[1,1,0] neg_lo:[1,0,0] neg_hi:[1,0,0]
	v_pk_fma_f32 v[244:245], v[246:247], v[244:245], v[244:245]
	v_pk_fma_f32 v[250:251], v[252:253], v[250:251], v[250:251]
	v_pk_fma_f32 v[246:247], v[240:241], v[244:245], 1.0 op_sel_hi:[1,1,0] neg_lo:[1,0,0] neg_hi:[1,0,0]
	v_pk_fma_f32 v[252:253], v[242:243], v[250:251], 1.0 op_sel_hi:[1,1,0] neg_lo:[1,0,0] neg_hi:[1,0,0]
	v_pk_fma_f32 v[248:249], v[246:247], v[244:245], v[244:245]
	v_pk_fma_f32 v[254:255], v[252:253], v[250:251], v[250:251]
	v_pk_fma_f32 v[246:247], v[240:241], v[248:249], 1.0 op_sel_hi:[1,1,0] neg_lo:[1,0,0] neg_hi:[1,0,0]
	v_pk_fma_f32 v[252:253], v[242:243], v[254:255], 1.0 op_sel_hi:[1,1,0] neg_lo:[1,0,0] neg_hi:[1,0,0]
	v_pk_fma_f32 v[248:249], v[246:247], v[244:245], v[248:249]
	v_pk_fma_f32 v[254:255], v[252:253], v[250:251], v[254:255]
	v_div_fixup_f32 v240, v248, v240, 1.0
	v_div_fixup_f32 v241, v249, v241, 1.0
	v_div_fixup_f32 v242, v254, v242, 1.0
	v_div_fixup_f32 v243, v255, v243, 1.0
	v_mul_f32_e32 v108, v108, v236
	v_mul_f32_e32 v114, v104, v238
	v_mul_f32_e32 v104, v109, v237
	v_mul_f32_e32 v109, v105, v239
	v_mul_f32_e32 v105, v110, v240
	v_mul_f32_e32 v110, v106, v242
	v_mul_f32_e32 v106, v111, v241
	v_mul_f32_e32 v107, v107, v243
	v_cvt_pk_bf16_f32 v104, v108, v104
	v_cvt_pk_bf16_f32 v105, v105, v106
	v_cvt_pk_bf16_f32 v106, v114, v109
	v_cvt_pk_bf16_f32 v107, v110, v107
	s_waitcnt vmcnt(7)
	v_mov_b32_e32 v108, v212
	v_mov_b32_e32 v109, v213
	v_mov_b64_e32 v[110:111], v[214:215]
	v_add_u32_e32 v199, 0x111b00, v198
	global_load_dwordx4 v[212:215], v199, s[24:25]
	s_mov_b32 s100, 0xbfb8aa3b
	v_lshlrev_b32_e32 v236, 16, v108
	v_and_b32_e32 v237, 0xffff0000, v108
	v_lshlrev_b32_e32 v238, 16, v110
	v_and_b32_e32 v239, 0xffff0000, v110
	v_lshlrev_b32_e32 v240, 16, v109
	v_and_b32_e32 v241, 0xffff0000, v109
	v_lshlrev_b32_e32 v242, 16, v111
	v_and_b32_e32 v243, 0xffff0000, v111
	v_pk_mul_f32 v[236:237], v[236:237], s[100:101] op_sel_hi:[1,0]
	v_pk_mul_f32 v[238:239], v[238:239], s[100:101] op_sel_hi:[1,0]
	v_pk_mul_f32 v[240:241], v[240:241], s[100:101] op_sel_hi:[1,0]
	v_pk_mul_f32 v[242:243], v[242:243], s[100:101] op_sel_hi:[1,0]
	v_exp_f32_e32 v236, v236
	v_exp_f32_e32 v237, v237
	v_exp_f32_e32 v238, v238
	v_exp_f32_e32 v239, v239
	v_exp_f32_e32 v240, v240
	v_exp_f32_e32 v241, v241
	v_exp_f32_e32 v242, v242
	v_exp_f32_e32 v243, v243
	s_nop 0
	v_pk_add_f32 v[236:237], v[236:237], 1.0 op_sel_hi:[1,0]
	v_pk_add_f32 v[238:239], v[238:239], 1.0 op_sel_hi:[1,0]
	v_pk_add_f32 v[240:241], v[240:241], 1.0 op_sel_hi:[1,0]
	v_pk_add_f32 v[242:243], v[242:243], 1.0 op_sel_hi:[1,0]
	v_rcp_f32_e32 v244, v236
	v_rcp_f32_e32 v245, v237
	v_rcp_f32_e32 v250, v238
	v_rcp_f32_e32 v251, v239
	v_pk_fma_f32 v[246:247], v[236:237], v[244:245], 1.0 op_sel_hi:[1,1,0] neg_lo:[1,0,0] neg_hi:[1,0,0]
	v_pk_fma_f32 v[252:253], v[238:239], v[250:251], 1.0 op_sel_hi:[1,1,0] neg_lo:[1,0,0] neg_hi:[1,0,0]
	v_pk_fma_f32 v[244:245], v[246:247], v[244:245], v[244:245]
; __device__ __forceinline__ float sigmoidf_(float x) { return 1.0f / (1.0f + __expf(-x)); }
; __device__ __forceinline__ u32x4 pack8(const f32x4 v0, const f32x4 v1) { u32x4 w; w.x = pk2(v0[0], v0[1]); w.y = pk2(v0[2], v0[3]); w.z = pk2(v1[0], v1[1]); w.w = pk2(v1[2], v1[3]); return w; }
; __device__ __forceinline__ void unpack8(const u32x4 w, f32x4& v0, f32x4& v1) { v0 = (f32x4){bflo(w.x), bfhi(w.x), bflo(w.y), bfhi(w.y)}; v1 = (f32x4){bflo(w.z), bfhi(w.z), bflo(w.w), bfhi(w.w)}; }
;     __device__ __forceinline__ void operator()(const f32x4 (&acc)[2][2][4][2], const Unit& u, int wr, int wc, int fr, int fq) const {
;     ...
; #pragma unroll
;         for (int ai = 0; ai < 2; ++ai)
; #pragma unroll
;             for (int m = 0; m < 4; ++m) {
;                 bf16_t* rowp = z + (size_t)(row0 + ai * 128 + m * 16) * DIN + col0;
; #pragma unroll
;                 for (int bj = 0; bj < 2; ++bj) {
;                     const u32x4 gw = *(const u32x4*)(rowp + (MODE == 0 ? O_GB : O_GA) + bj * 128);
;                     f32x4 g0, g1; unpack8(gw, g0, g1);
;                     f32x4 v0, v1;
; #pragma unroll
;                     for (int j = 0; j < 4; ++j) { v0[j] = sigmoidf_(g0[j]) * acc[ai][bj][m][0][j]; v1[j] = sigmoidf_(g1[j]) * acc[ai][bj][m][1][j]; }
;                     if (MODE == 1) { const u32x4 mw = *(const u32x4*)(rowp + bj * 128); f32x4 m0, m1; unpack8(mw, m0, m1); v0 += m0; v1 += m1; }
;                     *(u32x4*)(rowp + bj * 128) = pack8(v0, v1); }
	v_pk_fma_f32 v[250:251], v[252:253], v[250:251], v[250:251]
	v_pk_fma_f32 v[246:247], v[236:237], v[244:245], 1.0 op_sel_hi:[1,1,0] neg_lo:[1,0,0] neg_hi:[1,0,0]
	v_pk_fma_f32 v[252:253], v[238:239], v[250:251], 1.0 op_sel_hi:[1,1,0] neg_lo:[1,0,0] neg_hi:[1,0,0]
	v_pk_fma_f32 v[248:249], v[246:247], v[244:245], v[244:245]
	v_pk_fma_f32 v[254:255], v[252:253], v[250:251], v[250:251]
	v_pk_fma_f32 v[246:247], v[236:237], v[248:249], 1.0 op_sel_hi:[1,1,0] neg_lo:[1,0,0] neg_hi:[1,0,0]
	v_pk_fma_f32 v[252:253], v[238:239], v[254:255], 1.0 op_sel_hi:[1,1,0] neg_lo:[1,0,0] neg_hi:[1,0,0]
	v_pk_fma_f32 v[248:249], v[246:247], v[244:245], v[248:249]
	v_pk_fma_f32 v[254:255], v[252:253], v[250:251], v[254:255]
	v_div_fixup_f32 v236, v248, v236, 1.0
	v_div_fixup_f32 v237, v249, v237, 1.0
	v_div_fixup_f32 v238, v254, v238, 1.0
	v_div_fixup_f32 v239, v255, v239, 1.0
	v_rcp_f32_e32 v244, v240
	v_rcp_f32_e32 v245, v241
	v_rcp_f32_e32 v250, v242
	v_rcp_f32_e32 v251, v243
	v_pk_fma_f32 v[246:247], v[240:241], v[244:245], 1.0 op_sel_hi:[1,1,0] neg_lo:[1,0,0] neg_hi:[1,0,0]
	v_pk_fma_f32 v[252:253], v[242:243], v[250:251], 1.0 op_sel_hi:[1,1,0] neg_lo:[1,0,0] neg_hi:[1,0,0]
	v_pk_fma_f32 v[244:245], v[246:247], v[244:245], v[244:245]
	v_pk_fma_f32 v[250:251], v[252:253], v[250:251], v[250:251]
	v_pk_fma_f32 v[246:247], v[240:241], v[244:245], 1.0 op_sel_hi:[1,1,0] neg_lo:[1,0,0] neg_hi:[1,0,0]
	v_pk_fma_f32 v[252:253], v[242:243], v[250:251], 1.0 op_sel_hi:[1,1,0] neg_lo:[1,0,0] neg_hi:[1,0,0]
	v_pk_fma_f32 v[248:249], v[246:247], v[244:245], v[244:245]
	v_pk_fma_f32 v[254:255], v[252:253], v[250:251], v[250:251]
	v_pk_fma_f32 v[246:247], v[240:241], v[248:249], 1.0 op_sel_hi:[1,1,0] neg_lo:[1,0,0] neg_hi:[1,0,0]
	v_pk_fma_f32 v[252:253], v[242:243], v[254:255], 1.0 op_sel_hi:[1,1,0] neg_lo:[1,0,0] neg_hi:[1,0,0]
	v_pk_fma_f32 v[248:249], v[246:247], v[244:245], v[248:249]
	v_pk_fma_f32 v[254:255], v[252:253], v[250:251], v[254:255]
	v_div_fixup_f32 v240, v248, v240, 1.0
	v_div_fixup_f32 v241, v249, v241, 1.0
	v_div_fixup_f32 v242, v254, v242, 1.0
	v_div_fixup_f32 v243, v255, v243, 1.0
	global_store_dwordx4 v[112:113], v[104:107], off
	s_nop 0
	v_pk_mul_f32 v[100:101], v[100:101], v[236:237]
	v_pk_mul_f32 v[96:97], v[96:97], v[238:239]
	v_pk_mul_f32 v[102:103], v[102:103], v[240:241]
	v_pk_mul_f32 v[104:105], v[98:99], v[242:243]
	v_cvt_pk_bf16_f32 v98, v100, v101
	v_cvt_pk_bf16_f32 v99, v102, v103
	v_cvt_pk_bf16_f32 v100, v96, v97
	v_or_b32_e32 v96, 32, v160
	v_mad_i64_i32 v[96:97], s[6:7], v96, s61, v[146:147]
	v_lshl_add_u64 v[96:97], v[96:97], 0, v[148:149]
	v_add_co_u32_e32 v106, vcc, s62, v96
	v_cvt_pk_bf16_f32 v101, v104, v105
	global_store_dwordx4 v[112:113], v[98:101], off offset:256
	s_nop 0
	v_addc_co_u32_e32 v107, vcc, 0, v97, vcc
	s_waitcnt vmcnt(9)
	v_mov_b64_e32 v[102:103], v[216:217]
	v_mov_b64_e32 v[104:105], v[218:219]
	v_add_u32_e32 v199, 0x133a00, v198
	global_load_dwordx4 v[216:219], v199, s[24:25]
	s_mov_b32 s100, 0xbfb8aa3b
	v_lshlrev_b32_e32 v236, 16, v102
	v_and_b32_e32 v237, 0xffff0000, v102
	v_lshlrev_b32_e32 v238, 16, v104
	v_and_b32_e32 v239, 0xffff0000, v104
	v_lshlrev_b32_e32 v240, 16, v103
	v_and_b32_e32 v241, 0xffff0000, v103
	v_lshlrev_b32_e32 v242, 16, v105
	v_and_b32_e32 v243, 0xffff0000, v105
	v_pk_mul_f32 v[236:237], v[236:237], s[100:101] op_sel_hi:[1,0]
	v_pk_mul_f32 v[238:239], v[238:239], s[100:101] op_sel_hi:[1,0]
	v_pk_mul_f32 v[240:241], v[240:241], s[100:101] op_sel_hi:[1,0]
	v_pk_mul_f32 v[242:243], v[242:243], s[100:101] op_sel_hi:[1,0]
	v_exp_f32_e32 v236, v236
	v_exp_f32_e32 v237, v237
	v_exp_f32_e32 v238, v238
	v_exp_f32_e32 v239, v239
	v_exp_f32_e32 v240, v240
	v_exp_f32_e32 v241, v241
	v_exp_f32_e32 v242, v242
	v_exp_f32_e32 v243, v243
	s_nop 0
	v_pk_add_f32 v[236:237], v[236:237], 1.0 op_sel_hi:[1,0]
	v_pk_add_f32 v[238:239], v[238:239], 1.0 op_sel_hi:[1,0]
	v_pk_add_f32 v[240:241], v[240:241], 1.0 op_sel_hi:[1,0]
	v_pk_add_f32 v[242:243], v[242:243], 1.0 op_sel_hi:[1,0]
	v_rcp_f32_e32 v244, v236
	v_rcp_f32_e32 v245, v237
	v_rcp_f32_e32 v250, v238
	v_rcp_f32_e32 v251, v239
	v_pk_fma_f32 v[246:247], v[236:237], v[244:245], 1.0 op_sel_hi:[1,1,0] neg_lo:[1,0,0] neg_hi:[1,0,0]
	v_pk_fma_f32 v[252:253], v[238:239], v[250:251], 1.0 op_sel_hi:[1,1,0] neg_lo:[1,0,0] neg_hi:[1,0,0]
	v_pk_fma_f32 v[244:245], v[246:247], v[244:245], v[244:245]
	v_pk_fma_f32 v[250:251], v[252:253], v[250:251], v[250:251]
	v_pk_fma_f32 v[246:247], v[236:237], v[244:245], 1.0 op_sel_hi:[1,1,0] neg_lo:[1,0,0] neg_hi:[1,0,0]
	v_pk_fma_f32 v[252:253], v[238:239], v[250:251], 1.0 op_sel_hi:[1,1,0] neg_lo:[1,0,0] neg_hi:[1,0,0]
	v_pk_fma_f32 v[248:249], v[246:247], v[244:245], v[244:245]
	v_pk_fma_f32 v[254:255], v[252:253], v[250:251], v[250:251]
	v_pk_fma_f32 v[246:247], v[236:237], v[248:249], 1.0 op_sel_hi:[1,1,0] neg_lo:[1,0,0] neg_hi:[1,0,0]
	v_pk_fma_f32 v[252:253], v[238:239], v[254:255], 1.0 op_sel_hi:[1,1,0] neg_lo:[1,0,0] neg_hi:[1,0,0]
	v_pk_fma_f32 v[248:249], v[246:247], v[244:245], v[248:249]
	v_pk_fma_f32 v[254:255], v[252:253], v[250:251], v[254:255]
	v_div_fixup_f32 v236, v248, v236, 1.0
	v_div_fixup_f32 v237, v249, v237, 1.0
	v_div_fixup_f32 v238, v254, v238, 1.0
	v_div_fixup_f32 v239, v255, v239, 1.0
	v_rcp_f32_e32 v244, v240
	v_rcp_f32_e32 v245, v241
	v_rcp_f32_e32 v250, v242
	v_rcp_f32_e32 v251, v243
	v_pk_fma_f32 v[246:247], v[240:241], v[244:245], 1.0 op_sel_hi:[1,1,0] neg_lo:[1,0,0] neg_hi:[1,0,0]
	v_pk_fma_f32 v[252:253], v[242:243], v[250:251], 1.0 op_sel_hi:[1,1,0] neg_lo:[1,0,0] neg_hi:[1,0,0]
	v_pk_fma_f32 v[244:245], v[246:247], v[244:245], v[244:245]
	v_pk_fma_f32 v[250:251], v[252:253], v[250:251], v[250:251]
	v_pk_fma_f32 v[246:247], v[240:241], v[244:245], 1.0 op_sel_hi:[1,1,0] neg_lo:[1,0,0] neg_hi:[1,0,0]
	v_pk_fma_f32 v[252:253], v[242:243], v[250:251], 1.0 op_sel_hi:[1,1,0] neg_lo:[1,0,0] neg_hi:[1,0,0]
	v_pk_fma_f32 v[248:249], v[246:247], v[244:245], v[244:245]
	v_pk_fma_f32 v[254:255], v[252:253], v[250:251], v[250:251]
	v_pk_fma_f32 v[246:247], v[240:241], v[248:249], 1.0 op_sel_hi:[1,1,0] neg_lo:[1,0,0] neg_hi:[1,0,0]
	v_pk_fma_f32 v[252:253], v[242:243], v[254:255], 1.0 op_sel_hi:[1,1,0] neg_lo:[1,0,0] neg_hi:[1,0,0]
	v_pk_fma_f32 v[248:249], v[246:247], v[244:245], v[248:249]
	v_pk_fma_f32 v[254:255], v[252:253], v[250:251], v[254:255]
	v_div_fixup_f32 v240, v248, v240, 1.0
	v_div_fixup_f32 v241, v249, v241, 1.0
	v_div_fixup_f32 v242, v254, v242, 1.0
	v_div_fixup_f32 v243, v255, v243, 1.0
	v_mul_f32_e32 v92, v92, v236
	v_mul_f32_e32 v98, v88, v238
	v_mul_f32_e32 v88, v93, v237
	v_mul_f32_e32 v93, v89, v239
	v_mul_f32_e32 v89, v94, v240
	v_mul_f32_e32 v94, v90, v242
	v_mul_f32_e32 v90, v95, v241
	v_mul_f32_e32 v91, v91, v243
	v_cvt_pk_bf16_f32 v88, v92, v88
	v_cvt_pk_bf16_f32 v89, v89, v90
	v_cvt_pk_bf16_f32 v90, v98, v93
	v_cvt_pk_bf16_f32 v91, v94, v91
	s_waitcnt vmcnt(9)
; __device__ __forceinline__ float sigmoidf_(float x) { return 1.0f / (1.0f + __expf(-x)); }
; __device__ __forceinline__ u32x4 pack8(const f32x4 v0, const f32x4 v1) { u32x4 w; w.x = pk2(v0[0], v0[1]); w.y = pk2(v0[2], v0[3]); w.z = pk2(v1[0], v1[1]); w.w = pk2(v1[2], v1[3]); return w; }
; __device__ __forceinline__ void unpack8(const u32x4 w, f32x4& v0, f32x4& v1) { v0 = (f32x4){bflo(w.x), bfhi(w.x), bflo(w.y), bfhi(w.y)}; v1 = (f32x4){bflo(w.z), bfhi(w.z), bflo(w.w), bfhi(w.w)}; }
;     __device__ __forceinline__ void operator()(const f32x4 (&acc)[2][2][4][2], const Unit& u, int wr, int wc, int fr, int fq) const {
;     ...
; #pragma unroll
;         for (int ai = 0; ai < 2; ++ai)
; #pragma unroll
;             for (int m = 0; m < 4; ++m) {
;                 bf16_t* rowp = z + (size_t)(row0 + ai * 128 + m * 16) * DIN + col0;
; #pragma unroll
;                 for (int bj = 0; bj < 2; ++bj) {
;                     const u32x4 gw = *(const u32x4*)(rowp + (MODE == 0 ? O_GB : O_GA) + bj * 128);
;                     f32x4 g0, g1; unpack8(gw, g0, g1);
;                     f32x4 v0, v1;
; #pragma unroll
;                     for (int j = 0; j < 4; ++j) { v0[j] = sigmoidf_(g0[j]) * acc[ai][bj][m][0][j]; v1[j] = sigmoidf_(g1[j]) * acc[ai][bj][m][1][j]; }
;                     if (MODE == 1) { const u32x4 mw = *(const u32x4*)(rowp + bj * 128); f32x4 m0, m1; unpack8(mw, m0, m1); v0 += m0; v1 += m1; }
;                     *(u32x4*)(rowp + bj * 128) = pack8(v0, v1); }
	v_mov_b32_e32 v92, v232
	v_mov_b32_e32 v93, v233
	v_mov_b64_e32 v[94:95], v[234:235]
	v_add_u32_e32 v199, 0x133b00, v198
	global_load_dwordx4 v[232:235], v199, s[24:25]
	s_mov_b32 s100, 0xbfb8aa3b
	v_lshlrev_b32_e32 v236, 16, v92
	v_and_b32_e32 v237, 0xffff0000, v92
	v_lshlrev_b32_e32 v238, 16, v94
	v_and_b32_e32 v239, 0xffff0000, v94
	v_lshlrev_b32_e32 v240, 16, v93
	v_and_b32_e32 v241, 0xffff0000, v93
	v_lshlrev_b32_e32 v242, 16, v95
	v_and_b32_e32 v243, 0xffff0000, v95
	v_pk_mul_f32 v[236:237], v[236:237], s[100:101] op_sel_hi:[1,0]
	v_pk_mul_f32 v[238:239], v[238:239], s[100:101] op_sel_hi:[1,0]
	v_pk_mul_f32 v[240:241], v[240:241], s[100:101] op_sel_hi:[1,0]
	v_pk_mul_f32 v[242:243], v[242:243], s[100:101] op_sel_hi:[1,0]
	v_exp_f32_e32 v236, v236
	v_exp_f32_e32 v237, v237
	v_exp_f32_e32 v238, v238
	v_exp_f32_e32 v239, v239
	v_exp_f32_e32 v240, v240
	v_exp_f32_e32 v241, v241
	v_exp_f32_e32 v242, v242
	v_exp_f32_e32 v243, v243
	s_nop 0
	v_pk_add_f32 v[236:237], v[236:237], 1.0 op_sel_hi:[1,0]
	v_pk_add_f32 v[238:239], v[238:239], 1.0 op_sel_hi:[1,0]
	v_pk_add_f32 v[240:241], v[240:241], 1.0 op_sel_hi:[1,0]
	v_pk_add_f32 v[242:243], v[242:243], 1.0 op_sel_hi:[1,0]
	v_rcp_f32_e32 v244, v236
	v_rcp_f32_e32 v245, v237
	v_rcp_f32_e32 v250, v238
	v_rcp_f32_e32 v251, v239
	v_pk_fma_f32 v[246:247], v[236:237], v[244:245], 1.0 op_sel_hi:[1,1,0] neg_lo:[1,0,0] neg_hi:[1,0,0]
	v_pk_fma_f32 v[252:253], v[238:239], v[250:251], 1.0 op_sel_hi:[1,1,0] neg_lo:[1,0,0] neg_hi:[1,0,0]
	v_pk_fma_f32 v[244:245], v[246:247], v[244:245], v[244:245]
	v_pk_fma_f32 v[250:251], v[252:253], v[250:251], v[250:251]
	v_pk_fma_f32 v[246:247], v[236:237], v[244:245], 1.0 op_sel_hi:[1,1,0] neg_lo:[1,0,0] neg_hi:[1,0,0]
	v_pk_fma_f32 v[252:253], v[238:239], v[250:251], 1.0 op_sel_hi:[1,1,0] neg_lo:[1,0,0] neg_hi:[1,0,0]
	v_pk_fma_f32 v[248:249], v[246:247], v[244:245], v[244:245]
	v_pk_fma_f32 v[254:255], v[252:253], v[250:251], v[250:251]
	v_pk_fma_f32 v[246:247], v[236:237], v[248:249], 1.0 op_sel_hi:[1,1,0] neg_lo:[1,0,0] neg_hi:[1,0,0]
	v_pk_fma_f32 v[252:253], v[238:239], v[254:255], 1.0 op_sel_hi:[1,1,0] neg_lo:[1,0,0] neg_hi:[1,0,0]
	v_pk_fma_f32 v[248:249], v[246:247], v[244:245], v[248:249]
	v_pk_fma_f32 v[254:255], v[252:253], v[250:251], v[254:255]
	v_div_fixup_f32 v236, v248, v236, 1.0
	v_div_fixup_f32 v237, v249, v237, 1.0
	v_div_fixup_f32 v238, v254, v238, 1.0
	v_div_fixup_f32 v239, v255, v239, 1.0
	v_rcp_f32_e32 v244, v240
	v_rcp_f32_e32 v245, v241
	v_rcp_f32_e32 v250, v242
	v_rcp_f32_e32 v251, v243
	v_pk_fma_f32 v[246:247], v[240:241], v[244:245], 1.0 op_sel_hi:[1,1,0] neg_lo:[1,0,0] neg_hi:[1,0,0]
	v_pk_fma_f32 v[252:253], v[242:243], v[250:251], 1.0 op_sel_hi:[1,1,0] neg_lo:[1,0,0] neg_hi:[1,0,0]
	v_pk_fma_f32 v[244:245], v[246:247], v[244:245], v[244:245]
	v_pk_fma_f32 v[250:251], v[252:253], v[250:251], v[250:251]
	v_pk_fma_f32 v[246:247], v[240:241], v[244:245], 1.0 op_sel_hi:[1,1,0] neg_lo:[1,0,0] neg_hi:[1,0,0]
	v_pk_fma_f32 v[252:253], v[242:243], v[250:251], 1.0 op_sel_hi:[1,1,0] neg_lo:[1,0,0] neg_hi:[1,0,0]
	v_pk_fma_f32 v[248:249], v[246:247], v[244:245], v[244:245]
	v_pk_fma_f32 v[254:255], v[252:253], v[250:251], v[250:251]
	v_pk_fma_f32 v[246:247], v[240:241], v[248:249], 1.0 op_sel_hi:[1,1,0] neg_lo:[1,0,0] neg_hi:[1,0,0]
	v_pk_fma_f32 v[252:253], v[242:243], v[254:255], 1.0 op_sel_hi:[1,1,0] neg_lo:[1,0,0] neg_hi:[1,0,0]
	v_pk_fma_f32 v[248:249], v[246:247], v[244:245], v[248:249]
	v_pk_fma_f32 v[254:255], v[252:253], v[250:251], v[254:255]
	v_div_fixup_f32 v240, v248, v240, 1.0
	v_div_fixup_f32 v241, v249, v241, 1.0
	v_div_fixup_f32 v242, v254, v242, 1.0
	v_div_fixup_f32 v243, v255, v243, 1.0
	global_store_dwordx4 v[96:97], v[88:91], off
	s_nop 0
	v_pk_mul_f32 v[84:85], v[84:85], v[236:237]
	v_pk_mul_f32 v[80:81], v[80:81], v[238:239]
	v_pk_mul_f32 v[86:87], v[86:87], v[240:241]
	v_pk_mul_f32 v[88:89], v[82:83], v[242:243]
	v_cvt_pk_bf16_f32 v82, v84, v85
	v_cvt_pk_bf16_f32 v83, v86, v87
	v_cvt_pk_bf16_f32 v84, v80, v81
	v_or_b32_e32 v80, 48, v160
	v_mad_i64_i32 v[80:81], s[6:7], v80, s61, v[146:147]
	v_lshl_add_u64 v[80:81], v[80:81], 0, v[148:149]
	v_add_co_u32_e32 v90, vcc, s62, v80
	v_cvt_pk_bf16_f32 v85, v88, v89
	global_store_dwordx4 v[96:97], v[82:85], off offset:256
	s_nop 0
	v_addc_co_u32_e32 v91, vcc, 0, v81, vcc
	s_waitcnt vmcnt(11)
; __device__ __forceinline__ float sigmoidf_(float x) { return 1.0f / (1.0f + __expf(-x)); }
; __device__ __forceinline__ u32x4 pack8(const f32x4 v0, const f32x4 v1) { u32x4 w; w.x = pk2(v0[0], v0[1]); w.y = pk2(v0[2], v0[3]); w.z = pk2(v1[0], v1[1]); w.w = pk2(v1[2], v1[3]); return w; }
; __device__ __forceinline__ void unpack8(const u32x4 w, f32x4& v0, f32x4& v1) { v0 = (f32x4){bflo(w.x), bfhi(w.x), bflo(w.y), bfhi(w.y)}; v1 = (f32x4){bflo(w.z), bfhi(w.z), bflo(w.w), bfhi(w.w)}; }
;     __device__ __forceinline__ void operator()(const f32x4 (&acc)[2][2][4][2], const Unit& u, int wr, int wc, int fr, int fq) const {
;     ...
; #pragma unroll
;         for (int ai = 0; ai < 2; ++ai)
; #pragma unroll
;             for (int m = 0; m < 4; ++m) {
;                 bf16_t* rowp = z + (size_t)(row0 + ai * 128 + m * 16) * DIN + col0;
; #pragma unroll
;                 for (int bj = 0; bj < 2; ++bj) {
;                     const u32x4 gw = *(const u32x4*)(rowp + (MODE == 0 ? O_GB : O_GA) + bj * 128);
;                     f32x4 g0, g1; unpack8(gw, g0, g1);
;                     f32x4 v0, v1;
; #pragma unroll
;                     for (int j = 0; j < 4; ++j) { v0[j] = sigmoidf_(g0[j]) * acc[ai][bj][m][0][j]; v1[j] = sigmoidf_(g1[j]) * acc[ai][bj][m][1][j]; }
;                     if (MODE == 1) { const u32x4 mw = *(const u32x4*)(rowp + bj * 128); f32x4 m0, m1; unpack8(mw, m0, m1); v0 += m0; v1 += m1; }
;                     *(u32x4*)(rowp + bj * 128) = pack8(v0, v1); }
	v_mov_b64_e32 v[86:87], v[200:201]
	v_mov_b64_e32 v[88:89], v[202:203]
	v_add_u32_e32 v199, 0x155a00, v198
	global_load_dwordx4 v[200:203], v199, s[24:25]
	s_mov_b32 s100, 0xbfb8aa3b
	v_lshlrev_b32_e32 v236, 16, v86
	v_and_b32_e32 v237, 0xffff0000, v86
	v_lshlrev_b32_e32 v238, 16, v88
	v_and_b32_e32 v239, 0xffff0000, v88
	v_lshlrev_b32_e32 v240, 16, v87
	v_and_b32_e32 v241, 0xffff0000, v87
	v_lshlrev_b32_e32 v242, 16, v89
	v_and_b32_e32 v243, 0xffff0000, v89
	v_pk_mul_f32 v[236:237], v[236:237], s[100:101] op_sel_hi:[1,0]
	v_pk_mul_f32 v[238:239], v[238:239], s[100:101] op_sel_hi:[1,0]
	v_pk_mul_f32 v[240:241], v[240:241], s[100:101] op_sel_hi:[1,0]
	v_pk_mul_f32 v[242:243], v[242:243], s[100:101] op_sel_hi:[1,0]
	v_exp_f32_e32 v236, v236
	v_exp_f32_e32 v237, v237
	v_exp_f32_e32 v238, v238
	v_exp_f32_e32 v239, v239
	v_exp_f32_e32 v240, v240
	v_exp_f32_e32 v241, v241
	v_exp_f32_e32 v242, v242
	v_exp_f32_e32 v243, v243
	s_nop 0
	v_pk_add_f32 v[236:237], v[236:237], 1.0 op_sel_hi:[1,0]
	v_pk_add_f32 v[238:239], v[238:239], 1.0 op_sel_hi:[1,0]
	v_pk_add_f32 v[240:241], v[240:241], 1.0 op_sel_hi:[1,0]
	v_pk_add_f32 v[242:243], v[242:243], 1.0 op_sel_hi:[1,0]
	v_rcp_f32_e32 v244, v236
	v_rcp_f32_e32 v245, v237
	v_rcp_f32_e32 v250, v238
	v_rcp_f32_e32 v251, v239
	v_pk_fma_f32 v[246:247], v[236:237], v[244:245], 1.0 op_sel_hi:[1,1,0] neg_lo:[1,0,0] neg_hi:[1,0,0]
	v_pk_fma_f32 v[252:253], v[238:239], v[250:251], 1.0 op_sel_hi:[1,1,0] neg_lo:[1,0,0] neg_hi:[1,0,0]
	v_pk_fma_f32 v[244:245], v[246:247], v[244:245], v[244:245]
	v_pk_fma_f32 v[250:251], v[252:253], v[250:251], v[250:251]
	v_pk_fma_f32 v[246:247], v[236:237], v[244:245], 1.0 op_sel_hi:[1,1,0] neg_lo:[1,0,0] neg_hi:[1,0,0]
	v_pk_fma_f32 v[252:253], v[238:239], v[250:251], 1.0 op_sel_hi:[1,1,0] neg_lo:[1,0,0] neg_hi:[1,0,0]
	v_pk_fma_f32 v[248:249], v[246:247], v[244:245], v[244:245]
	v_pk_fma_f32 v[254:255], v[252:253], v[250:251], v[250:251]
	v_pk_fma_f32 v[246:247], v[236:237], v[248:249], 1.0 op_sel_hi:[1,1,0] neg_lo:[1,0,0] neg_hi:[1,0,0]
	v_pk_fma_f32 v[252:253], v[238:239], v[254:255], 1.0 op_sel_hi:[1,1,0] neg_lo:[1,0,0] neg_hi:[1,0,0]
	v_pk_fma_f32 v[248:249], v[246:247], v[244:245], v[248:249]
	v_pk_fma_f32 v[254:255], v[252:253], v[250:251], v[254:255]
	v_div_fixup_f32 v236, v248, v236, 1.0
	v_div_fixup_f32 v237, v249, v237, 1.0
	v_div_fixup_f32 v238, v254, v238, 1.0
	v_div_fixup_f32 v239, v255, v239, 1.0
	v_rcp_f32_e32 v244, v240
	v_rcp_f32_e32 v245, v241
	v_rcp_f32_e32 v250, v242
	v_rcp_f32_e32 v251, v243
	v_pk_fma_f32 v[246:247], v[240:241], v[244:245], 1.0 op_sel_hi:[1,1,0] neg_lo:[1,0,0] neg_hi:[1,0,0]
	v_pk_fma_f32 v[252:253], v[242:243], v[250:251], 1.0 op_sel_hi:[1,1,0] neg_lo:[1,0,0] neg_hi:[1,0,0]
	v_pk_fma_f32 v[244:245], v[246:247], v[244:245], v[244:245]
	v_pk_fma_f32 v[250:251], v[252:253], v[250:251], v[250:251]
	v_pk_fma_f32 v[246:247], v[240:241], v[244:245], 1.0 op_sel_hi:[1,1,0] neg_lo:[1,0,0] neg_hi:[1,0,0]
	v_pk_fma_f32 v[252:253], v[242:243], v[250:251], 1.0 op_sel_hi:[1,1,0] neg_lo:[1,0,0] neg_hi:[1,0,0]
	v_pk_fma_f32 v[248:249], v[246:247], v[244:245], v[244:245]
	v_pk_fma_f32 v[254:255], v[252:253], v[250:251], v[250:251]
	v_pk_fma_f32 v[246:247], v[240:241], v[248:249], 1.0 op_sel_hi:[1,1,0] neg_lo:[1,0,0] neg_hi:[1,0,0]
	v_pk_fma_f32 v[252:253], v[242:243], v[254:255], 1.0 op_sel_hi:[1,1,0] neg_lo:[1,0,0] neg_hi:[1,0,0]
	v_pk_fma_f32 v[248:249], v[246:247], v[244:245], v[248:249]
	v_pk_fma_f32 v[254:255], v[252:253], v[250:251], v[254:255]
	v_div_fixup_f32 v240, v248, v240, 1.0
	v_div_fixup_f32 v241, v249, v241, 1.0
	v_div_fixup_f32 v242, v254, v242, 1.0
	v_div_fixup_f32 v243, v255, v243, 1.0
	v_mul_f32_e32 v76, v76, v236
	v_mul_f32_e32 v82, v72, v238
	v_mul_f32_e32 v72, v77, v237
	v_mul_f32_e32 v77, v73, v239
	v_mul_f32_e32 v73, v78, v240
	v_mul_f32_e32 v78, v74, v242
	v_mul_f32_e32 v74, v79, v241
	v_mul_f32_e32 v75, v75, v243
	v_cvt_pk_bf16_f32 v72, v76, v72
	v_cvt_pk_bf16_f32 v73, v73, v74
	v_cvt_pk_bf16_f32 v74, v82, v77
	v_cvt_pk_bf16_f32 v75, v78, v75
	s_waitcnt vmcnt(10)
	v_mov_b32_e32 v76, v204
	v_mov_b32_e32 v77, v205
	v_mov_b64_e32 v[78:79], v[206:207]
	v_add_u32_e32 v199, 0x155b00, v198
	global_load_dwordx4 v[204:207], v199, s[24:25]
	s_mov_b32 s100, 0xbfb8aa3b
	v_lshlrev_b32_e32 v236, 16, v76
	v_and_b32_e32 v237, 0xffff0000, v76
	v_lshlrev_b32_e32 v238, 16, v78
	v_and_b32_e32 v239, 0xffff0000, v78
	v_lshlrev_b32_e32 v240, 16, v77
	v_and_b32_e32 v241, 0xffff0000, v77
	v_lshlrev_b32_e32 v242, 16, v79
	v_and_b32_e32 v243, 0xffff0000, v79
	v_pk_mul_f32 v[236:237], v[236:237], s[100:101] op_sel_hi:[1,0]
	v_pk_mul_f32 v[238:239], v[238:239], s[100:101] op_sel_hi:[1,0]
	v_pk_mul_f32 v[240:241], v[240:241], s[100:101] op_sel_hi:[1,0]
	v_pk_mul_f32 v[242:243], v[242:243], s[100:101] op_sel_hi:[1,0]
	v_exp_f32_e32 v236, v236
	v_exp_f32_e32 v237, v237
	v_exp_f32_e32 v238, v238
	v_exp_f32_e32 v239, v239
	v_exp_f32_e32 v240, v240
	v_exp_f32_e32 v241, v241
	v_exp_f32_e32 v242, v242
	v_exp_f32_e32 v243, v243
	s_nop 0
	v_pk_add_f32 v[236:237], v[236:237], 1.0 op_sel_hi:[1,0]
	v_pk_add_f32 v[238:239], v[238:239], 1.0 op_sel_hi:[1,0]
	v_pk_add_f32 v[240:241], v[240:241], 1.0 op_sel_hi:[1,0]
	v_pk_add_f32 v[242:243], v[242:243], 1.0 op_sel_hi:[1,0]
	v_rcp_f32_e32 v244, v236
	v_rcp_f32_e32 v245, v237
	v_rcp_f32_e32 v250, v238
	v_rcp_f32_e32 v251, v239
	v_pk_fma_f32 v[246:247], v[236:237], v[244:245], 1.0 op_sel_hi:[1,1,0] neg_lo:[1,0,0] neg_hi:[1,0,0]
	v_pk_fma_f32 v[252:253], v[238:239], v[250:251], 1.0 op_sel_hi:[1,1,0] neg_lo:[1,0,0] neg_hi:[1,0,0]
	v_pk_fma_f32 v[244:245], v[246:247], v[244:245], v[244:245]
	v_pk_fma_f32 v[250:251], v[252:253], v[250:251], v[250:251]
; __device__ __forceinline__ float sigmoidf_(float x) { return 1.0f / (1.0f + __expf(-x)); }
; __device__ __forceinline__ u32x4 pack8(const f32x4 v0, const f32x4 v1) { u32x4 w; w.x = pk2(v0[0], v0[1]); w.y = pk2(v0[2], v0[3]); w.z = pk2(v1[0], v1[1]); w.w = pk2(v1[2], v1[3]); return w; }
; __device__ __forceinline__ void unpack8(const u32x4 w, f32x4& v0, f32x4& v1) { v0 = (f32x4){bflo(w.x), bfhi(w.x), bflo(w.y), bfhi(w.y)}; v1 = (f32x4){bflo(w.z), bfhi(w.z), bflo(w.w), bfhi(w.w)}; }
;     __device__ __forceinline__ void operator()(const f32x4 (&acc)[2][2][4][2], const Unit& u, int wr, int wc, int fr, int fq) const {
;     ...
; #pragma unroll
;         for (int ai = 0; ai < 2; ++ai)
; #pragma unroll
;             for (int m = 0; m < 4; ++m) {
;                 bf16_t* rowp = z + (size_t)(row0 + ai * 128 + m * 16) * DIN + col0;
; #pragma unroll
;                 for (int bj = 0; bj < 2; ++bj) {
;                     const u32x4 gw = *(const u32x4*)(rowp + (MODE == 0 ? O_GB : O_GA) + bj * 128);
;                     f32x4 g0, g1; unpack8(gw, g0, g1);
;                     f32x4 v0, v1;
; #pragma unroll
;                     for (int j = 0; j < 4; ++j) { v0[j] = sigmoidf_(g0[j]) * acc[ai][bj][m][0][j]; v1[j] = sigmoidf_(g1[j]) * acc[ai][bj][m][1][j]; }
;                     if (MODE == 1) { const u32x4 mw = *(const u32x4*)(rowp + bj * 128); f32x4 m0, m1; unpack8(mw, m0, m1); v0 += m0; v1 += m1; }
;                     *(u32x4*)(rowp + bj * 128) = pack8(v0, v1); }
	v_pk_fma_f32 v[246:247], v[236:237], v[244:245], 1.0 op_sel_hi:[1,1,0] neg_lo:[1,0,0] neg_hi:[1,0,0]
	v_pk_fma_f32 v[252:253], v[238:239], v[250:251], 1.0 op_sel_hi:[1,1,0] neg_lo:[1,0,0] neg_hi:[1,0,0]
	v_pk_fma_f32 v[248:249], v[246:247], v[244:245], v[244:245]
	v_pk_fma_f32 v[254:255], v[252:253], v[250:251], v[250:251]
	v_pk_fma_f32 v[246:247], v[236:237], v[248:249], 1.0 op_sel_hi:[1,1,0] neg_lo:[1,0,0] neg_hi:[1,0,0]
	v_pk_fma_f32 v[252:253], v[238:239], v[254:255], 1.0 op_sel_hi:[1,1,0] neg_lo:[1,0,0] neg_hi:[1,0,0]
	v_pk_fma_f32 v[248:249], v[246:247], v[244:245], v[248:249]
	v_pk_fma_f32 v[254:255], v[252:253], v[250:251], v[254:255]
	v_div_fixup_f32 v236, v248, v236, 1.0
	v_div_fixup_f32 v237, v249, v237, 1.0
	v_div_fixup_f32 v238, v254, v238, 1.0
	v_div_fixup_f32 v239, v255, v239, 1.0
	v_rcp_f32_e32 v244, v240
	v_rcp_f32_e32 v245, v241
	v_rcp_f32_e32 v250, v242
	v_rcp_f32_e32 v251, v243
	v_pk_fma_f32 v[246:247], v[240:241], v[244:245], 1.0 op_sel_hi:[1,1,0] neg_lo:[1,0,0] neg_hi:[1,0,0]
	v_pk_fma_f32 v[252:253], v[242:243], v[250:251], 1.0 op_sel_hi:[1,1,0] neg_lo:[1,0,0] neg_hi:[1,0,0]
	v_pk_fma_f32 v[244:245], v[246:247], v[244:245], v[244:245]
	v_pk_fma_f32 v[250:251], v[252:253], v[250:251], v[250:251]
	v_pk_fma_f32 v[246:247], v[240:241], v[244:245], 1.0 op_sel_hi:[1,1,0] neg_lo:[1,0,0] neg_hi:[1,0,0]
	v_pk_fma_f32 v[252:253], v[242:243], v[250:251], 1.0 op_sel_hi:[1,1,0] neg_lo:[1,0,0] neg_hi:[1,0,0]
	v_pk_fma_f32 v[248:249], v[246:247], v[244:245], v[244:245]
	v_pk_fma_f32 v[254:255], v[252:253], v[250:251], v[250:251]
	v_pk_fma_f32 v[246:247], v[240:241], v[248:249], 1.0 op_sel_hi:[1,1,0] neg_lo:[1,0,0] neg_hi:[1,0,0]
	v_pk_fma_f32 v[252:253], v[242:243], v[254:255], 1.0 op_sel_hi:[1,1,0] neg_lo:[1,0,0] neg_hi:[1,0,0]
	v_pk_fma_f32 v[248:249], v[246:247], v[244:245], v[248:249]
	v_pk_fma_f32 v[254:255], v[252:253], v[250:251], v[254:255]
	v_div_fixup_f32 v240, v248, v240, 1.0
	v_div_fixup_f32 v241, v249, v241, 1.0
	v_div_fixup_f32 v242, v254, v242, 1.0
	v_div_fixup_f32 v243, v255, v243, 1.0
	global_store_dwordx4 v[80:81], v[72:75], off
	s_nop 0
	v_pk_mul_f32 v[68:69], v[68:69], v[236:237]
	v_pk_mul_f32 v[64:65], v[64:65], v[238:239]
	v_pk_mul_f32 v[70:71], v[70:71], v[240:241]
	v_pk_mul_f32 v[72:73], v[66:67], v[242:243]
	v_cvt_pk_bf16_f32 v66, v68, v69
	v_cvt_pk_bf16_f32 v67, v70, v71
	v_cvt_pk_bf16_f32 v68, v64, v65
	v_add_u32_e32 v64, 0x80, v160
	v_mad_i64_i32 v[64:65], s[6:7], v64, s61, v[146:147]
	v_lshl_add_u64 v[64:65], v[64:65], 0, v[148:149]
	v_add_co_u32_e32 v74, vcc, s62, v64
	v_cvt_pk_bf16_f32 v69, v72, v73
	global_store_dwordx4 v[80:81], v[66:69], off offset:256
	s_nop 0
	v_addc_co_u32_e32 v75, vcc, 0, v65, vcc
	s_waitcnt vmcnt(11)
	v_mov_b64_e32 v[70:71], v[208:209]
	v_mov_b64_e32 v[72:73], v[210:211]
	v_add_u32_e32 v199, 0x177a00, v198
	global_load_dwordx4 v[208:211], v199, s[24:25]
	s_mov_b32 s100, 0xbfb8aa3b
	v_lshlrev_b32_e32 v236, 16, v70
	v_and_b32_e32 v237, 0xffff0000, v70
	v_lshlrev_b32_e32 v238, 16, v72
	v_and_b32_e32 v239, 0xffff0000, v72
	v_lshlrev_b32_e32 v240, 16, v71
	v_and_b32_e32 v241, 0xffff0000, v71
	v_lshlrev_b32_e32 v242, 16, v73
	v_and_b32_e32 v243, 0xffff0000, v73
	v_pk_mul_f32 v[236:237], v[236:237], s[100:101] op_sel_hi:[1,0]
	v_pk_mul_f32 v[238:239], v[238:239], s[100:101] op_sel_hi:[1,0]
	v_pk_mul_f32 v[240:241], v[240:241], s[100:101] op_sel_hi:[1,0]
	v_pk_mul_f32 v[242:243], v[242:243], s[100:101] op_sel_hi:[1,0]
	v_exp_f32_e32 v236, v236
	v_exp_f32_e32 v237, v237
	v_exp_f32_e32 v238, v238
	v_exp_f32_e32 v239, v239
	v_exp_f32_e32 v240, v240
	v_exp_f32_e32 v241, v241
	v_exp_f32_e32 v242, v242
	v_exp_f32_e32 v243, v243
	s_nop 0
	v_pk_add_f32 v[236:237], v[236:237], 1.0 op_sel_hi:[1,0]
	v_pk_add_f32 v[238:239], v[238:239], 1.0 op_sel_hi:[1,0]
	v_pk_add_f32 v[240:241], v[240:241], 1.0 op_sel_hi:[1,0]
	v_pk_add_f32 v[242:243], v[242:243], 1.0 op_sel_hi:[1,0]
	v_rcp_f32_e32 v244, v236
	v_rcp_f32_e32 v245, v237
	v_rcp_f32_e32 v250, v238
	v_rcp_f32_e32 v251, v239
	v_pk_fma_f32 v[246:247], v[236:237], v[244:245], 1.0 op_sel_hi:[1,1,0] neg_lo:[1,0,0] neg_hi:[1,0,0]
	v_pk_fma_f32 v[252:253], v[238:239], v[250:251], 1.0 op_sel_hi:[1,1,0] neg_lo:[1,0,0] neg_hi:[1,0,0]
	v_pk_fma_f32 v[244:245], v[246:247], v[244:245], v[244:245]
	v_pk_fma_f32 v[250:251], v[252:253], v[250:251], v[250:251]
	v_pk_fma_f32 v[246:247], v[236:237], v[244:245], 1.0 op_sel_hi:[1,1,0] neg_lo:[1,0,0] neg_hi:[1,0,0]
	v_pk_fma_f32 v[252:253], v[238:239], v[250:251], 1.0 op_sel_hi:[1,1,0] neg_lo:[1,0,0] neg_hi:[1,0,0]
	v_pk_fma_f32 v[248:249], v[246:247], v[244:245], v[244:245]
	v_pk_fma_f32 v[254:255], v[252:253], v[250:251], v[250:251]
	v_pk_fma_f32 v[246:247], v[236:237], v[248:249], 1.0 op_sel_hi:[1,1,0] neg_lo:[1,0,0] neg_hi:[1,0,0]
	v_pk_fma_f32 v[252:253], v[238:239], v[254:255], 1.0 op_sel_hi:[1,1,0] neg_lo:[1,0,0] neg_hi:[1,0,0]
	v_pk_fma_f32 v[248:249], v[246:247], v[244:245], v[248:249]
	v_pk_fma_f32 v[254:255], v[252:253], v[250:251], v[254:255]
	v_div_fixup_f32 v236, v248, v236, 1.0
	v_div_fixup_f32 v237, v249, v237, 1.0
	v_div_fixup_f32 v238, v254, v238, 1.0
	v_div_fixup_f32 v239, v255, v239, 1.0
	v_rcp_f32_e32 v244, v240
	v_rcp_f32_e32 v245, v241
	v_rcp_f32_e32 v250, v242
	v_rcp_f32_e32 v251, v243
	v_pk_fma_f32 v[246:247], v[240:241], v[244:245], 1.0 op_sel_hi:[1,1,0] neg_lo:[1,0,0] neg_hi:[1,0,0]
	v_pk_fma_f32 v[252:253], v[242:243], v[250:251], 1.0 op_sel_hi:[1,1,0] neg_lo:[1,0,0] neg_hi:[1,0,0]
	v_pk_fma_f32 v[244:245], v[246:247], v[244:245], v[244:245]
	v_pk_fma_f32 v[250:251], v[252:253], v[250:251], v[250:251]
	v_pk_fma_f32 v[246:247], v[240:241], v[244:245], 1.0 op_sel_hi:[1,1,0] neg_lo:[1,0,0] neg_hi:[1,0,0]
	v_pk_fma_f32 v[252:253], v[242:243], v[250:251], 1.0 op_sel_hi:[1,1,0] neg_lo:[1,0,0] neg_hi:[1,0,0]
	v_pk_fma_f32 v[248:249], v[246:247], v[244:245], v[244:245]
	v_pk_fma_f32 v[254:255], v[252:253], v[250:251], v[250:251]
	v_pk_fma_f32 v[246:247], v[240:241], v[248:249], 1.0 op_sel_hi:[1,1,0] neg_lo:[1,0,0] neg_hi:[1,0,0]
	v_pk_fma_f32 v[252:253], v[242:243], v[254:255], 1.0 op_sel_hi:[1,1,0] neg_lo:[1,0,0] neg_hi:[1,0,0]
	v_pk_fma_f32 v[248:249], v[246:247], v[244:245], v[248:249]
	v_pk_fma_f32 v[254:255], v[252:253], v[250:251], v[254:255]
	v_div_fixup_f32 v240, v248, v240, 1.0
	v_div_fixup_f32 v241, v249, v241, 1.0
	v_div_fixup_f32 v242, v254, v242, 1.0
	v_div_fixup_f32 v243, v255, v243, 1.0
	v_mul_f32_e32 v60, v60, v236
	v_mul_f32_e32 v66, v56, v238
	v_mul_f32_e32 v56, v61, v237
	v_mul_f32_e32 v61, v57, v239
	v_mul_f32_e32 v57, v62, v240
	v_mul_f32_e32 v62, v58, v242
	v_mul_f32_e32 v58, v63, v241
	v_mul_f32_e32 v59, v59, v243
	v_cvt_pk_bf16_f32 v56, v60, v56
	v_cvt_pk_bf16_f32 v57, v57, v58
	v_cvt_pk_bf16_f32 v58, v66, v61
	v_cvt_pk_bf16_f32 v59, v62, v59
	s_waitcnt vmcnt(11)
; __device__ __forceinline__ float sigmoidf_(float x) { return 1.0f / (1.0f + __expf(-x)); }
; __device__ __forceinline__ u32x4 pack8(const f32x4 v0, const f32x4 v1) { u32x4 w; w.x = pk2(v0[0], v0[1]); w.y = pk2(v0[2], v0[3]); w.z = pk2(v1[0], v1[1]); w.w = pk2(v1[2], v1[3]); return w; }
; __device__ __forceinline__ void unpack8(const u32x4 w, f32x4& v0, f32x4& v1) { v0 = (f32x4){bflo(w.x), bfhi(w.x), bflo(w.y), bfhi(w.y)}; v1 = (f32x4){bflo(w.z), bfhi(w.z), bflo(w.w), bfhi(w.w)}; }
;     __device__ __forceinline__ void operator()(const f32x4 (&acc)[2][2][4][2], const Unit& u, int wr, int wc, int fr, int fq) const {
;     ...
; #pragma unroll
;         for (int ai = 0; ai < 2; ++ai)
; #pragma unroll
;             for (int m = 0; m < 4; ++m) {
;                 bf16_t* rowp = z + (size_t)(row0 + ai * 128 + m * 16) * DIN + col0;
; #pragma unroll
;                 for (int bj = 0; bj < 2; ++bj) {
;                     const u32x4 gw = *(const u32x4*)(rowp + (MODE == 0 ? O_GB : O_GA) + bj * 128);
;                     f32x4 g0, g1; unpack8(gw, g0, g1);
;                     f32x4 v0, v1;
; #pragma unroll
;                     for (int j = 0; j < 4; ++j) { v0[j] = sigmoidf_(g0[j]) * acc[ai][bj][m][0][j]; v1[j] = sigmoidf_(g1[j]) * acc[ai][bj][m][1][j]; }
;                     if (MODE == 1) { const u32x4 mw = *(const u32x4*)(rowp + bj * 128); f32x4 m0, m1; unpack8(mw, m0, m1); v0 += m0; v1 += m1; }
;                     *(u32x4*)(rowp + bj * 128) = pack8(v0, v1); }
	v_mov_b32_e32 v60, v212
	v_mov_b32_e32 v61, v213
	v_mov_b64_e32 v[62:63], v[214:215]
	v_add_u32_e32 v199, 0x177b00, v198
	global_load_dwordx4 v[212:215], v199, s[24:25]
	s_mov_b32 s100, 0xbfb8aa3b
	v_lshlrev_b32_e32 v236, 16, v60
	v_and_b32_e32 v237, 0xffff0000, v60
	v_lshlrev_b32_e32 v238, 16, v62
	v_and_b32_e32 v239, 0xffff0000, v62
	v_lshlrev_b32_e32 v240, 16, v61
	v_and_b32_e32 v241, 0xffff0000, v61
	v_lshlrev_b32_e32 v242, 16, v63
	v_and_b32_e32 v243, 0xffff0000, v63
	v_pk_mul_f32 v[236:237], v[236:237], s[100:101] op_sel_hi:[1,0]
	v_pk_mul_f32 v[238:239], v[238:239], s[100:101] op_sel_hi:[1,0]
	v_pk_mul_f32 v[240:241], v[240:241], s[100:101] op_sel_hi:[1,0]
	v_pk_mul_f32 v[242:243], v[242:243], s[100:101] op_sel_hi:[1,0]
	v_exp_f32_e32 v236, v236
	v_exp_f32_e32 v237, v237
	v_exp_f32_e32 v238, v238
	v_exp_f32_e32 v239, v239
	v_exp_f32_e32 v240, v240
	v_exp_f32_e32 v241, v241
	v_exp_f32_e32 v242, v242
	v_exp_f32_e32 v243, v243
	s_nop 0
	v_pk_add_f32 v[236:237], v[236:237], 1.0 op_sel_hi:[1,0]
	v_pk_add_f32 v[238:239], v[238:239], 1.0 op_sel_hi:[1,0]
	v_pk_add_f32 v[240:241], v[240:241], 1.0 op_sel_hi:[1,0]
	v_pk_add_f32 v[242:243], v[242:243], 1.0 op_sel_hi:[1,0]
	v_rcp_f32_e32 v244, v236
	v_rcp_f32_e32 v245, v237
	v_rcp_f32_e32 v250, v238
	v_rcp_f32_e32 v251, v239
	v_pk_fma_f32 v[246:247], v[236:237], v[244:245], 1.0 op_sel_hi:[1,1,0] neg_lo:[1,0,0] neg_hi:[1,0,0]
	v_pk_fma_f32 v[252:253], v[238:239], v[250:251], 1.0 op_sel_hi:[1,1,0] neg_lo:[1,0,0] neg_hi:[1,0,0]
	v_pk_fma_f32 v[244:245], v[246:247], v[244:245], v[244:245]
	v_pk_fma_f32 v[250:251], v[252:253], v[250:251], v[250:251]
	v_pk_fma_f32 v[246:247], v[236:237], v[244:245], 1.0 op_sel_hi:[1,1,0] neg_lo:[1,0,0] neg_hi:[1,0,0]
	v_pk_fma_f32 v[252:253], v[238:239], v[250:251], 1.0 op_sel_hi:[1,1,0] neg_lo:[1,0,0] neg_hi:[1,0,0]
	v_pk_fma_f32 v[248:249], v[246:247], v[244:245], v[244:245]
	v_pk_fma_f32 v[254:255], v[252:253], v[250:251], v[250:251]
	v_pk_fma_f32 v[246:247], v[236:237], v[248:249], 1.0 op_sel_hi:[1,1,0] neg_lo:[1,0,0] neg_hi:[1,0,0]
	v_pk_fma_f32 v[252:253], v[238:239], v[254:255], 1.0 op_sel_hi:[1,1,0] neg_lo:[1,0,0] neg_hi:[1,0,0]
	v_pk_fma_f32 v[248:249], v[246:247], v[244:245], v[248:249]
	v_pk_fma_f32 v[254:255], v[252:253], v[250:251], v[254:255]
	v_div_fixup_f32 v236, v248, v236, 1.0
	v_div_fixup_f32 v237, v249, v237, 1.0
	v_div_fixup_f32 v238, v254, v238, 1.0
	v_div_fixup_f32 v239, v255, v239, 1.0
	v_rcp_f32_e32 v244, v240
	v_rcp_f32_e32 v245, v241
	v_rcp_f32_e32 v250, v242
	v_rcp_f32_e32 v251, v243
	v_pk_fma_f32 v[246:247], v[240:241], v[244:245], 1.0 op_sel_hi:[1,1,0] neg_lo:[1,0,0] neg_hi:[1,0,0]
	v_pk_fma_f32 v[252:253], v[242:243], v[250:251], 1.0 op_sel_hi:[1,1,0] neg_lo:[1,0,0] neg_hi:[1,0,0]
	v_pk_fma_f32 v[244:245], v[246:247], v[244:245], v[244:245]
	v_pk_fma_f32 v[250:251], v[252:253], v[250:251], v[250:251]
	v_pk_fma_f32 v[246:247], v[240:241], v[244:245], 1.0 op_sel_hi:[1,1,0] neg_lo:[1,0,0] neg_hi:[1,0,0]
	v_pk_fma_f32 v[252:253], v[242:243], v[250:251], 1.0 op_sel_hi:[1,1,0] neg_lo:[1,0,0] neg_hi:[1,0,0]
	v_pk_fma_f32 v[248:249], v[246:247], v[244:245], v[244:245]
	v_pk_fma_f32 v[254:255], v[252:253], v[250:251], v[250:251]
	v_pk_fma_f32 v[246:247], v[240:241], v[248:249], 1.0 op_sel_hi:[1,1,0] neg_lo:[1,0,0] neg_hi:[1,0,0]
	v_pk_fma_f32 v[252:253], v[242:243], v[254:255], 1.0 op_sel_hi:[1,1,0] neg_lo:[1,0,0] neg_hi:[1,0,0]
	v_pk_fma_f32 v[248:249], v[246:247], v[244:245], v[248:249]
	v_pk_fma_f32 v[254:255], v[252:253], v[250:251], v[254:255]
	v_div_fixup_f32 v240, v248, v240, 1.0
	v_div_fixup_f32 v241, v249, v241, 1.0
	v_div_fixup_f32 v242, v254, v242, 1.0
	v_div_fixup_f32 v243, v255, v243, 1.0
	global_store_dwordx4 v[64:65], v[56:59], off
	s_nop 0
	v_pk_mul_f32 v[52:53], v[52:53], v[236:237]
	v_pk_mul_f32 v[48:49], v[48:49], v[238:239]
	v_pk_mul_f32 v[54:55], v[54:55], v[240:241]
	v_pk_mul_f32 v[56:57], v[50:51], v[242:243]
	v_cvt_pk_bf16_f32 v50, v52, v53
	v_cvt_pk_bf16_f32 v51, v54, v55
	v_cvt_pk_bf16_f32 v52, v48, v49
	v_add_u32_e32 v48, 0x90, v160
	v_mad_i64_i32 v[48:49], s[6:7], v48, s61, v[146:147]
	v_lshl_add_u64 v[48:49], v[48:49], 0, v[148:149]
	v_add_co_u32_e32 v58, vcc, s62, v48
	v_cvt_pk_bf16_f32 v53, v56, v57
	global_store_dwordx4 v[64:65], v[50:53], off offset:256
	s_nop 0
	v_addc_co_u32_e32 v59, vcc, 0, v49, vcc
	s_waitcnt vmcnt(11)
; __device__ __forceinline__ float sigmoidf_(float x) { return 1.0f / (1.0f + __expf(-x)); }
; __device__ __forceinline__ u32x4 pack8(const f32x4 v0, const f32x4 v1) { u32x4 w; w.x = pk2(v0[0], v0[1]); w.y = pk2(v0[2], v0[3]); w.z = pk2(v1[0], v1[1]); w.w = pk2(v1[2], v1[3]); return w; }
; __device__ __forceinline__ void unpack8(const u32x4 w, f32x4& v0, f32x4& v1) { v0 = (f32x4){bflo(w.x), bfhi(w.x), bflo(w.y), bfhi(w.y)}; v1 = (f32x4){bflo(w.z), bfhi(w.z), bflo(w.w), bfhi(w.w)}; }
;     __device__ __forceinline__ void operator()(const f32x4 (&acc)[2][2][4][2], const Unit& u, int wr, int wc, int fr, int fq) const {
;     ...
; #pragma unroll
;         for (int ai = 0; ai < 2; ++ai)
; #pragma unroll
;             for (int m = 0; m < 4; ++m) {
;                 bf16_t* rowp = z + (size_t)(row0 + ai * 128 + m * 16) * DIN + col0;
; #pragma unroll
;                 for (int bj = 0; bj < 2; ++bj) {
;                     const u32x4 gw = *(const u32x4*)(rowp + (MODE == 0 ? O_GB : O_GA) + bj * 128);
;                     f32x4 g0, g1; unpack8(gw, g0, g1);
;                     f32x4 v0, v1;
; #pragma unroll
;                     for (int j = 0; j < 4; ++j) { v0[j] = sigmoidf_(g0[j]) * acc[ai][bj][m][0][j]; v1[j] = sigmoidf_(g1[j]) * acc[ai][bj][m][1][j]; }
;                     if (MODE == 1) { const u32x4 mw = *(const u32x4*)(rowp + bj * 128); f32x4 m0, m1; unpack8(mw, m0, m1); v0 += m0; v1 += m1; }
;                     *(u32x4*)(rowp + bj * 128) = pack8(v0, v1); }
	v_mov_b64_e32 v[54:55], v[216:217]
	v_mov_b64_e32 v[56:57], v[218:219]
	s_mov_b32 s100, 0xbfb8aa3b
	v_lshlrev_b32_e32 v236, 16, v54
	v_and_b32_e32 v237, 0xffff0000, v54
	v_lshlrev_b32_e32 v238, 16, v56
	v_and_b32_e32 v239, 0xffff0000, v56
	v_lshlrev_b32_e32 v240, 16, v55
	v_and_b32_e32 v241, 0xffff0000, v55
	v_lshlrev_b32_e32 v242, 16, v57
	v_and_b32_e32 v243, 0xffff0000, v57
	v_pk_mul_f32 v[236:237], v[236:237], s[100:101] op_sel_hi:[1,0]
	v_pk_mul_f32 v[238:239], v[238:239], s[100:101] op_sel_hi:[1,0]
	v_pk_mul_f32 v[240:241], v[240:241], s[100:101] op_sel_hi:[1,0]
	v_pk_mul_f32 v[242:243], v[242:243], s[100:101] op_sel_hi:[1,0]
	v_exp_f32_e32 v236, v236
	v_exp_f32_e32 v237, v237
	v_exp_f32_e32 v238, v238
	v_exp_f32_e32 v239, v239
	v_exp_f32_e32 v240, v240
	v_exp_f32_e32 v241, v241
	v_exp_f32_e32 v242, v242
	v_exp_f32_e32 v243, v243
	s_nop 0
	v_pk_add_f32 v[236:237], v[236:237], 1.0 op_sel_hi:[1,0]
	v_pk_add_f32 v[238:239], v[238:239], 1.0 op_sel_hi:[1,0]
	v_pk_add_f32 v[240:241], v[240:241], 1.0 op_sel_hi:[1,0]
	v_pk_add_f32 v[242:243], v[242:243], 1.0 op_sel_hi:[1,0]
	v_rcp_f32_e32 v244, v236
	v_rcp_f32_e32 v245, v237
	v_rcp_f32_e32 v250, v238
	v_rcp_f32_e32 v251, v239
	v_pk_fma_f32 v[246:247], v[236:237], v[244:245], 1.0 op_sel_hi:[1,1,0] neg_lo:[1,0,0] neg_hi:[1,0,0]
	v_pk_fma_f32 v[252:253], v[238:239], v[250:251], 1.0 op_sel_hi:[1,1,0] neg_lo:[1,0,0] neg_hi:[1,0,0]
	v_pk_fma_f32 v[244:245], v[246:247], v[244:245], v[244:245]
	v_pk_fma_f32 v[250:251], v[252:253], v[250:251], v[250:251]
	v_pk_fma_f32 v[246:247], v[236:237], v[244:245], 1.0 op_sel_hi:[1,1,0] neg_lo:[1,0,0] neg_hi:[1,0,0]
	v_pk_fma_f32 v[252:253], v[238:239], v[250:251], 1.0 op_sel_hi:[1,1,0] neg_lo:[1,0,0] neg_hi:[1,0,0]
	v_pk_fma_f32 v[248:249], v[246:247], v[244:245], v[244:245]
	v_pk_fma_f32 v[254:255], v[252:253], v[250:251], v[250:251]
	v_pk_fma_f32 v[246:247], v[236:237], v[248:249], 1.0 op_sel_hi:[1,1,0] neg_lo:[1,0,0] neg_hi:[1,0,0]
	v_pk_fma_f32 v[252:253], v[238:239], v[254:255], 1.0 op_sel_hi:[1,1,0] neg_lo:[1,0,0] neg_hi:[1,0,0]
	v_pk_fma_f32 v[248:249], v[246:247], v[244:245], v[248:249]
	v_pk_fma_f32 v[254:255], v[252:253], v[250:251], v[254:255]
	v_div_fixup_f32 v236, v248, v236, 1.0
	v_div_fixup_f32 v237, v249, v237, 1.0
	v_div_fixup_f32 v238, v254, v238, 1.0
	v_div_fixup_f32 v239, v255, v239, 1.0
	v_rcp_f32_e32 v244, v240
	v_rcp_f32_e32 v245, v241
	v_rcp_f32_e32 v250, v242
	v_rcp_f32_e32 v251, v243
	v_pk_fma_f32 v[246:247], v[240:241], v[244:245], 1.0 op_sel_hi:[1,1,0] neg_lo:[1,0,0] neg_hi:[1,0,0]
	v_pk_fma_f32 v[252:253], v[242:243], v[250:251], 1.0 op_sel_hi:[1,1,0] neg_lo:[1,0,0] neg_hi:[1,0,0]
	v_pk_fma_f32 v[244:245], v[246:247], v[244:245], v[244:245]
	v_pk_fma_f32 v[250:251], v[252:253], v[250:251], v[250:251]
	v_pk_fma_f32 v[246:247], v[240:241], v[244:245], 1.0 op_sel_hi:[1,1,0] neg_lo:[1,0,0] neg_hi:[1,0,0]
	v_pk_fma_f32 v[252:253], v[242:243], v[250:251], 1.0 op_sel_hi:[1,1,0] neg_lo:[1,0,0] neg_hi:[1,0,0]
	v_pk_fma_f32 v[248:249], v[246:247], v[244:245], v[244:245]
	v_pk_fma_f32 v[254:255], v[252:253], v[250:251], v[250:251]
	v_pk_fma_f32 v[246:247], v[240:241], v[248:249], 1.0 op_sel_hi:[1,1,0] neg_lo:[1,0,0] neg_hi:[1,0,0]
	v_pk_fma_f32 v[252:253], v[242:243], v[254:255], 1.0 op_sel_hi:[1,1,0] neg_lo:[1,0,0] neg_hi:[1,0,0]
	v_pk_fma_f32 v[248:249], v[246:247], v[244:245], v[248:249]
	v_pk_fma_f32 v[254:255], v[252:253], v[250:251], v[254:255]
	v_div_fixup_f32 v240, v248, v240, 1.0
	v_div_fixup_f32 v241, v249, v241, 1.0
	v_div_fixup_f32 v242, v254, v242, 1.0
	v_div_fixup_f32 v243, v255, v243, 1.0
	v_mul_f32_e32 v44, v44, v236
	v_mul_f32_e32 v50, v40, v238
	v_mul_f32_e32 v40, v45, v237
	v_mul_f32_e32 v45, v41, v239
	v_mul_f32_e32 v41, v46, v240
	v_mul_f32_e32 v46, v42, v242
	v_mul_f32_e32 v42, v47, v241
	v_mul_f32_e32 v43, v43, v243
	v_cvt_pk_bf16_f32 v40, v44, v40
	v_cvt_pk_bf16_f32 v41, v41, v42
	v_cvt_pk_bf16_f32 v42, v50, v45
	v_cvt_pk_bf16_f32 v43, v46, v43
	s_waitcnt vmcnt(10)
	v_mov_b32_e32 v44, v232
	v_mov_b32_e32 v45, v233
	v_mov_b64_e32 v[46:47], v[234:235]
	s_mov_b32 s100, 0xbfb8aa3b
	v_lshlrev_b32_e32 v236, 16, v44
	v_and_b32_e32 v237, 0xffff0000, v44
	v_lshlrev_b32_e32 v238, 16, v46
	v_and_b32_e32 v239, 0xffff0000, v46
	v_lshlrev_b32_e32 v240, 16, v45
	v_and_b32_e32 v241, 0xffff0000, v45
	v_lshlrev_b32_e32 v242, 16, v47
	v_and_b32_e32 v243, 0xffff0000, v47
	v_pk_mul_f32 v[236:237], v[236:237], s[100:101] op_sel_hi:[1,0]
	v_pk_mul_f32 v[238:239], v[238:239], s[100:101] op_sel_hi:[1,0]
	v_pk_mul_f32 v[240:241], v[240:241], s[100:101] op_sel_hi:[1,0]
	v_pk_mul_f32 v[242:243], v[242:243], s[100:101] op_sel_hi:[1,0]
	v_exp_f32_e32 v236, v236
	v_exp_f32_e32 v237, v237
	v_exp_f32_e32 v238, v238
	v_exp_f32_e32 v239, v239
	v_exp_f32_e32 v240, v240
	v_exp_f32_e32 v241, v241
	v_exp_f32_e32 v242, v242
	v_exp_f32_e32 v243, v243
	s_nop 0
	v_pk_add_f32 v[236:237], v[236:237], 1.0 op_sel_hi:[1,0]
	v_pk_add_f32 v[238:239], v[238:239], 1.0 op_sel_hi:[1,0]
	v_pk_add_f32 v[240:241], v[240:241], 1.0 op_sel_hi:[1,0]
	v_pk_add_f32 v[242:243], v[242:243], 1.0 op_sel_hi:[1,0]
	v_rcp_f32_e32 v244, v236
	v_rcp_f32_e32 v245, v237
	v_rcp_f32_e32 v250, v238
	v_rcp_f32_e32 v251, v239
	v_pk_fma_f32 v[246:247], v[236:237], v[244:245], 1.0 op_sel_hi:[1,1,0] neg_lo:[1,0,0] neg_hi:[1,0,0]
	v_pk_fma_f32 v[252:253], v[238:239], v[250:251], 1.0 op_sel_hi:[1,1,0] neg_lo:[1,0,0] neg_hi:[1,0,0]
	v_pk_fma_f32 v[244:245], v[246:247], v[244:245], v[244:245]
	v_pk_fma_f32 v[250:251], v[252:253], v[250:251], v[250:251]
	v_pk_fma_f32 v[246:247], v[236:237], v[244:245], 1.0 op_sel_hi:[1,1,0] neg_lo:[1,0,0] neg_hi:[1,0,0]
; __device__ __forceinline__ float sigmoidf_(float x) { return 1.0f / (1.0f + __expf(-x)); }
; __device__ __forceinline__ u32x4 pack8(const f32x4 v0, const f32x4 v1) { u32x4 w; w.x = pk2(v0[0], v0[1]); w.y = pk2(v0[2], v0[3]); w.z = pk2(v1[0], v1[1]); w.w = pk2(v1[2], v1[3]); return w; }
; __device__ __forceinline__ void unpack8(const u32x4 w, f32x4& v0, f32x4& v1) { v0 = (f32x4){bflo(w.x), bfhi(w.x), bflo(w.y), bfhi(w.y)}; v1 = (f32x4){bflo(w.z), bfhi(w.z), bflo(w.w), bfhi(w.w)}; }
;     __device__ __forceinline__ void operator()(const f32x4 (&acc)[2][2][4][2], const Unit& u, int wr, int wc, int fr, int fq) const {
;     ...
; #pragma unroll
;         for (int ai = 0; ai < 2; ++ai)
; #pragma unroll
;             for (int m = 0; m < 4; ++m) {
;                 bf16_t* rowp = z + (size_t)(row0 + ai * 128 + m * 16) * DIN + col0;
; #pragma unroll
;                 for (int bj = 0; bj < 2; ++bj) {
;                     const u32x4 gw = *(const u32x4*)(rowp + (MODE == 0 ? O_GB : O_GA) + bj * 128);
;                     f32x4 g0, g1; unpack8(gw, g0, g1);
;                     f32x4 v0, v1;
; #pragma unroll
;                     for (int j = 0; j < 4; ++j) { v0[j] = sigmoidf_(g0[j]) * acc[ai][bj][m][0][j]; v1[j] = sigmoidf_(g1[j]) * acc[ai][bj][m][1][j]; }
;                     if (MODE == 1) { const u32x4 mw = *(const u32x4*)(rowp + bj * 128); f32x4 m0, m1; unpack8(mw, m0, m1); v0 += m0; v1 += m1; }
;                     *(u32x4*)(rowp + bj * 128) = pack8(v0, v1); }
	v_pk_fma_f32 v[252:253], v[238:239], v[250:251], 1.0 op_sel_hi:[1,1,0] neg_lo:[1,0,0] neg_hi:[1,0,0]
	v_pk_fma_f32 v[248:249], v[246:247], v[244:245], v[244:245]
	v_pk_fma_f32 v[254:255], v[252:253], v[250:251], v[250:251]
	v_pk_fma_f32 v[246:247], v[236:237], v[248:249], 1.0 op_sel_hi:[1,1,0] neg_lo:[1,0,0] neg_hi:[1,0,0]
	v_pk_fma_f32 v[252:253], v[238:239], v[254:255], 1.0 op_sel_hi:[1,1,0] neg_lo:[1,0,0] neg_hi:[1,0,0]
	v_pk_fma_f32 v[248:249], v[246:247], v[244:245], v[248:249]
	v_pk_fma_f32 v[254:255], v[252:253], v[250:251], v[254:255]
	v_div_fixup_f32 v236, v248, v236, 1.0
	v_div_fixup_f32 v237, v249, v237, 1.0
	v_div_fixup_f32 v238, v254, v238, 1.0
	v_div_fixup_f32 v239, v255, v239, 1.0
	v_rcp_f32_e32 v244, v240
	v_rcp_f32_e32 v245, v241
	v_rcp_f32_e32 v250, v242
	v_rcp_f32_e32 v251, v243
	v_pk_fma_f32 v[246:247], v[240:241], v[244:245], 1.0 op_sel_hi:[1,1,0] neg_lo:[1,0,0] neg_hi:[1,0,0]
	v_pk_fma_f32 v[252:253], v[242:243], v[250:251], 1.0 op_sel_hi:[1,1,0] neg_lo:[1,0,0] neg_hi:[1,0,0]
	v_pk_fma_f32 v[244:245], v[246:247], v[244:245], v[244:245]
	v_pk_fma_f32 v[250:251], v[252:253], v[250:251], v[250:251]
	v_pk_fma_f32 v[246:247], v[240:241], v[244:245], 1.0 op_sel_hi:[1,1,0] neg_lo:[1,0,0] neg_hi:[1,0,0]
	v_pk_fma_f32 v[252:253], v[242:243], v[250:251], 1.0 op_sel_hi:[1,1,0] neg_lo:[1,0,0] neg_hi:[1,0,0]
	v_pk_fma_f32 v[248:249], v[246:247], v[244:245], v[244:245]
	v_pk_fma_f32 v[254:255], v[252:253], v[250:251], v[250:251]
	v_pk_fma_f32 v[246:247], v[240:241], v[248:249], 1.0 op_sel_hi:[1,1,0] neg_lo:[1,0,0] neg_hi:[1,0,0]
	v_pk_fma_f32 v[252:253], v[242:243], v[254:255], 1.0 op_sel_hi:[1,1,0] neg_lo:[1,0,0] neg_hi:[1,0,0]
	v_pk_fma_f32 v[248:249], v[246:247], v[244:245], v[248:249]
	v_pk_fma_f32 v[254:255], v[252:253], v[250:251], v[254:255]
	v_div_fixup_f32 v240, v248, v240, 1.0
	v_div_fixup_f32 v241, v249, v241, 1.0
	v_div_fixup_f32 v242, v254, v242, 1.0
	v_div_fixup_f32 v243, v255, v243, 1.0
	global_store_dwordx4 v[48:49], v[40:43], off
	s_nop 0
	v_pk_mul_f32 v[36:37], v[36:37], v[236:237]
	v_pk_mul_f32 v[32:33], v[32:33], v[238:239]
	v_pk_mul_f32 v[38:39], v[38:39], v[240:241]
	v_pk_mul_f32 v[40:41], v[34:35], v[242:243]
	v_cvt_pk_bf16_f32 v34, v36, v37
	v_cvt_pk_bf16_f32 v35, v38, v39
	v_cvt_pk_bf16_f32 v36, v32, v33
	v_add_u32_e32 v32, 0xa0, v160
	v_mad_i64_i32 v[32:33], s[6:7], v32, s61, v[146:147]
	v_lshl_add_u64 v[32:33], v[32:33], 0, v[148:149]
	v_add_co_u32_e32 v42, vcc, s62, v32
	v_cvt_pk_bf16_f32 v37, v40, v41
	global_store_dwordx4 v[48:49], v[34:37], off offset:256
	s_nop 0
	v_addc_co_u32_e32 v43, vcc, 0, v33, vcc
	s_waitcnt vmcnt(9)
	v_mov_b64_e32 v[38:39], v[200:201]
	v_mov_b64_e32 v[40:41], v[202:203]
	s_mov_b32 s100, 0xbfb8aa3b
	v_lshlrev_b32_e32 v236, 16, v38
	v_and_b32_e32 v237, 0xffff0000, v38
	v_lshlrev_b32_e32 v238, 16, v40
	v_and_b32_e32 v239, 0xffff0000, v40
	v_lshlrev_b32_e32 v240, 16, v39
	v_and_b32_e32 v241, 0xffff0000, v39
	v_lshlrev_b32_e32 v242, 16, v41
	v_and_b32_e32 v243, 0xffff0000, v41
	v_pk_mul_f32 v[236:237], v[236:237], s[100:101] op_sel_hi:[1,0]
	v_pk_mul_f32 v[238:239], v[238:239], s[100:101] op_sel_hi:[1,0]
	v_pk_mul_f32 v[240:241], v[240:241], s[100:101] op_sel_hi:[1,0]
	v_pk_mul_f32 v[242:243], v[242:243], s[100:101] op_sel_hi:[1,0]
	v_exp_f32_e32 v236, v236
	v_exp_f32_e32 v237, v237
	v_exp_f32_e32 v238, v238
	v_exp_f32_e32 v239, v239
	v_exp_f32_e32 v240, v240
	v_exp_f32_e32 v241, v241
	v_exp_f32_e32 v242, v242
	v_exp_f32_e32 v243, v243
	s_nop 0
	v_pk_add_f32 v[236:237], v[236:237], 1.0 op_sel_hi:[1,0]
	v_pk_add_f32 v[238:239], v[238:239], 1.0 op_sel_hi:[1,0]
	v_pk_add_f32 v[240:241], v[240:241], 1.0 op_sel_hi:[1,0]
	v_pk_add_f32 v[242:243], v[242:243], 1.0 op_sel_hi:[1,0]
	v_rcp_f32_e32 v244, v236
	v_rcp_f32_e32 v245, v237
	v_rcp_f32_e32 v250, v238
	v_rcp_f32_e32 v251, v239
	v_pk_fma_f32 v[246:247], v[236:237], v[244:245], 1.0 op_sel_hi:[1,1,0] neg_lo:[1,0,0] neg_hi:[1,0,0]
	v_pk_fma_f32 v[252:253], v[238:239], v[250:251], 1.0 op_sel_hi:[1,1,0] neg_lo:[1,0,0] neg_hi:[1,0,0]
	v_pk_fma_f32 v[244:245], v[246:247], v[244:245], v[244:245]
	v_pk_fma_f32 v[250:251], v[252:253], v[250:251], v[250:251]
	v_pk_fma_f32 v[246:247], v[236:237], v[244:245], 1.0 op_sel_hi:[1,1,0] neg_lo:[1,0,0] neg_hi:[1,0,0]
	v_pk_fma_f32 v[252:253], v[238:239], v[250:251], 1.0 op_sel_hi:[1,1,0] neg_lo:[1,0,0] neg_hi:[1,0,0]
	v_pk_fma_f32 v[248:249], v[246:247], v[244:245], v[244:245]
	v_pk_fma_f32 v[254:255], v[252:253], v[250:251], v[250:251]
	v_pk_fma_f32 v[246:247], v[236:237], v[248:249], 1.0 op_sel_hi:[1,1,0] neg_lo:[1,0,0] neg_hi:[1,0,0]
	v_pk_fma_f32 v[252:253], v[238:239], v[254:255], 1.0 op_sel_hi:[1,1,0] neg_lo:[1,0,0] neg_hi:[1,0,0]
	v_pk_fma_f32 v[248:249], v[246:247], v[244:245], v[248:249]
	v_pk_fma_f32 v[254:255], v[252:253], v[250:251], v[254:255]
	v_div_fixup_f32 v236, v248, v236, 1.0
	v_div_fixup_f32 v237, v249, v237, 1.0
	v_div_fixup_f32 v238, v254, v238, 1.0
	v_div_fixup_f32 v239, v255, v239, 1.0
	v_rcp_f32_e32 v244, v240
	v_rcp_f32_e32 v245, v241
	v_rcp_f32_e32 v250, v242
	v_rcp_f32_e32 v251, v243
	v_pk_fma_f32 v[246:247], v[240:241], v[244:245], 1.0 op_sel_hi:[1,1,0] neg_lo:[1,0,0] neg_hi:[1,0,0]
	v_pk_fma_f32 v[252:253], v[242:243], v[250:251], 1.0 op_sel_hi:[1,1,0] neg_lo:[1,0,0] neg_hi:[1,0,0]
	v_pk_fma_f32 v[244:245], v[246:247], v[244:245], v[244:245]
	v_pk_fma_f32 v[250:251], v[252:253], v[250:251], v[250:251]
	v_pk_fma_f32 v[246:247], v[240:241], v[244:245], 1.0 op_sel_hi:[1,1,0] neg_lo:[1,0,0] neg_hi:[1,0,0]
	v_pk_fma_f32 v[252:253], v[242:243], v[250:251], 1.0 op_sel_hi:[1,1,0] neg_lo:[1,0,0] neg_hi:[1,0,0]
	v_pk_fma_f32 v[248:249], v[246:247], v[244:245], v[244:245]
	v_pk_fma_f32 v[254:255], v[252:253], v[250:251], v[250:251]
	v_pk_fma_f32 v[246:247], v[240:241], v[248:249], 1.0 op_sel_hi:[1,1,0] neg_lo:[1,0,0] neg_hi:[1,0,0]
	v_pk_fma_f32 v[252:253], v[242:243], v[254:255], 1.0 op_sel_hi:[1,1,0] neg_lo:[1,0,0] neg_hi:[1,0,0]
	v_pk_fma_f32 v[248:249], v[246:247], v[244:245], v[248:249]
	v_pk_fma_f32 v[254:255], v[252:253], v[250:251], v[254:255]
	v_div_fixup_f32 v240, v248, v240, 1.0
	v_div_fixup_f32 v241, v249, v241, 1.0
	v_div_fixup_f32 v242, v254, v242, 1.0
	v_div_fixup_f32 v243, v255, v243, 1.0
	v_mul_f32_e32 v28, v28, v236
	v_mul_f32_e32 v34, v24, v238
	v_mul_f32_e32 v24, v29, v237
	v_mul_f32_e32 v29, v25, v239
	v_mul_f32_e32 v25, v30, v240
	v_mul_f32_e32 v30, v26, v242
	v_mul_f32_e32 v26, v31, v241
	v_mul_f32_e32 v27, v27, v243
	v_cvt_pk_bf16_f32 v24, v28, v24
	v_cvt_pk_bf16_f32 v25, v25, v26
	v_cvt_pk_bf16_f32 v26, v34, v29
	v_cvt_pk_bf16_f32 v27, v30, v27
	s_waitcnt vmcnt(8)
; __device__ __forceinline__ float sigmoidf_(float x) { return 1.0f / (1.0f + __expf(-x)); }
; __device__ __forceinline__ u32x4 pack8(const f32x4 v0, const f32x4 v1) { u32x4 w; w.x = pk2(v0[0], v0[1]); w.y = pk2(v0[2], v0[3]); w.z = pk2(v1[0], v1[1]); w.w = pk2(v1[2], v1[3]); return w; }
; __device__ __forceinline__ void unpack8(const u32x4 w, f32x4& v0, f32x4& v1) { v0 = (f32x4){bflo(w.x), bfhi(w.x), bflo(w.y), bfhi(w.y)}; v1 = (f32x4){bflo(w.z), bfhi(w.z), bflo(w.w), bfhi(w.w)}; }
;     __device__ __forceinline__ void operator()(const f32x4 (&acc)[2][2][4][2], const Unit& u, int wr, int wc, int fr, int fq) const {
;     ...
; #pragma unroll
;         for (int ai = 0; ai < 2; ++ai)
; #pragma unroll
;             for (int m = 0; m < 4; ++m) {
;                 bf16_t* rowp = z + (size_t)(row0 + ai * 128 + m * 16) * DIN + col0;
; #pragma unroll
;                 for (int bj = 0; bj < 2; ++bj) {
;                     const u32x4 gw = *(const u32x4*)(rowp + (MODE == 0 ? O_GB : O_GA) + bj * 128);
;                     f32x4 g0, g1; unpack8(gw, g0, g1);
;                     f32x4 v0, v1;
; #pragma unroll
;                     for (int j = 0; j < 4; ++j) { v0[j] = sigmoidf_(g0[j]) * acc[ai][bj][m][0][j]; v1[j] = sigmoidf_(g1[j]) * acc[ai][bj][m][1][j]; }
;                     if (MODE == 1) { const u32x4 mw = *(const u32x4*)(rowp + bj * 128); f32x4 m0, m1; unpack8(mw, m0, m1); v0 += m0; v1 += m1; }
;                     *(u32x4*)(rowp + bj * 128) = pack8(v0, v1); }
	v_mov_b32_e32 v28, v204
	v_mov_b32_e32 v29, v205
	v_mov_b64_e32 v[30:31], v[206:207]
	s_mov_b32 s100, 0xbfb8aa3b
	v_lshlrev_b32_e32 v236, 16, v28
	v_and_b32_e32 v237, 0xffff0000, v28
	v_lshlrev_b32_e32 v238, 16, v30
	v_and_b32_e32 v239, 0xffff0000, v30
	v_lshlrev_b32_e32 v240, 16, v29
	v_and_b32_e32 v241, 0xffff0000, v29
	v_lshlrev_b32_e32 v242, 16, v31
	v_and_b32_e32 v243, 0xffff0000, v31
	v_pk_mul_f32 v[236:237], v[236:237], s[100:101] op_sel_hi:[1,0]
	v_pk_mul_f32 v[238:239], v[238:239], s[100:101] op_sel_hi:[1,0]
	v_pk_mul_f32 v[240:241], v[240:241], s[100:101] op_sel_hi:[1,0]
	v_pk_mul_f32 v[242:243], v[242:243], s[100:101] op_sel_hi:[1,0]
	v_exp_f32_e32 v236, v236
	v_exp_f32_e32 v237, v237
	v_exp_f32_e32 v238, v238
	v_exp_f32_e32 v239, v239
	v_exp_f32_e32 v240, v240
	v_exp_f32_e32 v241, v241
	v_exp_f32_e32 v242, v242
	v_exp_f32_e32 v243, v243
	s_nop 0
	v_pk_add_f32 v[236:237], v[236:237], 1.0 op_sel_hi:[1,0]
	v_pk_add_f32 v[238:239], v[238:239], 1.0 op_sel_hi:[1,0]
	v_pk_add_f32 v[240:241], v[240:241], 1.0 op_sel_hi:[1,0]
	v_pk_add_f32 v[242:243], v[242:243], 1.0 op_sel_hi:[1,0]
	v_rcp_f32_e32 v244, v236
	v_rcp_f32_e32 v245, v237
	v_rcp_f32_e32 v250, v238
	v_rcp_f32_e32 v251, v239
	v_pk_fma_f32 v[246:247], v[236:237], v[244:245], 1.0 op_sel_hi:[1,1,0] neg_lo:[1,0,0] neg_hi:[1,0,0]
	v_pk_fma_f32 v[252:253], v[238:239], v[250:251], 1.0 op_sel_hi:[1,1,0] neg_lo:[1,0,0] neg_hi:[1,0,0]
	v_pk_fma_f32 v[244:245], v[246:247], v[244:245], v[244:245]
	v_pk_fma_f32 v[250:251], v[252:253], v[250:251], v[250:251]
	v_pk_fma_f32 v[246:247], v[236:237], v[244:245], 1.0 op_sel_hi:[1,1,0] neg_lo:[1,0,0] neg_hi:[1,0,0]
	v_pk_fma_f32 v[252:253], v[238:239], v[250:251], 1.0 op_sel_hi:[1,1,0] neg_lo:[1,0,0] neg_hi:[1,0,0]
	v_pk_fma_f32 v[248:249], v[246:247], v[244:245], v[244:245]
	v_pk_fma_f32 v[254:255], v[252:253], v[250:251], v[250:251]
	v_pk_fma_f32 v[246:247], v[236:237], v[248:249], 1.0 op_sel_hi:[1,1,0] neg_lo:[1,0,0] neg_hi:[1,0,0]
	v_pk_fma_f32 v[252:253], v[238:239], v[254:255], 1.0 op_sel_hi:[1,1,0] neg_lo:[1,0,0] neg_hi:[1,0,0]
	v_pk_fma_f32 v[248:249], v[246:247], v[244:245], v[248:249]
	v_pk_fma_f32 v[254:255], v[252:253], v[250:251], v[254:255]
	v_div_fixup_f32 v236, v248, v236, 1.0
	v_div_fixup_f32 v237, v249, v237, 1.0
	v_div_fixup_f32 v238, v254, v238, 1.0
	v_div_fixup_f32 v239, v255, v239, 1.0
	v_rcp_f32_e32 v244, v240
	v_rcp_f32_e32 v245, v241
	v_rcp_f32_e32 v250, v242
	v_rcp_f32_e32 v251, v243
	v_pk_fma_f32 v[246:247], v[240:241], v[244:245], 1.0 op_sel_hi:[1,1,0] neg_lo:[1,0,0] neg_hi:[1,0,0]
	v_pk_fma_f32 v[252:253], v[242:243], v[250:251], 1.0 op_sel_hi:[1,1,0] neg_lo:[1,0,0] neg_hi:[1,0,0]
	v_pk_fma_f32 v[244:245], v[246:247], v[244:245], v[244:245]
	v_pk_fma_f32 v[250:251], v[252:253], v[250:251], v[250:251]
	v_pk_fma_f32 v[246:247], v[240:241], v[244:245], 1.0 op_sel_hi:[1,1,0] neg_lo:[1,0,0] neg_hi:[1,0,0]
	v_pk_fma_f32 v[252:253], v[242:243], v[250:251], 1.0 op_sel_hi:[1,1,0] neg_lo:[1,0,0] neg_hi:[1,0,0]
	v_pk_fma_f32 v[248:249], v[246:247], v[244:245], v[244:245]
	v_pk_fma_f32 v[254:255], v[252:253], v[250:251], v[250:251]
	v_pk_fma_f32 v[246:247], v[240:241], v[248:249], 1.0 op_sel_hi:[1,1,0] neg_lo:[1,0,0] neg_hi:[1,0,0]
	v_pk_fma_f32 v[252:253], v[242:243], v[254:255], 1.0 op_sel_hi:[1,1,0] neg_lo:[1,0,0] neg_hi:[1,0,0]
	v_pk_fma_f32 v[248:249], v[246:247], v[244:245], v[248:249]
	v_pk_fma_f32 v[254:255], v[252:253], v[250:251], v[254:255]
	v_div_fixup_f32 v240, v248, v240, 1.0
	v_div_fixup_f32 v241, v249, v241, 1.0
	v_div_fixup_f32 v242, v254, v242, 1.0
	v_div_fixup_f32 v243, v255, v243, 1.0
	global_store_dwordx4 v[32:33], v[24:27], off
	s_nop 0
	v_pk_mul_f32 v[20:21], v[20:21], v[236:237]
	v_pk_mul_f32 v[16:17], v[16:17], v[238:239]
	v_pk_mul_f32 v[22:23], v[22:23], v[240:241]
	v_pk_mul_f32 v[24:25], v[18:19], v[242:243]
	v_cvt_pk_bf16_f32 v18, v20, v21
	v_cvt_pk_bf16_f32 v19, v22, v23
	v_cvt_pk_bf16_f32 v20, v16, v17
	v_add_u32_e32 v16, 0xb0, v160
	v_mad_i64_i32 v[16:17], s[6:7], v16, s61, v[146:147]
	v_lshl_add_u64 v[16:17], v[16:17], 0, v[148:149]
	v_add_co_u32_e32 v26, vcc, s62, v16
	v_cvt_pk_bf16_f32 v21, v24, v25
	global_store_dwordx4 v[32:33], v[18:21], off offset:256
	s_nop 0
	v_addc_co_u32_e32 v27, vcc, 0, v17, vcc
	s_waitcnt vmcnt(7)
; __device__ __forceinline__ float sigmoidf_(float x) { return 1.0f / (1.0f + __expf(-x)); }
; __device__ __forceinline__ u32x4 pack8(const f32x4 v0, const f32x4 v1) { u32x4 w; w.x = pk2(v0[0], v0[1]); w.y = pk2(v0[2], v0[3]); w.z = pk2(v1[0], v1[1]); w.w = pk2(v1[2], v1[3]); return w; }
; __device__ __forceinline__ void unpack8(const u32x4 w, f32x4& v0, f32x4& v1) { v0 = (f32x4){bflo(w.x), bfhi(w.x), bflo(w.y), bfhi(w.y)}; v1 = (f32x4){bflo(w.z), bfhi(w.z), bflo(w.w), bfhi(w.w)}; }
;     __device__ __forceinline__ void operator()(const f32x4 (&acc)[2][2][4][2], const Unit& u, int wr, int wc, int fr, int fq) const {
;     ...
; #pragma unroll
;         for (int ai = 0; ai < 2; ++ai)
; #pragma unroll
;             for (int m = 0; m < 4; ++m) {
;                 bf16_t* rowp = z + (size_t)(row0 + ai * 128 + m * 16) * DIN + col0;
; #pragma unroll
;                 for (int bj = 0; bj < 2; ++bj) {
;                     const u32x4 gw = *(const u32x4*)(rowp + (MODE == 0 ? O_GB : O_GA) + bj * 128);
;                     f32x4 g0, g1; unpack8(gw, g0, g1);
;                     f32x4 v0, v1;
; #pragma unroll
;                     for (int j = 0; j < 4; ++j) { v0[j] = sigmoidf_(g0[j]) * acc[ai][bj][m][0][j]; v1[j] = sigmoidf_(g1[j]) * acc[ai][bj][m][1][j]; }
;                     if (MODE == 1) { const u32x4 mw = *(const u32x4*)(rowp + bj * 128); f32x4 m0, m1; unpack8(mw, m0, m1); v0 += m0; v1 += m1; }
;                     *(u32x4*)(rowp + bj * 128) = pack8(v0, v1); }
	v_mov_b64_e32 v[22:23], v[208:209]
	v_mov_b64_e32 v[24:25], v[210:211]
	s_mov_b32 s100, 0xbfb8aa3b
	v_lshlrev_b32_e32 v236, 16, v22
	v_and_b32_e32 v237, 0xffff0000, v22
	v_lshlrev_b32_e32 v238, 16, v24
	v_and_b32_e32 v239, 0xffff0000, v24
	v_lshlrev_b32_e32 v240, 16, v23
	v_and_b32_e32 v241, 0xffff0000, v23
	v_lshlrev_b32_e32 v242, 16, v25
	v_and_b32_e32 v243, 0xffff0000, v25
	v_pk_mul_f32 v[236:237], v[236:237], s[100:101] op_sel_hi:[1,0]
	v_pk_mul_f32 v[238:239], v[238:239], s[100:101] op_sel_hi:[1,0]
	v_pk_mul_f32 v[240:241], v[240:241], s[100:101] op_sel_hi:[1,0]
	v_pk_mul_f32 v[242:243], v[242:243], s[100:101] op_sel_hi:[1,0]
	v_exp_f32_e32 v236, v236
	v_exp_f32_e32 v237, v237
	v_exp_f32_e32 v238, v238
	v_exp_f32_e32 v239, v239
	v_exp_f32_e32 v240, v240
	v_exp_f32_e32 v241, v241
	v_exp_f32_e32 v242, v242
	v_exp_f32_e32 v243, v243
	s_nop 0
	v_pk_add_f32 v[236:237], v[236:237], 1.0 op_sel_hi:[1,0]
	v_pk_add_f32 v[238:239], v[238:239], 1.0 op_sel_hi:[1,0]
	v_pk_add_f32 v[240:241], v[240:241], 1.0 op_sel_hi:[1,0]
	v_pk_add_f32 v[242:243], v[242:243], 1.0 op_sel_hi:[1,0]
	v_rcp_f32_e32 v244, v236
	v_rcp_f32_e32 v245, v237
	v_rcp_f32_e32 v250, v238
	v_rcp_f32_e32 v251, v239
	v_pk_fma_f32 v[246:247], v[236:237], v[244:245], 1.0 op_sel_hi:[1,1,0] neg_lo:[1,0,0] neg_hi:[1,0,0]
	v_pk_fma_f32 v[252:253], v[238:239], v[250:251], 1.0 op_sel_hi:[1,1,0] neg_lo:[1,0,0] neg_hi:[1,0,0]
	v_pk_fma_f32 v[244:245], v[246:247], v[244:245], v[244:245]
	v_pk_fma_f32 v[250:251], v[252:253], v[250:251], v[250:251]
	v_pk_fma_f32 v[246:247], v[236:237], v[244:245], 1.0 op_sel_hi:[1,1,0] neg_lo:[1,0,0] neg_hi:[1,0,0]
	v_pk_fma_f32 v[252:253], v[238:239], v[250:251], 1.0 op_sel_hi:[1,1,0] neg_lo:[1,0,0] neg_hi:[1,0,0]
	v_pk_fma_f32 v[248:249], v[246:247], v[244:245], v[244:245]
	v_pk_fma_f32 v[254:255], v[252:253], v[250:251], v[250:251]
	v_pk_fma_f32 v[246:247], v[236:237], v[248:249], 1.0 op_sel_hi:[1,1,0] neg_lo:[1,0,0] neg_hi:[1,0,0]
	v_pk_fma_f32 v[252:253], v[238:239], v[254:255], 1.0 op_sel_hi:[1,1,0] neg_lo:[1,0,0] neg_hi:[1,0,0]
	v_pk_fma_f32 v[248:249], v[246:247], v[244:245], v[248:249]
	v_pk_fma_f32 v[254:255], v[252:253], v[250:251], v[254:255]
	v_div_fixup_f32 v236, v248, v236, 1.0
	v_div_fixup_f32 v237, v249, v237, 1.0
	v_div_fixup_f32 v238, v254, v238, 1.0
	v_div_fixup_f32 v239, v255, v239, 1.0
	v_rcp_f32_e32 v244, v240
	v_rcp_f32_e32 v245, v241
	v_rcp_f32_e32 v250, v242
	v_rcp_f32_e32 v251, v243
	v_pk_fma_f32 v[246:247], v[240:241], v[244:245], 1.0 op_sel_hi:[1,1,0] neg_lo:[1,0,0] neg_hi:[1,0,0]
	v_pk_fma_f32 v[252:253], v[242:243], v[250:251], 1.0 op_sel_hi:[1,1,0] neg_lo:[1,0,0] neg_hi:[1,0,0]
	v_pk_fma_f32 v[244:245], v[246:247], v[244:245], v[244:245]
	v_pk_fma_f32 v[250:251], v[252:253], v[250:251], v[250:251]
	v_pk_fma_f32 v[246:247], v[240:241], v[244:245], 1.0 op_sel_hi:[1,1,0] neg_lo:[1,0,0] neg_hi:[1,0,0]
	v_pk_fma_f32 v[252:253], v[242:243], v[250:251], 1.0 op_sel_hi:[1,1,0] neg_lo:[1,0,0] neg_hi:[1,0,0]
	v_pk_fma_f32 v[248:249], v[246:247], v[244:245], v[244:245]
	v_pk_fma_f32 v[254:255], v[252:253], v[250:251], v[250:251]
	v_pk_fma_f32 v[246:247], v[240:241], v[248:249], 1.0 op_sel_hi:[1,1,0] neg_lo:[1,0,0] neg_hi:[1,0,0]
	v_pk_fma_f32 v[252:253], v[242:243], v[254:255], 1.0 op_sel_hi:[1,1,0] neg_lo:[1,0,0] neg_hi:[1,0,0]
	v_pk_fma_f32 v[248:249], v[246:247], v[244:245], v[248:249]
	v_pk_fma_f32 v[254:255], v[252:253], v[250:251], v[254:255]
	v_div_fixup_f32 v240, v248, v240, 1.0
	v_div_fixup_f32 v241, v249, v241, 1.0
	v_div_fixup_f32 v242, v254, v242, 1.0
	v_div_fixup_f32 v243, v255, v243, 1.0
	v_mul_f32_e32 v12, v12, v236
	v_mul_f32_e32 v18, v8, v238
	v_mul_f32_e32 v8, v13, v237
	v_mul_f32_e32 v13, v9, v239
	v_mul_f32_e32 v9, v14, v240
	v_mul_f32_e32 v14, v10, v242
	v_mul_f32_e32 v10, v15, v241
	v_mul_f32_e32 v11, v11, v243
	v_cvt_pk_bf16_f32 v8, v12, v8
	v_cvt_pk_bf16_f32 v9, v9, v10
	v_cvt_pk_bf16_f32 v10, v18, v13
	v_cvt_pk_bf16_f32 v11, v14, v11
	s_waitcnt vmcnt(6)
; __device__ __forceinline__ float sigmoidf_(float x) { return 1.0f / (1.0f + __expf(-x)); }
; #define PG8_WAIT_V(n) asm volatile("s_waitcnt vmcnt(" #n ")" ::: "memory")
; #define PG8_BAR __builtin_amdgcn_s_barrier()
; __device__ __forceinline__ u32x4 pack8(const f32x4 v0, const f32x4 v1) { u32x4 w; w.x = pk2(v0[0], v0[1]); w.y = pk2(v0[2], v0[3]); w.z = pk2(v1[0], v1[1]); w.w = pk2(v1[2], v1[3]); return w; }
; __device__ __forceinline__ void unpack8(const u32x4 w, f32x4& v0, f32x4& v1) { v0 = (f32x4){bflo(w.x), bfhi(w.x), bflo(w.y), bfhi(w.y)}; v1 = (f32x4){bflo(w.z), bfhi(w.z), bflo(w.w), bfhi(w.w)}; }
;     ...
;         if (!has_next) break;
; #pragma unroll
;         for (int a = 0; a < 2; ++a)
; #pragma unroll
;             for (int b = 0; b < 2; ++b)
; #pragma unroll
;                 for (int m = 0; m < 4; ++m)
; #pragma unroll
;                     for (int n = 0; n < 2; ++n) acc[a][b][m][n] = (f32x4){0.f, 0.f, 0.f, 0.f};
;         cur = nxt; cA = nA; cB = nB; ++ui;
;     }
;     PG8_WAIT_V(0);
;     if (wr == 0) PG8_BAR;
;     PG8_BAR;
;     __device__ __forceinline__ void operator()(const f32x4 (&acc)[2][2][4][2], const Unit& u, int wr, int wc, int fr, int fq) const {
;     ...
; #pragma unroll
;         for (int ai = 0; ai < 2; ++ai)
; #pragma unroll
;             for (int m = 0; m < 4; ++m) {
;                 bf16_t* rowp = z + (size_t)(row0 + ai * 128 + m * 16) * DIN + col0;
; #pragma unroll
;                 for (int bj = 0; bj < 2; ++bj) {
;                     const u32x4 gw = *(const u32x4*)(rowp + (MODE == 0 ? O_GB : O_GA) + bj * 128);
;                     f32x4 g0, g1; unpack8(gw, g0, g1);
;                     f32x4 v0, v1;
; #pragma unroll
;                     for (int j = 0; j < 4; ++j) { v0[j] = sigmoidf_(g0[j]) * acc[ai][bj][m][0][j]; v1[j] = sigmoidf_(g1[j]) * acc[ai][bj][m][1][j]; }
;                     if (MODE == 1) { const u32x4 mw = *(const u32x4*)(rowp + bj * 128); f32x4 m0, m1; unpack8(mw, m0, m1); v0 += m0; v1 += m1; }
;                     *(u32x4*)(rowp + bj * 128) = pack8(v0, v1); }
	v_mov_b32_e32 v12, v212
	v_mov_b32_e32 v13, v213
	v_mov_b64_e32 v[14:15], v[214:215]
	s_mov_b32 s100, 0xbfb8aa3b
	v_lshlrev_b32_e32 v236, 16, v12
	v_and_b32_e32 v237, 0xffff0000, v12
	v_lshlrev_b32_e32 v238, 16, v14
	v_and_b32_e32 v239, 0xffff0000, v14
	v_lshlrev_b32_e32 v240, 16, v13
	v_and_b32_e32 v241, 0xffff0000, v13
	v_lshlrev_b32_e32 v242, 16, v15
	v_and_b32_e32 v243, 0xffff0000, v15
	v_pk_mul_f32 v[236:237], v[236:237], s[100:101] op_sel_hi:[1,0]
	v_pk_mul_f32 v[238:239], v[238:239], s[100:101] op_sel_hi:[1,0]
	v_pk_mul_f32 v[240:241], v[240:241], s[100:101] op_sel_hi:[1,0]
	v_pk_mul_f32 v[242:243], v[242:243], s[100:101] op_sel_hi:[1,0]
	v_exp_f32_e32 v236, v236
	v_exp_f32_e32 v237, v237
	v_exp_f32_e32 v238, v238
	v_exp_f32_e32 v239, v239
	v_exp_f32_e32 v240, v240
	v_exp_f32_e32 v241, v241
	v_exp_f32_e32 v242, v242
	v_exp_f32_e32 v243, v243
	s_nop 0
	v_pk_add_f32 v[236:237], v[236:237], 1.0 op_sel_hi:[1,0]
	v_pk_add_f32 v[238:239], v[238:239], 1.0 op_sel_hi:[1,0]
	v_pk_add_f32 v[240:241], v[240:241], 1.0 op_sel_hi:[1,0]
	v_pk_add_f32 v[242:243], v[242:243], 1.0 op_sel_hi:[1,0]
	v_rcp_f32_e32 v244, v236
	v_rcp_f32_e32 v245, v237
	v_rcp_f32_e32 v250, v238
	v_rcp_f32_e32 v251, v239
	v_pk_fma_f32 v[246:247], v[236:237], v[244:245], 1.0 op_sel_hi:[1,1,0] neg_lo:[1,0,0] neg_hi:[1,0,0]
	v_pk_fma_f32 v[252:253], v[238:239], v[250:251], 1.0 op_sel_hi:[1,1,0] neg_lo:[1,0,0] neg_hi:[1,0,0]
	v_pk_fma_f32 v[244:245], v[246:247], v[244:245], v[244:245]
	v_pk_fma_f32 v[250:251], v[252:253], v[250:251], v[250:251]
	v_pk_fma_f32 v[246:247], v[236:237], v[244:245], 1.0 op_sel_hi:[1,1,0] neg_lo:[1,0,0] neg_hi:[1,0,0]
	v_pk_fma_f32 v[252:253], v[238:239], v[250:251], 1.0 op_sel_hi:[1,1,0] neg_lo:[1,0,0] neg_hi:[1,0,0]
	v_pk_fma_f32 v[248:249], v[246:247], v[244:245], v[244:245]
	v_pk_fma_f32 v[254:255], v[252:253], v[250:251], v[250:251]
	v_pk_fma_f32 v[246:247], v[236:237], v[248:249], 1.0 op_sel_hi:[1,1,0] neg_lo:[1,0,0] neg_hi:[1,0,0]
	v_pk_fma_f32 v[252:253], v[238:239], v[254:255], 1.0 op_sel_hi:[1,1,0] neg_lo:[1,0,0] neg_hi:[1,0,0]
	v_pk_fma_f32 v[248:249], v[246:247], v[244:245], v[248:249]
	v_pk_fma_f32 v[254:255], v[252:253], v[250:251], v[254:255]
	v_div_fixup_f32 v236, v248, v236, 1.0
	v_div_fixup_f32 v237, v249, v237, 1.0
	v_div_fixup_f32 v238, v254, v238, 1.0
	v_div_fixup_f32 v239, v255, v239, 1.0
	v_rcp_f32_e32 v244, v240
	v_rcp_f32_e32 v245, v241
	v_rcp_f32_e32 v250, v242
	v_rcp_f32_e32 v251, v243
	v_pk_fma_f32 v[246:247], v[240:241], v[244:245], 1.0 op_sel_hi:[1,1,0] neg_lo:[1,0,0] neg_hi:[1,0,0]
	v_pk_fma_f32 v[252:253], v[242:243], v[250:251], 1.0 op_sel_hi:[1,1,0] neg_lo:[1,0,0] neg_hi:[1,0,0]
	v_pk_fma_f32 v[244:245], v[246:247], v[244:245], v[244:245]
	v_pk_fma_f32 v[250:251], v[252:253], v[250:251], v[250:251]
	v_pk_fma_f32 v[246:247], v[240:241], v[244:245], 1.0 op_sel_hi:[1,1,0] neg_lo:[1,0,0] neg_hi:[1,0,0]
	v_pk_fma_f32 v[252:253], v[242:243], v[250:251], 1.0 op_sel_hi:[1,1,0] neg_lo:[1,0,0] neg_hi:[1,0,0]
	v_pk_fma_f32 v[248:249], v[246:247], v[244:245], v[244:245]
	v_pk_fma_f32 v[254:255], v[252:253], v[250:251], v[250:251]
	v_pk_fma_f32 v[246:247], v[240:241], v[248:249], 1.0 op_sel_hi:[1,1,0] neg_lo:[1,0,0] neg_hi:[1,0,0]
	v_pk_fma_f32 v[252:253], v[242:243], v[254:255], 1.0 op_sel_hi:[1,1,0] neg_lo:[1,0,0] neg_hi:[1,0,0]
	v_pk_fma_f32 v[248:249], v[246:247], v[244:245], v[248:249]
	v_pk_fma_f32 v[254:255], v[252:253], v[250:251], v[254:255]
	v_div_fixup_f32 v240, v248, v240, 1.0
	v_div_fixup_f32 v241, v249, v241, 1.0
	v_div_fixup_f32 v242, v254, v242, 1.0
	v_div_fixup_f32 v243, v255, v243, 1.0
	global_store_dwordx4 v[16:17], v[8:11], off
	s_nop 0
	v_mul_f32_e32 v4, v4, v236
	v_mul_f32_e32 v8, v0, v238
	v_mul_f32_e32 v0, v5, v237
	v_mul_f32_e32 v5, v1, v239
	v_mul_f32_e32 v1, v6, v240
	v_mul_f32_e32 v6, v2, v242
	v_mul_f32_e32 v2, v7, v241
	v_mul_f32_e32 v3, v3, v243
	s_and_b64 vcc, exec, s[10:11]
	s_mov_b32 s7, s28
	s_mov_b32 s6, s63
	v_cvt_pk_bf16_f32 v0, v4, v0
	v_cvt_pk_bf16_f32 v1, v1, v2
	v_cvt_pk_bf16_f32 v2, v8, v5
	v_cvt_pk_bf16_f32 v3, v6, v3
	global_store_dwordx4 v[16:17], v[0:3], off offset:256
	s_cbranch_vccz .LBB0_622
	s_waitcnt vmcnt(0)
	s_cmpk_gt_u32 s36, 0xff
	s_cbranch_scc1 .LBB0_631
	s_barrier

; #define PG8_STAGE(bufoff, gbase, voff) do { _Pragma("unroll") for (int _i = 0; _i < 2; ++_i) \
;         __builtin_amdgcn_global_load_lds((const unsigned*)((const char*)(gbase) + (voff)[_i]), (LAS unsigned*)(lds + (bufoff) + ldsw + _i * 8192), 16, 0, 0); } while (0)
; #define PG8_LDA(dst, b, h) do { _Pragma("unroll") for (int m = 0; m < 4; ++m) _Pragma("unroll") for (int k = 0; k < 2; ++k) dst[m][k] = *(const LAS bf16x8*)(lds + PG8_SA(b, h) + aoff + m * 2048 + k * 1024); } while (0)
; #define PG8_LDB(dst, b, h) do { _Pragma("unroll") for (int n = 0; n < 2; ++n) _Pragma("unroll") for (int k = 0; k < 2; ++k) dst[n][k] = *(const LAS bf16x8*)(lds + PG8_SB(b, h) + boff + n * 2048 + k * 1024); } while (0)
; #define PG8_MMA(ai, bj, At, Bt) do { __builtin_amdgcn_s_setprio(1); _Pragma("unroll") for (int m = 0; m < 4; ++m) _Pragma("unroll") for (int n = 0; n < 2; ++n) _Pragma("unroll") for (int k = 0; k < 2; ++k) \
;         acc[ai][bj][m][n] = __builtin_amdgcn_mfma_f32_16x16x32_bf16(Bt[n][k], At[m][k], acc[ai][bj][m][n], 0, 0, 0); __builtin_amdgcn_s_setprio(0); } while (0)
; #define PG8_WAIT_L(n) asm volatile("s_waitcnt lgkmcnt(" #n ")" ::: "memory")
; #define PG8_BAR __builtin_amdgcn_s_barrier()
; #define PG8_SCHED __builtin_amdgcn_sched_barrier(0)
;     ...
;             PG8_LDB(B0, 0, 0); PG8_SCHED; PG8_LDA(At, 0, 0); PG8_STAGE(PG8_SA(1, 1), a1 + hA, voffA);
;             PG8_WAIT_L(8); PG8_BAR; PG8_WAIT_L(0); PG8_MMA(0, 0, At, B0); PG8_BAR; PG8_SCHED;
;             PG8_LDB(B1, 0, 1); PG8_STAGE(PG8_SB(0, 0), b2, voffB);
;             PG8_BAR; PG8_WAIT_L(0); PG8_MMA(0, 1, At, B1); PG8_BAR;
;             PG8_LDA(At, 0, 1); PG8_STAGE(PG8_SA(0, 0), a2, voffA);
;             PG8_BAR; PG8_WAIT_L(0); PG8_MMA(1, 0, At, B0); PG8_BAR; PG8_SCHED;
.LBB0_700:
	ds_read_b128 v[146:149], v159
	ds_read_b128 v[150:153], v159 offset:1024
	ds_read_b128 v[162:165], v159 offset:2048
	ds_read_b128 v[170:173], v159 offset:3072
	s_add_u32 s16, s14, 0xfffe0080
	s_addc_u32 s17, s15, -1
	s_cmp_eq_u32 s41, 4
	s_cselect_b32 s19, s7, s17
	s_cselect_b32 s18, s8, s16
	s_cselect_b32 s17, s9, s33
	s_cselect_b32 s16, s20, s21
	v_lshl_add_u64 v[154:155], s[14:15], 0, v[138:139]
	s_add_i32 m0, s67, 0xc000
	ds_read_b128 v[174:177], v160
	ds_read_b128 v[178:181], v160 offset:1024
	ds_read_b128 v[182:185], v160 offset:2048
	ds_read_b128 v[186:189], v160 offset:3072
	ds_read_b128 v[190:193], v160 offset:4096
	ds_read_b128 v[194:197], v160 offset:5120
	ds_read_b128 v[198:201], v160 offset:6144
	ds_read_b128 v[202:205], v160 offset:7168
	global_load_lds_dwordx4 v[154:155], off
	v_lshl_add_u64 v[154:155], s[14:15], 0, v[136:137]
	s_add_i32 m0, s67, 0xe000
	s_nop 0
	global_load_lds_dwordx4 v[154:155], off
	s_waitcnt lgkmcnt(8)
	s_barrier
	s_waitcnt lgkmcnt(0)
	s_setprio 1
	s_waitcnt lgkmcnt(0)
	v_mfma_f32_16x16x32_bf16 v[124:127], v[146:149], v[174:177], v[124:127]
	v_mfma_f32_16x16x32_bf16 v[120:123], v[162:165], v[174:177], v[120:123]
	v_mfma_f32_16x16x32_bf16 v[108:111], v[146:149], v[182:185], v[108:111]
	v_mfma_f32_16x16x32_bf16 v[104:107], v[162:165], v[182:185], v[104:107]
	v_mfma_f32_16x16x32_bf16 v[92:95], v[146:149], v[190:193], v[92:95]
	v_mfma_f32_16x16x32_bf16 v[88:91], v[162:165], v[190:193], v[88:91]
	v_mfma_f32_16x16x32_bf16 v[76:79], v[146:149], v[198:201], v[76:79]
	v_mfma_f32_16x16x32_bf16 v[72:75], v[162:165], v[198:201], v[72:75]
	v_mfma_f32_16x16x32_bf16 v[124:127], v[150:153], v[178:181], v[124:127]
	v_mfma_f32_16x16x32_bf16 v[120:123], v[170:173], v[178:181], v[120:123]
	v_mfma_f32_16x16x32_bf16 v[108:111], v[150:153], v[186:189], v[108:111]
	v_mfma_f32_16x16x32_bf16 v[104:107], v[170:173], v[186:189], v[104:107]
	v_mfma_f32_16x16x32_bf16 v[92:95], v[150:153], v[194:197], v[92:95]
	v_mfma_f32_16x16x32_bf16 v[88:91], v[170:173], v[194:197], v[88:91]
	v_mfma_f32_16x16x32_bf16 v[76:79], v[150:153], v[202:205], v[76:79]
	v_mfma_f32_16x16x32_bf16 v[72:75], v[170:173], v[202:205], v[72:75]
	s_setprio 0
	s_barrier
	s_add_i32 s42, s75, s66
	v_lshl_add_u64 v[154:155], s[16:17], 0, v[130:131]
	s_mov_b32 m0, s42
	ds_read_b128 v[206:209], v161
	ds_read_b128 v[210:213], v161 offset:1024
	ds_read_b128 v[214:217], v161 offset:2048
	ds_read_b128 v[218:221], v161 offset:3072
	global_load_lds_dwordx4 v[154:155], off
	v_lshl_add_u64 v[222:223], s[16:17], 0, v[134:135]
	s_add_i32 m0, s42, 0x2000
	s_nop 0
	global_load_lds_dwordx4 v[222:223], off
	s_barrier
	s_waitcnt lgkmcnt(0)
	s_setprio 1
	s_waitcnt lgkmcnt(0)
	v_mfma_f32_16x16x32_bf16 v[116:119], v[206:209], v[174:177], v[116:119]
	v_mfma_f32_16x16x32_bf16 v[112:115], v[214:217], v[174:177], v[112:115]
	v_mfma_f32_16x16x32_bf16 v[100:103], v[206:209], v[182:185], v[100:103]
	v_mfma_f32_16x16x32_bf16 v[96:99], v[214:217], v[182:185], v[96:99]
	v_mfma_f32_16x16x32_bf16 v[84:87], v[206:209], v[190:193], v[84:87]
	v_mfma_f32_16x16x32_bf16 v[80:83], v[214:217], v[190:193], v[80:83]
	v_mfma_f32_16x16x32_bf16 v[68:71], v[206:209], v[198:201], v[68:71]
	v_mfma_f32_16x16x32_bf16 v[64:67], v[214:217], v[198:201], v[64:67]
	v_mfma_f32_16x16x32_bf16 v[116:119], v[210:213], v[178:181], v[116:119]
	v_mfma_f32_16x16x32_bf16 v[112:115], v[218:221], v[178:181], v[112:115]
	v_mfma_f32_16x16x32_bf16 v[100:103], v[210:213], v[186:189], v[100:103]
	v_mfma_f32_16x16x32_bf16 v[96:99], v[218:221], v[186:189], v[96:99]
	v_mfma_f32_16x16x32_bf16 v[84:87], v[210:213], v[194:197], v[84:87]
	v_mfma_f32_16x16x32_bf16 v[80:83], v[218:221], v[194:197], v[80:83]
	v_mfma_f32_16x16x32_bf16 v[68:71], v[210:213], v[202:205], v[68:71]
	v_mfma_f32_16x16x32_bf16 v[64:67], v[218:221], v[202:205], v[64:67]
	s_setprio 0
	s_mov_b32 m0, s67
	v_lshl_add_u64 v[224:225], s[18:19], 0, v[128:129]
	s_barrier
	ds_read_b128 v[174:177], v160 offset:16384
	ds_read_b128 v[178:181], v160 offset:17408
	ds_read_b128 v[182:185], v160 offset:18432
	ds_read_b128 v[186:189], v160 offset:19456
	ds_read_b128 v[190:193], v160 offset:20480
	ds_read_b128 v[194:197], v160 offset:21504
	ds_read_b128 v[198:201], v160 offset:22528
	ds_read_b128 v[202:205], v160 offset:23552
	global_load_lds_dwordx4 v[224:225], off
	v_lshl_add_u64 v[226:227], s[18:19], 0, v[132:133]
	s_mov_b32 m0, s68
	s_nop 0
	global_load_lds_dwordx4 v[226:227], off
	s_barrier
	s_waitcnt lgkmcnt(0)
	s_setprio 1
	s_waitcnt lgkmcnt(0)
	v_mfma_f32_16x16x32_bf16 v[60:63], v[146:149], v[174:177], v[60:63]
	v_mfma_f32_16x16x32_bf16 v[56:59], v[162:165], v[174:177], v[56:59]
	v_mfma_f32_16x16x32_bf16 v[44:47], v[146:149], v[182:185], v[44:47]
	v_mfma_f32_16x16x32_bf16 v[40:43], v[162:165], v[182:185], v[40:43]
	v_mfma_f32_16x16x32_bf16 v[28:31], v[146:149], v[190:193], v[28:31]
	v_mfma_f32_16x16x32_bf16 v[24:27], v[162:165], v[190:193], v[24:27]
	v_mfma_f32_16x16x32_bf16 v[12:15], v[146:149], v[198:201], v[12:15]
	v_mfma_f32_16x16x32_bf16 v[8:11], v[162:165], v[198:201], v[8:11]
	v_mfma_f32_16x16x32_bf16 v[60:63], v[150:153], v[178:181], v[60:63]
	v_mfma_f32_16x16x32_bf16 v[56:59], v[170:173], v[178:181], v[56:59]
	v_mfma_f32_16x16x32_bf16 v[44:47], v[150:153], v[186:189], v[44:47]
	v_mfma_f32_16x16x32_bf16 v[40:43], v[170:173], v[186:189], v[40:43]
	v_mfma_f32_16x16x32_bf16 v[28:31], v[150:153], v[194:197], v[28:31]
	v_mfma_f32_16x16x32_bf16 v[24:27], v[170:173], v[194:197], v[24:27]
	v_mfma_f32_16x16x32_bf16 v[12:15], v[150:153], v[202:205], v[12:15]
	v_mfma_f32_16x16x32_bf16 v[8:11], v[170:173], v[202:205], v[8:11]
	s_setprio 0
	s_barrier
; #define PG8_STAGE(bufoff, gbase, voff) do { _Pragma("unroll") for (int _i = 0; _i < 2; ++_i) \
;         __builtin_amdgcn_global_load_lds((const unsigned*)((const char*)(gbase) + (voff)[_i]), (LAS unsigned*)(lds + (bufoff) + ldsw + _i * 8192), 16, 0, 0); } while (0)
; #define PG8_LDA(dst, b, h) do { _Pragma("unroll") for (int m = 0; m < 4; ++m) _Pragma("unroll") for (int k = 0; k < 2; ++k) dst[m][k] = *(const LAS bf16x8*)(lds + PG8_SA(b, h) + aoff + m * 2048 + k * 1024); } while (0)
; #define PG8_LDB(dst, b, h) do { _Pragma("unroll") for (int n = 0; n < 2; ++n) _Pragma("unroll") for (int k = 0; k < 2; ++k) dst[n][k] = *(const LAS bf16x8*)(lds + PG8_SB(b, h) + boff + n * 2048 + k * 1024); } while (0)
; #define PG8_MMA(ai, bj, At, Bt) do { __builtin_amdgcn_s_setprio(1); _Pragma("unroll") for (int m = 0; m < 4; ++m) _Pragma("unroll") for (int n = 0; n < 2; ++n) _Pragma("unroll") for (int k = 0; k < 2; ++k) \
;         acc[ai][bj][m][n] = __builtin_amdgcn_mfma_f32_16x16x32_bf16(Bt[n][k], At[m][k], acc[ai][bj][m][n], 0, 0, 0); __builtin_amdgcn_s_setprio(0); } while (0)
; #define PG8_WAIT_V(n) asm volatile("s_waitcnt vmcnt(" #n ")" ::: "memory")
; #define PG8_WAIT_L(n) asm volatile("s_waitcnt lgkmcnt(" #n ")" ::: "memory")
; #define PG8_BAR __builtin_amdgcn_s_barrier()
; #define PG8_SCHED __builtin_amdgcn_sched_barrier(0)
;     ...
;             PG8_STAGE(PG8_SB(0, 1), b2 + hB, voffB);
;             PG8_WAIT_V(6); PG8_BAR; PG8_MMA(1, 1, At, B1); PG8_BAR;
;             PG8_LDB(B0, 1, 0); PG8_SCHED; PG8_LDA(At, 1, 0); PG8_STAGE(PG8_SA(0, 1), a2 + hA, voffA);
;             PG8_WAIT_L(8); PG8_BAR; PG8_WAIT_L(0); PG8_MMA(0, 0, At, B0); PG8_BAR; PG8_SCHED;
;             PG8_LDB(B1, 1, 1); PG8_STAGE(PG8_SB(1, 0), b3, voffB);
;             PG8_BAR; PG8_WAIT_L(0); PG8_MMA(0, 1, At, B1); PG8_BAR;
;             PG8_LDA(At, 1, 1); PG8_STAGE(PG8_SA(1, 0), a3, voffA);
;             PG8_BAR; PG8_WAIT_L(0); PG8_MMA(1, 0, At, B0); PG8_BAR; PG8_SCHED;
	s_add_u32 s42, s16, 0x20000
	s_addc_u32 s43, s17, 0
	s_add_i32 s44, s76, s66
	v_lshl_add_u64 v[146:147], s[42:43], 0, v[130:131]
	s_mov_b32 m0, s44
	s_nop 0
	global_load_lds_dwordx4 v[146:147], off
	v_lshl_add_u64 v[146:147], s[42:43], 0, v[134:135]
	s_add_i32 m0, s44, 0x2000
	s_nop 0
	global_load_lds_dwordx4 v[146:147], off
	s_waitcnt vmcnt(6)
	s_barrier
	s_setprio 1
	v_mfma_f32_16x16x32_bf16 v[52:55], v[206:209], v[174:177], v[52:55]
	v_mfma_f32_16x16x32_bf16 v[48:51], v[214:217], v[174:177], v[48:51]
	v_mfma_f32_16x16x32_bf16 v[36:39], v[206:209], v[182:185], v[36:39]
	v_mfma_f32_16x16x32_bf16 v[32:35], v[214:217], v[182:185], v[32:35]
	v_mfma_f32_16x16x32_bf16 v[20:23], v[206:209], v[190:193], v[20:23]
	v_mfma_f32_16x16x32_bf16 v[16:19], v[214:217], v[190:193], v[16:19]
	v_mfma_f32_16x16x32_bf16 v[4:7], v[206:209], v[198:201], v[4:7]
	v_mfma_f32_16x16x32_bf16 v[0:3], v[214:217], v[198:201], v[0:3]
	v_mfma_f32_16x16x32_bf16 v[52:55], v[210:213], v[178:181], v[52:55]
	v_mfma_f32_16x16x32_bf16 v[48:51], v[218:221], v[178:181], v[48:51]
	v_mfma_f32_16x16x32_bf16 v[36:39], v[210:213], v[186:189], v[36:39]
	v_mfma_f32_16x16x32_bf16 v[32:35], v[218:221], v[186:189], v[32:35]
	v_mfma_f32_16x16x32_bf16 v[20:23], v[210:213], v[194:197], v[20:23]
	v_mfma_f32_16x16x32_bf16 v[16:19], v[218:221], v[194:197], v[16:19]
	v_mfma_f32_16x16x32_bf16 v[4:7], v[210:213], v[202:205], v[4:7]
	v_mfma_f32_16x16x32_bf16 v[0:3], v[218:221], v[202:205], v[0:3]
	s_setprio 0
	s_add_i32 s42, 0, 0x18000
	v_add_u32_e32 v170, s42, v157
	s_barrier
	ds_read_b128 v[146:149], v170
	ds_read_b128 v[150:153], v170 offset:1024
	ds_read_b128 v[162:165], v170 offset:2048
	ds_read_b128 v[170:173], v170 offset:3072
	s_add_u32 s18, s18, 0x20000
	s_addc_u32 s19, s19, 0
	s_mov_b32 m0, s69
	v_lshl_add_u64 v[206:207], s[18:19], 0, v[128:129]
	ds_read_b128 v[174:177], v160 offset:32768
	ds_read_b128 v[178:181], v160 offset:33792
	ds_read_b128 v[182:185], v160 offset:34816
	ds_read_b128 v[186:189], v160 offset:35840
	ds_read_b128 v[190:193], v160 offset:36864
	ds_read_b128 v[194:197], v160 offset:37888
	ds_read_b128 v[198:201], v160 offset:38912
	ds_read_b128 v[202:205], v160 offset:39936
	global_load_lds_dwordx4 v[206:207], off
	v_lshl_add_u64 v[206:207], s[18:19], 0, v[132:133]
	s_mov_b32 m0, s70
	s_nop 0
	global_load_lds_dwordx4 v[206:207], off
	s_waitcnt lgkmcnt(8)
	s_barrier
	s_waitcnt lgkmcnt(0)
	s_setprio 1
	s_waitcnt lgkmcnt(0)
	v_mfma_f32_16x16x32_bf16 v[124:127], v[146:149], v[174:177], v[124:127]
	v_mfma_f32_16x16x32_bf16 v[120:123], v[162:165], v[174:177], v[120:123]
	v_mfma_f32_16x16x32_bf16 v[108:111], v[146:149], v[182:185], v[108:111]
	v_mfma_f32_16x16x32_bf16 v[104:107], v[162:165], v[182:185], v[104:107]
	v_mfma_f32_16x16x32_bf16 v[92:95], v[146:149], v[190:193], v[92:95]
	v_mfma_f32_16x16x32_bf16 v[88:91], v[162:165], v[190:193], v[88:91]
	v_mfma_f32_16x16x32_bf16 v[76:79], v[146:149], v[198:201], v[76:79]
	v_mfma_f32_16x16x32_bf16 v[72:75], v[162:165], v[198:201], v[72:75]
	v_mfma_f32_16x16x32_bf16 v[124:127], v[150:153], v[178:181], v[124:127]
	v_mfma_f32_16x16x32_bf16 v[120:123], v[170:173], v[178:181], v[120:123]
	v_mfma_f32_16x16x32_bf16 v[108:111], v[150:153], v[186:189], v[108:111]
	v_mfma_f32_16x16x32_bf16 v[104:107], v[170:173], v[186:189], v[104:107]
	v_mfma_f32_16x16x32_bf16 v[92:95], v[150:153], v[194:197], v[92:95]
	v_mfma_f32_16x16x32_bf16 v[88:91], v[170:173], v[194:197], v[88:91]
	v_mfma_f32_16x16x32_bf16 v[76:79], v[150:153], v[202:205], v[76:79]
	v_mfma_f32_16x16x32_bf16 v[72:75], v[170:173], v[202:205], v[72:75]
	s_setprio 0
	s_barrier
	s_add_i32 s18, 0, 0x1c000
	s_add_i32 s19, s42, s66
	v_add_u32_e32 v218, s18, v157
	v_lshl_add_u64 v[154:155], v[154:155], 0, s[54:55]
	s_mov_b32 m0, s19
	ds_read_b128 v[206:209], v218
	ds_read_b128 v[210:213], v218 offset:1024
	ds_read_b128 v[214:217], v218 offset:2048
	ds_read_b128 v[218:221], v218 offset:3072
	global_load_lds_dwordx4 v[154:155], off
	v_lshl_add_u64 v[154:155], v[222:223], 0, s[54:55]
	s_add_i32 m0, s19, 0x2000
	s_nop 0
	global_load_lds_dwordx4 v[154:155], off
	s_barrier
	s_waitcnt lgkmcnt(0)
	s_setprio 1
	s_waitcnt lgkmcnt(0)
	v_mfma_f32_16x16x32_bf16 v[116:119], v[206:209], v[174:177], v[116:119]
	v_mfma_f32_16x16x32_bf16 v[112:115], v[214:217], v[174:177], v[112:115]
	v_mfma_f32_16x16x32_bf16 v[100:103], v[206:209], v[182:185], v[100:103]
	v_mfma_f32_16x16x32_bf16 v[96:99], v[214:217], v[182:185], v[96:99]
	v_mfma_f32_16x16x32_bf16 v[84:87], v[206:209], v[190:193], v[84:87]
	v_mfma_f32_16x16x32_bf16 v[80:83], v[214:217], v[190:193], v[80:83]
	v_mfma_f32_16x16x32_bf16 v[68:71], v[206:209], v[198:201], v[68:71]
	v_mfma_f32_16x16x32_bf16 v[64:67], v[214:217], v[198:201], v[64:67]
	v_mfma_f32_16x16x32_bf16 v[116:119], v[210:213], v[178:181], v[116:119]
	v_mfma_f32_16x16x32_bf16 v[112:115], v[218:221], v[178:181], v[112:115]
	v_mfma_f32_16x16x32_bf16 v[100:103], v[210:213], v[186:189], v[100:103]
	v_mfma_f32_16x16x32_bf16 v[96:99], v[218:221], v[186:189], v[96:99]
	v_mfma_f32_16x16x32_bf16 v[84:87], v[210:213], v[194:197], v[84:87]
	v_mfma_f32_16x16x32_bf16 v[80:83], v[218:221], v[194:197], v[80:83]
	v_mfma_f32_16x16x32_bf16 v[68:71], v[210:213], v[202:205], v[68:71]
	v_mfma_f32_16x16x32_bf16 v[64:67], v[218:221], v[202:205], v[64:67]
	s_setprio 0
	s_mov_b32 m0, s72
	v_lshl_add_u64 v[154:155], v[224:225], 0, s[54:55]
	s_barrier
	ds_read_b128 v[174:177], v160 offset:49152
	ds_read_b128 v[178:181], v160 offset:50176
	ds_read_b128 v[182:185], v160 offset:51200
	ds_read_b128 v[186:189], v160 offset:52224
	ds_read_b128 v[190:193], v160 offset:53248
	ds_read_b128 v[194:197], v160 offset:54272
	ds_read_b128 v[198:201], v160 offset:55296
	ds_read_b128 v[202:205], v160 offset:56320
	global_load_lds_dwordx4 v[154:155], off
	v_lshl_add_u64 v[154:155], v[226:227], 0, s[54:55]
	s_mov_b32 m0, s73
	s_nop 0
	global_load_lds_dwordx4 v[154:155], off
	s_barrier
; __device__ __forceinline__ float sigmoidf_(float x) { return 1.0f / (1.0f + __expf(-x)); }
; #define PG8_STAGE(bufoff, gbase, voff) do { _Pragma("unroll") for (int _i = 0; _i < 2; ++_i) \
;         __builtin_amdgcn_global_load_lds((const unsigned*)((const char*)(gbase) + (voff)[_i]), (LAS unsigned*)(lds + (bufoff) + ldsw + _i * 8192), 16, 0, 0); } while (0)
; #define PG8_MMA(ai, bj, At, Bt) do { __builtin_amdgcn_s_setprio(1); _Pragma("unroll") for (int m = 0; m < 4; ++m) _Pragma("unroll") for (int n = 0; n < 2; ++n) _Pragma("unroll") for (int k = 0; k < 2; ++k) \
;         acc[ai][bj][m][n] = __builtin_amdgcn_mfma_f32_16x16x32_bf16(Bt[n][k], At[m][k], acc[ai][bj][m][n], 0, 0, 0); __builtin_amdgcn_s_setprio(0); } while (0)
; #define PG8_WAIT_V(n) asm volatile("s_waitcnt vmcnt(" #n ")" ::: "memory")
; #define PG8_WAIT_L(n) asm volatile("s_waitcnt lgkmcnt(" #n ")" ::: "memory")
; #define PG8_BAR __builtin_amdgcn_s_barrier()
; #define PG8_SCHED __builtin_amdgcn_sched_barrier(0)
; __device__ __forceinline__ void unpack8(const u32x4 w, f32x4& v0, f32x4& v1) { v0 = (f32x4){bflo(w.x), bfhi(w.x), bflo(w.y), bfhi(w.y)}; v1 = (f32x4){bflo(w.z), bfhi(w.z), bflo(w.w), bfhi(w.w)}; }
;     ...
;             PG8_BAR; PG8_WAIT_L(0); PG8_MMA(1, 0, At, B0); PG8_BAR; PG8_SCHED;
;             PG8_STAGE(PG8_SB(1, 1), b3 + hB, voffB);
;             PG8_WAIT_V(6); PG8_BAR; PG8_MMA(1, 1, At, B1); PG8_BAR;
;     __device__ __forceinline__ void operator()(const f32x4 (&acc)[2][2][4][2], const Unit& u, int wr, int wc, int fr, int fq) const {
;     ...
;         for (int ai = 0; ai < 2; ++ai)
; #pragma unroll
;             for (int m = 0; m < 4; ++m) {
;                 const int row = row0 + ai * 128 + m * 16;
;                 const bf16_t* rowp = z + (size_t)row * DIN + col0;
; #pragma unroll
;                 for (int bj = 0; bj < 2; ++bj) {
;                     const u32x4 gw = *(const u32x4*)(rowp + O_GA + bj * 128);
;                     f32x4 g0, g1; unpack8(gw, g0, g1);
;                     f32x4 v0, v1;
; #pragma unroll
;                     for (int j = 0; j < 4; ++j) { v0[j] = sigmoidf_(g0[j]) * acc[ai][bj][m][0][j]; v1[j] = sigmoidf_(g1[j]) * acc[ai][bj][m][1][j]; }
;                     const u32x4 mw = *(const u32x4*)(rowp + bj * 128); f32x4 m0, m1; unpack8(mw, m0, m1); v0 += m0; v1 += m1;
	s_waitcnt lgkmcnt(0)
	s_setprio 1
	s_waitcnt lgkmcnt(0)
	v_mfma_f32_16x16x32_bf16 v[60:63], v[146:149], v[174:177], v[60:63]
	v_mfma_f32_16x16x32_bf16 v[56:59], v[162:165], v[174:177], v[56:59]
	v_mfma_f32_16x16x32_bf16 v[44:47], v[146:149], v[182:185], v[44:47]
	v_mfma_f32_16x16x32_bf16 v[40:43], v[162:165], v[182:185], v[40:43]
	v_mfma_f32_16x16x32_bf16 v[28:31], v[146:149], v[190:193], v[28:31]
	v_mfma_f32_16x16x32_bf16 v[24:27], v[162:165], v[190:193], v[24:27]
	v_mfma_f32_16x16x32_bf16 v[12:15], v[146:149], v[198:201], v[12:15]
	v_mfma_f32_16x16x32_bf16 v[8:11], v[162:165], v[198:201], v[8:11]
	v_mfma_f32_16x16x32_bf16 v[60:63], v[150:153], v[178:181], v[60:63]
	v_mfma_f32_16x16x32_bf16 v[56:59], v[170:173], v[178:181], v[56:59]
	v_mfma_f32_16x16x32_bf16 v[44:47], v[150:153], v[186:189], v[44:47]
	v_mfma_f32_16x16x32_bf16 v[40:43], v[170:173], v[186:189], v[40:43]
	v_mfma_f32_16x16x32_bf16 v[28:31], v[150:153], v[194:197], v[28:31]
	v_mfma_f32_16x16x32_bf16 v[24:27], v[170:173], v[194:197], v[24:27]
	v_mfma_f32_16x16x32_bf16 v[12:15], v[150:153], v[202:205], v[12:15]
	v_mfma_f32_16x16x32_bf16 v[8:11], v[170:173], v[202:205], v[8:11]
	s_setprio 0
	s_barrier
	s_add_u32 s16, s16, 0x20080
	s_addc_u32 s17, s17, 0
	s_add_i32 s18, s18, s66
	v_lshl_add_u64 v[146:147], s[16:17], 0, v[130:131]
	s_mov_b32 m0, s18
	s_nop 0
	global_load_lds_dwordx4 v[146:147], off
	v_lshl_add_u64 v[146:147], s[16:17], 0, v[134:135]
	s_add_i32 m0, s18, 0x2000
	s_nop 0
	global_load_lds_dwordx4 v[146:147], off
	s_waitcnt vmcnt(6)
	s_barrier
	s_setprio 1
	v_mfma_f32_16x16x32_bf16 v[52:55], v[206:209], v[174:177], v[52:55]
	v_mfma_f32_16x16x32_bf16 v[48:51], v[214:217], v[174:177], v[48:51]
	v_mfma_f32_16x16x32_bf16 v[36:39], v[206:209], v[182:185], v[36:39]
	v_mfma_f32_16x16x32_bf16 v[32:35], v[214:217], v[182:185], v[32:35]
	v_mfma_f32_16x16x32_bf16 v[20:23], v[206:209], v[190:193], v[20:23]
	v_mfma_f32_16x16x32_bf16 v[16:19], v[214:217], v[190:193], v[16:19]
	v_mfma_f32_16x16x32_bf16 v[4:7], v[206:209], v[198:201], v[4:7]
	v_mfma_f32_16x16x32_bf16 v[0:3], v[214:217], v[198:201], v[0:3]
	v_mfma_f32_16x16x32_bf16 v[52:55], v[210:213], v[178:181], v[52:55]
	v_mfma_f32_16x16x32_bf16 v[48:51], v[218:221], v[178:181], v[48:51]
	v_mfma_f32_16x16x32_bf16 v[36:39], v[210:213], v[186:189], v[36:39]
	v_mfma_f32_16x16x32_bf16 v[32:35], v[218:221], v[186:189], v[32:35]
	v_mfma_f32_16x16x32_bf16 v[20:23], v[210:213], v[194:197], v[20:23]
	v_mfma_f32_16x16x32_bf16 v[16:19], v[218:221], v[194:197], v[16:19]
	v_mfma_f32_16x16x32_bf16 v[4:7], v[210:213], v[202:205], v[4:7]
	v_mfma_f32_16x16x32_bf16 v[0:3], v[218:221], v[202:205], v[0:3]
	s_setprio 0
	s_add_i32 s41, s41, 2
	s_add_u32 s21, s21, 0x100
	s_addc_u32 s33, s33, 0
	s_add_u32 s14, s14, 0x100
	s_addc_u32 s15, s15, 0
	s_cmp_gt_u32 s41, 5
	s_barrier
	s_cbranch_scc0 .LBB0_700
	v_lshl_or_b32 v146, s6, 8, v158
	v_lshl_add_u32 v162, s79, 8, v156
	v_ashrrev_i32_e32 v147, 31, v146
	v_mad_i64_i32 v[154:155], s[6:7], v162, s77, 0
	v_lshl_add_u64 v[150:151], v[154:155], 1, s[38:39]
	v_lshlrev_b64 v[148:149], 1, v[146:147]
	v_lshl_add_u64 v[150:151], v[150:151], 0, v[148:149]
	v_add_co_u32_e32 v152, vcc, 0x1000, v150
	s_nop 1
	v_addc_co_u32_e32 v153, vcc, 0, v151, vcc
	v_subrev_u32_e32 v202, s38, v150
	v_add_u32_e32 v203, 0x1200, v202
	global_load_dwordx4 v[204:207], v203, s[38:39]
	v_add_u32_e32 v203, 0x0, v202
	global_load_dwordx4 v[208:211], v203, s[38:39]
	v_add_u32_e32 v203, 0x1300, v202
	global_load_dwordx4 v[212:215], v203, s[38:39]
	v_add_u32_e32 v203, 0x100, v202
	global_load_dwordx4 v[216:219], v203, s[38:39]
	v_add_u32_e32 v203, 0x23200, v202
	global_load_dwordx4 v[232:235], v203, s[38:39]
	v_add_u32_e32 v203, 0x22000, v202
	global_load_dwordx4 v[236:239], v203, s[38:39]
	s_waitcnt vmcnt(4)
	v_mov_b64_e32 v[170:171], v[204:205]
	v_mov_b64_e32 v[172:173], v[206:207]
	v_mov_b64_e32 v[174:175], v[208:209]
	v_mov_b64_e32 v[176:177], v[210:211]
	v_add_u32_e32 v203, 0x23300, v202
	global_load_dwordx4 v[204:207], v203, s[38:39]
	v_add_u32_e32 v203, 0x22100, v202
	global_load_dwordx4 v[208:211], v203, s[38:39]
	s_mov_b32 s100, 0xbfb8aa3b
	v_lshlrev_b32_e32 v242, 16, v170
	v_and_b32_e32 v243, 0xffff0000, v170
	v_lshlrev_b32_e32 v244, 16, v172
	v_and_b32_e32 v245, 0xffff0000, v172
	v_lshlrev_b32_e32 v246, 16, v171
	v_and_b32_e32 v247, 0xffff0000, v171
	v_lshlrev_b32_e32 v248, 16, v173
	v_and_b32_e32 v249, 0xffff0000, v173
	v_pk_mul_f32 v[242:243], v[242:243], s[100:101] op_sel_hi:[1,0]
	v_pk_mul_f32 v[244:245], v[244:245], s[100:101] op_sel_hi:[1,0]
	v_pk_mul_f32 v[246:247], v[246:247], s[100:101] op_sel_hi:[1,0]
	v_pk_mul_f32 v[248:249], v[248:249], s[100:101] op_sel_hi:[1,0]
	v_exp_f32_e32 v242, v242
	v_exp_f32_e32 v243, v243
	v_exp_f32_e32 v244, v244
	v_exp_f32_e32 v245, v245
	v_exp_f32_e32 v246, v246
	v_exp_f32_e32 v247, v247
	v_exp_f32_e32 v248, v248
	v_exp_f32_e32 v249, v249
	s_nop 0
	v_pk_add_f32 v[242:243], v[242:243], 1.0 op_sel_hi:[1,0]
	v_pk_add_f32 v[244:245], v[244:245], 1.0 op_sel_hi:[1,0]
	v_pk_add_f32 v[246:247], v[246:247], 1.0 op_sel_hi:[1,0]
	v_pk_add_f32 v[248:249], v[248:249], 1.0 op_sel_hi:[1,0]
	v_rcp_f32_e32 v250, v242
	v_rcp_f32_e32 v251, v243
	s_nop 0
	v_pk_fma_f32 v[252:253], v[242:243], v[250:251], 1.0 op_sel_hi:[1,1,0] neg_lo:[1,0,0] neg_hi:[1,0,0]
	v_pk_fma_f32 v[250:251], v[252:253], v[250:251], v[250:251]
	v_pk_fma_f32 v[252:253], v[242:243], v[250:251], 1.0 op_sel_hi:[1,1,0] neg_lo:[1,0,0] neg_hi:[1,0,0]
	v_pk_fma_f32 v[254:255], v[252:253], v[250:251], v[250:251]
	v_pk_fma_f32 v[252:253], v[242:243], v[254:255], 1.0 op_sel_hi:[1,1,0] neg_lo:[1,0,0] neg_hi:[1,0,0]
	v_pk_fma_f32 v[254:255], v[252:253], v[250:251], v[254:255]
; __device__ __forceinline__ float sigmoidf_(float x) { return 1.0f / (1.0f + __expf(-x)); }
; __device__ __forceinline__ u32x4 pack8(const f32x4 v0, const f32x4 v1) { u32x4 w; w.x = pk2(v0[0], v0[1]); w.y = pk2(v0[2], v0[3]); w.z = pk2(v1[0], v1[1]); w.w = pk2(v1[2], v1[3]); return w; }
; __device__ __forceinline__ void unpack8(const u32x4 w, f32x4& v0, f32x4& v1) { v0 = (f32x4){bflo(w.x), bfhi(w.x), bflo(w.y), bfhi(w.y)}; v1 = (f32x4){bflo(w.z), bfhi(w.z), bflo(w.w), bfhi(w.w)}; }
;     __device__ __forceinline__ void operator()(const f32x4 (&acc)[2][2][4][2], const Unit& u, int wr, int wc, int fr, int fq) const {
;     ...
;         for (int ai = 0; ai < 2; ++ai)
; #pragma unroll
;             for (int m = 0; m < 4; ++m) {
;                 const int row = row0 + ai * 128 + m * 16;
;                 const bf16_t* rowp = z + (size_t)row * DIN + col0;
; #pragma unroll
;                 for (int bj = 0; bj < 2; ++bj) {
;                     const u32x4 gw = *(const u32x4*)(rowp + O_GA + bj * 128);
;                     f32x4 g0, g1; unpack8(gw, g0, g1);
;                     f32x4 v0, v1;
; #pragma unroll
;                     for (int j = 0; j < 4; ++j) { v0[j] = sigmoidf_(g0[j]) * acc[ai][bj][m][0][j]; v1[j] = sigmoidf_(g1[j]) * acc[ai][bj][m][1][j]; }
;                     const u32x4 mw = *(const u32x4*)(rowp + bj * 128); f32x4 m0, m1; unpack8(mw, m0, m1); v0 += m0; v1 += m1;
;                     __builtin_amdgcn_raw_buffer_store_b128(pack8(v0, v1), rsrc, (unsigned)(((size_t)row * DIN + col0 + bj * 128) * 2), 0, 16  ); }
	v_div_fixup_f32 v242, v254, v242, 1.0
	v_div_fixup_f32 v243, v255, v243, 1.0
	v_rcp_f32_e32 v250, v244
	v_rcp_f32_e32 v251, v245
	s_nop 0
	v_pk_fma_f32 v[252:253], v[244:245], v[250:251], 1.0 op_sel_hi:[1,1,0] neg_lo:[1,0,0] neg_hi:[1,0,0]
	v_pk_fma_f32 v[250:251], v[252:253], v[250:251], v[250:251]
	v_pk_fma_f32 v[252:253], v[244:245], v[250:251], 1.0 op_sel_hi:[1,1,0] neg_lo:[1,0,0] neg_hi:[1,0,0]
	v_pk_fma_f32 v[254:255], v[252:253], v[250:251], v[250:251]
	v_pk_fma_f32 v[252:253], v[244:245], v[254:255], 1.0 op_sel_hi:[1,1,0] neg_lo:[1,0,0] neg_hi:[1,0,0]
	v_pk_fma_f32 v[254:255], v[252:253], v[250:251], v[254:255]
	v_div_fixup_f32 v244, v254, v244, 1.0
	v_div_fixup_f32 v245, v255, v245, 1.0
	v_rcp_f32_e32 v250, v246
	v_rcp_f32_e32 v251, v247
	s_nop 0
	v_pk_fma_f32 v[252:253], v[246:247], v[250:251], 1.0 op_sel_hi:[1,1,0] neg_lo:[1,0,0] neg_hi:[1,0,0]
	v_pk_fma_f32 v[250:251], v[252:253], v[250:251], v[250:251]
	v_pk_fma_f32 v[252:253], v[246:247], v[250:251], 1.0 op_sel_hi:[1,1,0] neg_lo:[1,0,0] neg_hi:[1,0,0]
	v_pk_fma_f32 v[254:255], v[252:253], v[250:251], v[250:251]
	v_pk_fma_f32 v[252:253], v[246:247], v[254:255], 1.0 op_sel_hi:[1,1,0] neg_lo:[1,0,0] neg_hi:[1,0,0]
	v_pk_fma_f32 v[254:255], v[252:253], v[250:251], v[254:255]
	v_div_fixup_f32 v246, v254, v246, 1.0
	v_div_fixup_f32 v247, v255, v247, 1.0
	v_rcp_f32_e32 v250, v248
	v_rcp_f32_e32 v251, v249
	s_nop 0
	v_pk_fma_f32 v[252:253], v[248:249], v[250:251], 1.0 op_sel_hi:[1,1,0] neg_lo:[1,0,0] neg_hi:[1,0,0]
	v_pk_fma_f32 v[250:251], v[252:253], v[250:251], v[250:251]
	v_pk_fma_f32 v[252:253], v[248:249], v[250:251], 1.0 op_sel_hi:[1,1,0] neg_lo:[1,0,0] neg_hi:[1,0,0]
	v_pk_fma_f32 v[254:255], v[252:253], v[250:251], v[250:251]
	v_pk_fma_f32 v[252:253], v[248:249], v[254:255], 1.0 op_sel_hi:[1,1,0] neg_lo:[1,0,0] neg_hi:[1,0,0]
	v_pk_fma_f32 v[254:255], v[252:253], v[250:251], v[254:255]
	v_div_fixup_f32 v248, v254, v248, 1.0
	v_div_fixup_f32 v249, v255, v249, 1.0
	s_mov_b64 vcc, s[14:15]
	s_mov_b64 vcc, s[16:17]
	s_mov_b64 vcc, s[18:19]
	s_mov_b64 vcc, s[20:21]
	v_lshlrev_b32_e32 v182, 16, v176
	v_and_b32_e32 v183, 0xffff0000, v176
	v_lshlrev_b32_e32 v180, 16, v174
	v_and_b32_e32 v181, 0xffff0000, v174
	v_lshlrev_b32_e32 v176, 16, v177
	v_and_b32_e32 v177, 0xffff0000, v177
	v_lshlrev_b32_e32 v174, 16, v175
	v_and_b32_e32 v175, 0xffff0000, v175
	v_pk_fma_f32 v[124:125], v[124:125], v[242:243], v[180:181]
	v_pk_fma_f32 v[164:165], v[122:123], v[248:249], v[176:177]
	v_pk_fma_f32 v[122:123], v[120:121], v[244:245], v[182:183]
	v_add_lshl_u32 v147, v146, v154, 1
	v_pk_fma_f32 v[126:127], v[126:127], v[246:247], v[174:175]
	v_cvt_pk_bf16_f32 v120, v124, v125
	s_nop 0
	v_cvt_pk_bf16_f32 v121, v126, v127
	v_cvt_pk_bf16_f32 v122, v122, v123
	v_cvt_pk_bf16_f32 v123, v164, v165
	buffer_store_dwordx4 v[120:123], v147, s[24:27], 0 offen sc1
	s_nop 0
	s_waitcnt vmcnt(5)
	v_mov_b64_e32 v[120:121], v[212:213]
	v_mov_b64_e32 v[122:123], v[214:215]
	v_mov_b64_e32 v[124:125], v[216:217]
	v_mov_b64_e32 v[126:127], v[218:219]
	v_add_u32_e32 v203, 0x45200, v202
	global_load_dwordx4 v[212:215], v203, s[38:39]
	v_add_u32_e32 v203, 0x44000, v202
	global_load_dwordx4 v[216:219], v203, s[38:39]
	s_mov_b32 s100, 0xbfb8aa3b
	v_lshlrev_b32_e32 v242, 16, v120
	v_and_b32_e32 v243, 0xffff0000, v120
	v_lshlrev_b32_e32 v244, 16, v122
	v_and_b32_e32 v245, 0xffff0000, v122
	v_lshlrev_b32_e32 v246, 16, v121
	v_and_b32_e32 v247, 0xffff0000, v121
	v_lshlrev_b32_e32 v248, 16, v123
	v_and_b32_e32 v249, 0xffff0000, v123
	v_pk_mul_f32 v[242:243], v[242:243], s[100:101] op_sel_hi:[1,0]
	v_pk_mul_f32 v[244:245], v[244:245], s[100:101] op_sel_hi:[1,0]
	v_pk_mul_f32 v[246:247], v[246:247], s[100:101] op_sel_hi:[1,0]
	v_pk_mul_f32 v[248:249], v[248:249], s[100:101] op_sel_hi:[1,0]
	v_exp_f32_e32 v242, v242
	v_exp_f32_e32 v243, v243
	v_exp_f32_e32 v244, v244
	v_exp_f32_e32 v245, v245
	v_exp_f32_e32 v246, v246
	v_exp_f32_e32 v247, v247
	v_exp_f32_e32 v248, v248
	v_exp_f32_e32 v249, v249
	s_nop 0
	v_pk_add_f32 v[242:243], v[242:243], 1.0 op_sel_hi:[1,0]
	v_pk_add_f32 v[244:245], v[244:245], 1.0 op_sel_hi:[1,0]
	v_pk_add_f32 v[246:247], v[246:247], 1.0 op_sel_hi:[1,0]
	v_pk_add_f32 v[248:249], v[248:249], 1.0 op_sel_hi:[1,0]
	v_rcp_f32_e32 v250, v242
	v_rcp_f32_e32 v251, v243
	s_nop 0
	v_pk_fma_f32 v[252:253], v[242:243], v[250:251], 1.0 op_sel_hi:[1,1,0] neg_lo:[1,0,0] neg_hi:[1,0,0]
	v_pk_fma_f32 v[250:251], v[252:253], v[250:251], v[250:251]
	v_pk_fma_f32 v[252:253], v[242:243], v[250:251], 1.0 op_sel_hi:[1,1,0] neg_lo:[1,0,0] neg_hi:[1,0,0]
	v_pk_fma_f32 v[254:255], v[252:253], v[250:251], v[250:251]
	v_pk_fma_f32 v[252:253], v[242:243], v[254:255], 1.0 op_sel_hi:[1,1,0] neg_lo:[1,0,0] neg_hi:[1,0,0]
	v_pk_fma_f32 v[254:255], v[252:253], v[250:251], v[254:255]
	v_div_fixup_f32 v242, v254, v242, 1.0
	v_div_fixup_f32 v243, v255, v243, 1.0
	v_rcp_f32_e32 v250, v244
	v_rcp_f32_e32 v251, v245
	s_nop 0
	v_pk_fma_f32 v[252:253], v[244:245], v[250:251], 1.0 op_sel_hi:[1,1,0] neg_lo:[1,0,0] neg_hi:[1,0,0]
	v_pk_fma_f32 v[250:251], v[252:253], v[250:251], v[250:251]
	v_pk_fma_f32 v[252:253], v[244:245], v[250:251], 1.0 op_sel_hi:[1,1,0] neg_lo:[1,0,0] neg_hi:[1,0,0]
	v_pk_fma_f32 v[254:255], v[252:253], v[250:251], v[250:251]
	v_pk_fma_f32 v[252:253], v[244:245], v[254:255], 1.0 op_sel_hi:[1,1,0] neg_lo:[1,0,0] neg_hi:[1,0,0]
	v_pk_fma_f32 v[254:255], v[252:253], v[250:251], v[254:255]
	v_div_fixup_f32 v244, v254, v244, 1.0
	v_div_fixup_f32 v245, v255, v245, 1.0
	v_rcp_f32_e32 v250, v246
	v_rcp_f32_e32 v251, v247
	s_nop 0
	v_pk_fma_f32 v[252:253], v[246:247], v[250:251], 1.0 op_sel_hi:[1,1,0] neg_lo:[1,0,0] neg_hi:[1,0,0]
; __device__ __forceinline__ float sigmoidf_(float x) { return 1.0f / (1.0f + __expf(-x)); }
; __device__ __forceinline__ u32x4 pack8(const f32x4 v0, const f32x4 v1) { u32x4 w; w.x = pk2(v0[0], v0[1]); w.y = pk2(v0[2], v0[3]); w.z = pk2(v1[0], v1[1]); w.w = pk2(v1[2], v1[3]); return w; }
; __device__ __forceinline__ void unpack8(const u32x4 w, f32x4& v0, f32x4& v1) { v0 = (f32x4){bflo(w.x), bfhi(w.x), bflo(w.y), bfhi(w.y)}; v1 = (f32x4){bflo(w.z), bfhi(w.z), bflo(w.w), bfhi(w.w)}; }
;     __device__ __forceinline__ void operator()(const f32x4 (&acc)[2][2][4][2], const Unit& u, int wr, int wc, int fr, int fq) const {
;     ...
;         for (int ai = 0; ai < 2; ++ai)
; #pragma unroll
;             for (int m = 0; m < 4; ++m) {
;                 const int row = row0 + ai * 128 + m * 16;
;                 const bf16_t* rowp = z + (size_t)row * DIN + col0;
; #pragma unroll
;                 for (int bj = 0; bj < 2; ++bj) {
;                     const u32x4 gw = *(const u32x4*)(rowp + O_GA + bj * 128);
;                     f32x4 g0, g1; unpack8(gw, g0, g1);
;                     f32x4 v0, v1;
; #pragma unroll
;                     for (int j = 0; j < 4; ++j) { v0[j] = sigmoidf_(g0[j]) * acc[ai][bj][m][0][j]; v1[j] = sigmoidf_(g1[j]) * acc[ai][bj][m][1][j]; }
;                     const u32x4 mw = *(const u32x4*)(rowp + bj * 128); f32x4 m0, m1; unpack8(mw, m0, m1); v0 += m0; v1 += m1;
;                     __builtin_amdgcn_raw_buffer_store_b128(pack8(v0, v1), rsrc, (unsigned)(((size_t)row * DIN + col0 + bj * 128) * 2), 0, 16  ); }
	v_pk_fma_f32 v[250:251], v[252:253], v[250:251], v[250:251]
	v_pk_fma_f32 v[252:253], v[246:247], v[250:251], 1.0 op_sel_hi:[1,1,0] neg_lo:[1,0,0] neg_hi:[1,0,0]
	v_pk_fma_f32 v[254:255], v[252:253], v[250:251], v[250:251]
	v_pk_fma_f32 v[252:253], v[246:247], v[254:255], 1.0 op_sel_hi:[1,1,0] neg_lo:[1,0,0] neg_hi:[1,0,0]
	v_pk_fma_f32 v[254:255], v[252:253], v[250:251], v[254:255]
	v_div_fixup_f32 v246, v254, v246, 1.0
	v_div_fixup_f32 v247, v255, v247, 1.0
	v_rcp_f32_e32 v250, v248
	v_rcp_f32_e32 v251, v249
	s_nop 0
	v_pk_fma_f32 v[252:253], v[248:249], v[250:251], 1.0 op_sel_hi:[1,1,0] neg_lo:[1,0,0] neg_hi:[1,0,0]
	v_pk_fma_f32 v[250:251], v[252:253], v[250:251], v[250:251]
	v_pk_fma_f32 v[252:253], v[248:249], v[250:251], 1.0 op_sel_hi:[1,1,0] neg_lo:[1,0,0] neg_hi:[1,0,0]
	v_pk_fma_f32 v[254:255], v[252:253], v[250:251], v[250:251]
	v_pk_fma_f32 v[252:253], v[248:249], v[254:255], 1.0 op_sel_hi:[1,1,0] neg_lo:[1,0,0] neg_hi:[1,0,0]
	v_pk_fma_f32 v[254:255], v[252:253], v[250:251], v[254:255]
	v_div_fixup_f32 v248, v254, v248, 1.0
	v_div_fixup_f32 v249, v255, v249, 1.0
	v_lshlrev_b32_e32 v154, 16, v124
	v_and_b32_e32 v155, 0xffff0000, v124
	v_lshlrev_b32_e32 v164, 16, v126
	v_and_b32_e32 v165, 0xffff0000, v126
	v_lshlrev_b32_e32 v126, 16, v127
	v_and_b32_e32 v127, 0xffff0000, v127
	v_lshlrev_b32_e32 v124, 16, v125
	v_and_b32_e32 v125, 0xffff0000, v125
	v_pk_fma_f32 v[116:117], v[116:117], v[242:243], v[154:155]
	v_pk_fma_f32 v[120:121], v[114:115], v[248:249], v[126:127]
	v_pk_fma_f32 v[114:115], v[112:113], v[244:245], v[164:165]
	v_cvt_pk_bf16_f32 v112, v116, v117
	v_pk_fma_f32 v[118:119], v[118:119], v[246:247], v[124:125]
	s_nop 0
	v_cvt_pk_bf16_f32 v113, v118, v119
	v_cvt_pk_bf16_f32 v114, v114, v115
	v_cvt_pk_bf16_f32 v115, v120, v121
	buffer_store_dwordx4 v[112:115], v147, s[24:27], 0 offen offset:256 sc1
	s_nop 1
	v_or_b32_e32 v112, 16, v162
	v_mad_i64_i32 v[114:115], s[6:7], v112, s77, 0
	v_lshl_add_u64 v[112:113], v[114:115], 1, s[38:39]
	v_lshl_add_u64 v[112:113], v[112:113], 0, v[148:149]
	v_add_co_u32_e32 v116, vcc, s78, v112
	s_nop 1
	v_addc_co_u32_e32 v117, vcc, 0, v113, vcc
	s_waitcnt vmcnt(6)
	v_mov_b64_e32 v[118:119], v[232:233]
	v_mov_b64_e32 v[120:121], v[234:235]
	v_mov_b64_e32 v[122:123], v[236:237]
	v_mov_b64_e32 v[124:125], v[238:239]
	v_add_u32_e32 v203, 0x45300, v202
	global_load_dwordx4 v[232:235], v203, s[38:39]
	v_add_u32_e32 v203, 0x44100, v202
	global_load_dwordx4 v[236:239], v203, s[38:39]
	s_mov_b32 s100, 0xbfb8aa3b
	v_lshlrev_b32_e32 v242, 16, v118
	v_and_b32_e32 v243, 0xffff0000, v118
	v_lshlrev_b32_e32 v244, 16, v120
	v_and_b32_e32 v245, 0xffff0000, v120
	v_lshlrev_b32_e32 v246, 16, v119
	v_and_b32_e32 v247, 0xffff0000, v119
	v_lshlrev_b32_e32 v248, 16, v121
	v_and_b32_e32 v249, 0xffff0000, v121
	v_pk_mul_f32 v[242:243], v[242:243], s[100:101] op_sel_hi:[1,0]
	v_pk_mul_f32 v[244:245], v[244:245], s[100:101] op_sel_hi:[1,0]
	v_pk_mul_f32 v[246:247], v[246:247], s[100:101] op_sel_hi:[1,0]
	v_pk_mul_f32 v[248:249], v[248:249], s[100:101] op_sel_hi:[1,0]
	v_exp_f32_e32 v242, v242
	v_exp_f32_e32 v243, v243
	v_exp_f32_e32 v244, v244
	v_exp_f32_e32 v245, v245
	v_exp_f32_e32 v246, v246
	v_exp_f32_e32 v247, v247
	v_exp_f32_e32 v248, v248
	v_exp_f32_e32 v249, v249
	s_nop 0
	v_pk_add_f32 v[242:243], v[242:243], 1.0 op_sel_hi:[1,0]
	v_pk_add_f32 v[244:245], v[244:245], 1.0 op_sel_hi:[1,0]
	v_pk_add_f32 v[246:247], v[246:247], 1.0 op_sel_hi:[1,0]
	v_pk_add_f32 v[248:249], v[248:249], 1.0 op_sel_hi:[1,0]
	v_rcp_f32_e32 v250, v242
	v_rcp_f32_e32 v251, v243
	s_nop 0
	v_pk_fma_f32 v[252:253], v[242:243], v[250:251], 1.0 op_sel_hi:[1,1,0] neg_lo:[1,0,0] neg_hi:[1,0,0]
	v_pk_fma_f32 v[250:251], v[252:253], v[250:251], v[250:251]
	v_pk_fma_f32 v[252:253], v[242:243], v[250:251], 1.0 op_sel_hi:[1,1,0] neg_lo:[1,0,0] neg_hi:[1,0,0]
	v_pk_fma_f32 v[254:255], v[252:253], v[250:251], v[250:251]
	v_pk_fma_f32 v[252:253], v[242:243], v[254:255], 1.0 op_sel_hi:[1,1,0] neg_lo:[1,0,0] neg_hi:[1,0,0]
	v_pk_fma_f32 v[254:255], v[252:253], v[250:251], v[254:255]
	v_div_fixup_f32 v242, v254, v242, 1.0
	v_div_fixup_f32 v243, v255, v243, 1.0
	v_rcp_f32_e32 v250, v244
	v_rcp_f32_e32 v251, v245
	s_nop 0
	v_pk_fma_f32 v[252:253], v[244:245], v[250:251], 1.0 op_sel_hi:[1,1,0] neg_lo:[1,0,0] neg_hi:[1,0,0]
	v_pk_fma_f32 v[250:251], v[252:253], v[250:251], v[250:251]
	v_pk_fma_f32 v[252:253], v[244:245], v[250:251], 1.0 op_sel_hi:[1,1,0] neg_lo:[1,0,0] neg_hi:[1,0,0]
	v_pk_fma_f32 v[254:255], v[252:253], v[250:251], v[250:251]
	v_pk_fma_f32 v[252:253], v[244:245], v[254:255], 1.0 op_sel_hi:[1,1,0] neg_lo:[1,0,0] neg_hi:[1,0,0]
	v_pk_fma_f32 v[254:255], v[252:253], v[250:251], v[254:255]
	v_div_fixup_f32 v244, v254, v244, 1.0
	v_div_fixup_f32 v245, v255, v245, 1.0
	v_rcp_f32_e32 v250, v246
	v_rcp_f32_e32 v251, v247
	s_nop 0
	v_pk_fma_f32 v[252:253], v[246:247], v[250:251], 1.0 op_sel_hi:[1,1,0] neg_lo:[1,0,0] neg_hi:[1,0,0]
	v_pk_fma_f32 v[250:251], v[252:253], v[250:251], v[250:251]
	v_pk_fma_f32 v[252:253], v[246:247], v[250:251], 1.0 op_sel_hi:[1,1,0] neg_lo:[1,0,0] neg_hi:[1,0,0]
	v_pk_fma_f32 v[254:255], v[252:253], v[250:251], v[250:251]
	v_pk_fma_f32 v[252:253], v[246:247], v[254:255], 1.0 op_sel_hi:[1,1,0] neg_lo:[1,0,0] neg_hi:[1,0,0]
	v_pk_fma_f32 v[254:255], v[252:253], v[250:251], v[254:255]
	v_div_fixup_f32 v246, v254, v246, 1.0
	v_div_fixup_f32 v247, v255, v247, 1.0
	v_rcp_f32_e32 v250, v248
	v_rcp_f32_e32 v251, v249
	s_nop 0
	v_pk_fma_f32 v[252:253], v[248:249], v[250:251], 1.0 op_sel_hi:[1,1,0] neg_lo:[1,0,0] neg_hi:[1,0,0]
	v_pk_fma_f32 v[250:251], v[252:253], v[250:251], v[250:251]
	v_pk_fma_f32 v[252:253], v[248:249], v[250:251], 1.0 op_sel_hi:[1,1,0] neg_lo:[1,0,0] neg_hi:[1,0,0]
	v_pk_fma_f32 v[254:255], v[252:253], v[250:251], v[250:251]
	v_pk_fma_f32 v[252:253], v[248:249], v[254:255], 1.0 op_sel_hi:[1,1,0] neg_lo:[1,0,0] neg_hi:[1,0,0]
	v_pk_fma_f32 v[254:255], v[252:253], v[250:251], v[254:255]
	v_div_fixup_f32 v248, v254, v248, 1.0
	v_div_fixup_f32 v249, v255, v249, 1.0
	v_and_b32_e32 v155, 0xffff0000, v124
	v_lshlrev_b32_e32 v152, 16, v122
	v_and_b32_e32 v153, 0xffff0000, v122
	v_lshlrev_b32_e32 v154, 16, v124
	v_lshlrev_b32_e32 v124, 16, v125
	v_and_b32_e32 v125, 0xffff0000, v125
	v_lshlrev_b32_e32 v122, 16, v123
	v_and_b32_e32 v123, 0xffff0000, v123
	v_pk_fma_f32 v[108:109], v[108:109], v[242:243], v[152:153]
	v_pk_fma_f32 v[118:119], v[106:107], v[248:249], v[124:125]
	v_pk_fma_f32 v[106:107], v[104:105], v[244:245], v[154:155]
	v_add_lshl_u32 v120, v146, v114, 1
	v_pk_fma_f32 v[110:111], v[110:111], v[246:247], v[122:123]
	v_cvt_pk_bf16_f32 v104, v108, v109
	s_nop 0
	v_cvt_pk_bf16_f32 v105, v110, v111
	v_cvt_pk_bf16_f32 v106, v106, v107
	v_cvt_pk_bf16_f32 v107, v118, v119
	buffer_store_dwordx4 v[104:107], v120, s[24:27], 0 offen sc1
	s_nop 0
	s_waitcnt vmcnt(7)
; __device__ __forceinline__ float sigmoidf_(float x) { return 1.0f / (1.0f + __expf(-x)); }
; __device__ __forceinline__ u32x4 pack8(const f32x4 v0, const f32x4 v1) { u32x4 w; w.x = pk2(v0[0], v0[1]); w.y = pk2(v0[2], v0[3]); w.z = pk2(v1[0], v1[1]); w.w = pk2(v1[2], v1[3]); return w; }
; __device__ __forceinline__ void unpack8(const u32x4 w, f32x4& v0, f32x4& v1) { v0 = (f32x4){bflo(w.x), bfhi(w.x), bflo(w.y), bfhi(w.y)}; v1 = (f32x4){bflo(w.z), bfhi(w.z), bflo(w.w), bfhi(w.w)}; }
;     __device__ __forceinline__ void operator()(const f32x4 (&acc)[2][2][4][2], const Unit& u, int wr, int wc, int fr, int fq) const {
;     ...
;         for (int ai = 0; ai < 2; ++ai)
; #pragma unroll
;             for (int m = 0; m < 4; ++m) {
;                 const int row = row0 + ai * 128 + m * 16;
;                 const bf16_t* rowp = z + (size_t)row * DIN + col0;
; #pragma unroll
;                 for (int bj = 0; bj < 2; ++bj) {
;                     const u32x4 gw = *(const u32x4*)(rowp + O_GA + bj * 128);
;                     f32x4 g0, g1; unpack8(gw, g0, g1);
;                     f32x4 v0, v1;
; #pragma unroll
;                     for (int j = 0; j < 4; ++j) { v0[j] = sigmoidf_(g0[j]) * acc[ai][bj][m][0][j]; v1[j] = sigmoidf_(g1[j]) * acc[ai][bj][m][1][j]; }
;                     const u32x4 mw = *(const u32x4*)(rowp + bj * 128); f32x4 m0, m1; unpack8(mw, m0, m1); v0 += m0; v1 += m1;
;                     __builtin_amdgcn_raw_buffer_store_b128(pack8(v0, v1), rsrc, (unsigned)(((size_t)row * DIN + col0 + bj * 128) * 2), 0, 16  ); }
	v_mov_b64_e32 v[104:105], v[204:205]
	v_mov_b64_e32 v[106:107], v[206:207]
	v_mov_b64_e32 v[108:109], v[208:209]
	v_mov_b64_e32 v[110:111], v[210:211]
	v_add_u32_e32 v203, 0x67200, v202
	global_load_dwordx4 v[204:207], v203, s[38:39]
	v_add_u32_e32 v203, 0x66000, v202
	global_load_dwordx4 v[208:211], v203, s[38:39]
	s_mov_b32 s100, 0xbfb8aa3b
	v_lshlrev_b32_e32 v242, 16, v106
	v_and_b32_e32 v243, 0xffff0000, v106
	v_lshlrev_b32_e32 v244, 16, v104
	v_and_b32_e32 v245, 0xffff0000, v104
	v_lshlrev_b32_e32 v246, 16, v105
	v_and_b32_e32 v247, 0xffff0000, v105
	v_lshlrev_b32_e32 v248, 16, v107
	v_and_b32_e32 v249, 0xffff0000, v107
	v_pk_mul_f32 v[242:243], v[242:243], s[100:101] op_sel_hi:[1,0]
	v_pk_mul_f32 v[244:245], v[244:245], s[100:101] op_sel_hi:[1,0]
	v_pk_mul_f32 v[246:247], v[246:247], s[100:101] op_sel_hi:[1,0]
	v_pk_mul_f32 v[248:249], v[248:249], s[100:101] op_sel_hi:[1,0]
	v_exp_f32_e32 v242, v242
	v_exp_f32_e32 v243, v243
	v_exp_f32_e32 v244, v244
	v_exp_f32_e32 v245, v245
	v_exp_f32_e32 v246, v246
	v_exp_f32_e32 v247, v247
	v_exp_f32_e32 v248, v248
	v_exp_f32_e32 v249, v249
	s_nop 0
	v_pk_add_f32 v[242:243], v[242:243], 1.0 op_sel_hi:[1,0]
	v_pk_add_f32 v[244:245], v[244:245], 1.0 op_sel_hi:[1,0]
	v_pk_add_f32 v[246:247], v[246:247], 1.0 op_sel_hi:[1,0]
	v_pk_add_f32 v[248:249], v[248:249], 1.0 op_sel_hi:[1,0]
	v_rcp_f32_e32 v250, v242
	v_rcp_f32_e32 v251, v243
	s_nop 0
	v_pk_fma_f32 v[252:253], v[242:243], v[250:251], 1.0 op_sel_hi:[1,1,0] neg_lo:[1,0,0] neg_hi:[1,0,0]
	v_pk_fma_f32 v[250:251], v[252:253], v[250:251], v[250:251]
	v_pk_fma_f32 v[252:253], v[242:243], v[250:251], 1.0 op_sel_hi:[1,1,0] neg_lo:[1,0,0] neg_hi:[1,0,0]
	v_pk_fma_f32 v[254:255], v[252:253], v[250:251], v[250:251]
	v_pk_fma_f32 v[252:253], v[242:243], v[254:255], 1.0 op_sel_hi:[1,1,0] neg_lo:[1,0,0] neg_hi:[1,0,0]
	v_pk_fma_f32 v[254:255], v[252:253], v[250:251], v[254:255]
	v_div_fixup_f32 v242, v254, v242, 1.0
	v_div_fixup_f32 v243, v255, v243, 1.0
	v_rcp_f32_e32 v250, v244
	v_rcp_f32_e32 v251, v245
	s_nop 0
	v_pk_fma_f32 v[252:253], v[244:245], v[250:251], 1.0 op_sel_hi:[1,1,0] neg_lo:[1,0,0] neg_hi:[1,0,0]
	v_pk_fma_f32 v[250:251], v[252:253], v[250:251], v[250:251]
	v_pk_fma_f32 v[252:253], v[244:245], v[250:251], 1.0 op_sel_hi:[1,1,0] neg_lo:[1,0,0] neg_hi:[1,0,0]
	v_pk_fma_f32 v[254:255], v[252:253], v[250:251], v[250:251]
	v_pk_fma_f32 v[252:253], v[244:245], v[254:255], 1.0 op_sel_hi:[1,1,0] neg_lo:[1,0,0] neg_hi:[1,0,0]
	v_pk_fma_f32 v[254:255], v[252:253], v[250:251], v[254:255]
	v_div_fixup_f32 v244, v254, v244, 1.0
	v_div_fixup_f32 v245, v255, v245, 1.0
	v_rcp_f32_e32 v250, v246
	v_rcp_f32_e32 v251, v247
	s_nop 0
	v_pk_fma_f32 v[252:253], v[246:247], v[250:251], 1.0 op_sel_hi:[1,1,0] neg_lo:[1,0,0] neg_hi:[1,0,0]
	v_pk_fma_f32 v[250:251], v[252:253], v[250:251], v[250:251]
	v_pk_fma_f32 v[252:253], v[246:247], v[250:251], 1.0 op_sel_hi:[1,1,0] neg_lo:[1,0,0] neg_hi:[1,0,0]
	v_pk_fma_f32 v[254:255], v[252:253], v[250:251], v[250:251]
	v_pk_fma_f32 v[252:253], v[246:247], v[254:255], 1.0 op_sel_hi:[1,1,0] neg_lo:[1,0,0] neg_hi:[1,0,0]
	v_pk_fma_f32 v[254:255], v[252:253], v[250:251], v[254:255]
	v_div_fixup_f32 v246, v254, v246, 1.0
	v_div_fixup_f32 v247, v255, v247, 1.0
	v_rcp_f32_e32 v250, v248
	v_rcp_f32_e32 v251, v249
	s_nop 0
	v_pk_fma_f32 v[252:253], v[248:249], v[250:251], 1.0 op_sel_hi:[1,1,0] neg_lo:[1,0,0] neg_hi:[1,0,0]
	v_pk_fma_f32 v[250:251], v[252:253], v[250:251], v[250:251]
	v_pk_fma_f32 v[252:253], v[248:249], v[250:251], 1.0 op_sel_hi:[1,1,0] neg_lo:[1,0,0] neg_hi:[1,0,0]
	v_pk_fma_f32 v[254:255], v[252:253], v[250:251], v[250:251]
	v_pk_fma_f32 v[252:253], v[248:249], v[254:255], 1.0 op_sel_hi:[1,1,0] neg_lo:[1,0,0] neg_hi:[1,0,0]
	v_pk_fma_f32 v[254:255], v[252:253], v[250:251], v[254:255]
	v_div_fixup_f32 v248, v254, v248, 1.0
	v_div_fixup_f32 v249, v255, v249, 1.0
	v_lshlrev_b32_e32 v116, 16, v108
	v_and_b32_e32 v117, 0xffff0000, v108
	v_lshlrev_b32_e32 v118, 16, v110
	v_and_b32_e32 v119, 0xffff0000, v110
	v_lshlrev_b32_e32 v110, 16, v111
	v_and_b32_e32 v111, 0xffff0000, v111
	v_lshlrev_b32_e32 v108, 16, v109
	v_and_b32_e32 v109, 0xffff0000, v109
	v_pk_fma_f32 v[100:101], v[100:101], v[244:245], v[116:117]
	v_pk_fma_f32 v[104:105], v[98:99], v[248:249], v[110:111]
	v_pk_fma_f32 v[98:99], v[96:97], v[242:243], v[118:119]
	v_cvt_pk_bf16_f32 v96, v100, v101
	v_pk_fma_f32 v[102:103], v[102:103], v[246:247], v[108:109]
	s_nop 0
	v_cvt_pk_bf16_f32 v97, v102, v103
	v_cvt_pk_bf16_f32 v98, v98, v99
	v_cvt_pk_bf16_f32 v99, v104, v105
	buffer_store_dwordx4 v[96:99], v120, s[24:27], 0 offen offset:256 sc1
	s_nop 1
	v_or_b32_e32 v96, 32, v162
	v_mad_i64_i32 v[98:99], s[6:7], v96, s77, 0
	v_lshl_add_u64 v[96:97], v[98:99], 1, s[38:39]
	v_lshl_add_u64 v[96:97], v[96:97], 0, v[148:149]
	v_add_co_u32_e32 v100, vcc, s78, v96
	s_nop 1
	v_addc_co_u32_e32 v101, vcc, 0, v97, vcc
	s_waitcnt vmcnt(7)
; __device__ __forceinline__ float sigmoidf_(float x) { return 1.0f / (1.0f + __expf(-x)); }
; __device__ __forceinline__ u32x4 pack8(const f32x4 v0, const f32x4 v1) { u32x4 w; w.x = pk2(v0[0], v0[1]); w.y = pk2(v0[2], v0[3]); w.z = pk2(v1[0], v1[1]); w.w = pk2(v1[2], v1[3]); return w; }
; __device__ __forceinline__ void unpack8(const u32x4 w, f32x4& v0, f32x4& v1) { v0 = (f32x4){bflo(w.x), bfhi(w.x), bflo(w.y), bfhi(w.y)}; v1 = (f32x4){bflo(w.z), bfhi(w.z), bflo(w.w), bfhi(w.w)}; }
;     __device__ __forceinline__ void operator()(const f32x4 (&acc)[2][2][4][2], const Unit& u, int wr, int wc, int fr, int fq) const {
;     ...
;         for (int ai = 0; ai < 2; ++ai)
; #pragma unroll
;             for (int m = 0; m < 4; ++m) {
;                 const int row = row0 + ai * 128 + m * 16;
;                 const bf16_t* rowp = z + (size_t)row * DIN + col0;
; #pragma unroll
;                 for (int bj = 0; bj < 2; ++bj) {
;                     const u32x4 gw = *(const u32x4*)(rowp + O_GA + bj * 128);
;                     f32x4 g0, g1; unpack8(gw, g0, g1);
;                     f32x4 v0, v1;
; #pragma unroll
;                     for (int j = 0; j < 4; ++j) { v0[j] = sigmoidf_(g0[j]) * acc[ai][bj][m][0][j]; v1[j] = sigmoidf_(g1[j]) * acc[ai][bj][m][1][j]; }
;                     const u32x4 mw = *(const u32x4*)(rowp + bj * 128); f32x4 m0, m1; unpack8(mw, m0, m1); v0 += m0; v1 += m1;
;                     __builtin_amdgcn_raw_buffer_store_b128(pack8(v0, v1), rsrc, (unsigned)(((size_t)row * DIN + col0 + bj * 128) * 2), 0, 16  ); }
	v_mov_b64_e32 v[102:103], v[212:213]
	v_mov_b64_e32 v[104:105], v[214:215]
	v_mov_b64_e32 v[106:107], v[216:217]
	v_mov_b64_e32 v[108:109], v[218:219]
	v_add_u32_e32 v203, 0x67300, v202
	global_load_dwordx4 v[212:215], v203, s[38:39]
	v_add_u32_e32 v203, 0x66100, v202
	global_load_dwordx4 v[216:219], v203, s[38:39]
	s_mov_b32 s100, 0xbfb8aa3b
	v_lshlrev_b32_e32 v242, 16, v102
	v_and_b32_e32 v243, 0xffff0000, v102
	v_lshlrev_b32_e32 v244, 16, v104
	v_and_b32_e32 v245, 0xffff0000, v104
	v_lshlrev_b32_e32 v246, 16, v103
	v_and_b32_e32 v247, 0xffff0000, v103
	v_lshlrev_b32_e32 v248, 16, v105
	v_and_b32_e32 v249, 0xffff0000, v105
	v_pk_mul_f32 v[242:243], v[242:243], s[100:101] op_sel_hi:[1,0]
	v_pk_mul_f32 v[244:245], v[244:245], s[100:101] op_sel_hi:[1,0]
	v_pk_mul_f32 v[246:247], v[246:247], s[100:101] op_sel_hi:[1,0]
	v_pk_mul_f32 v[248:249], v[248:249], s[100:101] op_sel_hi:[1,0]
	v_exp_f32_e32 v242, v242
	v_exp_f32_e32 v243, v243
	v_exp_f32_e32 v244, v244
	v_exp_f32_e32 v245, v245
	v_exp_f32_e32 v246, v246
	v_exp_f32_e32 v247, v247
	v_exp_f32_e32 v248, v248
	v_exp_f32_e32 v249, v249
	s_nop 0
	v_pk_add_f32 v[242:243], v[242:243], 1.0 op_sel_hi:[1,0]
	v_pk_add_f32 v[244:245], v[244:245], 1.0 op_sel_hi:[1,0]
	v_pk_add_f32 v[246:247], v[246:247], 1.0 op_sel_hi:[1,0]
	v_pk_add_f32 v[248:249], v[248:249], 1.0 op_sel_hi:[1,0]
	v_rcp_f32_e32 v250, v242
	v_rcp_f32_e32 v251, v243
	s_nop 0
	v_pk_fma_f32 v[252:253], v[242:243], v[250:251], 1.0 op_sel_hi:[1,1,0] neg_lo:[1,0,0] neg_hi:[1,0,0]
	v_pk_fma_f32 v[250:251], v[252:253], v[250:251], v[250:251]
	v_pk_fma_f32 v[252:253], v[242:243], v[250:251], 1.0 op_sel_hi:[1,1,0] neg_lo:[1,0,0] neg_hi:[1,0,0]
	v_pk_fma_f32 v[254:255], v[252:253], v[250:251], v[250:251]
	v_pk_fma_f32 v[252:253], v[242:243], v[254:255], 1.0 op_sel_hi:[1,1,0] neg_lo:[1,0,0] neg_hi:[1,0,0]
	v_pk_fma_f32 v[254:255], v[252:253], v[250:251], v[254:255]
	v_div_fixup_f32 v242, v254, v242, 1.0
	v_div_fixup_f32 v243, v255, v243, 1.0
	v_rcp_f32_e32 v250, v244
	v_rcp_f32_e32 v251, v245
	s_nop 0
	v_pk_fma_f32 v[252:253], v[244:245], v[250:251], 1.0 op_sel_hi:[1,1,0] neg_lo:[1,0,0] neg_hi:[1,0,0]
	v_pk_fma_f32 v[250:251], v[252:253], v[250:251], v[250:251]
	v_pk_fma_f32 v[252:253], v[244:245], v[250:251], 1.0 op_sel_hi:[1,1,0] neg_lo:[1,0,0] neg_hi:[1,0,0]
	v_pk_fma_f32 v[254:255], v[252:253], v[250:251], v[250:251]
	v_pk_fma_f32 v[252:253], v[244:245], v[254:255], 1.0 op_sel_hi:[1,1,0] neg_lo:[1,0,0] neg_hi:[1,0,0]
	v_pk_fma_f32 v[254:255], v[252:253], v[250:251], v[254:255]
	v_div_fixup_f32 v244, v254, v244, 1.0
	v_div_fixup_f32 v245, v255, v245, 1.0
	v_rcp_f32_e32 v250, v246
	v_rcp_f32_e32 v251, v247
	s_nop 0
	v_pk_fma_f32 v[252:253], v[246:247], v[250:251], 1.0 op_sel_hi:[1,1,0] neg_lo:[1,0,0] neg_hi:[1,0,0]
	v_pk_fma_f32 v[250:251], v[252:253], v[250:251], v[250:251]
	v_pk_fma_f32 v[252:253], v[246:247], v[250:251], 1.0 op_sel_hi:[1,1,0] neg_lo:[1,0,0] neg_hi:[1,0,0]
	v_pk_fma_f32 v[254:255], v[252:253], v[250:251], v[250:251]
	v_pk_fma_f32 v[252:253], v[246:247], v[254:255], 1.0 op_sel_hi:[1,1,0] neg_lo:[1,0,0] neg_hi:[1,0,0]
	v_pk_fma_f32 v[254:255], v[252:253], v[250:251], v[254:255]
	v_div_fixup_f32 v246, v254, v246, 1.0
	v_div_fixup_f32 v247, v255, v247, 1.0
	v_rcp_f32_e32 v250, v248
	v_rcp_f32_e32 v251, v249
	s_nop 0
	v_pk_fma_f32 v[252:253], v[248:249], v[250:251], 1.0 op_sel_hi:[1,1,0] neg_lo:[1,0,0] neg_hi:[1,0,0]
	v_pk_fma_f32 v[250:251], v[252:253], v[250:251], v[250:251]
	v_pk_fma_f32 v[252:253], v[248:249], v[250:251], 1.0 op_sel_hi:[1,1,0] neg_lo:[1,0,0] neg_hi:[1,0,0]
	v_pk_fma_f32 v[254:255], v[252:253], v[250:251], v[250:251]
	v_pk_fma_f32 v[252:253], v[248:249], v[254:255], 1.0 op_sel_hi:[1,1,0] neg_lo:[1,0,0] neg_hi:[1,0,0]
	v_pk_fma_f32 v[254:255], v[252:253], v[250:251], v[254:255]
	v_div_fixup_f32 v248, v254, v248, 1.0
	v_div_fixup_f32 v249, v255, v249, 1.0
	v_lshlrev_b32_e32 v114, 16, v106
	v_and_b32_e32 v115, 0xffff0000, v106
	v_lshlrev_b32_e32 v116, 16, v108
	v_and_b32_e32 v117, 0xffff0000, v108
	v_lshlrev_b32_e32 v108, 16, v109
	v_and_b32_e32 v109, 0xffff0000, v109
	v_lshlrev_b32_e32 v106, 16, v107
	v_and_b32_e32 v107, 0xffff0000, v107
	v_pk_fma_f32 v[92:93], v[92:93], v[242:243], v[114:115]
	v_pk_fma_f32 v[102:103], v[90:91], v[248:249], v[108:109]
	v_pk_fma_f32 v[90:91], v[88:89], v[244:245], v[116:117]
	v_add_lshl_u32 v104, v146, v98, 1
	v_pk_fma_f32 v[94:95], v[94:95], v[246:247], v[106:107]
	v_cvt_pk_bf16_f32 v88, v92, v93
	s_nop 0
	v_cvt_pk_bf16_f32 v89, v94, v95
	v_cvt_pk_bf16_f32 v90, v90, v91
	v_cvt_pk_bf16_f32 v91, v102, v103
	buffer_store_dwordx4 v[88:91], v104, s[24:27], 0 offen sc1
	s_nop 0
	s_waitcnt vmcnt(7)
; __device__ __forceinline__ float sigmoidf_(float x) { return 1.0f / (1.0f + __expf(-x)); }
; __device__ __forceinline__ u32x4 pack8(const f32x4 v0, const f32x4 v1) { u32x4 w; w.x = pk2(v0[0], v0[1]); w.y = pk2(v0[2], v0[3]); w.z = pk2(v1[0], v1[1]); w.w = pk2(v1[2], v1[3]); return w; }
; __device__ __forceinline__ void unpack8(const u32x4 w, f32x4& v0, f32x4& v1) { v0 = (f32x4){bflo(w.x), bfhi(w.x), bflo(w.y), bfhi(w.y)}; v1 = (f32x4){bflo(w.z), bfhi(w.z), bflo(w.w), bfhi(w.w)}; }
;     __device__ __forceinline__ void operator()(const f32x4 (&acc)[2][2][4][2], const Unit& u, int wr, int wc, int fr, int fq) const {
;     ...
;                 for (int bj = 0; bj < 2; ++bj) {
;                     const u32x4 gw = *(const u32x4*)(rowp + O_GA + bj * 128);
;                     f32x4 g0, g1; unpack8(gw, g0, g1);
;                     f32x4 v0, v1;
; #pragma unroll
;                     for (int j = 0; j < 4; ++j) { v0[j] = sigmoidf_(g0[j]) * acc[ai][bj][m][0][j]; v1[j] = sigmoidf_(g1[j]) * acc[ai][bj][m][1][j]; }
;                     const u32x4 mw = *(const u32x4*)(rowp + bj * 128); f32x4 m0, m1; unpack8(mw, m0, m1); v0 += m0; v1 += m1;
;                     __builtin_amdgcn_raw_buffer_store_b128(pack8(v0, v1), rsrc, (unsigned)(((size_t)row * DIN + col0 + bj * 128) * 2), 0, 16  ); }
	v_mov_b64_e32 v[88:89], v[232:233]
	v_mov_b64_e32 v[90:91], v[234:235]
	v_mov_b64_e32 v[92:93], v[236:237]
	v_mov_b64_e32 v[94:95], v[238:239]
	v_add_u32_e32 v203, 0x111200, v202
	global_load_dwordx4 v[232:235], v203, s[38:39]
	v_add_u32_e32 v203, 0x110000, v202
	global_load_dwordx4 v[236:239], v203, s[38:39]
	s_mov_b32 s100, 0xbfb8aa3b
	v_lshlrev_b32_e32 v242, 16, v90
	v_and_b32_e32 v243, 0xffff0000, v90
	v_lshlrev_b32_e32 v244, 16, v88
	v_and_b32_e32 v245, 0xffff0000, v88
	v_lshlrev_b32_e32 v246, 16, v89
	v_and_b32_e32 v247, 0xffff0000, v89
	v_lshlrev_b32_e32 v248, 16, v91
	v_and_b32_e32 v249, 0xffff0000, v91
	v_pk_mul_f32 v[242:243], v[242:243], s[100:101] op_sel_hi:[1,0]
	v_pk_mul_f32 v[244:245], v[244:245], s[100:101] op_sel_hi:[1,0]
	v_pk_mul_f32 v[246:247], v[246:247], s[100:101] op_sel_hi:[1,0]
	v_pk_mul_f32 v[248:249], v[248:249], s[100:101] op_sel_hi:[1,0]
	v_exp_f32_e32 v242, v242
	v_exp_f32_e32 v243, v243
	v_exp_f32_e32 v244, v244
	v_exp_f32_e32 v245, v245
	v_exp_f32_e32 v246, v246
	v_exp_f32_e32 v247, v247
	v_exp_f32_e32 v248, v248
	v_exp_f32_e32 v249, v249
	s_nop 0
	v_pk_add_f32 v[242:243], v[242:243], 1.0 op_sel_hi:[1,0]
	v_pk_add_f32 v[244:245], v[244:245], 1.0 op_sel_hi:[1,0]
	v_pk_add_f32 v[246:247], v[246:247], 1.0 op_sel_hi:[1,0]
	v_pk_add_f32 v[248:249], v[248:249], 1.0 op_sel_hi:[1,0]
	v_rcp_f32_e32 v250, v242
	v_rcp_f32_e32 v251, v243
	s_nop 0
	v_pk_fma_f32 v[252:253], v[242:243], v[250:251], 1.0 op_sel_hi:[1,1,0] neg_lo:[1,0,0] neg_hi:[1,0,0]
	v_pk_fma_f32 v[250:251], v[252:253], v[250:251], v[250:251]
	v_pk_fma_f32 v[252:253], v[242:243], v[250:251], 1.0 op_sel_hi:[1,1,0] neg_lo:[1,0,0] neg_hi:[1,0,0]
	v_pk_fma_f32 v[254:255], v[252:253], v[250:251], v[250:251]
	v_pk_fma_f32 v[252:253], v[242:243], v[254:255], 1.0 op_sel_hi:[1,1,0] neg_lo:[1,0,0] neg_hi:[1,0,0]
	v_pk_fma_f32 v[254:255], v[252:253], v[250:251], v[254:255]
	v_div_fixup_f32 v242, v254, v242, 1.0
	v_div_fixup_f32 v243, v255, v243, 1.0
	v_rcp_f32_e32 v250, v244
	v_rcp_f32_e32 v251, v245
	s_nop 0
	v_pk_fma_f32 v[252:253], v[244:245], v[250:251], 1.0 op_sel_hi:[1,1,0] neg_lo:[1,0,0] neg_hi:[1,0,0]
	v_pk_fma_f32 v[250:251], v[252:253], v[250:251], v[250:251]
	v_pk_fma_f32 v[252:253], v[244:245], v[250:251], 1.0 op_sel_hi:[1,1,0] neg_lo:[1,0,0] neg_hi:[1,0,0]
	v_pk_fma_f32 v[254:255], v[252:253], v[250:251], v[250:251]
	v_pk_fma_f32 v[252:253], v[244:245], v[254:255], 1.0 op_sel_hi:[1,1,0] neg_lo:[1,0,0] neg_hi:[1,0,0]
	v_pk_fma_f32 v[254:255], v[252:253], v[250:251], v[254:255]
	v_div_fixup_f32 v244, v254, v244, 1.0
	v_div_fixup_f32 v245, v255, v245, 1.0
	v_rcp_f32_e32 v250, v246
	v_rcp_f32_e32 v251, v247
	s_nop 0
	v_pk_fma_f32 v[252:253], v[246:247], v[250:251], 1.0 op_sel_hi:[1,1,0] neg_lo:[1,0,0] neg_hi:[1,0,0]
	v_pk_fma_f32 v[250:251], v[252:253], v[250:251], v[250:251]
	v_pk_fma_f32 v[252:253], v[246:247], v[250:251], 1.0 op_sel_hi:[1,1,0] neg_lo:[1,0,0] neg_hi:[1,0,0]
	v_pk_fma_f32 v[254:255], v[252:253], v[250:251], v[250:251]
	v_pk_fma_f32 v[252:253], v[246:247], v[254:255], 1.0 op_sel_hi:[1,1,0] neg_lo:[1,0,0] neg_hi:[1,0,0]
	v_pk_fma_f32 v[254:255], v[252:253], v[250:251], v[254:255]
	v_div_fixup_f32 v246, v254, v246, 1.0
	v_div_fixup_f32 v247, v255, v247, 1.0
	v_rcp_f32_e32 v250, v248
	v_rcp_f32_e32 v251, v249
	s_nop 0
	v_pk_fma_f32 v[252:253], v[248:249], v[250:251], 1.0 op_sel_hi:[1,1,0] neg_lo:[1,0,0] neg_hi:[1,0,0]
	v_pk_fma_f32 v[250:251], v[252:253], v[250:251], v[250:251]
	v_pk_fma_f32 v[252:253], v[248:249], v[250:251], 1.0 op_sel_hi:[1,1,0] neg_lo:[1,0,0] neg_hi:[1,0,0]
	v_pk_fma_f32 v[254:255], v[252:253], v[250:251], v[250:251]
	v_pk_fma_f32 v[252:253], v[248:249], v[254:255], 1.0 op_sel_hi:[1,1,0] neg_lo:[1,0,0] neg_hi:[1,0,0]
	v_pk_fma_f32 v[254:255], v[252:253], v[250:251], v[254:255]
	v_div_fixup_f32 v248, v254, v248, 1.0
	v_div_fixup_f32 v249, v255, v249, 1.0
	v_lshlrev_b32_e32 v100, 16, v92
	v_and_b32_e32 v101, 0xffff0000, v92
	v_lshlrev_b32_e32 v102, 16, v94
	v_and_b32_e32 v103, 0xffff0000, v94
	v_lshlrev_b32_e32 v94, 16, v95
	v_and_b32_e32 v95, 0xffff0000, v95
	v_lshlrev_b32_e32 v92, 16, v93
	v_and_b32_e32 v93, 0xffff0000, v93
	v_pk_fma_f32 v[84:85], v[84:85], v[244:245], v[100:101]
	v_pk_fma_f32 v[88:89], v[82:83], v[248:249], v[94:95]
	v_pk_fma_f32 v[82:83], v[80:81], v[242:243], v[102:103]
	v_cvt_pk_bf16_f32 v80, v84, v85
	v_pk_fma_f32 v[86:87], v[86:87], v[246:247], v[92:93]
	s_nop 0
	v_cvt_pk_bf16_f32 v81, v86, v87
	v_cvt_pk_bf16_f32 v82, v82, v83
	v_cvt_pk_bf16_f32 v83, v88, v89
	buffer_store_dwordx4 v[80:83], v104, s[24:27], 0 offen offset:256 sc1
	s_nop 1
	v_or_b32_e32 v80, 48, v162
	v_mad_i64_i32 v[82:83], s[6:7], v80, s77, 0
	v_lshl_add_u64 v[80:81], v[82:83], 1, s[38:39]
	v_lshl_add_u64 v[80:81], v[80:81], 0, v[148:149]
	v_add_co_u32_e32 v84, vcc, s78, v80
	s_nop 1
	v_addc_co_u32_e32 v85, vcc, 0, v81, vcc
	s_waitcnt vmcnt(7)
; __device__ __forceinline__ float sigmoidf_(float x) { return 1.0f / (1.0f + __expf(-x)); }
; __device__ __forceinline__ u32x4 pack8(const f32x4 v0, const f32x4 v1) { u32x4 w; w.x = pk2(v0[0], v0[1]); w.y = pk2(v0[2], v0[3]); w.z = pk2(v1[0], v1[1]); w.w = pk2(v1[2], v1[3]); return w; }
; __device__ __forceinline__ void unpack8(const u32x4 w, f32x4& v0, f32x4& v1) { v0 = (f32x4){bflo(w.x), bfhi(w.x), bflo(w.y), bfhi(w.y)}; v1 = (f32x4){bflo(w.z), bfhi(w.z), bflo(w.w), bfhi(w.w)}; }
;     __device__ __forceinline__ void operator()(const f32x4 (&acc)[2][2][4][2], const Unit& u, int wr, int wc, int fr, int fq) const {
;     ...
;                 for (int bj = 0; bj < 2; ++bj) {
;                     const u32x4 gw = *(const u32x4*)(rowp + O_GA + bj * 128);
;                     f32x4 g0, g1; unpack8(gw, g0, g1);
;                     f32x4 v0, v1;
; #pragma unroll
;                     for (int j = 0; j < 4; ++j) { v0[j] = sigmoidf_(g0[j]) * acc[ai][bj][m][0][j]; v1[j] = sigmoidf_(g1[j]) * acc[ai][bj][m][1][j]; }
;                     const u32x4 mw = *(const u32x4*)(rowp + bj * 128); f32x4 m0, m1; unpack8(mw, m0, m1); v0 += m0; v1 += m1;
;                     __builtin_amdgcn_raw_buffer_store_b128(pack8(v0, v1), rsrc, (unsigned)(((size_t)row * DIN + col0 + bj * 128) * 2), 0, 16  ); }
	v_mov_b64_e32 v[86:87], v[204:205]
	v_mov_b64_e32 v[88:89], v[206:207]
	v_mov_b64_e32 v[90:91], v[208:209]
	v_mov_b64_e32 v[92:93], v[210:211]
	v_add_u32_e32 v203, 0x111300, v202
	global_load_dwordx4 v[204:207], v203, s[38:39]
	v_add_u32_e32 v203, 0x110100, v202
	global_load_dwordx4 v[208:211], v203, s[38:39]
	s_mov_b32 s100, 0xbfb8aa3b
	v_lshlrev_b32_e32 v242, 16, v86
	v_and_b32_e32 v243, 0xffff0000, v86
	v_lshlrev_b32_e32 v244, 16, v88
	v_and_b32_e32 v245, 0xffff0000, v88
	v_lshlrev_b32_e32 v246, 16, v87
	v_and_b32_e32 v247, 0xffff0000, v87
	v_lshlrev_b32_e32 v248, 16, v89
	v_and_b32_e32 v249, 0xffff0000, v89
	v_pk_mul_f32 v[242:243], v[242:243], s[100:101] op_sel_hi:[1,0]
	v_pk_mul_f32 v[244:245], v[244:245], s[100:101] op_sel_hi:[1,0]
	v_pk_mul_f32 v[246:247], v[246:247], s[100:101] op_sel_hi:[1,0]
	v_pk_mul_f32 v[248:249], v[248:249], s[100:101] op_sel_hi:[1,0]
	v_exp_f32_e32 v242, v242
	v_exp_f32_e32 v243, v243
	v_exp_f32_e32 v244, v244
	v_exp_f32_e32 v245, v245
	v_exp_f32_e32 v246, v246
	v_exp_f32_e32 v247, v247
	v_exp_f32_e32 v248, v248
	v_exp_f32_e32 v249, v249
	s_nop 0
	v_pk_add_f32 v[242:243], v[242:243], 1.0 op_sel_hi:[1,0]
	v_pk_add_f32 v[244:245], v[244:245], 1.0 op_sel_hi:[1,0]
	v_pk_add_f32 v[246:247], v[246:247], 1.0 op_sel_hi:[1,0]
	v_pk_add_f32 v[248:249], v[248:249], 1.0 op_sel_hi:[1,0]
	v_rcp_f32_e32 v250, v242
	v_rcp_f32_e32 v251, v243
	s_nop 0
	v_pk_fma_f32 v[252:253], v[242:243], v[250:251], 1.0 op_sel_hi:[1,1,0] neg_lo:[1,0,0] neg_hi:[1,0,0]
	v_pk_fma_f32 v[250:251], v[252:253], v[250:251], v[250:251]
	v_pk_fma_f32 v[252:253], v[242:243], v[250:251], 1.0 op_sel_hi:[1,1,0] neg_lo:[1,0,0] neg_hi:[1,0,0]
	v_pk_fma_f32 v[254:255], v[252:253], v[250:251], v[250:251]
	v_pk_fma_f32 v[252:253], v[242:243], v[254:255], 1.0 op_sel_hi:[1,1,0] neg_lo:[1,0,0] neg_hi:[1,0,0]
	v_pk_fma_f32 v[254:255], v[252:253], v[250:251], v[254:255]
	v_div_fixup_f32 v242, v254, v242, 1.0
	v_div_fixup_f32 v243, v255, v243, 1.0
	v_rcp_f32_e32 v250, v244
	v_rcp_f32_e32 v251, v245
	s_nop 0
	v_pk_fma_f32 v[252:253], v[244:245], v[250:251], 1.0 op_sel_hi:[1,1,0] neg_lo:[1,0,0] neg_hi:[1,0,0]
	v_pk_fma_f32 v[250:251], v[252:253], v[250:251], v[250:251]
	v_pk_fma_f32 v[252:253], v[244:245], v[250:251], 1.0 op_sel_hi:[1,1,0] neg_lo:[1,0,0] neg_hi:[1,0,0]
	v_pk_fma_f32 v[254:255], v[252:253], v[250:251], v[250:251]
	v_pk_fma_f32 v[252:253], v[244:245], v[254:255], 1.0 op_sel_hi:[1,1,0] neg_lo:[1,0,0] neg_hi:[1,0,0]
	v_pk_fma_f32 v[254:255], v[252:253], v[250:251], v[254:255]
	v_div_fixup_f32 v244, v254, v244, 1.0
	v_div_fixup_f32 v245, v255, v245, 1.0
	v_rcp_f32_e32 v250, v246
	v_rcp_f32_e32 v251, v247
	s_nop 0
	v_pk_fma_f32 v[252:253], v[246:247], v[250:251], 1.0 op_sel_hi:[1,1,0] neg_lo:[1,0,0] neg_hi:[1,0,0]
	v_pk_fma_f32 v[250:251], v[252:253], v[250:251], v[250:251]
	v_pk_fma_f32 v[252:253], v[246:247], v[250:251], 1.0 op_sel_hi:[1,1,0] neg_lo:[1,0,0] neg_hi:[1,0,0]
	v_pk_fma_f32 v[254:255], v[252:253], v[250:251], v[250:251]
	v_pk_fma_f32 v[252:253], v[246:247], v[254:255], 1.0 op_sel_hi:[1,1,0] neg_lo:[1,0,0] neg_hi:[1,0,0]
	v_pk_fma_f32 v[254:255], v[252:253], v[250:251], v[254:255]
	v_div_fixup_f32 v246, v254, v246, 1.0
	v_div_fixup_f32 v247, v255, v247, 1.0
	v_rcp_f32_e32 v250, v248
	v_rcp_f32_e32 v251, v249
	s_nop 0
	v_pk_fma_f32 v[252:253], v[248:249], v[250:251], 1.0 op_sel_hi:[1,1,0] neg_lo:[1,0,0] neg_hi:[1,0,0]
	v_pk_fma_f32 v[250:251], v[252:253], v[250:251], v[250:251]
	v_pk_fma_f32 v[252:253], v[248:249], v[250:251], 1.0 op_sel_hi:[1,1,0] neg_lo:[1,0,0] neg_hi:[1,0,0]
	v_pk_fma_f32 v[254:255], v[252:253], v[250:251], v[250:251]
	v_pk_fma_f32 v[252:253], v[248:249], v[254:255], 1.0 op_sel_hi:[1,1,0] neg_lo:[1,0,0] neg_hi:[1,0,0]
	v_pk_fma_f32 v[254:255], v[252:253], v[250:251], v[254:255]
	v_div_fixup_f32 v248, v254, v248, 1.0
	v_div_fixup_f32 v249, v255, v249, 1.0
	v_lshlrev_b32_e32 v98, 16, v90
	v_and_b32_e32 v99, 0xffff0000, v90
	v_lshlrev_b32_e32 v100, 16, v92
	v_and_b32_e32 v101, 0xffff0000, v92
	v_lshlrev_b32_e32 v92, 16, v93
	v_and_b32_e32 v93, 0xffff0000, v93
	v_lshlrev_b32_e32 v90, 16, v91
	v_and_b32_e32 v91, 0xffff0000, v91
	v_pk_fma_f32 v[76:77], v[76:77], v[242:243], v[98:99]
	v_pk_fma_f32 v[86:87], v[74:75], v[248:249], v[92:93]
	v_pk_fma_f32 v[74:75], v[72:73], v[244:245], v[100:101]
	v_add_lshl_u32 v88, v146, v82, 1
	v_pk_fma_f32 v[78:79], v[78:79], v[246:247], v[90:91]
	v_cvt_pk_bf16_f32 v72, v76, v77
	s_nop 0
	v_cvt_pk_bf16_f32 v73, v78, v79
	v_cvt_pk_bf16_f32 v74, v74, v75
	v_cvt_pk_bf16_f32 v75, v86, v87
	buffer_store_dwordx4 v[72:75], v88, s[24:27], 0 offen sc1
	s_nop 0
	s_waitcnt vmcnt(7)
; __device__ __forceinline__ float sigmoidf_(float x) { return 1.0f / (1.0f + __expf(-x)); }
; __device__ __forceinline__ u32x4 pack8(const f32x4 v0, const f32x4 v1) { u32x4 w; w.x = pk2(v0[0], v0[1]); w.y = pk2(v0[2], v0[3]); w.z = pk2(v1[0], v1[1]); w.w = pk2(v1[2], v1[3]); return w; }
; __device__ __forceinline__ void unpack8(const u32x4 w, f32x4& v0, f32x4& v1) { v0 = (f32x4){bflo(w.x), bfhi(w.x), bflo(w.y), bfhi(w.y)}; v1 = (f32x4){bflo(w.z), bfhi(w.z), bflo(w.w), bfhi(w.w)}; }
;     __device__ __forceinline__ void operator()(const f32x4 (&acc)[2][2][4][2], const Unit& u, int wr, int wc, int fr, int fq) const {
;     ...
;                 for (int bj = 0; bj < 2; ++bj) {
;                     const u32x4 gw = *(const u32x4*)(rowp + O_GA + bj * 128);
;                     f32x4 g0, g1; unpack8(gw, g0, g1);
;                     f32x4 v0, v1;
; #pragma unroll
;                     for (int j = 0; j < 4; ++j) { v0[j] = sigmoidf_(g0[j]) * acc[ai][bj][m][0][j]; v1[j] = sigmoidf_(g1[j]) * acc[ai][bj][m][1][j]; }
;                     const u32x4 mw = *(const u32x4*)(rowp + bj * 128); f32x4 m0, m1; unpack8(mw, m0, m1); v0 += m0; v1 += m1;
;                     __builtin_amdgcn_raw_buffer_store_b128(pack8(v0, v1), rsrc, (unsigned)(((size_t)row * DIN + col0 + bj * 128) * 2), 0, 16  ); }
	v_mov_b64_e32 v[72:73], v[212:213]
	v_mov_b64_e32 v[74:75], v[214:215]
	v_mov_b64_e32 v[76:77], v[216:217]
	v_mov_b64_e32 v[78:79], v[218:219]
	v_add_u32_e32 v203, 0x133200, v202
	global_load_dwordx4 v[212:215], v203, s[38:39]
	v_add_u32_e32 v203, 0x132000, v202
	global_load_dwordx4 v[216:219], v203, s[38:39]
	s_mov_b32 s100, 0xbfb8aa3b
	v_lshlrev_b32_e32 v242, 16, v74
	v_and_b32_e32 v243, 0xffff0000, v74
	v_lshlrev_b32_e32 v244, 16, v72
	v_and_b32_e32 v245, 0xffff0000, v72
	v_lshlrev_b32_e32 v246, 16, v73
	v_and_b32_e32 v247, 0xffff0000, v73
	v_lshlrev_b32_e32 v248, 16, v75
	v_and_b32_e32 v249, 0xffff0000, v75
	v_pk_mul_f32 v[242:243], v[242:243], s[100:101] op_sel_hi:[1,0]
	v_pk_mul_f32 v[244:245], v[244:245], s[100:101] op_sel_hi:[1,0]
	v_pk_mul_f32 v[246:247], v[246:247], s[100:101] op_sel_hi:[1,0]
	v_pk_mul_f32 v[248:249], v[248:249], s[100:101] op_sel_hi:[1,0]
	v_exp_f32_e32 v242, v242
	v_exp_f32_e32 v243, v243
	v_exp_f32_e32 v244, v244
	v_exp_f32_e32 v245, v245
	v_exp_f32_e32 v246, v246
	v_exp_f32_e32 v247, v247
	v_exp_f32_e32 v248, v248
	v_exp_f32_e32 v249, v249
	s_nop 0
	v_pk_add_f32 v[242:243], v[242:243], 1.0 op_sel_hi:[1,0]
	v_pk_add_f32 v[244:245], v[244:245], 1.0 op_sel_hi:[1,0]
	v_pk_add_f32 v[246:247], v[246:247], 1.0 op_sel_hi:[1,0]
	v_pk_add_f32 v[248:249], v[248:249], 1.0 op_sel_hi:[1,0]
	v_rcp_f32_e32 v250, v242
	v_rcp_f32_e32 v251, v243
	s_nop 0
	v_pk_fma_f32 v[252:253], v[242:243], v[250:251], 1.0 op_sel_hi:[1,1,0] neg_lo:[1,0,0] neg_hi:[1,0,0]
	v_pk_fma_f32 v[250:251], v[252:253], v[250:251], v[250:251]
	v_pk_fma_f32 v[252:253], v[242:243], v[250:251], 1.0 op_sel_hi:[1,1,0] neg_lo:[1,0,0] neg_hi:[1,0,0]
	v_pk_fma_f32 v[254:255], v[252:253], v[250:251], v[250:251]
	v_pk_fma_f32 v[252:253], v[242:243], v[254:255], 1.0 op_sel_hi:[1,1,0] neg_lo:[1,0,0] neg_hi:[1,0,0]
	v_pk_fma_f32 v[254:255], v[252:253], v[250:251], v[254:255]
	v_div_fixup_f32 v242, v254, v242, 1.0
	v_div_fixup_f32 v243, v255, v243, 1.0
	v_rcp_f32_e32 v250, v244
	v_rcp_f32_e32 v251, v245
	s_nop 0
	v_pk_fma_f32 v[252:253], v[244:245], v[250:251], 1.0 op_sel_hi:[1,1,0] neg_lo:[1,0,0] neg_hi:[1,0,0]
	v_pk_fma_f32 v[250:251], v[252:253], v[250:251], v[250:251]
	v_pk_fma_f32 v[252:253], v[244:245], v[250:251], 1.0 op_sel_hi:[1,1,0] neg_lo:[1,0,0] neg_hi:[1,0,0]
	v_pk_fma_f32 v[254:255], v[252:253], v[250:251], v[250:251]
	v_pk_fma_f32 v[252:253], v[244:245], v[254:255], 1.0 op_sel_hi:[1,1,0] neg_lo:[1,0,0] neg_hi:[1,0,0]
	v_pk_fma_f32 v[254:255], v[252:253], v[250:251], v[254:255]
	v_div_fixup_f32 v244, v254, v244, 1.0
	v_div_fixup_f32 v245, v255, v245, 1.0
	v_rcp_f32_e32 v250, v246
	v_rcp_f32_e32 v251, v247
	s_nop 0
	v_pk_fma_f32 v[252:253], v[246:247], v[250:251], 1.0 op_sel_hi:[1,1,0] neg_lo:[1,0,0] neg_hi:[1,0,0]
	v_pk_fma_f32 v[250:251], v[252:253], v[250:251], v[250:251]
	v_pk_fma_f32 v[252:253], v[246:247], v[250:251], 1.0 op_sel_hi:[1,1,0] neg_lo:[1,0,0] neg_hi:[1,0,0]
	v_pk_fma_f32 v[254:255], v[252:253], v[250:251], v[250:251]
	v_pk_fma_f32 v[252:253], v[246:247], v[254:255], 1.0 op_sel_hi:[1,1,0] neg_lo:[1,0,0] neg_hi:[1,0,0]
	v_pk_fma_f32 v[254:255], v[252:253], v[250:251], v[254:255]
	v_div_fixup_f32 v246, v254, v246, 1.0
	v_div_fixup_f32 v247, v255, v247, 1.0
	v_rcp_f32_e32 v250, v248
	v_rcp_f32_e32 v251, v249
	s_nop 0
	v_pk_fma_f32 v[252:253], v[248:249], v[250:251], 1.0 op_sel_hi:[1,1,0] neg_lo:[1,0,0] neg_hi:[1,0,0]
	v_pk_fma_f32 v[250:251], v[252:253], v[250:251], v[250:251]
	v_pk_fma_f32 v[252:253], v[248:249], v[250:251], 1.0 op_sel_hi:[1,1,0] neg_lo:[1,0,0] neg_hi:[1,0,0]
	v_pk_fma_f32 v[254:255], v[252:253], v[250:251], v[250:251]
	v_pk_fma_f32 v[252:253], v[248:249], v[254:255], 1.0 op_sel_hi:[1,1,0] neg_lo:[1,0,0] neg_hi:[1,0,0]
	v_pk_fma_f32 v[254:255], v[252:253], v[250:251], v[254:255]
	v_div_fixup_f32 v248, v254, v248, 1.0
	v_div_fixup_f32 v249, v255, v249, 1.0
	v_lshlrev_b32_e32 v84, 16, v76
	v_and_b32_e32 v85, 0xffff0000, v76
	v_lshlrev_b32_e32 v86, 16, v78
	v_and_b32_e32 v87, 0xffff0000, v78
	v_lshlrev_b32_e32 v78, 16, v79
	v_and_b32_e32 v79, 0xffff0000, v79
	v_lshlrev_b32_e32 v76, 16, v77
	v_and_b32_e32 v77, 0xffff0000, v77
	v_pk_fma_f32 v[68:69], v[68:69], v[244:245], v[84:85]
	v_pk_fma_f32 v[72:73], v[66:67], v[248:249], v[78:79]
	v_pk_fma_f32 v[66:67], v[64:65], v[242:243], v[86:87]
	v_cvt_pk_bf16_f32 v64, v68, v69
	v_pk_fma_f32 v[70:71], v[70:71], v[246:247], v[76:77]
	s_nop 0
	v_cvt_pk_bf16_f32 v65, v70, v71
	v_cvt_pk_bf16_f32 v66, v66, v67
	v_cvt_pk_bf16_f32 v67, v72, v73
	buffer_store_dwordx4 v[64:67], v88, s[24:27], 0 offen offset:256 sc1
	s_nop 1
	v_add_u32_e32 v64, 0x80, v162
	v_mad_i64_i32 v[66:67], s[6:7], v64, s77, 0
	v_lshl_add_u64 v[64:65], v[66:67], 1, s[38:39]
	v_lshl_add_u64 v[64:65], v[64:65], 0, v[148:149]
	v_add_co_u32_e32 v68, vcc, s78, v64
	s_nop 1
	v_addc_co_u32_e32 v69, vcc, 0, v65, vcc
	s_waitcnt vmcnt(7)
; __device__ __forceinline__ float sigmoidf_(float x) { return 1.0f / (1.0f + __expf(-x)); }
; __device__ __forceinline__ u32x4 pack8(const f32x4 v0, const f32x4 v1) { u32x4 w; w.x = pk2(v0[0], v0[1]); w.y = pk2(v0[2], v0[3]); w.z = pk2(v1[0], v1[1]); w.w = pk2(v1[2], v1[3]); return w; }
; __device__ __forceinline__ void unpack8(const u32x4 w, f32x4& v0, f32x4& v1) { v0 = (f32x4){bflo(w.x), bfhi(w.x), bflo(w.y), bfhi(w.y)}; v1 = (f32x4){bflo(w.z), bfhi(w.z), bflo(w.w), bfhi(w.w)}; }
;     __device__ __forceinline__ void operator()(const f32x4 (&acc)[2][2][4][2], const Unit& u, int wr, int wc, int fr, int fq) const {
;     ...
;                 for (int bj = 0; bj < 2; ++bj) {
;                     const u32x4 gw = *(const u32x4*)(rowp + O_GA + bj * 128);
;                     f32x4 g0, g1; unpack8(gw, g0, g1);
;                     f32x4 v0, v1;
; #pragma unroll
;                     for (int j = 0; j < 4; ++j) { v0[j] = sigmoidf_(g0[j]) * acc[ai][bj][m][0][j]; v1[j] = sigmoidf_(g1[j]) * acc[ai][bj][m][1][j]; }
;                     const u32x4 mw = *(const u32x4*)(rowp + bj * 128); f32x4 m0, m1; unpack8(mw, m0, m1); v0 += m0; v1 += m1;
;                     __builtin_amdgcn_raw_buffer_store_b128(pack8(v0, v1), rsrc, (unsigned)(((size_t)row * DIN + col0 + bj * 128) * 2), 0, 16  ); }
	v_mov_b64_e32 v[70:71], v[232:233]
	v_mov_b64_e32 v[72:73], v[234:235]
	v_mov_b64_e32 v[74:75], v[236:237]
	v_mov_b64_e32 v[76:77], v[238:239]
	v_add_u32_e32 v203, 0x133300, v202
	global_load_dwordx4 v[232:235], v203, s[38:39]
	v_add_u32_e32 v203, 0x132100, v202
	global_load_dwordx4 v[236:239], v203, s[38:39]
	s_mov_b32 s100, 0xbfb8aa3b
	v_lshlrev_b32_e32 v242, 16, v70
	v_and_b32_e32 v243, 0xffff0000, v70
	v_lshlrev_b32_e32 v244, 16, v72
	v_and_b32_e32 v245, 0xffff0000, v72
	v_lshlrev_b32_e32 v246, 16, v71
	v_and_b32_e32 v247, 0xffff0000, v71
	v_lshlrev_b32_e32 v248, 16, v73
	v_and_b32_e32 v249, 0xffff0000, v73
	v_pk_mul_f32 v[242:243], v[242:243], s[100:101] op_sel_hi:[1,0]
	v_pk_mul_f32 v[244:245], v[244:245], s[100:101] op_sel_hi:[1,0]
	v_pk_mul_f32 v[246:247], v[246:247], s[100:101] op_sel_hi:[1,0]
	v_pk_mul_f32 v[248:249], v[248:249], s[100:101] op_sel_hi:[1,0]
	v_exp_f32_e32 v242, v242
	v_exp_f32_e32 v243, v243
	v_exp_f32_e32 v244, v244
	v_exp_f32_e32 v245, v245
	v_exp_f32_e32 v246, v246
	v_exp_f32_e32 v247, v247
	v_exp_f32_e32 v248, v248
	v_exp_f32_e32 v249, v249
	s_nop 0
	v_pk_add_f32 v[242:243], v[242:243], 1.0 op_sel_hi:[1,0]
	v_pk_add_f32 v[244:245], v[244:245], 1.0 op_sel_hi:[1,0]
	v_pk_add_f32 v[246:247], v[246:247], 1.0 op_sel_hi:[1,0]
	v_pk_add_f32 v[248:249], v[248:249], 1.0 op_sel_hi:[1,0]
	v_rcp_f32_e32 v250, v242
	v_rcp_f32_e32 v251, v243
	s_nop 0
	v_pk_fma_f32 v[252:253], v[242:243], v[250:251], 1.0 op_sel_hi:[1,1,0] neg_lo:[1,0,0] neg_hi:[1,0,0]
	v_pk_fma_f32 v[250:251], v[252:253], v[250:251], v[250:251]
	v_pk_fma_f32 v[252:253], v[242:243], v[250:251], 1.0 op_sel_hi:[1,1,0] neg_lo:[1,0,0] neg_hi:[1,0,0]
	v_pk_fma_f32 v[254:255], v[252:253], v[250:251], v[250:251]
	v_pk_fma_f32 v[252:253], v[242:243], v[254:255], 1.0 op_sel_hi:[1,1,0] neg_lo:[1,0,0] neg_hi:[1,0,0]
	v_pk_fma_f32 v[254:255], v[252:253], v[250:251], v[254:255]
	v_div_fixup_f32 v242, v254, v242, 1.0
	v_div_fixup_f32 v243, v255, v243, 1.0
	v_rcp_f32_e32 v250, v244
	v_rcp_f32_e32 v251, v245
	s_nop 0
	v_pk_fma_f32 v[252:253], v[244:245], v[250:251], 1.0 op_sel_hi:[1,1,0] neg_lo:[1,0,0] neg_hi:[1,0,0]
	v_pk_fma_f32 v[250:251], v[252:253], v[250:251], v[250:251]
	v_pk_fma_f32 v[252:253], v[244:245], v[250:251], 1.0 op_sel_hi:[1,1,0] neg_lo:[1,0,0] neg_hi:[1,0,0]
	v_pk_fma_f32 v[254:255], v[252:253], v[250:251], v[250:251]
	v_pk_fma_f32 v[252:253], v[244:245], v[254:255], 1.0 op_sel_hi:[1,1,0] neg_lo:[1,0,0] neg_hi:[1,0,0]
	v_pk_fma_f32 v[254:255], v[252:253], v[250:251], v[254:255]
	v_div_fixup_f32 v244, v254, v244, 1.0
	v_div_fixup_f32 v245, v255, v245, 1.0
	v_rcp_f32_e32 v250, v246
	v_rcp_f32_e32 v251, v247
	s_nop 0
	v_pk_fma_f32 v[252:253], v[246:247], v[250:251], 1.0 op_sel_hi:[1,1,0] neg_lo:[1,0,0] neg_hi:[1,0,0]
	v_pk_fma_f32 v[250:251], v[252:253], v[250:251], v[250:251]
	v_pk_fma_f32 v[252:253], v[246:247], v[250:251], 1.0 op_sel_hi:[1,1,0] neg_lo:[1,0,0] neg_hi:[1,0,0]
	v_pk_fma_f32 v[254:255], v[252:253], v[250:251], v[250:251]
	v_pk_fma_f32 v[252:253], v[246:247], v[254:255], 1.0 op_sel_hi:[1,1,0] neg_lo:[1,0,0] neg_hi:[1,0,0]
	v_pk_fma_f32 v[254:255], v[252:253], v[250:251], v[254:255]
	v_div_fixup_f32 v246, v254, v246, 1.0
	v_div_fixup_f32 v247, v255, v247, 1.0
	v_rcp_f32_e32 v250, v248
	v_rcp_f32_e32 v251, v249
	s_nop 0
	v_pk_fma_f32 v[252:253], v[248:249], v[250:251], 1.0 op_sel_hi:[1,1,0] neg_lo:[1,0,0] neg_hi:[1,0,0]
	v_pk_fma_f32 v[250:251], v[252:253], v[250:251], v[250:251]
	v_pk_fma_f32 v[252:253], v[248:249], v[250:251], 1.0 op_sel_hi:[1,1,0] neg_lo:[1,0,0] neg_hi:[1,0,0]
	v_pk_fma_f32 v[254:255], v[252:253], v[250:251], v[250:251]
	v_pk_fma_f32 v[252:253], v[248:249], v[254:255], 1.0 op_sel_hi:[1,1,0] neg_lo:[1,0,0] neg_hi:[1,0,0]
	v_pk_fma_f32 v[254:255], v[252:253], v[250:251], v[254:255]
	v_div_fixup_f32 v248, v254, v248, 1.0
	v_div_fixup_f32 v249, v255, v249, 1.0
	v_lshlrev_b32_e32 v82, 16, v74
	v_and_b32_e32 v83, 0xffff0000, v74
	v_lshlrev_b32_e32 v84, 16, v76
	v_and_b32_e32 v85, 0xffff0000, v76
	v_lshlrev_b32_e32 v76, 16, v77
	v_and_b32_e32 v77, 0xffff0000, v77
	v_lshlrev_b32_e32 v74, 16, v75
	v_and_b32_e32 v75, 0xffff0000, v75
	v_pk_fma_f32 v[60:61], v[60:61], v[242:243], v[82:83]
	v_pk_fma_f32 v[70:71], v[58:59], v[248:249], v[76:77]
	v_pk_fma_f32 v[58:59], v[56:57], v[244:245], v[84:85]
	v_add_lshl_u32 v72, v146, v66, 1
	v_pk_fma_f32 v[62:63], v[62:63], v[246:247], v[74:75]
	v_cvt_pk_bf16_f32 v56, v60, v61
	s_nop 0
	v_cvt_pk_bf16_f32 v57, v62, v63
	v_cvt_pk_bf16_f32 v58, v58, v59
	v_cvt_pk_bf16_f32 v59, v70, v71
	buffer_store_dwordx4 v[56:59], v72, s[24:27], 0 offen sc1
	s_nop 0
	s_waitcnt vmcnt(7)
; __device__ __forceinline__ float sigmoidf_(float x) { return 1.0f / (1.0f + __expf(-x)); }
; __device__ __forceinline__ u32x4 pack8(const f32x4 v0, const f32x4 v1) { u32x4 w; w.x = pk2(v0[0], v0[1]); w.y = pk2(v0[2], v0[3]); w.z = pk2(v1[0], v1[1]); w.w = pk2(v1[2], v1[3]); return w; }
; __device__ __forceinline__ void unpack8(const u32x4 w, f32x4& v0, f32x4& v1) { v0 = (f32x4){bflo(w.x), bfhi(w.x), bflo(w.y), bfhi(w.y)}; v1 = (f32x4){bflo(w.z), bfhi(w.z), bflo(w.w), bfhi(w.w)}; }
;     __device__ __forceinline__ void operator()(const f32x4 (&acc)[2][2][4][2], const Unit& u, int wr, int wc, int fr, int fq) const {
;     ...
;                 for (int bj = 0; bj < 2; ++bj) {
;                     const u32x4 gw = *(const u32x4*)(rowp + O_GA + bj * 128);
;                     f32x4 g0, g1; unpack8(gw, g0, g1);
;                     f32x4 v0, v1;
; #pragma unroll
;                     for (int j = 0; j < 4; ++j) { v0[j] = sigmoidf_(g0[j]) * acc[ai][bj][m][0][j]; v1[j] = sigmoidf_(g1[j]) * acc[ai][bj][m][1][j]; }
;                     const u32x4 mw = *(const u32x4*)(rowp + bj * 128); f32x4 m0, m1; unpack8(mw, m0, m1); v0 += m0; v1 += m1;
;                     __builtin_amdgcn_raw_buffer_store_b128(pack8(v0, v1), rsrc, (unsigned)(((size_t)row * DIN + col0 + bj * 128) * 2), 0, 16  ); }
	v_mov_b64_e32 v[56:57], v[204:205]
	v_mov_b64_e32 v[58:59], v[206:207]
	v_mov_b64_e32 v[60:61], v[208:209]
	v_mov_b64_e32 v[62:63], v[210:211]
	v_add_u32_e32 v203, 0x155200, v202
	global_load_dwordx4 v[204:207], v203, s[38:39]
	v_add_u32_e32 v203, 0x154000, v202
	global_load_dwordx4 v[208:211], v203, s[38:39]
	s_mov_b32 s100, 0xbfb8aa3b
	v_lshlrev_b32_e32 v242, 16, v58
	v_and_b32_e32 v243, 0xffff0000, v58
	v_lshlrev_b32_e32 v244, 16, v56
	v_and_b32_e32 v245, 0xffff0000, v56
	v_lshlrev_b32_e32 v246, 16, v57
	v_and_b32_e32 v247, 0xffff0000, v57
	v_lshlrev_b32_e32 v248, 16, v59
	v_and_b32_e32 v249, 0xffff0000, v59
	v_pk_mul_f32 v[242:243], v[242:243], s[100:101] op_sel_hi:[1,0]
	v_pk_mul_f32 v[244:245], v[244:245], s[100:101] op_sel_hi:[1,0]
	v_pk_mul_f32 v[246:247], v[246:247], s[100:101] op_sel_hi:[1,0]
	v_pk_mul_f32 v[248:249], v[248:249], s[100:101] op_sel_hi:[1,0]
	v_exp_f32_e32 v242, v242
	v_exp_f32_e32 v243, v243
	v_exp_f32_e32 v244, v244
	v_exp_f32_e32 v245, v245
	v_exp_f32_e32 v246, v246
	v_exp_f32_e32 v247, v247
	v_exp_f32_e32 v248, v248
	v_exp_f32_e32 v249, v249
	s_nop 0
	v_pk_add_f32 v[242:243], v[242:243], 1.0 op_sel_hi:[1,0]
	v_pk_add_f32 v[244:245], v[244:245], 1.0 op_sel_hi:[1,0]
	v_pk_add_f32 v[246:247], v[246:247], 1.0 op_sel_hi:[1,0]
	v_pk_add_f32 v[248:249], v[248:249], 1.0 op_sel_hi:[1,0]
	v_rcp_f32_e32 v250, v242
	v_rcp_f32_e32 v251, v243
	s_nop 0
	v_pk_fma_f32 v[252:253], v[242:243], v[250:251], 1.0 op_sel_hi:[1,1,0] neg_lo:[1,0,0] neg_hi:[1,0,0]
	v_pk_fma_f32 v[250:251], v[252:253], v[250:251], v[250:251]
	v_pk_fma_f32 v[252:253], v[242:243], v[250:251], 1.0 op_sel_hi:[1,1,0] neg_lo:[1,0,0] neg_hi:[1,0,0]
	v_pk_fma_f32 v[254:255], v[252:253], v[250:251], v[250:251]
	v_pk_fma_f32 v[252:253], v[242:243], v[254:255], 1.0 op_sel_hi:[1,1,0] neg_lo:[1,0,0] neg_hi:[1,0,0]
	v_pk_fma_f32 v[254:255], v[252:253], v[250:251], v[254:255]
	v_div_fixup_f32 v242, v254, v242, 1.0
	v_div_fixup_f32 v243, v255, v243, 1.0
	v_rcp_f32_e32 v250, v244
	v_rcp_f32_e32 v251, v245
	s_nop 0
	v_pk_fma_f32 v[252:253], v[244:245], v[250:251], 1.0 op_sel_hi:[1,1,0] neg_lo:[1,0,0] neg_hi:[1,0,0]
	v_pk_fma_f32 v[250:251], v[252:253], v[250:251], v[250:251]
	v_pk_fma_f32 v[252:253], v[244:245], v[250:251], 1.0 op_sel_hi:[1,1,0] neg_lo:[1,0,0] neg_hi:[1,0,0]
	v_pk_fma_f32 v[254:255], v[252:253], v[250:251], v[250:251]
	v_pk_fma_f32 v[252:253], v[244:245], v[254:255], 1.0 op_sel_hi:[1,1,0] neg_lo:[1,0,0] neg_hi:[1,0,0]
	v_pk_fma_f32 v[254:255], v[252:253], v[250:251], v[254:255]
	v_div_fixup_f32 v244, v254, v244, 1.0
	v_div_fixup_f32 v245, v255, v245, 1.0
	v_rcp_f32_e32 v250, v246
	v_rcp_f32_e32 v251, v247
	s_nop 0
	v_pk_fma_f32 v[252:253], v[246:247], v[250:251], 1.0 op_sel_hi:[1,1,0] neg_lo:[1,0,0] neg_hi:[1,0,0]
	v_pk_fma_f32 v[250:251], v[252:253], v[250:251], v[250:251]
	v_pk_fma_f32 v[252:253], v[246:247], v[250:251], 1.0 op_sel_hi:[1,1,0] neg_lo:[1,0,0] neg_hi:[1,0,0]
	v_pk_fma_f32 v[254:255], v[252:253], v[250:251], v[250:251]
	v_pk_fma_f32 v[252:253], v[246:247], v[254:255], 1.0 op_sel_hi:[1,1,0] neg_lo:[1,0,0] neg_hi:[1,0,0]
	v_pk_fma_f32 v[254:255], v[252:253], v[250:251], v[254:255]
	v_div_fixup_f32 v246, v254, v246, 1.0
	v_div_fixup_f32 v247, v255, v247, 1.0
	v_rcp_f32_e32 v250, v248
	v_rcp_f32_e32 v251, v249
	s_nop 0
	v_pk_fma_f32 v[252:253], v[248:249], v[250:251], 1.0 op_sel_hi:[1,1,0] neg_lo:[1,0,0] neg_hi:[1,0,0]
	v_pk_fma_f32 v[250:251], v[252:253], v[250:251], v[250:251]
	v_pk_fma_f32 v[252:253], v[248:249], v[250:251], 1.0 op_sel_hi:[1,1,0] neg_lo:[1,0,0] neg_hi:[1,0,0]
	v_pk_fma_f32 v[254:255], v[252:253], v[250:251], v[250:251]
	v_pk_fma_f32 v[252:253], v[248:249], v[254:255], 1.0 op_sel_hi:[1,1,0] neg_lo:[1,0,0] neg_hi:[1,0,0]
	v_pk_fma_f32 v[254:255], v[252:253], v[250:251], v[254:255]
	v_div_fixup_f32 v248, v254, v248, 1.0
	v_div_fixup_f32 v249, v255, v249, 1.0
	v_lshlrev_b32_e32 v68, 16, v60
	v_and_b32_e32 v69, 0xffff0000, v60
	v_lshlrev_b32_e32 v70, 16, v62
	v_and_b32_e32 v71, 0xffff0000, v62
	v_lshlrev_b32_e32 v62, 16, v63
	v_and_b32_e32 v63, 0xffff0000, v63
	v_lshlrev_b32_e32 v60, 16, v61
	v_and_b32_e32 v61, 0xffff0000, v61
	v_pk_fma_f32 v[52:53], v[52:53], v[244:245], v[68:69]
	v_pk_fma_f32 v[56:57], v[50:51], v[248:249], v[62:63]
	v_pk_fma_f32 v[50:51], v[48:49], v[242:243], v[70:71]
	v_cvt_pk_bf16_f32 v48, v52, v53
	v_pk_fma_f32 v[54:55], v[54:55], v[246:247], v[60:61]
	s_nop 0
	v_cvt_pk_bf16_f32 v49, v54, v55
	v_cvt_pk_bf16_f32 v50, v50, v51
	v_cvt_pk_bf16_f32 v51, v56, v57
	buffer_store_dwordx4 v[48:51], v72, s[24:27], 0 offen offset:256 sc1
	s_nop 1
	v_add_u32_e32 v48, 0x90, v162
	v_mad_i64_i32 v[50:51], s[6:7], v48, s77, 0
	v_lshl_add_u64 v[48:49], v[50:51], 1, s[38:39]
	v_lshl_add_u64 v[48:49], v[48:49], 0, v[148:149]
	v_add_co_u32_e32 v52, vcc, s78, v48
	s_nop 1
	v_addc_co_u32_e32 v53, vcc, 0, v49, vcc
	s_waitcnt vmcnt(7)
; __device__ __forceinline__ float sigmoidf_(float x) { return 1.0f / (1.0f + __expf(-x)); }
; __device__ __forceinline__ u32x4 pack8(const f32x4 v0, const f32x4 v1) { u32x4 w; w.x = pk2(v0[0], v0[1]); w.y = pk2(v0[2], v0[3]); w.z = pk2(v1[0], v1[1]); w.w = pk2(v1[2], v1[3]); return w; }
; __device__ __forceinline__ void unpack8(const u32x4 w, f32x4& v0, f32x4& v1) { v0 = (f32x4){bflo(w.x), bfhi(w.x), bflo(w.y), bfhi(w.y)}; v1 = (f32x4){bflo(w.z), bfhi(w.z), bflo(w.w), bfhi(w.w)}; }
;     __device__ __forceinline__ void operator()(const f32x4 (&acc)[2][2][4][2], const Unit& u, int wr, int wc, int fr, int fq) const {
;     ...
;                 for (int bj = 0; bj < 2; ++bj) {
;                     const u32x4 gw = *(const u32x4*)(rowp + O_GA + bj * 128);
;                     f32x4 g0, g1; unpack8(gw, g0, g1);
;                     f32x4 v0, v1;
; #pragma unroll
;                     for (int j = 0; j < 4; ++j) { v0[j] = sigmoidf_(g0[j]) * acc[ai][bj][m][0][j]; v1[j] = sigmoidf_(g1[j]) * acc[ai][bj][m][1][j]; }
;                     const u32x4 mw = *(const u32x4*)(rowp + bj * 128); f32x4 m0, m1; unpack8(mw, m0, m1); v0 += m0; v1 += m1;
;                     __builtin_amdgcn_raw_buffer_store_b128(pack8(v0, v1), rsrc, (unsigned)(((size_t)row * DIN + col0 + bj * 128) * 2), 0, 16  ); }
	v_mov_b64_e32 v[54:55], v[212:213]
	v_mov_b64_e32 v[56:57], v[214:215]
	v_mov_b64_e32 v[58:59], v[216:217]
	v_mov_b64_e32 v[60:61], v[218:219]
	v_add_u32_e32 v203, 0x155300, v202
	global_load_dwordx4 v[212:215], v203, s[38:39]
	v_add_u32_e32 v203, 0x154100, v202
	global_load_dwordx4 v[216:219], v203, s[38:39]
	s_mov_b32 s100, 0xbfb8aa3b
	v_lshlrev_b32_e32 v242, 16, v54
	v_and_b32_e32 v243, 0xffff0000, v54
	v_lshlrev_b32_e32 v244, 16, v56
	v_and_b32_e32 v245, 0xffff0000, v56
	v_lshlrev_b32_e32 v246, 16, v55
	v_and_b32_e32 v247, 0xffff0000, v55
	v_lshlrev_b32_e32 v248, 16, v57
	v_and_b32_e32 v249, 0xffff0000, v57
	v_pk_mul_f32 v[242:243], v[242:243], s[100:101] op_sel_hi:[1,0]
	v_pk_mul_f32 v[244:245], v[244:245], s[100:101] op_sel_hi:[1,0]
	v_pk_mul_f32 v[246:247], v[246:247], s[100:101] op_sel_hi:[1,0]
	v_pk_mul_f32 v[248:249], v[248:249], s[100:101] op_sel_hi:[1,0]
	v_exp_f32_e32 v242, v242
	v_exp_f32_e32 v243, v243
	v_exp_f32_e32 v244, v244
	v_exp_f32_e32 v245, v245
	v_exp_f32_e32 v246, v246
	v_exp_f32_e32 v247, v247
	v_exp_f32_e32 v248, v248
	v_exp_f32_e32 v249, v249
	s_nop 0
	v_pk_add_f32 v[242:243], v[242:243], 1.0 op_sel_hi:[1,0]
	v_pk_add_f32 v[244:245], v[244:245], 1.0 op_sel_hi:[1,0]
	v_pk_add_f32 v[246:247], v[246:247], 1.0 op_sel_hi:[1,0]
	v_pk_add_f32 v[248:249], v[248:249], 1.0 op_sel_hi:[1,0]
	v_rcp_f32_e32 v250, v242
	v_rcp_f32_e32 v251, v243
	s_nop 0
	v_pk_fma_f32 v[252:253], v[242:243], v[250:251], 1.0 op_sel_hi:[1,1,0] neg_lo:[1,0,0] neg_hi:[1,0,0]
	v_pk_fma_f32 v[250:251], v[252:253], v[250:251], v[250:251]
	v_pk_fma_f32 v[252:253], v[242:243], v[250:251], 1.0 op_sel_hi:[1,1,0] neg_lo:[1,0,0] neg_hi:[1,0,0]
	v_pk_fma_f32 v[254:255], v[252:253], v[250:251], v[250:251]
	v_pk_fma_f32 v[252:253], v[242:243], v[254:255], 1.0 op_sel_hi:[1,1,0] neg_lo:[1,0,0] neg_hi:[1,0,0]
	v_pk_fma_f32 v[254:255], v[252:253], v[250:251], v[254:255]
	v_div_fixup_f32 v242, v254, v242, 1.0
	v_div_fixup_f32 v243, v255, v243, 1.0
	v_rcp_f32_e32 v250, v244
	v_rcp_f32_e32 v251, v245
	s_nop 0
	v_pk_fma_f32 v[252:253], v[244:245], v[250:251], 1.0 op_sel_hi:[1,1,0] neg_lo:[1,0,0] neg_hi:[1,0,0]
	v_pk_fma_f32 v[250:251], v[252:253], v[250:251], v[250:251]
	v_pk_fma_f32 v[252:253], v[244:245], v[250:251], 1.0 op_sel_hi:[1,1,0] neg_lo:[1,0,0] neg_hi:[1,0,0]
	v_pk_fma_f32 v[254:255], v[252:253], v[250:251], v[250:251]
	v_pk_fma_f32 v[252:253], v[244:245], v[254:255], 1.0 op_sel_hi:[1,1,0] neg_lo:[1,0,0] neg_hi:[1,0,0]
	v_pk_fma_f32 v[254:255], v[252:253], v[250:251], v[254:255]
	v_div_fixup_f32 v244, v254, v244, 1.0
	v_div_fixup_f32 v245, v255, v245, 1.0
	v_rcp_f32_e32 v250, v246
	v_rcp_f32_e32 v251, v247
	s_nop 0
	v_pk_fma_f32 v[252:253], v[246:247], v[250:251], 1.0 op_sel_hi:[1,1,0] neg_lo:[1,0,0] neg_hi:[1,0,0]
	v_pk_fma_f32 v[250:251], v[252:253], v[250:251], v[250:251]
	v_pk_fma_f32 v[252:253], v[246:247], v[250:251], 1.0 op_sel_hi:[1,1,0] neg_lo:[1,0,0] neg_hi:[1,0,0]
	v_pk_fma_f32 v[254:255], v[252:253], v[250:251], v[250:251]
	v_pk_fma_f32 v[252:253], v[246:247], v[254:255], 1.0 op_sel_hi:[1,1,0] neg_lo:[1,0,0] neg_hi:[1,0,0]
	v_pk_fma_f32 v[254:255], v[252:253], v[250:251], v[254:255]
	v_div_fixup_f32 v246, v254, v246, 1.0
	v_div_fixup_f32 v247, v255, v247, 1.0
	v_rcp_f32_e32 v250, v248
	v_rcp_f32_e32 v251, v249
	s_nop 0
	v_pk_fma_f32 v[252:253], v[248:249], v[250:251], 1.0 op_sel_hi:[1,1,0] neg_lo:[1,0,0] neg_hi:[1,0,0]
	v_pk_fma_f32 v[250:251], v[252:253], v[250:251], v[250:251]
	v_pk_fma_f32 v[252:253], v[248:249], v[250:251], 1.0 op_sel_hi:[1,1,0] neg_lo:[1,0,0] neg_hi:[1,0,0]
	v_pk_fma_f32 v[254:255], v[252:253], v[250:251], v[250:251]
	v_pk_fma_f32 v[252:253], v[248:249], v[254:255], 1.0 op_sel_hi:[1,1,0] neg_lo:[1,0,0] neg_hi:[1,0,0]
	v_pk_fma_f32 v[254:255], v[252:253], v[250:251], v[254:255]
	v_div_fixup_f32 v248, v254, v248, 1.0
	v_div_fixup_f32 v249, v255, v249, 1.0
	v_lshlrev_b32_e32 v66, 16, v58
	v_and_b32_e32 v67, 0xffff0000, v58
	v_lshlrev_b32_e32 v68, 16, v60
	v_and_b32_e32 v69, 0xffff0000, v60
	v_lshlrev_b32_e32 v60, 16, v61
	v_and_b32_e32 v61, 0xffff0000, v61
	v_lshlrev_b32_e32 v58, 16, v59
	v_and_b32_e32 v59, 0xffff0000, v59
	v_pk_fma_f32 v[44:45], v[44:45], v[242:243], v[66:67]
	v_pk_fma_f32 v[54:55], v[42:43], v[248:249], v[60:61]
	v_pk_fma_f32 v[42:43], v[40:41], v[244:245], v[68:69]
	v_add_lshl_u32 v56, v146, v50, 1
	v_pk_fma_f32 v[46:47], v[46:47], v[246:247], v[58:59]
	v_cvt_pk_bf16_f32 v40, v44, v45
	s_nop 0
	v_cvt_pk_bf16_f32 v41, v46, v47
	v_cvt_pk_bf16_f32 v42, v42, v43
	v_cvt_pk_bf16_f32 v43, v54, v55
	buffer_store_dwordx4 v[40:43], v56, s[24:27], 0 offen sc1
	s_nop 0
	s_waitcnt vmcnt(7)
; __device__ __forceinline__ float sigmoidf_(float x) { return 1.0f / (1.0f + __expf(-x)); }
; __device__ __forceinline__ u32x4 pack8(const f32x4 v0, const f32x4 v1) { u32x4 w; w.x = pk2(v0[0], v0[1]); w.y = pk2(v0[2], v0[3]); w.z = pk2(v1[0], v1[1]); w.w = pk2(v1[2], v1[3]); return w; }
; __device__ __forceinline__ void unpack8(const u32x4 w, f32x4& v0, f32x4& v1) { v0 = (f32x4){bflo(w.x), bfhi(w.x), bflo(w.y), bfhi(w.y)}; v1 = (f32x4){bflo(w.z), bfhi(w.z), bflo(w.w), bfhi(w.w)}; }
;     __device__ __forceinline__ void operator()(const f32x4 (&acc)[2][2][4][2], const Unit& u, int wr, int wc, int fr, int fq) const {
;     ...
;                 for (int bj = 0; bj < 2; ++bj) {
;                     const u32x4 gw = *(const u32x4*)(rowp + O_GA + bj * 128);
;                     f32x4 g0, g1; unpack8(gw, g0, g1);
;                     f32x4 v0, v1;
; #pragma unroll
;                     for (int j = 0; j < 4; ++j) { v0[j] = sigmoidf_(g0[j]) * acc[ai][bj][m][0][j]; v1[j] = sigmoidf_(g1[j]) * acc[ai][bj][m][1][j]; }
;                     const u32x4 mw = *(const u32x4*)(rowp + bj * 128); f32x4 m0, m1; unpack8(mw, m0, m1); v0 += m0; v1 += m1;
;                     __builtin_amdgcn_raw_buffer_store_b128(pack8(v0, v1), rsrc, (unsigned)(((size_t)row * DIN + col0 + bj * 128) * 2), 0, 16  ); }
	v_mov_b64_e32 v[40:41], v[232:233]
	v_mov_b64_e32 v[42:43], v[234:235]
	v_mov_b64_e32 v[44:45], v[236:237]
	v_mov_b64_e32 v[46:47], v[238:239]
	v_add_u32_e32 v203, 0x177200, v202
	global_load_dwordx4 v[232:235], v203, s[38:39]
	v_add_u32_e32 v203, 0x176000, v202
	global_load_dwordx4 v[236:239], v203, s[38:39]
	s_mov_b32 s100, 0xbfb8aa3b
	v_lshlrev_b32_e32 v242, 16, v42
	v_and_b32_e32 v243, 0xffff0000, v42
	v_lshlrev_b32_e32 v244, 16, v40
	v_and_b32_e32 v245, 0xffff0000, v40
	v_lshlrev_b32_e32 v246, 16, v41
	v_and_b32_e32 v247, 0xffff0000, v41
	v_lshlrev_b32_e32 v248, 16, v43
	v_and_b32_e32 v249, 0xffff0000, v43
	v_pk_mul_f32 v[242:243], v[242:243], s[100:101] op_sel_hi:[1,0]
	v_pk_mul_f32 v[244:245], v[244:245], s[100:101] op_sel_hi:[1,0]
	v_pk_mul_f32 v[246:247], v[246:247], s[100:101] op_sel_hi:[1,0]
	v_pk_mul_f32 v[248:249], v[248:249], s[100:101] op_sel_hi:[1,0]
	v_exp_f32_e32 v242, v242
	v_exp_f32_e32 v243, v243
	v_exp_f32_e32 v244, v244
	v_exp_f32_e32 v245, v245
	v_exp_f32_e32 v246, v246
	v_exp_f32_e32 v247, v247
	v_exp_f32_e32 v248, v248
	v_exp_f32_e32 v249, v249
	s_nop 0
	v_pk_add_f32 v[242:243], v[242:243], 1.0 op_sel_hi:[1,0]
	v_pk_add_f32 v[244:245], v[244:245], 1.0 op_sel_hi:[1,0]
	v_pk_add_f32 v[246:247], v[246:247], 1.0 op_sel_hi:[1,0]
	v_pk_add_f32 v[248:249], v[248:249], 1.0 op_sel_hi:[1,0]
	v_rcp_f32_e32 v250, v242
	v_rcp_f32_e32 v251, v243
	s_nop 0
	v_pk_fma_f32 v[252:253], v[242:243], v[250:251], 1.0 op_sel_hi:[1,1,0] neg_lo:[1,0,0] neg_hi:[1,0,0]
	v_pk_fma_f32 v[250:251], v[252:253], v[250:251], v[250:251]
	v_pk_fma_f32 v[252:253], v[242:243], v[250:251], 1.0 op_sel_hi:[1,1,0] neg_lo:[1,0,0] neg_hi:[1,0,0]
	v_pk_fma_f32 v[254:255], v[252:253], v[250:251], v[250:251]
	v_pk_fma_f32 v[252:253], v[242:243], v[254:255], 1.0 op_sel_hi:[1,1,0] neg_lo:[1,0,0] neg_hi:[1,0,0]
	v_pk_fma_f32 v[254:255], v[252:253], v[250:251], v[254:255]
	v_div_fixup_f32 v242, v254, v242, 1.0
	v_div_fixup_f32 v243, v255, v243, 1.0
	v_rcp_f32_e32 v250, v244
	v_rcp_f32_e32 v251, v245
	s_nop 0
	v_pk_fma_f32 v[252:253], v[244:245], v[250:251], 1.0 op_sel_hi:[1,1,0] neg_lo:[1,0,0] neg_hi:[1,0,0]
	v_pk_fma_f32 v[250:251], v[252:253], v[250:251], v[250:251]
	v_pk_fma_f32 v[252:253], v[244:245], v[250:251], 1.0 op_sel_hi:[1,1,0] neg_lo:[1,0,0] neg_hi:[1,0,0]
	v_pk_fma_f32 v[254:255], v[252:253], v[250:251], v[250:251]
	v_pk_fma_f32 v[252:253], v[244:245], v[254:255], 1.0 op_sel_hi:[1,1,0] neg_lo:[1,0,0] neg_hi:[1,0,0]
	v_pk_fma_f32 v[254:255], v[252:253], v[250:251], v[254:255]
	v_div_fixup_f32 v244, v254, v244, 1.0
	v_div_fixup_f32 v245, v255, v245, 1.0
	v_rcp_f32_e32 v250, v246
	v_rcp_f32_e32 v251, v247
	s_nop 0
	v_pk_fma_f32 v[252:253], v[246:247], v[250:251], 1.0 op_sel_hi:[1,1,0] neg_lo:[1,0,0] neg_hi:[1,0,0]
	v_pk_fma_f32 v[250:251], v[252:253], v[250:251], v[250:251]
	v_pk_fma_f32 v[252:253], v[246:247], v[250:251], 1.0 op_sel_hi:[1,1,0] neg_lo:[1,0,0] neg_hi:[1,0,0]
	v_pk_fma_f32 v[254:255], v[252:253], v[250:251], v[250:251]
	v_pk_fma_f32 v[252:253], v[246:247], v[254:255], 1.0 op_sel_hi:[1,1,0] neg_lo:[1,0,0] neg_hi:[1,0,0]
	v_pk_fma_f32 v[254:255], v[252:253], v[250:251], v[254:255]
	v_div_fixup_f32 v246, v254, v246, 1.0
	v_div_fixup_f32 v247, v255, v247, 1.0
	v_rcp_f32_e32 v250, v248
	v_rcp_f32_e32 v251, v249
	s_nop 0
	v_pk_fma_f32 v[252:253], v[248:249], v[250:251], 1.0 op_sel_hi:[1,1,0] neg_lo:[1,0,0] neg_hi:[1,0,0]
	v_pk_fma_f32 v[250:251], v[252:253], v[250:251], v[250:251]
	v_pk_fma_f32 v[252:253], v[248:249], v[250:251], 1.0 op_sel_hi:[1,1,0] neg_lo:[1,0,0] neg_hi:[1,0,0]
	v_pk_fma_f32 v[254:255], v[252:253], v[250:251], v[250:251]
	v_pk_fma_f32 v[252:253], v[248:249], v[254:255], 1.0 op_sel_hi:[1,1,0] neg_lo:[1,0,0] neg_hi:[1,0,0]
	v_pk_fma_f32 v[254:255], v[252:253], v[250:251], v[254:255]
	v_div_fixup_f32 v248, v254, v248, 1.0
	v_div_fixup_f32 v249, v255, v249, 1.0
	v_lshlrev_b32_e32 v52, 16, v44
	v_and_b32_e32 v53, 0xffff0000, v44
	v_lshlrev_b32_e32 v54, 16, v46
	v_and_b32_e32 v55, 0xffff0000, v46
	v_lshlrev_b32_e32 v46, 16, v47
	v_and_b32_e32 v47, 0xffff0000, v47
	v_lshlrev_b32_e32 v44, 16, v45
	v_and_b32_e32 v45, 0xffff0000, v45
	v_pk_fma_f32 v[36:37], v[36:37], v[244:245], v[52:53]
	v_pk_fma_f32 v[40:41], v[34:35], v[248:249], v[46:47]
	v_pk_fma_f32 v[34:35], v[32:33], v[242:243], v[54:55]
	v_cvt_pk_bf16_f32 v32, v36, v37
	v_pk_fma_f32 v[38:39], v[38:39], v[246:247], v[44:45]
	s_nop 0
	v_cvt_pk_bf16_f32 v33, v38, v39
	v_cvt_pk_bf16_f32 v34, v34, v35
	v_cvt_pk_bf16_f32 v35, v40, v41
	buffer_store_dwordx4 v[32:35], v56, s[24:27], 0 offen offset:256 sc1
	s_nop 1
	v_add_u32_e32 v32, 0xa0, v162
	v_mad_i64_i32 v[34:35], s[6:7], v32, s77, 0
	v_lshl_add_u64 v[32:33], v[34:35], 1, s[38:39]
	v_lshl_add_u64 v[32:33], v[32:33], 0, v[148:149]
	v_add_co_u32_e32 v36, vcc, s78, v32
	s_nop 1
	v_addc_co_u32_e32 v37, vcc, 0, v33, vcc
	s_waitcnt vmcnt(7)
; __device__ __forceinline__ float sigmoidf_(float x) { return 1.0f / (1.0f + __expf(-x)); }
; __device__ __forceinline__ u32x4 pack8(const f32x4 v0, const f32x4 v1) { u32x4 w; w.x = pk2(v0[0], v0[1]); w.y = pk2(v0[2], v0[3]); w.z = pk2(v1[0], v1[1]); w.w = pk2(v1[2], v1[3]); return w; }
; __device__ __forceinline__ void unpack8(const u32x4 w, f32x4& v0, f32x4& v1) { v0 = (f32x4){bflo(w.x), bfhi(w.x), bflo(w.y), bfhi(w.y)}; v1 = (f32x4){bflo(w.z), bfhi(w.z), bflo(w.w), bfhi(w.w)}; }
;     __device__ __forceinline__ void operator()(const f32x4 (&acc)[2][2][4][2], const Unit& u, int wr, int wc, int fr, int fq) const {
;     ...
;                 for (int bj = 0; bj < 2; ++bj) {
;                     const u32x4 gw = *(const u32x4*)(rowp + O_GA + bj * 128);
;                     f32x4 g0, g1; unpack8(gw, g0, g1);
;                     f32x4 v0, v1;
; #pragma unroll
;                     for (int j = 0; j < 4; ++j) { v0[j] = sigmoidf_(g0[j]) * acc[ai][bj][m][0][j]; v1[j] = sigmoidf_(g1[j]) * acc[ai][bj][m][1][j]; }
;                     const u32x4 mw = *(const u32x4*)(rowp + bj * 128); f32x4 m0, m1; unpack8(mw, m0, m1); v0 += m0; v1 += m1;
;                     __builtin_amdgcn_raw_buffer_store_b128(pack8(v0, v1), rsrc, (unsigned)(((size_t)row * DIN + col0 + bj * 128) * 2), 0, 16  ); }
	v_mov_b64_e32 v[38:39], v[204:205]
	v_mov_b64_e32 v[40:41], v[206:207]
	v_mov_b64_e32 v[42:43], v[208:209]
	v_mov_b64_e32 v[44:45], v[210:211]
	v_add_u32_e32 v203, 0x177300, v202
	global_load_dwordx4 v[204:207], v203, s[38:39]
	v_add_u32_e32 v203, 0x176100, v202
	global_load_dwordx4 v[208:211], v203, s[38:39]
	s_mov_b32 s100, 0xbfb8aa3b
	v_lshlrev_b32_e32 v242, 16, v38
	v_and_b32_e32 v243, 0xffff0000, v38
	v_lshlrev_b32_e32 v244, 16, v40
	v_and_b32_e32 v245, 0xffff0000, v40
	v_lshlrev_b32_e32 v246, 16, v39
	v_and_b32_e32 v247, 0xffff0000, v39
	v_lshlrev_b32_e32 v248, 16, v41
	v_and_b32_e32 v249, 0xffff0000, v41
	v_pk_mul_f32 v[242:243], v[242:243], s[100:101] op_sel_hi:[1,0]
	v_pk_mul_f32 v[244:245], v[244:245], s[100:101] op_sel_hi:[1,0]
	v_pk_mul_f32 v[246:247], v[246:247], s[100:101] op_sel_hi:[1,0]
	v_pk_mul_f32 v[248:249], v[248:249], s[100:101] op_sel_hi:[1,0]
	v_exp_f32_e32 v242, v242
	v_exp_f32_e32 v243, v243
	v_exp_f32_e32 v244, v244
	v_exp_f32_e32 v245, v245
	v_exp_f32_e32 v246, v246
	v_exp_f32_e32 v247, v247
	v_exp_f32_e32 v248, v248
	v_exp_f32_e32 v249, v249
	s_nop 0
	v_pk_add_f32 v[242:243], v[242:243], 1.0 op_sel_hi:[1,0]
	v_pk_add_f32 v[244:245], v[244:245], 1.0 op_sel_hi:[1,0]
	v_pk_add_f32 v[246:247], v[246:247], 1.0 op_sel_hi:[1,0]
	v_pk_add_f32 v[248:249], v[248:249], 1.0 op_sel_hi:[1,0]
	v_rcp_f32_e32 v250, v242
	v_rcp_f32_e32 v251, v243
	s_nop 0
	v_pk_fma_f32 v[252:253], v[242:243], v[250:251], 1.0 op_sel_hi:[1,1,0] neg_lo:[1,0,0] neg_hi:[1,0,0]
	v_pk_fma_f32 v[250:251], v[252:253], v[250:251], v[250:251]
	v_pk_fma_f32 v[252:253], v[242:243], v[250:251], 1.0 op_sel_hi:[1,1,0] neg_lo:[1,0,0] neg_hi:[1,0,0]
	v_pk_fma_f32 v[254:255], v[252:253], v[250:251], v[250:251]
	v_pk_fma_f32 v[252:253], v[242:243], v[254:255], 1.0 op_sel_hi:[1,1,0] neg_lo:[1,0,0] neg_hi:[1,0,0]
	v_pk_fma_f32 v[254:255], v[252:253], v[250:251], v[254:255]
	v_div_fixup_f32 v242, v254, v242, 1.0
	v_div_fixup_f32 v243, v255, v243, 1.0
	v_rcp_f32_e32 v250, v244
	v_rcp_f32_e32 v251, v245
	s_nop 0
	v_pk_fma_f32 v[252:253], v[244:245], v[250:251], 1.0 op_sel_hi:[1,1,0] neg_lo:[1,0,0] neg_hi:[1,0,0]
	v_pk_fma_f32 v[250:251], v[252:253], v[250:251], v[250:251]
	v_pk_fma_f32 v[252:253], v[244:245], v[250:251], 1.0 op_sel_hi:[1,1,0] neg_lo:[1,0,0] neg_hi:[1,0,0]
	v_pk_fma_f32 v[254:255], v[252:253], v[250:251], v[250:251]
	v_pk_fma_f32 v[252:253], v[244:245], v[254:255], 1.0 op_sel_hi:[1,1,0] neg_lo:[1,0,0] neg_hi:[1,0,0]
	v_pk_fma_f32 v[254:255], v[252:253], v[250:251], v[254:255]
	v_div_fixup_f32 v244, v254, v244, 1.0
	v_div_fixup_f32 v245, v255, v245, 1.0
	v_rcp_f32_e32 v250, v246
	v_rcp_f32_e32 v251, v247
	s_nop 0
	v_pk_fma_f32 v[252:253], v[246:247], v[250:251], 1.0 op_sel_hi:[1,1,0] neg_lo:[1,0,0] neg_hi:[1,0,0]
	v_pk_fma_f32 v[250:251], v[252:253], v[250:251], v[250:251]
	v_pk_fma_f32 v[252:253], v[246:247], v[250:251], 1.0 op_sel_hi:[1,1,0] neg_lo:[1,0,0] neg_hi:[1,0,0]
	v_pk_fma_f32 v[254:255], v[252:253], v[250:251], v[250:251]
	v_pk_fma_f32 v[252:253], v[246:247], v[254:255], 1.0 op_sel_hi:[1,1,0] neg_lo:[1,0,0] neg_hi:[1,0,0]
	v_pk_fma_f32 v[254:255], v[252:253], v[250:251], v[254:255]
	v_div_fixup_f32 v246, v254, v246, 1.0
	v_div_fixup_f32 v247, v255, v247, 1.0
	v_rcp_f32_e32 v250, v248
	v_rcp_f32_e32 v251, v249
	s_nop 0
	v_pk_fma_f32 v[252:253], v[248:249], v[250:251], 1.0 op_sel_hi:[1,1,0] neg_lo:[1,0,0] neg_hi:[1,0,0]
	v_pk_fma_f32 v[250:251], v[252:253], v[250:251], v[250:251]
	v_pk_fma_f32 v[252:253], v[248:249], v[250:251], 1.0 op_sel_hi:[1,1,0] neg_lo:[1,0,0] neg_hi:[1,0,0]
	v_pk_fma_f32 v[254:255], v[252:253], v[250:251], v[250:251]
	v_pk_fma_f32 v[252:253], v[248:249], v[254:255], 1.0 op_sel_hi:[1,1,0] neg_lo:[1,0,0] neg_hi:[1,0,0]
	v_pk_fma_f32 v[254:255], v[252:253], v[250:251], v[254:255]
	v_div_fixup_f32 v248, v254, v248, 1.0
	v_div_fixup_f32 v249, v255, v249, 1.0
	v_lshlrev_b32_e32 v50, 16, v42
	v_and_b32_e32 v51, 0xffff0000, v42
	v_lshlrev_b32_e32 v52, 16, v44
	v_and_b32_e32 v53, 0xffff0000, v44
	v_lshlrev_b32_e32 v44, 16, v45
	v_and_b32_e32 v45, 0xffff0000, v45
	v_lshlrev_b32_e32 v42, 16, v43
	v_and_b32_e32 v43, 0xffff0000, v43
	v_pk_fma_f32 v[28:29], v[28:29], v[242:243], v[50:51]
	v_pk_fma_f32 v[38:39], v[26:27], v[248:249], v[44:45]
	v_pk_fma_f32 v[26:27], v[24:25], v[244:245], v[52:53]
	v_add_lshl_u32 v40, v146, v34, 1
	v_pk_fma_f32 v[30:31], v[30:31], v[246:247], v[42:43]
	v_cvt_pk_bf16_f32 v24, v28, v29
	s_nop 0
	v_cvt_pk_bf16_f32 v25, v30, v31
	v_cvt_pk_bf16_f32 v26, v26, v27
	v_cvt_pk_bf16_f32 v27, v38, v39
	buffer_store_dwordx4 v[24:27], v40, s[24:27], 0 offen sc1
	s_nop 0
	s_waitcnt vmcnt(7)
; __device__ __forceinline__ float sigmoidf_(float x) { return 1.0f / (1.0f + __expf(-x)); }
; __device__ __forceinline__ u32x4 pack8(const f32x4 v0, const f32x4 v1) { u32x4 w; w.x = pk2(v0[0], v0[1]); w.y = pk2(v0[2], v0[3]); w.z = pk2(v1[0], v1[1]); w.w = pk2(v1[2], v1[3]); return w; }
; __device__ __forceinline__ void unpack8(const u32x4 w, f32x4& v0, f32x4& v1) { v0 = (f32x4){bflo(w.x), bfhi(w.x), bflo(w.y), bfhi(w.y)}; v1 = (f32x4){bflo(w.z), bfhi(w.z), bflo(w.w), bfhi(w.w)}; }
;     __device__ __forceinline__ void operator()(const f32x4 (&acc)[2][2][4][2], const Unit& u, int wr, int wc, int fr, int fq) const {
;     ...
;                 for (int bj = 0; bj < 2; ++bj) {
;                     const u32x4 gw = *(const u32x4*)(rowp + O_GA + bj * 128);
;                     f32x4 g0, g1; unpack8(gw, g0, g1);
;                     f32x4 v0, v1;
; #pragma unroll
;                     for (int j = 0; j < 4; ++j) { v0[j] = sigmoidf_(g0[j]) * acc[ai][bj][m][0][j]; v1[j] = sigmoidf_(g1[j]) * acc[ai][bj][m][1][j]; }
;                     const u32x4 mw = *(const u32x4*)(rowp + bj * 128); f32x4 m0, m1; unpack8(mw, m0, m1); v0 += m0; v1 += m1;
;                     __builtin_amdgcn_raw_buffer_store_b128(pack8(v0, v1), rsrc, (unsigned)(((size_t)row * DIN + col0 + bj * 128) * 2), 0, 16  ); }
	v_mov_b64_e32 v[24:25], v[212:213]
	v_mov_b64_e32 v[26:27], v[214:215]
	v_mov_b64_e32 v[28:29], v[216:217]
	v_mov_b64_e32 v[30:31], v[218:219]
	s_mov_b32 s100, 0xbfb8aa3b
	v_lshlrev_b32_e32 v242, 16, v26
	v_and_b32_e32 v243, 0xffff0000, v26
	v_lshlrev_b32_e32 v244, 16, v24
	v_and_b32_e32 v245, 0xffff0000, v24
	v_lshlrev_b32_e32 v246, 16, v25
	v_and_b32_e32 v247, 0xffff0000, v25
	v_lshlrev_b32_e32 v248, 16, v27
	v_and_b32_e32 v249, 0xffff0000, v27
	v_pk_mul_f32 v[242:243], v[242:243], s[100:101] op_sel_hi:[1,0]
	v_pk_mul_f32 v[244:245], v[244:245], s[100:101] op_sel_hi:[1,0]
	v_pk_mul_f32 v[246:247], v[246:247], s[100:101] op_sel_hi:[1,0]
	v_pk_mul_f32 v[248:249], v[248:249], s[100:101] op_sel_hi:[1,0]
	v_exp_f32_e32 v242, v242
	v_exp_f32_e32 v243, v243
	v_exp_f32_e32 v244, v244
	v_exp_f32_e32 v245, v245
	v_exp_f32_e32 v246, v246
	v_exp_f32_e32 v247, v247
	v_exp_f32_e32 v248, v248
	v_exp_f32_e32 v249, v249
	s_nop 0
	v_pk_add_f32 v[242:243], v[242:243], 1.0 op_sel_hi:[1,0]
	v_pk_add_f32 v[244:245], v[244:245], 1.0 op_sel_hi:[1,0]
	v_pk_add_f32 v[246:247], v[246:247], 1.0 op_sel_hi:[1,0]
	v_pk_add_f32 v[248:249], v[248:249], 1.0 op_sel_hi:[1,0]
	v_rcp_f32_e32 v250, v242
	v_rcp_f32_e32 v251, v243
	s_nop 0
	v_pk_fma_f32 v[252:253], v[242:243], v[250:251], 1.0 op_sel_hi:[1,1,0] neg_lo:[1,0,0] neg_hi:[1,0,0]
	v_pk_fma_f32 v[250:251], v[252:253], v[250:251], v[250:251]
	v_pk_fma_f32 v[252:253], v[242:243], v[250:251], 1.0 op_sel_hi:[1,1,0] neg_lo:[1,0,0] neg_hi:[1,0,0]
	v_pk_fma_f32 v[254:255], v[252:253], v[250:251], v[250:251]
	v_pk_fma_f32 v[252:253], v[242:243], v[254:255], 1.0 op_sel_hi:[1,1,0] neg_lo:[1,0,0] neg_hi:[1,0,0]
	v_pk_fma_f32 v[254:255], v[252:253], v[250:251], v[254:255]
	v_div_fixup_f32 v242, v254, v242, 1.0
	v_div_fixup_f32 v243, v255, v243, 1.0
	v_rcp_f32_e32 v250, v244
	v_rcp_f32_e32 v251, v245
	s_nop 0
	v_pk_fma_f32 v[252:253], v[244:245], v[250:251], 1.0 op_sel_hi:[1,1,0] neg_lo:[1,0,0] neg_hi:[1,0,0]
	v_pk_fma_f32 v[250:251], v[252:253], v[250:251], v[250:251]
	v_pk_fma_f32 v[252:253], v[244:245], v[250:251], 1.0 op_sel_hi:[1,1,0] neg_lo:[1,0,0] neg_hi:[1,0,0]
	v_pk_fma_f32 v[254:255], v[252:253], v[250:251], v[250:251]
	v_pk_fma_f32 v[252:253], v[244:245], v[254:255], 1.0 op_sel_hi:[1,1,0] neg_lo:[1,0,0] neg_hi:[1,0,0]
	v_pk_fma_f32 v[254:255], v[252:253], v[250:251], v[254:255]
	v_div_fixup_f32 v244, v254, v244, 1.0
	v_div_fixup_f32 v245, v255, v245, 1.0
	v_rcp_f32_e32 v250, v246
	v_rcp_f32_e32 v251, v247
	s_nop 0
	v_pk_fma_f32 v[252:253], v[246:247], v[250:251], 1.0 op_sel_hi:[1,1,0] neg_lo:[1,0,0] neg_hi:[1,0,0]
	v_pk_fma_f32 v[250:251], v[252:253], v[250:251], v[250:251]
	v_pk_fma_f32 v[252:253], v[246:247], v[250:251], 1.0 op_sel_hi:[1,1,0] neg_lo:[1,0,0] neg_hi:[1,0,0]
	v_pk_fma_f32 v[254:255], v[252:253], v[250:251], v[250:251]
	v_pk_fma_f32 v[252:253], v[246:247], v[254:255], 1.0 op_sel_hi:[1,1,0] neg_lo:[1,0,0] neg_hi:[1,0,0]
	v_pk_fma_f32 v[254:255], v[252:253], v[250:251], v[254:255]
	v_div_fixup_f32 v246, v254, v246, 1.0
	v_div_fixup_f32 v247, v255, v247, 1.0
	v_rcp_f32_e32 v250, v248
	v_rcp_f32_e32 v251, v249
	s_nop 0
	v_pk_fma_f32 v[252:253], v[248:249], v[250:251], 1.0 op_sel_hi:[1,1,0] neg_lo:[1,0,0] neg_hi:[1,0,0]
	v_pk_fma_f32 v[250:251], v[252:253], v[250:251], v[250:251]
	v_pk_fma_f32 v[252:253], v[248:249], v[250:251], 1.0 op_sel_hi:[1,1,0] neg_lo:[1,0,0] neg_hi:[1,0,0]
	v_pk_fma_f32 v[254:255], v[252:253], v[250:251], v[250:251]
	v_pk_fma_f32 v[252:253], v[248:249], v[254:255], 1.0 op_sel_hi:[1,1,0] neg_lo:[1,0,0] neg_hi:[1,0,0]
	v_pk_fma_f32 v[254:255], v[252:253], v[250:251], v[254:255]
	v_div_fixup_f32 v248, v254, v248, 1.0
	v_div_fixup_f32 v249, v255, v249, 1.0
	v_lshlrev_b32_e32 v36, 16, v28
	v_and_b32_e32 v37, 0xffff0000, v28
	v_lshlrev_b32_e32 v38, 16, v30
	v_and_b32_e32 v39, 0xffff0000, v30
	v_lshlrev_b32_e32 v30, 16, v31
	v_and_b32_e32 v31, 0xffff0000, v31
	v_lshlrev_b32_e32 v28, 16, v29
	v_and_b32_e32 v29, 0xffff0000, v29
	v_pk_fma_f32 v[20:21], v[20:21], v[244:245], v[36:37]
	v_pk_fma_f32 v[24:25], v[18:19], v[248:249], v[30:31]
	v_pk_fma_f32 v[18:19], v[16:17], v[242:243], v[38:39]
	v_cvt_pk_bf16_f32 v16, v20, v21
	v_pk_fma_f32 v[22:23], v[22:23], v[246:247], v[28:29]
	s_nop 0
	v_cvt_pk_bf16_f32 v17, v22, v23
	v_cvt_pk_bf16_f32 v18, v18, v19
	v_cvt_pk_bf16_f32 v19, v24, v25
	buffer_store_dwordx4 v[16:19], v40, s[24:27], 0 offen offset:256 sc1
	s_nop 1
	v_add_u32_e32 v16, 0xb0, v162
	v_mad_i64_i32 v[18:19], s[6:7], v16, s77, 0
	v_lshl_add_u64 v[16:17], v[18:19], 1, s[38:39]
	v_lshl_add_u64 v[16:17], v[16:17], 0, v[148:149]
	v_add_co_u32_e32 v20, vcc, s78, v16
	s_nop 1
	v_addc_co_u32_e32 v21, vcc, 0, v17, vcc
	s_waitcnt vmcnt(5)
; __device__ __forceinline__ float sigmoidf_(float x) { return 1.0f / (1.0f + __expf(-x)); }
; __device__ __forceinline__ u32x4 pack8(const f32x4 v0, const f32x4 v1) { u32x4 w; w.x = pk2(v0[0], v0[1]); w.y = pk2(v0[2], v0[3]); w.z = pk2(v1[0], v1[1]); w.w = pk2(v1[2], v1[3]); return w; }
; __device__ __forceinline__ void unpack8(const u32x4 w, f32x4& v0, f32x4& v1) { v0 = (f32x4){bflo(w.x), bfhi(w.x), bflo(w.y), bfhi(w.y)}; v1 = (f32x4){bflo(w.z), bfhi(w.z), bflo(w.w), bfhi(w.w)}; }
;     __device__ __forceinline__ void operator()(const f32x4 (&acc)[2][2][4][2], const Unit& u, int wr, int wc, int fr, int fq) const {
;     ...
;                 for (int bj = 0; bj < 2; ++bj) {
;                     const u32x4 gw = *(const u32x4*)(rowp + O_GA + bj * 128);
;                     f32x4 g0, g1; unpack8(gw, g0, g1);
;                     f32x4 v0, v1;
; #pragma unroll
;                     for (int j = 0; j < 4; ++j) { v0[j] = sigmoidf_(g0[j]) * acc[ai][bj][m][0][j]; v1[j] = sigmoidf_(g1[j]) * acc[ai][bj][m][1][j]; }
;                     const u32x4 mw = *(const u32x4*)(rowp + bj * 128); f32x4 m0, m1; unpack8(mw, m0, m1); v0 += m0; v1 += m1;
;                     __builtin_amdgcn_raw_buffer_store_b128(pack8(v0, v1), rsrc, (unsigned)(((size_t)row * DIN + col0 + bj * 128) * 2), 0, 16  ); }
	v_mov_b64_e32 v[22:23], v[232:233]
	v_mov_b64_e32 v[24:25], v[234:235]
	v_mov_b64_e32 v[26:27], v[236:237]
	v_mov_b64_e32 v[28:29], v[238:239]
	s_mov_b32 s100, 0xbfb8aa3b
	v_lshlrev_b32_e32 v242, 16, v22
	v_and_b32_e32 v243, 0xffff0000, v22
	v_lshlrev_b32_e32 v244, 16, v24
	v_and_b32_e32 v245, 0xffff0000, v24
	v_lshlrev_b32_e32 v246, 16, v23
	v_and_b32_e32 v247, 0xffff0000, v23
	v_lshlrev_b32_e32 v248, 16, v25
	v_and_b32_e32 v249, 0xffff0000, v25
	v_pk_mul_f32 v[242:243], v[242:243], s[100:101] op_sel_hi:[1,0]
	v_pk_mul_f32 v[244:245], v[244:245], s[100:101] op_sel_hi:[1,0]
	v_pk_mul_f32 v[246:247], v[246:247], s[100:101] op_sel_hi:[1,0]
	v_pk_mul_f32 v[248:249], v[248:249], s[100:101] op_sel_hi:[1,0]
	v_exp_f32_e32 v242, v242
	v_exp_f32_e32 v243, v243
	v_exp_f32_e32 v244, v244
	v_exp_f32_e32 v245, v245
	v_exp_f32_e32 v246, v246
	v_exp_f32_e32 v247, v247
	v_exp_f32_e32 v248, v248
	v_exp_f32_e32 v249, v249
	s_nop 0
	v_pk_add_f32 v[242:243], v[242:243], 1.0 op_sel_hi:[1,0]
	v_pk_add_f32 v[244:245], v[244:245], 1.0 op_sel_hi:[1,0]
	v_pk_add_f32 v[246:247], v[246:247], 1.0 op_sel_hi:[1,0]
	v_pk_add_f32 v[248:249], v[248:249], 1.0 op_sel_hi:[1,0]
	v_rcp_f32_e32 v250, v242
	v_rcp_f32_e32 v251, v243
	s_nop 0
	v_pk_fma_f32 v[252:253], v[242:243], v[250:251], 1.0 op_sel_hi:[1,1,0] neg_lo:[1,0,0] neg_hi:[1,0,0]
	v_pk_fma_f32 v[250:251], v[252:253], v[250:251], v[250:251]
	v_pk_fma_f32 v[252:253], v[242:243], v[250:251], 1.0 op_sel_hi:[1,1,0] neg_lo:[1,0,0] neg_hi:[1,0,0]
	v_pk_fma_f32 v[254:255], v[252:253], v[250:251], v[250:251]
	v_pk_fma_f32 v[252:253], v[242:243], v[254:255], 1.0 op_sel_hi:[1,1,0] neg_lo:[1,0,0] neg_hi:[1,0,0]
	v_pk_fma_f32 v[254:255], v[252:253], v[250:251], v[254:255]
	v_div_fixup_f32 v242, v254, v242, 1.0
	v_div_fixup_f32 v243, v255, v243, 1.0
	v_rcp_f32_e32 v250, v244
	v_rcp_f32_e32 v251, v245
	s_nop 0
	v_pk_fma_f32 v[252:253], v[244:245], v[250:251], 1.0 op_sel_hi:[1,1,0] neg_lo:[1,0,0] neg_hi:[1,0,0]
	v_pk_fma_f32 v[250:251], v[252:253], v[250:251], v[250:251]
	v_pk_fma_f32 v[252:253], v[244:245], v[250:251], 1.0 op_sel_hi:[1,1,0] neg_lo:[1,0,0] neg_hi:[1,0,0]
	v_pk_fma_f32 v[254:255], v[252:253], v[250:251], v[250:251]
	v_pk_fma_f32 v[252:253], v[244:245], v[254:255], 1.0 op_sel_hi:[1,1,0] neg_lo:[1,0,0] neg_hi:[1,0,0]
	v_pk_fma_f32 v[254:255], v[252:253], v[250:251], v[254:255]
	v_div_fixup_f32 v244, v254, v244, 1.0
	v_div_fixup_f32 v245, v255, v245, 1.0
	v_rcp_f32_e32 v250, v246
	v_rcp_f32_e32 v251, v247
	s_nop 0
	v_pk_fma_f32 v[252:253], v[246:247], v[250:251], 1.0 op_sel_hi:[1,1,0] neg_lo:[1,0,0] neg_hi:[1,0,0]
	v_pk_fma_f32 v[250:251], v[252:253], v[250:251], v[250:251]
	v_pk_fma_f32 v[252:253], v[246:247], v[250:251], 1.0 op_sel_hi:[1,1,0] neg_lo:[1,0,0] neg_hi:[1,0,0]
	v_pk_fma_f32 v[254:255], v[252:253], v[250:251], v[250:251]
	v_pk_fma_f32 v[252:253], v[246:247], v[254:255], 1.0 op_sel_hi:[1,1,0] neg_lo:[1,0,0] neg_hi:[1,0,0]
	v_pk_fma_f32 v[254:255], v[252:253], v[250:251], v[254:255]
	v_div_fixup_f32 v246, v254, v246, 1.0
	v_div_fixup_f32 v247, v255, v247, 1.0
	v_rcp_f32_e32 v250, v248
	v_rcp_f32_e32 v251, v249
	s_nop 0
	v_pk_fma_f32 v[252:253], v[248:249], v[250:251], 1.0 op_sel_hi:[1,1,0] neg_lo:[1,0,0] neg_hi:[1,0,0]
	v_pk_fma_f32 v[250:251], v[252:253], v[250:251], v[250:251]
	v_pk_fma_f32 v[252:253], v[248:249], v[250:251], 1.0 op_sel_hi:[1,1,0] neg_lo:[1,0,0] neg_hi:[1,0,0]
	v_pk_fma_f32 v[254:255], v[252:253], v[250:251], v[250:251]
	v_pk_fma_f32 v[252:253], v[248:249], v[254:255], 1.0 op_sel_hi:[1,1,0] neg_lo:[1,0,0] neg_hi:[1,0,0]
	v_pk_fma_f32 v[254:255], v[252:253], v[250:251], v[254:255]
	v_div_fixup_f32 v248, v254, v248, 1.0
	v_div_fixup_f32 v249, v255, v249, 1.0
	v_lshlrev_b32_e32 v34, 16, v26
	v_and_b32_e32 v35, 0xffff0000, v26
	v_lshlrev_b32_e32 v36, 16, v28
	v_and_b32_e32 v37, 0xffff0000, v28
	v_lshlrev_b32_e32 v28, 16, v29
	v_and_b32_e32 v29, 0xffff0000, v29
	v_lshlrev_b32_e32 v26, 16, v27
	v_and_b32_e32 v27, 0xffff0000, v27
	v_pk_fma_f32 v[12:13], v[12:13], v[242:243], v[34:35]
	v_pk_fma_f32 v[22:23], v[10:11], v[248:249], v[28:29]
	v_pk_fma_f32 v[10:11], v[8:9], v[244:245], v[36:37]
	v_add_lshl_u32 v24, v146, v18, 1
	v_pk_fma_f32 v[14:15], v[14:15], v[246:247], v[26:27]
	v_cvt_pk_bf16_f32 v8, v12, v13
	s_nop 0
	v_cvt_pk_bf16_f32 v9, v14, v15
	v_cvt_pk_bf16_f32 v10, v10, v11
	v_cvt_pk_bf16_f32 v11, v22, v23
	buffer_store_dwordx4 v[8:11], v24, s[24:27], 0 offen sc1
	s_nop 0
	s_waitcnt vmcnt(3)
; __device__ __forceinline__ float sigmoidf_(float x) { return 1.0f / (1.0f + __expf(-x)); }
; __device__ __forceinline__ u32x4 pack8(const f32x4 v0, const f32x4 v1) { u32x4 w; w.x = pk2(v0[0], v0[1]); w.y = pk2(v0[2], v0[3]); w.z = pk2(v1[0], v1[1]); w.w = pk2(v1[2], v1[3]); return w; }
; __device__ __forceinline__ void unpack8(const u32x4 w, f32x4& v0, f32x4& v1) { v0 = (f32x4){bflo(w.x), bfhi(w.x), bflo(w.y), bfhi(w.y)}; v1 = (f32x4){bflo(w.z), bfhi(w.z), bflo(w.w), bfhi(w.w)}; }
;     __device__ __forceinline__ void operator()(const f32x4 (&acc)[2][2][4][2], const Unit& u, int wr, int wc, int fr, int fq) const {
;     ...
;                 for (int bj = 0; bj < 2; ++bj) {
;                     const u32x4 gw = *(const u32x4*)(rowp + O_GA + bj * 128);
;                     f32x4 g0, g1; unpack8(gw, g0, g1);
;                     f32x4 v0, v1;
; #pragma unroll
;                     for (int j = 0; j < 4; ++j) { v0[j] = sigmoidf_(g0[j]) * acc[ai][bj][m][0][j]; v1[j] = sigmoidf_(g1[j]) * acc[ai][bj][m][1][j]; }
;                     const u32x4 mw = *(const u32x4*)(rowp + bj * 128); f32x4 m0, m1; unpack8(mw, m0, m1); v0 += m0; v1 += m1;
;                     __builtin_amdgcn_raw_buffer_store_b128(pack8(v0, v1), rsrc, (unsigned)(((size_t)row * DIN + col0 + bj * 128) * 2), 0, 16  ); }
;             }
;         asm volatile("s_waitcnt vmcnt(0)" ::: "memory");
;         if (fr == 0 && fq == 0) (void)__hip_atomic_fetch_add(ready + 64 * (pm_off + u.pm), 1u, __ATOMIC_RELAXED, __HIP_MEMORY_SCOPE_AGENT);
	v_mov_b64_e32 v[8:9], v[204:205]
	v_mov_b64_e32 v[10:11], v[206:207]
	v_mov_b64_e32 v[12:13], v[208:209]
	v_mov_b64_e32 v[14:15], v[210:211]
	s_mov_b32 s100, 0xbfb8aa3b
	v_lshlrev_b32_e32 v242, 16, v10
	v_and_b32_e32 v243, 0xffff0000, v10
	v_lshlrev_b32_e32 v244, 16, v8
	v_and_b32_e32 v245, 0xffff0000, v8
	v_lshlrev_b32_e32 v246, 16, v9
	v_and_b32_e32 v247, 0xffff0000, v9
	v_lshlrev_b32_e32 v248, 16, v11
	v_and_b32_e32 v249, 0xffff0000, v11
	v_pk_mul_f32 v[242:243], v[242:243], s[100:101] op_sel_hi:[1,0]
	v_pk_mul_f32 v[244:245], v[244:245], s[100:101] op_sel_hi:[1,0]
	v_pk_mul_f32 v[246:247], v[246:247], s[100:101] op_sel_hi:[1,0]
	v_pk_mul_f32 v[248:249], v[248:249], s[100:101] op_sel_hi:[1,0]
	v_exp_f32_e32 v242, v242
	v_exp_f32_e32 v243, v243
	v_exp_f32_e32 v244, v244
	v_exp_f32_e32 v245, v245
	v_exp_f32_e32 v246, v246
	v_exp_f32_e32 v247, v247
	v_exp_f32_e32 v248, v248
	v_exp_f32_e32 v249, v249
	s_nop 0
	v_pk_add_f32 v[242:243], v[242:243], 1.0 op_sel_hi:[1,0]
	v_pk_add_f32 v[244:245], v[244:245], 1.0 op_sel_hi:[1,0]
	v_pk_add_f32 v[246:247], v[246:247], 1.0 op_sel_hi:[1,0]
	v_pk_add_f32 v[248:249], v[248:249], 1.0 op_sel_hi:[1,0]
	v_rcp_f32_e32 v250, v242
	v_rcp_f32_e32 v251, v243
	s_nop 0
	v_pk_fma_f32 v[252:253], v[242:243], v[250:251], 1.0 op_sel_hi:[1,1,0] neg_lo:[1,0,0] neg_hi:[1,0,0]
	v_pk_fma_f32 v[250:251], v[252:253], v[250:251], v[250:251]
	v_pk_fma_f32 v[252:253], v[242:243], v[250:251], 1.0 op_sel_hi:[1,1,0] neg_lo:[1,0,0] neg_hi:[1,0,0]
	v_pk_fma_f32 v[254:255], v[252:253], v[250:251], v[250:251]
	v_pk_fma_f32 v[252:253], v[242:243], v[254:255], 1.0 op_sel_hi:[1,1,0] neg_lo:[1,0,0] neg_hi:[1,0,0]
	v_pk_fma_f32 v[254:255], v[252:253], v[250:251], v[254:255]
	v_div_fixup_f32 v242, v254, v242, 1.0
	v_div_fixup_f32 v243, v255, v243, 1.0
	v_rcp_f32_e32 v250, v244
	v_rcp_f32_e32 v251, v245
	s_nop 0
	v_pk_fma_f32 v[252:253], v[244:245], v[250:251], 1.0 op_sel_hi:[1,1,0] neg_lo:[1,0,0] neg_hi:[1,0,0]
	v_pk_fma_f32 v[250:251], v[252:253], v[250:251], v[250:251]
	v_pk_fma_f32 v[252:253], v[244:245], v[250:251], 1.0 op_sel_hi:[1,1,0] neg_lo:[1,0,0] neg_hi:[1,0,0]
	v_pk_fma_f32 v[254:255], v[252:253], v[250:251], v[250:251]
	v_pk_fma_f32 v[252:253], v[244:245], v[254:255], 1.0 op_sel_hi:[1,1,0] neg_lo:[1,0,0] neg_hi:[1,0,0]
	v_pk_fma_f32 v[254:255], v[252:253], v[250:251], v[254:255]
	v_div_fixup_f32 v244, v254, v244, 1.0
	v_div_fixup_f32 v245, v255, v245, 1.0
	v_rcp_f32_e32 v250, v246
	v_rcp_f32_e32 v251, v247
	s_nop 0
	v_pk_fma_f32 v[252:253], v[246:247], v[250:251], 1.0 op_sel_hi:[1,1,0] neg_lo:[1,0,0] neg_hi:[1,0,0]
	v_pk_fma_f32 v[250:251], v[252:253], v[250:251], v[250:251]
	v_pk_fma_f32 v[252:253], v[246:247], v[250:251], 1.0 op_sel_hi:[1,1,0] neg_lo:[1,0,0] neg_hi:[1,0,0]
	v_pk_fma_f32 v[254:255], v[252:253], v[250:251], v[250:251]
	v_pk_fma_f32 v[252:253], v[246:247], v[254:255], 1.0 op_sel_hi:[1,1,0] neg_lo:[1,0,0] neg_hi:[1,0,0]
	v_pk_fma_f32 v[254:255], v[252:253], v[250:251], v[254:255]
	v_div_fixup_f32 v246, v254, v246, 1.0
	v_div_fixup_f32 v247, v255, v247, 1.0
	v_rcp_f32_e32 v250, v248
	v_rcp_f32_e32 v251, v249
	s_nop 0
	v_pk_fma_f32 v[252:253], v[248:249], v[250:251], 1.0 op_sel_hi:[1,1,0] neg_lo:[1,0,0] neg_hi:[1,0,0]
	v_pk_fma_f32 v[250:251], v[252:253], v[250:251], v[250:251]
	v_pk_fma_f32 v[252:253], v[248:249], v[250:251], 1.0 op_sel_hi:[1,1,0] neg_lo:[1,0,0] neg_hi:[1,0,0]
	v_pk_fma_f32 v[254:255], v[252:253], v[250:251], v[250:251]
	v_pk_fma_f32 v[252:253], v[248:249], v[254:255], 1.0 op_sel_hi:[1,1,0] neg_lo:[1,0,0] neg_hi:[1,0,0]
	v_pk_fma_f32 v[254:255], v[252:253], v[250:251], v[254:255]
	v_div_fixup_f32 v248, v254, v248, 1.0
	v_div_fixup_f32 v249, v255, v249, 1.0
	v_lshlrev_b32_e32 v20, 16, v12
	v_and_b32_e32 v21, 0xffff0000, v12
	v_lshlrev_b32_e32 v22, 16, v14
	v_and_b32_e32 v23, 0xffff0000, v14
	v_lshlrev_b32_e32 v14, 16, v15
	v_and_b32_e32 v15, 0xffff0000, v15
	v_lshlrev_b32_e32 v12, 16, v13
	v_and_b32_e32 v13, 0xffff0000, v13
	v_pk_fma_f32 v[4:5], v[4:5], v[244:245], v[20:21]
	v_pk_fma_f32 v[8:9], v[2:3], v[248:249], v[14:15]
	v_pk_fma_f32 v[2:3], v[0:1], v[242:243], v[22:23]
	v_pk_fma_f32 v[6:7], v[6:7], v[246:247], v[12:13]
	v_cvt_pk_bf16_f32 v0, v4, v5
	s_nop 0
	v_cvt_pk_bf16_f32 v1, v6, v7
	v_cvt_pk_bf16_f32 v2, v2, v3
	v_cvt_pk_bf16_f32 v3, v8, v9
	buffer_store_dwordx4 v[0:3], v24, s[24:27], 0 offen offset:256 sc1
	s_waitcnt vmcnt(0)
	s_and_saveexec_b64 s[14:15], s[10:11]
	s_cbranch_execz .LBB0_692
	s_mov_b64 s[16:17], exec
	v_mbcnt_lo_u32_b32 v0, s16, 0
	v_mbcnt_hi_u32_b32 v0, s17, v0
	v_cmp_eq_u32_e32 vcc, 0, v0
	s_and_b64 s[6:7], exec, vcc
	s_mov_b64 exec, s[6:7]
	s_cbranch_execz .LBB0_692
	s_lshl_b32 s6, s79, 6
	s_ashr_i32 s7, s6, 31
	s_lshl_b64 s[6:7], s[6:7], 2
	s_add_u32 s6, s34, s6
	s_addc_u32 s7, s35, s7
	s_bcnt1_i32_b64 s8, s[16:17]
	v_mov_b32_e32 v0, s8
	global_atomic_add v131, v0, s[6:7]
	s_branch .LBB0_692

; #define PG8_STAGE(bufoff, gbase, voff) do { _Pragma("unroll") for (int _i = 0; _i < 2; ++_i) \
;         __builtin_amdgcn_global_load_lds((const unsigned*)((const char*)(gbase) + (voff)[_i]), (LAS unsigned*)(lds + (bufoff) + ldsw + _i * 8192), 16, 0, 0); } while (0)
; #define PG8_LDA(dst, b, h) do { _Pragma("unroll") for (int m = 0; m < 4; ++m) _Pragma("unroll") for (int k = 0; k < 2; ++k) dst[m][k] = *(const LAS bf16x8*)(lds + PG8_SA(b, h) + aoff + m * 2048 + k * 1024); } while (0)
; #define PG8_LDB(dst, b, h) do { _Pragma("unroll") for (int n = 0; n < 2; ++n) _Pragma("unroll") for (int k = 0; k < 2; ++k) dst[n][k] = *(const LAS bf16x8*)(lds + PG8_SB(b, h) + boff + n * 2048 + k * 1024); } while (0)
; #define PG8_MMA(ai, bj, At, Bt) do { __builtin_amdgcn_s_setprio(1); _Pragma("unroll") for (int m = 0; m < 4; ++m) _Pragma("unroll") for (int n = 0; n < 2; ++n) _Pragma("unroll") for (int k = 0; k < 2; ++k) \
;         acc[ai][bj][m][n] = __builtin_amdgcn_mfma_f32_16x16x32_bf16(Bt[n][k], At[m][k], acc[ai][bj][m][n], 0, 0, 0); __builtin_amdgcn_s_setprio(0); } while (0)
; #define PG8_WAIT_V(n) asm volatile("s_waitcnt vmcnt(" #n ")" ::: "memory")
; #define PG8_WAIT_L(n) asm volatile("s_waitcnt lgkmcnt(" #n ")" ::: "memory")
; #define PG8_BAR __builtin_amdgcn_s_barrier()
; #define PG8_SCHED __builtin_amdgcn_sched_barrier(0)
;     ...
;             PG8_LDB(B0, 0, 0); PG8_SCHED; PG8_LDA(At, 0, 0); PG8_STAGE(PG8_SA(1, 1), a1 + hA, voffA);
;             PG8_WAIT_L(8); PG8_BAR; PG8_WAIT_L(0); PG8_MMA(0, 0, At, B0); PG8_BAR; PG8_SCHED;
;             PG8_LDB(B1, 0, 1); PG8_STAGE(PG8_SB(0, 0), b2, voffB);
;             PG8_BAR; PG8_WAIT_L(0); PG8_MMA(0, 1, At, B1); PG8_BAR;
;             PG8_LDA(At, 0, 1); PG8_STAGE(PG8_SA(0, 0), a2, voffA);
;             PG8_BAR; PG8_WAIT_L(0); PG8_MMA(1, 0, At, B0); PG8_BAR; PG8_SCHED;
;             PG8_STAGE(PG8_SB(0, 1), b2 + hB, voffB);
;             PG8_WAIT_V(6); PG8_BAR; PG8_MMA(1, 1, At, B1); PG8_BAR;
.LBB0_723:
	ds_read_b128 v[140:143], v155
	ds_read_b128 v[146:149], v155 offset:1024
	ds_read_b128 v[158:161], v155 offset:2048
	ds_read_b128 v[162:165], v155 offset:3072
	s_add_u32 s14, s12, 0xfffe0080
	s_addc_u32 s15, s13, -1
	s_cmp_eq_u32 s39, 4
	s_cselect_b32 s17, s7, s15
	s_cselect_b32 s16, s8, s14
	s_cselect_b32 s15, s9, s33
	s_cselect_b32 s14, s18, s19
	v_lshl_add_u64 v[150:151], s[12:13], 0, v[138:139]
	s_add_i32 m0, s67, 0xc000
	ds_read_b128 v[170:173], v156
	ds_read_b128 v[174:177], v156 offset:1024
	ds_read_b128 v[178:181], v156 offset:2048
	ds_read_b128 v[182:185], v156 offset:3072
	ds_read_b128 v[186:189], v156 offset:4096
	ds_read_b128 v[190:193], v156 offset:5120
	ds_read_b128 v[194:197], v156 offset:6144
	ds_read_b128 v[198:201], v156 offset:7168
	global_load_lds_dwordx4 v[150:151], off
	v_lshl_add_u64 v[150:151], s[12:13], 0, v[136:137]
	s_add_i32 m0, s67, 0xe000
	s_nop 0
	global_load_lds_dwordx4 v[150:151], off
	s_waitcnt lgkmcnt(8)
	s_barrier
	s_waitcnt lgkmcnt(0)
	s_setprio 1
	s_waitcnt lgkmcnt(0)
	v_mfma_f32_16x16x32_bf16 v[124:127], v[140:143], v[170:173], v[124:127]
	v_mfma_f32_16x16x32_bf16 v[120:123], v[158:161], v[170:173], v[120:123]
	v_mfma_f32_16x16x32_bf16 v[108:111], v[140:143], v[178:181], v[108:111]
	v_mfma_f32_16x16x32_bf16 v[104:107], v[158:161], v[178:181], v[104:107]
	v_mfma_f32_16x16x32_bf16 v[92:95], v[140:143], v[186:189], v[92:95]
	v_mfma_f32_16x16x32_bf16 v[88:91], v[158:161], v[186:189], v[88:91]
	v_mfma_f32_16x16x32_bf16 v[76:79], v[140:143], v[194:197], v[76:79]
	v_mfma_f32_16x16x32_bf16 v[72:75], v[158:161], v[194:197], v[72:75]
	v_mfma_f32_16x16x32_bf16 v[124:127], v[146:149], v[174:177], v[124:127]
	v_mfma_f32_16x16x32_bf16 v[120:123], v[162:165], v[174:177], v[120:123]
	v_mfma_f32_16x16x32_bf16 v[108:111], v[146:149], v[182:185], v[108:111]
	v_mfma_f32_16x16x32_bf16 v[104:107], v[162:165], v[182:185], v[104:107]
	v_mfma_f32_16x16x32_bf16 v[92:95], v[146:149], v[190:193], v[92:95]
	v_mfma_f32_16x16x32_bf16 v[88:91], v[162:165], v[190:193], v[88:91]
	v_mfma_f32_16x16x32_bf16 v[76:79], v[146:149], v[198:201], v[76:79]
	v_mfma_f32_16x16x32_bf16 v[72:75], v[162:165], v[198:201], v[72:75]
	s_setprio 0
	s_barrier
	s_add_i32 s42, s75, s66
	v_lshl_add_u64 v[150:151], s[14:15], 0, v[130:131]
	s_mov_b32 m0, s42
	ds_read_b128 v[202:205], v157
	ds_read_b128 v[206:209], v157 offset:1024
	ds_read_b128 v[210:213], v157 offset:2048
	ds_read_b128 v[214:217], v157 offset:3072
	global_load_lds_dwordx4 v[150:151], off
	v_lshl_add_u64 v[218:219], s[14:15], 0, v[134:135]
	s_add_i32 m0, s42, 0x2000
	s_nop 0
	global_load_lds_dwordx4 v[218:219], off
	s_barrier
	s_waitcnt lgkmcnt(0)
	s_setprio 1
	s_waitcnt lgkmcnt(0)
	v_mfma_f32_16x16x32_bf16 v[116:119], v[202:205], v[170:173], v[116:119]
	v_mfma_f32_16x16x32_bf16 v[112:115], v[210:213], v[170:173], v[112:115]
	v_mfma_f32_16x16x32_bf16 v[100:103], v[202:205], v[178:181], v[100:103]
	v_mfma_f32_16x16x32_bf16 v[96:99], v[210:213], v[178:181], v[96:99]
	v_mfma_f32_16x16x32_bf16 v[84:87], v[202:205], v[186:189], v[84:87]
	v_mfma_f32_16x16x32_bf16 v[80:83], v[210:213], v[186:189], v[80:83]
	v_mfma_f32_16x16x32_bf16 v[68:71], v[202:205], v[194:197], v[68:71]
	v_mfma_f32_16x16x32_bf16 v[64:67], v[210:213], v[194:197], v[64:67]
	v_mfma_f32_16x16x32_bf16 v[116:119], v[206:209], v[174:177], v[116:119]
	v_mfma_f32_16x16x32_bf16 v[112:115], v[214:217], v[174:177], v[112:115]
	v_mfma_f32_16x16x32_bf16 v[100:103], v[206:209], v[182:185], v[100:103]
	v_mfma_f32_16x16x32_bf16 v[96:99], v[214:217], v[182:185], v[96:99]
	v_mfma_f32_16x16x32_bf16 v[84:87], v[206:209], v[190:193], v[84:87]
	v_mfma_f32_16x16x32_bf16 v[80:83], v[214:217], v[190:193], v[80:83]
	v_mfma_f32_16x16x32_bf16 v[68:71], v[206:209], v[198:201], v[68:71]
	v_mfma_f32_16x16x32_bf16 v[64:67], v[214:217], v[198:201], v[64:67]
	s_setprio 0
	s_mov_b32 m0, s67
	v_lshl_add_u64 v[220:221], s[16:17], 0, v[128:129]
	s_barrier
	ds_read_b128 v[170:173], v156 offset:16384
	ds_read_b128 v[174:177], v156 offset:17408
	ds_read_b128 v[178:181], v156 offset:18432
	ds_read_b128 v[182:185], v156 offset:19456
	ds_read_b128 v[186:189], v156 offset:20480
	ds_read_b128 v[190:193], v156 offset:21504
	ds_read_b128 v[194:197], v156 offset:22528
	ds_read_b128 v[198:201], v156 offset:23552
	global_load_lds_dwordx4 v[220:221], off
	v_lshl_add_u64 v[222:223], s[16:17], 0, v[132:133]
	s_mov_b32 m0, s68
	s_nop 0
	global_load_lds_dwordx4 v[222:223], off
	s_barrier
	s_waitcnt lgkmcnt(0)
	s_setprio 1
	s_waitcnt lgkmcnt(0)
	v_mfma_f32_16x16x32_bf16 v[60:63], v[140:143], v[170:173], v[60:63]
	v_mfma_f32_16x16x32_bf16 v[56:59], v[158:161], v[170:173], v[56:59]
	v_mfma_f32_16x16x32_bf16 v[44:47], v[140:143], v[178:181], v[44:47]
	v_mfma_f32_16x16x32_bf16 v[40:43], v[158:161], v[178:181], v[40:43]
	v_mfma_f32_16x16x32_bf16 v[28:31], v[140:143], v[186:189], v[28:31]
	v_mfma_f32_16x16x32_bf16 v[24:27], v[158:161], v[186:189], v[24:27]
	v_mfma_f32_16x16x32_bf16 v[12:15], v[140:143], v[194:197], v[12:15]
	v_mfma_f32_16x16x32_bf16 v[8:11], v[158:161], v[194:197], v[8:11]
	v_mfma_f32_16x16x32_bf16 v[60:63], v[146:149], v[174:177], v[60:63]
	v_mfma_f32_16x16x32_bf16 v[56:59], v[162:165], v[174:177], v[56:59]
	v_mfma_f32_16x16x32_bf16 v[44:47], v[146:149], v[182:185], v[44:47]
	v_mfma_f32_16x16x32_bf16 v[40:43], v[162:165], v[182:185], v[40:43]
	v_mfma_f32_16x16x32_bf16 v[28:31], v[146:149], v[190:193], v[28:31]
	v_mfma_f32_16x16x32_bf16 v[24:27], v[162:165], v[190:193], v[24:27]
	v_mfma_f32_16x16x32_bf16 v[12:15], v[146:149], v[198:201], v[12:15]
	v_mfma_f32_16x16x32_bf16 v[8:11], v[162:165], v[198:201], v[8:11]
	s_setprio 0
	s_barrier
; #define PG8_STAGE(bufoff, gbase, voff) do { _Pragma("unroll") for (int _i = 0; _i < 2; ++_i) \
;         __builtin_amdgcn_global_load_lds((const unsigned*)((const char*)(gbase) + (voff)[_i]), (LAS unsigned*)(lds + (bufoff) + ldsw + _i * 8192), 16, 0, 0); } while (0)
; #define PG8_LDA(dst, b, h) do { _Pragma("unroll") for (int m = 0; m < 4; ++m) _Pragma("unroll") for (int k = 0; k < 2; ++k) dst[m][k] = *(const LAS bf16x8*)(lds + PG8_SA(b, h) + aoff + m * 2048 + k * 1024); } while (0)
; #define PG8_LDB(dst, b, h) do { _Pragma("unroll") for (int n = 0; n < 2; ++n) _Pragma("unroll") for (int k = 0; k < 2; ++k) dst[n][k] = *(const LAS bf16x8*)(lds + PG8_SB(b, h) + boff + n * 2048 + k * 1024); } while (0)
; #define PG8_MMA(ai, bj, At, Bt) do { __builtin_amdgcn_s_setprio(1); _Pragma("unroll") for (int m = 0; m < 4; ++m) _Pragma("unroll") for (int n = 0; n < 2; ++n) _Pragma("unroll") for (int k = 0; k < 2; ++k) \
;         acc[ai][bj][m][n] = __builtin_amdgcn_mfma_f32_16x16x32_bf16(Bt[n][k], At[m][k], acc[ai][bj][m][n], 0, 0, 0); __builtin_amdgcn_s_setprio(0); } while (0)
; #define PG8_WAIT_V(n) asm volatile("s_waitcnt vmcnt(" #n ")" ::: "memory")
; #define PG8_WAIT_L(n) asm volatile("s_waitcnt lgkmcnt(" #n ")" ::: "memory")
; #define PG8_BAR __builtin_amdgcn_s_barrier()
; #define PG8_SCHED __builtin_amdgcn_sched_barrier(0)
;     ...
;             PG8_STAGE(PG8_SB(0, 1), b2 + hB, voffB);
;             PG8_WAIT_V(6); PG8_BAR; PG8_MMA(1, 1, At, B1); PG8_BAR;
;             PG8_LDB(B0, 1, 0); PG8_SCHED; PG8_LDA(At, 1, 0); PG8_STAGE(PG8_SA(0, 1), a2 + hA, voffA);
;             PG8_WAIT_L(8); PG8_BAR; PG8_WAIT_L(0); PG8_MMA(0, 0, At, B0); PG8_BAR; PG8_SCHED;
;             PG8_LDB(B1, 1, 1); PG8_STAGE(PG8_SB(1, 0), b3, voffB);
;             PG8_BAR; PG8_WAIT_L(0); PG8_MMA(0, 1, At, B1); PG8_BAR;
;             PG8_LDA(At, 1, 1); PG8_STAGE(PG8_SA(1, 0), a3, voffA);
;             PG8_BAR; PG8_WAIT_L(0); PG8_MMA(1, 0, At, B0); PG8_BAR; PG8_SCHED;
	s_add_u32 s42, s14, 0x20000
	s_addc_u32 s43, s15, 0
	s_add_i32 s44, s76, s66
	v_lshl_add_u64 v[140:141], s[42:43], 0, v[130:131]
	s_mov_b32 m0, s44
	s_nop 0
	global_load_lds_dwordx4 v[140:141], off
	v_lshl_add_u64 v[140:141], s[42:43], 0, v[134:135]
	s_add_i32 m0, s44, 0x2000
	s_nop 0
	global_load_lds_dwordx4 v[140:141], off
	s_waitcnt vmcnt(6)
	s_barrier
	s_setprio 1
	v_mfma_f32_16x16x32_bf16 v[52:55], v[202:205], v[170:173], v[52:55]
	v_mfma_f32_16x16x32_bf16 v[48:51], v[210:213], v[170:173], v[48:51]
	v_mfma_f32_16x16x32_bf16 v[36:39], v[202:205], v[178:181], v[36:39]
	v_mfma_f32_16x16x32_bf16 v[32:35], v[210:213], v[178:181], v[32:35]
	v_mfma_f32_16x16x32_bf16 v[20:23], v[202:205], v[186:189], v[20:23]
	v_mfma_f32_16x16x32_bf16 v[16:19], v[210:213], v[186:189], v[16:19]
	v_mfma_f32_16x16x32_bf16 v[4:7], v[202:205], v[194:197], v[4:7]
	v_mfma_f32_16x16x32_bf16 v[0:3], v[210:213], v[194:197], v[0:3]
	v_mfma_f32_16x16x32_bf16 v[52:55], v[206:209], v[174:177], v[52:55]
	v_mfma_f32_16x16x32_bf16 v[48:51], v[214:217], v[174:177], v[48:51]
	v_mfma_f32_16x16x32_bf16 v[36:39], v[206:209], v[182:185], v[36:39]
	v_mfma_f32_16x16x32_bf16 v[32:35], v[214:217], v[182:185], v[32:35]
	v_mfma_f32_16x16x32_bf16 v[20:23], v[206:209], v[190:193], v[20:23]
	v_mfma_f32_16x16x32_bf16 v[16:19], v[214:217], v[190:193], v[16:19]
	v_mfma_f32_16x16x32_bf16 v[4:7], v[206:209], v[198:201], v[4:7]
	v_mfma_f32_16x16x32_bf16 v[0:3], v[214:217], v[198:201], v[0:3]
	s_setprio 0
	s_add_i32 s42, 0, 0x18000
	v_add_u32_e32 v162, s42, v153
	s_barrier
	ds_read_b128 v[140:143], v162
	ds_read_b128 v[146:149], v162 offset:1024
	ds_read_b128 v[158:161], v162 offset:2048
	ds_read_b128 v[162:165], v162 offset:3072
	s_add_u32 s16, s16, 0x20000
	s_addc_u32 s17, s17, 0
	s_mov_b32 m0, s69
	v_lshl_add_u64 v[202:203], s[16:17], 0, v[128:129]
	ds_read_b128 v[170:173], v156 offset:32768
	ds_read_b128 v[174:177], v156 offset:33792
	ds_read_b128 v[178:181], v156 offset:34816
	ds_read_b128 v[182:185], v156 offset:35840
	ds_read_b128 v[186:189], v156 offset:36864
	ds_read_b128 v[190:193], v156 offset:37888
	ds_read_b128 v[194:197], v156 offset:38912
	ds_read_b128 v[198:201], v156 offset:39936
	global_load_lds_dwordx4 v[202:203], off
	v_lshl_add_u64 v[202:203], s[16:17], 0, v[132:133]
	s_mov_b32 m0, s70
	s_nop 0
	global_load_lds_dwordx4 v[202:203], off
	s_waitcnt lgkmcnt(8)
	s_barrier
	s_waitcnt lgkmcnt(0)
	s_setprio 1
	s_waitcnt lgkmcnt(0)
	v_mfma_f32_16x16x32_bf16 v[124:127], v[140:143], v[170:173], v[124:127]
	v_mfma_f32_16x16x32_bf16 v[120:123], v[158:161], v[170:173], v[120:123]
	v_mfma_f32_16x16x32_bf16 v[108:111], v[140:143], v[178:181], v[108:111]
	v_mfma_f32_16x16x32_bf16 v[104:107], v[158:161], v[178:181], v[104:107]
	v_mfma_f32_16x16x32_bf16 v[92:95], v[140:143], v[186:189], v[92:95]
	v_mfma_f32_16x16x32_bf16 v[88:91], v[158:161], v[186:189], v[88:91]
	v_mfma_f32_16x16x32_bf16 v[76:79], v[140:143], v[194:197], v[76:79]
	v_mfma_f32_16x16x32_bf16 v[72:75], v[158:161], v[194:197], v[72:75]
	v_mfma_f32_16x16x32_bf16 v[124:127], v[146:149], v[174:177], v[124:127]
	v_mfma_f32_16x16x32_bf16 v[120:123], v[162:165], v[174:177], v[120:123]
	v_mfma_f32_16x16x32_bf16 v[108:111], v[146:149], v[182:185], v[108:111]
	v_mfma_f32_16x16x32_bf16 v[104:107], v[162:165], v[182:185], v[104:107]
	v_mfma_f32_16x16x32_bf16 v[92:95], v[146:149], v[190:193], v[92:95]
	v_mfma_f32_16x16x32_bf16 v[88:91], v[162:165], v[190:193], v[88:91]
	v_mfma_f32_16x16x32_bf16 v[76:79], v[146:149], v[198:201], v[76:79]
	v_mfma_f32_16x16x32_bf16 v[72:75], v[162:165], v[198:201], v[72:75]
	s_setprio 0
	s_barrier
	s_add_i32 s16, 0, 0x1c000
	s_add_i32 s17, s42, s66
	v_add_u32_e32 v214, s16, v153
	v_lshl_add_u64 v[150:151], v[150:151], 0, s[40:41]
	s_mov_b32 m0, s17
	ds_read_b128 v[202:205], v214
	ds_read_b128 v[206:209], v214 offset:1024
	ds_read_b128 v[210:213], v214 offset:2048
	ds_read_b128 v[214:217], v214 offset:3072
	global_load_lds_dwordx4 v[150:151], off
	v_lshl_add_u64 v[150:151], v[218:219], 0, s[40:41]
	s_add_i32 m0, s17, 0x2000
	s_nop 0
	global_load_lds_dwordx4 v[150:151], off
	s_barrier
	s_waitcnt lgkmcnt(0)
	s_setprio 1
	s_waitcnt lgkmcnt(0)
	v_mfma_f32_16x16x32_bf16 v[116:119], v[202:205], v[170:173], v[116:119]
	v_mfma_f32_16x16x32_bf16 v[112:115], v[210:213], v[170:173], v[112:115]
	v_mfma_f32_16x16x32_bf16 v[100:103], v[202:205], v[178:181], v[100:103]
	v_mfma_f32_16x16x32_bf16 v[96:99], v[210:213], v[178:181], v[96:99]
	v_mfma_f32_16x16x32_bf16 v[84:87], v[202:205], v[186:189], v[84:87]
	v_mfma_f32_16x16x32_bf16 v[80:83], v[210:213], v[186:189], v[80:83]
	v_mfma_f32_16x16x32_bf16 v[68:71], v[202:205], v[194:197], v[68:71]
	v_mfma_f32_16x16x32_bf16 v[64:67], v[210:213], v[194:197], v[64:67]
	v_mfma_f32_16x16x32_bf16 v[116:119], v[206:209], v[174:177], v[116:119]
	v_mfma_f32_16x16x32_bf16 v[112:115], v[214:217], v[174:177], v[112:115]
	v_mfma_f32_16x16x32_bf16 v[100:103], v[206:209], v[182:185], v[100:103]
	v_mfma_f32_16x16x32_bf16 v[96:99], v[214:217], v[182:185], v[96:99]
	v_mfma_f32_16x16x32_bf16 v[84:87], v[206:209], v[190:193], v[84:87]
	v_mfma_f32_16x16x32_bf16 v[80:83], v[214:217], v[190:193], v[80:83]
	v_mfma_f32_16x16x32_bf16 v[68:71], v[206:209], v[198:201], v[68:71]
	v_mfma_f32_16x16x32_bf16 v[64:67], v[214:217], v[198:201], v[64:67]
	s_setprio 0
	s_mov_b32 m0, s72
	v_lshl_add_u64 v[150:151], v[220:221], 0, s[40:41]
	s_barrier
	ds_read_b128 v[170:173], v156 offset:49152
	ds_read_b128 v[174:177], v156 offset:50176
	ds_read_b128 v[178:181], v156 offset:51200
	ds_read_b128 v[182:185], v156 offset:52224
	ds_read_b128 v[186:189], v156 offset:53248
	ds_read_b128 v[190:193], v156 offset:54272
	ds_read_b128 v[194:197], v156 offset:55296
	ds_read_b128 v[198:201], v156 offset:56320
	global_load_lds_dwordx4 v[150:151], off
	v_lshl_add_u64 v[150:151], v[222:223], 0, s[40:41]
	s_mov_b32 m0, s73
	s_nop 0
	global_load_lds_dwordx4 v[150:151], off
	s_barrier
; __device__ __forceinline__ float sigmoidf_(float x) { return 1.0f / (1.0f + __expf(-x)); }
; #define PG8_STAGE(bufoff, gbase, voff) do { _Pragma("unroll") for (int _i = 0; _i < 2; ++_i) \
;         __builtin_amdgcn_global_load_lds((const unsigned*)((const char*)(gbase) + (voff)[_i]), (LAS unsigned*)(lds + (bufoff) + ldsw + _i * 8192), 16, 0, 0); } while (0)
; #define PG8_MMA(ai, bj, At, Bt) do { __builtin_amdgcn_s_setprio(1); _Pragma("unroll") for (int m = 0; m < 4; ++m) _Pragma("unroll") for (int n = 0; n < 2; ++n) _Pragma("unroll") for (int k = 0; k < 2; ++k) \
;         acc[ai][bj][m][n] = __builtin_amdgcn_mfma_f32_16x16x32_bf16(Bt[n][k], At[m][k], acc[ai][bj][m][n], 0, 0, 0); __builtin_amdgcn_s_setprio(0); } while (0)
; #define PG8_WAIT_V(n) asm volatile("s_waitcnt vmcnt(" #n ")" ::: "memory")
; #define PG8_WAIT_L(n) asm volatile("s_waitcnt lgkmcnt(" #n ")" ::: "memory")
;     ...
;             PG8_BAR; PG8_WAIT_L(0); PG8_MMA(1, 0, At, B0); PG8_BAR; PG8_SCHED;
;             PG8_STAGE(PG8_SB(1, 1), b3 + hB, voffB);
;             PG8_WAIT_V(6); PG8_BAR; PG8_MMA(1, 1, At, B1); PG8_BAR;
;     __device__ __forceinline__ void operator()(const f32x4 (&acc)[2][2][4][2], const Unit& u, int wr, int wc, int fr, int fq) const {
;         const __amdgpu_buffer_rsrc_t rsrc = __builtin_amdgcn_make_buffer_rsrc((void*)z, 0, T_ALL * DIN * 2, 0x00020000);
;         const int row0 = row_off + u.pm * 256 + wr * 64 + fr, col0 = u.pn * 256 + wc * 32 + 8 * fq;
; #pragma unroll
;         for (int ai = 0; ai < 2; ++ai)
; #pragma unroll
;             for (int m = 0; m < 4; ++m) {
;                 const int row = row0 + ai * 128 + m * 16;
;                 const bf16_t* rowp = z + (size_t)row * DIN + col0;
; #pragma unroll
;                 for (int bj = 0; bj < 2; ++bj) {
;                     const u32x4 gw = *(const u32x4*)(rowp + O_GA + bj * 128);
;                     f32x4 g0, g1; unpack8(gw, g0, g1);
;                     f32x4 v0, v1;
; #pragma unroll
;                     for (int j = 0; j < 4; ++j) { v0[j] = sigmoidf_(g0[j]) * acc[ai][bj][m][0][j]; v1[j] = sigmoidf_(g1[j]) * acc[ai][bj][m][1][j]; }
;                     const u32x4 mw = *(const u32x4*)(rowp + bj * 128); f32x4 m0, m1; unpack8(mw, m0, m1); v0 += m0; v1 += m1;
;                     __builtin_amdgcn_raw_buffer_store_b128(pack8(v0, v1), rsrc, (unsigned)(((size_t)row * DIN + col0 + bj * 128) * 2), 0, 16  ); }
	s_waitcnt lgkmcnt(0)
	s_setprio 1
	s_waitcnt lgkmcnt(0)
	v_mfma_f32_16x16x32_bf16 v[60:63], v[140:143], v[170:173], v[60:63]
	v_mfma_f32_16x16x32_bf16 v[56:59], v[158:161], v[170:173], v[56:59]
	v_mfma_f32_16x16x32_bf16 v[44:47], v[140:143], v[178:181], v[44:47]
	v_mfma_f32_16x16x32_bf16 v[40:43], v[158:161], v[178:181], v[40:43]
	v_mfma_f32_16x16x32_bf16 v[28:31], v[140:143], v[186:189], v[28:31]
	v_mfma_f32_16x16x32_bf16 v[24:27], v[158:161], v[186:189], v[24:27]
	v_mfma_f32_16x16x32_bf16 v[12:15], v[140:143], v[194:197], v[12:15]
	v_mfma_f32_16x16x32_bf16 v[8:11], v[158:161], v[194:197], v[8:11]
	v_mfma_f32_16x16x32_bf16 v[60:63], v[146:149], v[174:177], v[60:63]
	v_mfma_f32_16x16x32_bf16 v[56:59], v[162:165], v[174:177], v[56:59]
	v_mfma_f32_16x16x32_bf16 v[44:47], v[146:149], v[182:185], v[44:47]
	v_mfma_f32_16x16x32_bf16 v[40:43], v[162:165], v[182:185], v[40:43]
	v_mfma_f32_16x16x32_bf16 v[28:31], v[146:149], v[190:193], v[28:31]
	v_mfma_f32_16x16x32_bf16 v[24:27], v[162:165], v[190:193], v[24:27]
	v_mfma_f32_16x16x32_bf16 v[12:15], v[146:149], v[198:201], v[12:15]
	v_mfma_f32_16x16x32_bf16 v[8:11], v[162:165], v[198:201], v[8:11]
	s_setprio 0
	s_barrier
	s_add_u32 s14, s14, 0x20080
	s_addc_u32 s15, s15, 0
	s_add_i32 s16, s16, s66
	v_lshl_add_u64 v[140:141], s[14:15], 0, v[130:131]
	s_mov_b32 m0, s16
	s_nop 0
	global_load_lds_dwordx4 v[140:141], off
	v_lshl_add_u64 v[140:141], s[14:15], 0, v[134:135]
	s_add_i32 m0, s16, 0x2000
	s_nop 0
	global_load_lds_dwordx4 v[140:141], off
	s_waitcnt vmcnt(6)
	s_barrier
	s_setprio 1
	v_mfma_f32_16x16x32_bf16 v[52:55], v[202:205], v[170:173], v[52:55]
	v_mfma_f32_16x16x32_bf16 v[48:51], v[210:213], v[170:173], v[48:51]
	v_mfma_f32_16x16x32_bf16 v[36:39], v[202:205], v[178:181], v[36:39]
	v_mfma_f32_16x16x32_bf16 v[32:35], v[210:213], v[178:181], v[32:35]
	v_mfma_f32_16x16x32_bf16 v[20:23], v[202:205], v[186:189], v[20:23]
	v_mfma_f32_16x16x32_bf16 v[16:19], v[210:213], v[186:189], v[16:19]
	v_mfma_f32_16x16x32_bf16 v[4:7], v[202:205], v[194:197], v[4:7]
	v_mfma_f32_16x16x32_bf16 v[0:3], v[210:213], v[194:197], v[0:3]
	v_mfma_f32_16x16x32_bf16 v[52:55], v[206:209], v[174:177], v[52:55]
	v_mfma_f32_16x16x32_bf16 v[48:51], v[214:217], v[174:177], v[48:51]
	v_mfma_f32_16x16x32_bf16 v[36:39], v[206:209], v[182:185], v[36:39]
	v_mfma_f32_16x16x32_bf16 v[32:35], v[214:217], v[182:185], v[32:35]
	v_mfma_f32_16x16x32_bf16 v[20:23], v[206:209], v[190:193], v[20:23]
	v_mfma_f32_16x16x32_bf16 v[16:19], v[214:217], v[190:193], v[16:19]
	v_mfma_f32_16x16x32_bf16 v[4:7], v[206:209], v[198:201], v[4:7]
	v_mfma_f32_16x16x32_bf16 v[0:3], v[214:217], v[198:201], v[0:3]
	s_setprio 0
	s_add_i32 s39, s39, 2
	s_add_u32 s19, s19, 0x100
	s_addc_u32 s33, s33, 0
	s_add_u32 s12, s12, 0x100
	s_addc_u32 s13, s13, 0
	s_cmp_gt_u32 s39, 5
	s_barrier
	s_cbranch_scc0 .LBB0_723
	v_lshl_add_u32 v158, s79, 8, v152
	v_lshl_or_b32 v140, s6, 8, v154
	v_add_u32_e32 v142, 0x4000, v158
	v_ashrrev_i32_e32 v141, 31, v140
	v_mad_i64_i32 v[150:151], s[6:7], v142, s77, 0
	v_lshl_add_u64 v[146:147], v[150:151], 1, s[26:27]
	v_lshlrev_b64 v[142:143], 1, v[140:141]
	v_lshl_add_u64 v[146:147], v[146:147], 0, v[142:143]
	v_add_co_u32_e32 v148, vcc, 0x1000, v146
	s_nop 1
	v_addc_co_u32_e32 v149, vcc, 0, v147, vcc
	v_subrev_u32_e32 v198, s26, v146
	v_add_u32_e32 v199, 0x1200, v198
	global_load_dwordx4 v[200:203], v199, s[26:27]
	v_add_u32_e32 v199, 0x0, v198
	global_load_dwordx4 v[204:207], v199, s[26:27]
	v_add_u32_e32 v199, 0x1300, v198
	global_load_dwordx4 v[208:211], v199, s[26:27]
	v_add_u32_e32 v199, 0x100, v198
	global_load_dwordx4 v[212:215], v199, s[26:27]
	v_add_u32_e32 v199, 0x23200, v198
	global_load_dwordx4 v[232:235], v199, s[26:27]
	v_add_u32_e32 v199, 0x22000, v198
	global_load_dwordx4 v[236:239], v199, s[26:27]
	s_waitcnt vmcnt(4)
	v_mov_b64_e32 v[160:161], v[200:201]
	v_mov_b64_e32 v[162:163], v[202:203]
	v_mov_b64_e32 v[170:171], v[204:205]
	v_mov_b64_e32 v[172:173], v[206:207]
	v_add_u32_e32 v199, 0x23300, v198
	global_load_dwordx4 v[200:203], v199, s[26:27]
	v_add_u32_e32 v199, 0x22100, v198
	global_load_dwordx4 v[204:207], v199, s[26:27]
	s_mov_b32 s100, 0xbfb8aa3b
	v_lshlrev_b32_e32 v242, 16, v160
	v_and_b32_e32 v243, 0xffff0000, v160
	v_lshlrev_b32_e32 v244, 16, v162
	v_and_b32_e32 v245, 0xffff0000, v162
	v_lshlrev_b32_e32 v246, 16, v161
	v_and_b32_e32 v247, 0xffff0000, v161
	v_lshlrev_b32_e32 v248, 16, v163
	v_and_b32_e32 v249, 0xffff0000, v163
	v_pk_mul_f32 v[242:243], v[242:243], s[100:101] op_sel_hi:[1,0]
	v_pk_mul_f32 v[244:245], v[244:245], s[100:101] op_sel_hi:[1,0]
	v_pk_mul_f32 v[246:247], v[246:247], s[100:101] op_sel_hi:[1,0]
	v_pk_mul_f32 v[248:249], v[248:249], s[100:101] op_sel_hi:[1,0]
	v_exp_f32_e32 v242, v242
	v_exp_f32_e32 v243, v243
	v_exp_f32_e32 v244, v244
	v_exp_f32_e32 v245, v245
	v_exp_f32_e32 v246, v246
	v_exp_f32_e32 v247, v247
	v_exp_f32_e32 v248, v248
	v_exp_f32_e32 v249, v249
	s_nop 0
	v_pk_add_f32 v[242:243], v[242:243], 1.0 op_sel_hi:[1,0]
	v_pk_add_f32 v[244:245], v[244:245], 1.0 op_sel_hi:[1,0]
	v_pk_add_f32 v[246:247], v[246:247], 1.0 op_sel_hi:[1,0]
	v_pk_add_f32 v[248:249], v[248:249], 1.0 op_sel_hi:[1,0]
	v_rcp_f32_e32 v250, v242
	v_rcp_f32_e32 v251, v243
	s_nop 0
	v_pk_fma_f32 v[252:253], v[242:243], v[250:251], 1.0 op_sel_hi:[1,1,0] neg_lo:[1,0,0] neg_hi:[1,0,0]
	v_pk_fma_f32 v[250:251], v[252:253], v[250:251], v[250:251]
	v_pk_fma_f32 v[252:253], v[242:243], v[250:251], 1.0 op_sel_hi:[1,1,0] neg_lo:[1,0,0] neg_hi:[1,0,0]
	v_pk_fma_f32 v[254:255], v[252:253], v[250:251], v[250:251]
	v_pk_fma_f32 v[252:253], v[242:243], v[254:255], 1.0 op_sel_hi:[1,1,0] neg_lo:[1,0,0] neg_hi:[1,0,0]
; __device__ __forceinline__ float sigmoidf_(float x) { return 1.0f / (1.0f + __expf(-x)); }
; __device__ __forceinline__ u32x4 pack8(const f32x4 v0, const f32x4 v1) { u32x4 w; w.x = pk2(v0[0], v0[1]); w.y = pk2(v0[2], v0[3]); w.z = pk2(v1[0], v1[1]); w.w = pk2(v1[2], v1[3]); return w; }
; __device__ __forceinline__ void unpack8(const u32x4 w, f32x4& v0, f32x4& v1) { v0 = (f32x4){bflo(w.x), bfhi(w.x), bflo(w.y), bfhi(w.y)}; v1 = (f32x4){bflo(w.z), bfhi(w.z), bflo(w.w), bfhi(w.w)}; }
;     __device__ __forceinline__ void operator()(const f32x4 (&acc)[2][2][4][2], const Unit& u, int wr, int wc, int fr, int fq) const {
;     ...
;                 for (int bj = 0; bj < 2; ++bj) {
;                     const u32x4 gw = *(const u32x4*)(rowp + O_GA + bj * 128);
;                     f32x4 g0, g1; unpack8(gw, g0, g1);
;                     f32x4 v0, v1;
; #pragma unroll
;                     for (int j = 0; j < 4; ++j) { v0[j] = sigmoidf_(g0[j]) * acc[ai][bj][m][0][j]; v1[j] = sigmoidf_(g1[j]) * acc[ai][bj][m][1][j]; }
;                     const u32x4 mw = *(const u32x4*)(rowp + bj * 128); f32x4 m0, m1; unpack8(mw, m0, m1); v0 += m0; v1 += m1;
;                     __builtin_amdgcn_raw_buffer_store_b128(pack8(v0, v1), rsrc, (unsigned)(((size_t)row * DIN + col0 + bj * 128) * 2), 0, 16  ); }
	v_pk_fma_f32 v[254:255], v[252:253], v[250:251], v[254:255]
	v_div_fixup_f32 v242, v254, v242, 1.0
	v_div_fixup_f32 v243, v255, v243, 1.0
	v_rcp_f32_e32 v250, v244
	v_rcp_f32_e32 v251, v245
	s_nop 0
	v_pk_fma_f32 v[252:253], v[244:245], v[250:251], 1.0 op_sel_hi:[1,1,0] neg_lo:[1,0,0] neg_hi:[1,0,0]
	v_pk_fma_f32 v[250:251], v[252:253], v[250:251], v[250:251]
	v_pk_fma_f32 v[252:253], v[244:245], v[250:251], 1.0 op_sel_hi:[1,1,0] neg_lo:[1,0,0] neg_hi:[1,0,0]
	v_pk_fma_f32 v[254:255], v[252:253], v[250:251], v[250:251]
	v_pk_fma_f32 v[252:253], v[244:245], v[254:255], 1.0 op_sel_hi:[1,1,0] neg_lo:[1,0,0] neg_hi:[1,0,0]
	v_pk_fma_f32 v[254:255], v[252:253], v[250:251], v[254:255]
	v_div_fixup_f32 v244, v254, v244, 1.0
	v_div_fixup_f32 v245, v255, v245, 1.0
	v_rcp_f32_e32 v250, v246
	v_rcp_f32_e32 v251, v247
	s_nop 0
	v_pk_fma_f32 v[252:253], v[246:247], v[250:251], 1.0 op_sel_hi:[1,1,0] neg_lo:[1,0,0] neg_hi:[1,0,0]
	v_pk_fma_f32 v[250:251], v[252:253], v[250:251], v[250:251]
	v_pk_fma_f32 v[252:253], v[246:247], v[250:251], 1.0 op_sel_hi:[1,1,0] neg_lo:[1,0,0] neg_hi:[1,0,0]
	v_pk_fma_f32 v[254:255], v[252:253], v[250:251], v[250:251]
	v_pk_fma_f32 v[252:253], v[246:247], v[254:255], 1.0 op_sel_hi:[1,1,0] neg_lo:[1,0,0] neg_hi:[1,0,0]
	v_pk_fma_f32 v[254:255], v[252:253], v[250:251], v[254:255]
	v_div_fixup_f32 v246, v254, v246, 1.0
	v_div_fixup_f32 v247, v255, v247, 1.0
	v_rcp_f32_e32 v250, v248
	v_rcp_f32_e32 v251, v249
	s_nop 0
	v_pk_fma_f32 v[252:253], v[248:249], v[250:251], 1.0 op_sel_hi:[1,1,0] neg_lo:[1,0,0] neg_hi:[1,0,0]
	v_pk_fma_f32 v[250:251], v[252:253], v[250:251], v[250:251]
	v_pk_fma_f32 v[252:253], v[248:249], v[250:251], 1.0 op_sel_hi:[1,1,0] neg_lo:[1,0,0] neg_hi:[1,0,0]
	v_pk_fma_f32 v[254:255], v[252:253], v[250:251], v[250:251]
	v_pk_fma_f32 v[252:253], v[248:249], v[254:255], 1.0 op_sel_hi:[1,1,0] neg_lo:[1,0,0] neg_hi:[1,0,0]
	v_pk_fma_f32 v[254:255], v[252:253], v[250:251], v[254:255]
	v_div_fixup_f32 v248, v254, v248, 1.0
	v_div_fixup_f32 v249, v255, v249, 1.0
	s_mov_b64 vcc, s[12:13]
	s_mov_b64 vcc, s[14:15]
	s_mov_b64 vcc, s[16:17]
	s_mov_b64 vcc, s[18:19]
	v_lshlrev_b32_e32 v178, 16, v172
	v_and_b32_e32 v179, 0xffff0000, v172
	v_lshlrev_b32_e32 v176, 16, v170
	v_and_b32_e32 v177, 0xffff0000, v170
	v_lshlrev_b32_e32 v172, 16, v173
	v_and_b32_e32 v173, 0xffff0000, v173
	v_lshlrev_b32_e32 v170, 16, v171
	v_and_b32_e32 v171, 0xffff0000, v171
	v_pk_fma_f32 v[124:125], v[124:125], v[242:243], v[176:177]
	v_pk_fma_f32 v[160:161], v[122:123], v[248:249], v[172:173]
	v_pk_fma_f32 v[122:123], v[120:121], v[244:245], v[178:179]
	v_add_lshl_u32 v141, v140, v150, 1
	v_pk_fma_f32 v[126:127], v[126:127], v[246:247], v[170:171]
	v_cvt_pk_bf16_f32 v120, v124, v125
	s_nop 0
	v_cvt_pk_bf16_f32 v121, v126, v127
	v_cvt_pk_bf16_f32 v122, v122, v123
	v_cvt_pk_bf16_f32 v123, v160, v161
	buffer_store_dwordx4 v[120:123], v141, s[20:23], 0 offen sc1
	s_nop 0
	s_waitcnt vmcnt(5)
	v_mov_b64_e32 v[120:121], v[208:209]
	v_mov_b64_e32 v[122:123], v[210:211]
	v_mov_b64_e32 v[124:125], v[212:213]
	v_mov_b64_e32 v[126:127], v[214:215]
	v_add_u32_e32 v199, 0x45200, v198
	global_load_dwordx4 v[208:211], v199, s[26:27]
	v_add_u32_e32 v199, 0x44000, v198
	global_load_dwordx4 v[212:215], v199, s[26:27]
	s_mov_b32 s100, 0xbfb8aa3b
	v_lshlrev_b32_e32 v242, 16, v120
	v_and_b32_e32 v243, 0xffff0000, v120
	v_lshlrev_b32_e32 v244, 16, v122
	v_and_b32_e32 v245, 0xffff0000, v122
	v_lshlrev_b32_e32 v246, 16, v121
	v_and_b32_e32 v247, 0xffff0000, v121
	v_lshlrev_b32_e32 v248, 16, v123
	v_and_b32_e32 v249, 0xffff0000, v123
	v_pk_mul_f32 v[242:243], v[242:243], s[100:101] op_sel_hi:[1,0]
	v_pk_mul_f32 v[244:245], v[244:245], s[100:101] op_sel_hi:[1,0]
	v_pk_mul_f32 v[246:247], v[246:247], s[100:101] op_sel_hi:[1,0]
	v_pk_mul_f32 v[248:249], v[248:249], s[100:101] op_sel_hi:[1,0]
	v_exp_f32_e32 v242, v242
	v_exp_f32_e32 v243, v243
	v_exp_f32_e32 v244, v244
	v_exp_f32_e32 v245, v245
	v_exp_f32_e32 v246, v246
	v_exp_f32_e32 v247, v247
	v_exp_f32_e32 v248, v248
	v_exp_f32_e32 v249, v249
	s_nop 0
	v_pk_add_f32 v[242:243], v[242:243], 1.0 op_sel_hi:[1,0]
	v_pk_add_f32 v[244:245], v[244:245], 1.0 op_sel_hi:[1,0]
	v_pk_add_f32 v[246:247], v[246:247], 1.0 op_sel_hi:[1,0]
	v_pk_add_f32 v[248:249], v[248:249], 1.0 op_sel_hi:[1,0]
	v_rcp_f32_e32 v250, v242
	v_rcp_f32_e32 v251, v243
	s_nop 0
	v_pk_fma_f32 v[252:253], v[242:243], v[250:251], 1.0 op_sel_hi:[1,1,0] neg_lo:[1,0,0] neg_hi:[1,0,0]
	v_pk_fma_f32 v[250:251], v[252:253], v[250:251], v[250:251]
	v_pk_fma_f32 v[252:253], v[242:243], v[250:251], 1.0 op_sel_hi:[1,1,0] neg_lo:[1,0,0] neg_hi:[1,0,0]
	v_pk_fma_f32 v[254:255], v[252:253], v[250:251], v[250:251]
	v_pk_fma_f32 v[252:253], v[242:243], v[254:255], 1.0 op_sel_hi:[1,1,0] neg_lo:[1,0,0] neg_hi:[1,0,0]
	v_pk_fma_f32 v[254:255], v[252:253], v[250:251], v[254:255]
	v_div_fixup_f32 v242, v254, v242, 1.0
	v_div_fixup_f32 v243, v255, v243, 1.0
	v_rcp_f32_e32 v250, v244
	v_rcp_f32_e32 v251, v245
	s_nop 0
	v_pk_fma_f32 v[252:253], v[244:245], v[250:251], 1.0 op_sel_hi:[1,1,0] neg_lo:[1,0,0] neg_hi:[1,0,0]
	v_pk_fma_f32 v[250:251], v[252:253], v[250:251], v[250:251]
	v_pk_fma_f32 v[252:253], v[244:245], v[250:251], 1.0 op_sel_hi:[1,1,0] neg_lo:[1,0,0] neg_hi:[1,0,0]
	v_pk_fma_f32 v[254:255], v[252:253], v[250:251], v[250:251]
	v_pk_fma_f32 v[252:253], v[244:245], v[254:255], 1.0 op_sel_hi:[1,1,0] neg_lo:[1,0,0] neg_hi:[1,0,0]
	v_pk_fma_f32 v[254:255], v[252:253], v[250:251], v[254:255]
	v_div_fixup_f32 v244, v254, v244, 1.0
	v_div_fixup_f32 v245, v255, v245, 1.0
	v_rcp_f32_e32 v250, v246
	v_rcp_f32_e32 v251, v247
	s_nop 0
; __device__ __forceinline__ float sigmoidf_(float x) { return 1.0f / (1.0f + __expf(-x)); }
; __device__ __forceinline__ u32x4 pack8(const f32x4 v0, const f32x4 v1) { u32x4 w; w.x = pk2(v0[0], v0[1]); w.y = pk2(v0[2], v0[3]); w.z = pk2(v1[0], v1[1]); w.w = pk2(v1[2], v1[3]); return w; }
; __device__ __forceinline__ void unpack8(const u32x4 w, f32x4& v0, f32x4& v1) { v0 = (f32x4){bflo(w.x), bfhi(w.x), bflo(w.y), bfhi(w.y)}; v1 = (f32x4){bflo(w.z), bfhi(w.z), bflo(w.w), bfhi(w.w)}; }
;     __device__ __forceinline__ void operator()(const f32x4 (&acc)[2][2][4][2], const Unit& u, int wr, int wc, int fr, int fq) const {
;     ...
;                 for (int bj = 0; bj < 2; ++bj) {
;                     const u32x4 gw = *(const u32x4*)(rowp + O_GA + bj * 128);
;                     f32x4 g0, g1; unpack8(gw, g0, g1);
;                     f32x4 v0, v1;
; #pragma unroll
;                     for (int j = 0; j < 4; ++j) { v0[j] = sigmoidf_(g0[j]) * acc[ai][bj][m][0][j]; v1[j] = sigmoidf_(g1[j]) * acc[ai][bj][m][1][j]; }
;                     const u32x4 mw = *(const u32x4*)(rowp + bj * 128); f32x4 m0, m1; unpack8(mw, m0, m1); v0 += m0; v1 += m1;
;                     __builtin_amdgcn_raw_buffer_store_b128(pack8(v0, v1), rsrc, (unsigned)(((size_t)row * DIN + col0 + bj * 128) * 2), 0, 16  ); }
	v_pk_fma_f32 v[252:253], v[246:247], v[250:251], 1.0 op_sel_hi:[1,1,0] neg_lo:[1,0,0] neg_hi:[1,0,0]
	v_pk_fma_f32 v[250:251], v[252:253], v[250:251], v[250:251]
	v_pk_fma_f32 v[252:253], v[246:247], v[250:251], 1.0 op_sel_hi:[1,1,0] neg_lo:[1,0,0] neg_hi:[1,0,0]
	v_pk_fma_f32 v[254:255], v[252:253], v[250:251], v[250:251]
	v_pk_fma_f32 v[252:253], v[246:247], v[254:255], 1.0 op_sel_hi:[1,1,0] neg_lo:[1,0,0] neg_hi:[1,0,0]
	v_pk_fma_f32 v[254:255], v[252:253], v[250:251], v[254:255]
	v_div_fixup_f32 v246, v254, v246, 1.0
	v_div_fixup_f32 v247, v255, v247, 1.0
	v_rcp_f32_e32 v250, v248
	v_rcp_f32_e32 v251, v249
	s_nop 0
	v_pk_fma_f32 v[252:253], v[248:249], v[250:251], 1.0 op_sel_hi:[1,1,0] neg_lo:[1,0,0] neg_hi:[1,0,0]
	v_pk_fma_f32 v[250:251], v[252:253], v[250:251], v[250:251]
	v_pk_fma_f32 v[252:253], v[248:249], v[250:251], 1.0 op_sel_hi:[1,1,0] neg_lo:[1,0,0] neg_hi:[1,0,0]
	v_pk_fma_f32 v[254:255], v[252:253], v[250:251], v[250:251]
	v_pk_fma_f32 v[252:253], v[248:249], v[254:255], 1.0 op_sel_hi:[1,1,0] neg_lo:[1,0,0] neg_hi:[1,0,0]
	v_pk_fma_f32 v[254:255], v[252:253], v[250:251], v[254:255]
	v_div_fixup_f32 v248, v254, v248, 1.0
	v_div_fixup_f32 v249, v255, v249, 1.0
	v_lshlrev_b32_e32 v150, 16, v124
	v_and_b32_e32 v151, 0xffff0000, v124
	v_lshlrev_b32_e32 v160, 16, v126
	v_and_b32_e32 v161, 0xffff0000, v126
	v_lshlrev_b32_e32 v126, 16, v127
	v_and_b32_e32 v127, 0xffff0000, v127
	v_lshlrev_b32_e32 v124, 16, v125
	v_and_b32_e32 v125, 0xffff0000, v125
	v_pk_fma_f32 v[116:117], v[116:117], v[242:243], v[150:151]
	v_pk_fma_f32 v[120:121], v[114:115], v[248:249], v[126:127]
	v_pk_fma_f32 v[114:115], v[112:113], v[244:245], v[160:161]
	v_cvt_pk_bf16_f32 v112, v116, v117
	v_pk_fma_f32 v[118:119], v[118:119], v[246:247], v[124:125]
	s_nop 0
	v_cvt_pk_bf16_f32 v113, v118, v119
	v_cvt_pk_bf16_f32 v114, v114, v115
	v_cvt_pk_bf16_f32 v115, v120, v121
	buffer_store_dwordx4 v[112:115], v141, s[20:23], 0 offen offset:256 sc1
	s_nop 1
	v_add_u32_e32 v112, 0x4010, v158
	v_mad_i64_i32 v[114:115], s[6:7], v112, s77, 0
	v_lshl_add_u64 v[112:113], v[114:115], 1, s[26:27]
	v_lshl_add_u64 v[112:113], v[112:113], 0, v[142:143]
	v_add_co_u32_e32 v116, vcc, s78, v112
	s_nop 1
	v_addc_co_u32_e32 v117, vcc, 0, v113, vcc
	s_waitcnt vmcnt(6)
	v_mov_b64_e32 v[118:119], v[232:233]
	v_mov_b64_e32 v[120:121], v[234:235]
	v_mov_b64_e32 v[122:123], v[236:237]
	v_mov_b64_e32 v[124:125], v[238:239]
	v_add_u32_e32 v199, 0x45300, v198
	global_load_dwordx4 v[232:235], v199, s[26:27]
	v_add_u32_e32 v199, 0x44100, v198
	global_load_dwordx4 v[236:239], v199, s[26:27]
	s_mov_b32 s100, 0xbfb8aa3b
	v_lshlrev_b32_e32 v242, 16, v118
	v_and_b32_e32 v243, 0xffff0000, v118
	v_lshlrev_b32_e32 v244, 16, v120
	v_and_b32_e32 v245, 0xffff0000, v120
	v_lshlrev_b32_e32 v246, 16, v119
	v_and_b32_e32 v247, 0xffff0000, v119
	v_lshlrev_b32_e32 v248, 16, v121
	v_and_b32_e32 v249, 0xffff0000, v121
	v_pk_mul_f32 v[242:243], v[242:243], s[100:101] op_sel_hi:[1,0]
	v_pk_mul_f32 v[244:245], v[244:245], s[100:101] op_sel_hi:[1,0]
	v_pk_mul_f32 v[246:247], v[246:247], s[100:101] op_sel_hi:[1,0]
	v_pk_mul_f32 v[248:249], v[248:249], s[100:101] op_sel_hi:[1,0]
	v_exp_f32_e32 v242, v242
	v_exp_f32_e32 v243, v243
	v_exp_f32_e32 v244, v244
	v_exp_f32_e32 v245, v245
	v_exp_f32_e32 v246, v246
	v_exp_f32_e32 v247, v247
	v_exp_f32_e32 v248, v248
	v_exp_f32_e32 v249, v249
	s_nop 0
	v_pk_add_f32 v[242:243], v[242:243], 1.0 op_sel_hi:[1,0]
	v_pk_add_f32 v[244:245], v[244:245], 1.0 op_sel_hi:[1,0]
	v_pk_add_f32 v[246:247], v[246:247], 1.0 op_sel_hi:[1,0]
	v_pk_add_f32 v[248:249], v[248:249], 1.0 op_sel_hi:[1,0]
	v_rcp_f32_e32 v250, v242
	v_rcp_f32_e32 v251, v243
	s_nop 0
	v_pk_fma_f32 v[252:253], v[242:243], v[250:251], 1.0 op_sel_hi:[1,1,0] neg_lo:[1,0,0] neg_hi:[1,0,0]
	v_pk_fma_f32 v[250:251], v[252:253], v[250:251], v[250:251]
	v_pk_fma_f32 v[252:253], v[242:243], v[250:251], 1.0 op_sel_hi:[1,1,0] neg_lo:[1,0,0] neg_hi:[1,0,0]
	v_pk_fma_f32 v[254:255], v[252:253], v[250:251], v[250:251]
	v_pk_fma_f32 v[252:253], v[242:243], v[254:255], 1.0 op_sel_hi:[1,1,0] neg_lo:[1,0,0] neg_hi:[1,0,0]
	v_pk_fma_f32 v[254:255], v[252:253], v[250:251], v[254:255]
	v_div_fixup_f32 v242, v254, v242, 1.0
	v_div_fixup_f32 v243, v255, v243, 1.0
	v_rcp_f32_e32 v250, v244
	v_rcp_f32_e32 v251, v245
	s_nop 0
	v_pk_fma_f32 v[252:253], v[244:245], v[250:251], 1.0 op_sel_hi:[1,1,0] neg_lo:[1,0,0] neg_hi:[1,0,0]
	v_pk_fma_f32 v[250:251], v[252:253], v[250:251], v[250:251]
	v_pk_fma_f32 v[252:253], v[244:245], v[250:251], 1.0 op_sel_hi:[1,1,0] neg_lo:[1,0,0] neg_hi:[1,0,0]
	v_pk_fma_f32 v[254:255], v[252:253], v[250:251], v[250:251]
	v_pk_fma_f32 v[252:253], v[244:245], v[254:255], 1.0 op_sel_hi:[1,1,0] neg_lo:[1,0,0] neg_hi:[1,0,0]
	v_pk_fma_f32 v[254:255], v[252:253], v[250:251], v[254:255]
	v_div_fixup_f32 v244, v254, v244, 1.0
	v_div_fixup_f32 v245, v255, v245, 1.0
	v_rcp_f32_e32 v250, v246
	v_rcp_f32_e32 v251, v247
	s_nop 0
	v_pk_fma_f32 v[252:253], v[246:247], v[250:251], 1.0 op_sel_hi:[1,1,0] neg_lo:[1,0,0] neg_hi:[1,0,0]
	v_pk_fma_f32 v[250:251], v[252:253], v[250:251], v[250:251]
	v_pk_fma_f32 v[252:253], v[246:247], v[250:251], 1.0 op_sel_hi:[1,1,0] neg_lo:[1,0,0] neg_hi:[1,0,0]
	v_pk_fma_f32 v[254:255], v[252:253], v[250:251], v[250:251]
	v_pk_fma_f32 v[252:253], v[246:247], v[254:255], 1.0 op_sel_hi:[1,1,0] neg_lo:[1,0,0] neg_hi:[1,0,0]
	v_pk_fma_f32 v[254:255], v[252:253], v[250:251], v[254:255]
	v_div_fixup_f32 v246, v254, v246, 1.0
	v_div_fixup_f32 v247, v255, v247, 1.0
	v_rcp_f32_e32 v250, v248
	v_rcp_f32_e32 v251, v249
	s_nop 0
	v_pk_fma_f32 v[252:253], v[248:249], v[250:251], 1.0 op_sel_hi:[1,1,0] neg_lo:[1,0,0] neg_hi:[1,0,0]
	v_pk_fma_f32 v[250:251], v[252:253], v[250:251], v[250:251]
	v_pk_fma_f32 v[252:253], v[248:249], v[250:251], 1.0 op_sel_hi:[1,1,0] neg_lo:[1,0,0] neg_hi:[1,0,0]
	v_pk_fma_f32 v[254:255], v[252:253], v[250:251], v[250:251]
	v_pk_fma_f32 v[252:253], v[248:249], v[254:255], 1.0 op_sel_hi:[1,1,0] neg_lo:[1,0,0] neg_hi:[1,0,0]
	v_pk_fma_f32 v[254:255], v[252:253], v[250:251], v[254:255]
	v_div_fixup_f32 v248, v254, v248, 1.0
	v_div_fixup_f32 v249, v255, v249, 1.0
	v_and_b32_e32 v151, 0xffff0000, v124
	v_lshlrev_b32_e32 v148, 16, v122
	v_and_b32_e32 v149, 0xffff0000, v122
	v_lshlrev_b32_e32 v150, 16, v124
	v_lshlrev_b32_e32 v124, 16, v125
	v_and_b32_e32 v125, 0xffff0000, v125
	v_lshlrev_b32_e32 v122, 16, v123
	v_and_b32_e32 v123, 0xffff0000, v123
	v_pk_fma_f32 v[108:109], v[108:109], v[242:243], v[148:149]
	v_pk_fma_f32 v[118:119], v[106:107], v[248:249], v[124:125]
	v_pk_fma_f32 v[106:107], v[104:105], v[244:245], v[150:151]
	v_add_lshl_u32 v120, v140, v114, 1
	v_pk_fma_f32 v[110:111], v[110:111], v[246:247], v[122:123]
	v_cvt_pk_bf16_f32 v104, v108, v109
	s_nop 0
	v_cvt_pk_bf16_f32 v105, v110, v111
	v_cvt_pk_bf16_f32 v106, v106, v107
	v_cvt_pk_bf16_f32 v107, v118, v119
	buffer_store_dwordx4 v[104:107], v120, s[20:23], 0 offen sc1
	s_nop 0
	s_waitcnt vmcnt(7)
; __device__ __forceinline__ float sigmoidf_(float x) { return 1.0f / (1.0f + __expf(-x)); }
; __device__ __forceinline__ u32x4 pack8(const f32x4 v0, const f32x4 v1) { u32x4 w; w.x = pk2(v0[0], v0[1]); w.y = pk2(v0[2], v0[3]); w.z = pk2(v1[0], v1[1]); w.w = pk2(v1[2], v1[3]); return w; }
; __device__ __forceinline__ void unpack8(const u32x4 w, f32x4& v0, f32x4& v1) { v0 = (f32x4){bflo(w.x), bfhi(w.x), bflo(w.y), bfhi(w.y)}; v1 = (f32x4){bflo(w.z), bfhi(w.z), bflo(w.w), bfhi(w.w)}; }
;     __device__ __forceinline__ void operator()(const f32x4 (&acc)[2][2][4][2], const Unit& u, int wr, int wc, int fr, int fq) const {
;     ...
;                 for (int bj = 0; bj < 2; ++bj) {
;                     const u32x4 gw = *(const u32x4*)(rowp + O_GA + bj * 128);
;                     f32x4 g0, g1; unpack8(gw, g0, g1);
;                     f32x4 v0, v1;
; #pragma unroll
;                     for (int j = 0; j < 4; ++j) { v0[j] = sigmoidf_(g0[j]) * acc[ai][bj][m][0][j]; v1[j] = sigmoidf_(g1[j]) * acc[ai][bj][m][1][j]; }
;                     const u32x4 mw = *(const u32x4*)(rowp + bj * 128); f32x4 m0, m1; unpack8(mw, m0, m1); v0 += m0; v1 += m1;
;                     __builtin_amdgcn_raw_buffer_store_b128(pack8(v0, v1), rsrc, (unsigned)(((size_t)row * DIN + col0 + bj * 128) * 2), 0, 16  ); }
	v_mov_b64_e32 v[104:105], v[200:201]
	v_mov_b64_e32 v[106:107], v[202:203]
	v_mov_b64_e32 v[108:109], v[204:205]
	v_mov_b64_e32 v[110:111], v[206:207]
	v_add_u32_e32 v199, 0x67200, v198
	global_load_dwordx4 v[200:203], v199, s[26:27]
	v_add_u32_e32 v199, 0x66000, v198
	global_load_dwordx4 v[204:207], v199, s[26:27]
	s_mov_b32 s100, 0xbfb8aa3b
	v_lshlrev_b32_e32 v242, 16, v106
	v_and_b32_e32 v243, 0xffff0000, v106
	v_lshlrev_b32_e32 v244, 16, v104
	v_and_b32_e32 v245, 0xffff0000, v104
	v_lshlrev_b32_e32 v246, 16, v105
	v_and_b32_e32 v247, 0xffff0000, v105
	v_lshlrev_b32_e32 v248, 16, v107
	v_and_b32_e32 v249, 0xffff0000, v107
	v_pk_mul_f32 v[242:243], v[242:243], s[100:101] op_sel_hi:[1,0]
	v_pk_mul_f32 v[244:245], v[244:245], s[100:101] op_sel_hi:[1,0]
	v_pk_mul_f32 v[246:247], v[246:247], s[100:101] op_sel_hi:[1,0]
	v_pk_mul_f32 v[248:249], v[248:249], s[100:101] op_sel_hi:[1,0]
	v_exp_f32_e32 v242, v242
	v_exp_f32_e32 v243, v243
	v_exp_f32_e32 v244, v244
	v_exp_f32_e32 v245, v245
	v_exp_f32_e32 v246, v246
	v_exp_f32_e32 v247, v247
	v_exp_f32_e32 v248, v248
	v_exp_f32_e32 v249, v249
	s_nop 0
	v_pk_add_f32 v[242:243], v[242:243], 1.0 op_sel_hi:[1,0]
	v_pk_add_f32 v[244:245], v[244:245], 1.0 op_sel_hi:[1,0]
	v_pk_add_f32 v[246:247], v[246:247], 1.0 op_sel_hi:[1,0]
	v_pk_add_f32 v[248:249], v[248:249], 1.0 op_sel_hi:[1,0]
	v_rcp_f32_e32 v250, v242
	v_rcp_f32_e32 v251, v243
	s_nop 0
	v_pk_fma_f32 v[252:253], v[242:243], v[250:251], 1.0 op_sel_hi:[1,1,0] neg_lo:[1,0,0] neg_hi:[1,0,0]
	v_pk_fma_f32 v[250:251], v[252:253], v[250:251], v[250:251]
	v_pk_fma_f32 v[252:253], v[242:243], v[250:251], 1.0 op_sel_hi:[1,1,0] neg_lo:[1,0,0] neg_hi:[1,0,0]
	v_pk_fma_f32 v[254:255], v[252:253], v[250:251], v[250:251]
	v_pk_fma_f32 v[252:253], v[242:243], v[254:255], 1.0 op_sel_hi:[1,1,0] neg_lo:[1,0,0] neg_hi:[1,0,0]
	v_pk_fma_f32 v[254:255], v[252:253], v[250:251], v[254:255]
	v_div_fixup_f32 v242, v254, v242, 1.0
	v_div_fixup_f32 v243, v255, v243, 1.0
	v_rcp_f32_e32 v250, v244
	v_rcp_f32_e32 v251, v245
	s_nop 0
	v_pk_fma_f32 v[252:253], v[244:245], v[250:251], 1.0 op_sel_hi:[1,1,0] neg_lo:[1,0,0] neg_hi:[1,0,0]
	v_pk_fma_f32 v[250:251], v[252:253], v[250:251], v[250:251]
	v_pk_fma_f32 v[252:253], v[244:245], v[250:251], 1.0 op_sel_hi:[1,1,0] neg_lo:[1,0,0] neg_hi:[1,0,0]
	v_pk_fma_f32 v[254:255], v[252:253], v[250:251], v[250:251]
	v_pk_fma_f32 v[252:253], v[244:245], v[254:255], 1.0 op_sel_hi:[1,1,0] neg_lo:[1,0,0] neg_hi:[1,0,0]
	v_pk_fma_f32 v[254:255], v[252:253], v[250:251], v[254:255]
	v_div_fixup_f32 v244, v254, v244, 1.0
	v_div_fixup_f32 v245, v255, v245, 1.0
	v_rcp_f32_e32 v250, v246
	v_rcp_f32_e32 v251, v247
	s_nop 0
	v_pk_fma_f32 v[252:253], v[246:247], v[250:251], 1.0 op_sel_hi:[1,1,0] neg_lo:[1,0,0] neg_hi:[1,0,0]
	v_pk_fma_f32 v[250:251], v[252:253], v[250:251], v[250:251]
	v_pk_fma_f32 v[252:253], v[246:247], v[250:251], 1.0 op_sel_hi:[1,1,0] neg_lo:[1,0,0] neg_hi:[1,0,0]
	v_pk_fma_f32 v[254:255], v[252:253], v[250:251], v[250:251]
	v_pk_fma_f32 v[252:253], v[246:247], v[254:255], 1.0 op_sel_hi:[1,1,0] neg_lo:[1,0,0] neg_hi:[1,0,0]
	v_pk_fma_f32 v[254:255], v[252:253], v[250:251], v[254:255]
	v_div_fixup_f32 v246, v254, v246, 1.0
	v_div_fixup_f32 v247, v255, v247, 1.0
	v_rcp_f32_e32 v250, v248
	v_rcp_f32_e32 v251, v249
	s_nop 0
	v_pk_fma_f32 v[252:253], v[248:249], v[250:251], 1.0 op_sel_hi:[1,1,0] neg_lo:[1,0,0] neg_hi:[1,0,0]
	v_pk_fma_f32 v[250:251], v[252:253], v[250:251], v[250:251]
	v_pk_fma_f32 v[252:253], v[248:249], v[250:251], 1.0 op_sel_hi:[1,1,0] neg_lo:[1,0,0] neg_hi:[1,0,0]
	v_pk_fma_f32 v[254:255], v[252:253], v[250:251], v[250:251]
	v_pk_fma_f32 v[252:253], v[248:249], v[254:255], 1.0 op_sel_hi:[1,1,0] neg_lo:[1,0,0] neg_hi:[1,0,0]
	v_pk_fma_f32 v[254:255], v[252:253], v[250:251], v[254:255]
	v_div_fixup_f32 v248, v254, v248, 1.0
	v_div_fixup_f32 v249, v255, v249, 1.0
	v_lshlrev_b32_e32 v116, 16, v108
	v_and_b32_e32 v117, 0xffff0000, v108
	v_lshlrev_b32_e32 v118, 16, v110
	v_and_b32_e32 v119, 0xffff0000, v110
	v_lshlrev_b32_e32 v110, 16, v111
	v_and_b32_e32 v111, 0xffff0000, v111
	v_lshlrev_b32_e32 v108, 16, v109
	v_and_b32_e32 v109, 0xffff0000, v109
	v_pk_fma_f32 v[100:101], v[100:101], v[244:245], v[116:117]
	v_pk_fma_f32 v[104:105], v[98:99], v[248:249], v[110:111]
	v_pk_fma_f32 v[98:99], v[96:97], v[242:243], v[118:119]
	v_cvt_pk_bf16_f32 v96, v100, v101
	v_pk_fma_f32 v[102:103], v[102:103], v[246:247], v[108:109]
	s_nop 0
	v_cvt_pk_bf16_f32 v97, v102, v103
	v_cvt_pk_bf16_f32 v98, v98, v99
	v_cvt_pk_bf16_f32 v99, v104, v105
	buffer_store_dwordx4 v[96:99], v120, s[20:23], 0 offen offset:256 sc1
	s_nop 1
	v_add_u32_e32 v96, 0x4020, v158
	v_mad_i64_i32 v[98:99], s[6:7], v96, s77, 0
	v_lshl_add_u64 v[96:97], v[98:99], 1, s[26:27]
	v_lshl_add_u64 v[96:97], v[96:97], 0, v[142:143]
	v_add_co_u32_e32 v100, vcc, s78, v96
	s_nop 1
	v_addc_co_u32_e32 v101, vcc, 0, v97, vcc
	s_waitcnt vmcnt(7)
; __device__ __forceinline__ float sigmoidf_(float x) { return 1.0f / (1.0f + __expf(-x)); }
; __device__ __forceinline__ u32x4 pack8(const f32x4 v0, const f32x4 v1) { u32x4 w; w.x = pk2(v0[0], v0[1]); w.y = pk2(v0[2], v0[3]); w.z = pk2(v1[0], v1[1]); w.w = pk2(v1[2], v1[3]); return w; }
; __device__ __forceinline__ void unpack8(const u32x4 w, f32x4& v0, f32x4& v1) { v0 = (f32x4){bflo(w.x), bfhi(w.x), bflo(w.y), bfhi(w.y)}; v1 = (f32x4){bflo(w.z), bfhi(w.z), bflo(w.w), bfhi(w.w)}; }
;     __device__ __forceinline__ void operator()(const f32x4 (&acc)[2][2][4][2], const Unit& u, int wr, int wc, int fr, int fq) const {
;     ...
;                 for (int bj = 0; bj < 2; ++bj) {
;                     const u32x4 gw = *(const u32x4*)(rowp + O_GA + bj * 128);
;                     f32x4 g0, g1; unpack8(gw, g0, g1);
;                     f32x4 v0, v1;
; #pragma unroll
;                     for (int j = 0; j < 4; ++j) { v0[j] = sigmoidf_(g0[j]) * acc[ai][bj][m][0][j]; v1[j] = sigmoidf_(g1[j]) * acc[ai][bj][m][1][j]; }
;                     const u32x4 mw = *(const u32x4*)(rowp + bj * 128); f32x4 m0, m1; unpack8(mw, m0, m1); v0 += m0; v1 += m1;
;                     __builtin_amdgcn_raw_buffer_store_b128(pack8(v0, v1), rsrc, (unsigned)(((size_t)row * DIN + col0 + bj * 128) * 2), 0, 16  ); }
	v_mov_b64_e32 v[102:103], v[208:209]
	v_mov_b64_e32 v[104:105], v[210:211]
	v_mov_b64_e32 v[106:107], v[212:213]
	v_mov_b64_e32 v[108:109], v[214:215]
	v_add_u32_e32 v199, 0x67300, v198
	global_load_dwordx4 v[208:211], v199, s[26:27]
	v_add_u32_e32 v199, 0x66100, v198
	global_load_dwordx4 v[212:215], v199, s[26:27]
	s_mov_b32 s100, 0xbfb8aa3b
	v_lshlrev_b32_e32 v242, 16, v102
	v_and_b32_e32 v243, 0xffff0000, v102
	v_lshlrev_b32_e32 v244, 16, v104
	v_and_b32_e32 v245, 0xffff0000, v104
	v_lshlrev_b32_e32 v246, 16, v103
	v_and_b32_e32 v247, 0xffff0000, v103
	v_lshlrev_b32_e32 v248, 16, v105
	v_and_b32_e32 v249, 0xffff0000, v105
	v_pk_mul_f32 v[242:243], v[242:243], s[100:101] op_sel_hi:[1,0]
	v_pk_mul_f32 v[244:245], v[244:245], s[100:101] op_sel_hi:[1,0]
	v_pk_mul_f32 v[246:247], v[246:247], s[100:101] op_sel_hi:[1,0]
	v_pk_mul_f32 v[248:249], v[248:249], s[100:101] op_sel_hi:[1,0]
	v_exp_f32_e32 v242, v242
	v_exp_f32_e32 v243, v243
	v_exp_f32_e32 v244, v244
	v_exp_f32_e32 v245, v245
	v_exp_f32_e32 v246, v246
	v_exp_f32_e32 v247, v247
	v_exp_f32_e32 v248, v248
	v_exp_f32_e32 v249, v249
	s_nop 0
	v_pk_add_f32 v[242:243], v[242:243], 1.0 op_sel_hi:[1,0]
	v_pk_add_f32 v[244:245], v[244:245], 1.0 op_sel_hi:[1,0]
	v_pk_add_f32 v[246:247], v[246:247], 1.0 op_sel_hi:[1,0]
	v_pk_add_f32 v[248:249], v[248:249], 1.0 op_sel_hi:[1,0]
	v_rcp_f32_e32 v250, v242
	v_rcp_f32_e32 v251, v243
	s_nop 0
	v_pk_fma_f32 v[252:253], v[242:243], v[250:251], 1.0 op_sel_hi:[1,1,0] neg_lo:[1,0,0] neg_hi:[1,0,0]
	v_pk_fma_f32 v[250:251], v[252:253], v[250:251], v[250:251]
	v_pk_fma_f32 v[252:253], v[242:243], v[250:251], 1.0 op_sel_hi:[1,1,0] neg_lo:[1,0,0] neg_hi:[1,0,0]
	v_pk_fma_f32 v[254:255], v[252:253], v[250:251], v[250:251]
	v_pk_fma_f32 v[252:253], v[242:243], v[254:255], 1.0 op_sel_hi:[1,1,0] neg_lo:[1,0,0] neg_hi:[1,0,0]
	v_pk_fma_f32 v[254:255], v[252:253], v[250:251], v[254:255]
	v_div_fixup_f32 v242, v254, v242, 1.0
	v_div_fixup_f32 v243, v255, v243, 1.0
	v_rcp_f32_e32 v250, v244
	v_rcp_f32_e32 v251, v245
	s_nop 0
	v_pk_fma_f32 v[252:253], v[244:245], v[250:251], 1.0 op_sel_hi:[1,1,0] neg_lo:[1,0,0] neg_hi:[1,0,0]
	v_pk_fma_f32 v[250:251], v[252:253], v[250:251], v[250:251]
	v_pk_fma_f32 v[252:253], v[244:245], v[250:251], 1.0 op_sel_hi:[1,1,0] neg_lo:[1,0,0] neg_hi:[1,0,0]
	v_pk_fma_f32 v[254:255], v[252:253], v[250:251], v[250:251]
	v_pk_fma_f32 v[252:253], v[244:245], v[254:255], 1.0 op_sel_hi:[1,1,0] neg_lo:[1,0,0] neg_hi:[1,0,0]
	v_pk_fma_f32 v[254:255], v[252:253], v[250:251], v[254:255]
	v_div_fixup_f32 v244, v254, v244, 1.0
	v_div_fixup_f32 v245, v255, v245, 1.0
	v_rcp_f32_e32 v250, v246
	v_rcp_f32_e32 v251, v247
	s_nop 0
	v_pk_fma_f32 v[252:253], v[246:247], v[250:251], 1.0 op_sel_hi:[1,1,0] neg_lo:[1,0,0] neg_hi:[1,0,0]
	v_pk_fma_f32 v[250:251], v[252:253], v[250:251], v[250:251]
	v_pk_fma_f32 v[252:253], v[246:247], v[250:251], 1.0 op_sel_hi:[1,1,0] neg_lo:[1,0,0] neg_hi:[1,0,0]
	v_pk_fma_f32 v[254:255], v[252:253], v[250:251], v[250:251]
	v_pk_fma_f32 v[252:253], v[246:247], v[254:255], 1.0 op_sel_hi:[1,1,0] neg_lo:[1,0,0] neg_hi:[1,0,0]
	v_pk_fma_f32 v[254:255], v[252:253], v[250:251], v[254:255]
	v_div_fixup_f32 v246, v254, v246, 1.0
	v_div_fixup_f32 v247, v255, v247, 1.0
	v_rcp_f32_e32 v250, v248
	v_rcp_f32_e32 v251, v249
	s_nop 0
	v_pk_fma_f32 v[252:253], v[248:249], v[250:251], 1.0 op_sel_hi:[1,1,0] neg_lo:[1,0,0] neg_hi:[1,0,0]
	v_pk_fma_f32 v[250:251], v[252:253], v[250:251], v[250:251]
	v_pk_fma_f32 v[252:253], v[248:249], v[250:251], 1.0 op_sel_hi:[1,1,0] neg_lo:[1,0,0] neg_hi:[1,0,0]
	v_pk_fma_f32 v[254:255], v[252:253], v[250:251], v[250:251]
	v_pk_fma_f32 v[252:253], v[248:249], v[254:255], 1.0 op_sel_hi:[1,1,0] neg_lo:[1,0,0] neg_hi:[1,0,0]
	v_pk_fma_f32 v[254:255], v[252:253], v[250:251], v[254:255]
	v_div_fixup_f32 v248, v254, v248, 1.0
	v_div_fixup_f32 v249, v255, v249, 1.0
	v_lshlrev_b32_e32 v114, 16, v106
	v_and_b32_e32 v115, 0xffff0000, v106
	v_lshlrev_b32_e32 v116, 16, v108
	v_and_b32_e32 v117, 0xffff0000, v108
	v_lshlrev_b32_e32 v108, 16, v109
	v_and_b32_e32 v109, 0xffff0000, v109
	v_lshlrev_b32_e32 v106, 16, v107
	v_and_b32_e32 v107, 0xffff0000, v107
	v_pk_fma_f32 v[92:93], v[92:93], v[242:243], v[114:115]
	v_pk_fma_f32 v[102:103], v[90:91], v[248:249], v[108:109]
	v_pk_fma_f32 v[90:91], v[88:89], v[244:245], v[116:117]
	v_add_lshl_u32 v104, v140, v98, 1
	v_pk_fma_f32 v[94:95], v[94:95], v[246:247], v[106:107]
	v_cvt_pk_bf16_f32 v88, v92, v93
	s_nop 0
	v_cvt_pk_bf16_f32 v89, v94, v95
	v_cvt_pk_bf16_f32 v90, v90, v91
	v_cvt_pk_bf16_f32 v91, v102, v103
	buffer_store_dwordx4 v[88:91], v104, s[20:23], 0 offen sc1
	s_nop 0
	s_waitcnt vmcnt(7)
; __device__ __forceinline__ float sigmoidf_(float x) { return 1.0f / (1.0f + __expf(-x)); }
; __device__ __forceinline__ u32x4 pack8(const f32x4 v0, const f32x4 v1) { u32x4 w; w.x = pk2(v0[0], v0[1]); w.y = pk2(v0[2], v0[3]); w.z = pk2(v1[0], v1[1]); w.w = pk2(v1[2], v1[3]); return w; }
; __device__ __forceinline__ void unpack8(const u32x4 w, f32x4& v0, f32x4& v1) { v0 = (f32x4){bflo(w.x), bfhi(w.x), bflo(w.y), bfhi(w.y)}; v1 = (f32x4){bflo(w.z), bfhi(w.z), bflo(w.w), bfhi(w.w)}; }
;     __device__ __forceinline__ void operator()(const f32x4 (&acc)[2][2][4][2], const Unit& u, int wr, int wc, int fr, int fq) const {
;     ...
;                 for (int bj = 0; bj < 2; ++bj) {
;                     const u32x4 gw = *(const u32x4*)(rowp + O_GA + bj * 128);
;                     f32x4 g0, g1; unpack8(gw, g0, g1);
;                     f32x4 v0, v1;
; #pragma unroll
;                     for (int j = 0; j < 4; ++j) { v0[j] = sigmoidf_(g0[j]) * acc[ai][bj][m][0][j]; v1[j] = sigmoidf_(g1[j]) * acc[ai][bj][m][1][j]; }
;                     const u32x4 mw = *(const u32x4*)(rowp + bj * 128); f32x4 m0, m1; unpack8(mw, m0, m1); v0 += m0; v1 += m1;
;                     __builtin_amdgcn_raw_buffer_store_b128(pack8(v0, v1), rsrc, (unsigned)(((size_t)row * DIN + col0 + bj * 128) * 2), 0, 16  ); }
	v_mov_b64_e32 v[88:89], v[232:233]
	v_mov_b64_e32 v[90:91], v[234:235]
	v_mov_b64_e32 v[92:93], v[236:237]
	v_mov_b64_e32 v[94:95], v[238:239]
	v_add_u32_e32 v199, 0x111200, v198
	global_load_dwordx4 v[232:235], v199, s[26:27]
	v_add_u32_e32 v199, 0x110000, v198
	global_load_dwordx4 v[236:239], v199, s[26:27]
	s_mov_b32 s100, 0xbfb8aa3b
	v_lshlrev_b32_e32 v242, 16, v90
	v_and_b32_e32 v243, 0xffff0000, v90
	v_lshlrev_b32_e32 v244, 16, v88
	v_and_b32_e32 v245, 0xffff0000, v88
	v_lshlrev_b32_e32 v246, 16, v89
	v_and_b32_e32 v247, 0xffff0000, v89
	v_lshlrev_b32_e32 v248, 16, v91
	v_and_b32_e32 v249, 0xffff0000, v91
	v_pk_mul_f32 v[242:243], v[242:243], s[100:101] op_sel_hi:[1,0]
	v_pk_mul_f32 v[244:245], v[244:245], s[100:101] op_sel_hi:[1,0]
	v_pk_mul_f32 v[246:247], v[246:247], s[100:101] op_sel_hi:[1,0]
	v_pk_mul_f32 v[248:249], v[248:249], s[100:101] op_sel_hi:[1,0]
	v_exp_f32_e32 v242, v242
	v_exp_f32_e32 v243, v243
	v_exp_f32_e32 v244, v244
	v_exp_f32_e32 v245, v245
	v_exp_f32_e32 v246, v246
	v_exp_f32_e32 v247, v247
	v_exp_f32_e32 v248, v248
	v_exp_f32_e32 v249, v249
	s_nop 0
	v_pk_add_f32 v[242:243], v[242:243], 1.0 op_sel_hi:[1,0]
	v_pk_add_f32 v[244:245], v[244:245], 1.0 op_sel_hi:[1,0]
	v_pk_add_f32 v[246:247], v[246:247], 1.0 op_sel_hi:[1,0]
	v_pk_add_f32 v[248:249], v[248:249], 1.0 op_sel_hi:[1,0]
	v_rcp_f32_e32 v250, v242
	v_rcp_f32_e32 v251, v243
	s_nop 0
	v_pk_fma_f32 v[252:253], v[242:243], v[250:251], 1.0 op_sel_hi:[1,1,0] neg_lo:[1,0,0] neg_hi:[1,0,0]
	v_pk_fma_f32 v[250:251], v[252:253], v[250:251], v[250:251]
	v_pk_fma_f32 v[252:253], v[242:243], v[250:251], 1.0 op_sel_hi:[1,1,0] neg_lo:[1,0,0] neg_hi:[1,0,0]
	v_pk_fma_f32 v[254:255], v[252:253], v[250:251], v[250:251]
	v_pk_fma_f32 v[252:253], v[242:243], v[254:255], 1.0 op_sel_hi:[1,1,0] neg_lo:[1,0,0] neg_hi:[1,0,0]
	v_pk_fma_f32 v[254:255], v[252:253], v[250:251], v[254:255]
	v_div_fixup_f32 v242, v254, v242, 1.0
	v_div_fixup_f32 v243, v255, v243, 1.0
	v_rcp_f32_e32 v250, v244
	v_rcp_f32_e32 v251, v245
	s_nop 0
	v_pk_fma_f32 v[252:253], v[244:245], v[250:251], 1.0 op_sel_hi:[1,1,0] neg_lo:[1,0,0] neg_hi:[1,0,0]
	v_pk_fma_f32 v[250:251], v[252:253], v[250:251], v[250:251]
	v_pk_fma_f32 v[252:253], v[244:245], v[250:251], 1.0 op_sel_hi:[1,1,0] neg_lo:[1,0,0] neg_hi:[1,0,0]
	v_pk_fma_f32 v[254:255], v[252:253], v[250:251], v[250:251]
	v_pk_fma_f32 v[252:253], v[244:245], v[254:255], 1.0 op_sel_hi:[1,1,0] neg_lo:[1,0,0] neg_hi:[1,0,0]
	v_pk_fma_f32 v[254:255], v[252:253], v[250:251], v[254:255]
	v_div_fixup_f32 v244, v254, v244, 1.0
	v_div_fixup_f32 v245, v255, v245, 1.0
	v_rcp_f32_e32 v250, v246
	v_rcp_f32_e32 v251, v247
	s_nop 0
	v_pk_fma_f32 v[252:253], v[246:247], v[250:251], 1.0 op_sel_hi:[1,1,0] neg_lo:[1,0,0] neg_hi:[1,0,0]
	v_pk_fma_f32 v[250:251], v[252:253], v[250:251], v[250:251]
	v_pk_fma_f32 v[252:253], v[246:247], v[250:251], 1.0 op_sel_hi:[1,1,0] neg_lo:[1,0,0] neg_hi:[1,0,0]
	v_pk_fma_f32 v[254:255], v[252:253], v[250:251], v[250:251]
	v_pk_fma_f32 v[252:253], v[246:247], v[254:255], 1.0 op_sel_hi:[1,1,0] neg_lo:[1,0,0] neg_hi:[1,0,0]
	v_pk_fma_f32 v[254:255], v[252:253], v[250:251], v[254:255]
	v_div_fixup_f32 v246, v254, v246, 1.0
	v_div_fixup_f32 v247, v255, v247, 1.0
	v_rcp_f32_e32 v250, v248
	v_rcp_f32_e32 v251, v249
	s_nop 0
	v_pk_fma_f32 v[252:253], v[248:249], v[250:251], 1.0 op_sel_hi:[1,1,0] neg_lo:[1,0,0] neg_hi:[1,0,0]
	v_pk_fma_f32 v[250:251], v[252:253], v[250:251], v[250:251]
	v_pk_fma_f32 v[252:253], v[248:249], v[250:251], 1.0 op_sel_hi:[1,1,0] neg_lo:[1,0,0] neg_hi:[1,0,0]
	v_pk_fma_f32 v[254:255], v[252:253], v[250:251], v[250:251]
	v_pk_fma_f32 v[252:253], v[248:249], v[254:255], 1.0 op_sel_hi:[1,1,0] neg_lo:[1,0,0] neg_hi:[1,0,0]
	v_pk_fma_f32 v[254:255], v[252:253], v[250:251], v[254:255]
	v_div_fixup_f32 v248, v254, v248, 1.0
	v_div_fixup_f32 v249, v255, v249, 1.0
	v_lshlrev_b32_e32 v100, 16, v92
	v_and_b32_e32 v101, 0xffff0000, v92
	v_lshlrev_b32_e32 v102, 16, v94
	v_and_b32_e32 v103, 0xffff0000, v94
	v_lshlrev_b32_e32 v94, 16, v95
	v_and_b32_e32 v95, 0xffff0000, v95
	v_lshlrev_b32_e32 v92, 16, v93
	v_and_b32_e32 v93, 0xffff0000, v93
	v_pk_fma_f32 v[84:85], v[84:85], v[244:245], v[100:101]
	v_pk_fma_f32 v[88:89], v[82:83], v[248:249], v[94:95]
	v_pk_fma_f32 v[82:83], v[80:81], v[242:243], v[102:103]
	v_cvt_pk_bf16_f32 v80, v84, v85
	v_pk_fma_f32 v[86:87], v[86:87], v[246:247], v[92:93]
	s_nop 0
	v_cvt_pk_bf16_f32 v81, v86, v87
	v_cvt_pk_bf16_f32 v82, v82, v83
	v_cvt_pk_bf16_f32 v83, v88, v89
	buffer_store_dwordx4 v[80:83], v104, s[20:23], 0 offen offset:256 sc1
	s_nop 1
	v_add_u32_e32 v80, 0x4030, v158
	v_mad_i64_i32 v[82:83], s[6:7], v80, s77, 0
	v_lshl_add_u64 v[80:81], v[82:83], 1, s[26:27]
	v_lshl_add_u64 v[80:81], v[80:81], 0, v[142:143]
	v_add_co_u32_e32 v84, vcc, s78, v80
	s_nop 1
	v_addc_co_u32_e32 v85, vcc, 0, v81, vcc
	s_waitcnt vmcnt(7)
; __device__ __forceinline__ float sigmoidf_(float x) { return 1.0f / (1.0f + __expf(-x)); }
; __device__ __forceinline__ u32x4 pack8(const f32x4 v0, const f32x4 v1) { u32x4 w; w.x = pk2(v0[0], v0[1]); w.y = pk2(v0[2], v0[3]); w.z = pk2(v1[0], v1[1]); w.w = pk2(v1[2], v1[3]); return w; }
; __device__ __forceinline__ void unpack8(const u32x4 w, f32x4& v0, f32x4& v1) { v0 = (f32x4){bflo(w.x), bfhi(w.x), bflo(w.y), bfhi(w.y)}; v1 = (f32x4){bflo(w.z), bfhi(w.z), bflo(w.w), bfhi(w.w)}; }
;     __device__ __forceinline__ void operator()(const f32x4 (&acc)[2][2][4][2], const Unit& u, int wr, int wc, int fr, int fq) const {
;     ...
;                 for (int bj = 0; bj < 2; ++bj) {
;                     const u32x4 gw = *(const u32x4*)(rowp + O_GA + bj * 128);
;                     f32x4 g0, g1; unpack8(gw, g0, g1);
;                     f32x4 v0, v1;
; #pragma unroll
;                     for (int j = 0; j < 4; ++j) { v0[j] = sigmoidf_(g0[j]) * acc[ai][bj][m][0][j]; v1[j] = sigmoidf_(g1[j]) * acc[ai][bj][m][1][j]; }
;                     const u32x4 mw = *(const u32x4*)(rowp + bj * 128); f32x4 m0, m1; unpack8(mw, m0, m1); v0 += m0; v1 += m1;
;                     __builtin_amdgcn_raw_buffer_store_b128(pack8(v0, v1), rsrc, (unsigned)(((size_t)row * DIN + col0 + bj * 128) * 2), 0, 16  ); }
	v_mov_b64_e32 v[86:87], v[200:201]
	v_mov_b64_e32 v[88:89], v[202:203]
	v_mov_b64_e32 v[90:91], v[204:205]
	v_mov_b64_e32 v[92:93], v[206:207]
	v_add_u32_e32 v199, 0x111300, v198
	global_load_dwordx4 v[200:203], v199, s[26:27]
	v_add_u32_e32 v199, 0x110100, v198
	global_load_dwordx4 v[204:207], v199, s[26:27]
	s_mov_b32 s100, 0xbfb8aa3b
	v_lshlrev_b32_e32 v242, 16, v86
	v_and_b32_e32 v243, 0xffff0000, v86
	v_lshlrev_b32_e32 v244, 16, v88
	v_and_b32_e32 v245, 0xffff0000, v88
	v_lshlrev_b32_e32 v246, 16, v87
	v_and_b32_e32 v247, 0xffff0000, v87
	v_lshlrev_b32_e32 v248, 16, v89
	v_and_b32_e32 v249, 0xffff0000, v89
	v_pk_mul_f32 v[242:243], v[242:243], s[100:101] op_sel_hi:[1,0]
	v_pk_mul_f32 v[244:245], v[244:245], s[100:101] op_sel_hi:[1,0]
	v_pk_mul_f32 v[246:247], v[246:247], s[100:101] op_sel_hi:[1,0]
	v_pk_mul_f32 v[248:249], v[248:249], s[100:101] op_sel_hi:[1,0]
	v_exp_f32_e32 v242, v242
	v_exp_f32_e32 v243, v243
	v_exp_f32_e32 v244, v244
	v_exp_f32_e32 v245, v245
	v_exp_f32_e32 v246, v246
	v_exp_f32_e32 v247, v247
	v_exp_f32_e32 v248, v248
	v_exp_f32_e32 v249, v249
	s_nop 0
	v_pk_add_f32 v[242:243], v[242:243], 1.0 op_sel_hi:[1,0]
	v_pk_add_f32 v[244:245], v[244:245], 1.0 op_sel_hi:[1,0]
	v_pk_add_f32 v[246:247], v[246:247], 1.0 op_sel_hi:[1,0]
	v_pk_add_f32 v[248:249], v[248:249], 1.0 op_sel_hi:[1,0]
	v_rcp_f32_e32 v250, v242
	v_rcp_f32_e32 v251, v243
	s_nop 0
	v_pk_fma_f32 v[252:253], v[242:243], v[250:251], 1.0 op_sel_hi:[1,1,0] neg_lo:[1,0,0] neg_hi:[1,0,0]
	v_pk_fma_f32 v[250:251], v[252:253], v[250:251], v[250:251]
	v_pk_fma_f32 v[252:253], v[242:243], v[250:251], 1.0 op_sel_hi:[1,1,0] neg_lo:[1,0,0] neg_hi:[1,0,0]
	v_pk_fma_f32 v[254:255], v[252:253], v[250:251], v[250:251]
	v_pk_fma_f32 v[252:253], v[242:243], v[254:255], 1.0 op_sel_hi:[1,1,0] neg_lo:[1,0,0] neg_hi:[1,0,0]
	v_pk_fma_f32 v[254:255], v[252:253], v[250:251], v[254:255]
	v_div_fixup_f32 v242, v254, v242, 1.0
	v_div_fixup_f32 v243, v255, v243, 1.0
	v_rcp_f32_e32 v250, v244
	v_rcp_f32_e32 v251, v245
	s_nop 0
	v_pk_fma_f32 v[252:253], v[244:245], v[250:251], 1.0 op_sel_hi:[1,1,0] neg_lo:[1,0,0] neg_hi:[1,0,0]
	v_pk_fma_f32 v[250:251], v[252:253], v[250:251], v[250:251]
	v_pk_fma_f32 v[252:253], v[244:245], v[250:251], 1.0 op_sel_hi:[1,1,0] neg_lo:[1,0,0] neg_hi:[1,0,0]
	v_pk_fma_f32 v[254:255], v[252:253], v[250:251], v[250:251]
	v_pk_fma_f32 v[252:253], v[244:245], v[254:255], 1.0 op_sel_hi:[1,1,0] neg_lo:[1,0,0] neg_hi:[1,0,0]
	v_pk_fma_f32 v[254:255], v[252:253], v[250:251], v[254:255]
	v_div_fixup_f32 v244, v254, v244, 1.0
	v_div_fixup_f32 v245, v255, v245, 1.0
	v_rcp_f32_e32 v250, v246
	v_rcp_f32_e32 v251, v247
	s_nop 0
	v_pk_fma_f32 v[252:253], v[246:247], v[250:251], 1.0 op_sel_hi:[1,1,0] neg_lo:[1,0,0] neg_hi:[1,0,0]
	v_pk_fma_f32 v[250:251], v[252:253], v[250:251], v[250:251]
	v_pk_fma_f32 v[252:253], v[246:247], v[250:251], 1.0 op_sel_hi:[1,1,0] neg_lo:[1,0,0] neg_hi:[1,0,0]
	v_pk_fma_f32 v[254:255], v[252:253], v[250:251], v[250:251]
	v_pk_fma_f32 v[252:253], v[246:247], v[254:255], 1.0 op_sel_hi:[1,1,0] neg_lo:[1,0,0] neg_hi:[1,0,0]
	v_pk_fma_f32 v[254:255], v[252:253], v[250:251], v[254:255]
	v_div_fixup_f32 v246, v254, v246, 1.0
	v_div_fixup_f32 v247, v255, v247, 1.0
	v_rcp_f32_e32 v250, v248
	v_rcp_f32_e32 v251, v249
	s_nop 0
	v_pk_fma_f32 v[252:253], v[248:249], v[250:251], 1.0 op_sel_hi:[1,1,0] neg_lo:[1,0,0] neg_hi:[1,0,0]
	v_pk_fma_f32 v[250:251], v[252:253], v[250:251], v[250:251]
	v_pk_fma_f32 v[252:253], v[248:249], v[250:251], 1.0 op_sel_hi:[1,1,0] neg_lo:[1,0,0] neg_hi:[1,0,0]
	v_pk_fma_f32 v[254:255], v[252:253], v[250:251], v[250:251]
	v_pk_fma_f32 v[252:253], v[248:249], v[254:255], 1.0 op_sel_hi:[1,1,0] neg_lo:[1,0,0] neg_hi:[1,0,0]
	v_pk_fma_f32 v[254:255], v[252:253], v[250:251], v[254:255]
	v_div_fixup_f32 v248, v254, v248, 1.0
	v_div_fixup_f32 v249, v255, v249, 1.0
	v_lshlrev_b32_e32 v98, 16, v90
	v_and_b32_e32 v99, 0xffff0000, v90
	v_lshlrev_b32_e32 v100, 16, v92
	v_and_b32_e32 v101, 0xffff0000, v92
	v_lshlrev_b32_e32 v92, 16, v93
	v_and_b32_e32 v93, 0xffff0000, v93
	v_lshlrev_b32_e32 v90, 16, v91
	v_and_b32_e32 v91, 0xffff0000, v91
	v_pk_fma_f32 v[76:77], v[76:77], v[242:243], v[98:99]
	v_pk_fma_f32 v[86:87], v[74:75], v[248:249], v[92:93]
	v_pk_fma_f32 v[74:75], v[72:73], v[244:245], v[100:101]
	v_add_lshl_u32 v88, v140, v82, 1
	v_pk_fma_f32 v[78:79], v[78:79], v[246:247], v[90:91]
	v_cvt_pk_bf16_f32 v72, v76, v77
	s_nop 0
	v_cvt_pk_bf16_f32 v73, v78, v79
	v_cvt_pk_bf16_f32 v74, v74, v75
	v_cvt_pk_bf16_f32 v75, v86, v87
	buffer_store_dwordx4 v[72:75], v88, s[20:23], 0 offen sc1
	s_nop 0
	s_waitcnt vmcnt(7)
; __device__ __forceinline__ float sigmoidf_(float x) { return 1.0f / (1.0f + __expf(-x)); }
; __device__ __forceinline__ u32x4 pack8(const f32x4 v0, const f32x4 v1) { u32x4 w; w.x = pk2(v0[0], v0[1]); w.y = pk2(v0[2], v0[3]); w.z = pk2(v1[0], v1[1]); w.w = pk2(v1[2], v1[3]); return w; }
; __device__ __forceinline__ void unpack8(const u32x4 w, f32x4& v0, f32x4& v1) { v0 = (f32x4){bflo(w.x), bfhi(w.x), bflo(w.y), bfhi(w.y)}; v1 = (f32x4){bflo(w.z), bfhi(w.z), bflo(w.w), bfhi(w.w)}; }
;     __device__ __forceinline__ void operator()(const f32x4 (&acc)[2][2][4][2], const Unit& u, int wr, int wc, int fr, int fq) const {
;     ...
;                 for (int bj = 0; bj < 2; ++bj) {
;                     const u32x4 gw = *(const u32x4*)(rowp + O_GA + bj * 128);
;                     f32x4 g0, g1; unpack8(gw, g0, g1);
;                     f32x4 v0, v1;
; #pragma unroll
;                     for (int j = 0; j < 4; ++j) { v0[j] = sigmoidf_(g0[j]) * acc[ai][bj][m][0][j]; v1[j] = sigmoidf_(g1[j]) * acc[ai][bj][m][1][j]; }
;                     const u32x4 mw = *(const u32x4*)(rowp + bj * 128); f32x4 m0, m1; unpack8(mw, m0, m1); v0 += m0; v1 += m1;
;                     __builtin_amdgcn_raw_buffer_store_b128(pack8(v0, v1), rsrc, (unsigned)(((size_t)row * DIN + col0 + bj * 128) * 2), 0, 16  ); }
	v_mov_b64_e32 v[72:73], v[208:209]
	v_mov_b64_e32 v[74:75], v[210:211]
	v_mov_b64_e32 v[76:77], v[212:213]
	v_mov_b64_e32 v[78:79], v[214:215]
	v_add_u32_e32 v199, 0x133200, v198
	global_load_dwordx4 v[208:211], v199, s[26:27]
	v_add_u32_e32 v199, 0x132000, v198
	global_load_dwordx4 v[212:215], v199, s[26:27]
	s_mov_b32 s100, 0xbfb8aa3b
	v_lshlrev_b32_e32 v242, 16, v74
	v_and_b32_e32 v243, 0xffff0000, v74
	v_lshlrev_b32_e32 v244, 16, v72
	v_and_b32_e32 v245, 0xffff0000, v72
	v_lshlrev_b32_e32 v246, 16, v73
	v_and_b32_e32 v247, 0xffff0000, v73
	v_lshlrev_b32_e32 v248, 16, v75
	v_and_b32_e32 v249, 0xffff0000, v75
	v_pk_mul_f32 v[242:243], v[242:243], s[100:101] op_sel_hi:[1,0]
	v_pk_mul_f32 v[244:245], v[244:245], s[100:101] op_sel_hi:[1,0]
	v_pk_mul_f32 v[246:247], v[246:247], s[100:101] op_sel_hi:[1,0]
	v_pk_mul_f32 v[248:249], v[248:249], s[100:101] op_sel_hi:[1,0]
	v_exp_f32_e32 v242, v242
	v_exp_f32_e32 v243, v243
	v_exp_f32_e32 v244, v244
	v_exp_f32_e32 v245, v245
	v_exp_f32_e32 v246, v246
	v_exp_f32_e32 v247, v247
	v_exp_f32_e32 v248, v248
	v_exp_f32_e32 v249, v249
	s_nop 0
	v_pk_add_f32 v[242:243], v[242:243], 1.0 op_sel_hi:[1,0]
	v_pk_add_f32 v[244:245], v[244:245], 1.0 op_sel_hi:[1,0]
	v_pk_add_f32 v[246:247], v[246:247], 1.0 op_sel_hi:[1,0]
	v_pk_add_f32 v[248:249], v[248:249], 1.0 op_sel_hi:[1,0]
	v_rcp_f32_e32 v250, v242
	v_rcp_f32_e32 v251, v243
	s_nop 0
	v_pk_fma_f32 v[252:253], v[242:243], v[250:251], 1.0 op_sel_hi:[1,1,0] neg_lo:[1,0,0] neg_hi:[1,0,0]
	v_pk_fma_f32 v[250:251], v[252:253], v[250:251], v[250:251]
	v_pk_fma_f32 v[252:253], v[242:243], v[250:251], 1.0 op_sel_hi:[1,1,0] neg_lo:[1,0,0] neg_hi:[1,0,0]
	v_pk_fma_f32 v[254:255], v[252:253], v[250:251], v[250:251]
	v_pk_fma_f32 v[252:253], v[242:243], v[254:255], 1.0 op_sel_hi:[1,1,0] neg_lo:[1,0,0] neg_hi:[1,0,0]
	v_pk_fma_f32 v[254:255], v[252:253], v[250:251], v[254:255]
	v_div_fixup_f32 v242, v254, v242, 1.0
	v_div_fixup_f32 v243, v255, v243, 1.0
	v_rcp_f32_e32 v250, v244
	v_rcp_f32_e32 v251, v245
	s_nop 0
	v_pk_fma_f32 v[252:253], v[244:245], v[250:251], 1.0 op_sel_hi:[1,1,0] neg_lo:[1,0,0] neg_hi:[1,0,0]
	v_pk_fma_f32 v[250:251], v[252:253], v[250:251], v[250:251]
	v_pk_fma_f32 v[252:253], v[244:245], v[250:251], 1.0 op_sel_hi:[1,1,0] neg_lo:[1,0,0] neg_hi:[1,0,0]
	v_pk_fma_f32 v[254:255], v[252:253], v[250:251], v[250:251]
	v_pk_fma_f32 v[252:253], v[244:245], v[254:255], 1.0 op_sel_hi:[1,1,0] neg_lo:[1,0,0] neg_hi:[1,0,0]
	v_pk_fma_f32 v[254:255], v[252:253], v[250:251], v[254:255]
	v_div_fixup_f32 v244, v254, v244, 1.0
	v_div_fixup_f32 v245, v255, v245, 1.0
	v_rcp_f32_e32 v250, v246
	v_rcp_f32_e32 v251, v247
	s_nop 0
	v_pk_fma_f32 v[252:253], v[246:247], v[250:251], 1.0 op_sel_hi:[1,1,0] neg_lo:[1,0,0] neg_hi:[1,0,0]
	v_pk_fma_f32 v[250:251], v[252:253], v[250:251], v[250:251]
	v_pk_fma_f32 v[252:253], v[246:247], v[250:251], 1.0 op_sel_hi:[1,1,0] neg_lo:[1,0,0] neg_hi:[1,0,0]
	v_pk_fma_f32 v[254:255], v[252:253], v[250:251], v[250:251]
	v_pk_fma_f32 v[252:253], v[246:247], v[254:255], 1.0 op_sel_hi:[1,1,0] neg_lo:[1,0,0] neg_hi:[1,0,0]
	v_pk_fma_f32 v[254:255], v[252:253], v[250:251], v[254:255]
	v_div_fixup_f32 v246, v254, v246, 1.0
	v_div_fixup_f32 v247, v255, v247, 1.0
	v_rcp_f32_e32 v250, v248
	v_rcp_f32_e32 v251, v249
	s_nop 0
	v_pk_fma_f32 v[252:253], v[248:249], v[250:251], 1.0 op_sel_hi:[1,1,0] neg_lo:[1,0,0] neg_hi:[1,0,0]
	v_pk_fma_f32 v[250:251], v[252:253], v[250:251], v[250:251]
	v_pk_fma_f32 v[252:253], v[248:249], v[250:251], 1.0 op_sel_hi:[1,1,0] neg_lo:[1,0,0] neg_hi:[1,0,0]
	v_pk_fma_f32 v[254:255], v[252:253], v[250:251], v[250:251]
	v_pk_fma_f32 v[252:253], v[248:249], v[254:255], 1.0 op_sel_hi:[1,1,0] neg_lo:[1,0,0] neg_hi:[1,0,0]
	v_pk_fma_f32 v[254:255], v[252:253], v[250:251], v[254:255]
	v_div_fixup_f32 v248, v254, v248, 1.0
	v_div_fixup_f32 v249, v255, v249, 1.0
	v_lshlrev_b32_e32 v84, 16, v76
	v_and_b32_e32 v85, 0xffff0000, v76
	v_lshlrev_b32_e32 v86, 16, v78
	v_and_b32_e32 v87, 0xffff0000, v78
	v_lshlrev_b32_e32 v78, 16, v79
	v_and_b32_e32 v79, 0xffff0000, v79
	v_lshlrev_b32_e32 v76, 16, v77
	v_and_b32_e32 v77, 0xffff0000, v77
	v_pk_fma_f32 v[68:69], v[68:69], v[244:245], v[84:85]
	v_pk_fma_f32 v[72:73], v[66:67], v[248:249], v[78:79]
	v_pk_fma_f32 v[66:67], v[64:65], v[242:243], v[86:87]
	v_cvt_pk_bf16_f32 v64, v68, v69
	v_pk_fma_f32 v[70:71], v[70:71], v[246:247], v[76:77]
	s_nop 0
	v_cvt_pk_bf16_f32 v65, v70, v71
	v_cvt_pk_bf16_f32 v66, v66, v67
	v_cvt_pk_bf16_f32 v67, v72, v73
	buffer_store_dwordx4 v[64:67], v88, s[20:23], 0 offen offset:256 sc1
	s_nop 1
	v_add_u32_e32 v64, 0x4080, v158
	v_mad_i64_i32 v[66:67], s[6:7], v64, s77, 0
	v_lshl_add_u64 v[64:65], v[66:67], 1, s[26:27]
	v_lshl_add_u64 v[64:65], v[64:65], 0, v[142:143]
	v_add_co_u32_e32 v68, vcc, s78, v64
	s_nop 1
	v_addc_co_u32_e32 v69, vcc, 0, v65, vcc
	s_waitcnt vmcnt(7)
; __device__ __forceinline__ float sigmoidf_(float x) { return 1.0f / (1.0f + __expf(-x)); }
; __device__ __forceinline__ u32x4 pack8(const f32x4 v0, const f32x4 v1) { u32x4 w; w.x = pk2(v0[0], v0[1]); w.y = pk2(v0[2], v0[3]); w.z = pk2(v1[0], v1[1]); w.w = pk2(v1[2], v1[3]); return w; }
; __device__ __forceinline__ void unpack8(const u32x4 w, f32x4& v0, f32x4& v1) { v0 = (f32x4){bflo(w.x), bfhi(w.x), bflo(w.y), bfhi(w.y)}; v1 = (f32x4){bflo(w.z), bfhi(w.z), bflo(w.w), bfhi(w.w)}; }
;     __device__ __forceinline__ void operator()(const f32x4 (&acc)[2][2][4][2], const Unit& u, int wr, int wc, int fr, int fq) const {
;     ...
;                 for (int bj = 0; bj < 2; ++bj) {
;                     const u32x4 gw = *(const u32x4*)(rowp + O_GA + bj * 128);
;                     f32x4 g0, g1; unpack8(gw, g0, g1);
;                     f32x4 v0, v1;
; #pragma unroll
;                     for (int j = 0; j < 4; ++j) { v0[j] = sigmoidf_(g0[j]) * acc[ai][bj][m][0][j]; v1[j] = sigmoidf_(g1[j]) * acc[ai][bj][m][1][j]; }
;                     const u32x4 mw = *(const u32x4*)(rowp + bj * 128); f32x4 m0, m1; unpack8(mw, m0, m1); v0 += m0; v1 += m1;
;                     __builtin_amdgcn_raw_buffer_store_b128(pack8(v0, v1), rsrc, (unsigned)(((size_t)row * DIN + col0 + bj * 128) * 2), 0, 16  ); }
	v_mov_b64_e32 v[70:71], v[232:233]
	v_mov_b64_e32 v[72:73], v[234:235]
	v_mov_b64_e32 v[74:75], v[236:237]
	v_mov_b64_e32 v[76:77], v[238:239]
	v_add_u32_e32 v199, 0x133300, v198
	global_load_dwordx4 v[232:235], v199, s[26:27]
	v_add_u32_e32 v199, 0x132100, v198
	global_load_dwordx4 v[236:239], v199, s[26:27]
	s_mov_b32 s100, 0xbfb8aa3b
	v_lshlrev_b32_e32 v242, 16, v70
	v_and_b32_e32 v243, 0xffff0000, v70
	v_lshlrev_b32_e32 v244, 16, v72
	v_and_b32_e32 v245, 0xffff0000, v72
	v_lshlrev_b32_e32 v246, 16, v71
	v_and_b32_e32 v247, 0xffff0000, v71
	v_lshlrev_b32_e32 v248, 16, v73
	v_and_b32_e32 v249, 0xffff0000, v73
	v_pk_mul_f32 v[242:243], v[242:243], s[100:101] op_sel_hi:[1,0]
	v_pk_mul_f32 v[244:245], v[244:245], s[100:101] op_sel_hi:[1,0]
	v_pk_mul_f32 v[246:247], v[246:247], s[100:101] op_sel_hi:[1,0]
	v_pk_mul_f32 v[248:249], v[248:249], s[100:101] op_sel_hi:[1,0]
	v_exp_f32_e32 v242, v242
	v_exp_f32_e32 v243, v243
	v_exp_f32_e32 v244, v244
	v_exp_f32_e32 v245, v245
	v_exp_f32_e32 v246, v246
	v_exp_f32_e32 v247, v247
	v_exp_f32_e32 v248, v248
	v_exp_f32_e32 v249, v249
	s_nop 0
	v_pk_add_f32 v[242:243], v[242:243], 1.0 op_sel_hi:[1,0]
	v_pk_add_f32 v[244:245], v[244:245], 1.0 op_sel_hi:[1,0]
	v_pk_add_f32 v[246:247], v[246:247], 1.0 op_sel_hi:[1,0]
	v_pk_add_f32 v[248:249], v[248:249], 1.0 op_sel_hi:[1,0]
	v_rcp_f32_e32 v250, v242
	v_rcp_f32_e32 v251, v243
	s_nop 0
	v_pk_fma_f32 v[252:253], v[242:243], v[250:251], 1.0 op_sel_hi:[1,1,0] neg_lo:[1,0,0] neg_hi:[1,0,0]
	v_pk_fma_f32 v[250:251], v[252:253], v[250:251], v[250:251]
	v_pk_fma_f32 v[252:253], v[242:243], v[250:251], 1.0 op_sel_hi:[1,1,0] neg_lo:[1,0,0] neg_hi:[1,0,0]
	v_pk_fma_f32 v[254:255], v[252:253], v[250:251], v[250:251]
	v_pk_fma_f32 v[252:253], v[242:243], v[254:255], 1.0 op_sel_hi:[1,1,0] neg_lo:[1,0,0] neg_hi:[1,0,0]
	v_pk_fma_f32 v[254:255], v[252:253], v[250:251], v[254:255]
	v_div_fixup_f32 v242, v254, v242, 1.0
	v_div_fixup_f32 v243, v255, v243, 1.0
	v_rcp_f32_e32 v250, v244
	v_rcp_f32_e32 v251, v245
	s_nop 0
	v_pk_fma_f32 v[252:253], v[244:245], v[250:251], 1.0 op_sel_hi:[1,1,0] neg_lo:[1,0,0] neg_hi:[1,0,0]
	v_pk_fma_f32 v[250:251], v[252:253], v[250:251], v[250:251]
	v_pk_fma_f32 v[252:253], v[244:245], v[250:251], 1.0 op_sel_hi:[1,1,0] neg_lo:[1,0,0] neg_hi:[1,0,0]
	v_pk_fma_f32 v[254:255], v[252:253], v[250:251], v[250:251]
	v_pk_fma_f32 v[252:253], v[244:245], v[254:255], 1.0 op_sel_hi:[1,1,0] neg_lo:[1,0,0] neg_hi:[1,0,0]
	v_pk_fma_f32 v[254:255], v[252:253], v[250:251], v[254:255]
	v_div_fixup_f32 v244, v254, v244, 1.0
	v_div_fixup_f32 v245, v255, v245, 1.0
	v_rcp_f32_e32 v250, v246
	v_rcp_f32_e32 v251, v247
	s_nop 0
	v_pk_fma_f32 v[252:253], v[246:247], v[250:251], 1.0 op_sel_hi:[1,1,0] neg_lo:[1,0,0] neg_hi:[1,0,0]
	v_pk_fma_f32 v[250:251], v[252:253], v[250:251], v[250:251]
	v_pk_fma_f32 v[252:253], v[246:247], v[250:251], 1.0 op_sel_hi:[1,1,0] neg_lo:[1,0,0] neg_hi:[1,0,0]
	v_pk_fma_f32 v[254:255], v[252:253], v[250:251], v[250:251]
	v_pk_fma_f32 v[252:253], v[246:247], v[254:255], 1.0 op_sel_hi:[1,1,0] neg_lo:[1,0,0] neg_hi:[1,0,0]
	v_pk_fma_f32 v[254:255], v[252:253], v[250:251], v[254:255]
	v_div_fixup_f32 v246, v254, v246, 1.0
	v_div_fixup_f32 v247, v255, v247, 1.0
	v_rcp_f32_e32 v250, v248
	v_rcp_f32_e32 v251, v249
	s_nop 0
	v_pk_fma_f32 v[252:253], v[248:249], v[250:251], 1.0 op_sel_hi:[1,1,0] neg_lo:[1,0,0] neg_hi:[1,0,0]
	v_pk_fma_f32 v[250:251], v[252:253], v[250:251], v[250:251]
	v_pk_fma_f32 v[252:253], v[248:249], v[250:251], 1.0 op_sel_hi:[1,1,0] neg_lo:[1,0,0] neg_hi:[1,0,0]
	v_pk_fma_f32 v[254:255], v[252:253], v[250:251], v[250:251]
	v_pk_fma_f32 v[252:253], v[248:249], v[254:255], 1.0 op_sel_hi:[1,1,0] neg_lo:[1,0,0] neg_hi:[1,0,0]
	v_pk_fma_f32 v[254:255], v[252:253], v[250:251], v[254:255]
	v_div_fixup_f32 v248, v254, v248, 1.0
	v_div_fixup_f32 v249, v255, v249, 1.0
	v_lshlrev_b32_e32 v82, 16, v74
	v_and_b32_e32 v83, 0xffff0000, v74
	v_lshlrev_b32_e32 v84, 16, v76
	v_and_b32_e32 v85, 0xffff0000, v76
	v_lshlrev_b32_e32 v76, 16, v77
	v_and_b32_e32 v77, 0xffff0000, v77
	v_lshlrev_b32_e32 v74, 16, v75
	v_and_b32_e32 v75, 0xffff0000, v75
	v_pk_fma_f32 v[60:61], v[60:61], v[242:243], v[82:83]
	v_pk_fma_f32 v[70:71], v[58:59], v[248:249], v[76:77]
	v_pk_fma_f32 v[58:59], v[56:57], v[244:245], v[84:85]
	v_add_lshl_u32 v72, v140, v66, 1
	v_pk_fma_f32 v[62:63], v[62:63], v[246:247], v[74:75]
	v_cvt_pk_bf16_f32 v56, v60, v61
	s_nop 0
	v_cvt_pk_bf16_f32 v57, v62, v63
	v_cvt_pk_bf16_f32 v58, v58, v59
	v_cvt_pk_bf16_f32 v59, v70, v71
	buffer_store_dwordx4 v[56:59], v72, s[20:23], 0 offen sc1
	s_nop 0
	s_waitcnt vmcnt(7)
; __device__ __forceinline__ float sigmoidf_(float x) { return 1.0f / (1.0f + __expf(-x)); }
; __device__ __forceinline__ u32x4 pack8(const f32x4 v0, const f32x4 v1) { u32x4 w; w.x = pk2(v0[0], v0[1]); w.y = pk2(v0[2], v0[3]); w.z = pk2(v1[0], v1[1]); w.w = pk2(v1[2], v1[3]); return w; }
; __device__ __forceinline__ void unpack8(const u32x4 w, f32x4& v0, f32x4& v1) { v0 = (f32x4){bflo(w.x), bfhi(w.x), bflo(w.y), bfhi(w.y)}; v1 = (f32x4){bflo(w.z), bfhi(w.z), bflo(w.w), bfhi(w.w)}; }
;     __device__ __forceinline__ void operator()(const f32x4 (&acc)[2][2][4][2], const Unit& u, int wr, int wc, int fr, int fq) const {
;     ...
;                 for (int bj = 0; bj < 2; ++bj) {
;                     const u32x4 gw = *(const u32x4*)(rowp + O_GA + bj * 128);
;                     f32x4 g0, g1; unpack8(gw, g0, g1);
;                     f32x4 v0, v1;
; #pragma unroll
;                     for (int j = 0; j < 4; ++j) { v0[j] = sigmoidf_(g0[j]) * acc[ai][bj][m][0][j]; v1[j] = sigmoidf_(g1[j]) * acc[ai][bj][m][1][j]; }
;                     const u32x4 mw = *(const u32x4*)(rowp + bj * 128); f32x4 m0, m1; unpack8(mw, m0, m1); v0 += m0; v1 += m1;
;                     __builtin_amdgcn_raw_buffer_store_b128(pack8(v0, v1), rsrc, (unsigned)(((size_t)row * DIN + col0 + bj * 128) * 2), 0, 16  ); }
	v_mov_b64_e32 v[56:57], v[200:201]
	v_mov_b64_e32 v[58:59], v[202:203]
	v_mov_b64_e32 v[60:61], v[204:205]
	v_mov_b64_e32 v[62:63], v[206:207]
	v_add_u32_e32 v199, 0x155200, v198
	global_load_dwordx4 v[200:203], v199, s[26:27]
	v_add_u32_e32 v199, 0x154000, v198
	global_load_dwordx4 v[204:207], v199, s[26:27]
	s_mov_b32 s100, 0xbfb8aa3b
	v_lshlrev_b32_e32 v242, 16, v58
	v_and_b32_e32 v243, 0xffff0000, v58
	v_lshlrev_b32_e32 v244, 16, v56
	v_and_b32_e32 v245, 0xffff0000, v56
	v_lshlrev_b32_e32 v246, 16, v57
	v_and_b32_e32 v247, 0xffff0000, v57
	v_lshlrev_b32_e32 v248, 16, v59
	v_and_b32_e32 v249, 0xffff0000, v59
	v_pk_mul_f32 v[242:243], v[242:243], s[100:101] op_sel_hi:[1,0]
	v_pk_mul_f32 v[244:245], v[244:245], s[100:101] op_sel_hi:[1,0]
	v_pk_mul_f32 v[246:247], v[246:247], s[100:101] op_sel_hi:[1,0]
	v_pk_mul_f32 v[248:249], v[248:249], s[100:101] op_sel_hi:[1,0]
	v_exp_f32_e32 v242, v242
	v_exp_f32_e32 v243, v243
	v_exp_f32_e32 v244, v244
	v_exp_f32_e32 v245, v245
	v_exp_f32_e32 v246, v246
	v_exp_f32_e32 v247, v247
	v_exp_f32_e32 v248, v248
	v_exp_f32_e32 v249, v249
	s_nop 0
	v_pk_add_f32 v[242:243], v[242:243], 1.0 op_sel_hi:[1,0]
	v_pk_add_f32 v[244:245], v[244:245], 1.0 op_sel_hi:[1,0]
	v_pk_add_f32 v[246:247], v[246:247], 1.0 op_sel_hi:[1,0]
	v_pk_add_f32 v[248:249], v[248:249], 1.0 op_sel_hi:[1,0]
	v_rcp_f32_e32 v250, v242
	v_rcp_f32_e32 v251, v243
	s_nop 0
	v_pk_fma_f32 v[252:253], v[242:243], v[250:251], 1.0 op_sel_hi:[1,1,0] neg_lo:[1,0,0] neg_hi:[1,0,0]
	v_pk_fma_f32 v[250:251], v[252:253], v[250:251], v[250:251]
	v_pk_fma_f32 v[252:253], v[242:243], v[250:251], 1.0 op_sel_hi:[1,1,0] neg_lo:[1,0,0] neg_hi:[1,0,0]
	v_pk_fma_f32 v[254:255], v[252:253], v[250:251], v[250:251]
	v_pk_fma_f32 v[252:253], v[242:243], v[254:255], 1.0 op_sel_hi:[1,1,0] neg_lo:[1,0,0] neg_hi:[1,0,0]
	v_pk_fma_f32 v[254:255], v[252:253], v[250:251], v[254:255]
	v_div_fixup_f32 v242, v254, v242, 1.0
	v_div_fixup_f32 v243, v255, v243, 1.0
	v_rcp_f32_e32 v250, v244
	v_rcp_f32_e32 v251, v245
	s_nop 0
	v_pk_fma_f32 v[252:253], v[244:245], v[250:251], 1.0 op_sel_hi:[1,1,0] neg_lo:[1,0,0] neg_hi:[1,0,0]
	v_pk_fma_f32 v[250:251], v[252:253], v[250:251], v[250:251]
	v_pk_fma_f32 v[252:253], v[244:245], v[250:251], 1.0 op_sel_hi:[1,1,0] neg_lo:[1,0,0] neg_hi:[1,0,0]
	v_pk_fma_f32 v[254:255], v[252:253], v[250:251], v[250:251]
	v_pk_fma_f32 v[252:253], v[244:245], v[254:255], 1.0 op_sel_hi:[1,1,0] neg_lo:[1,0,0] neg_hi:[1,0,0]
	v_pk_fma_f32 v[254:255], v[252:253], v[250:251], v[254:255]
	v_div_fixup_f32 v244, v254, v244, 1.0
	v_div_fixup_f32 v245, v255, v245, 1.0
	v_rcp_f32_e32 v250, v246
	v_rcp_f32_e32 v251, v247
	s_nop 0
	v_pk_fma_f32 v[252:253], v[246:247], v[250:251], 1.0 op_sel_hi:[1,1,0] neg_lo:[1,0,0] neg_hi:[1,0,0]
	v_pk_fma_f32 v[250:251], v[252:253], v[250:251], v[250:251]
	v_pk_fma_f32 v[252:253], v[246:247], v[250:251], 1.0 op_sel_hi:[1,1,0] neg_lo:[1,0,0] neg_hi:[1,0,0]
	v_pk_fma_f32 v[254:255], v[252:253], v[250:251], v[250:251]
	v_pk_fma_f32 v[252:253], v[246:247], v[254:255], 1.0 op_sel_hi:[1,1,0] neg_lo:[1,0,0] neg_hi:[1,0,0]
	v_pk_fma_f32 v[254:255], v[252:253], v[250:251], v[254:255]
	v_div_fixup_f32 v246, v254, v246, 1.0
	v_div_fixup_f32 v247, v255, v247, 1.0
	v_rcp_f32_e32 v250, v248
	v_rcp_f32_e32 v251, v249
	s_nop 0
	v_pk_fma_f32 v[252:253], v[248:249], v[250:251], 1.0 op_sel_hi:[1,1,0] neg_lo:[1,0,0] neg_hi:[1,0,0]
	v_pk_fma_f32 v[250:251], v[252:253], v[250:251], v[250:251]
	v_pk_fma_f32 v[252:253], v[248:249], v[250:251], 1.0 op_sel_hi:[1,1,0] neg_lo:[1,0,0] neg_hi:[1,0,0]
	v_pk_fma_f32 v[254:255], v[252:253], v[250:251], v[250:251]
	v_pk_fma_f32 v[252:253], v[248:249], v[254:255], 1.0 op_sel_hi:[1,1,0] neg_lo:[1,0,0] neg_hi:[1,0,0]
	v_pk_fma_f32 v[254:255], v[252:253], v[250:251], v[254:255]
	v_div_fixup_f32 v248, v254, v248, 1.0
	v_div_fixup_f32 v249, v255, v249, 1.0
	v_lshlrev_b32_e32 v68, 16, v60
	v_and_b32_e32 v69, 0xffff0000, v60
	v_lshlrev_b32_e32 v70, 16, v62
	v_and_b32_e32 v71, 0xffff0000, v62
	v_lshlrev_b32_e32 v62, 16, v63
	v_and_b32_e32 v63, 0xffff0000, v63
	v_lshlrev_b32_e32 v60, 16, v61
	v_and_b32_e32 v61, 0xffff0000, v61
	v_pk_fma_f32 v[52:53], v[52:53], v[244:245], v[68:69]
	v_pk_fma_f32 v[56:57], v[50:51], v[248:249], v[62:63]
	v_pk_fma_f32 v[50:51], v[48:49], v[242:243], v[70:71]
	v_cvt_pk_bf16_f32 v48, v52, v53
	v_pk_fma_f32 v[54:55], v[54:55], v[246:247], v[60:61]
	s_nop 0
	v_cvt_pk_bf16_f32 v49, v54, v55
	v_cvt_pk_bf16_f32 v50, v50, v51
	v_cvt_pk_bf16_f32 v51, v56, v57
	buffer_store_dwordx4 v[48:51], v72, s[20:23], 0 offen offset:256 sc1
	s_nop 1
	v_add_u32_e32 v48, 0x4090, v158
	v_mad_i64_i32 v[50:51], s[6:7], v48, s77, 0
	v_lshl_add_u64 v[48:49], v[50:51], 1, s[26:27]
	v_lshl_add_u64 v[48:49], v[48:49], 0, v[142:143]
	v_add_co_u32_e32 v52, vcc, s78, v48
	s_nop 1
	v_addc_co_u32_e32 v53, vcc, 0, v49, vcc
	s_waitcnt vmcnt(7)
; __device__ __forceinline__ float sigmoidf_(float x) { return 1.0f / (1.0f + __expf(-x)); }
; __device__ __forceinline__ u32x4 pack8(const f32x4 v0, const f32x4 v1) { u32x4 w; w.x = pk2(v0[0], v0[1]); w.y = pk2(v0[2], v0[3]); w.z = pk2(v1[0], v1[1]); w.w = pk2(v1[2], v1[3]); return w; }
; __device__ __forceinline__ void unpack8(const u32x4 w, f32x4& v0, f32x4& v1) { v0 = (f32x4){bflo(w.x), bfhi(w.x), bflo(w.y), bfhi(w.y)}; v1 = (f32x4){bflo(w.z), bfhi(w.z), bflo(w.w), bfhi(w.w)}; }
;     __device__ __forceinline__ void operator()(const f32x4 (&acc)[2][2][4][2], const Unit& u, int wr, int wc, int fr, int fq) const {
;     ...
;                 for (int bj = 0; bj < 2; ++bj) {
;                     const u32x4 gw = *(const u32x4*)(rowp + O_GA + bj * 128);
;                     f32x4 g0, g1; unpack8(gw, g0, g1);
;                     f32x4 v0, v1;
; #pragma unroll
;                     for (int j = 0; j < 4; ++j) { v0[j] = sigmoidf_(g0[j]) * acc[ai][bj][m][0][j]; v1[j] = sigmoidf_(g1[j]) * acc[ai][bj][m][1][j]; }
;                     const u32x4 mw = *(const u32x4*)(rowp + bj * 128); f32x4 m0, m1; unpack8(mw, m0, m1); v0 += m0; v1 += m1;
;                     __builtin_amdgcn_raw_buffer_store_b128(pack8(v0, v1), rsrc, (unsigned)(((size_t)row * DIN + col0 + bj * 128) * 2), 0, 16  ); }
	v_mov_b64_e32 v[54:55], v[208:209]
	v_mov_b64_e32 v[56:57], v[210:211]
	v_mov_b64_e32 v[58:59], v[212:213]
	v_mov_b64_e32 v[60:61], v[214:215]
	v_add_u32_e32 v199, 0x155300, v198
	global_load_dwordx4 v[208:211], v199, s[26:27]
	v_add_u32_e32 v199, 0x154100, v198
	global_load_dwordx4 v[212:215], v199, s[26:27]
	s_mov_b32 s100, 0xbfb8aa3b
	v_lshlrev_b32_e32 v242, 16, v54
	v_and_b32_e32 v243, 0xffff0000, v54
	v_lshlrev_b32_e32 v244, 16, v56
	v_and_b32_e32 v245, 0xffff0000, v56
	v_lshlrev_b32_e32 v246, 16, v55
	v_and_b32_e32 v247, 0xffff0000, v55
	v_lshlrev_b32_e32 v248, 16, v57
	v_and_b32_e32 v249, 0xffff0000, v57
	v_pk_mul_f32 v[242:243], v[242:243], s[100:101] op_sel_hi:[1,0]
	v_pk_mul_f32 v[244:245], v[244:245], s[100:101] op_sel_hi:[1,0]
	v_pk_mul_f32 v[246:247], v[246:247], s[100:101] op_sel_hi:[1,0]
	v_pk_mul_f32 v[248:249], v[248:249], s[100:101] op_sel_hi:[1,0]
	v_exp_f32_e32 v242, v242
	v_exp_f32_e32 v243, v243
	v_exp_f32_e32 v244, v244
	v_exp_f32_e32 v245, v245
	v_exp_f32_e32 v246, v246
	v_exp_f32_e32 v247, v247
	v_exp_f32_e32 v248, v248
	v_exp_f32_e32 v249, v249
	s_nop 0
	v_pk_add_f32 v[242:243], v[242:243], 1.0 op_sel_hi:[1,0]
	v_pk_add_f32 v[244:245], v[244:245], 1.0 op_sel_hi:[1,0]
	v_pk_add_f32 v[246:247], v[246:247], 1.0 op_sel_hi:[1,0]
	v_pk_add_f32 v[248:249], v[248:249], 1.0 op_sel_hi:[1,0]
	v_rcp_f32_e32 v250, v242
	v_rcp_f32_e32 v251, v243
	s_nop 0
	v_pk_fma_f32 v[252:253], v[242:243], v[250:251], 1.0 op_sel_hi:[1,1,0] neg_lo:[1,0,0] neg_hi:[1,0,0]
	v_pk_fma_f32 v[250:251], v[252:253], v[250:251], v[250:251]
	v_pk_fma_f32 v[252:253], v[242:243], v[250:251], 1.0 op_sel_hi:[1,1,0] neg_lo:[1,0,0] neg_hi:[1,0,0]
	v_pk_fma_f32 v[254:255], v[252:253], v[250:251], v[250:251]
	v_pk_fma_f32 v[252:253], v[242:243], v[254:255], 1.0 op_sel_hi:[1,1,0] neg_lo:[1,0,0] neg_hi:[1,0,0]
	v_pk_fma_f32 v[254:255], v[252:253], v[250:251], v[254:255]
	v_div_fixup_f32 v242, v254, v242, 1.0
	v_div_fixup_f32 v243, v255, v243, 1.0
	v_rcp_f32_e32 v250, v244
	v_rcp_f32_e32 v251, v245
	s_nop 0
	v_pk_fma_f32 v[252:253], v[244:245], v[250:251], 1.0 op_sel_hi:[1,1,0] neg_lo:[1,0,0] neg_hi:[1,0,0]
	v_pk_fma_f32 v[250:251], v[252:253], v[250:251], v[250:251]
	v_pk_fma_f32 v[252:253], v[244:245], v[250:251], 1.0 op_sel_hi:[1,1,0] neg_lo:[1,0,0] neg_hi:[1,0,0]
	v_pk_fma_f32 v[254:255], v[252:253], v[250:251], v[250:251]
	v_pk_fma_f32 v[252:253], v[244:245], v[254:255], 1.0 op_sel_hi:[1,1,0] neg_lo:[1,0,0] neg_hi:[1,0,0]
	v_pk_fma_f32 v[254:255], v[252:253], v[250:251], v[254:255]
	v_div_fixup_f32 v244, v254, v244, 1.0
	v_div_fixup_f32 v245, v255, v245, 1.0
	v_rcp_f32_e32 v250, v246
	v_rcp_f32_e32 v251, v247
	s_nop 0
	v_pk_fma_f32 v[252:253], v[246:247], v[250:251], 1.0 op_sel_hi:[1,1,0] neg_lo:[1,0,0] neg_hi:[1,0,0]
	v_pk_fma_f32 v[250:251], v[252:253], v[250:251], v[250:251]
	v_pk_fma_f32 v[252:253], v[246:247], v[250:251], 1.0 op_sel_hi:[1,1,0] neg_lo:[1,0,0] neg_hi:[1,0,0]
	v_pk_fma_f32 v[254:255], v[252:253], v[250:251], v[250:251]
	v_pk_fma_f32 v[252:253], v[246:247], v[254:255], 1.0 op_sel_hi:[1,1,0] neg_lo:[1,0,0] neg_hi:[1,0,0]
	v_pk_fma_f32 v[254:255], v[252:253], v[250:251], v[254:255]
	v_div_fixup_f32 v246, v254, v246, 1.0
	v_div_fixup_f32 v247, v255, v247, 1.0
	v_rcp_f32_e32 v250, v248
	v_rcp_f32_e32 v251, v249
	s_nop 0
	v_pk_fma_f32 v[252:253], v[248:249], v[250:251], 1.0 op_sel_hi:[1,1,0] neg_lo:[1,0,0] neg_hi:[1,0,0]
	v_pk_fma_f32 v[250:251], v[252:253], v[250:251], v[250:251]
	v_pk_fma_f32 v[252:253], v[248:249], v[250:251], 1.0 op_sel_hi:[1,1,0] neg_lo:[1,0,0] neg_hi:[1,0,0]
	v_pk_fma_f32 v[254:255], v[252:253], v[250:251], v[250:251]
	v_pk_fma_f32 v[252:253], v[248:249], v[254:255], 1.0 op_sel_hi:[1,1,0] neg_lo:[1,0,0] neg_hi:[1,0,0]
	v_pk_fma_f32 v[254:255], v[252:253], v[250:251], v[254:255]
	v_div_fixup_f32 v248, v254, v248, 1.0
	v_div_fixup_f32 v249, v255, v249, 1.0
	v_lshlrev_b32_e32 v66, 16, v58
	v_and_b32_e32 v67, 0xffff0000, v58
	v_lshlrev_b32_e32 v68, 16, v60
	v_and_b32_e32 v69, 0xffff0000, v60
	v_lshlrev_b32_e32 v60, 16, v61
	v_and_b32_e32 v61, 0xffff0000, v61
	v_lshlrev_b32_e32 v58, 16, v59
	v_and_b32_e32 v59, 0xffff0000, v59
	v_pk_fma_f32 v[44:45], v[44:45], v[242:243], v[66:67]
	v_pk_fma_f32 v[54:55], v[42:43], v[248:249], v[60:61]
	v_pk_fma_f32 v[42:43], v[40:41], v[244:245], v[68:69]
	v_add_lshl_u32 v56, v140, v50, 1
	v_pk_fma_f32 v[46:47], v[46:47], v[246:247], v[58:59]
	v_cvt_pk_bf16_f32 v40, v44, v45
	s_nop 0
	v_cvt_pk_bf16_f32 v41, v46, v47
	v_cvt_pk_bf16_f32 v42, v42, v43
	v_cvt_pk_bf16_f32 v43, v54, v55
	buffer_store_dwordx4 v[40:43], v56, s[20:23], 0 offen sc1
	s_nop 0
	s_waitcnt vmcnt(7)
; __device__ __forceinline__ float sigmoidf_(float x) { return 1.0f / (1.0f + __expf(-x)); }
; __device__ __forceinline__ u32x4 pack8(const f32x4 v0, const f32x4 v1) { u32x4 w; w.x = pk2(v0[0], v0[1]); w.y = pk2(v0[2], v0[3]); w.z = pk2(v1[0], v1[1]); w.w = pk2(v1[2], v1[3]); return w; }
; __device__ __forceinline__ void unpack8(const u32x4 w, f32x4& v0, f32x4& v1) { v0 = (f32x4){bflo(w.x), bfhi(w.x), bflo(w.y), bfhi(w.y)}; v1 = (f32x4){bflo(w.z), bfhi(w.z), bflo(w.w), bfhi(w.w)}; }
;     __device__ __forceinline__ void operator()(const f32x4 (&acc)[2][2][4][2], const Unit& u, int wr, int wc, int fr, int fq) const {
;     ...
;                 const int row = row0 + ai * 128 + m * 16;
;                 const bf16_t* rowp = z + (size_t)row * DIN + col0;
; #pragma unroll
;                 for (int bj = 0; bj < 2; ++bj) {
;                     const u32x4 gw = *(const u32x4*)(rowp + O_GA + bj * 128);
;                     f32x4 g0, g1; unpack8(gw, g0, g1);
;                     f32x4 v0, v1;
; #pragma unroll
;                     for (int j = 0; j < 4; ++j) { v0[j] = sigmoidf_(g0[j]) * acc[ai][bj][m][0][j]; v1[j] = sigmoidf_(g1[j]) * acc[ai][bj][m][1][j]; }
;                     const u32x4 mw = *(const u32x4*)(rowp + bj * 128); f32x4 m0, m1; unpack8(mw, m0, m1); v0 += m0; v1 += m1;
;                     __builtin_amdgcn_raw_buffer_store_b128(pack8(v0, v1), rsrc, (unsigned)(((size_t)row * DIN + col0 + bj * 128) * 2), 0, 16  ); }
	v_mov_b64_e32 v[40:41], v[232:233]
	v_mov_b64_e32 v[42:43], v[234:235]
	v_mov_b64_e32 v[44:45], v[236:237]
	v_mov_b64_e32 v[46:47], v[238:239]
	v_add_u32_e32 v199, 0x177200, v198
	global_load_dwordx4 v[232:235], v199, s[26:27]
	v_add_u32_e32 v199, 0x176000, v198
	global_load_dwordx4 v[236:239], v199, s[26:27]
	s_mov_b32 s100, 0xbfb8aa3b
	v_lshlrev_b32_e32 v242, 16, v42
	v_and_b32_e32 v243, 0xffff0000, v42
	v_lshlrev_b32_e32 v244, 16, v40
	v_and_b32_e32 v245, 0xffff0000, v40
	v_lshlrev_b32_e32 v246, 16, v41
	v_and_b32_e32 v247, 0xffff0000, v41
	v_lshlrev_b32_e32 v248, 16, v43
	v_and_b32_e32 v249, 0xffff0000, v43
	v_pk_mul_f32 v[242:243], v[242:243], s[100:101] op_sel_hi:[1,0]
	v_pk_mul_f32 v[244:245], v[244:245], s[100:101] op_sel_hi:[1,0]
	v_pk_mul_f32 v[246:247], v[246:247], s[100:101] op_sel_hi:[1,0]
	v_pk_mul_f32 v[248:249], v[248:249], s[100:101] op_sel_hi:[1,0]
	v_exp_f32_e32 v242, v242
	v_exp_f32_e32 v243, v243
	v_exp_f32_e32 v244, v244
	v_exp_f32_e32 v245, v245
	v_exp_f32_e32 v246, v246
	v_exp_f32_e32 v247, v247
	v_exp_f32_e32 v248, v248
	v_exp_f32_e32 v249, v249
	s_nop 0
	v_pk_add_f32 v[242:243], v[242:243], 1.0 op_sel_hi:[1,0]
	v_pk_add_f32 v[244:245], v[244:245], 1.0 op_sel_hi:[1,0]
	v_pk_add_f32 v[246:247], v[246:247], 1.0 op_sel_hi:[1,0]
	v_pk_add_f32 v[248:249], v[248:249], 1.0 op_sel_hi:[1,0]
	v_rcp_f32_e32 v250, v242
	v_rcp_f32_e32 v251, v243
	s_nop 0
	v_pk_fma_f32 v[252:253], v[242:243], v[250:251], 1.0 op_sel_hi:[1,1,0] neg_lo:[1,0,0] neg_hi:[1,0,0]
	v_pk_fma_f32 v[250:251], v[252:253], v[250:251], v[250:251]
	v_pk_fma_f32 v[252:253], v[242:243], v[250:251], 1.0 op_sel_hi:[1,1,0] neg_lo:[1,0,0] neg_hi:[1,0,0]
	v_pk_fma_f32 v[254:255], v[252:253], v[250:251], v[250:251]
	v_pk_fma_f32 v[252:253], v[242:243], v[254:255], 1.0 op_sel_hi:[1,1,0] neg_lo:[1,0,0] neg_hi:[1,0,0]
	v_pk_fma_f32 v[254:255], v[252:253], v[250:251], v[254:255]
	v_div_fixup_f32 v242, v254, v242, 1.0
	v_div_fixup_f32 v243, v255, v243, 1.0
	v_rcp_f32_e32 v250, v244
	v_rcp_f32_e32 v251, v245
	s_nop 0
	v_pk_fma_f32 v[252:253], v[244:245], v[250:251], 1.0 op_sel_hi:[1,1,0] neg_lo:[1,0,0] neg_hi:[1,0,0]
	v_pk_fma_f32 v[250:251], v[252:253], v[250:251], v[250:251]
	v_pk_fma_f32 v[252:253], v[244:245], v[250:251], 1.0 op_sel_hi:[1,1,0] neg_lo:[1,0,0] neg_hi:[1,0,0]
	v_pk_fma_f32 v[254:255], v[252:253], v[250:251], v[250:251]
	v_pk_fma_f32 v[252:253], v[244:245], v[254:255], 1.0 op_sel_hi:[1,1,0] neg_lo:[1,0,0] neg_hi:[1,0,0]
	v_pk_fma_f32 v[254:255], v[252:253], v[250:251], v[254:255]
	v_div_fixup_f32 v244, v254, v244, 1.0
	v_div_fixup_f32 v245, v255, v245, 1.0
	v_rcp_f32_e32 v250, v246
	v_rcp_f32_e32 v251, v247
	s_nop 0
	v_pk_fma_f32 v[252:253], v[246:247], v[250:251], 1.0 op_sel_hi:[1,1,0] neg_lo:[1,0,0] neg_hi:[1,0,0]
	v_pk_fma_f32 v[250:251], v[252:253], v[250:251], v[250:251]
	v_pk_fma_f32 v[252:253], v[246:247], v[250:251], 1.0 op_sel_hi:[1,1,0] neg_lo:[1,0,0] neg_hi:[1,0,0]
	v_pk_fma_f32 v[254:255], v[252:253], v[250:251], v[250:251]
	v_pk_fma_f32 v[252:253], v[246:247], v[254:255], 1.0 op_sel_hi:[1,1,0] neg_lo:[1,0,0] neg_hi:[1,0,0]
	v_pk_fma_f32 v[254:255], v[252:253], v[250:251], v[254:255]
	v_div_fixup_f32 v246, v254, v246, 1.0
	v_div_fixup_f32 v247, v255, v247, 1.0
	v_rcp_f32_e32 v250, v248
	v_rcp_f32_e32 v251, v249
	s_nop 0
	v_pk_fma_f32 v[252:253], v[248:249], v[250:251], 1.0 op_sel_hi:[1,1,0] neg_lo:[1,0,0] neg_hi:[1,0,0]
	v_pk_fma_f32 v[250:251], v[252:253], v[250:251], v[250:251]
	v_pk_fma_f32 v[252:253], v[248:249], v[250:251], 1.0 op_sel_hi:[1,1,0] neg_lo:[1,0,0] neg_hi:[1,0,0]
	v_pk_fma_f32 v[254:255], v[252:253], v[250:251], v[250:251]
	v_pk_fma_f32 v[252:253], v[248:249], v[254:255], 1.0 op_sel_hi:[1,1,0] neg_lo:[1,0,0] neg_hi:[1,0,0]
	v_pk_fma_f32 v[254:255], v[252:253], v[250:251], v[254:255]
	v_div_fixup_f32 v248, v254, v248, 1.0
	v_div_fixup_f32 v249, v255, v249, 1.0
	v_lshlrev_b32_e32 v52, 16, v44
	v_and_b32_e32 v53, 0xffff0000, v44
	v_lshlrev_b32_e32 v54, 16, v46
	v_and_b32_e32 v55, 0xffff0000, v46
	v_lshlrev_b32_e32 v46, 16, v47
	v_and_b32_e32 v47, 0xffff0000, v47
	v_lshlrev_b32_e32 v44, 16, v45
	v_and_b32_e32 v45, 0xffff0000, v45
	v_pk_fma_f32 v[36:37], v[36:37], v[244:245], v[52:53]
	v_pk_fma_f32 v[40:41], v[34:35], v[248:249], v[46:47]
	v_pk_fma_f32 v[34:35], v[32:33], v[242:243], v[54:55]
	v_cvt_pk_bf16_f32 v32, v36, v37
	v_pk_fma_f32 v[38:39], v[38:39], v[246:247], v[44:45]
	s_nop 0
	v_cvt_pk_bf16_f32 v33, v38, v39
	v_cvt_pk_bf16_f32 v34, v34, v35
	v_cvt_pk_bf16_f32 v35, v40, v41
	buffer_store_dwordx4 v[32:35], v56, s[20:23], 0 offen offset:256 sc1
	s_nop 1
	v_add_u32_e32 v32, 0x40a0, v158
	v_mad_i64_i32 v[34:35], s[6:7], v32, s77, 0
	v_lshl_add_u64 v[32:33], v[34:35], 1, s[26:27]
	v_lshl_add_u64 v[32:33], v[32:33], 0, v[142:143]
	v_add_co_u32_e32 v36, vcc, s78, v32
	s_nop 1
	v_addc_co_u32_e32 v37, vcc, 0, v33, vcc
	s_waitcnt vmcnt(7)
; __device__ __forceinline__ float sigmoidf_(float x) { return 1.0f / (1.0f + __expf(-x)); }
; __device__ __forceinline__ u32x4 pack8(const f32x4 v0, const f32x4 v1) { u32x4 w; w.x = pk2(v0[0], v0[1]); w.y = pk2(v0[2], v0[3]); w.z = pk2(v1[0], v1[1]); w.w = pk2(v1[2], v1[3]); return w; }
; __device__ __forceinline__ void unpack8(const u32x4 w, f32x4& v0, f32x4& v1) { v0 = (f32x4){bflo(w.x), bfhi(w.x), bflo(w.y), bfhi(w.y)}; v1 = (f32x4){bflo(w.z), bfhi(w.z), bflo(w.w), bfhi(w.w)}; }
;     __device__ __forceinline__ void operator()(const f32x4 (&acc)[2][2][4][2], const Unit& u, int wr, int wc, int fr, int fq) const {
;     ...
;                 const int row = row0 + ai * 128 + m * 16;
;                 const bf16_t* rowp = z + (size_t)row * DIN + col0;
; #pragma unroll
;                 for (int bj = 0; bj < 2; ++bj) {
;                     const u32x4 gw = *(const u32x4*)(rowp + O_GA + bj * 128);
;                     f32x4 g0, g1; unpack8(gw, g0, g1);
;                     f32x4 v0, v1;
; #pragma unroll
;                     for (int j = 0; j < 4; ++j) { v0[j] = sigmoidf_(g0[j]) * acc[ai][bj][m][0][j]; v1[j] = sigmoidf_(g1[j]) * acc[ai][bj][m][1][j]; }
;                     const u32x4 mw = *(const u32x4*)(rowp + bj * 128); f32x4 m0, m1; unpack8(mw, m0, m1); v0 += m0; v1 += m1;
;                     __builtin_amdgcn_raw_buffer_store_b128(pack8(v0, v1), rsrc, (unsigned)(((size_t)row * DIN + col0 + bj * 128) * 2), 0, 16  ); }
	v_mov_b64_e32 v[38:39], v[200:201]
	v_mov_b64_e32 v[40:41], v[202:203]
	v_mov_b64_e32 v[42:43], v[204:205]
	v_mov_b64_e32 v[44:45], v[206:207]
	v_add_u32_e32 v199, 0x177300, v198
	global_load_dwordx4 v[200:203], v199, s[26:27]
	v_add_u32_e32 v199, 0x176100, v198
	global_load_dwordx4 v[204:207], v199, s[26:27]
	s_mov_b32 s100, 0xbfb8aa3b
	v_lshlrev_b32_e32 v242, 16, v38
	v_and_b32_e32 v243, 0xffff0000, v38
	v_lshlrev_b32_e32 v244, 16, v40
	v_and_b32_e32 v245, 0xffff0000, v40
	v_lshlrev_b32_e32 v246, 16, v39
	v_and_b32_e32 v247, 0xffff0000, v39
	v_lshlrev_b32_e32 v248, 16, v41
	v_and_b32_e32 v249, 0xffff0000, v41
	v_pk_mul_f32 v[242:243], v[242:243], s[100:101] op_sel_hi:[1,0]
	v_pk_mul_f32 v[244:245], v[244:245], s[100:101] op_sel_hi:[1,0]
	v_pk_mul_f32 v[246:247], v[246:247], s[100:101] op_sel_hi:[1,0]
	v_pk_mul_f32 v[248:249], v[248:249], s[100:101] op_sel_hi:[1,0]
	v_exp_f32_e32 v242, v242
	v_exp_f32_e32 v243, v243
	v_exp_f32_e32 v244, v244
	v_exp_f32_e32 v245, v245
	v_exp_f32_e32 v246, v246
	v_exp_f32_e32 v247, v247
	v_exp_f32_e32 v248, v248
	v_exp_f32_e32 v249, v249
	s_nop 0
	v_pk_add_f32 v[242:243], v[242:243], 1.0 op_sel_hi:[1,0]
	v_pk_add_f32 v[244:245], v[244:245], 1.0 op_sel_hi:[1,0]
	v_pk_add_f32 v[246:247], v[246:247], 1.0 op_sel_hi:[1,0]
	v_pk_add_f32 v[248:249], v[248:249], 1.0 op_sel_hi:[1,0]
	v_rcp_f32_e32 v250, v242
	v_rcp_f32_e32 v251, v243
	s_nop 0
	v_pk_fma_f32 v[252:253], v[242:243], v[250:251], 1.0 op_sel_hi:[1,1,0] neg_lo:[1,0,0] neg_hi:[1,0,0]
	v_pk_fma_f32 v[250:251], v[252:253], v[250:251], v[250:251]
	v_pk_fma_f32 v[252:253], v[242:243], v[250:251], 1.0 op_sel_hi:[1,1,0] neg_lo:[1,0,0] neg_hi:[1,0,0]
	v_pk_fma_f32 v[254:255], v[252:253], v[250:251], v[250:251]
	v_pk_fma_f32 v[252:253], v[242:243], v[254:255], 1.0 op_sel_hi:[1,1,0] neg_lo:[1,0,0] neg_hi:[1,0,0]
	v_pk_fma_f32 v[254:255], v[252:253], v[250:251], v[254:255]
	v_div_fixup_f32 v242, v254, v242, 1.0
	v_div_fixup_f32 v243, v255, v243, 1.0
	v_rcp_f32_e32 v250, v244
	v_rcp_f32_e32 v251, v245
	s_nop 0
	v_pk_fma_f32 v[252:253], v[244:245], v[250:251], 1.0 op_sel_hi:[1,1,0] neg_lo:[1,0,0] neg_hi:[1,0,0]
	v_pk_fma_f32 v[250:251], v[252:253], v[250:251], v[250:251]
	v_pk_fma_f32 v[252:253], v[244:245], v[250:251], 1.0 op_sel_hi:[1,1,0] neg_lo:[1,0,0] neg_hi:[1,0,0]
	v_pk_fma_f32 v[254:255], v[252:253], v[250:251], v[250:251]
	v_pk_fma_f32 v[252:253], v[244:245], v[254:255], 1.0 op_sel_hi:[1,1,0] neg_lo:[1,0,0] neg_hi:[1,0,0]
	v_pk_fma_f32 v[254:255], v[252:253], v[250:251], v[254:255]
	v_div_fixup_f32 v244, v254, v244, 1.0
	v_div_fixup_f32 v245, v255, v245, 1.0
	v_rcp_f32_e32 v250, v246
	v_rcp_f32_e32 v251, v247
	s_nop 0
	v_pk_fma_f32 v[252:253], v[246:247], v[250:251], 1.0 op_sel_hi:[1,1,0] neg_lo:[1,0,0] neg_hi:[1,0,0]
	v_pk_fma_f32 v[250:251], v[252:253], v[250:251], v[250:251]
	v_pk_fma_f32 v[252:253], v[246:247], v[250:251], 1.0 op_sel_hi:[1,1,0] neg_lo:[1,0,0] neg_hi:[1,0,0]
	v_pk_fma_f32 v[254:255], v[252:253], v[250:251], v[250:251]
	v_pk_fma_f32 v[252:253], v[246:247], v[254:255], 1.0 op_sel_hi:[1,1,0] neg_lo:[1,0,0] neg_hi:[1,0,0]
	v_pk_fma_f32 v[254:255], v[252:253], v[250:251], v[254:255]
	v_div_fixup_f32 v246, v254, v246, 1.0
	v_div_fixup_f32 v247, v255, v247, 1.0
	v_rcp_f32_e32 v250, v248
	v_rcp_f32_e32 v251, v249
	s_nop 0
	v_pk_fma_f32 v[252:253], v[248:249], v[250:251], 1.0 op_sel_hi:[1,1,0] neg_lo:[1,0,0] neg_hi:[1,0,0]
	v_pk_fma_f32 v[250:251], v[252:253], v[250:251], v[250:251]
	v_pk_fma_f32 v[252:253], v[248:249], v[250:251], 1.0 op_sel_hi:[1,1,0] neg_lo:[1,0,0] neg_hi:[1,0,0]
	v_pk_fma_f32 v[254:255], v[252:253], v[250:251], v[250:251]
	v_pk_fma_f32 v[252:253], v[248:249], v[254:255], 1.0 op_sel_hi:[1,1,0] neg_lo:[1,0,0] neg_hi:[1,0,0]
	v_pk_fma_f32 v[254:255], v[252:253], v[250:251], v[254:255]
	v_div_fixup_f32 v248, v254, v248, 1.0
	v_div_fixup_f32 v249, v255, v249, 1.0
	v_lshlrev_b32_e32 v50, 16, v42
	v_and_b32_e32 v51, 0xffff0000, v42
	v_lshlrev_b32_e32 v52, 16, v44
	v_and_b32_e32 v53, 0xffff0000, v44
	v_lshlrev_b32_e32 v44, 16, v45
	v_and_b32_e32 v45, 0xffff0000, v45
	v_lshlrev_b32_e32 v42, 16, v43
	v_and_b32_e32 v43, 0xffff0000, v43
	v_pk_fma_f32 v[28:29], v[28:29], v[242:243], v[50:51]
	v_pk_fma_f32 v[38:39], v[26:27], v[248:249], v[44:45]
	v_pk_fma_f32 v[26:27], v[24:25], v[244:245], v[52:53]
	v_add_lshl_u32 v40, v140, v34, 1
	v_pk_fma_f32 v[30:31], v[30:31], v[246:247], v[42:43]
	v_cvt_pk_bf16_f32 v24, v28, v29
	s_nop 0
	v_cvt_pk_bf16_f32 v25, v30, v31
	v_cvt_pk_bf16_f32 v26, v26, v27
	v_cvt_pk_bf16_f32 v27, v38, v39
	buffer_store_dwordx4 v[24:27], v40, s[20:23], 0 offen sc1
	s_nop 0
	s_waitcnt vmcnt(7)
; __device__ __forceinline__ float sigmoidf_(float x) { return 1.0f / (1.0f + __expf(-x)); }
; __device__ __forceinline__ u32x4 pack8(const f32x4 v0, const f32x4 v1) { u32x4 w; w.x = pk2(v0[0], v0[1]); w.y = pk2(v0[2], v0[3]); w.z = pk2(v1[0], v1[1]); w.w = pk2(v1[2], v1[3]); return w; }
; __device__ __forceinline__ void unpack8(const u32x4 w, f32x4& v0, f32x4& v1) { v0 = (f32x4){bflo(w.x), bfhi(w.x), bflo(w.y), bfhi(w.y)}; v1 = (f32x4){bflo(w.z), bfhi(w.z), bflo(w.w), bfhi(w.w)}; }
;     __device__ __forceinline__ void operator()(const f32x4 (&acc)[2][2][4][2], const Unit& u, int wr, int wc, int fr, int fq) const {
;     ...
;                 const int row = row0 + ai * 128 + m * 16;
;                 const bf16_t* rowp = z + (size_t)row * DIN + col0;
; #pragma unroll
;                 for (int bj = 0; bj < 2; ++bj) {
;                     const u32x4 gw = *(const u32x4*)(rowp + O_GA + bj * 128);
;                     f32x4 g0, g1; unpack8(gw, g0, g1);
;                     f32x4 v0, v1;
; #pragma unroll
;                     for (int j = 0; j < 4; ++j) { v0[j] = sigmoidf_(g0[j]) * acc[ai][bj][m][0][j]; v1[j] = sigmoidf_(g1[j]) * acc[ai][bj][m][1][j]; }
;                     const u32x4 mw = *(const u32x4*)(rowp + bj * 128); f32x4 m0, m1; unpack8(mw, m0, m1); v0 += m0; v1 += m1;
;                     __builtin_amdgcn_raw_buffer_store_b128(pack8(v0, v1), rsrc, (unsigned)(((size_t)row * DIN + col0 + bj * 128) * 2), 0, 16  ); }
	v_mov_b64_e32 v[24:25], v[208:209]
	v_mov_b64_e32 v[26:27], v[210:211]
	v_mov_b64_e32 v[28:29], v[212:213]
	v_mov_b64_e32 v[30:31], v[214:215]
	s_mov_b32 s100, 0xbfb8aa3b
	v_lshlrev_b32_e32 v242, 16, v26
	v_and_b32_e32 v243, 0xffff0000, v26
	v_lshlrev_b32_e32 v244, 16, v24
	v_and_b32_e32 v245, 0xffff0000, v24
	v_lshlrev_b32_e32 v246, 16, v25
	v_and_b32_e32 v247, 0xffff0000, v25
	v_lshlrev_b32_e32 v248, 16, v27
	v_and_b32_e32 v249, 0xffff0000, v27
	v_pk_mul_f32 v[242:243], v[242:243], s[100:101] op_sel_hi:[1,0]
	v_pk_mul_f32 v[244:245], v[244:245], s[100:101] op_sel_hi:[1,0]
	v_pk_mul_f32 v[246:247], v[246:247], s[100:101] op_sel_hi:[1,0]
	v_pk_mul_f32 v[248:249], v[248:249], s[100:101] op_sel_hi:[1,0]
	v_exp_f32_e32 v242, v242
	v_exp_f32_e32 v243, v243
	v_exp_f32_e32 v244, v244
	v_exp_f32_e32 v245, v245
	v_exp_f32_e32 v246, v246
	v_exp_f32_e32 v247, v247
	v_exp_f32_e32 v248, v248
	v_exp_f32_e32 v249, v249
	s_nop 0
	v_pk_add_f32 v[242:243], v[242:243], 1.0 op_sel_hi:[1,0]
	v_pk_add_f32 v[244:245], v[244:245], 1.0 op_sel_hi:[1,0]
	v_pk_add_f32 v[246:247], v[246:247], 1.0 op_sel_hi:[1,0]
	v_pk_add_f32 v[248:249], v[248:249], 1.0 op_sel_hi:[1,0]
	v_rcp_f32_e32 v250, v242
	v_rcp_f32_e32 v251, v243
	s_nop 0
	v_pk_fma_f32 v[252:253], v[242:243], v[250:251], 1.0 op_sel_hi:[1,1,0] neg_lo:[1,0,0] neg_hi:[1,0,0]
	v_pk_fma_f32 v[250:251], v[252:253], v[250:251], v[250:251]
	v_pk_fma_f32 v[252:253], v[242:243], v[250:251], 1.0 op_sel_hi:[1,1,0] neg_lo:[1,0,0] neg_hi:[1,0,0]
	v_pk_fma_f32 v[254:255], v[252:253], v[250:251], v[250:251]
	v_pk_fma_f32 v[252:253], v[242:243], v[254:255], 1.0 op_sel_hi:[1,1,0] neg_lo:[1,0,0] neg_hi:[1,0,0]
	v_pk_fma_f32 v[254:255], v[252:253], v[250:251], v[254:255]
	v_div_fixup_f32 v242, v254, v242, 1.0
	v_div_fixup_f32 v243, v255, v243, 1.0
	v_rcp_f32_e32 v250, v244
	v_rcp_f32_e32 v251, v245
	s_nop 0
	v_pk_fma_f32 v[252:253], v[244:245], v[250:251], 1.0 op_sel_hi:[1,1,0] neg_lo:[1,0,0] neg_hi:[1,0,0]
	v_pk_fma_f32 v[250:251], v[252:253], v[250:251], v[250:251]
	v_pk_fma_f32 v[252:253], v[244:245], v[250:251], 1.0 op_sel_hi:[1,1,0] neg_lo:[1,0,0] neg_hi:[1,0,0]
	v_pk_fma_f32 v[254:255], v[252:253], v[250:251], v[250:251]
	v_pk_fma_f32 v[252:253], v[244:245], v[254:255], 1.0 op_sel_hi:[1,1,0] neg_lo:[1,0,0] neg_hi:[1,0,0]
	v_pk_fma_f32 v[254:255], v[252:253], v[250:251], v[254:255]
	v_div_fixup_f32 v244, v254, v244, 1.0
	v_div_fixup_f32 v245, v255, v245, 1.0
	v_rcp_f32_e32 v250, v246
	v_rcp_f32_e32 v251, v247
	s_nop 0
	v_pk_fma_f32 v[252:253], v[246:247], v[250:251], 1.0 op_sel_hi:[1,1,0] neg_lo:[1,0,0] neg_hi:[1,0,0]
	v_pk_fma_f32 v[250:251], v[252:253], v[250:251], v[250:251]
	v_pk_fma_f32 v[252:253], v[246:247], v[250:251], 1.0 op_sel_hi:[1,1,0] neg_lo:[1,0,0] neg_hi:[1,0,0]
	v_pk_fma_f32 v[254:255], v[252:253], v[250:251], v[250:251]
	v_pk_fma_f32 v[252:253], v[246:247], v[254:255], 1.0 op_sel_hi:[1,1,0] neg_lo:[1,0,0] neg_hi:[1,0,0]
	v_pk_fma_f32 v[254:255], v[252:253], v[250:251], v[254:255]
	v_div_fixup_f32 v246, v254, v246, 1.0
	v_div_fixup_f32 v247, v255, v247, 1.0
	v_rcp_f32_e32 v250, v248
	v_rcp_f32_e32 v251, v249
	s_nop 0
	v_pk_fma_f32 v[252:253], v[248:249], v[250:251], 1.0 op_sel_hi:[1,1,0] neg_lo:[1,0,0] neg_hi:[1,0,0]
	v_pk_fma_f32 v[250:251], v[252:253], v[250:251], v[250:251]
	v_pk_fma_f32 v[252:253], v[248:249], v[250:251], 1.0 op_sel_hi:[1,1,0] neg_lo:[1,0,0] neg_hi:[1,0,0]
	v_pk_fma_f32 v[254:255], v[252:253], v[250:251], v[250:251]
	v_pk_fma_f32 v[252:253], v[248:249], v[254:255], 1.0 op_sel_hi:[1,1,0] neg_lo:[1,0,0] neg_hi:[1,0,0]
	v_pk_fma_f32 v[254:255], v[252:253], v[250:251], v[254:255]
	v_div_fixup_f32 v248, v254, v248, 1.0
	v_div_fixup_f32 v249, v255, v249, 1.0
	v_lshlrev_b32_e32 v36, 16, v28
	v_and_b32_e32 v37, 0xffff0000, v28
	v_lshlrev_b32_e32 v38, 16, v30
	v_and_b32_e32 v39, 0xffff0000, v30
	v_lshlrev_b32_e32 v30, 16, v31
	v_and_b32_e32 v31, 0xffff0000, v31
	v_lshlrev_b32_e32 v28, 16, v29
	v_and_b32_e32 v29, 0xffff0000, v29
	v_pk_fma_f32 v[20:21], v[20:21], v[244:245], v[36:37]
	v_pk_fma_f32 v[24:25], v[18:19], v[248:249], v[30:31]
	v_pk_fma_f32 v[18:19], v[16:17], v[242:243], v[38:39]
	v_cvt_pk_bf16_f32 v16, v20, v21
	v_pk_fma_f32 v[22:23], v[22:23], v[246:247], v[28:29]
	s_nop 0
	v_cvt_pk_bf16_f32 v17, v22, v23
	v_cvt_pk_bf16_f32 v18, v18, v19
	v_cvt_pk_bf16_f32 v19, v24, v25
	buffer_store_dwordx4 v[16:19], v40, s[20:23], 0 offen offset:256 sc1
	s_nop 1
	v_add_u32_e32 v16, 0x40b0, v158
	v_mad_i64_i32 v[18:19], s[6:7], v16, s77, 0
	v_lshl_add_u64 v[16:17], v[18:19], 1, s[26:27]
	v_lshl_add_u64 v[16:17], v[16:17], 0, v[142:143]
	v_add_co_u32_e32 v20, vcc, s78, v16
	s_nop 1
	v_addc_co_u32_e32 v21, vcc, 0, v17, vcc
	s_waitcnt vmcnt(5)
; __device__ __forceinline__ float sigmoidf_(float x) { return 1.0f / (1.0f + __expf(-x)); }
; __device__ __forceinline__ u32x4 pack8(const f32x4 v0, const f32x4 v1) { u32x4 w; w.x = pk2(v0[0], v0[1]); w.y = pk2(v0[2], v0[3]); w.z = pk2(v1[0], v1[1]); w.w = pk2(v1[2], v1[3]); return w; }
; __device__ __forceinline__ void unpack8(const u32x4 w, f32x4& v0, f32x4& v1) { v0 = (f32x4){bflo(w.x), bfhi(w.x), bflo(w.y), bfhi(w.y)}; v1 = (f32x4){bflo(w.z), bfhi(w.z), bflo(w.w), bfhi(w.w)}; }
;     __device__ __forceinline__ void operator()(const f32x4 (&acc)[2][2][4][2], const Unit& u, int wr, int wc, int fr, int fq) const {
;     ...
;                 const int row = row0 + ai * 128 + m * 16;
;                 const bf16_t* rowp = z + (size_t)row * DIN + col0;
; #pragma unroll
;                 for (int bj = 0; bj < 2; ++bj) {
;                     const u32x4 gw = *(const u32x4*)(rowp + O_GA + bj * 128);
;                     f32x4 g0, g1; unpack8(gw, g0, g1);
;                     f32x4 v0, v1;
; #pragma unroll
;                     for (int j = 0; j < 4; ++j) { v0[j] = sigmoidf_(g0[j]) * acc[ai][bj][m][0][j]; v1[j] = sigmoidf_(g1[j]) * acc[ai][bj][m][1][j]; }
;                     const u32x4 mw = *(const u32x4*)(rowp + bj * 128); f32x4 m0, m1; unpack8(mw, m0, m1); v0 += m0; v1 += m1;
;                     __builtin_amdgcn_raw_buffer_store_b128(pack8(v0, v1), rsrc, (unsigned)(((size_t)row * DIN + col0 + bj * 128) * 2), 0, 16  ); }
	v_mov_b64_e32 v[22:23], v[232:233]
	v_mov_b64_e32 v[24:25], v[234:235]
	v_mov_b64_e32 v[26:27], v[236:237]
	v_mov_b64_e32 v[28:29], v[238:239]
	s_mov_b32 s100, 0xbfb8aa3b
	v_lshlrev_b32_e32 v242, 16, v22
	v_and_b32_e32 v243, 0xffff0000, v22
	v_lshlrev_b32_e32 v244, 16, v24
	v_and_b32_e32 v245, 0xffff0000, v24
	v_lshlrev_b32_e32 v246, 16, v23
	v_and_b32_e32 v247, 0xffff0000, v23
	v_lshlrev_b32_e32 v248, 16, v25
	v_and_b32_e32 v249, 0xffff0000, v25
	v_pk_mul_f32 v[242:243], v[242:243], s[100:101] op_sel_hi:[1,0]
	v_pk_mul_f32 v[244:245], v[244:245], s[100:101] op_sel_hi:[1,0]
	v_pk_mul_f32 v[246:247], v[246:247], s[100:101] op_sel_hi:[1,0]
	v_pk_mul_f32 v[248:249], v[248:249], s[100:101] op_sel_hi:[1,0]
	v_exp_f32_e32 v242, v242
	v_exp_f32_e32 v243, v243
	v_exp_f32_e32 v244, v244
	v_exp_f32_e32 v245, v245
	v_exp_f32_e32 v246, v246
	v_exp_f32_e32 v247, v247
	v_exp_f32_e32 v248, v248
	v_exp_f32_e32 v249, v249
	s_nop 0
	v_pk_add_f32 v[242:243], v[242:243], 1.0 op_sel_hi:[1,0]
	v_pk_add_f32 v[244:245], v[244:245], 1.0 op_sel_hi:[1,0]
	v_pk_add_f32 v[246:247], v[246:247], 1.0 op_sel_hi:[1,0]
	v_pk_add_f32 v[248:249], v[248:249], 1.0 op_sel_hi:[1,0]
	v_rcp_f32_e32 v250, v242
	v_rcp_f32_e32 v251, v243
	s_nop 0
	v_pk_fma_f32 v[252:253], v[242:243], v[250:251], 1.0 op_sel_hi:[1,1,0] neg_lo:[1,0,0] neg_hi:[1,0,0]
	v_pk_fma_f32 v[250:251], v[252:253], v[250:251], v[250:251]
	v_pk_fma_f32 v[252:253], v[242:243], v[250:251], 1.0 op_sel_hi:[1,1,0] neg_lo:[1,0,0] neg_hi:[1,0,0]
	v_pk_fma_f32 v[254:255], v[252:253], v[250:251], v[250:251]
	v_pk_fma_f32 v[252:253], v[242:243], v[254:255], 1.0 op_sel_hi:[1,1,0] neg_lo:[1,0,0] neg_hi:[1,0,0]
	v_pk_fma_f32 v[254:255], v[252:253], v[250:251], v[254:255]
	v_div_fixup_f32 v242, v254, v242, 1.0
	v_div_fixup_f32 v243, v255, v243, 1.0
	v_rcp_f32_e32 v250, v244
	v_rcp_f32_e32 v251, v245
	s_nop 0
	v_pk_fma_f32 v[252:253], v[244:245], v[250:251], 1.0 op_sel_hi:[1,1,0] neg_lo:[1,0,0] neg_hi:[1,0,0]
	v_pk_fma_f32 v[250:251], v[252:253], v[250:251], v[250:251]
	v_pk_fma_f32 v[252:253], v[244:245], v[250:251], 1.0 op_sel_hi:[1,1,0] neg_lo:[1,0,0] neg_hi:[1,0,0]
	v_pk_fma_f32 v[254:255], v[252:253], v[250:251], v[250:251]
	v_pk_fma_f32 v[252:253], v[244:245], v[254:255], 1.0 op_sel_hi:[1,1,0] neg_lo:[1,0,0] neg_hi:[1,0,0]
	v_pk_fma_f32 v[254:255], v[252:253], v[250:251], v[254:255]
	v_div_fixup_f32 v244, v254, v244, 1.0
	v_div_fixup_f32 v245, v255, v245, 1.0
	v_rcp_f32_e32 v250, v246
	v_rcp_f32_e32 v251, v247
	s_nop 0
	v_pk_fma_f32 v[252:253], v[246:247], v[250:251], 1.0 op_sel_hi:[1,1,0] neg_lo:[1,0,0] neg_hi:[1,0,0]
	v_pk_fma_f32 v[250:251], v[252:253], v[250:251], v[250:251]
	v_pk_fma_f32 v[252:253], v[246:247], v[250:251], 1.0 op_sel_hi:[1,1,0] neg_lo:[1,0,0] neg_hi:[1,0,0]
	v_pk_fma_f32 v[254:255], v[252:253], v[250:251], v[250:251]
	v_pk_fma_f32 v[252:253], v[246:247], v[254:255], 1.0 op_sel_hi:[1,1,0] neg_lo:[1,0,0] neg_hi:[1,0,0]
	v_pk_fma_f32 v[254:255], v[252:253], v[250:251], v[254:255]
	v_div_fixup_f32 v246, v254, v246, 1.0
	v_div_fixup_f32 v247, v255, v247, 1.0
	v_rcp_f32_e32 v250, v248
	v_rcp_f32_e32 v251, v249
	s_nop 0
	v_pk_fma_f32 v[252:253], v[248:249], v[250:251], 1.0 op_sel_hi:[1,1,0] neg_lo:[1,0,0] neg_hi:[1,0,0]
	v_pk_fma_f32 v[250:251], v[252:253], v[250:251], v[250:251]
	v_pk_fma_f32 v[252:253], v[248:249], v[250:251], 1.0 op_sel_hi:[1,1,0] neg_lo:[1,0,0] neg_hi:[1,0,0]
	v_pk_fma_f32 v[254:255], v[252:253], v[250:251], v[250:251]
	v_pk_fma_f32 v[252:253], v[248:249], v[254:255], 1.0 op_sel_hi:[1,1,0] neg_lo:[1,0,0] neg_hi:[1,0,0]
	v_pk_fma_f32 v[254:255], v[252:253], v[250:251], v[254:255]
	v_div_fixup_f32 v248, v254, v248, 1.0
	v_div_fixup_f32 v249, v255, v249, 1.0
	v_lshlrev_b32_e32 v34, 16, v26
	v_and_b32_e32 v35, 0xffff0000, v26
	v_lshlrev_b32_e32 v36, 16, v28
	v_and_b32_e32 v37, 0xffff0000, v28
	v_lshlrev_b32_e32 v28, 16, v29
	v_and_b32_e32 v29, 0xffff0000, v29
	v_lshlrev_b32_e32 v26, 16, v27
	v_and_b32_e32 v27, 0xffff0000, v27
	v_pk_fma_f32 v[12:13], v[12:13], v[242:243], v[34:35]
	v_pk_fma_f32 v[22:23], v[10:11], v[248:249], v[28:29]
	v_pk_fma_f32 v[10:11], v[8:9], v[244:245], v[36:37]
	v_add_lshl_u32 v24, v140, v18, 1
	v_pk_fma_f32 v[14:15], v[14:15], v[246:247], v[26:27]
	v_cvt_pk_bf16_f32 v8, v12, v13
	s_nop 0
	v_cvt_pk_bf16_f32 v9, v14, v15
	v_cvt_pk_bf16_f32 v10, v10, v11
	v_cvt_pk_bf16_f32 v11, v22, v23
	buffer_store_dwordx4 v[8:11], v24, s[20:23], 0 offen sc1
	s_nop 0
	s_waitcnt vmcnt(3)
; __device__ __forceinline__ float sigmoidf_(float x) { return 1.0f / (1.0f + __expf(-x)); }
; __device__ __forceinline__ u32x4 pack8(const f32x4 v0, const f32x4 v1) { u32x4 w; w.x = pk2(v0[0], v0[1]); w.y = pk2(v0[2], v0[3]); w.z = pk2(v1[0], v1[1]); w.w = pk2(v1[2], v1[3]); return w; }
; __device__ __forceinline__ void unpack8(const u32x4 w, f32x4& v0, f32x4& v1) { v0 = (f32x4){bflo(w.x), bfhi(w.x), bflo(w.y), bfhi(w.y)}; v1 = (f32x4){bflo(w.z), bfhi(w.z), bflo(w.w), bfhi(w.w)}; }
;     __device__ __forceinline__ void operator()(const f32x4 (&acc)[2][2][4][2], const Unit& u, int wr, int wc, int fr, int fq) const {
;     ...
;                 const int row = row0 + ai * 128 + m * 16;
;                 const bf16_t* rowp = z + (size_t)row * DIN + col0;
; #pragma unroll
;                 for (int bj = 0; bj < 2; ++bj) {
;                     const u32x4 gw = *(const u32x4*)(rowp + O_GA + bj * 128);
;                     f32x4 g0, g1; unpack8(gw, g0, g1);
;                     f32x4 v0, v1;
; #pragma unroll
;                     for (int j = 0; j < 4; ++j) { v0[j] = sigmoidf_(g0[j]) * acc[ai][bj][m][0][j]; v1[j] = sigmoidf_(g1[j]) * acc[ai][bj][m][1][j]; }
;                     const u32x4 mw = *(const u32x4*)(rowp + bj * 128); f32x4 m0, m1; unpack8(mw, m0, m1); v0 += m0; v1 += m1;
;                     __builtin_amdgcn_raw_buffer_store_b128(pack8(v0, v1), rsrc, (unsigned)(((size_t)row * DIN + col0 + bj * 128) * 2), 0, 16  ); }
;             }
;         asm volatile("s_waitcnt vmcnt(0)" ::: "memory");
;         if (fr == 0 && fq == 0) (void)__hip_atomic_fetch_add(ready + 64 * (pm_off + u.pm), 1u, __ATOMIC_RELAXED, __HIP_MEMORY_SCOPE_AGENT);
	v_mov_b64_e32 v[8:9], v[200:201]
	v_mov_b64_e32 v[10:11], v[202:203]
	v_mov_b64_e32 v[12:13], v[204:205]
	v_mov_b64_e32 v[14:15], v[206:207]
	s_mov_b32 s100, 0xbfb8aa3b
	v_lshlrev_b32_e32 v242, 16, v10
	v_and_b32_e32 v243, 0xffff0000, v10
	v_lshlrev_b32_e32 v244, 16, v8
	v_and_b32_e32 v245, 0xffff0000, v8
	v_lshlrev_b32_e32 v246, 16, v9
	v_and_b32_e32 v247, 0xffff0000, v9
	v_lshlrev_b32_e32 v248, 16, v11
	v_and_b32_e32 v249, 0xffff0000, v11
	v_pk_mul_f32 v[242:243], v[242:243], s[100:101] op_sel_hi:[1,0]
	v_pk_mul_f32 v[244:245], v[244:245], s[100:101] op_sel_hi:[1,0]
	v_pk_mul_f32 v[246:247], v[246:247], s[100:101] op_sel_hi:[1,0]
	v_pk_mul_f32 v[248:249], v[248:249], s[100:101] op_sel_hi:[1,0]
	v_exp_f32_e32 v242, v242
	v_exp_f32_e32 v243, v243
	v_exp_f32_e32 v244, v244
	v_exp_f32_e32 v245, v245
	v_exp_f32_e32 v246, v246
	v_exp_f32_e32 v247, v247
	v_exp_f32_e32 v248, v248
	v_exp_f32_e32 v249, v249
	s_nop 0
	v_pk_add_f32 v[242:243], v[242:243], 1.0 op_sel_hi:[1,0]
	v_pk_add_f32 v[244:245], v[244:245], 1.0 op_sel_hi:[1,0]
	v_pk_add_f32 v[246:247], v[246:247], 1.0 op_sel_hi:[1,0]
	v_pk_add_f32 v[248:249], v[248:249], 1.0 op_sel_hi:[1,0]
	v_rcp_f32_e32 v250, v242
	v_rcp_f32_e32 v251, v243
	s_nop 0
	v_pk_fma_f32 v[252:253], v[242:243], v[250:251], 1.0 op_sel_hi:[1,1,0] neg_lo:[1,0,0] neg_hi:[1,0,0]
	v_pk_fma_f32 v[250:251], v[252:253], v[250:251], v[250:251]
	v_pk_fma_f32 v[252:253], v[242:243], v[250:251], 1.0 op_sel_hi:[1,1,0] neg_lo:[1,0,0] neg_hi:[1,0,0]
	v_pk_fma_f32 v[254:255], v[252:253], v[250:251], v[250:251]
	v_pk_fma_f32 v[252:253], v[242:243], v[254:255], 1.0 op_sel_hi:[1,1,0] neg_lo:[1,0,0] neg_hi:[1,0,0]
	v_pk_fma_f32 v[254:255], v[252:253], v[250:251], v[254:255]
	v_div_fixup_f32 v242, v254, v242, 1.0
	v_div_fixup_f32 v243, v255, v243, 1.0
	v_rcp_f32_e32 v250, v244
	v_rcp_f32_e32 v251, v245
	s_nop 0
	v_pk_fma_f32 v[252:253], v[244:245], v[250:251], 1.0 op_sel_hi:[1,1,0] neg_lo:[1,0,0] neg_hi:[1,0,0]
	v_pk_fma_f32 v[250:251], v[252:253], v[250:251], v[250:251]
	v_pk_fma_f32 v[252:253], v[244:245], v[250:251], 1.0 op_sel_hi:[1,1,0] neg_lo:[1,0,0] neg_hi:[1,0,0]
	v_pk_fma_f32 v[254:255], v[252:253], v[250:251], v[250:251]
	v_pk_fma_f32 v[252:253], v[244:245], v[254:255], 1.0 op_sel_hi:[1,1,0] neg_lo:[1,0,0] neg_hi:[1,0,0]
	v_pk_fma_f32 v[254:255], v[252:253], v[250:251], v[254:255]
	v_div_fixup_f32 v244, v254, v244, 1.0
	v_div_fixup_f32 v245, v255, v245, 1.0
	v_rcp_f32_e32 v250, v246
	v_rcp_f32_e32 v251, v247
	s_nop 0
	v_pk_fma_f32 v[252:253], v[246:247], v[250:251], 1.0 op_sel_hi:[1,1,0] neg_lo:[1,0,0] neg_hi:[1,0,0]
	v_pk_fma_f32 v[250:251], v[252:253], v[250:251], v[250:251]
	v_pk_fma_f32 v[252:253], v[246:247], v[250:251], 1.0 op_sel_hi:[1,1,0] neg_lo:[1,0,0] neg_hi:[1,0,0]
	v_pk_fma_f32 v[254:255], v[252:253], v[250:251], v[250:251]
	v_pk_fma_f32 v[252:253], v[246:247], v[254:255], 1.0 op_sel_hi:[1,1,0] neg_lo:[1,0,0] neg_hi:[1,0,0]
	v_pk_fma_f32 v[254:255], v[252:253], v[250:251], v[254:255]
	v_div_fixup_f32 v246, v254, v246, 1.0
	v_div_fixup_f32 v247, v255, v247, 1.0
	v_rcp_f32_e32 v250, v248
	v_rcp_f32_e32 v251, v249
	s_nop 0
	v_pk_fma_f32 v[252:253], v[248:249], v[250:251], 1.0 op_sel_hi:[1,1,0] neg_lo:[1,0,0] neg_hi:[1,0,0]
	v_pk_fma_f32 v[250:251], v[252:253], v[250:251], v[250:251]
	v_pk_fma_f32 v[252:253], v[248:249], v[250:251], 1.0 op_sel_hi:[1,1,0] neg_lo:[1,0,0] neg_hi:[1,0,0]
	v_pk_fma_f32 v[254:255], v[252:253], v[250:251], v[250:251]
	v_pk_fma_f32 v[252:253], v[248:249], v[254:255], 1.0 op_sel_hi:[1,1,0] neg_lo:[1,0,0] neg_hi:[1,0,0]
	v_pk_fma_f32 v[254:255], v[252:253], v[250:251], v[254:255]
	v_div_fixup_f32 v248, v254, v248, 1.0
	v_div_fixup_f32 v249, v255, v249, 1.0
	v_lshlrev_b32_e32 v20, 16, v12
	v_and_b32_e32 v21, 0xffff0000, v12
	v_lshlrev_b32_e32 v22, 16, v14
	v_and_b32_e32 v23, 0xffff0000, v14
	v_lshlrev_b32_e32 v14, 16, v15
	v_and_b32_e32 v15, 0xffff0000, v15
	v_lshlrev_b32_e32 v12, 16, v13
	v_and_b32_e32 v13, 0xffff0000, v13
	v_pk_fma_f32 v[4:5], v[4:5], v[244:245], v[20:21]
	v_pk_fma_f32 v[8:9], v[2:3], v[248:249], v[14:15]
	v_pk_fma_f32 v[2:3], v[0:1], v[242:243], v[22:23]
	v_pk_fma_f32 v[6:7], v[6:7], v[246:247], v[12:13]
	v_cvt_pk_bf16_f32 v0, v4, v5
	s_nop 0
	v_cvt_pk_bf16_f32 v1, v6, v7
	v_cvt_pk_bf16_f32 v2, v2, v3
	v_cvt_pk_bf16_f32 v3, v8, v9
	buffer_store_dwordx4 v[0:3], v24, s[20:23], 0 offen offset:256 sc1
	s_waitcnt vmcnt(0)
	s_and_saveexec_b64 s[12:13], s[10:11]
	s_cbranch_execz .LBB0_715
	s_mov_b64 s[14:15], exec
	v_mbcnt_lo_u32_b32 v0, s14, 0
	v_mbcnt_hi_u32_b32 v0, s15, v0
	v_cmp_eq_u32_e32 vcc, 0, v0
	s_and_b64 s[6:7], exec, vcc
	s_mov_b64 exec, s[6:7]
	s_cbranch_execz .LBB0_715
	s_lshl_b32 s6, s79, 6
	s_addk_i32 s6, 0x1000
	s_ashr_i32 s7, s6, 31
	s_lshl_b64 s[6:7], s[6:7], 2
	s_add_u32 s6, s34, s6
	s_addc_u32 s7, s35, s7
	s_bcnt1_i32_b64 s8, s[14:15]
	v_mov_b32_e32 v0, s8
	global_atomic_add v131, v0, s[6:7]
	s_branch .LBB0_715

; __device__ __forceinline__ unsigned pk2(float lo, float hi) { unsigned r; asm volatile("v_cvt_pk_bf16_f32 %0, %1, %2" : "=v"(r) : "v"(lo), "v"(hi)); return r; }
;     __device__ __forceinline__ void operator()(const f32x4 (&acc)[2][2][4][2], const Unit& u, int wr, int wc, int fr, int fq) const {
;     ...
;         const float* xo = (u.pm < 64) ? xoldA : (xoldB - (size_t)T_P * DM);
; #pragma unroll
;         for (int ai = 0; ai < 2; ++ai)
; #pragma unroll
;             for (int m = 0; m < 4; ++m) {
;                 const int row = row0 + ai * 128 + m * 16; const size_t ro = (size_t)row * DM + col0;
;                 float s = 0.f;
; #pragma unroll
;                 for (int bj = 0; bj < 2; ++bj)
; #pragma unroll
;                     for (int n = 0; n < 2; ++n) {
;                         const size_t o = ro + bj * 128 + n * 16;
;                         const f32x4 xn = *(const f32x4*)(xo + o) + acc[ai][bj][m][n];
;                         *(f32x4*)(xf + o) = xn;
;                         u32x2 w; w.x = pk2(xn[0], xn[1]); w.y = pk2(xn[2], xn[3]); *(u32x2*)(xb + o) = w;
;                         s += (xn[0] * xn[0] + xn[1] * xn[1]) + (xn[2] * xn[2] + xn[3] * xn[3]);
;                     }
;                 s += __shfl_xor(s, 16); s += __shfl_xor(s, 32);
;                 if (fq == 0) ssq[(size_t)row * 16 + u.pn * 4 + wc] = s;
.LBB0_781:
	v_lshl_add_u32 v146, s83, 8, v148
	v_lshl_or_b32 v142, s56, 8, v150
	v_ashrrev_i32_e32 v147, 31, v146
	v_ashrrev_i32_e32 v143, 31, v142
	v_lshlrev_b64 v[154:155], 10, v[146:147]
	s_cmp_lt_i32 s83, 64
	v_lshl_add_u64 v[158:159], v[154:155], 0, v[142:143]
	s_cselect_b32 s17, s23, -1
	s_cselect_b32 s16, s22, 0xfc000000
	v_lshlrev_b64 v[160:161], 2, v[158:159]
	v_lshl_add_u64 v[162:163], s[16:17], 0, v[160:161]
	v_subrev_u32_e32 v172, s16, v162
	v_add_u32_e32 v173, 0x0, v172
	global_load_dwordx4 v[174:177], v173, s[16:17]
	v_add_u32_e32 v173, 0x40, v172
	global_load_dwordx4 v[178:181], v173, s[16:17]
	v_add_u32_e32 v173, 0x200, v172
	global_load_dwordx4 v[182:185], v173, s[16:17]
	v_add_u32_e32 v173, 0x240, v172
	global_load_dwordx4 v[186:189], v173, s[16:17]
	v_add_u32_e32 v173, 0x10000, v172
	global_load_dwordx4 v[190:193], v173, s[16:17]
	v_add_u32_e32 v173, 0x10040, v172
	global_load_dwordx4 v[194:197], v173, s[16:17]
	v_add_u32_e32 v173, 0x10200, v172
	global_load_dwordx4 v[198:201], v173, s[16:17]
	v_add_u32_e32 v173, 0x10240, v172
	global_load_dwordx4 v[202:205], v173, s[16:17]
	v_add_u32_e32 v173, 0x20000, v172
	global_load_dwordx4 v[206:209], v173, s[16:17]
	v_add_u32_e32 v173, 0x20040, v172
	global_load_dwordx4 v[210:213], v173, s[16:17]
	v_add_u32_e32 v173, 0x20200, v172
	global_load_dwordx4 v[214:217], v173, s[16:17]
	v_add_u32_e32 v173, 0x20240, v172
	global_load_dwordx4 v[218:221], v173, s[16:17]
	v_add_u32_e32 v173, 0x30000, v172
	global_load_dwordx4 v[232:235], v173, s[16:17]
	v_add_u32_e32 v173, 0x30040, v172
	global_load_dwordx4 v[236:239], v173, s[16:17]
	v_add_u32_e32 v173, 0x30200, v172
	global_load_dwordx4 v[240:243], v173, s[16:17]
	v_add_u32_e32 v173, 0x30240, v172
	global_load_dwordx4 v[244:247], v173, s[16:17]
	v_add_u32_e32 v173, 0x80000, v172
	global_load_dwordx4 v[248:251], v173, s[16:17]
	v_add_u32_e32 v173, 0x80040, v172
	global_load_dwordx4 v[252:255], v173, s[16:17]
	v_lshl_add_u64 v[164:165], v[158:159], 1, s[24:25]
	v_lshl_add_u64 v[170:171], s[28:29], 0, v[160:161]
	v_xor_b32_e32 v153, 32, v152
	s_lshl_b32 s56, s56, 2
	s_ashr_i32 s57, s56, 31
	s_waitcnt vmcnt(17)
	v_mov_b64_e32 v[154:155], v[174:175]
	v_mov_b64_e32 v[156:157], v[176:177]
	v_add_u32_e32 v173, 0x80200, v172
	global_load_dwordx4 v[174:177], v173, s[16:17]
	v_pk_add_f32 v[126:127], v[126:127], v[156:157]
	v_pk_add_f32 v[124:125], v[124:125], v[154:155]
	global_store_dwordx4 v[170:171], v[124:127], off
	v_cvt_pk_bf16_f32 v154, v124, v125
	v_cvt_pk_bf16_f32 v155, v126, v127
	global_store_dwordx2 v[164:165], v[154:155], off
	s_waitcnt vmcnt(19)
	v_mov_b64_e32 v[154:155], v[178:179]
	v_mov_b64_e32 v[156:157], v[180:181]
	v_add_u32_e32 v173, 0x80240, v172
	global_load_dwordx4 v[178:181], v173, s[16:17]
	v_pk_add_f32 v[122:123], v[122:123], v[156:157]
	v_pk_add_f32 v[120:121], v[120:121], v[154:155]
	global_store_dwordx4 v[170:171], v[120:123], off offset:64
	v_cvt_pk_bf16_f32 v154, v120, v121
	v_cvt_pk_bf16_f32 v155, v122, v123
	global_store_dwordx2 v[164:165], v[154:155], off offset:32
	s_waitcnt vmcnt(21)
	v_mov_b64_e32 v[154:155], v[182:183]
	v_mov_b64_e32 v[156:157], v[184:185]
	v_add_u32_e32 v173, 0x90000, v172
	global_load_dwordx4 v[182:185], v173, s[16:17]
	v_pk_add_f32 v[156:157], v[118:119], v[156:157]
	v_pk_add_f32 v[154:155], v[116:117], v[154:155]
	global_store_dwordx4 v[170:171], v[154:157], off offset:512
	v_cvt_pk_bf16_f32 v116, v154, v155
	v_cvt_pk_bf16_f32 v117, v156, v157
	global_store_dwordx2 v[164:165], v[116:117], off offset:256
	v_mul_f32_e32 v118, v125, v125
	v_mul_f32_e32 v119, v127, v127
	v_fmac_f32_e32 v118, v124, v124
	v_fmac_f32_e32 v119, v126, v126
	v_add_f32_e32 v118, v118, v119
	v_mul_f32_e32 v119, v121, v121
	v_mul_f32_e32 v121, v123, v123
	v_fmac_f32_e32 v119, v120, v120
	v_fmac_f32_e32 v121, v122, v122
	v_add_f32_e32 v119, v119, v121
	v_add_f32_e32 v118, v118, v119
	v_mul_f32_e32 v119, v155, v155
	v_mul_f32_e32 v120, v157, v157
	v_fmac_f32_e32 v119, v154, v154
	v_fmac_f32_e32 v120, v156, v156
	v_add_f32_e32 v119, v119, v120
	v_and_b32_e32 v117, 64, v152
	v_add_f32_e32 v122, v118, v119
	v_xor_b32_e32 v116, 16, v152
	v_add_u32_e32 v117, 64, v117
	v_cmp_lt_i32_e32 vcc, v116, v117
	s_waitcnt vmcnt(23)
	v_mov_b64_e32 v[158:159], v[186:187]
	v_mov_b64_e32 v[160:161], v[188:189]
	v_add_u32_e32 v173, 0x90040, v172
	global_load_dwordx4 v[186:189], v173, s[16:17]
	v_pk_add_f32 v[120:121], v[114:115], v[160:161]
	v_pk_add_f32 v[118:119], v[112:113], v[158:159]
	v_mul_f32_e32 v113, v121, v121
	v_mul_f32_e32 v112, v119, v119
	v_fmac_f32_e32 v112, v118, v118
	v_fmac_f32_e32 v113, v120, v120
	v_cndmask_b32_e32 v116, v152, v116, vcc
	v_add_f32_e32 v112, v112, v113
	v_lshlrev_b32_e32 v116, 2, v116
	v_add_f32_e32 v112, v122, v112
	ds_bpermute_b32 v113, v116, v112
	v_cmp_lt_i32_e32 vcc, v153, v117
	global_store_dwordx4 v[170:171], v[118:121], off offset:576
	s_waitcnt lgkmcnt(0)
	v_add_f32_e32 v112, v112, v113
	v_cndmask_b32_e32 v114, v152, v153, vcc
	v_lshlrev_b32_e32 v114, 2, v114
	ds_bpermute_b32 v113, v114, v112
	v_cvt_pk_bf16_f32 v118, v118, v119
	v_cvt_pk_bf16_f32 v119, v120, v121
	global_store_dwordx2 v[164:165], v[118:119], off offset:288
	s_and_saveexec_b64 s[58:59], s[12:13]
	s_cbranch_execz .LBB0_783
	s_waitcnt lgkmcnt(0)
	v_add_f32_e32 v115, v112, v113
	v_lshlrev_b64 v[112:113], 6, v[146:147]
	v_lshl_add_u64 v[112:113], s[26:27], 0, v[112:113]
	v_lshl_add_u64 v[112:113], s[56:57], 2, v[112:113]
	s_lshl_b32 s36, s74, 2
	v_lshl_add_u64 v[112:113], v[112:113], 0, s[36:37]
	global_store_dword v[112:113], v115, off
; __device__ __forceinline__ unsigned pk2(float lo, float hi) { unsigned r; asm volatile("v_cvt_pk_bf16_f32 %0, %1, %2" : "=v"(r) : "v"(lo), "v"(hi)); return r; }
;     __device__ __forceinline__ void operator()(const f32x4 (&acc)[2][2][4][2], const Unit& u, int wr, int wc, int fr, int fq) const {
;     ...
;         const float* xo = (u.pm < 64) ? xoldA : (xoldB - (size_t)T_P * DM);
; #pragma unroll
;         for (int ai = 0; ai < 2; ++ai)
; #pragma unroll
;             for (int m = 0; m < 4; ++m) {
;                 const int row = row0 + ai * 128 + m * 16; const size_t ro = (size_t)row * DM + col0;
;                 float s = 0.f;
; #pragma unroll
;                 for (int bj = 0; bj < 2; ++bj)
; #pragma unroll
;                     for (int n = 0; n < 2; ++n) {
;                         const size_t o = ro + bj * 128 + n * 16;
;                         const f32x4 xn = *(const f32x4*)(xo + o) + acc[ai][bj][m][n];
;                         *(f32x4*)(xf + o) = xn;
;                         u32x2 w; w.x = pk2(xn[0], xn[1]); w.y = pk2(xn[2], xn[3]); *(u32x2*)(xb + o) = w;
;                         s += (xn[0] * xn[0] + xn[1] * xn[1]) + (xn[2] * xn[2] + xn[3] * xn[3]);
;                     }
;                 s += __shfl_xor(s, 16); s += __shfl_xor(s, 32);
;                 if (fq == 0) ssq[(size_t)row * 16 + u.pn * 4 + wc] = s;
.LBB0_783:
	s_or_b64 exec, exec, s[58:59]
	v_or_b32_e32 v112, 16, v146
	s_waitcnt lgkmcnt(0)
	v_ashrrev_i32_e32 v113, 31, v112
	v_lshlrev_b64 v[118:119], 10, v[112:113]
	v_lshl_add_u64 v[122:123], v[118:119], 0, v[142:143]
	v_lshlrev_b64 v[124:125], 2, v[122:123]
	v_lshl_add_u64 v[126:127], s[16:17], 0, v[124:125]
	v_lshl_add_u64 v[122:123], v[122:123], 1, s[24:25]
	v_lshl_add_u64 v[124:125], s[28:29], 0, v[124:125]
	s_waitcnt vmcnt(25)
	v_mov_b64_e32 v[118:119], v[190:191]
	v_mov_b64_e32 v[120:121], v[192:193]
	v_add_u32_e32 v173, 0x90200, v172
	global_load_dwordx4 v[190:193], v173, s[16:17]
	v_pk_add_f32 v[110:111], v[110:111], v[120:121]
	v_pk_add_f32 v[108:109], v[108:109], v[118:119]
	global_store_dwordx4 v[124:125], v[108:111], off
	v_cvt_pk_bf16_f32 v118, v108, v109
	v_cvt_pk_bf16_f32 v119, v110, v111
	global_store_dwordx2 v[122:123], v[118:119], off
	v_mul_f32_e32 v109, v109, v109
	v_mul_f32_e32 v111, v111, v111
	v_fmac_f32_e32 v109, v108, v108
	v_fmac_f32_e32 v111, v110, v110
	v_add_f32_e32 v108, v109, v111
	s_waitcnt vmcnt(27)
	v_mov_b64_e32 v[118:119], v[194:195]
	v_mov_b64_e32 v[120:121], v[196:197]
	v_add_u32_e32 v173, 0x90240, v172
	global_load_dwordx4 v[194:197], v173, s[16:17]
	v_pk_add_f32 v[106:107], v[106:107], v[120:121]
	v_pk_add_f32 v[104:105], v[104:105], v[118:119]
	global_store_dwordx4 v[124:125], v[104:107], off offset:64
	v_cvt_pk_bf16_f32 v118, v104, v105
	v_cvt_pk_bf16_f32 v119, v106, v107
	global_store_dwordx2 v[122:123], v[118:119], off offset:32
	v_mul_f32_e32 v105, v105, v105
	v_mul_f32_e32 v107, v107, v107
	v_fmac_f32_e32 v105, v104, v104
	v_fmac_f32_e32 v107, v106, v106
	v_add_f32_e32 v104, v105, v107
	v_add_f32_e32 v104, v108, v104
	s_waitcnt vmcnt(29)
	v_mov_b64_e32 v[118:119], v[198:199]
	v_mov_b64_e32 v[120:121], v[200:201]
	v_add_u32_e32 v173, 0xa0000, v172
	global_load_dwordx4 v[198:201], v173, s[16:17]
	v_pk_add_f32 v[102:103], v[102:103], v[120:121]
	v_pk_add_f32 v[100:101], v[100:101], v[118:119]
	global_store_dwordx4 v[124:125], v[100:103], off offset:512
	v_cvt_pk_bf16_f32 v118, v100, v101
	v_cvt_pk_bf16_f32 v119, v102, v103
	global_store_dwordx2 v[122:123], v[118:119], off offset:256
	v_mul_f32_e32 v101, v101, v101
	v_mul_f32_e32 v103, v103, v103
	v_fmac_f32_e32 v101, v100, v100
	v_fmac_f32_e32 v103, v102, v102
	v_add_f32_e32 v100, v101, v103
	v_add_f32_e32 v102, v104, v100
	s_waitcnt vmcnt(31)
	v_mov_b64_e32 v[118:119], v[202:203]
	v_mov_b64_e32 v[120:121], v[204:205]
	v_add_u32_e32 v173, 0xa0040, v172
	global_load_dwordx4 v[202:205], v173, s[16:17]
	v_pk_add_f32 v[100:101], v[98:99], v[120:121]
	v_pk_add_f32 v[98:99], v[96:97], v[118:119]
	v_mul_f32_e32 v97, v101, v101
	v_mul_f32_e32 v96, v99, v99
	v_fmac_f32_e32 v96, v98, v98
	v_fmac_f32_e32 v97, v100, v100
	v_add_f32_e32 v96, v96, v97
	v_add_f32_e32 v96, v102, v96
	ds_bpermute_b32 v97, v116, v96
	global_store_dwordx4 v[124:125], v[98:101], off offset:576
	s_waitcnt lgkmcnt(0)
	v_add_f32_e32 v96, v96, v97
	ds_bpermute_b32 v97, v114, v96
	v_cvt_pk_bf16_f32 v98, v98, v99
	v_cvt_pk_bf16_f32 v99, v100, v101
	global_store_dwordx2 v[122:123], v[98:99], off offset:288
	s_and_saveexec_b64 s[58:59], s[12:13]
	s_cbranch_execz .LBB0_785
	s_waitcnt lgkmcnt(0)
	v_add_f32_e32 v98, v96, v97
	v_lshlrev_b64 v[96:97], 6, v[112:113]
	v_lshl_add_u64 v[96:97], s[26:27], 0, v[96:97]
	v_lshl_add_u64 v[96:97], s[56:57], 2, v[96:97]
	s_lshl_b32 s36, s74, 2
	v_lshl_add_u64 v[96:97], v[96:97], 0, s[36:37]
	global_store_dword v[96:97], v98, off
.LBB0_785:
	s_or_b64 exec, exec, s[58:59]
	v_or_b32_e32 v96, 32, v146
	s_waitcnt lgkmcnt(0)
	v_ashrrev_i32_e32 v97, 31, v96
	v_lshlrev_b64 v[98:99], 10, v[96:97]
	v_lshl_add_u64 v[102:103], v[98:99], 0, v[142:143]
	v_lshlrev_b64 v[104:105], 2, v[102:103]
	v_lshl_add_u64 v[106:107], s[16:17], 0, v[104:105]
	v_lshl_add_u64 v[102:103], v[102:103], 1, s[24:25]
	v_lshl_add_u64 v[104:105], s[28:29], 0, v[104:105]
	s_waitcnt vmcnt(33)
	v_mov_b64_e32 v[98:99], v[206:207]
	v_mov_b64_e32 v[100:101], v[208:209]
	v_add_u32_e32 v173, 0xa0200, v172
	global_load_dwordx4 v[206:209], v173, s[16:17]
	v_pk_add_f32 v[94:95], v[94:95], v[100:101]
	v_pk_add_f32 v[92:93], v[92:93], v[98:99]
	global_store_dwordx4 v[104:105], v[92:95], off
	v_cvt_pk_bf16_f32 v98, v92, v93
	v_cvt_pk_bf16_f32 v99, v94, v95
	global_store_dwordx2 v[102:103], v[98:99], off
	v_mul_f32_e32 v93, v93, v93
	v_mul_f32_e32 v95, v95, v95
	v_fmac_f32_e32 v93, v92, v92
	v_fmac_f32_e32 v95, v94, v94
	v_add_f32_e32 v92, v93, v95
	s_waitcnt vmcnt(35)
	v_mov_b64_e32 v[98:99], v[210:211]
	v_mov_b64_e32 v[100:101], v[212:213]
	v_add_u32_e32 v173, 0xa0240, v172
	global_load_dwordx4 v[210:213], v173, s[16:17]
	v_pk_add_f32 v[90:91], v[90:91], v[100:101]
	v_pk_add_f32 v[88:89], v[88:89], v[98:99]
	global_store_dwordx4 v[104:105], v[88:91], off offset:64
	v_cvt_pk_bf16_f32 v98, v88, v89
	v_cvt_pk_bf16_f32 v99, v90, v91
	global_store_dwordx2 v[102:103], v[98:99], off offset:32
	v_mul_f32_e32 v89, v89, v89
	v_mul_f32_e32 v91, v91, v91
	v_fmac_f32_e32 v89, v88, v88
	v_fmac_f32_e32 v91, v90, v90
	v_add_f32_e32 v88, v89, v91
	v_add_f32_e32 v88, v92, v88
	s_waitcnt vmcnt(37)
	v_mov_b64_e32 v[98:99], v[214:215]
	v_mov_b64_e32 v[100:101], v[216:217]
	v_add_u32_e32 v173, 0xb0000, v172
	global_load_dwordx4 v[214:217], v173, s[16:17]
	v_pk_add_f32 v[86:87], v[86:87], v[100:101]
	v_pk_add_f32 v[84:85], v[84:85], v[98:99]
	global_store_dwordx4 v[104:105], v[84:87], off offset:512
	v_cvt_pk_bf16_f32 v98, v84, v85
	v_cvt_pk_bf16_f32 v99, v86, v87
	global_store_dwordx2 v[102:103], v[98:99], off offset:256
	v_mul_f32_e32 v85, v85, v85
	v_mul_f32_e32 v87, v87, v87
	v_fmac_f32_e32 v85, v84, v84
	v_fmac_f32_e32 v87, v86, v86
	v_add_f32_e32 v84, v85, v87
	v_add_f32_e32 v86, v88, v84
	s_waitcnt vmcnt(39)
	v_mov_b64_e32 v[98:99], v[218:219]
	v_mov_b64_e32 v[100:101], v[220:221]
	v_add_u32_e32 v173, 0xb0040, v172
	global_load_dwordx4 v[218:221], v173, s[16:17]
	v_pk_add_f32 v[84:85], v[82:83], v[100:101]
	v_pk_add_f32 v[82:83], v[80:81], v[98:99]
	v_mul_f32_e32 v81, v85, v85
	v_mul_f32_e32 v80, v83, v83
	v_fmac_f32_e32 v80, v82, v82
	v_fmac_f32_e32 v81, v84, v84
	v_add_f32_e32 v80, v80, v81
	v_add_f32_e32 v80, v86, v80
	ds_bpermute_b32 v81, v116, v80
	global_store_dwordx4 v[104:105], v[82:85], off offset:576
	s_waitcnt lgkmcnt(0)
	v_add_f32_e32 v80, v80, v81
	ds_bpermute_b32 v81, v114, v80
	v_cvt_pk_bf16_f32 v82, v82, v83
	v_cvt_pk_bf16_f32 v83, v84, v85
	global_store_dwordx2 v[102:103], v[82:83], off offset:288
	s_and_saveexec_b64 s[58:59], s[12:13]
	s_cbranch_execz .LBB0_787
	s_waitcnt lgkmcnt(0)
	v_add_f32_e32 v82, v80, v81
	v_lshlrev_b64 v[80:81], 6, v[96:97]
	v_lshl_add_u64 v[80:81], s[26:27], 0, v[80:81]
	v_lshl_add_u64 v[80:81], s[56:57], 2, v[80:81]
	s_lshl_b32 s36, s74, 2
	v_lshl_add_u64 v[80:81], v[80:81], 0, s[36:37]
	global_store_dword v[80:81], v82, off
; __device__ __forceinline__ unsigned pk2(float lo, float hi) { unsigned r; asm volatile("v_cvt_pk_bf16_f32 %0, %1, %2" : "=v"(r) : "v"(lo), "v"(hi)); return r; }
;     __device__ __forceinline__ void operator()(const f32x4 (&acc)[2][2][4][2], const Unit& u, int wr, int wc, int fr, int fq) const {
;     ...
;         const float* xo = (u.pm < 64) ? xoldA : (xoldB - (size_t)T_P * DM);
; #pragma unroll
;         for (int ai = 0; ai < 2; ++ai)
; #pragma unroll
;             for (int m = 0; m < 4; ++m) {
;                 const int row = row0 + ai * 128 + m * 16; const size_t ro = (size_t)row * DM + col0;
;                 float s = 0.f;
; #pragma unroll
;                 for (int bj = 0; bj < 2; ++bj)
; #pragma unroll
;                     for (int n = 0; n < 2; ++n) {
;                         const size_t o = ro + bj * 128 + n * 16;
;                         const f32x4 xn = *(const f32x4*)(xo + o) + acc[ai][bj][m][n];
;                         *(f32x4*)(xf + o) = xn;
;                         u32x2 w; w.x = pk2(xn[0], xn[1]); w.y = pk2(xn[2], xn[3]); *(u32x2*)(xb + o) = w;
;                         s += (xn[0] * xn[0] + xn[1] * xn[1]) + (xn[2] * xn[2] + xn[3] * xn[3]);
;                     }
;                 s += __shfl_xor(s, 16); s += __shfl_xor(s, 32);
;                 if (fq == 0) ssq[(size_t)row * 16 + u.pn * 4 + wc] = s;
.LBB0_787:
	s_or_b64 exec, exec, s[58:59]
	v_or_b32_e32 v80, 48, v146
	s_waitcnt lgkmcnt(0)
	v_ashrrev_i32_e32 v81, 31, v80
	v_lshlrev_b64 v[82:83], 10, v[80:81]
	v_lshl_add_u64 v[86:87], v[82:83], 0, v[142:143]
	v_lshlrev_b64 v[88:89], 2, v[86:87]
	v_lshl_add_u64 v[90:91], s[16:17], 0, v[88:89]
	v_lshl_add_u64 v[86:87], v[86:87], 1, s[24:25]
	v_lshl_add_u64 v[88:89], s[28:29], 0, v[88:89]
	s_waitcnt vmcnt(41)
	v_mov_b64_e32 v[82:83], v[232:233]
	v_mov_b64_e32 v[84:85], v[234:235]
	v_add_u32_e32 v173, 0xb0200, v172
	global_load_dwordx4 v[232:235], v173, s[16:17]
	v_pk_add_f32 v[78:79], v[78:79], v[84:85]
	v_pk_add_f32 v[76:77], v[76:77], v[82:83]
	global_store_dwordx4 v[88:89], v[76:79], off
	v_cvt_pk_bf16_f32 v82, v76, v77
	v_cvt_pk_bf16_f32 v83, v78, v79
	global_store_dwordx2 v[86:87], v[82:83], off
	v_mul_f32_e32 v77, v77, v77
	v_mul_f32_e32 v79, v79, v79
	v_fmac_f32_e32 v77, v76, v76
	v_fmac_f32_e32 v79, v78, v78
	v_add_f32_e32 v76, v77, v79
	s_waitcnt vmcnt(43)
	v_mov_b64_e32 v[82:83], v[236:237]
	v_mov_b64_e32 v[84:85], v[238:239]
	v_add_u32_e32 v173, 0xb0240, v172
	global_load_dwordx4 v[236:239], v173, s[16:17]
	v_pk_add_f32 v[74:75], v[74:75], v[84:85]
	v_pk_add_f32 v[72:73], v[72:73], v[82:83]
	global_store_dwordx4 v[88:89], v[72:75], off offset:64
	v_cvt_pk_bf16_f32 v82, v72, v73
	v_cvt_pk_bf16_f32 v83, v74, v75
	global_store_dwordx2 v[86:87], v[82:83], off offset:32
	v_mul_f32_e32 v73, v73, v73
	v_mul_f32_e32 v75, v75, v75
	v_fmac_f32_e32 v73, v72, v72
	v_fmac_f32_e32 v75, v74, v74
	v_add_f32_e32 v72, v73, v75
	v_add_f32_e32 v72, v76, v72
	s_waitcnt vmcnt(45)
	v_mov_b64_e32 v[82:83], v[240:241]
	v_mov_b64_e32 v[84:85], v[242:243]
	v_pk_add_f32 v[70:71], v[70:71], v[84:85]
	v_pk_add_f32 v[68:69], v[68:69], v[82:83]
	global_store_dwordx4 v[88:89], v[68:71], off offset:512
	v_cvt_pk_bf16_f32 v82, v68, v69
	v_cvt_pk_bf16_f32 v83, v70, v71
	global_store_dwordx2 v[86:87], v[82:83], off offset:256
	v_mul_f32_e32 v69, v69, v69
	v_mul_f32_e32 v71, v71, v71
	v_fmac_f32_e32 v69, v68, v68
	v_fmac_f32_e32 v71, v70, v70
	v_add_f32_e32 v68, v69, v71
	v_add_f32_e32 v70, v72, v68
	s_waitcnt vmcnt(46)
	v_mov_b64_e32 v[82:83], v[244:245]
	v_mov_b64_e32 v[84:85], v[246:247]
	v_pk_add_f32 v[68:69], v[66:67], v[84:85]
	v_pk_add_f32 v[66:67], v[64:65], v[82:83]
	v_mul_f32_e32 v65, v69, v69
	v_mul_f32_e32 v64, v67, v67
	v_fmac_f32_e32 v64, v66, v66
	v_fmac_f32_e32 v65, v68, v68
	v_add_f32_e32 v64, v64, v65
	v_add_f32_e32 v64, v70, v64
	ds_bpermute_b32 v65, v116, v64
	global_store_dwordx4 v[88:89], v[66:69], off offset:576
	s_waitcnt lgkmcnt(0)
	v_add_f32_e32 v64, v64, v65
	ds_bpermute_b32 v65, v114, v64
	v_cvt_pk_bf16_f32 v66, v66, v67
	v_cvt_pk_bf16_f32 v67, v68, v69
	global_store_dwordx2 v[86:87], v[66:67], off offset:288
	s_and_saveexec_b64 s[58:59], s[12:13]
	s_cbranch_execz .LBB0_789
	s_waitcnt lgkmcnt(0)
	v_add_f32_e32 v66, v64, v65
	v_lshlrev_b64 v[64:65], 6, v[80:81]
	v_lshl_add_u64 v[64:65], s[26:27], 0, v[64:65]
	v_lshl_add_u64 v[64:65], s[56:57], 2, v[64:65]
	s_lshl_b32 s36, s74, 2
	v_lshl_add_u64 v[64:65], v[64:65], 0, s[36:37]
	global_store_dword v[64:65], v66, off
.LBB0_789:
	s_or_b64 exec, exec, s[58:59]
	v_add_u32_e32 v64, 0x80, v146
	s_waitcnt lgkmcnt(0)
	v_ashrrev_i32_e32 v65, 31, v64
	v_lshlrev_b64 v[66:67], 10, v[64:65]
	v_lshl_add_u64 v[70:71], v[66:67], 0, v[142:143]
	v_lshlrev_b64 v[72:73], 2, v[70:71]
	v_lshl_add_u64 v[74:75], s[16:17], 0, v[72:73]
	v_lshl_add_u64 v[70:71], v[70:71], 1, s[24:25]
	v_lshl_add_u64 v[72:73], s[28:29], 0, v[72:73]
	s_waitcnt vmcnt(47)
	v_mov_b64_e32 v[66:67], v[248:249]
	v_mov_b64_e32 v[68:69], v[250:251]
	v_pk_add_f32 v[62:63], v[62:63], v[68:69]
	v_pk_add_f32 v[60:61], v[60:61], v[66:67]
	global_store_dwordx4 v[72:73], v[60:63], off
	v_cvt_pk_bf16_f32 v66, v60, v61
	v_cvt_pk_bf16_f32 v67, v62, v63
	global_store_dwordx2 v[70:71], v[66:67], off
	v_mul_f32_e32 v61, v61, v61
	v_mul_f32_e32 v63, v63, v63
	v_fmac_f32_e32 v61, v60, v60
	v_fmac_f32_e32 v63, v62, v62
	v_add_f32_e32 v60, v61, v63
	s_waitcnt vmcnt(48)
	v_mov_b64_e32 v[66:67], v[252:253]
	v_mov_b64_e32 v[68:69], v[254:255]
	v_pk_add_f32 v[58:59], v[58:59], v[68:69]
	v_pk_add_f32 v[56:57], v[56:57], v[66:67]
	global_store_dwordx4 v[72:73], v[56:59], off offset:64
	v_cvt_pk_bf16_f32 v66, v56, v57
	v_cvt_pk_bf16_f32 v67, v58, v59
	global_store_dwordx2 v[70:71], v[66:67], off offset:32
	v_mul_f32_e32 v57, v57, v57
	v_mul_f32_e32 v59, v59, v59
	v_fmac_f32_e32 v57, v56, v56
	v_fmac_f32_e32 v59, v58, v58
	v_add_f32_e32 v56, v57, v59
	v_add_f32_e32 v56, v60, v56
	s_waitcnt vmcnt(49)
	v_mov_b64_e32 v[66:67], v[174:175]
	v_mov_b64_e32 v[68:69], v[176:177]
	v_pk_add_f32 v[54:55], v[54:55], v[68:69]
	v_pk_add_f32 v[52:53], v[52:53], v[66:67]
	global_store_dwordx4 v[72:73], v[52:55], off offset:512
	v_cvt_pk_bf16_f32 v66, v52, v53
	v_cvt_pk_bf16_f32 v67, v54, v55
	global_store_dwordx2 v[70:71], v[66:67], off offset:256
	v_mul_f32_e32 v53, v53, v53
	v_mul_f32_e32 v55, v55, v55
	v_fmac_f32_e32 v53, v52, v52
	v_fmac_f32_e32 v55, v54, v54
	v_add_f32_e32 v52, v53, v55
	v_add_f32_e32 v54, v56, v52
	s_waitcnt vmcnt(48)
	v_mov_b64_e32 v[66:67], v[178:179]
	v_mov_b64_e32 v[68:69], v[180:181]
	v_pk_add_f32 v[52:53], v[50:51], v[68:69]
	v_pk_add_f32 v[50:51], v[48:49], v[66:67]
	v_mul_f32_e32 v49, v53, v53
	v_mul_f32_e32 v48, v51, v51
	v_fmac_f32_e32 v48, v50, v50
	v_fmac_f32_e32 v49, v52, v52
	v_add_f32_e32 v48, v48, v49
	v_add_f32_e32 v48, v54, v48
	ds_bpermute_b32 v49, v116, v48
	global_store_dwordx4 v[72:73], v[50:53], off offset:576
	s_waitcnt lgkmcnt(0)
	v_add_f32_e32 v48, v48, v49
	ds_bpermute_b32 v49, v114, v48
	v_cvt_pk_bf16_f32 v50, v50, v51
	v_cvt_pk_bf16_f32 v51, v52, v53
	global_store_dwordx2 v[70:71], v[50:51], off offset:288
	s_and_saveexec_b64 s[58:59], s[12:13]
	s_cbranch_execz .LBB0_791
	s_waitcnt lgkmcnt(0)
	v_add_f32_e32 v50, v48, v49
	v_lshlrev_b64 v[48:49], 6, v[64:65]
	v_lshl_add_u64 v[48:49], s[26:27], 0, v[48:49]
	v_lshl_add_u64 v[48:49], s[56:57], 2, v[48:49]
	s_lshl_b32 s36, s74, 2
	v_lshl_add_u64 v[48:49], v[48:49], 0, s[36:37]
	global_store_dword v[48:49], v50, off
; __device__ __forceinline__ unsigned pk2(float lo, float hi) { unsigned r; asm volatile("v_cvt_pk_bf16_f32 %0, %1, %2" : "=v"(r) : "v"(lo), "v"(hi)); return r; }
;     __device__ __forceinline__ void operator()(const f32x4 (&acc)[2][2][4][2], const Unit& u, int wr, int wc, int fr, int fq) const {
;     ...
;         const float* xo = (u.pm < 64) ? xoldA : (xoldB - (size_t)T_P * DM);
; #pragma unroll
;         for (int ai = 0; ai < 2; ++ai)
; #pragma unroll
;             for (int m = 0; m < 4; ++m) {
;                 const int row = row0 + ai * 128 + m * 16; const size_t ro = (size_t)row * DM + col0;
;                 float s = 0.f;
; #pragma unroll
;                 for (int bj = 0; bj < 2; ++bj)
; #pragma unroll
;                     for (int n = 0; n < 2; ++n) {
;                         const size_t o = ro + bj * 128 + n * 16;
;                         const f32x4 xn = *(const f32x4*)(xo + o) + acc[ai][bj][m][n];
;                         *(f32x4*)(xf + o) = xn;
;                         u32x2 w; w.x = pk2(xn[0], xn[1]); w.y = pk2(xn[2], xn[3]); *(u32x2*)(xb + o) = w;
;                         s += (xn[0] * xn[0] + xn[1] * xn[1]) + (xn[2] * xn[2] + xn[3] * xn[3]);
;                     }
;                 s += __shfl_xor(s, 16); s += __shfl_xor(s, 32);
;                 if (fq == 0) ssq[(size_t)row * 16 + u.pn * 4 + wc] = s;
.LBB0_791:
	s_or_b64 exec, exec, s[58:59]
	v_add_u32_e32 v48, 0x90, v146
	s_waitcnt lgkmcnt(0)
	v_ashrrev_i32_e32 v49, 31, v48
	v_lshlrev_b64 v[50:51], 10, v[48:49]
	v_lshl_add_u64 v[54:55], v[50:51], 0, v[142:143]
	v_lshlrev_b64 v[56:57], 2, v[54:55]
	v_lshl_add_u64 v[58:59], s[16:17], 0, v[56:57]
	v_lshl_add_u64 v[54:55], v[54:55], 1, s[24:25]
	v_lshl_add_u64 v[56:57], s[28:29], 0, v[56:57]
	s_waitcnt vmcnt(47)
	v_mov_b64_e32 v[50:51], v[182:183]
	v_mov_b64_e32 v[52:53], v[184:185]
	v_pk_add_f32 v[46:47], v[46:47], v[52:53]
	v_pk_add_f32 v[44:45], v[44:45], v[50:51]
	global_store_dwordx4 v[56:57], v[44:47], off
	v_cvt_pk_bf16_f32 v50, v44, v45
	v_cvt_pk_bf16_f32 v51, v46, v47
	global_store_dwordx2 v[54:55], v[50:51], off
	v_mul_f32_e32 v45, v45, v45
	v_mul_f32_e32 v47, v47, v47
	v_fmac_f32_e32 v45, v44, v44
	v_fmac_f32_e32 v47, v46, v46
	v_add_f32_e32 v44, v45, v47
	s_waitcnt vmcnt(46)
	v_mov_b64_e32 v[50:51], v[186:187]
	v_mov_b64_e32 v[52:53], v[188:189]
	v_pk_add_f32 v[42:43], v[42:43], v[52:53]
	v_pk_add_f32 v[40:41], v[40:41], v[50:51]
	global_store_dwordx4 v[56:57], v[40:43], off offset:64
	v_cvt_pk_bf16_f32 v50, v40, v41
	v_cvt_pk_bf16_f32 v51, v42, v43
	global_store_dwordx2 v[54:55], v[50:51], off offset:32
	v_mul_f32_e32 v41, v41, v41
	v_mul_f32_e32 v43, v43, v43
	v_fmac_f32_e32 v41, v40, v40
	v_fmac_f32_e32 v43, v42, v42
	v_add_f32_e32 v40, v41, v43
	v_add_f32_e32 v40, v44, v40
	s_waitcnt vmcnt(45)
	v_mov_b64_e32 v[50:51], v[190:191]
	v_mov_b64_e32 v[52:53], v[192:193]
	v_pk_add_f32 v[38:39], v[38:39], v[52:53]
	v_pk_add_f32 v[36:37], v[36:37], v[50:51]
	global_store_dwordx4 v[56:57], v[36:39], off offset:512
	v_cvt_pk_bf16_f32 v50, v36, v37
	v_cvt_pk_bf16_f32 v51, v38, v39
	global_store_dwordx2 v[54:55], v[50:51], off offset:256
	v_mul_f32_e32 v37, v37, v37
	v_mul_f32_e32 v39, v39, v39
	v_fmac_f32_e32 v37, v36, v36
	v_fmac_f32_e32 v39, v38, v38
	v_add_f32_e32 v36, v37, v39
	v_add_f32_e32 v38, v40, v36
	s_waitcnt vmcnt(44)
	v_mov_b64_e32 v[50:51], v[194:195]
	v_mov_b64_e32 v[52:53], v[196:197]
	v_pk_add_f32 v[36:37], v[34:35], v[52:53]
	v_pk_add_f32 v[34:35], v[32:33], v[50:51]
	v_mul_f32_e32 v33, v37, v37
	v_mul_f32_e32 v32, v35, v35
	v_fmac_f32_e32 v32, v34, v34
	v_fmac_f32_e32 v33, v36, v36
	v_add_f32_e32 v32, v32, v33
	v_add_f32_e32 v32, v38, v32
	ds_bpermute_b32 v33, v116, v32
	global_store_dwordx4 v[56:57], v[34:37], off offset:576
	s_waitcnt lgkmcnt(0)
	v_add_f32_e32 v32, v32, v33
	ds_bpermute_b32 v33, v114, v32
	v_cvt_pk_bf16_f32 v34, v34, v35
	v_cvt_pk_bf16_f32 v35, v36, v37
	global_store_dwordx2 v[54:55], v[34:35], off offset:288
	s_and_saveexec_b64 s[58:59], s[12:13]
	s_cbranch_execz .LBB0_793
	s_waitcnt lgkmcnt(0)
	v_add_f32_e32 v34, v32, v33
	v_lshlrev_b64 v[32:33], 6, v[48:49]
	v_lshl_add_u64 v[32:33], s[26:27], 0, v[32:33]
	v_lshl_add_u64 v[32:33], s[56:57], 2, v[32:33]
	s_lshl_b32 s36, s74, 2
	v_lshl_add_u64 v[32:33], v[32:33], 0, s[36:37]
	global_store_dword v[32:33], v34, off
; __device__ __forceinline__ unsigned pk2(float lo, float hi) { unsigned r; asm volatile("v_cvt_pk_bf16_f32 %0, %1, %2" : "=v"(r) : "v"(lo), "v"(hi)); return r; }
;     __device__ __forceinline__ void operator()(const f32x4 (&acc)[2][2][4][2], const Unit& u, int wr, int wc, int fr, int fq) const {
;     ...
;         const float* xo = (u.pm < 64) ? xoldA : (xoldB - (size_t)T_P * DM);
; #pragma unroll
;         for (int ai = 0; ai < 2; ++ai)
; #pragma unroll
;             for (int m = 0; m < 4; ++m) {
;                 const int row = row0 + ai * 128 + m * 16; const size_t ro = (size_t)row * DM + col0;
;                 float s = 0.f;
; #pragma unroll
;                 for (int bj = 0; bj < 2; ++bj)
; #pragma unroll
;                     for (int n = 0; n < 2; ++n) {
;                         const size_t o = ro + bj * 128 + n * 16;
;                         const f32x4 xn = *(const f32x4*)(xo + o) + acc[ai][bj][m][n];
;                         *(f32x4*)(xf + o) = xn;
;                         u32x2 w; w.x = pk2(xn[0], xn[1]); w.y = pk2(xn[2], xn[3]); *(u32x2*)(xb + o) = w;
;                         s += (xn[0] * xn[0] + xn[1] * xn[1]) + (xn[2] * xn[2] + xn[3] * xn[3]);
;                     }
;                 s += __shfl_xor(s, 16); s += __shfl_xor(s, 32);
;                 if (fq == 0) ssq[(size_t)row * 16 + u.pn * 4 + wc] = s;
.LBB0_793:
	s_or_b64 exec, exec, s[58:59]
	v_add_u32_e32 v32, 0xa0, v146
	s_waitcnt lgkmcnt(0)
	v_ashrrev_i32_e32 v33, 31, v32
	v_lshlrev_b64 v[34:35], 10, v[32:33]
	v_lshl_add_u64 v[38:39], v[34:35], 0, v[142:143]
	v_lshlrev_b64 v[40:41], 2, v[38:39]
	v_lshl_add_u64 v[42:43], s[16:17], 0, v[40:41]
	v_lshl_add_u64 v[38:39], v[38:39], 1, s[24:25]
	v_lshl_add_u64 v[40:41], s[28:29], 0, v[40:41]
	s_waitcnt vmcnt(43)
	v_mov_b64_e32 v[34:35], v[198:199]
	v_mov_b64_e32 v[36:37], v[200:201]
	v_pk_add_f32 v[30:31], v[30:31], v[36:37]
	v_pk_add_f32 v[28:29], v[28:29], v[34:35]
	global_store_dwordx4 v[40:41], v[28:31], off
	v_cvt_pk_bf16_f32 v34, v28, v29
	v_cvt_pk_bf16_f32 v35, v30, v31
	global_store_dwordx2 v[38:39], v[34:35], off
	v_mul_f32_e32 v29, v29, v29
	v_mul_f32_e32 v31, v31, v31
	v_fmac_f32_e32 v29, v28, v28
	v_fmac_f32_e32 v31, v30, v30
	v_add_f32_e32 v28, v29, v31
	s_waitcnt vmcnt(42)
	v_mov_b64_e32 v[34:35], v[202:203]
	v_mov_b64_e32 v[36:37], v[204:205]
	v_pk_add_f32 v[26:27], v[26:27], v[36:37]
	v_pk_add_f32 v[24:25], v[24:25], v[34:35]
	global_store_dwordx4 v[40:41], v[24:27], off offset:64
	v_cvt_pk_bf16_f32 v34, v24, v25
	v_cvt_pk_bf16_f32 v35, v26, v27
	global_store_dwordx2 v[38:39], v[34:35], off offset:32
	v_mul_f32_e32 v25, v25, v25
	v_mul_f32_e32 v27, v27, v27
	v_fmac_f32_e32 v25, v24, v24
	v_fmac_f32_e32 v27, v26, v26
	v_add_f32_e32 v24, v25, v27
	v_add_f32_e32 v24, v28, v24
	s_waitcnt vmcnt(41)
	v_mov_b64_e32 v[34:35], v[206:207]
	v_mov_b64_e32 v[36:37], v[208:209]
	v_pk_add_f32 v[22:23], v[22:23], v[36:37]
	v_pk_add_f32 v[20:21], v[20:21], v[34:35]
	global_store_dwordx4 v[40:41], v[20:23], off offset:512
	v_cvt_pk_bf16_f32 v34, v20, v21
	v_cvt_pk_bf16_f32 v35, v22, v23
	global_store_dwordx2 v[38:39], v[34:35], off offset:256
	v_mul_f32_e32 v21, v21, v21
	v_mul_f32_e32 v23, v23, v23
	v_fmac_f32_e32 v21, v20, v20
	v_fmac_f32_e32 v23, v22, v22
	v_add_f32_e32 v20, v21, v23
	v_add_f32_e32 v22, v24, v20
	s_waitcnt vmcnt(40)
	v_mov_b64_e32 v[34:35], v[210:211]
	v_mov_b64_e32 v[36:37], v[212:213]
	v_pk_add_f32 v[20:21], v[18:19], v[36:37]
	v_pk_add_f32 v[18:19], v[16:17], v[34:35]
	v_mul_f32_e32 v17, v21, v21
	v_mul_f32_e32 v16, v19, v19
	v_fmac_f32_e32 v16, v18, v18
	v_fmac_f32_e32 v17, v20, v20
	v_add_f32_e32 v16, v16, v17
	v_add_f32_e32 v16, v22, v16
	ds_bpermute_b32 v17, v116, v16
	global_store_dwordx4 v[40:41], v[18:21], off offset:576
	s_waitcnt lgkmcnt(0)
	v_add_f32_e32 v16, v16, v17
	ds_bpermute_b32 v17, v114, v16
	v_cvt_pk_bf16_f32 v18, v18, v19
	v_cvt_pk_bf16_f32 v19, v20, v21
	global_store_dwordx2 v[38:39], v[18:19], off offset:288
	s_and_saveexec_b64 s[58:59], s[12:13]
	s_cbranch_execz .LBB0_795
	s_waitcnt lgkmcnt(0)
	v_add_f32_e32 v18, v16, v17
	v_lshlrev_b64 v[16:17], 6, v[32:33]
	v_lshl_add_u64 v[16:17], s[26:27], 0, v[16:17]
	v_lshl_add_u64 v[16:17], s[56:57], 2, v[16:17]
	s_lshl_b32 s36, s74, 2
	v_lshl_add_u64 v[16:17], v[16:17], 0, s[36:37]
	global_store_dword v[16:17], v18, off
.LBB0_795:
	s_or_b64 exec, exec, s[58:59]
	v_add_u32_e32 v16, 0xb0, v146
	s_waitcnt lgkmcnt(0)
	v_ashrrev_i32_e32 v17, 31, v16
	v_lshlrev_b64 v[18:19], 10, v[16:17]
	v_lshl_add_u64 v[22:23], v[18:19], 0, v[142:143]
	v_lshlrev_b64 v[24:25], 2, v[22:23]
	v_lshl_add_u64 v[26:27], s[16:17], 0, v[24:25]
	v_lshl_add_u64 v[22:23], v[22:23], 1, s[24:25]
	v_lshl_add_u64 v[24:25], s[28:29], 0, v[24:25]
	s_waitcnt vmcnt(39)
	v_mov_b64_e32 v[18:19], v[214:215]
	v_mov_b64_e32 v[20:21], v[216:217]
	v_pk_add_f32 v[14:15], v[14:15], v[20:21]
	v_pk_add_f32 v[12:13], v[12:13], v[18:19]
	global_store_dwordx4 v[24:25], v[12:15], off
	v_cvt_pk_bf16_f32 v18, v12, v13
	v_cvt_pk_bf16_f32 v19, v14, v15
	global_store_dwordx2 v[22:23], v[18:19], off
	v_mul_f32_e32 v13, v13, v13
	v_mul_f32_e32 v15, v15, v15
	v_fmac_f32_e32 v13, v12, v12
	v_fmac_f32_e32 v15, v14, v14
	v_add_f32_e32 v12, v13, v15
	s_waitcnt vmcnt(38)
	v_mov_b64_e32 v[18:19], v[218:219]
	v_mov_b64_e32 v[20:21], v[220:221]
	v_pk_add_f32 v[10:11], v[10:11], v[20:21]
	v_pk_add_f32 v[8:9], v[8:9], v[18:19]
	global_store_dwordx4 v[24:25], v[8:11], off offset:64
	v_cvt_pk_bf16_f32 v18, v8, v9
	v_cvt_pk_bf16_f32 v19, v10, v11
	global_store_dwordx2 v[22:23], v[18:19], off offset:32
	v_mul_f32_e32 v9, v9, v9
	v_mul_f32_e32 v11, v11, v11
	v_fmac_f32_e32 v9, v8, v8
	v_fmac_f32_e32 v11, v10, v10
	v_add_f32_e32 v8, v9, v11
	v_add_f32_e32 v8, v12, v8
	s_waitcnt vmcnt(37)
	v_mov_b64_e32 v[18:19], v[232:233]
	v_mov_b64_e32 v[20:21], v[234:235]
	v_pk_add_f32 v[6:7], v[6:7], v[20:21]
	v_pk_add_f32 v[4:5], v[4:5], v[18:19]
	global_store_dwordx4 v[24:25], v[4:7], off offset:512
	v_cvt_pk_bf16_f32 v18, v4, v5
	v_cvt_pk_bf16_f32 v19, v6, v7
	global_store_dwordx2 v[22:23], v[18:19], off offset:256
	v_mul_f32_e32 v5, v5, v5
	v_mul_f32_e32 v7, v7, v7
	v_fmac_f32_e32 v5, v4, v4
	v_fmac_f32_e32 v7, v6, v6
	v_add_f32_e32 v4, v5, v7
	v_add_f32_e32 v6, v8, v4
	s_waitcnt vmcnt(36)
	v_mov_b64_e32 v[18:19], v[236:237]
	v_mov_b64_e32 v[20:21], v[238:239]
	v_pk_add_f32 v[4:5], v[2:3], v[20:21]
	v_pk_add_f32 v[2:3], v[0:1], v[18:19]
	v_mul_f32_e32 v1, v5, v5
	v_mul_f32_e32 v0, v3, v3
	v_fmac_f32_e32 v0, v2, v2
	v_fmac_f32_e32 v1, v4, v4
	v_add_f32_e32 v0, v0, v1
	v_add_f32_e32 v0, v6, v0
	ds_bpermute_b32 v1, v116, v0
	global_store_dwordx4 v[24:25], v[2:5], off offset:576
	s_waitcnt lgkmcnt(0)
	v_add_f32_e32 v0, v0, v1
	ds_bpermute_b32 v1, v114, v0
	v_cvt_pk_bf16_f32 v2, v2, v3
	v_cvt_pk_bf16_f32 v3, v4, v5
	global_store_dwordx2 v[22:23], v[2:3], off offset:288
	s_and_saveexec_b64 s[16:17], s[12:13]
	s_cbranch_execz .LBB0_754
	s_waitcnt lgkmcnt(0)
	v_add_f32_e32 v2, v0, v1
	v_lshlrev_b64 v[0:1], 6, v[16:17]
	v_lshl_add_u64 v[0:1], s[26:27], 0, v[0:1]
	v_lshl_add_u64 v[0:1], s[56:57], 2, v[0:1]
	s_lshl_b32 s36, s74, 2
	v_lshl_add_u64 v[0:1], v[0:1], 0, s[36:37]
	global_store_dword v[0:1], v2, off
	s_branch .LBB0_754

; __device__ __forceinline__ unsigned pk2(float lo, float hi) { unsigned r; asm volatile("v_cvt_pk_bf16_f32 %0, %1, %2" : "=v"(r) : "v"(lo), "v"(hi)); return r; }
;     ...
;         const int lane = threadIdx.x & 63, wv = threadIdx.x >> 6;
;         const int rbase = u.pm * 256 + (kq * 4 + u.pn) * 16 + wv * 2;
; #pragma unroll
;         for (int rr = 0; rr < 2; ++rr) {
;             const int row = rbase + rr; float sq = 0.f;
; #pragma unroll
;             for (int i = 0; i < 4; ++i) {
;                 const size_t o = (size_t)row * DM + i * 256 + lane * 4;
;                 f32x4 v = *(const f32x4*)(xold + o);
; #pragma unroll
;                 for (int q = 0; q < 4; ++q) v += *(const f32x4*)(part + (size_t)q * 1024 * DM + o);
;                 *(f32x4*)(xf_s + o) = v;
;                 u32x2 w; w.x = pk2(v[0], v[1]); w.y = pk2(v[2], v[3]); *(u32x2*)(xb_s + o) = w;
;                 sq += (v[0] * v[0] + v[1] * v[1]) + (v[2] * v[2] + v[3] * v[3]);
;             }
; #pragma unroll
;             for (int o = 32; o >= 1; o >>= 1) sq += __shfl_xor(sq, o);
;             if (lane < 16) ssq_s[(size_t)row * 16 + lane] = lane == 0 ? sq : 0.f;
;         }
.LBB0_879:
	s_or_b64 exec, exec, s[10:11]
	s_add_u32 s22, s28, 0x4000000
	s_addc_u32 s23, s29, 0
	s_add_u32 s20, s20, 0x2000000
	s_addc_u32 s21, s21, 0
	s_lshr_b32 s8, s81, 2
	v_lshrrev_b32_e32 v0, 5, v166
	s_and_b32 s8, s8, 0xffffffc
	v_and_b32_e32 v0, 30, v0
	s_add_i32 s6, s6, s8
	v_lshl_or_b32 v0, s7, 8, v0
	v_lshl_add_u32 v2, s6, 4, v0
	v_ashrrev_i32_e32 v3, 31, v2
	v_lshlrev_b32_e32 v0, 2, v167
	v_lshlrev_b64 v[4:5], 10, v[2:3]
	v_or_b32_e32 v4, v4, v0
	v_lshlrev_b64 v[26:27], 2, v[4:5]
	v_lshl_add_u64 v[40:41], s[16:17], 0, v[26:27]
	s_mov_b32 s6, 0x400000
	v_add_co_u32_e32 v42, vcc, s6, v40
	s_mov_b32 s7, 0x800000
	s_nop 0
	v_addc_co_u32_e32 v43, vcc, 0, v41, vcc
	v_lshl_add_u64 v[38:39], s[14:15], 0, v[26:27]
	v_add_co_u32_e32 v44, vcc, s7, v40
	s_barrier
	global_load_dwordx4 v[6:9], v[38:39], off
	v_addc_co_u32_e32 v45, vcc, 0, v41, vcc
	s_mov_b32 s8, 0xc00000
	global_load_dwordx4 v[10:13], v[40:41], off
	global_load_dwordx4 v[14:17], v[42:43], off
	v_add_co_u32_e32 v46, vcc, s8, v40
	global_load_dwordx4 v[18:21], v[44:45], off
	s_nop 0
	v_addc_co_u32_e32 v47, vcc, 0, v41, vcc
	global_load_dwordx4 v[22:25], v[46:47], off
	v_lshl_add_u64 v[28:29], v[4:5], 1, s[20:21]
	v_lshl_add_u64 v[26:27], s[22:23], 0, v[26:27]
	v_mov_b32_e32 v31, v5
	v_or_b32_e32 v30, 0x100, v4
	v_lshl_add_u64 v[32:33], v[30:31], 2, s[22:23]
	v_lshl_add_u64 v[30:31], v[30:31], 1, s[20:21]
	v_mov_b32_e32 v35, v5
	v_or_b32_e32 v34, 0x200, v4
	v_lshl_add_u64 v[36:37], v[34:35], 2, s[22:23]
	v_lshl_add_u64 v[34:35], v[34:35], 1, s[20:21]
	v_mov_b32_e32 v1, 0
	v_or_b32_e32 v4, 0x300, v4
	s_mov_b64 s[24:25], 0x100000
	v_cmp_gt_u32_e64 s[10:11], 16, v167
	v_cmp_eq_u32_e32 vcc, 0, v167
	global_load_dwordx4 v[186:189], v[38:39], off offset:1024
	global_load_dwordx4 v[190:193], v[40:41], off offset:1024
	global_load_dwordx4 v[194:197], v[42:43], off offset:1024
	global_load_dwordx4 v[198:201], v[44:45], off offset:1024
	global_load_dwordx4 v[202:205], v[46:47], off offset:1024
	global_load_dwordx4 v[206:209], v[38:39], off offset:2048
	global_load_dwordx4 v[210:213], v[40:41], off offset:2048
	global_load_dwordx4 v[214:217], v[42:43], off offset:2048
	global_load_dwordx4 v[218:221], v[44:45], off offset:2048
	global_load_dwordx4 v[222:225], v[46:47], off offset:2048
	global_load_dwordx4 v[226:229], v[38:39], off offset:3072
	global_load_dwordx4 v[232:235], v[40:41], off offset:3072
	global_load_dwordx4 v[236:239], v[42:43], off offset:3072
	global_load_dwordx4 v[240:243], v[44:45], off offset:3072
	global_load_dwordx4 v[244:247], v[46:47], off offset:3072
	s_waitcnt vmcnt(18)
	v_pk_add_f32 v[8:9], v[8:9], v[12:13]
	v_pk_add_f32 v[6:7], v[6:7], v[10:11]
	s_waitcnt vmcnt(17)
	v_pk_add_f32 v[8:9], v[8:9], v[16:17]
	v_pk_add_f32 v[6:7], v[6:7], v[14:15]
	s_waitcnt vmcnt(16)
	v_pk_add_f32 v[8:9], v[8:9], v[20:21]
	v_pk_add_f32 v[6:7], v[6:7], v[18:19]
	s_waitcnt vmcnt(15)
	v_pk_add_f32 v[8:9], v[8:9], v[24:25]
	v_pk_add_f32 v[6:7], v[6:7], v[22:23]
	global_store_dwordx4 v[26:27], v[6:9], off
	v_cvt_pk_bf16_f32 v10, v6, v7
	v_cvt_pk_bf16_f32 v11, v8, v9
	global_store_dwordx2 v[28:29], v[10:11], off
	s_nop 0
	v_mul_f32_e32 v7, v7, v7
	v_mul_f32_e32 v9, v9, v9
	v_fmac_f32_e32 v7, v6, v6
	v_fmac_f32_e32 v9, v8, v8
	v_add_f32_e32 v6, v7, v9
	s_waitcnt vmcnt(12)
	v_mov_b64_e32 v[10:11], v[186:187]
	v_mov_b64_e32 v[12:13], v[188:189]
	v_mov_b64_e32 v[14:15], v[190:191]
	v_mov_b64_e32 v[16:17], v[192:193]
	v_mov_b64_e32 v[18:19], v[194:195]
	v_mov_b64_e32 v[20:21], v[196:197]
	v_mov_b64_e32 v[22:23], v[198:199]
	v_mov_b64_e32 v[24:25], v[200:201]
	v_mov_b64_e32 v[26:27], v[202:203]
	v_mov_b64_e32 v[28:29], v[204:205]
	v_pk_add_f32 v[12:13], v[12:13], v[16:17]
	v_pk_add_f32 v[10:11], v[10:11], v[14:15]
	v_pk_add_f32 v[12:13], v[12:13], v[20:21]
	v_pk_add_f32 v[10:11], v[10:11], v[18:19]
	v_pk_add_f32 v[12:13], v[12:13], v[24:25]
	v_pk_add_f32 v[10:11], v[10:11], v[22:23]
	v_pk_add_f32 v[12:13], v[12:13], v[28:29]
	v_pk_add_f32 v[10:11], v[10:11], v[26:27]
	global_store_dwordx4 v[32:33], v[10:13], off
	v_cvt_pk_bf16_f32 v14, v10, v11
	v_cvt_pk_bf16_f32 v15, v12, v13
	global_store_dwordx2 v[30:31], v[14:15], off
	s_nop 0
	v_mul_f32_e32 v7, v11, v11
	v_mul_f32_e32 v8, v13, v13
	v_fmac_f32_e32 v7, v10, v10
	v_fmac_f32_e32 v8, v12, v12
	v_add_f32_e32 v7, v7, v8
	v_add_f32_e32 v6, v6, v7
	s_waitcnt vmcnt(9)
	v_mov_b64_e32 v[14:15], v[206:207]
	v_mov_b64_e32 v[16:17], v[208:209]
	v_mov_b64_e32 v[18:19], v[210:211]
	v_mov_b64_e32 v[20:21], v[212:213]
	v_mov_b64_e32 v[22:23], v[214:215]
	v_mov_b64_e32 v[24:25], v[216:217]
	v_mov_b64_e32 v[26:27], v[218:219]
	v_mov_b64_e32 v[28:29], v[220:221]
	v_mov_b64_e32 v[30:31], v[222:223]
	v_mov_b64_e32 v[32:33], v[224:225]
	v_pk_add_f32 v[16:17], v[16:17], v[20:21]
	v_pk_add_f32 v[14:15], v[14:15], v[18:19]
	v_pk_add_f32 v[16:17], v[16:17], v[24:25]
	v_pk_add_f32 v[14:15], v[14:15], v[22:23]
	v_pk_add_f32 v[16:17], v[16:17], v[28:29]
	v_pk_add_f32 v[14:15], v[14:15], v[26:27]
	v_pk_add_f32 v[16:17], v[16:17], v[32:33]
	v_pk_add_f32 v[14:15], v[14:15], v[30:31]
	global_store_dwordx4 v[36:37], v[14:17], off
	v_cvt_pk_bf16_f32 v18, v14, v15
	v_cvt_pk_bf16_f32 v19, v16, v17
	global_store_dwordx2 v[34:35], v[18:19], off
	s_nop 0
	v_mul_f32_e32 v7, v15, v15
	v_mul_f32_e32 v8, v17, v17
	v_fmac_f32_e32 v7, v14, v14
	v_fmac_f32_e32 v8, v16, v16
	v_add_f32_e32 v7, v7, v8
	v_add_f32_e32 v10, v6, v7
	v_mbcnt_hi_u32_b32 v40, -1, v168
	v_lshl_add_u64 v[38:39], s[18:19], 0, v[0:1]
	v_and_b32_e32 v1, 64, v40
	v_xor_b32_e32 v41, 32, v40
	v_add_u32_e32 v44, 64, v1
	v_cmp_lt_i32_e64 s[12:13], v41, v44
	v_xor_b32_e32 v42, 16, v40
	v_xor_b32_e32 v43, 8, v40
	v_cndmask_b32_e64 v1, v40, v41, s[12:13]
	v_lshlrev_b32_e32 v1, 2, v1
	v_cmp_lt_i32_e64 s[12:13], v42, v44
	v_xor_b32_e32 v11, 2, v40
	v_xor_b32_e32 v12, 1, v40
	s_waitcnt vmcnt(6)
; __device__ __forceinline__ unsigned pk2(float lo, float hi) { unsigned r; asm volatile("v_cvt_pk_bf16_f32 %0, %1, %2" : "=v"(r) : "v"(lo), "v"(hi)); return r; }
;     ...
;         const int lane = threadIdx.x & 63, wv = threadIdx.x >> 6;
;         const int rbase = u.pm * 256 + (kq * 4 + u.pn) * 16 + wv * 2;
; #pragma unroll
;         for (int rr = 0; rr < 2; ++rr) {
;             const int row = rbase + rr; float sq = 0.f;
; #pragma unroll
;             for (int i = 0; i < 4; ++i) {
;                 const size_t o = (size_t)row * DM + i * 256 + lane * 4;
;                 f32x4 v = *(const f32x4*)(xold + o);
; #pragma unroll
;                 for (int q = 0; q < 4; ++q) v += *(const f32x4*)(part + (size_t)q * 1024 * DM + o);
;                 *(f32x4*)(xf_s + o) = v;
;                 u32x2 w; w.x = pk2(v[0], v[1]); w.y = pk2(v[2], v[3]); *(u32x2*)(xb_s + o) = w;
;                 sq += (v[0] * v[0] + v[1] * v[1]) + (v[2] * v[2] + v[3] * v[3]);
;             }
; #pragma unroll
;             for (int o = 32; o >= 1; o >>= 1) sq += __shfl_xor(sq, o);
;             if (lane < 16) ssq_s[(size_t)row * 16 + lane] = lane == 0 ? sq : 0.f;
;         }
	v_mov_b64_e32 v[18:19], v[226:227]
	v_mov_b64_e32 v[20:21], v[228:229]
	v_mov_b64_e32 v[22:23], v[232:233]
	v_mov_b64_e32 v[24:25], v[234:235]
	v_mov_b64_e32 v[26:27], v[236:237]
	v_mov_b64_e32 v[28:29], v[238:239]
	v_mov_b64_e32 v[30:31], v[240:241]
	v_mov_b64_e32 v[32:33], v[242:243]
	v_mov_b64_e32 v[34:35], v[244:245]
	v_mov_b64_e32 v[36:37], v[246:247]
	v_pk_add_f32 v[6:7], v[20:21], v[24:25]
	v_pk_add_f32 v[8:9], v[18:19], v[22:23]
	v_pk_add_f32 v[6:7], v[6:7], v[28:29]
	v_pk_add_f32 v[8:9], v[8:9], v[26:27]
	v_pk_add_f32 v[6:7], v[6:7], v[32:33]
	v_pk_add_f32 v[8:9], v[8:9], v[30:31]
	v_pk_add_f32 v[18:19], v[6:7], v[36:37]
	v_pk_add_f32 v[16:17], v[8:9], v[34:35]
	v_mul_f32_e32 v7, v19, v19
	v_mul_f32_e32 v6, v17, v17
	v_fmac_f32_e32 v6, v16, v16
	v_fmac_f32_e32 v7, v18, v18
	v_add_f32_e32 v6, v6, v7
	v_add_f32_e32 v6, v10, v6
	ds_bpermute_b32 v7, v1, v6
	v_cndmask_b32_e64 v8, v40, v42, s[12:13]
	v_lshlrev_b32_e32 v8, 2, v8
	v_cmp_lt_i32_e64 s[12:13], v43, v44
	v_xor_b32_e32 v10, 4, v40
	s_waitcnt lgkmcnt(0)
	v_add_f32_e32 v6, v6, v7
	ds_bpermute_b32 v7, v8, v6
	v_cndmask_b32_e64 v9, v40, v43, s[12:13]
	v_lshlrev_b32_e32 v9, 2, v9
	v_cmp_lt_i32_e64 s[12:13], v10, v44
	s_waitcnt lgkmcnt(0)
	v_add_f32_e32 v6, v6, v7
	ds_bpermute_b32 v7, v9, v6
	v_cndmask_b32_e64 v10, v40, v10, s[12:13]
	v_lshlrev_b32_e32 v10, 2, v10
	v_cmp_lt_i32_e64 s[12:13], v11, v44
	s_waitcnt lgkmcnt(0)
	v_add_f32_e32 v13, v6, v7
	ds_bpermute_b32 v14, v10, v13
	v_cndmask_b32_e64 v11, v40, v11, s[12:13]
	v_lshlrev_b32_e32 v11, 2, v11
	v_cmp_lt_i32_e64 s[12:13], v12, v44
	v_lshl_add_u64 v[6:7], v[38:39], 0, s[24:25]
	s_waitcnt lgkmcnt(0)
	v_add_f32_e32 v14, v13, v14
	ds_bpermute_b32 v15, v11, v14
	v_cndmask_b32_e64 v20, v40, v12, s[12:13]
	v_lshl_add_u64 v[12:13], v[4:5], 2, s[22:23]
	global_store_dwordx4 v[12:13], v[16:19], off
	v_lshlrev_b32_e32 v12, 2, v20
	s_waitcnt lgkmcnt(0)
	v_add_f32_e32 v13, v14, v15
	ds_bpermute_b32 v14, v12, v13
	v_lshl_add_u64 v[4:5], v[4:5], 1, s[20:21]
	v_cvt_pk_bf16_f32 v16, v16, v17
	v_cvt_pk_bf16_f32 v17, v18, v19
	global_store_dwordx2 v[4:5], v[16:17], off
	s_and_saveexec_b64 s[12:13], s[10:11]
	s_cbranch_execz .LBB0_881
	v_lshlrev_b64 v[4:5], 6, v[2:3]
	s_waitcnt lgkmcnt(0)
	v_add_f32_e32 v3, v13, v14
	v_lshl_add_u64 v[4:5], v[6:7], 0, v[4:5]
	v_cndmask_b32_e32 v3, 0, v3, vcc
	global_store_dword v[4:5], v3, off
; __device__ __forceinline__ unsigned pk2(float lo, float hi) { unsigned r; asm volatile("v_cvt_pk_bf16_f32 %0, %1, %2" : "=v"(r) : "v"(lo), "v"(hi)); return r; }
;     ...
;         const int lane = threadIdx.x & 63, wv = threadIdx.x >> 6;
;         const int rbase = u.pm * 256 + (kq * 4 + u.pn) * 16 + wv * 2;
; #pragma unroll
;         for (int rr = 0; rr < 2; ++rr) {
;             const int row = rbase + rr; float sq = 0.f;
; #pragma unroll
;             for (int i = 0; i < 4; ++i) {
;                 const size_t o = (size_t)row * DM + i * 256 + lane * 4;
;                 f32x4 v = *(const f32x4*)(xold + o);
; #pragma unroll
;                 for (int q = 0; q < 4; ++q) v += *(const f32x4*)(part + (size_t)q * 1024 * DM + o);
;                 *(f32x4*)(xf_s + o) = v;
;                 u32x2 w; w.x = pk2(v[0], v[1]); w.y = pk2(v[2], v[3]); *(u32x2*)(xb_s + o) = w;
;                 sq += (v[0] * v[0] + v[1] * v[1]) + (v[2] * v[2] + v[3] * v[3]);
;             }
; #pragma unroll
;             for (int o = 32; o >= 1; o >>= 1) sq += __shfl_xor(sq, o);
;             if (lane < 16) ssq_s[(size_t)row * 16 + lane] = lane == 0 ? sq : 0.f;
;         }
.LBB0_881:
	s_or_b64 exec, exec, s[12:13]
	v_or_b32_e32 v2, 1, v2
	v_ashrrev_i32_e32 v3, 31, v2
	v_lshlrev_b64 v[4:5], 10, v[2:3]
	v_or_b32_e32 v4, v4, v0
	v_lshlrev_b64 v[34:35], 2, v[4:5]
	v_lshl_add_u64 v[48:49], s[16:17], 0, v[34:35]
	v_add_co_u32_e64 v50, s[12:13], s6, v48
	v_lshl_add_u64 v[46:47], s[14:15], 0, v[34:35]
	s_nop 0
	v_addc_co_u32_e64 v51, s[12:13], 0, v49, s[12:13]
	v_add_co_u32_e64 v52, s[12:13], s7, v48
	s_waitcnt lgkmcnt(0)
	global_load_dwordx4 v[14:17], v[46:47], off
	v_addc_co_u32_e64 v53, s[12:13], 0, v49, s[12:13]
	global_load_dwordx4 v[18:21], v[48:49], off
	global_load_dwordx4 v[22:25], v[50:51], off
	v_add_co_u32_e64 v54, s[12:13], s8, v48
	global_load_dwordx4 v[26:29], v[52:53], off
	s_nop 0
	v_addc_co_u32_e64 v55, s[12:13], 0, v49, s[12:13]
	global_load_dwordx4 v[30:33], v[54:55], off
	v_lshl_add_u64 v[36:37], v[4:5], 1, s[20:21]
	v_lshl_add_u64 v[34:35], s[22:23], 0, v[34:35]
	v_mov_b32_e32 v39, v5
	v_or_b32_e32 v38, 0x100, v4
	v_lshl_add_u64 v[40:41], v[38:39], 2, s[22:23]
	v_lshl_add_u64 v[38:39], v[38:39], 1, s[20:21]
	v_mov_b32_e32 v43, v5
	v_or_b32_e32 v42, 0x200, v4
	v_lshl_add_u64 v[44:45], v[42:43], 2, s[22:23]
	v_lshl_add_u64 v[42:43], v[42:43], 1, s[20:21]
	v_or_b32_e32 v4, 0x300, v4
	global_load_dwordx4 v[186:189], v[46:47], off offset:1024
	global_load_dwordx4 v[190:193], v[48:49], off offset:1024
	global_load_dwordx4 v[194:197], v[50:51], off offset:1024
	global_load_dwordx4 v[198:201], v[52:53], off offset:1024
	global_load_dwordx4 v[202:205], v[54:55], off offset:1024
	global_load_dwordx4 v[206:209], v[46:47], off offset:2048
	global_load_dwordx4 v[210:213], v[48:49], off offset:2048
	global_load_dwordx4 v[214:217], v[50:51], off offset:2048
	global_load_dwordx4 v[218:221], v[52:53], off offset:2048
	global_load_dwordx4 v[222:225], v[54:55], off offset:2048
	global_load_dwordx4 v[226:229], v[46:47], off offset:3072
	global_load_dwordx4 v[232:235], v[48:49], off offset:3072
	global_load_dwordx4 v[236:239], v[50:51], off offset:3072
	global_load_dwordx4 v[240:243], v[52:53], off offset:3072
	global_load_dwordx4 v[244:247], v[54:55], off offset:3072
	s_waitcnt vmcnt(18)
	v_pk_add_f32 v[16:17], v[16:17], v[20:21]
	v_pk_add_f32 v[14:15], v[14:15], v[18:19]
	s_waitcnt vmcnt(17)
	v_pk_add_f32 v[16:17], v[16:17], v[24:25]
	v_pk_add_f32 v[14:15], v[14:15], v[22:23]
	s_waitcnt vmcnt(16)
	v_pk_add_f32 v[16:17], v[16:17], v[28:29]
	v_pk_add_f32 v[14:15], v[14:15], v[26:27]
	s_waitcnt vmcnt(15)
	v_pk_add_f32 v[16:17], v[16:17], v[32:33]
	v_pk_add_f32 v[14:15], v[14:15], v[30:31]
	global_store_dwordx4 v[34:35], v[14:17], off
	v_cvt_pk_bf16_f32 v18, v14, v15
	v_cvt_pk_bf16_f32 v19, v16, v17
	global_store_dwordx2 v[36:37], v[18:19], off
	s_nop 0
	v_mul_f32_e32 v0, v15, v15
	v_mul_f32_e32 v13, v17, v17
	v_fmac_f32_e32 v0, v14, v14
	v_fmac_f32_e32 v13, v16, v16
	v_add_f32_e32 v0, v0, v13
	s_waitcnt vmcnt(12)
	v_mov_b64_e32 v[18:19], v[186:187]
	v_mov_b64_e32 v[20:21], v[188:189]
	v_mov_b64_e32 v[22:23], v[190:191]
	v_mov_b64_e32 v[24:25], v[192:193]
	v_mov_b64_e32 v[26:27], v[194:195]
	v_mov_b64_e32 v[28:29], v[196:197]
	v_mov_b64_e32 v[30:31], v[198:199]
	v_mov_b64_e32 v[32:33], v[200:201]
	v_mov_b64_e32 v[34:35], v[202:203]
	v_mov_b64_e32 v[36:37], v[204:205]
	v_pk_add_f32 v[20:21], v[20:21], v[24:25]
	v_pk_add_f32 v[18:19], v[18:19], v[22:23]
	v_pk_add_f32 v[20:21], v[20:21], v[28:29]
	v_pk_add_f32 v[18:19], v[18:19], v[26:27]
	v_pk_add_f32 v[20:21], v[20:21], v[32:33]
	v_pk_add_f32 v[18:19], v[18:19], v[30:31]
	v_pk_add_f32 v[20:21], v[20:21], v[36:37]
	v_pk_add_f32 v[18:19], v[18:19], v[34:35]
	global_store_dwordx4 v[40:41], v[18:21], off
	v_cvt_pk_bf16_f32 v22, v18, v19
	v_cvt_pk_bf16_f32 v23, v20, v21
	global_store_dwordx2 v[38:39], v[22:23], off
	s_nop 0
	v_mul_f32_e32 v13, v19, v19
	v_mul_f32_e32 v14, v21, v21
	v_fmac_f32_e32 v13, v18, v18
	v_fmac_f32_e32 v14, v20, v20
	v_add_f32_e32 v13, v13, v14
	v_add_f32_e32 v0, v0, v13
	s_waitcnt vmcnt(9)
	v_mov_b64_e32 v[22:23], v[206:207]
	v_mov_b64_e32 v[24:25], v[208:209]
	v_mov_b64_e32 v[26:27], v[210:211]
	v_mov_b64_e32 v[28:29], v[212:213]
	v_mov_b64_e32 v[30:31], v[214:215]
	v_mov_b64_e32 v[32:33], v[216:217]
	v_mov_b64_e32 v[34:35], v[218:219]
	v_mov_b64_e32 v[36:37], v[220:221]
	v_mov_b64_e32 v[38:39], v[222:223]
	v_mov_b64_e32 v[40:41], v[224:225]
	v_pk_add_f32 v[24:25], v[24:25], v[28:29]
	v_pk_add_f32 v[22:23], v[22:23], v[26:27]
	v_pk_add_f32 v[24:25], v[24:25], v[32:33]
	v_pk_add_f32 v[22:23], v[22:23], v[30:31]
	v_pk_add_f32 v[24:25], v[24:25], v[36:37]
	v_pk_add_f32 v[22:23], v[22:23], v[34:35]
	v_pk_add_f32 v[24:25], v[24:25], v[40:41]
	v_pk_add_f32 v[22:23], v[22:23], v[38:39]
	global_store_dwordx4 v[44:45], v[22:25], off
	v_cvt_pk_bf16_f32 v26, v22, v23
	v_cvt_pk_bf16_f32 v27, v24, v25
	global_store_dwordx2 v[42:43], v[26:27], off
	s_nop 0
	v_mul_f32_e32 v13, v23, v23
	v_mul_f32_e32 v14, v25, v25
	v_fmac_f32_e32 v13, v22, v22
	v_fmac_f32_e32 v14, v24, v24
	v_add_f32_e32 v13, v13, v14
	v_add_f32_e32 v0, v0, v13
	s_waitcnt vmcnt(6)
	v_mov_b64_e32 v[26:27], v[226:227]
	v_mov_b64_e32 v[28:29], v[228:229]
	v_mov_b64_e32 v[30:31], v[232:233]
	v_mov_b64_e32 v[32:33], v[234:235]
	v_mov_b64_e32 v[34:35], v[236:237]
	v_mov_b64_e32 v[36:37], v[238:239]
	v_mov_b64_e32 v[38:39], v[240:241]
	v_mov_b64_e32 v[40:41], v[242:243]
	v_mov_b64_e32 v[42:43], v[244:245]
	v_mov_b64_e32 v[44:45], v[246:247]
	v_pk_add_f32 v[14:15], v[28:29], v[32:33]
	v_pk_add_f32 v[16:17], v[26:27], v[30:31]
	v_pk_add_f32 v[14:15], v[14:15], v[36:37]
	v_pk_add_f32 v[16:17], v[16:17], v[34:35]
	v_pk_add_f32 v[14:15], v[14:15], v[40:41]
	v_pk_add_f32 v[18:19], v[16:17], v[38:39]
	v_pk_add_f32 v[16:17], v[14:15], v[44:45]
	v_pk_add_f32 v[14:15], v[18:19], v[42:43]
	v_mul_f32_e32 v18, v17, v17
	v_mul_f32_e32 v13, v15, v15
	v_fmac_f32_e32 v13, v14, v14
	v_fmac_f32_e32 v18, v16, v16
	v_add_f32_e32 v13, v13, v18
	v_add_f32_e32 v0, v0, v13
	ds_bpermute_b32 v1, v1, v0
	s_waitcnt lgkmcnt(0)
	v_add_f32_e32 v0, v0, v1
	ds_bpermute_b32 v1, v8, v0
	s_waitcnt lgkmcnt(0)
	v_add_f32_e32 v0, v0, v1
	ds_bpermute_b32 v1, v9, v0
	s_waitcnt lgkmcnt(0)
	v_add_f32_e32 v0, v0, v1
	ds_bpermute_b32 v1, v10, v0
	s_waitcnt lgkmcnt(0)
	v_add_f32_e32 v8, v0, v1
	ds_bpermute_b32 v9, v11, v8
	v_lshl_add_u64 v[0:1], v[4:5], 2, s[22:23]
	global_store_dwordx4 v[0:1], v[14:17], off
	v_lshl_add_u64 v[4:5], v[4:5], 1, s[20:21]
	s_waitcnt lgkmcnt(0)
	v_add_f32_e32 v0, v8, v9
	ds_bpermute_b32 v1, v12, v0
	v_cvt_pk_bf16_f32 v8, v14, v15
	v_cvt_pk_bf16_f32 v9, v16, v17
	global_store_dwordx2 v[4:5], v[8:9], off
	s_and_saveexec_b64 s[12:13], s[10:11]
	s_cbranch_execz .LBB0_883
	v_lshlrev_b64 v[2:3], 6, v[2:3]
	s_waitcnt lgkmcnt(0)
	v_add_f32_e32 v0, v0, v1
	v_lshl_add_u64 v[2:3], v[6:7], 0, v[2:3]
	v_cndmask_b32_e32 v0, 0, v0, vcc
	global_store_dword v[2:3], v0, off

; __device__ __forceinline__ unsigned pk2(float lo, float hi) { unsigned r; asm volatile("v_cvt_pk_bf16_f32 %0, %1, %2" : "=v"(r) : "v"(lo), "v"(hi)); return r; }
;     __device__ __forceinline__ void operator()(const f32x4 (&acc)[2][2][4][2], const Unit& u, int wr, int wc, int fr, int fq) const {
;     ...
;         const float* xo = (u.pm < 64) ? xoldA : (xoldB - (size_t)T_P * DM);
; #pragma unroll
;         for (int ai = 0; ai < 2; ++ai)
; #pragma unroll
;             for (int m = 0; m < 4; ++m) {
;                 const int row = row0 + ai * 128 + m * 16; const size_t ro = (size_t)row * DM + col0;
;                 float s = 0.f;
; #pragma unroll
;                 for (int bj = 0; bj < 2; ++bj)
; #pragma unroll
;                     for (int n = 0; n < 2; ++n) {
;                         const size_t o = ro + bj * 128 + n * 16;
;                         const f32x4 xn = *(const f32x4*)(xo + o) + acc[ai][bj][m][n];
;                         *(f32x4*)(xf + o) = xn;
;                         u32x2 w; w.x = pk2(xn[0], xn[1]); w.y = pk2(xn[2], xn[3]); *(u32x2*)(xb + o) = w;
;                         s += (xn[0] * xn[0] + xn[1] * xn[1]) + (xn[2] * xn[2] + xn[3] * xn[3]);
;                     }
;                 s += __shfl_xor(s, 16); s += __shfl_xor(s, 32);
;                 if (fq == 0) ssq[(size_t)row * 16 + u.pn * 4 + wc] = s;
.LBB0_1037:
	v_lshl_add_u32 v138, s58, 8, v140
	v_lshl_or_b32 v136, s56, 8, v142
	v_ashrrev_i32_e32 v139, 31, v138
	v_ashrrev_i32_e32 v137, 31, v136
	v_lshlrev_b64 v[148:149], 10, v[138:139]
	s_cmp_lt_i32 s58, 64
	v_lshl_add_u64 v[152:153], v[148:149], 0, v[136:137]
	s_cselect_b32 s17, s21, -1
	s_cselect_b32 s16, s20, 0xfc000000
	v_lshlrev_b64 v[154:155], 2, v[152:153]
	v_lshl_add_u64 v[156:157], s[16:17], 0, v[154:155]
	v_subrev_u32_e32 v162, s16, v156
	v_add_u32_e32 v163, 0x0, v162
	global_load_dwordx4 v[170:173], v163, s[16:17]
	v_add_u32_e32 v163, 0x40, v162
	global_load_dwordx4 v[174:177], v163, s[16:17]
	v_add_u32_e32 v163, 0x200, v162
	global_load_dwordx4 v[178:181], v163, s[16:17]
	v_add_u32_e32 v163, 0x240, v162
	global_load_dwordx4 v[182:185], v163, s[16:17]
	v_add_u32_e32 v163, 0x10000, v162
	global_load_dwordx4 v[186:189], v163, s[16:17]
	v_add_u32_e32 v163, 0x10040, v162
	global_load_dwordx4 v[190:193], v163, s[16:17]
	v_add_u32_e32 v163, 0x10200, v162
	global_load_dwordx4 v[194:197], v163, s[16:17]
	v_add_u32_e32 v163, 0x10240, v162
	global_load_dwordx4 v[198:201], v163, s[16:17]
	v_add_u32_e32 v163, 0x20000, v162
	global_load_dwordx4 v[202:205], v163, s[16:17]
	v_add_u32_e32 v163, 0x20040, v162
	global_load_dwordx4 v[206:209], v163, s[16:17]
	v_add_u32_e32 v163, 0x20200, v162
	global_load_dwordx4 v[210:213], v163, s[16:17]
	v_add_u32_e32 v163, 0x20240, v162
	global_load_dwordx4 v[232:235], v163, s[16:17]
	v_add_u32_e32 v163, 0x30000, v162
	global_load_dwordx4 v[236:239], v163, s[16:17]
	v_add_u32_e32 v163, 0x30040, v162
	global_load_dwordx4 v[240:243], v163, s[16:17]
	v_add_u32_e32 v163, 0x30200, v162
	global_load_dwordx4 v[244:247], v163, s[16:17]
	v_add_u32_e32 v163, 0x30240, v162
	global_load_dwordx4 v[248:251], v163, s[16:17]
	v_add_u32_e32 v163, 0x80000, v162
	global_load_dwordx4 v[252:255], v163, s[16:17]
	v_lshl_add_u64 v[158:159], v[152:153], 1, s[26:27]
	v_lshl_add_u64 v[160:161], s[20:21], 0, v[154:155]
	v_xor_b32_e32 v147, 32, v146
	s_lshl_b32 s56, s56, 2
	s_ashr_i32 s57, s56, 31
	s_waitcnt vmcnt(16)
	v_mov_b64_e32 v[148:149], v[170:171]
	v_mov_b64_e32 v[150:151], v[172:173]
	v_add_u32_e32 v163, 0x80040, v162
	global_load_dwordx4 v[170:173], v163, s[16:17]
	v_pk_add_f32 v[126:127], v[126:127], v[150:151]
	v_pk_add_f32 v[124:125], v[124:125], v[148:149]
	global_store_dwordx4 v[160:161], v[124:127], off
	v_cvt_pk_bf16_f32 v148, v124, v125
	v_cvt_pk_bf16_f32 v149, v126, v127
	global_store_dwordx2 v[158:159], v[148:149], off
	s_waitcnt vmcnt(18)
	v_mov_b64_e32 v[148:149], v[174:175]
	v_mov_b64_e32 v[150:151], v[176:177]
	v_add_u32_e32 v163, 0x80200, v162
	global_load_dwordx4 v[174:177], v163, s[16:17]
	v_pk_add_f32 v[122:123], v[122:123], v[150:151]
	v_pk_add_f32 v[120:121], v[120:121], v[148:149]
	global_store_dwordx4 v[160:161], v[120:123], off offset:64
	v_cvt_pk_bf16_f32 v148, v120, v121
	v_cvt_pk_bf16_f32 v149, v122, v123
	global_store_dwordx2 v[158:159], v[148:149], off offset:32
	s_waitcnt vmcnt(20)
	v_mov_b64_e32 v[148:149], v[178:179]
	v_mov_b64_e32 v[150:151], v[180:181]
	v_add_u32_e32 v163, 0x80240, v162
	global_load_dwordx4 v[178:181], v163, s[16:17]
	v_pk_add_f32 v[150:151], v[118:119], v[150:151]
	v_pk_add_f32 v[148:149], v[116:117], v[148:149]
	global_store_dwordx4 v[160:161], v[148:151], off offset:512
	v_cvt_pk_bf16_f32 v116, v148, v149
	v_cvt_pk_bf16_f32 v117, v150, v151
	global_store_dwordx2 v[158:159], v[116:117], off offset:256
	v_mul_f32_e32 v118, v125, v125
	v_mul_f32_e32 v119, v127, v127
	v_fmac_f32_e32 v118, v124, v124
	v_fmac_f32_e32 v119, v126, v126
	v_add_f32_e32 v118, v118, v119
	v_mul_f32_e32 v119, v121, v121
	v_mul_f32_e32 v121, v123, v123
	v_fmac_f32_e32 v119, v120, v120
	v_fmac_f32_e32 v121, v122, v122
	v_add_f32_e32 v119, v119, v121
	v_add_f32_e32 v118, v118, v119
	v_mul_f32_e32 v119, v149, v149
	v_mul_f32_e32 v120, v151, v151
	v_fmac_f32_e32 v119, v148, v148
	v_fmac_f32_e32 v120, v150, v150
	v_add_f32_e32 v119, v119, v120
	v_and_b32_e32 v117, 64, v146
	v_add_f32_e32 v122, v118, v119
	v_xor_b32_e32 v116, 16, v146
	v_add_u32_e32 v117, 64, v117
	v_cmp_lt_i32_e32 vcc, v116, v117
	s_waitcnt vmcnt(22)
	v_mov_b64_e32 v[152:153], v[182:183]
	v_mov_b64_e32 v[154:155], v[184:185]
	v_add_u32_e32 v163, 0x90000, v162
	global_load_dwordx4 v[182:185], v163, s[16:17]
	v_pk_add_f32 v[120:121], v[114:115], v[154:155]
	v_pk_add_f32 v[118:119], v[112:113], v[152:153]
	v_mul_f32_e32 v113, v121, v121
	v_mul_f32_e32 v112, v119, v119
	v_fmac_f32_e32 v112, v118, v118
	v_fmac_f32_e32 v113, v120, v120
	v_cndmask_b32_e32 v116, v146, v116, vcc
	v_add_f32_e32 v112, v112, v113
	v_lshlrev_b32_e32 v116, 2, v116
	v_add_f32_e32 v112, v122, v112
	ds_bpermute_b32 v113, v116, v112
	v_cmp_lt_i32_e32 vcc, v147, v117
	global_store_dwordx4 v[160:161], v[118:121], off offset:576
	s_waitcnt lgkmcnt(0)
	v_add_f32_e32 v112, v112, v113
	v_cndmask_b32_e32 v114, v146, v147, vcc
	v_lshlrev_b32_e32 v114, 2, v114
	ds_bpermute_b32 v113, v114, v112
	v_cvt_pk_bf16_f32 v118, v118, v119
	v_cvt_pk_bf16_f32 v119, v120, v121
	global_store_dwordx2 v[158:159], v[118:119], off offset:288
	s_and_saveexec_b64 s[58:59], s[12:13]
	s_cbranch_execz .LBB0_1039
	s_waitcnt lgkmcnt(0)
	v_add_f32_e32 v115, v112, v113
	v_lshlrev_b64 v[112:113], 6, v[138:139]
	v_lshl_add_u64 v[112:113], s[28:29], 0, v[112:113]
	v_lshl_add_u64 v[112:113], s[56:57], 2, v[112:113]
	s_lshl_b32 s30, s84, 2
	v_lshl_add_u64 v[112:113], v[112:113], 0, s[30:31]
	global_store_dword v[112:113], v115, off
; __device__ __forceinline__ unsigned pk2(float lo, float hi) { unsigned r; asm volatile("v_cvt_pk_bf16_f32 %0, %1, %2" : "=v"(r) : "v"(lo), "v"(hi)); return r; }
;     __device__ __forceinline__ void operator()(const f32x4 (&acc)[2][2][4][2], const Unit& u, int wr, int wc, int fr, int fq) const {
;     ...
;         const float* xo = (u.pm < 64) ? xoldA : (xoldB - (size_t)T_P * DM);
; #pragma unroll
;         for (int ai = 0; ai < 2; ++ai)
; #pragma unroll
;             for (int m = 0; m < 4; ++m) {
;                 const int row = row0 + ai * 128 + m * 16; const size_t ro = (size_t)row * DM + col0;
;                 float s = 0.f;
; #pragma unroll
;                 for (int bj = 0; bj < 2; ++bj)
; #pragma unroll
;                     for (int n = 0; n < 2; ++n) {
;                         const size_t o = ro + bj * 128 + n * 16;
;                         const f32x4 xn = *(const f32x4*)(xo + o) + acc[ai][bj][m][n];
;                         *(f32x4*)(xf + o) = xn;
;                         u32x2 w; w.x = pk2(xn[0], xn[1]); w.y = pk2(xn[2], xn[3]); *(u32x2*)(xb + o) = w;
;                         s += (xn[0] * xn[0] + xn[1] * xn[1]) + (xn[2] * xn[2] + xn[3] * xn[3]);
;                     }
;                 s += __shfl_xor(s, 16); s += __shfl_xor(s, 32);
;                 if (fq == 0) ssq[(size_t)row * 16 + u.pn * 4 + wc] = s;
.LBB0_1039:
	s_or_b64 exec, exec, s[58:59]
	v_or_b32_e32 v112, 16, v138
	s_waitcnt lgkmcnt(0)
	v_ashrrev_i32_e32 v113, 31, v112
	v_lshlrev_b64 v[118:119], 10, v[112:113]
	v_lshl_add_u64 v[122:123], v[118:119], 0, v[136:137]
	v_lshlrev_b64 v[124:125], 2, v[122:123]
	v_lshl_add_u64 v[126:127], s[16:17], 0, v[124:125]
	v_lshl_add_u64 v[122:123], v[122:123], 1, s[26:27]
	v_lshl_add_u64 v[124:125], s[20:21], 0, v[124:125]
	s_waitcnt vmcnt(24)
	v_mov_b64_e32 v[118:119], v[186:187]
	v_mov_b64_e32 v[120:121], v[188:189]
	v_add_u32_e32 v163, 0x90040, v162
	global_load_dwordx4 v[186:189], v163, s[16:17]
	v_pk_add_f32 v[110:111], v[110:111], v[120:121]
	v_pk_add_f32 v[108:109], v[108:109], v[118:119]
	global_store_dwordx4 v[124:125], v[108:111], off
	v_cvt_pk_bf16_f32 v118, v108, v109
	v_cvt_pk_bf16_f32 v119, v110, v111
	global_store_dwordx2 v[122:123], v[118:119], off
	v_mul_f32_e32 v109, v109, v109
	v_mul_f32_e32 v111, v111, v111
	v_fmac_f32_e32 v109, v108, v108
	v_fmac_f32_e32 v111, v110, v110
	v_add_f32_e32 v108, v109, v111
	s_waitcnt vmcnt(26)
	v_mov_b64_e32 v[118:119], v[190:191]
	v_mov_b64_e32 v[120:121], v[192:193]
	v_add_u32_e32 v163, 0x90200, v162
	global_load_dwordx4 v[190:193], v163, s[16:17]
	v_pk_add_f32 v[106:107], v[106:107], v[120:121]
	v_pk_add_f32 v[104:105], v[104:105], v[118:119]
	global_store_dwordx4 v[124:125], v[104:107], off offset:64
	v_cvt_pk_bf16_f32 v118, v104, v105
	v_cvt_pk_bf16_f32 v119, v106, v107
	global_store_dwordx2 v[122:123], v[118:119], off offset:32
	v_mul_f32_e32 v105, v105, v105
	v_mul_f32_e32 v107, v107, v107
	v_fmac_f32_e32 v105, v104, v104
	v_fmac_f32_e32 v107, v106, v106
	v_add_f32_e32 v104, v105, v107
	v_add_f32_e32 v104, v108, v104
	s_waitcnt vmcnt(28)
	v_mov_b64_e32 v[118:119], v[194:195]
	v_mov_b64_e32 v[120:121], v[196:197]
	v_add_u32_e32 v163, 0x90240, v162
	global_load_dwordx4 v[194:197], v163, s[16:17]
	v_pk_add_f32 v[102:103], v[102:103], v[120:121]
	v_pk_add_f32 v[100:101], v[100:101], v[118:119]
	global_store_dwordx4 v[124:125], v[100:103], off offset:512
	v_cvt_pk_bf16_f32 v118, v100, v101
	v_cvt_pk_bf16_f32 v119, v102, v103
	global_store_dwordx2 v[122:123], v[118:119], off offset:256
	v_mul_f32_e32 v101, v101, v101
	v_mul_f32_e32 v103, v103, v103
	v_fmac_f32_e32 v101, v100, v100
	v_fmac_f32_e32 v103, v102, v102
	v_add_f32_e32 v100, v101, v103
	v_add_f32_e32 v102, v104, v100
	s_waitcnt vmcnt(30)
	v_mov_b64_e32 v[118:119], v[198:199]
	v_mov_b64_e32 v[120:121], v[200:201]
	v_add_u32_e32 v163, 0xa0000, v162
	global_load_dwordx4 v[198:201], v163, s[16:17]
	v_pk_add_f32 v[100:101], v[98:99], v[120:121]
	v_pk_add_f32 v[98:99], v[96:97], v[118:119]
	v_mul_f32_e32 v97, v101, v101
	v_mul_f32_e32 v96, v99, v99
	v_fmac_f32_e32 v96, v98, v98
	v_fmac_f32_e32 v97, v100, v100
	v_add_f32_e32 v96, v96, v97
	v_add_f32_e32 v96, v102, v96
	ds_bpermute_b32 v97, v116, v96
	global_store_dwordx4 v[124:125], v[98:101], off offset:576
	s_waitcnt lgkmcnt(0)
	v_add_f32_e32 v96, v96, v97
	ds_bpermute_b32 v97, v114, v96
	v_cvt_pk_bf16_f32 v98, v98, v99
	v_cvt_pk_bf16_f32 v99, v100, v101
	global_store_dwordx2 v[122:123], v[98:99], off offset:288
	s_and_saveexec_b64 s[58:59], s[12:13]
	s_cbranch_execz .LBB0_1041
	s_waitcnt lgkmcnt(0)
	v_add_f32_e32 v98, v96, v97
	v_lshlrev_b64 v[96:97], 6, v[112:113]
	v_lshl_add_u64 v[96:97], s[28:29], 0, v[96:97]
	v_lshl_add_u64 v[96:97], s[56:57], 2, v[96:97]
	s_lshl_b32 s30, s84, 2
	v_lshl_add_u64 v[96:97], v[96:97], 0, s[30:31]
	global_store_dword v[96:97], v98, off
.LBB0_1041:
	s_or_b64 exec, exec, s[58:59]
	v_or_b32_e32 v96, 32, v138
	s_waitcnt lgkmcnt(0)
	v_ashrrev_i32_e32 v97, 31, v96
	v_lshlrev_b64 v[98:99], 10, v[96:97]
	v_lshl_add_u64 v[102:103], v[98:99], 0, v[136:137]
	v_lshlrev_b64 v[104:105], 2, v[102:103]
	v_lshl_add_u64 v[106:107], s[16:17], 0, v[104:105]
	v_lshl_add_u64 v[102:103], v[102:103], 1, s[26:27]
	v_lshl_add_u64 v[104:105], s[20:21], 0, v[104:105]
	s_waitcnt vmcnt(32)
	v_mov_b64_e32 v[98:99], v[202:203]
	v_mov_b64_e32 v[100:101], v[204:205]
	v_add_u32_e32 v163, 0xa0040, v162
	global_load_dwordx4 v[202:205], v163, s[16:17]
	v_pk_add_f32 v[94:95], v[94:95], v[100:101]
	v_pk_add_f32 v[92:93], v[92:93], v[98:99]
	global_store_dwordx4 v[104:105], v[92:95], off
	v_cvt_pk_bf16_f32 v98, v92, v93
	v_cvt_pk_bf16_f32 v99, v94, v95
	global_store_dwordx2 v[102:103], v[98:99], off
	v_mul_f32_e32 v93, v93, v93
	v_mul_f32_e32 v95, v95, v95
	v_fmac_f32_e32 v93, v92, v92
	v_fmac_f32_e32 v95, v94, v94
	v_add_f32_e32 v92, v93, v95
	s_waitcnt vmcnt(34)
	v_mov_b64_e32 v[98:99], v[206:207]
	v_mov_b64_e32 v[100:101], v[208:209]
	v_add_u32_e32 v163, 0xa0200, v162
	global_load_dwordx4 v[206:209], v163, s[16:17]
	v_pk_add_f32 v[90:91], v[90:91], v[100:101]
	v_pk_add_f32 v[88:89], v[88:89], v[98:99]
	global_store_dwordx4 v[104:105], v[88:91], off offset:64
	v_cvt_pk_bf16_f32 v98, v88, v89
	v_cvt_pk_bf16_f32 v99, v90, v91
	global_store_dwordx2 v[102:103], v[98:99], off offset:32
	v_mul_f32_e32 v89, v89, v89
	v_mul_f32_e32 v91, v91, v91
	v_fmac_f32_e32 v89, v88, v88
	v_fmac_f32_e32 v91, v90, v90
	v_add_f32_e32 v88, v89, v91
	v_add_f32_e32 v88, v92, v88
	s_waitcnt vmcnt(36)
	v_mov_b64_e32 v[98:99], v[210:211]
	v_mov_b64_e32 v[100:101], v[212:213]
	v_add_u32_e32 v163, 0xa0240, v162
	global_load_dwordx4 v[210:213], v163, s[16:17]
	v_pk_add_f32 v[86:87], v[86:87], v[100:101]
	v_pk_add_f32 v[84:85], v[84:85], v[98:99]
	global_store_dwordx4 v[104:105], v[84:87], off offset:512
	v_cvt_pk_bf16_f32 v98, v84, v85
	v_cvt_pk_bf16_f32 v99, v86, v87
	global_store_dwordx2 v[102:103], v[98:99], off offset:256
	v_mul_f32_e32 v85, v85, v85
	v_mul_f32_e32 v87, v87, v87
	v_fmac_f32_e32 v85, v84, v84
	v_fmac_f32_e32 v87, v86, v86
	v_add_f32_e32 v84, v85, v87
	v_add_f32_e32 v86, v88, v84
	s_waitcnt vmcnt(38)
	v_mov_b64_e32 v[98:99], v[232:233]
	v_mov_b64_e32 v[100:101], v[234:235]
	v_add_u32_e32 v163, 0xb0000, v162
	global_load_dwordx4 v[232:235], v163, s[16:17]
	v_pk_add_f32 v[84:85], v[82:83], v[100:101]
	v_pk_add_f32 v[82:83], v[80:81], v[98:99]
	v_mul_f32_e32 v81, v85, v85
	v_mul_f32_e32 v80, v83, v83
	v_fmac_f32_e32 v80, v82, v82
	v_fmac_f32_e32 v81, v84, v84
	v_add_f32_e32 v80, v80, v81
	v_add_f32_e32 v80, v86, v80
	ds_bpermute_b32 v81, v116, v80
	global_store_dwordx4 v[104:105], v[82:85], off offset:576
	s_waitcnt lgkmcnt(0)
	v_add_f32_e32 v80, v80, v81
	ds_bpermute_b32 v81, v114, v80
	v_cvt_pk_bf16_f32 v82, v82, v83
	v_cvt_pk_bf16_f32 v83, v84, v85
	global_store_dwordx2 v[102:103], v[82:83], off offset:288
	s_and_saveexec_b64 s[58:59], s[12:13]
	s_cbranch_execz .LBB0_1043
	s_waitcnt lgkmcnt(0)
	v_add_f32_e32 v82, v80, v81
	v_lshlrev_b64 v[80:81], 6, v[96:97]
	v_lshl_add_u64 v[80:81], s[28:29], 0, v[80:81]
	v_lshl_add_u64 v[80:81], s[56:57], 2, v[80:81]
	s_lshl_b32 s30, s84, 2
	v_lshl_add_u64 v[80:81], v[80:81], 0, s[30:31]
	global_store_dword v[80:81], v82, off
; __device__ __forceinline__ unsigned pk2(float lo, float hi) { unsigned r; asm volatile("v_cvt_pk_bf16_f32 %0, %1, %2" : "=v"(r) : "v"(lo), "v"(hi)); return r; }
;     __device__ __forceinline__ void operator()(const f32x4 (&acc)[2][2][4][2], const Unit& u, int wr, int wc, int fr, int fq) const {
;     ...
;         const float* xo = (u.pm < 64) ? xoldA : (xoldB - (size_t)T_P * DM);
; #pragma unroll
;         for (int ai = 0; ai < 2; ++ai)
; #pragma unroll
;             for (int m = 0; m < 4; ++m) {
;                 const int row = row0 + ai * 128 + m * 16; const size_t ro = (size_t)row * DM + col0;
;                 float s = 0.f;
; #pragma unroll
;                 for (int bj = 0; bj < 2; ++bj)
; #pragma unroll
;                     for (int n = 0; n < 2; ++n) {
;                         const size_t o = ro + bj * 128 + n * 16;
;                         const f32x4 xn = *(const f32x4*)(xo + o) + acc[ai][bj][m][n];
;                         *(f32x4*)(xf + o) = xn;
;                         u32x2 w; w.x = pk2(xn[0], xn[1]); w.y = pk2(xn[2], xn[3]); *(u32x2*)(xb + o) = w;
;                         s += (xn[0] * xn[0] + xn[1] * xn[1]) + (xn[2] * xn[2] + xn[3] * xn[3]);
;                     }
;                 s += __shfl_xor(s, 16); s += __shfl_xor(s, 32);
;                 if (fq == 0) ssq[(size_t)row * 16 + u.pn * 4 + wc] = s;
.LBB0_1043:
	s_or_b64 exec, exec, s[58:59]
	v_or_b32_e32 v80, 48, v138
	s_waitcnt lgkmcnt(0)
	v_ashrrev_i32_e32 v81, 31, v80
	v_lshlrev_b64 v[82:83], 10, v[80:81]
	v_lshl_add_u64 v[86:87], v[82:83], 0, v[136:137]
	v_lshlrev_b64 v[88:89], 2, v[86:87]
	v_lshl_add_u64 v[90:91], s[16:17], 0, v[88:89]
	v_lshl_add_u64 v[86:87], v[86:87], 1, s[26:27]
	v_lshl_add_u64 v[88:89], s[20:21], 0, v[88:89]
	s_waitcnt vmcnt(40)
	v_mov_b64_e32 v[82:83], v[236:237]
	v_mov_b64_e32 v[84:85], v[238:239]
	v_add_u32_e32 v163, 0xb0040, v162
	global_load_dwordx4 v[236:239], v163, s[16:17]
	v_pk_add_f32 v[78:79], v[78:79], v[84:85]
	v_pk_add_f32 v[76:77], v[76:77], v[82:83]
	global_store_dwordx4 v[88:89], v[76:79], off
	v_cvt_pk_bf16_f32 v82, v76, v77
	v_cvt_pk_bf16_f32 v83, v78, v79
	global_store_dwordx2 v[86:87], v[82:83], off
	v_mul_f32_e32 v77, v77, v77
	v_mul_f32_e32 v79, v79, v79
	v_fmac_f32_e32 v77, v76, v76
	v_fmac_f32_e32 v79, v78, v78
	v_add_f32_e32 v76, v77, v79
	s_waitcnt vmcnt(42)
	v_mov_b64_e32 v[82:83], v[240:241]
	v_mov_b64_e32 v[84:85], v[242:243]
	v_add_u32_e32 v163, 0xb0200, v162
	global_load_dwordx4 v[240:243], v163, s[16:17]
	v_pk_add_f32 v[74:75], v[74:75], v[84:85]
	v_pk_add_f32 v[72:73], v[72:73], v[82:83]
	global_store_dwordx4 v[88:89], v[72:75], off offset:64
	v_cvt_pk_bf16_f32 v82, v72, v73
	v_cvt_pk_bf16_f32 v83, v74, v75
	global_store_dwordx2 v[86:87], v[82:83], off offset:32
	v_mul_f32_e32 v73, v73, v73
	v_mul_f32_e32 v75, v75, v75
	v_fmac_f32_e32 v73, v72, v72
	v_fmac_f32_e32 v75, v74, v74
	v_add_f32_e32 v72, v73, v75
	v_add_f32_e32 v72, v76, v72
	s_waitcnt vmcnt(44)
	v_mov_b64_e32 v[82:83], v[244:245]
	v_mov_b64_e32 v[84:85], v[246:247]
	v_add_u32_e32 v163, 0xb0240, v162
	global_load_dwordx4 v[244:247], v163, s[16:17]
	v_pk_add_f32 v[70:71], v[70:71], v[84:85]
	v_pk_add_f32 v[68:69], v[68:69], v[82:83]
	global_store_dwordx4 v[88:89], v[68:71], off offset:512
	v_cvt_pk_bf16_f32 v82, v68, v69
	v_cvt_pk_bf16_f32 v83, v70, v71
	global_store_dwordx2 v[86:87], v[82:83], off offset:256
	v_mul_f32_e32 v69, v69, v69
	v_mul_f32_e32 v71, v71, v71
	v_fmac_f32_e32 v69, v68, v68
	v_fmac_f32_e32 v71, v70, v70
	v_add_f32_e32 v68, v69, v71
	v_add_f32_e32 v70, v72, v68
	s_waitcnt vmcnt(46)
	v_mov_b64_e32 v[82:83], v[248:249]
	v_mov_b64_e32 v[84:85], v[250:251]
	v_pk_add_f32 v[68:69], v[66:67], v[84:85]
	v_pk_add_f32 v[66:67], v[64:65], v[82:83]
	v_mul_f32_e32 v65, v69, v69
	v_mul_f32_e32 v64, v67, v67
	v_fmac_f32_e32 v64, v66, v66
	v_fmac_f32_e32 v65, v68, v68
	v_add_f32_e32 v64, v64, v65
	v_add_f32_e32 v64, v70, v64
	ds_bpermute_b32 v65, v116, v64
	global_store_dwordx4 v[88:89], v[66:69], off offset:576
	s_waitcnt lgkmcnt(0)
	v_add_f32_e32 v64, v64, v65
	ds_bpermute_b32 v65, v114, v64
	v_cvt_pk_bf16_f32 v66, v66, v67
	v_cvt_pk_bf16_f32 v67, v68, v69
	global_store_dwordx2 v[86:87], v[66:67], off offset:288
	s_and_saveexec_b64 s[58:59], s[12:13]
	s_cbranch_execz .LBB0_1045
	s_waitcnt lgkmcnt(0)
	v_add_f32_e32 v66, v64, v65
	v_lshlrev_b64 v[64:65], 6, v[80:81]
	v_lshl_add_u64 v[64:65], s[28:29], 0, v[64:65]
	v_lshl_add_u64 v[64:65], s[56:57], 2, v[64:65]
	s_lshl_b32 s30, s84, 2
	v_lshl_add_u64 v[64:65], v[64:65], 0, s[30:31]
	global_store_dword v[64:65], v66, off
.LBB0_1045:
	s_or_b64 exec, exec, s[58:59]
	v_add_u32_e32 v64, 0x80, v138
	s_waitcnt lgkmcnt(0)
	v_ashrrev_i32_e32 v65, 31, v64
	v_lshlrev_b64 v[66:67], 10, v[64:65]
	v_lshl_add_u64 v[70:71], v[66:67], 0, v[136:137]
	v_lshlrev_b64 v[72:73], 2, v[70:71]
	v_lshl_add_u64 v[74:75], s[16:17], 0, v[72:73]
	v_lshl_add_u64 v[70:71], v[70:71], 1, s[26:27]
	v_lshl_add_u64 v[72:73], s[20:21], 0, v[72:73]
	s_waitcnt vmcnt(47)
	v_mov_b64_e32 v[66:67], v[252:253]
	v_mov_b64_e32 v[68:69], v[254:255]
	v_pk_add_f32 v[62:63], v[62:63], v[68:69]
	v_pk_add_f32 v[60:61], v[60:61], v[66:67]
	global_store_dwordx4 v[72:73], v[60:63], off
	v_cvt_pk_bf16_f32 v66, v60, v61
	v_cvt_pk_bf16_f32 v67, v62, v63
	global_store_dwordx2 v[70:71], v[66:67], off
	v_mul_f32_e32 v61, v61, v61
	v_mul_f32_e32 v63, v63, v63
	v_fmac_f32_e32 v61, v60, v60
	v_fmac_f32_e32 v63, v62, v62
	v_add_f32_e32 v60, v61, v63
	s_waitcnt vmcnt(48)
	v_mov_b64_e32 v[66:67], v[170:171]
	v_mov_b64_e32 v[68:69], v[172:173]
	v_pk_add_f32 v[58:59], v[58:59], v[68:69]
	v_pk_add_f32 v[56:57], v[56:57], v[66:67]
	global_store_dwordx4 v[72:73], v[56:59], off offset:64
	v_cvt_pk_bf16_f32 v66, v56, v57
	v_cvt_pk_bf16_f32 v67, v58, v59
	global_store_dwordx2 v[70:71], v[66:67], off offset:32
	v_mul_f32_e32 v57, v57, v57
	v_mul_f32_e32 v59, v59, v59
	v_fmac_f32_e32 v57, v56, v56
	v_fmac_f32_e32 v59, v58, v58
	v_add_f32_e32 v56, v57, v59
	v_add_f32_e32 v56, v60, v56
	s_waitcnt vmcnt(47)
	v_mov_b64_e32 v[66:67], v[174:175]
	v_mov_b64_e32 v[68:69], v[176:177]
	v_pk_add_f32 v[54:55], v[54:55], v[68:69]
	v_pk_add_f32 v[52:53], v[52:53], v[66:67]
	global_store_dwordx4 v[72:73], v[52:55], off offset:512
	v_cvt_pk_bf16_f32 v66, v52, v53
	v_cvt_pk_bf16_f32 v67, v54, v55
	global_store_dwordx2 v[70:71], v[66:67], off offset:256
	v_mul_f32_e32 v53, v53, v53
	v_mul_f32_e32 v55, v55, v55
	v_fmac_f32_e32 v53, v52, v52
	v_fmac_f32_e32 v55, v54, v54
	v_add_f32_e32 v52, v53, v55
	v_add_f32_e32 v54, v56, v52
	s_waitcnt vmcnt(46)
	v_mov_b64_e32 v[66:67], v[178:179]
	v_mov_b64_e32 v[68:69], v[180:181]
	v_pk_add_f32 v[52:53], v[50:51], v[68:69]
	v_pk_add_f32 v[50:51], v[48:49], v[66:67]
	v_mul_f32_e32 v49, v53, v53
	v_mul_f32_e32 v48, v51, v51
	v_fmac_f32_e32 v48, v50, v50
	v_fmac_f32_e32 v49, v52, v52
	v_add_f32_e32 v48, v48, v49
	v_add_f32_e32 v48, v54, v48
	ds_bpermute_b32 v49, v116, v48
	global_store_dwordx4 v[72:73], v[50:53], off offset:576
	s_waitcnt lgkmcnt(0)
	v_add_f32_e32 v48, v48, v49
	ds_bpermute_b32 v49, v114, v48
	v_cvt_pk_bf16_f32 v50, v50, v51
	v_cvt_pk_bf16_f32 v51, v52, v53
	global_store_dwordx2 v[70:71], v[50:51], off offset:288
	s_and_saveexec_b64 s[58:59], s[12:13]
	s_cbranch_execz .LBB0_1047
	s_waitcnt lgkmcnt(0)
	v_add_f32_e32 v50, v48, v49
	v_lshlrev_b64 v[48:49], 6, v[64:65]
	v_lshl_add_u64 v[48:49], s[28:29], 0, v[48:49]
	v_lshl_add_u64 v[48:49], s[56:57], 2, v[48:49]
	s_lshl_b32 s30, s84, 2
	v_lshl_add_u64 v[48:49], v[48:49], 0, s[30:31]
	global_store_dword v[48:49], v50, off
; __device__ __forceinline__ unsigned pk2(float lo, float hi) { unsigned r; asm volatile("v_cvt_pk_bf16_f32 %0, %1, %2" : "=v"(r) : "v"(lo), "v"(hi)); return r; }
;     __device__ __forceinline__ void operator()(const f32x4 (&acc)[2][2][4][2], const Unit& u, int wr, int wc, int fr, int fq) const {
;     ...
;         const float* xo = (u.pm < 64) ? xoldA : (xoldB - (size_t)T_P * DM);
; #pragma unroll
;         for (int ai = 0; ai < 2; ++ai)
; #pragma unroll
;             for (int m = 0; m < 4; ++m) {
;                 const int row = row0 + ai * 128 + m * 16; const size_t ro = (size_t)row * DM + col0;
;                 float s = 0.f;
; #pragma unroll
;                 for (int bj = 0; bj < 2; ++bj)
; #pragma unroll
;                     for (int n = 0; n < 2; ++n) {
;                         const size_t o = ro + bj * 128 + n * 16;
;                         const f32x4 xn = *(const f32x4*)(xo + o) + acc[ai][bj][m][n];
;                         *(f32x4*)(xf + o) = xn;
;                         u32x2 w; w.x = pk2(xn[0], xn[1]); w.y = pk2(xn[2], xn[3]); *(u32x2*)(xb + o) = w;
;                         s += (xn[0] * xn[0] + xn[1] * xn[1]) + (xn[2] * xn[2] + xn[3] * xn[3]);
;                     }
;                 s += __shfl_xor(s, 16); s += __shfl_xor(s, 32);
;                 if (fq == 0) ssq[(size_t)row * 16 + u.pn * 4 + wc] = s;
.LBB0_1047:
	s_or_b64 exec, exec, s[58:59]
	v_add_u32_e32 v48, 0x90, v138
	s_waitcnt lgkmcnt(0)
	v_ashrrev_i32_e32 v49, 31, v48
	v_lshlrev_b64 v[50:51], 10, v[48:49]
	v_lshl_add_u64 v[54:55], v[50:51], 0, v[136:137]
	v_lshlrev_b64 v[56:57], 2, v[54:55]
	v_lshl_add_u64 v[58:59], s[16:17], 0, v[56:57]
	v_lshl_add_u64 v[54:55], v[54:55], 1, s[26:27]
	v_lshl_add_u64 v[56:57], s[20:21], 0, v[56:57]
	s_waitcnt vmcnt(45)
	v_mov_b64_e32 v[50:51], v[182:183]
	v_mov_b64_e32 v[52:53], v[184:185]
	v_pk_add_f32 v[46:47], v[46:47], v[52:53]
	v_pk_add_f32 v[44:45], v[44:45], v[50:51]
	global_store_dwordx4 v[56:57], v[44:47], off
	v_cvt_pk_bf16_f32 v50, v44, v45
	v_cvt_pk_bf16_f32 v51, v46, v47
	global_store_dwordx2 v[54:55], v[50:51], off
	v_mul_f32_e32 v45, v45, v45
	v_mul_f32_e32 v47, v47, v47
	v_fmac_f32_e32 v45, v44, v44
	v_fmac_f32_e32 v47, v46, v46
	v_add_f32_e32 v44, v45, v47
	s_waitcnt vmcnt(44)
	v_mov_b64_e32 v[50:51], v[186:187]
	v_mov_b64_e32 v[52:53], v[188:189]
	v_pk_add_f32 v[42:43], v[42:43], v[52:53]
	v_pk_add_f32 v[40:41], v[40:41], v[50:51]
	global_store_dwordx4 v[56:57], v[40:43], off offset:64
	v_cvt_pk_bf16_f32 v50, v40, v41
	v_cvt_pk_bf16_f32 v51, v42, v43
	global_store_dwordx2 v[54:55], v[50:51], off offset:32
	v_mul_f32_e32 v41, v41, v41
	v_mul_f32_e32 v43, v43, v43
	v_fmac_f32_e32 v41, v40, v40
	v_fmac_f32_e32 v43, v42, v42
	v_add_f32_e32 v40, v41, v43
	v_add_f32_e32 v40, v44, v40
	s_waitcnt vmcnt(43)
	v_mov_b64_e32 v[50:51], v[190:191]
	v_mov_b64_e32 v[52:53], v[192:193]
	v_pk_add_f32 v[38:39], v[38:39], v[52:53]
	v_pk_add_f32 v[36:37], v[36:37], v[50:51]
	global_store_dwordx4 v[56:57], v[36:39], off offset:512
	v_cvt_pk_bf16_f32 v50, v36, v37
	v_cvt_pk_bf16_f32 v51, v38, v39
	global_store_dwordx2 v[54:55], v[50:51], off offset:256
	v_mul_f32_e32 v37, v37, v37
	v_mul_f32_e32 v39, v39, v39
	v_fmac_f32_e32 v37, v36, v36
	v_fmac_f32_e32 v39, v38, v38
	v_add_f32_e32 v36, v37, v39
	v_add_f32_e32 v38, v40, v36
	s_waitcnt vmcnt(42)
	v_mov_b64_e32 v[50:51], v[194:195]
	v_mov_b64_e32 v[52:53], v[196:197]
	v_pk_add_f32 v[36:37], v[34:35], v[52:53]
	v_pk_add_f32 v[34:35], v[32:33], v[50:51]
	v_mul_f32_e32 v33, v37, v37
	v_mul_f32_e32 v32, v35, v35
	v_fmac_f32_e32 v32, v34, v34
	v_fmac_f32_e32 v33, v36, v36
	v_add_f32_e32 v32, v32, v33
	v_add_f32_e32 v32, v38, v32
	ds_bpermute_b32 v33, v116, v32
	global_store_dwordx4 v[56:57], v[34:37], off offset:576
	s_waitcnt lgkmcnt(0)
	v_add_f32_e32 v32, v32, v33
	ds_bpermute_b32 v33, v114, v32
	v_cvt_pk_bf16_f32 v34, v34, v35
	v_cvt_pk_bf16_f32 v35, v36, v37
	global_store_dwordx2 v[54:55], v[34:35], off offset:288
	s_and_saveexec_b64 s[58:59], s[12:13]
	s_cbranch_execz .LBB0_1049
	s_waitcnt lgkmcnt(0)
	v_add_f32_e32 v34, v32, v33
	v_lshlrev_b64 v[32:33], 6, v[48:49]
	v_lshl_add_u64 v[32:33], s[28:29], 0, v[32:33]
	v_lshl_add_u64 v[32:33], s[56:57], 2, v[32:33]
	s_lshl_b32 s30, s84, 2
	v_lshl_add_u64 v[32:33], v[32:33], 0, s[30:31]
	global_store_dword v[32:33], v34, off
; __device__ __forceinline__ unsigned pk2(float lo, float hi) { unsigned r; asm volatile("v_cvt_pk_bf16_f32 %0, %1, %2" : "=v"(r) : "v"(lo), "v"(hi)); return r; }
;     __device__ __forceinline__ void operator()(const f32x4 (&acc)[2][2][4][2], const Unit& u, int wr, int wc, int fr, int fq) const {
;     ...
;         const float* xo = (u.pm < 64) ? xoldA : (xoldB - (size_t)T_P * DM);
; #pragma unroll
;         for (int ai = 0; ai < 2; ++ai)
; #pragma unroll
;             for (int m = 0; m < 4; ++m) {
;                 const int row = row0 + ai * 128 + m * 16; const size_t ro = (size_t)row * DM + col0;
;                 float s = 0.f;
; #pragma unroll
;                 for (int bj = 0; bj < 2; ++bj)
; #pragma unroll
;                     for (int n = 0; n < 2; ++n) {
;                         const size_t o = ro + bj * 128 + n * 16;
;                         const f32x4 xn = *(const f32x4*)(xo + o) + acc[ai][bj][m][n];
;                         *(f32x4*)(xf + o) = xn;
;                         u32x2 w; w.x = pk2(xn[0], xn[1]); w.y = pk2(xn[2], xn[3]); *(u32x2*)(xb + o) = w;
;                         s += (xn[0] * xn[0] + xn[1] * xn[1]) + (xn[2] * xn[2] + xn[3] * xn[3]);
;                     }
;                 s += __shfl_xor(s, 16); s += __shfl_xor(s, 32);
;                 if (fq == 0) ssq[(size_t)row * 16 + u.pn * 4 + wc] = s;
.LBB0_1049:
	s_or_b64 exec, exec, s[58:59]
	v_add_u32_e32 v32, 0xa0, v138
	s_waitcnt lgkmcnt(0)
	v_ashrrev_i32_e32 v33, 31, v32
	v_lshlrev_b64 v[34:35], 10, v[32:33]
	v_lshl_add_u64 v[38:39], v[34:35], 0, v[136:137]
	v_lshlrev_b64 v[40:41], 2, v[38:39]
	v_lshl_add_u64 v[42:43], s[16:17], 0, v[40:41]
	v_lshl_add_u64 v[38:39], v[38:39], 1, s[26:27]
	v_lshl_add_u64 v[40:41], s[20:21], 0, v[40:41]
	s_waitcnt vmcnt(41)
	v_mov_b64_e32 v[34:35], v[198:199]
	v_mov_b64_e32 v[36:37], v[200:201]
	v_pk_add_f32 v[30:31], v[30:31], v[36:37]
	v_pk_add_f32 v[28:29], v[28:29], v[34:35]
	global_store_dwordx4 v[40:41], v[28:31], off
	v_cvt_pk_bf16_f32 v34, v28, v29
	v_cvt_pk_bf16_f32 v35, v30, v31
	global_store_dwordx2 v[38:39], v[34:35], off
	v_mul_f32_e32 v29, v29, v29
	v_mul_f32_e32 v31, v31, v31
	v_fmac_f32_e32 v29, v28, v28
	v_fmac_f32_e32 v31, v30, v30
	v_add_f32_e32 v28, v29, v31
	s_waitcnt vmcnt(40)
	v_mov_b64_e32 v[34:35], v[202:203]
	v_mov_b64_e32 v[36:37], v[204:205]
	v_pk_add_f32 v[26:27], v[26:27], v[36:37]
	v_pk_add_f32 v[24:25], v[24:25], v[34:35]
	global_store_dwordx4 v[40:41], v[24:27], off offset:64
	v_cvt_pk_bf16_f32 v34, v24, v25
	v_cvt_pk_bf16_f32 v35, v26, v27
	global_store_dwordx2 v[38:39], v[34:35], off offset:32
	v_mul_f32_e32 v25, v25, v25
	v_mul_f32_e32 v27, v27, v27
	v_fmac_f32_e32 v25, v24, v24
	v_fmac_f32_e32 v27, v26, v26
	v_add_f32_e32 v24, v25, v27
	v_add_f32_e32 v24, v28, v24
	s_waitcnt vmcnt(39)
	v_mov_b64_e32 v[34:35], v[206:207]
	v_mov_b64_e32 v[36:37], v[208:209]
	v_pk_add_f32 v[22:23], v[22:23], v[36:37]
	v_pk_add_f32 v[20:21], v[20:21], v[34:35]
	global_store_dwordx4 v[40:41], v[20:23], off offset:512
	v_cvt_pk_bf16_f32 v34, v20, v21
	v_cvt_pk_bf16_f32 v35, v22, v23
	global_store_dwordx2 v[38:39], v[34:35], off offset:256
	v_mul_f32_e32 v21, v21, v21
	v_mul_f32_e32 v23, v23, v23
	v_fmac_f32_e32 v21, v20, v20
	v_fmac_f32_e32 v23, v22, v22
	v_add_f32_e32 v20, v21, v23
	v_add_f32_e32 v22, v24, v20
	s_waitcnt vmcnt(38)
	v_mov_b64_e32 v[34:35], v[210:211]
	v_mov_b64_e32 v[36:37], v[212:213]
	v_pk_add_f32 v[20:21], v[18:19], v[36:37]
	v_pk_add_f32 v[18:19], v[16:17], v[34:35]
	v_mul_f32_e32 v17, v21, v21
	v_mul_f32_e32 v16, v19, v19
	v_fmac_f32_e32 v16, v18, v18
	v_fmac_f32_e32 v17, v20, v20
	v_add_f32_e32 v16, v16, v17
	v_add_f32_e32 v16, v22, v16
	ds_bpermute_b32 v17, v116, v16
	global_store_dwordx4 v[40:41], v[18:21], off offset:576
	s_waitcnt lgkmcnt(0)
	v_add_f32_e32 v16, v16, v17
	ds_bpermute_b32 v17, v114, v16
	v_cvt_pk_bf16_f32 v18, v18, v19
	v_cvt_pk_bf16_f32 v19, v20, v21
	global_store_dwordx2 v[38:39], v[18:19], off offset:288
	s_and_saveexec_b64 s[58:59], s[12:13]
	s_cbranch_execz .LBB0_1051
	s_waitcnt lgkmcnt(0)
	v_add_f32_e32 v18, v16, v17
	v_lshlrev_b64 v[16:17], 6, v[32:33]
	v_lshl_add_u64 v[16:17], s[28:29], 0, v[16:17]
	v_lshl_add_u64 v[16:17], s[56:57], 2, v[16:17]
	s_lshl_b32 s30, s84, 2
	v_lshl_add_u64 v[16:17], v[16:17], 0, s[30:31]
	global_store_dword v[16:17], v18, off
.LBB0_1051:
	s_or_b64 exec, exec, s[58:59]
	v_add_u32_e32 v16, 0xb0, v138
	s_waitcnt lgkmcnt(0)
	v_ashrrev_i32_e32 v17, 31, v16
	v_lshlrev_b64 v[18:19], 10, v[16:17]
	v_lshl_add_u64 v[22:23], v[18:19], 0, v[136:137]
	v_lshlrev_b64 v[24:25], 2, v[22:23]
	v_lshl_add_u64 v[26:27], s[16:17], 0, v[24:25]
	v_lshl_add_u64 v[22:23], v[22:23], 1, s[26:27]
	v_lshl_add_u64 v[24:25], s[20:21], 0, v[24:25]
	s_waitcnt vmcnt(37)
	v_mov_b64_e32 v[18:19], v[232:233]
	v_mov_b64_e32 v[20:21], v[234:235]
	v_pk_add_f32 v[14:15], v[14:15], v[20:21]
	v_pk_add_f32 v[12:13], v[12:13], v[18:19]
	global_store_dwordx4 v[24:25], v[12:15], off
	v_cvt_pk_bf16_f32 v18, v12, v13
	v_cvt_pk_bf16_f32 v19, v14, v15
	global_store_dwordx2 v[22:23], v[18:19], off
	v_mul_f32_e32 v13, v13, v13
	v_mul_f32_e32 v15, v15, v15
	v_fmac_f32_e32 v13, v12, v12
	v_fmac_f32_e32 v15, v14, v14
	v_add_f32_e32 v12, v13, v15
	s_waitcnt vmcnt(36)
	v_mov_b64_e32 v[18:19], v[236:237]
	v_mov_b64_e32 v[20:21], v[238:239]
	v_pk_add_f32 v[10:11], v[10:11], v[20:21]
	v_pk_add_f32 v[8:9], v[8:9], v[18:19]
	global_store_dwordx4 v[24:25], v[8:11], off offset:64
	v_cvt_pk_bf16_f32 v18, v8, v9
	v_cvt_pk_bf16_f32 v19, v10, v11
	global_store_dwordx2 v[22:23], v[18:19], off offset:32
	v_mul_f32_e32 v9, v9, v9
	v_mul_f32_e32 v11, v11, v11
	v_fmac_f32_e32 v9, v8, v8
	v_fmac_f32_e32 v11, v10, v10
	v_add_f32_e32 v8, v9, v11
	v_add_f32_e32 v8, v12, v8
	s_waitcnt vmcnt(35)
	v_mov_b64_e32 v[18:19], v[240:241]
	v_mov_b64_e32 v[20:21], v[242:243]
	v_pk_add_f32 v[6:7], v[6:7], v[20:21]
	v_pk_add_f32 v[4:5], v[4:5], v[18:19]
	global_store_dwordx4 v[24:25], v[4:7], off offset:512
	v_cvt_pk_bf16_f32 v18, v4, v5
	v_cvt_pk_bf16_f32 v19, v6, v7
	global_store_dwordx2 v[22:23], v[18:19], off offset:256
	v_mul_f32_e32 v5, v5, v5
	v_mul_f32_e32 v7, v7, v7
	v_fmac_f32_e32 v5, v4, v4
	v_fmac_f32_e32 v7, v6, v6
	v_add_f32_e32 v4, v5, v7
	v_add_f32_e32 v6, v8, v4
	s_waitcnt vmcnt(34)
	v_mov_b64_e32 v[18:19], v[244:245]
	v_mov_b64_e32 v[20:21], v[246:247]
	v_pk_add_f32 v[4:5], v[2:3], v[20:21]
	v_pk_add_f32 v[2:3], v[0:1], v[18:19]
	v_mul_f32_e32 v1, v5, v5
	v_mul_f32_e32 v0, v3, v3
	v_fmac_f32_e32 v0, v2, v2
	v_fmac_f32_e32 v1, v4, v4
	v_add_f32_e32 v0, v0, v1
	v_add_f32_e32 v0, v6, v0
	ds_bpermute_b32 v1, v116, v0
	global_store_dwordx4 v[24:25], v[2:5], off offset:576
	s_waitcnt lgkmcnt(0)
	v_add_f32_e32 v0, v0, v1
	ds_bpermute_b32 v1, v114, v0
	v_cvt_pk_bf16_f32 v2, v2, v3
	v_cvt_pk_bf16_f32 v3, v4, v5
	global_store_dwordx2 v[22:23], v[2:3], off offset:288
	s_and_saveexec_b64 s[16:17], s[12:13]
	s_cbranch_execz .LBB0_1012
	s_waitcnt lgkmcnt(0)
	v_add_f32_e32 v2, v0, v1
	v_lshlrev_b64 v[0:1], 6, v[16:17]
	v_lshl_add_u64 v[0:1], s[28:29], 0, v[0:1]
	v_lshl_add_u64 v[0:1], s[56:57], 2, v[0:1]
	s_lshl_b32 s30, s84, 2
	v_lshl_add_u64 v[0:1], v[0:1], 0, s[30:31]
	global_store_dword v[0:1], v2, off
	s_branch .LBB0_1012

; __device__ __forceinline__ unsigned pk2(float lo, float hi) { unsigned r; asm volatile("v_cvt_pk_bf16_f32 %0, %1, %2" : "=v"(r) : "v"(lo), "v"(hi)); return r; }
;     ...
;         const int lane = threadIdx.x & 63, wv = threadIdx.x >> 6;
;         const int rbase = u.pm * 256 + (kq * 4 + u.pn) * 16 + wv * 2;
; #pragma unroll
;         for (int rr = 0; rr < 2; ++rr) {
;             const int row = rbase + rr; float sq = 0.f;
; #pragma unroll
;             for (int i = 0; i < 4; ++i) {
;                 const size_t o = (size_t)row * DM + i * 256 + lane * 4;
;                 f32x4 v = *(const f32x4*)(xold + o);
; #pragma unroll
;                 for (int q = 0; q < 4; ++q) v += *(const f32x4*)(part + (size_t)q * 1024 * DM + o);
;                 *(f32x4*)(xf_s + o) = v;
;                 u32x2 w; w.x = pk2(v[0], v[1]); w.y = pk2(v[2], v[3]); *(u32x2*)(xb_s + o) = w;
;                 sq += (v[0] * v[0] + v[1] * v[1]) + (v[2] * v[2] + v[3] * v[3]);
;             }
; #pragma unroll
;             for (int o = 32; o >= 1; o >>= 1) sq += __shfl_xor(sq, o);
;             if (lane < 16) ssq_s[(size_t)row * 16 + lane] = lane == 0 ? sq : 0.f;
;         }
.LBB0_1154:
	s_or_b64 exec, exec, s[10:11]
	s_add_u32 s18, s20, 0x4000000
	s_addc_u32 s19, s21, 0
	s_add_u32 s16, s16, 0x2000000
	s_addc_u32 s17, s17, 0
	s_lshr_b32 s8, s70, 2
	v_lshrrev_b32_e32 v0, 5, v166
	s_and_b32 s8, s8, 0xffffffc
	v_and_b32_e32 v0, 30, v0
	s_add_i32 s6, s6, s8
	v_lshl_or_b32 v0, s7, 8, v0
	v_lshl_add_u32 v2, s6, 4, v0
	v_ashrrev_i32_e32 v3, 31, v2
	v_lshlrev_b32_e32 v0, 2, v167
	v_lshlrev_b64 v[4:5], 10, v[2:3]
	v_or_b32_e32 v4, v4, v0
	v_lshlrev_b64 v[10:11], 2, v[4:5]
	v_lshl_add_u64 v[38:39], s[14:15], 0, v[10:11]
	s_mov_b32 s6, 0x400000
	v_add_co_u32_e32 v40, vcc, s6, v38
	s_mov_b32 s7, 0x800000
	s_nop 0
	v_addc_co_u32_e32 v41, vcc, 0, v39, vcc
	v_lshl_add_u64 v[26:27], s[18:19], 0, v[10:11]
	v_add_co_u32_e32 v42, vcc, s7, v38
	s_barrier
	global_load_dwordx4 v[6:9], v[26:27], off
	v_addc_co_u32_e32 v43, vcc, 0, v39, vcc
	s_mov_b32 s8, 0xc00000
	global_load_dwordx4 v[10:13], v[38:39], off
	global_load_dwordx4 v[14:17], v[40:41], off
	v_add_co_u32_e32 v44, vcc, s8, v38
	global_load_dwordx4 v[18:21], v[42:43], off
	s_nop 0
	v_addc_co_u32_e32 v45, vcc, 0, v39, vcc
	global_load_dwordx4 v[22:25], v[44:45], off
	v_mov_b32_e32 v31, v5
	v_lshl_add_u64 v[28:29], v[4:5], 1, s[16:17]
	v_or_b32_e32 v30, 0x100, v4
	v_lshl_add_u64 v[32:33], v[30:31], 2, s[18:19]
	v_mov_b32_e32 v35, v5
	v_or_b32_e32 v34, 0x200, v4
	v_lshl_add_u64 v[30:31], v[30:31], 1, s[16:17]
	v_lshl_add_u64 v[36:37], v[34:35], 2, s[18:19]
	v_or_b32_e32 v4, 0x300, v4
	v_lshl_add_u64 v[34:35], v[34:35], 1, s[16:17]
	v_lshl_add_u64 v[46:47], v[4:5], 2, s[18:19]
	v_mov_b32_e32 v1, 0
	s_mov_b64 s[20:21], 0x100000
	v_cmp_gt_u32_e64 s[10:11], 16, v167
	v_cmp_eq_u32_e32 vcc, 0, v167
	v_lshl_add_u64 v[4:5], v[4:5], 1, s[16:17]
	global_load_dwordx4 v[186:189], v[32:33], off
	global_load_dwordx4 v[190:193], v[38:39], off offset:1024
	global_load_dwordx4 v[194:197], v[40:41], off offset:1024
	global_load_dwordx4 v[198:201], v[42:43], off offset:1024
	global_load_dwordx4 v[202:205], v[44:45], off offset:1024
	global_load_dwordx4 v[206:209], v[36:37], off
	global_load_dwordx4 v[210:213], v[38:39], off offset:2048
	global_load_dwordx4 v[214:217], v[40:41], off offset:2048
	global_load_dwordx4 v[218:221], v[42:43], off offset:2048
	global_load_dwordx4 v[222:225], v[44:45], off offset:2048
	global_load_dwordx4 v[226:229], v[46:47], off
	global_load_dwordx4 v[232:235], v[38:39], off offset:3072
	global_load_dwordx4 v[236:239], v[40:41], off offset:3072
	global_load_dwordx4 v[240:243], v[42:43], off offset:3072
	global_load_dwordx4 v[244:247], v[44:45], off offset:3072
	s_waitcnt vmcnt(18)
	v_pk_add_f32 v[8:9], v[8:9], v[12:13]
	v_pk_add_f32 v[6:7], v[6:7], v[10:11]
	s_waitcnt vmcnt(17)
	v_pk_add_f32 v[8:9], v[8:9], v[16:17]
	v_pk_add_f32 v[6:7], v[6:7], v[14:15]
	s_waitcnt vmcnt(16)
	v_pk_add_f32 v[8:9], v[8:9], v[20:21]
	v_pk_add_f32 v[6:7], v[6:7], v[18:19]
	s_waitcnt vmcnt(15)
	v_pk_add_f32 v[8:9], v[8:9], v[24:25]
	v_pk_add_f32 v[6:7], v[6:7], v[22:23]
	global_store_dwordx4 v[26:27], v[6:9], off
	v_cvt_pk_bf16_f32 v10, v6, v7
	v_cvt_pk_bf16_f32 v11, v8, v9
	global_store_dwordx2 v[28:29], v[10:11], off
	s_nop 0
	v_mul_f32_e32 v7, v7, v7
	v_mul_f32_e32 v9, v9, v9
	v_fmac_f32_e32 v7, v6, v6
	v_fmac_f32_e32 v9, v8, v8
	v_add_f32_e32 v6, v7, v9
	s_waitcnt vmcnt(12)
	v_mov_b64_e32 v[10:11], v[186:187]
	v_mov_b64_e32 v[12:13], v[188:189]
	v_mov_b64_e32 v[14:15], v[190:191]
	v_mov_b64_e32 v[16:17], v[192:193]
	v_mov_b64_e32 v[18:19], v[194:195]
	v_mov_b64_e32 v[20:21], v[196:197]
	v_mov_b64_e32 v[22:23], v[198:199]
	v_mov_b64_e32 v[24:25], v[200:201]
	v_mov_b64_e32 v[26:27], v[202:203]
	v_mov_b64_e32 v[28:29], v[204:205]
	v_pk_add_f32 v[12:13], v[12:13], v[16:17]
	v_pk_add_f32 v[10:11], v[10:11], v[14:15]
	v_pk_add_f32 v[12:13], v[12:13], v[20:21]
	v_pk_add_f32 v[10:11], v[10:11], v[18:19]
	v_pk_add_f32 v[12:13], v[12:13], v[24:25]
	v_pk_add_f32 v[10:11], v[10:11], v[22:23]
	v_pk_add_f32 v[12:13], v[12:13], v[28:29]
	v_pk_add_f32 v[10:11], v[10:11], v[26:27]
	global_store_dwordx4 v[32:33], v[10:13], off
	v_cvt_pk_bf16_f32 v14, v10, v11
	v_cvt_pk_bf16_f32 v15, v12, v13
	global_store_dwordx2 v[30:31], v[14:15], off
	s_nop 0
	v_mul_f32_e32 v7, v11, v11
	v_mul_f32_e32 v8, v13, v13
	v_fmac_f32_e32 v7, v10, v10
	v_fmac_f32_e32 v8, v12, v12
	v_add_f32_e32 v7, v7, v8
	v_add_f32_e32 v6, v6, v7
	s_waitcnt vmcnt(9)
	v_mov_b64_e32 v[14:15], v[206:207]
	v_mov_b64_e32 v[16:17], v[208:209]
	v_mov_b64_e32 v[18:19], v[210:211]
	v_mov_b64_e32 v[20:21], v[212:213]
	v_mov_b64_e32 v[22:23], v[214:215]
	v_mov_b64_e32 v[24:25], v[216:217]
	v_mov_b64_e32 v[26:27], v[218:219]
	v_mov_b64_e32 v[28:29], v[220:221]
	v_mov_b64_e32 v[30:31], v[222:223]
	v_mov_b64_e32 v[32:33], v[224:225]
	v_pk_add_f32 v[16:17], v[16:17], v[20:21]
	v_pk_add_f32 v[14:15], v[14:15], v[18:19]
	v_pk_add_f32 v[16:17], v[16:17], v[24:25]
	v_pk_add_f32 v[14:15], v[14:15], v[22:23]
	v_pk_add_f32 v[16:17], v[16:17], v[28:29]
	v_pk_add_f32 v[14:15], v[14:15], v[26:27]
	v_pk_add_f32 v[16:17], v[16:17], v[32:33]
	v_pk_add_f32 v[14:15], v[14:15], v[30:31]
	global_store_dwordx4 v[36:37], v[14:17], off
	v_cvt_pk_bf16_f32 v18, v14, v15
	v_cvt_pk_bf16_f32 v19, v16, v17
	global_store_dwordx2 v[34:35], v[18:19], off
	s_nop 0
	v_mul_f32_e32 v7, v15, v15
	v_mul_f32_e32 v8, v17, v17
	v_fmac_f32_e32 v7, v14, v14
	v_fmac_f32_e32 v8, v16, v16
	v_add_f32_e32 v7, v7, v8
	v_add_f32_e32 v10, v6, v7
	v_mbcnt_hi_u32_b32 v40, -1, v168
	v_lshl_add_u64 v[38:39], s[12:13], 0, v[0:1]
	v_and_b32_e32 v1, 64, v40
	v_xor_b32_e32 v41, 32, v40
	v_add_u32_e32 v43, 64, v1
	v_cmp_lt_i32_e64 s[12:13], v41, v43
	v_xor_b32_e32 v42, 16, v40
	v_xor_b32_e32 v11, 2, v40
	v_cndmask_b32_e64 v1, v40, v41, s[12:13]
	v_lshlrev_b32_e32 v1, 2, v1
	v_cmp_lt_i32_e64 s[12:13], v42, v43
	v_xor_b32_e32 v12, 1, v40
	s_waitcnt vmcnt(6)
; __device__ __forceinline__ unsigned pk2(float lo, float hi) { unsigned r; asm volatile("v_cvt_pk_bf16_f32 %0, %1, %2" : "=v"(r) : "v"(lo), "v"(hi)); return r; }
;     ...
;         const int lane = threadIdx.x & 63, wv = threadIdx.x >> 6;
;         const int rbase = u.pm * 256 + (kq * 4 + u.pn) * 16 + wv * 2;
; #pragma unroll
;         for (int rr = 0; rr < 2; ++rr) {
;             const int row = rbase + rr; float sq = 0.f;
; #pragma unroll
;             for (int i = 0; i < 4; ++i) {
;                 const size_t o = (size_t)row * DM + i * 256 + lane * 4;
;                 f32x4 v = *(const f32x4*)(xold + o);
; #pragma unroll
;                 for (int q = 0; q < 4; ++q) v += *(const f32x4*)(part + (size_t)q * 1024 * DM + o);
;                 *(f32x4*)(xf_s + o) = v;
;                 u32x2 w; w.x = pk2(v[0], v[1]); w.y = pk2(v[2], v[3]); *(u32x2*)(xb_s + o) = w;
;                 sq += (v[0] * v[0] + v[1] * v[1]) + (v[2] * v[2] + v[3] * v[3]);
;             }
; #pragma unroll
;             for (int o = 32; o >= 1; o >>= 1) sq += __shfl_xor(sq, o);
;             if (lane < 16) ssq_s[(size_t)row * 16 + lane] = lane == 0 ? sq : 0.f;
;         }
	v_mov_b64_e32 v[18:19], v[226:227]
	v_mov_b64_e32 v[20:21], v[228:229]
	v_mov_b64_e32 v[22:23], v[232:233]
	v_mov_b64_e32 v[24:25], v[234:235]
	v_mov_b64_e32 v[26:27], v[236:237]
	v_mov_b64_e32 v[28:29], v[238:239]
	v_mov_b64_e32 v[30:31], v[240:241]
	v_mov_b64_e32 v[32:33], v[242:243]
	v_mov_b64_e32 v[34:35], v[244:245]
	v_mov_b64_e32 v[36:37], v[246:247]
	v_pk_add_f32 v[6:7], v[20:21], v[24:25]
	v_pk_add_f32 v[8:9], v[18:19], v[22:23]
	v_pk_add_f32 v[6:7], v[6:7], v[28:29]
	v_pk_add_f32 v[8:9], v[8:9], v[26:27]
	v_pk_add_f32 v[6:7], v[6:7], v[32:33]
	v_pk_add_f32 v[8:9], v[8:9], v[30:31]
	v_pk_add_f32 v[18:19], v[6:7], v[36:37]
	v_pk_add_f32 v[16:17], v[8:9], v[34:35]
	v_mul_f32_e32 v7, v19, v19
	v_mul_f32_e32 v6, v17, v17
	v_fmac_f32_e32 v6, v16, v16
	v_fmac_f32_e32 v7, v18, v18
	v_add_f32_e32 v6, v6, v7
	v_add_f32_e32 v6, v10, v6
	ds_bpermute_b32 v7, v1, v6
	v_cndmask_b32_e64 v8, v40, v42, s[12:13]
	v_lshlrev_b32_e32 v8, 2, v8
	v_xor_b32_e32 v9, 8, v40
	v_cmp_lt_i32_e64 s[12:13], v9, v43
	s_waitcnt lgkmcnt(0)
	v_add_f32_e32 v6, v6, v7
	ds_bpermute_b32 v7, v8, v6
	v_cndmask_b32_e64 v9, v40, v9, s[12:13]
	v_lshlrev_b32_e32 v9, 2, v9
	v_xor_b32_e32 v10, 4, v40
	v_cmp_lt_i32_e64 s[12:13], v10, v43
	s_waitcnt lgkmcnt(0)
	v_add_f32_e32 v6, v6, v7
	ds_bpermute_b32 v7, v9, v6
	v_cndmask_b32_e64 v10, v40, v10, s[12:13]
	v_lshlrev_b32_e32 v10, 2, v10
	v_cmp_lt_i32_e64 s[12:13], v11, v43
	global_store_dwordx4 v[46:47], v[16:19], off
	s_waitcnt lgkmcnt(0)
	v_add_f32_e32 v6, v6, v7
	ds_bpermute_b32 v7, v10, v6
	v_cndmask_b32_e64 v11, v40, v11, s[12:13]
	v_lshlrev_b32_e32 v11, 2, v11
	v_cmp_lt_i32_e64 s[12:13], v12, v43
	v_cvt_pk_bf16_f32 v16, v16, v17
	s_waitcnt lgkmcnt(0)
	v_add_f32_e32 v13, v6, v7
	ds_bpermute_b32 v14, v11, v13
	v_cndmask_b32_e64 v12, v40, v12, s[12:13]
	v_lshlrev_b32_e32 v12, 2, v12
	v_lshl_add_u64 v[6:7], v[38:39], 0, s[20:21]
	v_cvt_pk_bf16_f32 v17, v18, v19
	s_waitcnt lgkmcnt(0)
	v_add_f32_e32 v13, v13, v14
	ds_bpermute_b32 v14, v12, v13
	global_store_dwordx2 v[4:5], v[16:17], off
	s_and_saveexec_b64 s[12:13], s[10:11]
	s_cbranch_execz .LBB0_1156
	v_lshlrev_b64 v[4:5], 6, v[2:3]
	s_waitcnt lgkmcnt(0)
	v_add_f32_e32 v3, v13, v14
	v_lshl_add_u64 v[4:5], v[6:7], 0, v[4:5]
	v_cndmask_b32_e32 v3, 0, v3, vcc
	global_store_dword v[4:5], v3, off
; __device__ __forceinline__ unsigned pk2(float lo, float hi) { unsigned r; asm volatile("v_cvt_pk_bf16_f32 %0, %1, %2" : "=v"(r) : "v"(lo), "v"(hi)); return r; }
;     ...
;         const int lane = threadIdx.x & 63, wv = threadIdx.x >> 6;
;         const int rbase = u.pm * 256 + (kq * 4 + u.pn) * 16 + wv * 2;
; #pragma unroll
;         for (int rr = 0; rr < 2; ++rr) {
;             const int row = rbase + rr; float sq = 0.f;
; #pragma unroll
;             for (int i = 0; i < 4; ++i) {
;                 const size_t o = (size_t)row * DM + i * 256 + lane * 4;
;                 f32x4 v = *(const f32x4*)(xold + o);
; #pragma unroll
;                 for (int q = 0; q < 4; ++q) v += *(const f32x4*)(part + (size_t)q * 1024 * DM + o);
;                 *(f32x4*)(xf_s + o) = v;
;                 u32x2 w; w.x = pk2(v[0], v[1]); w.y = pk2(v[2], v[3]); *(u32x2*)(xb_s + o) = w;
;                 sq += (v[0] * v[0] + v[1] * v[1]) + (v[2] * v[2] + v[3] * v[3]);
;             }
; #pragma unroll
;             for (int o = 32; o >= 1; o >>= 1) sq += __shfl_xor(sq, o);
;             if (lane < 16) ssq_s[(size_t)row * 16 + lane] = lane == 0 ? sq : 0.f;
;         }
.LBB0_1156:
	s_or_b64 exec, exec, s[12:13]
	v_or_b32_e32 v2, 1, v2
	v_ashrrev_i32_e32 v3, 31, v2
	v_lshlrev_b64 v[4:5], 10, v[2:3]
	v_or_b32_e32 v4, v4, v0
	v_lshlrev_b64 v[18:19], 2, v[4:5]
	v_lshl_add_u64 v[46:47], s[14:15], 0, v[18:19]
	v_add_co_u32_e64 v48, s[12:13], s6, v46
	v_lshl_add_u64 v[34:35], s[18:19], 0, v[18:19]
	s_nop 0
	v_addc_co_u32_e64 v49, s[12:13], 0, v47, s[12:13]
	v_add_co_u32_e64 v50, s[12:13], s7, v46
	s_waitcnt lgkmcnt(0)
	global_load_dwordx4 v[14:17], v[34:35], off
	v_addc_co_u32_e64 v51, s[12:13], 0, v47, s[12:13]
	global_load_dwordx4 v[18:21], v[46:47], off
	global_load_dwordx4 v[22:25], v[48:49], off
	v_add_co_u32_e64 v52, s[12:13], s8, v46
	global_load_dwordx4 v[26:29], v[50:51], off
	s_nop 0
	v_addc_co_u32_e64 v53, s[12:13], 0, v47, s[12:13]
	global_load_dwordx4 v[30:33], v[52:53], off
	v_mov_b32_e32 v39, v5
	v_lshl_add_u64 v[36:37], v[4:5], 1, s[16:17]
	v_or_b32_e32 v38, 0x100, v4
	v_lshl_add_u64 v[40:41], v[38:39], 2, s[18:19]
	v_mov_b32_e32 v43, v5
	v_or_b32_e32 v42, 0x200, v4
	v_lshl_add_u64 v[38:39], v[38:39], 1, s[16:17]
	v_lshl_add_u64 v[44:45], v[42:43], 2, s[18:19]
	v_or_b32_e32 v4, 0x300, v4
	v_lshl_add_u64 v[42:43], v[42:43], 1, s[16:17]
	v_lshl_add_u64 v[54:55], v[4:5], 2, s[18:19]
	v_lshl_add_u64 v[4:5], v[4:5], 1, s[16:17]
	global_load_dwordx4 v[186:189], v[40:41], off
	global_load_dwordx4 v[190:193], v[46:47], off offset:1024
	global_load_dwordx4 v[194:197], v[48:49], off offset:1024
	global_load_dwordx4 v[198:201], v[50:51], off offset:1024
	global_load_dwordx4 v[202:205], v[52:53], off offset:1024
	global_load_dwordx4 v[206:209], v[44:45], off
	global_load_dwordx4 v[210:213], v[46:47], off offset:2048
	global_load_dwordx4 v[214:217], v[48:49], off offset:2048
	global_load_dwordx4 v[218:221], v[50:51], off offset:2048
	global_load_dwordx4 v[222:225], v[52:53], off offset:2048
	global_load_dwordx4 v[226:229], v[54:55], off
	global_load_dwordx4 v[232:235], v[46:47], off offset:3072
	global_load_dwordx4 v[236:239], v[48:49], off offset:3072
	global_load_dwordx4 v[240:243], v[50:51], off offset:3072
	global_load_dwordx4 v[244:247], v[52:53], off offset:3072
	s_waitcnt vmcnt(18)
	v_pk_add_f32 v[16:17], v[16:17], v[20:21]
	v_pk_add_f32 v[14:15], v[14:15], v[18:19]
	s_waitcnt vmcnt(17)
	v_pk_add_f32 v[16:17], v[16:17], v[24:25]
	v_pk_add_f32 v[14:15], v[14:15], v[22:23]
	s_waitcnt vmcnt(16)
	v_pk_add_f32 v[16:17], v[16:17], v[28:29]
	v_pk_add_f32 v[14:15], v[14:15], v[26:27]
	s_waitcnt vmcnt(15)
	v_pk_add_f32 v[16:17], v[16:17], v[32:33]
	v_pk_add_f32 v[14:15], v[14:15], v[30:31]
	global_store_dwordx4 v[34:35], v[14:17], off
	v_cvt_pk_bf16_f32 v18, v14, v15
	v_cvt_pk_bf16_f32 v19, v16, v17
	global_store_dwordx2 v[36:37], v[18:19], off
	s_nop 0
	v_mul_f32_e32 v0, v15, v15
	v_mul_f32_e32 v13, v17, v17
	v_fmac_f32_e32 v0, v14, v14
	v_fmac_f32_e32 v13, v16, v16
	v_add_f32_e32 v0, v0, v13
	s_waitcnt vmcnt(12)
	v_mov_b64_e32 v[18:19], v[186:187]
	v_mov_b64_e32 v[20:21], v[188:189]
	v_mov_b64_e32 v[22:23], v[190:191]
	v_mov_b64_e32 v[24:25], v[192:193]
	v_mov_b64_e32 v[26:27], v[194:195]
	v_mov_b64_e32 v[28:29], v[196:197]
	v_mov_b64_e32 v[30:31], v[198:199]
	v_mov_b64_e32 v[32:33], v[200:201]
	v_mov_b64_e32 v[34:35], v[202:203]
	v_mov_b64_e32 v[36:37], v[204:205]
	v_pk_add_f32 v[20:21], v[20:21], v[24:25]
	v_pk_add_f32 v[18:19], v[18:19], v[22:23]
	v_pk_add_f32 v[20:21], v[20:21], v[28:29]
	v_pk_add_f32 v[18:19], v[18:19], v[26:27]
	v_pk_add_f32 v[20:21], v[20:21], v[32:33]
	v_pk_add_f32 v[18:19], v[18:19], v[30:31]
	v_pk_add_f32 v[20:21], v[20:21], v[36:37]
	v_pk_add_f32 v[18:19], v[18:19], v[34:35]
	global_store_dwordx4 v[40:41], v[18:21], off
	v_cvt_pk_bf16_f32 v22, v18, v19
	v_cvt_pk_bf16_f32 v23, v20, v21
	global_store_dwordx2 v[38:39], v[22:23], off
	s_nop 0
	v_mul_f32_e32 v13, v19, v19
	v_mul_f32_e32 v14, v21, v21
	v_fmac_f32_e32 v13, v18, v18
	v_fmac_f32_e32 v14, v20, v20
	v_add_f32_e32 v13, v13, v14
	v_add_f32_e32 v0, v0, v13
	s_waitcnt vmcnt(9)
	v_mov_b64_e32 v[22:23], v[206:207]
	v_mov_b64_e32 v[24:25], v[208:209]
	v_mov_b64_e32 v[26:27], v[210:211]
	v_mov_b64_e32 v[28:29], v[212:213]
	v_mov_b64_e32 v[30:31], v[214:215]
	v_mov_b64_e32 v[32:33], v[216:217]
	v_mov_b64_e32 v[34:35], v[218:219]
	v_mov_b64_e32 v[36:37], v[220:221]
	v_mov_b64_e32 v[38:39], v[222:223]
	v_mov_b64_e32 v[40:41], v[224:225]
	v_pk_add_f32 v[24:25], v[24:25], v[28:29]
	v_pk_add_f32 v[22:23], v[22:23], v[26:27]
	v_pk_add_f32 v[24:25], v[24:25], v[32:33]
	v_pk_add_f32 v[22:23], v[22:23], v[30:31]
	v_pk_add_f32 v[24:25], v[24:25], v[36:37]
	v_pk_add_f32 v[22:23], v[22:23], v[34:35]
	v_pk_add_f32 v[24:25], v[24:25], v[40:41]
	v_pk_add_f32 v[22:23], v[22:23], v[38:39]
	global_store_dwordx4 v[44:45], v[22:25], off
	v_cvt_pk_bf16_f32 v26, v22, v23
	v_cvt_pk_bf16_f32 v27, v24, v25
	global_store_dwordx2 v[42:43], v[26:27], off
	s_nop 0
	v_mul_f32_e32 v13, v23, v23
	v_mul_f32_e32 v14, v25, v25
	v_fmac_f32_e32 v13, v22, v22
	v_fmac_f32_e32 v14, v24, v24
	v_add_f32_e32 v13, v13, v14
	v_add_f32_e32 v0, v0, v13
	s_waitcnt vmcnt(6)
	v_mov_b64_e32 v[26:27], v[226:227]
	v_mov_b64_e32 v[28:29], v[228:229]
	v_mov_b64_e32 v[30:31], v[232:233]
	v_mov_b64_e32 v[32:33], v[234:235]
	v_mov_b64_e32 v[34:35], v[236:237]
	v_mov_b64_e32 v[36:37], v[238:239]
	v_mov_b64_e32 v[38:39], v[240:241]
	v_mov_b64_e32 v[40:41], v[242:243]
	v_mov_b64_e32 v[42:43], v[244:245]
	v_mov_b64_e32 v[44:45], v[246:247]
	v_pk_add_f32 v[14:15], v[28:29], v[32:33]
	v_pk_add_f32 v[16:17], v[26:27], v[30:31]
	v_pk_add_f32 v[14:15], v[14:15], v[36:37]
	v_pk_add_f32 v[16:17], v[16:17], v[34:35]
	v_pk_add_f32 v[14:15], v[14:15], v[40:41]
	v_pk_add_f32 v[18:19], v[16:17], v[38:39]
	v_pk_add_f32 v[16:17], v[14:15], v[44:45]
	v_pk_add_f32 v[14:15], v[18:19], v[42:43]
	v_mul_f32_e32 v18, v17, v17
	v_mul_f32_e32 v13, v15, v15
	v_fmac_f32_e32 v13, v14, v14
	v_fmac_f32_e32 v18, v16, v16
	v_add_f32_e32 v13, v13, v18
	v_add_f32_e32 v0, v0, v13
	ds_bpermute_b32 v1, v1, v0
	global_store_dwordx4 v[54:55], v[14:17], off
	s_waitcnt lgkmcnt(0)
	v_add_f32_e32 v0, v0, v1
	ds_bpermute_b32 v1, v8, v0
	v_cvt_pk_bf16_f32 v8, v14, v15
	s_waitcnt lgkmcnt(0)
	v_add_f32_e32 v0, v0, v1
	ds_bpermute_b32 v1, v9, v0
	v_cvt_pk_bf16_f32 v9, v16, v17
	global_store_dwordx2 v[4:5], v[8:9], off
	s_waitcnt lgkmcnt(0)
	v_add_f32_e32 v0, v0, v1
	ds_bpermute_b32 v1, v10, v0
	s_waitcnt lgkmcnt(0)
	v_add_f32_e32 v0, v0, v1
	ds_bpermute_b32 v1, v11, v0
	s_waitcnt lgkmcnt(0)
	v_add_f32_e32 v0, v0, v1
	ds_bpermute_b32 v1, v12, v0
	s_and_saveexec_b64 s[12:13], s[10:11]
	s_cbranch_execz .LBB0_1158
	v_lshlrev_b64 v[2:3], 6, v[2:3]
	s_waitcnt lgkmcnt(0)
	v_add_f32_e32 v0, v0, v1
	v_lshl_add_u64 v[2:3], v[6:7], 0, v[2:3]
	v_cndmask_b32_e32 v0, 0, v0, vcc
	global_store_dword v[2:3], v0, off

; __device__ __forceinline__ f32x4 cv_bf4(const u32x2 w) { return (f32x4){bflo(w.x), bfhi(w.x), bflo(w.y), bfhi(w.y)}; }
; __device__ __forceinline__ void scan_finish(const ScanPtrs& Q, int J, int ci, unsigned char* buf, int ltid, const LStage& L, int toff) {
;     ...
;         f32x4 r = cv_bf4(L.r), k0 = cv_bf4(L.k), v = cv_bf4(L.v), rp, kp, vp;
;         if (tseq > 0) { rp = cv_bf4(L.rp); kp = cv_bf4(L.kp); vp = cv_bf4(L.vp); }
;         else if (jb.is_s) { rp = L.fr; kp = L.fk; vp = L.fv; }
;         else { rp = (f32x4){0.f, 0.f, 0.f, 0.f}; kp = rp; vp = rp; }
.LBB0_1585:
	s_or_b64 exec, exec, s[68:69]
	v_cndmask_b32_e64 v18, 64, 1, s[12:13]
	s_and_saveexec_b64 s[18:19], s[66:67]
	s_cbranch_execz .LBB0_1551
	v_cmp_gt_i32_e32 vcc, v102, v94
	v_mov_b64_e32 v[44:45], 0
	v_mov_b64_e32 v[46:47], 0
	v_mov_b32_e32 v48, 0
	v_mov_b32_e32 v50, 0
	v_mov_b32_e32 v49, 0
	v_mov_b32_e32 v51, 0
	v_mov_b32_e32 v40, 0
	v_mov_b32_e32 v41, 0
	v_mov_b32_e32 v42, 0
	v_mov_b32_e32 v43, 0
	s_and_saveexec_b64 s[12:13], vcc
	s_cbranch_execz .LBB0_1588
	s_waitcnt vmcnt(4)
	v_lshlrev_b32_e32 v40, 16, v54
	v_and_b32_e32 v41, 0xffff0000, v54
	v_lshlrev_b32_e32 v42, 16, v55
	v_and_b32_e32 v43, 0xffff0000, v55
	s_waitcnt vmcnt(3)
	v_lshlrev_b32_e32 v48, 16, v58
	v_and_b32_e32 v50, 0xffff0000, v58
	v_lshlrev_b32_e32 v49, 16, v59
	v_and_b32_e32 v51, 0xffff0000, v59
	s_waitcnt vmcnt(2)
	v_lshlrev_b32_e32 v44, 16, v66
	v_and_b32_e32 v45, 0xffff0000, v66
	v_lshlrev_b32_e32 v46, 16, v67
	v_and_b32_e32 v47, 0xffff0000, v67

; __device__ __forceinline__ f32x4 cv_bf4(const u32x2 w) { return (f32x4){bflo(w.x), bfhi(w.x), bflo(w.y), bfhi(w.y)}; }
; __device__ __forceinline__ void scan_finish(const ScanPtrs& Q, int J, int ci, unsigned char* buf, int ltid, const LStage& L, int toff) {
;     ...
;         f32x4 r = cv_bf4(L.r), k0 = cv_bf4(L.k), v = cv_bf4(L.v), rp, kp, vp;
;         if (tseq > 0) { rp = cv_bf4(L.rp); kp = cv_bf4(L.kp); vp = cv_bf4(L.vp); }
;         else if (jb.is_s) { rp = L.fr; kp = L.fk; vp = L.fv; }
;         else { rp = (f32x4){0.f, 0.f, 0.f, 0.f}; kp = rp; vp = rp; }
.LBB0_1633:
	s_or_b64 exec, exec, s[72:73]
	s_nor_b64 s[16:17], s[14:15], s[8:9]
	v_cndmask_b32_e64 v18, 64, 1, s[14:15]
	s_and_saveexec_b64 s[20:21], s[16:17]
	s_cbranch_execz .LBB0_1641
	v_cmp_gt_i32_e32 vcc, v120, v104
	s_andn2_b64 s[100:101], exec, vcc
	s_cbranch_scc0 .Lzs_1
	v_mov_b64_e32 v[48:49], 0
	v_mov_b64_e32 v[50:51], 0
	v_mov_b32_e32 v52, 0
	v_mov_b32_e32 v92, 0
	v_mov_b32_e32 v53, 0
	v_mov_b32_e32 v93, 0
	v_mov_b32_e32 v44, 0
	v_mov_b32_e32 v45, 0
	v_mov_b32_e32 v46, 0
	v_mov_b32_e32 v47, 0

; #define PG8_STAGE(bufoff, gbase, voff) do { _Pragma("unroll") for (int _i = 0; _i < 2; ++_i) \
;         __builtin_amdgcn_global_load_lds((const unsigned*)((const char*)(gbase) + (voff)[_i]), (LAS unsigned*)(lds + (bufoff) + ldsw + _i * 8192), 16, 0, 0); } while (0)
; #define PG8_LDA(dst, b, h) do { _Pragma("unroll") for (int m = 0; m < 4; ++m) _Pragma("unroll") for (int k = 0; k < 2; ++k) dst[m][k] = *(const LAS bf16x8*)(lds + PG8_SA(b, h) + aoff + m * 2048 + k * 1024); } while (0)
; #define PG8_LDB(dst, b, h) do { _Pragma("unroll") for (int n = 0; n < 2; ++n) _Pragma("unroll") for (int k = 0; k < 2; ++k) dst[n][k] = *(const LAS bf16x8*)(lds + PG8_SB(b, h) + boff + n * 2048 + k * 1024); } while (0)
; #define PG8_MMA(ai, bj, At, Bt) do { __builtin_amdgcn_s_setprio(1); _Pragma("unroll") for (int m = 0; m < 4; ++m) _Pragma("unroll") for (int n = 0; n < 2; ++n) _Pragma("unroll") for (int k = 0; k < 2; ++k) \
;         acc[ai][bj][m][n] = __builtin_amdgcn_mfma_f32_16x16x32_bf16(Bt[n][k], At[m][k], acc[ai][bj][m][n], 0, 0, 0); __builtin_amdgcn_s_setprio(0); } while (0)
; #define PG8_WAIT_V(n) asm volatile("s_waitcnt vmcnt(" #n ")" ::: "memory")
; #define PG8_WAIT_L(n) asm volatile("s_waitcnt lgkmcnt(" #n ")" ::: "memory")
; #define PG8_BAR __builtin_amdgcn_s_barrier()
; #define PG8_SCHED __builtin_amdgcn_sched_barrier(0)
;     ...
;             PG8_LDB(B0, 0, 0); PG8_SCHED; PG8_LDA(At, 0, 0); PG8_STAGE(PG8_SA(1, 1), a1 + hA, voffA);
;             PG8_WAIT_L(8); PG8_BAR; PG8_WAIT_L(0); PG8_MMA(0, 0, At, B0); PG8_BAR; PG8_SCHED;
;             PG8_LDB(B1, 0, 1); PG8_STAGE(PG8_SB(0, 0), b2, voffB);
;             PG8_BAR; PG8_WAIT_L(0); PG8_MMA(0, 1, At, B1); PG8_BAR;
;             PG8_LDA(At, 0, 1); PG8_STAGE(PG8_SA(0, 0), a2, voffA);
;             PG8_BAR; PG8_WAIT_L(0); PG8_MMA(1, 0, At, B0); PG8_BAR; PG8_SCHED;
;             PG8_STAGE(PG8_SB(0, 1), b2 + hB, voffB);
;             PG8_WAIT_V(6); PG8_BAR; PG8_MMA(1, 1, At, B1); PG8_BAR;
.LBB0_1768:
	ds_read_b128 v[146:149], v157
	ds_read_b128 v[150:153], v157 offset:1024
	ds_read_b128 v[160:163], v157 offset:2048
	ds_read_b128 v[170:173], v157 offset:3072
	s_add_u32 s10, s12, 0x100
	s_addc_u32 s11, s13, 0
	s_cmp_eq_u32 s60, 4
	s_cselect_b32 s17, s29, s11
	s_cselect_b32 s16, s28, s10
	s_cselect_b32 s15, s27, s45
	s_cselect_b32 s14, s33, s44
	v_lshl_add_u64 v[164:165], s[12:13], 0, v[138:139]
	s_add_i32 m0, s37, 0xc000
	ds_read_b128 v[174:177], v158
	ds_read_b128 v[178:181], v158 offset:1024
	ds_read_b128 v[182:185], v158 offset:2048
	ds_read_b128 v[186:189], v158 offset:3072
	ds_read_b128 v[190:193], v158 offset:4096
	ds_read_b128 v[194:197], v158 offset:5120
	ds_read_b128 v[198:201], v158 offset:6144
	ds_read_b128 v[202:205], v158 offset:7168
	global_load_lds_dwordx4 v[164:165], off
	v_lshl_add_u64 v[164:165], s[12:13], 0, v[136:137]
	s_add_i32 m0, s37, 0xe000
	s_nop 0
	global_load_lds_dwordx4 v[164:165], off
	s_waitcnt lgkmcnt(8)
	s_barrier
	s_waitcnt lgkmcnt(0)
	s_setprio 1
	s_waitcnt lgkmcnt(0)
	v_mfma_f32_16x16x32_bf16 v[124:127], v[146:149], v[174:177], v[124:127]
	v_mfma_f32_16x16x32_bf16 v[120:123], v[160:163], v[174:177], v[120:123]
	v_mfma_f32_16x16x32_bf16 v[108:111], v[146:149], v[182:185], v[108:111]
	v_mfma_f32_16x16x32_bf16 v[104:107], v[160:163], v[182:185], v[104:107]
	v_mfma_f32_16x16x32_bf16 v[92:95], v[146:149], v[190:193], v[92:95]
	v_mfma_f32_16x16x32_bf16 v[88:91], v[160:163], v[190:193], v[88:91]
	v_mfma_f32_16x16x32_bf16 v[76:79], v[146:149], v[198:201], v[76:79]
	v_mfma_f32_16x16x32_bf16 v[72:75], v[160:163], v[198:201], v[72:75]
	v_mfma_f32_16x16x32_bf16 v[124:127], v[150:153], v[178:181], v[124:127]
	v_mfma_f32_16x16x32_bf16 v[120:123], v[170:173], v[178:181], v[120:123]
	v_mfma_f32_16x16x32_bf16 v[108:111], v[150:153], v[186:189], v[108:111]
	v_mfma_f32_16x16x32_bf16 v[104:107], v[170:173], v[186:189], v[104:107]
	v_mfma_f32_16x16x32_bf16 v[92:95], v[150:153], v[194:197], v[92:95]
	v_mfma_f32_16x16x32_bf16 v[88:91], v[170:173], v[194:197], v[88:91]
	v_mfma_f32_16x16x32_bf16 v[76:79], v[150:153], v[202:205], v[76:79]
	v_mfma_f32_16x16x32_bf16 v[72:75], v[170:173], v[202:205], v[72:75]
	s_setprio 0
	s_barrier
	s_add_i32 s12, s55, s35
	v_lshl_add_u64 v[164:165], s[14:15], 0, v[132:133]
	s_mov_b32 m0, s12
	ds_read_b128 v[206:209], v159
	ds_read_b128 v[210:213], v159 offset:1024
	ds_read_b128 v[214:217], v159 offset:2048
	ds_read_b128 v[218:221], v159 offset:3072
	global_load_lds_dwordx4 v[164:165], off
	v_lshl_add_u64 v[222:223], s[14:15], 0, v[128:129]
	s_add_i32 m0, s12, 0x2000
	s_nop 0
	global_load_lds_dwordx4 v[222:223], off
	s_barrier
	s_waitcnt lgkmcnt(0)
	s_setprio 1
	s_waitcnt lgkmcnt(0)
	v_mfma_f32_16x16x32_bf16 v[116:119], v[206:209], v[174:177], v[116:119]
	v_mfma_f32_16x16x32_bf16 v[112:115], v[214:217], v[174:177], v[112:115]
	v_mfma_f32_16x16x32_bf16 v[100:103], v[206:209], v[182:185], v[100:103]
	v_mfma_f32_16x16x32_bf16 v[96:99], v[214:217], v[182:185], v[96:99]
	v_mfma_f32_16x16x32_bf16 v[84:87], v[206:209], v[190:193], v[84:87]
	v_mfma_f32_16x16x32_bf16 v[80:83], v[214:217], v[190:193], v[80:83]
	v_mfma_f32_16x16x32_bf16 v[68:71], v[206:209], v[198:201], v[68:71]
	v_mfma_f32_16x16x32_bf16 v[64:67], v[214:217], v[198:201], v[64:67]
	v_mfma_f32_16x16x32_bf16 v[116:119], v[210:213], v[178:181], v[116:119]
	v_mfma_f32_16x16x32_bf16 v[112:115], v[218:221], v[178:181], v[112:115]
	v_mfma_f32_16x16x32_bf16 v[100:103], v[210:213], v[186:189], v[100:103]
	v_mfma_f32_16x16x32_bf16 v[96:99], v[218:221], v[186:189], v[96:99]
	v_mfma_f32_16x16x32_bf16 v[84:87], v[210:213], v[194:197], v[84:87]
	v_mfma_f32_16x16x32_bf16 v[80:83], v[218:221], v[194:197], v[80:83]
	v_mfma_f32_16x16x32_bf16 v[68:71], v[210:213], v[202:205], v[68:71]
	v_mfma_f32_16x16x32_bf16 v[64:67], v[218:221], v[202:205], v[64:67]
	s_setprio 0
	s_mov_b32 m0, s37
	v_lshl_add_u64 v[224:225], s[16:17], 0, v[134:135]
	s_barrier
	ds_read_b128 v[174:177], v158 offset:16384
	ds_read_b128 v[178:181], v158 offset:17408
	ds_read_b128 v[182:185], v158 offset:18432
	ds_read_b128 v[186:189], v158 offset:19456
	ds_read_b128 v[190:193], v158 offset:20480
	ds_read_b128 v[194:197], v158 offset:21504
	ds_read_b128 v[198:201], v158 offset:22528
	ds_read_b128 v[202:205], v158 offset:23552
	global_load_lds_dwordx4 v[224:225], off
	v_lshl_add_u64 v[226:227], s[16:17], 0, v[130:131]
	s_mov_b32 m0, s40
	s_nop 0
	global_load_lds_dwordx4 v[226:227], off
	s_barrier
	s_waitcnt lgkmcnt(0)
	s_setprio 1
	s_waitcnt lgkmcnt(0)
	v_mfma_f32_16x16x32_bf16 v[60:63], v[146:149], v[174:177], v[60:63]
	v_mfma_f32_16x16x32_bf16 v[56:59], v[160:163], v[174:177], v[56:59]
	v_mfma_f32_16x16x32_bf16 v[44:47], v[146:149], v[182:185], v[44:47]
	v_mfma_f32_16x16x32_bf16 v[40:43], v[160:163], v[182:185], v[40:43]
	v_mfma_f32_16x16x32_bf16 v[28:31], v[146:149], v[190:193], v[28:31]
	v_mfma_f32_16x16x32_bf16 v[24:27], v[160:163], v[190:193], v[24:27]
	v_mfma_f32_16x16x32_bf16 v[12:15], v[146:149], v[198:201], v[12:15]
	v_mfma_f32_16x16x32_bf16 v[8:11], v[160:163], v[198:201], v[8:11]
	v_mfma_f32_16x16x32_bf16 v[60:63], v[150:153], v[178:181], v[60:63]
	v_mfma_f32_16x16x32_bf16 v[56:59], v[170:173], v[178:181], v[56:59]
	v_mfma_f32_16x16x32_bf16 v[44:47], v[150:153], v[186:189], v[44:47]
	v_mfma_f32_16x16x32_bf16 v[40:43], v[170:173], v[186:189], v[40:43]
	v_mfma_f32_16x16x32_bf16 v[28:31], v[150:153], v[194:197], v[28:31]
	v_mfma_f32_16x16x32_bf16 v[24:27], v[170:173], v[194:197], v[24:27]
	v_mfma_f32_16x16x32_bf16 v[12:15], v[150:153], v[202:205], v[12:15]
	v_mfma_f32_16x16x32_bf16 v[8:11], v[170:173], v[202:205], v[8:11]
	s_setprio 0
	s_barrier
; #define PG8_STAGE(bufoff, gbase, voff) do { _Pragma("unroll") for (int _i = 0; _i < 2; ++_i) \
;         __builtin_amdgcn_global_load_lds((const unsigned*)((const char*)(gbase) + (voff)[_i]), (LAS unsigned*)(lds + (bufoff) + ldsw + _i * 8192), 16, 0, 0); } while (0)
; #define PG8_LDA(dst, b, h) do { _Pragma("unroll") for (int m = 0; m < 4; ++m) _Pragma("unroll") for (int k = 0; k < 2; ++k) dst[m][k] = *(const LAS bf16x8*)(lds + PG8_SA(b, h) + aoff + m * 2048 + k * 1024); } while (0)
; #define PG8_LDB(dst, b, h) do { _Pragma("unroll") for (int n = 0; n < 2; ++n) _Pragma("unroll") for (int k = 0; k < 2; ++k) dst[n][k] = *(const LAS bf16x8*)(lds + PG8_SB(b, h) + boff + n * 2048 + k * 1024); } while (0)
; #define PG8_MMA(ai, bj, At, Bt) do { __builtin_amdgcn_s_setprio(1); _Pragma("unroll") for (int m = 0; m < 4; ++m) _Pragma("unroll") for (int n = 0; n < 2; ++n) _Pragma("unroll") for (int k = 0; k < 2; ++k) \
;         acc[ai][bj][m][n] = __builtin_amdgcn_mfma_f32_16x16x32_bf16(Bt[n][k], At[m][k], acc[ai][bj][m][n], 0, 0, 0); __builtin_amdgcn_s_setprio(0); } while (0)
; #define PG8_WAIT_V(n) asm volatile("s_waitcnt vmcnt(" #n ")" ::: "memory")
; #define PG8_WAIT_L(n) asm volatile("s_waitcnt lgkmcnt(" #n ")" ::: "memory")
; #define PG8_BAR __builtin_amdgcn_s_barrier()
; #define PG8_SCHED __builtin_amdgcn_sched_barrier(0)
;     ...
;             PG8_WAIT_V(6); PG8_BAR; PG8_MMA(1, 1, At, B1); PG8_BAR;
;             PG8_LDB(B0, 1, 0); PG8_SCHED; PG8_LDA(At, 1, 0); PG8_STAGE(PG8_SA(0, 1), a2 + hA, voffA);
;             PG8_WAIT_L(8); PG8_BAR; PG8_WAIT_L(0); PG8_MMA(0, 0, At, B0); PG8_BAR; PG8_SCHED;
;             PG8_LDB(B1, 1, 1); PG8_STAGE(PG8_SB(1, 0), b3, voffB);
;             PG8_BAR; PG8_WAIT_L(0); PG8_MMA(0, 1, At, B1); PG8_BAR;
;             PG8_LDA(At, 1, 1); PG8_STAGE(PG8_SA(1, 0), a3, voffA);
;             PG8_BAR; PG8_WAIT_L(0); PG8_MMA(1, 0, At, B0); PG8_BAR; PG8_SCHED;
	s_add_u32 s12, s14, 0x20000
	s_addc_u32 s13, s15, 0
	s_add_i32 s61, s56, s35
	v_lshl_add_u64 v[146:147], s[12:13], 0, v[132:133]
	s_mov_b32 m0, s61
	s_nop 0
	global_load_lds_dwordx4 v[146:147], off
	v_lshl_add_u64 v[146:147], s[12:13], 0, v[128:129]
	s_add_i32 m0, s61, 0x2000
	s_nop 0
	global_load_lds_dwordx4 v[146:147], off
	s_waitcnt vmcnt(6)
	s_barrier
	s_setprio 1
	v_mfma_f32_16x16x32_bf16 v[52:55], v[206:209], v[174:177], v[52:55]
	v_mfma_f32_16x16x32_bf16 v[48:51], v[214:217], v[174:177], v[48:51]
	v_mfma_f32_16x16x32_bf16 v[36:39], v[206:209], v[182:185], v[36:39]
	v_mfma_f32_16x16x32_bf16 v[32:35], v[214:217], v[182:185], v[32:35]
	v_mfma_f32_16x16x32_bf16 v[20:23], v[206:209], v[190:193], v[20:23]
	v_mfma_f32_16x16x32_bf16 v[16:19], v[214:217], v[190:193], v[16:19]
	v_mfma_f32_16x16x32_bf16 v[4:7], v[206:209], v[198:201], v[4:7]
	v_mfma_f32_16x16x32_bf16 v[0:3], v[214:217], v[198:201], v[0:3]
	v_mfma_f32_16x16x32_bf16 v[52:55], v[210:213], v[178:181], v[52:55]
	v_mfma_f32_16x16x32_bf16 v[48:51], v[218:221], v[178:181], v[48:51]
	v_mfma_f32_16x16x32_bf16 v[36:39], v[210:213], v[186:189], v[36:39]
	v_mfma_f32_16x16x32_bf16 v[32:35], v[218:221], v[186:189], v[32:35]
	v_mfma_f32_16x16x32_bf16 v[20:23], v[210:213], v[194:197], v[20:23]
	v_mfma_f32_16x16x32_bf16 v[16:19], v[218:221], v[194:197], v[16:19]
	v_mfma_f32_16x16x32_bf16 v[4:7], v[210:213], v[202:205], v[4:7]
	v_mfma_f32_16x16x32_bf16 v[0:3], v[218:221], v[202:205], v[0:3]
	s_setprio 0
	s_add_i32 s61, 0, 0x18000
	v_add_u32_e32 v169, s61, v155
	s_barrier
	ds_read_b128 v[146:149], v169
	ds_read_b128 v[150:153], v169 offset:1024
	ds_read_b128 v[160:163], v169 offset:2048
	ds_read_b128 v[170:173], v169 offset:3072
	s_add_u32 s12, s16, 0x110000
	s_addc_u32 s13, s17, 0
	s_mov_b32 m0, s41
	v_lshl_add_u64 v[206:207], s[12:13], 0, v[134:135]
	ds_read_b128 v[174:177], v158 offset:32768
	ds_read_b128 v[178:181], v158 offset:33792
	ds_read_b128 v[182:185], v158 offset:34816
	ds_read_b128 v[186:189], v158 offset:35840
	ds_read_b128 v[190:193], v158 offset:36864
	ds_read_b128 v[194:197], v158 offset:37888
	ds_read_b128 v[198:201], v158 offset:38912
	ds_read_b128 v[202:205], v158 offset:39936
	global_load_lds_dwordx4 v[206:207], off
	v_lshl_add_u64 v[206:207], s[12:13], 0, v[130:131]
	s_mov_b32 m0, s42
	s_nop 0
	global_load_lds_dwordx4 v[206:207], off
	s_waitcnt lgkmcnt(8)
	s_barrier
	s_waitcnt lgkmcnt(0)
	s_setprio 1
	s_waitcnt lgkmcnt(0)
	v_mfma_f32_16x16x32_bf16 v[124:127], v[146:149], v[174:177], v[124:127]
	v_mfma_f32_16x16x32_bf16 v[120:123], v[160:163], v[174:177], v[120:123]
	v_mfma_f32_16x16x32_bf16 v[108:111], v[146:149], v[182:185], v[108:111]
	v_mfma_f32_16x16x32_bf16 v[104:107], v[160:163], v[182:185], v[104:107]
	v_mfma_f32_16x16x32_bf16 v[92:95], v[146:149], v[190:193], v[92:95]
	v_mfma_f32_16x16x32_bf16 v[88:91], v[160:163], v[190:193], v[88:91]
	v_mfma_f32_16x16x32_bf16 v[76:79], v[146:149], v[198:201], v[76:79]
	v_mfma_f32_16x16x32_bf16 v[72:75], v[160:163], v[198:201], v[72:75]
	v_mfma_f32_16x16x32_bf16 v[124:127], v[150:153], v[178:181], v[124:127]
	v_mfma_f32_16x16x32_bf16 v[120:123], v[170:173], v[178:181], v[120:123]
	v_mfma_f32_16x16x32_bf16 v[108:111], v[150:153], v[186:189], v[108:111]
	v_mfma_f32_16x16x32_bf16 v[104:107], v[170:173], v[186:189], v[104:107]
	v_mfma_f32_16x16x32_bf16 v[92:95], v[150:153], v[194:197], v[92:95]
	v_mfma_f32_16x16x32_bf16 v[88:91], v[170:173], v[194:197], v[88:91]
	v_mfma_f32_16x16x32_bf16 v[76:79], v[150:153], v[202:205], v[76:79]
	v_mfma_f32_16x16x32_bf16 v[72:75], v[170:173], v[202:205], v[72:75]
	s_setprio 0
	s_barrier
	s_add_i32 s16, 0, 0x1c000
	s_add_i32 s12, s61, s35
	v_add_u32_e32 v169, s16, v155
	v_lshl_add_u64 v[164:165], v[164:165], 0, s[24:25]
	s_mov_b32 m0, s12
	ds_read_b128 v[206:209], v169
	ds_read_b128 v[210:213], v169 offset:1024
	ds_read_b128 v[214:217], v169 offset:2048
	ds_read_b128 v[218:221], v169 offset:3072
	global_load_lds_dwordx4 v[164:165], off
	v_lshl_add_u64 v[164:165], v[222:223], 0, s[24:25]
	s_add_i32 m0, s12, 0x2000
	s_nop 0
	global_load_lds_dwordx4 v[164:165], off
	s_barrier
	s_waitcnt lgkmcnt(0)
	s_setprio 1
	s_waitcnt lgkmcnt(0)
	v_mfma_f32_16x16x32_bf16 v[116:119], v[206:209], v[174:177], v[116:119]
	v_mfma_f32_16x16x32_bf16 v[112:115], v[214:217], v[174:177], v[112:115]
	v_mfma_f32_16x16x32_bf16 v[100:103], v[206:209], v[182:185], v[100:103]
	v_mfma_f32_16x16x32_bf16 v[96:99], v[214:217], v[182:185], v[96:99]
	v_mfma_f32_16x16x32_bf16 v[84:87], v[206:209], v[190:193], v[84:87]
	v_mfma_f32_16x16x32_bf16 v[80:83], v[214:217], v[190:193], v[80:83]
	v_mfma_f32_16x16x32_bf16 v[68:71], v[206:209], v[198:201], v[68:71]
	v_mfma_f32_16x16x32_bf16 v[64:67], v[214:217], v[198:201], v[64:67]
	v_mfma_f32_16x16x32_bf16 v[116:119], v[210:213], v[178:181], v[116:119]
	v_mfma_f32_16x16x32_bf16 v[112:115], v[218:221], v[178:181], v[112:115]
	v_mfma_f32_16x16x32_bf16 v[100:103], v[210:213], v[186:189], v[100:103]
	v_mfma_f32_16x16x32_bf16 v[96:99], v[218:221], v[186:189], v[96:99]
	v_mfma_f32_16x16x32_bf16 v[84:87], v[210:213], v[194:197], v[84:87]
	v_mfma_f32_16x16x32_bf16 v[80:83], v[218:221], v[194:197], v[80:83]
	v_mfma_f32_16x16x32_bf16 v[68:71], v[210:213], v[202:205], v[68:71]
	v_mfma_f32_16x16x32_bf16 v[64:67], v[218:221], v[202:205], v[64:67]
	s_setprio 0
	s_mov_b32 m0, s52
	v_lshl_add_u64 v[164:165], v[224:225], 0, s[24:25]
	s_barrier
	ds_read_b128 v[174:177], v158 offset:49152
	ds_read_b128 v[178:181], v158 offset:50176
	ds_read_b128 v[182:185], v158 offset:51200
	ds_read_b128 v[186:189], v158 offset:52224
	ds_read_b128 v[190:193], v158 offset:53248
	ds_read_b128 v[194:197], v158 offset:54272
	ds_read_b128 v[198:201], v158 offset:55296
	ds_read_b128 v[202:205], v158 offset:56320
	global_load_lds_dwordx4 v[164:165], off
	v_lshl_add_u64 v[164:165], v[226:227], 0, s[24:25]
	s_mov_b32 m0, s53
	s_nop 0
	global_load_lds_dwordx4 v[164:165], off
	s_barrier
; __device__ __forceinline__ float sigmoidf_(float x) { return 1.0f / (1.0f + __expf(-x)); }
; #define PG8_STAGE(bufoff, gbase, voff) do { _Pragma("unroll") for (int _i = 0; _i < 2; ++_i) \
;         __builtin_amdgcn_global_load_lds((const unsigned*)((const char*)(gbase) + (voff)[_i]), (LAS unsigned*)(lds + (bufoff) + ldsw + _i * 8192), 16, 0, 0); } while (0)
; #define PG8_MMA(ai, bj, At, Bt) do { __builtin_amdgcn_s_setprio(1); _Pragma("unroll") for (int m = 0; m < 4; ++m) _Pragma("unroll") for (int n = 0; n < 2; ++n) _Pragma("unroll") for (int k = 0; k < 2; ++k) \
;         acc[ai][bj][m][n] = __builtin_amdgcn_mfma_f32_16x16x32_bf16(Bt[n][k], At[m][k], acc[ai][bj][m][n], 0, 0, 0); __builtin_amdgcn_s_setprio(0); } while (0)
; #define PG8_WAIT_V(n) asm volatile("s_waitcnt vmcnt(" #n ")" ::: "memory")
; #define PG8_BAR __builtin_amdgcn_s_barrier()
; __device__ __forceinline__ u32x4 pack8(const f32x4 v0, const f32x4 v1) { u32x4 w; w.x = pk2(v0[0], v0[1]); w.y = pk2(v0[2], v0[3]); w.z = pk2(v1[0], v1[1]); w.w = pk2(v1[2], v1[3]); return w; }
;     ...
;             PG8_STAGE(PG8_SB(1, 1), b3 + hB, voffB);
;             PG8_WAIT_V(6); PG8_BAR; PG8_MMA(1, 1, At, B1); PG8_BAR;
;     __device__ __forceinline__ void operator()(const f32x4 (&acc)[2][2][4][2], const Unit& u, int wr, int wc, int fr, int fq) const {
;         const int row0 = u.pm * 256 + wr * 64 + fr, col0 = u.pn * 256 + wc * 32 + 8 * fq;
; #pragma unroll
;         for (int ai = 0; ai < 2; ++ai)
; #pragma unroll
;             for (int m = 0; m < 4; ++m) {
;                 bf16_t* rowp = z + (size_t)(row0 + ai * 128 + m * 16) * DIN + col0;
; #pragma unroll
;                 for (int bj = 0; bj < 2; ++bj) {
;                     const u32x4 gw = *(const u32x4*)(rowp + (MODE == 0 ? O_GB : O_GA) + bj * 128);
;                     f32x4 g0, g1; unpack8(gw, g0, g1);
;                     f32x4 v0, v1;
; #pragma unroll
;                     for (int j = 0; j < 4; ++j) { v0[j] = sigmoidf_(g0[j]) * acc[ai][bj][m][0][j]; v1[j] = sigmoidf_(g1[j]) * acc[ai][bj][m][1][j]; }
;                     if (MODE == 1) { const u32x4 mw = *(const u32x4*)(rowp + bj * 128); f32x4 m0, m1; unpack8(mw, m0, m1); v0 += m0; v1 += m1; }
;                     *(u32x4*)(rowp + bj * 128) = pack8(v0, v1); }
	s_waitcnt lgkmcnt(0)
	s_setprio 1
	s_waitcnt lgkmcnt(0)
	v_mfma_f32_16x16x32_bf16 v[60:63], v[146:149], v[174:177], v[60:63]
	v_mfma_f32_16x16x32_bf16 v[56:59], v[160:163], v[174:177], v[56:59]
	v_mfma_f32_16x16x32_bf16 v[44:47], v[146:149], v[182:185], v[44:47]
	v_mfma_f32_16x16x32_bf16 v[40:43], v[160:163], v[182:185], v[40:43]
	v_mfma_f32_16x16x32_bf16 v[28:31], v[146:149], v[190:193], v[28:31]
	v_mfma_f32_16x16x32_bf16 v[24:27], v[160:163], v[190:193], v[24:27]
	v_mfma_f32_16x16x32_bf16 v[12:15], v[146:149], v[198:201], v[12:15]
	v_mfma_f32_16x16x32_bf16 v[8:11], v[160:163], v[198:201], v[8:11]
	v_mfma_f32_16x16x32_bf16 v[60:63], v[150:153], v[178:181], v[60:63]
	v_mfma_f32_16x16x32_bf16 v[56:59], v[170:173], v[178:181], v[56:59]
	v_mfma_f32_16x16x32_bf16 v[44:47], v[150:153], v[186:189], v[44:47]
	v_mfma_f32_16x16x32_bf16 v[40:43], v[170:173], v[186:189], v[40:43]
	v_mfma_f32_16x16x32_bf16 v[28:31], v[150:153], v[194:197], v[28:31]
	v_mfma_f32_16x16x32_bf16 v[24:27], v[170:173], v[194:197], v[24:27]
	v_mfma_f32_16x16x32_bf16 v[12:15], v[150:153], v[202:205], v[12:15]
	v_mfma_f32_16x16x32_bf16 v[8:11], v[170:173], v[202:205], v[8:11]
	s_setprio 0
	s_barrier
	s_add_u32 s12, s14, 0x20080
	s_addc_u32 s13, s15, 0
	s_add_i32 s14, s16, s35
	v_lshl_add_u64 v[146:147], s[12:13], 0, v[132:133]
	s_mov_b32 m0, s14
	s_nop 0
	global_load_lds_dwordx4 v[146:147], off
	v_lshl_add_u64 v[146:147], s[12:13], 0, v[128:129]
	s_add_i32 m0, s14, 0x2000
	s_nop 0
	global_load_lds_dwordx4 v[146:147], off
	s_waitcnt vmcnt(6)
	s_barrier
	s_setprio 1
	v_mfma_f32_16x16x32_bf16 v[52:55], v[206:209], v[174:177], v[52:55]
	v_mfma_f32_16x16x32_bf16 v[48:51], v[214:217], v[174:177], v[48:51]
	v_mfma_f32_16x16x32_bf16 v[36:39], v[206:209], v[182:185], v[36:39]
	v_mfma_f32_16x16x32_bf16 v[32:35], v[214:217], v[182:185], v[32:35]
	v_mfma_f32_16x16x32_bf16 v[20:23], v[206:209], v[190:193], v[20:23]
	v_mfma_f32_16x16x32_bf16 v[16:19], v[214:217], v[190:193], v[16:19]
	v_mfma_f32_16x16x32_bf16 v[4:7], v[206:209], v[198:201], v[4:7]
	v_mfma_f32_16x16x32_bf16 v[0:3], v[214:217], v[198:201], v[0:3]
	v_mfma_f32_16x16x32_bf16 v[52:55], v[210:213], v[178:181], v[52:55]
	v_mfma_f32_16x16x32_bf16 v[48:51], v[218:221], v[178:181], v[48:51]
	v_mfma_f32_16x16x32_bf16 v[36:39], v[210:213], v[186:189], v[36:39]
	v_mfma_f32_16x16x32_bf16 v[32:35], v[218:221], v[186:189], v[32:35]
	v_mfma_f32_16x16x32_bf16 v[20:23], v[210:213], v[194:197], v[20:23]
	v_mfma_f32_16x16x32_bf16 v[16:19], v[218:221], v[194:197], v[16:19]
	v_mfma_f32_16x16x32_bf16 v[4:7], v[210:213], v[202:205], v[4:7]
	v_mfma_f32_16x16x32_bf16 v[0:3], v[218:221], v[202:205], v[0:3]
	s_setprio 0
	s_add_i32 s60, s60, 2
	s_add_u32 s44, s44, 0x100
	s_addc_u32 s45, s45, 0
	s_cmp_gt_u32 s60, 5
	s_mov_b64 s[12:13], s[10:11]
	s_barrier
	s_cbranch_scc0 .LBB0_1768
	v_lshl_or_b32 v148, s7, 8, v156
	v_lshl_add_u32 v160, s6, 8, v154
	v_ashrrev_i32_e32 v149, 31, v148
	v_mov_b64_e32 v[146:147], s[22:23]
	v_mad_i64_i32 v[150:151], s[6:7], v160, s57, v[146:147]
	v_lshlrev_b64 v[148:149], 1, v[148:149]
	v_lshl_add_u64 v[150:151], v[150:151], 0, v[148:149]
	v_add_co_u32_e32 v152, vcc, 0x1000, v150
	s_nop 1
	v_addc_co_u32_e32 v153, vcc, 0, v151, vcc
	v_subrev_u32_e32 v197, s22, v150
	v_add_u32_e32 v198, 0x1a00, v197
	global_load_dwordx4 v[200:203], v198, s[22:23]
	v_add_u32_e32 v198, 0x1b00, v197
	global_load_dwordx4 v[204:207], v198, s[22:23]
	v_add_u32_e32 v198, 0x23a00, v197
	global_load_dwordx4 v[208:211], v198, s[22:23]
	v_add_u32_e32 v198, 0x23b00, v197
	global_load_dwordx4 v[212:215], v198, s[22:23]
	v_add_u32_e32 v198, 0x45a00, v197
	global_load_dwordx4 v[216:219], v198, s[22:23]
	v_add_u32_e32 v198, 0x45b00, v197
	global_load_dwordx4 v[232:235], v198, s[22:23]
	s_waitcnt vmcnt(5)
	v_mov_b64_e32 v[162:163], v[200:201]
	v_mov_b64_e32 v[164:165], v[202:203]
	v_add_u32_e32 v198, 0x67a00, v197
	global_load_dwordx4 v[200:203], v198, s[22:23]
	s_mov_b32 s100, 0xbfb8aa3b
	v_lshlrev_b32_e32 v236, 16, v162
	v_and_b32_e32 v237, 0xffff0000, v162
	v_lshlrev_b32_e32 v238, 16, v164
	v_and_b32_e32 v239, 0xffff0000, v164
	v_lshlrev_b32_e32 v240, 16, v163
	v_and_b32_e32 v241, 0xffff0000, v163
	v_lshlrev_b32_e32 v242, 16, v165
	v_and_b32_e32 v243, 0xffff0000, v165
	v_pk_mul_f32 v[236:237], v[236:237], s[100:101] op_sel_hi:[1,0]
	v_pk_mul_f32 v[238:239], v[238:239], s[100:101] op_sel_hi:[1,0]
	v_pk_mul_f32 v[240:241], v[240:241], s[100:101] op_sel_hi:[1,0]
	v_pk_mul_f32 v[242:243], v[242:243], s[100:101] op_sel_hi:[1,0]
	v_exp_f32_e32 v236, v236
	v_exp_f32_e32 v237, v237
	v_exp_f32_e32 v238, v238
	v_exp_f32_e32 v239, v239
	v_exp_f32_e32 v240, v240
	v_exp_f32_e32 v241, v241
	v_exp_f32_e32 v242, v242
	v_exp_f32_e32 v243, v243
	s_nop 0
	v_pk_add_f32 v[236:237], v[236:237], 1.0 op_sel_hi:[1,0]
	v_pk_add_f32 v[238:239], v[238:239], 1.0 op_sel_hi:[1,0]
	v_pk_add_f32 v[240:241], v[240:241], 1.0 op_sel_hi:[1,0]
	v_pk_add_f32 v[242:243], v[242:243], 1.0 op_sel_hi:[1,0]
	v_rcp_f32_e32 v244, v236
	v_rcp_f32_e32 v245, v237
	v_rcp_f32_e32 v250, v238
	v_rcp_f32_e32 v251, v239
	v_pk_fma_f32 v[246:247], v[236:237], v[244:245], 1.0 op_sel_hi:[1,1,0] neg_lo:[1,0,0] neg_hi:[1,0,0]
	v_pk_fma_f32 v[252:253], v[238:239], v[250:251], 1.0 op_sel_hi:[1,1,0] neg_lo:[1,0,0] neg_hi:[1,0,0]
	v_pk_fma_f32 v[244:245], v[246:247], v[244:245], v[244:245]
	v_pk_fma_f32 v[250:251], v[252:253], v[250:251], v[250:251]
	v_pk_fma_f32 v[246:247], v[236:237], v[244:245], 1.0 op_sel_hi:[1,1,0] neg_lo:[1,0,0] neg_hi:[1,0,0]
	v_pk_fma_f32 v[252:253], v[238:239], v[250:251], 1.0 op_sel_hi:[1,1,0] neg_lo:[1,0,0] neg_hi:[1,0,0]
	v_pk_fma_f32 v[248:249], v[246:247], v[244:245], v[244:245]
; __device__ __forceinline__ float sigmoidf_(float x) { return 1.0f / (1.0f + __expf(-x)); }
; __device__ __forceinline__ u32x4 pack8(const f32x4 v0, const f32x4 v1) { u32x4 w; w.x = pk2(v0[0], v0[1]); w.y = pk2(v0[2], v0[3]); w.z = pk2(v1[0], v1[1]); w.w = pk2(v1[2], v1[3]); return w; }
; __device__ __forceinline__ void unpack8(const u32x4 w, f32x4& v0, f32x4& v1) { v0 = (f32x4){bflo(w.x), bfhi(w.x), bflo(w.y), bfhi(w.y)}; v1 = (f32x4){bflo(w.z), bfhi(w.z), bflo(w.w), bfhi(w.w)}; }
;     __device__ __forceinline__ void operator()(const f32x4 (&acc)[2][2][4][2], const Unit& u, int wr, int wc, int fr, int fq) const {
;     ...
;         for (int ai = 0; ai < 2; ++ai)
; #pragma unroll
;             for (int m = 0; m < 4; ++m) {
;                 bf16_t* rowp = z + (size_t)(row0 + ai * 128 + m * 16) * DIN + col0;
; #pragma unroll
;                 for (int bj = 0; bj < 2; ++bj) {
;                     const u32x4 gw = *(const u32x4*)(rowp + (MODE == 0 ? O_GB : O_GA) + bj * 128);
;                     f32x4 g0, g1; unpack8(gw, g0, g1);
;                     f32x4 v0, v1;
; #pragma unroll
;                     for (int j = 0; j < 4; ++j) { v0[j] = sigmoidf_(g0[j]) * acc[ai][bj][m][0][j]; v1[j] = sigmoidf_(g1[j]) * acc[ai][bj][m][1][j]; }
;                     if (MODE == 1) { const u32x4 mw = *(const u32x4*)(rowp + bj * 128); f32x4 m0, m1; unpack8(mw, m0, m1); v0 += m0; v1 += m1; }
;                     *(u32x4*)(rowp + bj * 128) = pack8(v0, v1); }
	v_pk_fma_f32 v[254:255], v[252:253], v[250:251], v[250:251]
	v_pk_fma_f32 v[246:247], v[236:237], v[248:249], 1.0 op_sel_hi:[1,1,0] neg_lo:[1,0,0] neg_hi:[1,0,0]
	v_pk_fma_f32 v[252:253], v[238:239], v[254:255], 1.0 op_sel_hi:[1,1,0] neg_lo:[1,0,0] neg_hi:[1,0,0]
	v_pk_fma_f32 v[248:249], v[246:247], v[244:245], v[248:249]
	v_pk_fma_f32 v[254:255], v[252:253], v[250:251], v[254:255]
	v_div_fixup_f32 v236, v248, v236, 1.0
	v_div_fixup_f32 v237, v249, v237, 1.0
	v_div_fixup_f32 v238, v254, v238, 1.0
	v_div_fixup_f32 v239, v255, v239, 1.0
	v_rcp_f32_e32 v244, v240
	v_rcp_f32_e32 v245, v241
	v_rcp_f32_e32 v250, v242
	v_rcp_f32_e32 v251, v243
	v_pk_fma_f32 v[246:247], v[240:241], v[244:245], 1.0 op_sel_hi:[1,1,0] neg_lo:[1,0,0] neg_hi:[1,0,0]
	v_pk_fma_f32 v[252:253], v[242:243], v[250:251], 1.0 op_sel_hi:[1,1,0] neg_lo:[1,0,0] neg_hi:[1,0,0]
	v_pk_fma_f32 v[244:245], v[246:247], v[244:245], v[244:245]
	v_pk_fma_f32 v[250:251], v[252:253], v[250:251], v[250:251]
	v_pk_fma_f32 v[246:247], v[240:241], v[244:245], 1.0 op_sel_hi:[1,1,0] neg_lo:[1,0,0] neg_hi:[1,0,0]
	v_pk_fma_f32 v[252:253], v[242:243], v[250:251], 1.0 op_sel_hi:[1,1,0] neg_lo:[1,0,0] neg_hi:[1,0,0]
	v_pk_fma_f32 v[248:249], v[246:247], v[244:245], v[244:245]
	v_pk_fma_f32 v[254:255], v[252:253], v[250:251], v[250:251]
	v_pk_fma_f32 v[246:247], v[240:241], v[248:249], 1.0 op_sel_hi:[1,1,0] neg_lo:[1,0,0] neg_hi:[1,0,0]
	v_pk_fma_f32 v[252:253], v[242:243], v[254:255], 1.0 op_sel_hi:[1,1,0] neg_lo:[1,0,0] neg_hi:[1,0,0]
	v_pk_fma_f32 v[248:249], v[246:247], v[244:245], v[248:249]
	v_pk_fma_f32 v[254:255], v[252:253], v[250:251], v[254:255]
	v_div_fixup_f32 v240, v248, v240, 1.0
	v_div_fixup_f32 v241, v249, v241, 1.0
	v_div_fixup_f32 v242, v254, v242, 1.0
	v_div_fixup_f32 v243, v255, v243, 1.0
	s_mov_b64 vcc, s[10:11]
	s_mov_b64 vcc, s[12:13]
	v_mul_f32_e32 v124, v124, v236
	s_mov_b64 vcc, s[14:15]
	v_mul_f32_e32 v161, v120, v238
	v_mul_f32_e32 v120, v125, v237
	v_mul_f32_e32 v125, v121, v239
	s_mov_b64 vcc, s[16:17]
	v_mul_f32_e32 v126, v126, v240
	v_mul_f32_e32 v162, v122, v242
	v_mul_f32_e32 v121, v127, v241
	v_mul_f32_e32 v123, v123, v243
	v_cvt_pk_bf16_f32 v120, v124, v120
	v_cvt_pk_bf16_f32 v121, v126, v121
	v_cvt_pk_bf16_f32 v122, v161, v125
	v_cvt_pk_bf16_f32 v123, v162, v123
	s_mov_b64 s[14:15], s[30:31]
	global_store_dwordx4 v[150:151], v[120:123], off
	s_mov_b64 s[12:13], s[28:29]
	s_waitcnt vmcnt(6)
	v_mov_b64_e32 v[124:125], v[204:205]
	v_mov_b64_e32 v[126:127], v[206:207]
	v_add_u32_e32 v198, 0x67b00, v197
	global_load_dwordx4 v[204:207], v198, s[22:23]
	s_mov_b32 s100, 0xbfb8aa3b
	v_lshlrev_b32_e32 v236, 16, v124
	v_and_b32_e32 v237, 0xffff0000, v124
	v_lshlrev_b32_e32 v238, 16, v126
	v_and_b32_e32 v239, 0xffff0000, v126
	v_lshlrev_b32_e32 v240, 16, v125
	v_and_b32_e32 v241, 0xffff0000, v125
	v_lshlrev_b32_e32 v242, 16, v127
	v_and_b32_e32 v243, 0xffff0000, v127
	v_pk_mul_f32 v[236:237], v[236:237], s[100:101] op_sel_hi:[1,0]
	v_pk_mul_f32 v[238:239], v[238:239], s[100:101] op_sel_hi:[1,0]
	v_pk_mul_f32 v[240:241], v[240:241], s[100:101] op_sel_hi:[1,0]
	v_pk_mul_f32 v[242:243], v[242:243], s[100:101] op_sel_hi:[1,0]
	v_exp_f32_e32 v236, v236
	v_exp_f32_e32 v237, v237
	v_exp_f32_e32 v238, v238
	v_exp_f32_e32 v239, v239
	v_exp_f32_e32 v240, v240
	v_exp_f32_e32 v241, v241
	v_exp_f32_e32 v242, v242
	v_exp_f32_e32 v243, v243
	s_nop 0
	v_pk_add_f32 v[236:237], v[236:237], 1.0 op_sel_hi:[1,0]
	v_pk_add_f32 v[238:239], v[238:239], 1.0 op_sel_hi:[1,0]
	v_pk_add_f32 v[240:241], v[240:241], 1.0 op_sel_hi:[1,0]
	v_pk_add_f32 v[242:243], v[242:243], 1.0 op_sel_hi:[1,0]
	v_rcp_f32_e32 v244, v236
	v_rcp_f32_e32 v245, v237
	v_rcp_f32_e32 v250, v238
	v_rcp_f32_e32 v251, v239
	v_pk_fma_f32 v[246:247], v[236:237], v[244:245], 1.0 op_sel_hi:[1,1,0] neg_lo:[1,0,0] neg_hi:[1,0,0]
	v_pk_fma_f32 v[252:253], v[238:239], v[250:251], 1.0 op_sel_hi:[1,1,0] neg_lo:[1,0,0] neg_hi:[1,0,0]
	v_pk_fma_f32 v[244:245], v[246:247], v[244:245], v[244:245]
	v_pk_fma_f32 v[250:251], v[252:253], v[250:251], v[250:251]
	v_pk_fma_f32 v[246:247], v[236:237], v[244:245], 1.0 op_sel_hi:[1,1,0] neg_lo:[1,0,0] neg_hi:[1,0,0]
	v_pk_fma_f32 v[252:253], v[238:239], v[250:251], 1.0 op_sel_hi:[1,1,0] neg_lo:[1,0,0] neg_hi:[1,0,0]
	v_pk_fma_f32 v[248:249], v[246:247], v[244:245], v[244:245]
	v_pk_fma_f32 v[254:255], v[252:253], v[250:251], v[250:251]
	v_pk_fma_f32 v[246:247], v[236:237], v[248:249], 1.0 op_sel_hi:[1,1,0] neg_lo:[1,0,0] neg_hi:[1,0,0]
	v_pk_fma_f32 v[252:253], v[238:239], v[254:255], 1.0 op_sel_hi:[1,1,0] neg_lo:[1,0,0] neg_hi:[1,0,0]
	v_pk_fma_f32 v[248:249], v[246:247], v[244:245], v[248:249]
	v_pk_fma_f32 v[254:255], v[252:253], v[250:251], v[254:255]
	v_div_fixup_f32 v236, v248, v236, 1.0
	v_div_fixup_f32 v237, v249, v237, 1.0
	v_div_fixup_f32 v238, v254, v238, 1.0
	v_div_fixup_f32 v239, v255, v239, 1.0
	v_rcp_f32_e32 v244, v240
	v_rcp_f32_e32 v245, v241
	v_rcp_f32_e32 v250, v242
	v_rcp_f32_e32 v251, v243
	v_pk_fma_f32 v[246:247], v[240:241], v[244:245], 1.0 op_sel_hi:[1,1,0] neg_lo:[1,0,0] neg_hi:[1,0,0]
	v_pk_fma_f32 v[252:253], v[242:243], v[250:251], 1.0 op_sel_hi:[1,1,0] neg_lo:[1,0,0] neg_hi:[1,0,0]
	v_pk_fma_f32 v[244:245], v[246:247], v[244:245], v[244:245]
	v_pk_fma_f32 v[250:251], v[252:253], v[250:251], v[250:251]
	v_pk_fma_f32 v[246:247], v[240:241], v[244:245], 1.0 op_sel_hi:[1,1,0] neg_lo:[1,0,0] neg_hi:[1,0,0]
	v_pk_fma_f32 v[252:253], v[242:243], v[250:251], 1.0 op_sel_hi:[1,1,0] neg_lo:[1,0,0] neg_hi:[1,0,0]
	v_pk_fma_f32 v[248:249], v[246:247], v[244:245], v[244:245]
	v_pk_fma_f32 v[254:255], v[252:253], v[250:251], v[250:251]
	v_pk_fma_f32 v[246:247], v[240:241], v[248:249], 1.0 op_sel_hi:[1,1,0] neg_lo:[1,0,0] neg_hi:[1,0,0]
	v_pk_fma_f32 v[252:253], v[242:243], v[254:255], 1.0 op_sel_hi:[1,1,0] neg_lo:[1,0,0] neg_hi:[1,0,0]
	v_pk_fma_f32 v[248:249], v[246:247], v[244:245], v[248:249]
	v_pk_fma_f32 v[254:255], v[252:253], v[250:251], v[254:255]
	v_div_fixup_f32 v240, v248, v240, 1.0
	v_div_fixup_f32 v241, v249, v241, 1.0
	v_div_fixup_f32 v242, v254, v242, 1.0
	v_div_fixup_f32 v243, v255, v243, 1.0
	s_mov_b64 vcc, s[10:11]
	v_pk_mul_f32 v[116:117], v[116:117], v[236:237]
	v_pk_mul_f32 v[112:113], v[112:113], v[238:239]
	v_pk_mul_f32 v[118:119], v[118:119], v[240:241]
	v_pk_mul_f32 v[120:121], v[114:115], v[242:243]
	v_cvt_pk_bf16_f32 v114, v116, v117
	v_cvt_pk_bf16_f32 v115, v118, v119
	v_cvt_pk_bf16_f32 v116, v112, v113
	v_or_b32_e32 v112, 16, v160
	v_mad_i64_i32 v[112:113], s[6:7], v112, s57, v[146:147]
	v_lshl_add_u64 v[112:113], v[112:113], 0, v[148:149]
	v_add_co_u32_e32 v122, vcc, s58, v112
	v_cvt_pk_bf16_f32 v117, v120, v121
	global_store_dwordx4 v[150:151], v[114:117], off offset:256
	s_nop 0
	v_addc_co_u32_e32 v123, vcc, 0, v113, vcc
	s_waitcnt vmcnt(7)
; __device__ __forceinline__ float sigmoidf_(float x) { return 1.0f / (1.0f + __expf(-x)); }
; __device__ __forceinline__ u32x4 pack8(const f32x4 v0, const f32x4 v1) { u32x4 w; w.x = pk2(v0[0], v0[1]); w.y = pk2(v0[2], v0[3]); w.z = pk2(v1[0], v1[1]); w.w = pk2(v1[2], v1[3]); return w; }
; __device__ __forceinline__ void unpack8(const u32x4 w, f32x4& v0, f32x4& v1) { v0 = (f32x4){bflo(w.x), bfhi(w.x), bflo(w.y), bfhi(w.y)}; v1 = (f32x4){bflo(w.z), bfhi(w.z), bflo(w.w), bfhi(w.w)}; }
;     __device__ __forceinline__ void operator()(const f32x4 (&acc)[2][2][4][2], const Unit& u, int wr, int wc, int fr, int fq) const {
;     ...
;         for (int ai = 0; ai < 2; ++ai)
; #pragma unroll
;             for (int m = 0; m < 4; ++m) {
;                 bf16_t* rowp = z + (size_t)(row0 + ai * 128 + m * 16) * DIN + col0;
; #pragma unroll
;                 for (int bj = 0; bj < 2; ++bj) {
;                     const u32x4 gw = *(const u32x4*)(rowp + (MODE == 0 ? O_GB : O_GA) + bj * 128);
;                     f32x4 g0, g1; unpack8(gw, g0, g1);
;                     f32x4 v0, v1;
; #pragma unroll
;                     for (int j = 0; j < 4; ++j) { v0[j] = sigmoidf_(g0[j]) * acc[ai][bj][m][0][j]; v1[j] = sigmoidf_(g1[j]) * acc[ai][bj][m][1][j]; }
;                     if (MODE == 1) { const u32x4 mw = *(const u32x4*)(rowp + bj * 128); f32x4 m0, m1; unpack8(mw, m0, m1); v0 += m0; v1 += m1; }
;                     *(u32x4*)(rowp + bj * 128) = pack8(v0, v1); }
	v_mov_b64_e32 v[118:119], v[208:209]
	v_mov_b64_e32 v[120:121], v[210:211]
	v_add_u32_e32 v198, 0x111a00, v197
	global_load_dwordx4 v[208:211], v198, s[22:23]
	s_mov_b32 s100, 0xbfb8aa3b
	v_lshlrev_b32_e32 v236, 16, v118
	v_and_b32_e32 v237, 0xffff0000, v118
	v_lshlrev_b32_e32 v238, 16, v120
	v_and_b32_e32 v239, 0xffff0000, v120
	v_lshlrev_b32_e32 v240, 16, v119
	v_and_b32_e32 v241, 0xffff0000, v119
	v_lshlrev_b32_e32 v242, 16, v121
	v_and_b32_e32 v243, 0xffff0000, v121
	v_pk_mul_f32 v[236:237], v[236:237], s[100:101] op_sel_hi:[1,0]
	v_pk_mul_f32 v[238:239], v[238:239], s[100:101] op_sel_hi:[1,0]
	v_pk_mul_f32 v[240:241], v[240:241], s[100:101] op_sel_hi:[1,0]
	v_pk_mul_f32 v[242:243], v[242:243], s[100:101] op_sel_hi:[1,0]
	v_exp_f32_e32 v236, v236
	v_exp_f32_e32 v237, v237
	v_exp_f32_e32 v238, v238
	v_exp_f32_e32 v239, v239
	v_exp_f32_e32 v240, v240
	v_exp_f32_e32 v241, v241
	v_exp_f32_e32 v242, v242
	v_exp_f32_e32 v243, v243
	s_nop 0
	v_pk_add_f32 v[236:237], v[236:237], 1.0 op_sel_hi:[1,0]
	v_pk_add_f32 v[238:239], v[238:239], 1.0 op_sel_hi:[1,0]
	v_pk_add_f32 v[240:241], v[240:241], 1.0 op_sel_hi:[1,0]
	v_pk_add_f32 v[242:243], v[242:243], 1.0 op_sel_hi:[1,0]
	v_rcp_f32_e32 v244, v236
	v_rcp_f32_e32 v245, v237
	v_rcp_f32_e32 v250, v238
	v_rcp_f32_e32 v251, v239
	v_pk_fma_f32 v[246:247], v[236:237], v[244:245], 1.0 op_sel_hi:[1,1,0] neg_lo:[1,0,0] neg_hi:[1,0,0]
	v_pk_fma_f32 v[252:253], v[238:239], v[250:251], 1.0 op_sel_hi:[1,1,0] neg_lo:[1,0,0] neg_hi:[1,0,0]
	v_pk_fma_f32 v[244:245], v[246:247], v[244:245], v[244:245]
	v_pk_fma_f32 v[250:251], v[252:253], v[250:251], v[250:251]
	v_pk_fma_f32 v[246:247], v[236:237], v[244:245], 1.0 op_sel_hi:[1,1,0] neg_lo:[1,0,0] neg_hi:[1,0,0]
	v_pk_fma_f32 v[252:253], v[238:239], v[250:251], 1.0 op_sel_hi:[1,1,0] neg_lo:[1,0,0] neg_hi:[1,0,0]
	v_pk_fma_f32 v[248:249], v[246:247], v[244:245], v[244:245]
	v_pk_fma_f32 v[254:255], v[252:253], v[250:251], v[250:251]
	v_pk_fma_f32 v[246:247], v[236:237], v[248:249], 1.0 op_sel_hi:[1,1,0] neg_lo:[1,0,0] neg_hi:[1,0,0]
	v_pk_fma_f32 v[252:253], v[238:239], v[254:255], 1.0 op_sel_hi:[1,1,0] neg_lo:[1,0,0] neg_hi:[1,0,0]
	v_pk_fma_f32 v[248:249], v[246:247], v[244:245], v[248:249]
	v_pk_fma_f32 v[254:255], v[252:253], v[250:251], v[254:255]
	v_div_fixup_f32 v236, v248, v236, 1.0
	v_div_fixup_f32 v237, v249, v237, 1.0
	v_div_fixup_f32 v238, v254, v238, 1.0
	v_div_fixup_f32 v239, v255, v239, 1.0
	v_rcp_f32_e32 v244, v240
	v_rcp_f32_e32 v245, v241
	v_rcp_f32_e32 v250, v242
	v_rcp_f32_e32 v251, v243
	v_pk_fma_f32 v[246:247], v[240:241], v[244:245], 1.0 op_sel_hi:[1,1,0] neg_lo:[1,0,0] neg_hi:[1,0,0]
	v_pk_fma_f32 v[252:253], v[242:243], v[250:251], 1.0 op_sel_hi:[1,1,0] neg_lo:[1,0,0] neg_hi:[1,0,0]
	v_pk_fma_f32 v[244:245], v[246:247], v[244:245], v[244:245]
	v_pk_fma_f32 v[250:251], v[252:253], v[250:251], v[250:251]
	v_pk_fma_f32 v[246:247], v[240:241], v[244:245], 1.0 op_sel_hi:[1,1,0] neg_lo:[1,0,0] neg_hi:[1,0,0]
	v_pk_fma_f32 v[252:253], v[242:243], v[250:251], 1.0 op_sel_hi:[1,1,0] neg_lo:[1,0,0] neg_hi:[1,0,0]
	v_pk_fma_f32 v[248:249], v[246:247], v[244:245], v[244:245]
	v_pk_fma_f32 v[254:255], v[252:253], v[250:251], v[250:251]
	v_pk_fma_f32 v[246:247], v[240:241], v[248:249], 1.0 op_sel_hi:[1,1,0] neg_lo:[1,0,0] neg_hi:[1,0,0]
	v_pk_fma_f32 v[252:253], v[242:243], v[254:255], 1.0 op_sel_hi:[1,1,0] neg_lo:[1,0,0] neg_hi:[1,0,0]
	v_pk_fma_f32 v[248:249], v[246:247], v[244:245], v[248:249]
	v_pk_fma_f32 v[254:255], v[252:253], v[250:251], v[254:255]
	v_div_fixup_f32 v240, v248, v240, 1.0
	v_div_fixup_f32 v241, v249, v241, 1.0
	v_div_fixup_f32 v242, v254, v242, 1.0
	v_div_fixup_f32 v243, v255, v243, 1.0
	v_mul_f32_e32 v108, v108, v236
	v_mul_f32_e32 v114, v104, v238
	v_mul_f32_e32 v104, v109, v237
	v_mul_f32_e32 v109, v105, v239
	v_mul_f32_e32 v105, v110, v240
	v_mul_f32_e32 v110, v106, v242
	v_mul_f32_e32 v106, v111, v241
	v_mul_f32_e32 v107, v107, v243
	v_cvt_pk_bf16_f32 v104, v108, v104
	v_cvt_pk_bf16_f32 v105, v105, v106
	v_cvt_pk_bf16_f32 v106, v114, v109
	v_cvt_pk_bf16_f32 v107, v110, v107
	s_waitcnt vmcnt(7)
	v_mov_b32_e32 v108, v212
	v_mov_b32_e32 v109, v213
	v_mov_b64_e32 v[110:111], v[214:215]
	v_add_u32_e32 v198, 0x111b00, v197
	global_load_dwordx4 v[212:215], v198, s[22:23]
	s_mov_b32 s100, 0xbfb8aa3b
	v_lshlrev_b32_e32 v236, 16, v108
	v_and_b32_e32 v237, 0xffff0000, v108
	v_lshlrev_b32_e32 v238, 16, v110
	v_and_b32_e32 v239, 0xffff0000, v110
	v_lshlrev_b32_e32 v240, 16, v109
	v_and_b32_e32 v241, 0xffff0000, v109
	v_lshlrev_b32_e32 v242, 16, v111
	v_and_b32_e32 v243, 0xffff0000, v111
	v_pk_mul_f32 v[236:237], v[236:237], s[100:101] op_sel_hi:[1,0]
	v_pk_mul_f32 v[238:239], v[238:239], s[100:101] op_sel_hi:[1,0]
	v_pk_mul_f32 v[240:241], v[240:241], s[100:101] op_sel_hi:[1,0]
	v_pk_mul_f32 v[242:243], v[242:243], s[100:101] op_sel_hi:[1,0]
	v_exp_f32_e32 v236, v236
	v_exp_f32_e32 v237, v237
	v_exp_f32_e32 v238, v238
	v_exp_f32_e32 v239, v239
	v_exp_f32_e32 v240, v240
	v_exp_f32_e32 v241, v241
	v_exp_f32_e32 v242, v242
	v_exp_f32_e32 v243, v243
	s_nop 0
	v_pk_add_f32 v[236:237], v[236:237], 1.0 op_sel_hi:[1,0]
	v_pk_add_f32 v[238:239], v[238:239], 1.0 op_sel_hi:[1,0]
	v_pk_add_f32 v[240:241], v[240:241], 1.0 op_sel_hi:[1,0]
	v_pk_add_f32 v[242:243], v[242:243], 1.0 op_sel_hi:[1,0]
	v_rcp_f32_e32 v244, v236
	v_rcp_f32_e32 v245, v237
	v_rcp_f32_e32 v250, v238
	v_rcp_f32_e32 v251, v239
	v_pk_fma_f32 v[246:247], v[236:237], v[244:245], 1.0 op_sel_hi:[1,1,0] neg_lo:[1,0,0] neg_hi:[1,0,0]
	v_pk_fma_f32 v[252:253], v[238:239], v[250:251], 1.0 op_sel_hi:[1,1,0] neg_lo:[1,0,0] neg_hi:[1,0,0]
	v_pk_fma_f32 v[244:245], v[246:247], v[244:245], v[244:245]
; __device__ __forceinline__ float sigmoidf_(float x) { return 1.0f / (1.0f + __expf(-x)); }
; __device__ __forceinline__ u32x4 pack8(const f32x4 v0, const f32x4 v1) { u32x4 w; w.x = pk2(v0[0], v0[1]); w.y = pk2(v0[2], v0[3]); w.z = pk2(v1[0], v1[1]); w.w = pk2(v1[2], v1[3]); return w; }
; __device__ __forceinline__ void unpack8(const u32x4 w, f32x4& v0, f32x4& v1) { v0 = (f32x4){bflo(w.x), bfhi(w.x), bflo(w.y), bfhi(w.y)}; v1 = (f32x4){bflo(w.z), bfhi(w.z), bflo(w.w), bfhi(w.w)}; }
;     __device__ __forceinline__ void operator()(const f32x4 (&acc)[2][2][4][2], const Unit& u, int wr, int wc, int fr, int fq) const {
;     ...
;         for (int ai = 0; ai < 2; ++ai)
; #pragma unroll
;             for (int m = 0; m < 4; ++m) {
;                 bf16_t* rowp = z + (size_t)(row0 + ai * 128 + m * 16) * DIN + col0;
; #pragma unroll
;                 for (int bj = 0; bj < 2; ++bj) {
;                     const u32x4 gw = *(const u32x4*)(rowp + (MODE == 0 ? O_GB : O_GA) + bj * 128);
;                     f32x4 g0, g1; unpack8(gw, g0, g1);
;                     f32x4 v0, v1;
; #pragma unroll
;                     for (int j = 0; j < 4; ++j) { v0[j] = sigmoidf_(g0[j]) * acc[ai][bj][m][0][j]; v1[j] = sigmoidf_(g1[j]) * acc[ai][bj][m][1][j]; }
;                     if (MODE == 1) { const u32x4 mw = *(const u32x4*)(rowp + bj * 128); f32x4 m0, m1; unpack8(mw, m0, m1); v0 += m0; v1 += m1; }
;                     *(u32x4*)(rowp + bj * 128) = pack8(v0, v1); }
	v_pk_fma_f32 v[250:251], v[252:253], v[250:251], v[250:251]
	v_pk_fma_f32 v[246:247], v[236:237], v[244:245], 1.0 op_sel_hi:[1,1,0] neg_lo:[1,0,0] neg_hi:[1,0,0]
	v_pk_fma_f32 v[252:253], v[238:239], v[250:251], 1.0 op_sel_hi:[1,1,0] neg_lo:[1,0,0] neg_hi:[1,0,0]
	v_pk_fma_f32 v[248:249], v[246:247], v[244:245], v[244:245]
	v_pk_fma_f32 v[254:255], v[252:253], v[250:251], v[250:251]
	v_pk_fma_f32 v[246:247], v[236:237], v[248:249], 1.0 op_sel_hi:[1,1,0] neg_lo:[1,0,0] neg_hi:[1,0,0]
	v_pk_fma_f32 v[252:253], v[238:239], v[254:255], 1.0 op_sel_hi:[1,1,0] neg_lo:[1,0,0] neg_hi:[1,0,0]
	v_pk_fma_f32 v[248:249], v[246:247], v[244:245], v[248:249]
	v_pk_fma_f32 v[254:255], v[252:253], v[250:251], v[254:255]
	v_div_fixup_f32 v236, v248, v236, 1.0
	v_div_fixup_f32 v237, v249, v237, 1.0
	v_div_fixup_f32 v238, v254, v238, 1.0
	v_div_fixup_f32 v239, v255, v239, 1.0
	v_rcp_f32_e32 v244, v240
	v_rcp_f32_e32 v245, v241
	v_rcp_f32_e32 v250, v242
	v_rcp_f32_e32 v251, v243
	v_pk_fma_f32 v[246:247], v[240:241], v[244:245], 1.0 op_sel_hi:[1,1,0] neg_lo:[1,0,0] neg_hi:[1,0,0]
	v_pk_fma_f32 v[252:253], v[242:243], v[250:251], 1.0 op_sel_hi:[1,1,0] neg_lo:[1,0,0] neg_hi:[1,0,0]
	v_pk_fma_f32 v[244:245], v[246:247], v[244:245], v[244:245]
	v_pk_fma_f32 v[250:251], v[252:253], v[250:251], v[250:251]
	v_pk_fma_f32 v[246:247], v[240:241], v[244:245], 1.0 op_sel_hi:[1,1,0] neg_lo:[1,0,0] neg_hi:[1,0,0]
	v_pk_fma_f32 v[252:253], v[242:243], v[250:251], 1.0 op_sel_hi:[1,1,0] neg_lo:[1,0,0] neg_hi:[1,0,0]
	v_pk_fma_f32 v[248:249], v[246:247], v[244:245], v[244:245]
	v_pk_fma_f32 v[254:255], v[252:253], v[250:251], v[250:251]
	v_pk_fma_f32 v[246:247], v[240:241], v[248:249], 1.0 op_sel_hi:[1,1,0] neg_lo:[1,0,0] neg_hi:[1,0,0]
	v_pk_fma_f32 v[252:253], v[242:243], v[254:255], 1.0 op_sel_hi:[1,1,0] neg_lo:[1,0,0] neg_hi:[1,0,0]
	v_pk_fma_f32 v[248:249], v[246:247], v[244:245], v[248:249]
	v_pk_fma_f32 v[254:255], v[252:253], v[250:251], v[254:255]
	v_div_fixup_f32 v240, v248, v240, 1.0
	v_div_fixup_f32 v241, v249, v241, 1.0
	v_div_fixup_f32 v242, v254, v242, 1.0
	v_div_fixup_f32 v243, v255, v243, 1.0
	global_store_dwordx4 v[112:113], v[104:107], off
	s_nop 0
	v_pk_mul_f32 v[100:101], v[100:101], v[236:237]
	v_pk_mul_f32 v[96:97], v[96:97], v[238:239]
	v_pk_mul_f32 v[102:103], v[102:103], v[240:241]
	v_pk_mul_f32 v[104:105], v[98:99], v[242:243]
	v_cvt_pk_bf16_f32 v98, v100, v101
	v_cvt_pk_bf16_f32 v99, v102, v103
	v_cvt_pk_bf16_f32 v100, v96, v97
	v_or_b32_e32 v96, 32, v160
	v_mad_i64_i32 v[96:97], s[6:7], v96, s57, v[146:147]
	v_lshl_add_u64 v[96:97], v[96:97], 0, v[148:149]
	v_add_co_u32_e32 v106, vcc, s58, v96
	v_cvt_pk_bf16_f32 v101, v104, v105
	global_store_dwordx4 v[112:113], v[98:101], off offset:256
	s_nop 0
	v_addc_co_u32_e32 v107, vcc, 0, v97, vcc
	s_waitcnt vmcnt(9)
	v_mov_b64_e32 v[102:103], v[216:217]
	v_mov_b64_e32 v[104:105], v[218:219]
	v_add_u32_e32 v198, 0x133a00, v197
	global_load_dwordx4 v[216:219], v198, s[22:23]
	s_mov_b32 s100, 0xbfb8aa3b
	v_lshlrev_b32_e32 v236, 16, v102
	v_and_b32_e32 v237, 0xffff0000, v102
	v_lshlrev_b32_e32 v238, 16, v104
	v_and_b32_e32 v239, 0xffff0000, v104
	v_lshlrev_b32_e32 v240, 16, v103
	v_and_b32_e32 v241, 0xffff0000, v103
	v_lshlrev_b32_e32 v242, 16, v105
	v_and_b32_e32 v243, 0xffff0000, v105
	v_pk_mul_f32 v[236:237], v[236:237], s[100:101] op_sel_hi:[1,0]
	v_pk_mul_f32 v[238:239], v[238:239], s[100:101] op_sel_hi:[1,0]
	v_pk_mul_f32 v[240:241], v[240:241], s[100:101] op_sel_hi:[1,0]
	v_pk_mul_f32 v[242:243], v[242:243], s[100:101] op_sel_hi:[1,0]
	v_exp_f32_e32 v236, v236
	v_exp_f32_e32 v237, v237
	v_exp_f32_e32 v238, v238
	v_exp_f32_e32 v239, v239
	v_exp_f32_e32 v240, v240
	v_exp_f32_e32 v241, v241
	v_exp_f32_e32 v242, v242
	v_exp_f32_e32 v243, v243
	s_nop 0
	v_pk_add_f32 v[236:237], v[236:237], 1.0 op_sel_hi:[1,0]
	v_pk_add_f32 v[238:239], v[238:239], 1.0 op_sel_hi:[1,0]
	v_pk_add_f32 v[240:241], v[240:241], 1.0 op_sel_hi:[1,0]
	v_pk_add_f32 v[242:243], v[242:243], 1.0 op_sel_hi:[1,0]
	v_rcp_f32_e32 v244, v236
	v_rcp_f32_e32 v245, v237
	v_rcp_f32_e32 v250, v238
	v_rcp_f32_e32 v251, v239
	v_pk_fma_f32 v[246:247], v[236:237], v[244:245], 1.0 op_sel_hi:[1,1,0] neg_lo:[1,0,0] neg_hi:[1,0,0]
	v_pk_fma_f32 v[252:253], v[238:239], v[250:251], 1.0 op_sel_hi:[1,1,0] neg_lo:[1,0,0] neg_hi:[1,0,0]
	v_pk_fma_f32 v[244:245], v[246:247], v[244:245], v[244:245]
	v_pk_fma_f32 v[250:251], v[252:253], v[250:251], v[250:251]
	v_pk_fma_f32 v[246:247], v[236:237], v[244:245], 1.0 op_sel_hi:[1,1,0] neg_lo:[1,0,0] neg_hi:[1,0,0]
	v_pk_fma_f32 v[252:253], v[238:239], v[250:251], 1.0 op_sel_hi:[1,1,0] neg_lo:[1,0,0] neg_hi:[1,0,0]
	v_pk_fma_f32 v[248:249], v[246:247], v[244:245], v[244:245]
	v_pk_fma_f32 v[254:255], v[252:253], v[250:251], v[250:251]
	v_pk_fma_f32 v[246:247], v[236:237], v[248:249], 1.0 op_sel_hi:[1,1,0] neg_lo:[1,0,0] neg_hi:[1,0,0]
	v_pk_fma_f32 v[252:253], v[238:239], v[254:255], 1.0 op_sel_hi:[1,1,0] neg_lo:[1,0,0] neg_hi:[1,0,0]
	v_pk_fma_f32 v[248:249], v[246:247], v[244:245], v[248:249]
	v_pk_fma_f32 v[254:255], v[252:253], v[250:251], v[254:255]
	v_div_fixup_f32 v236, v248, v236, 1.0
	v_div_fixup_f32 v237, v249, v237, 1.0
	v_div_fixup_f32 v238, v254, v238, 1.0
	v_div_fixup_f32 v239, v255, v239, 1.0
	v_rcp_f32_e32 v244, v240
	v_rcp_f32_e32 v245, v241
	v_rcp_f32_e32 v250, v242
	v_rcp_f32_e32 v251, v243
	v_pk_fma_f32 v[246:247], v[240:241], v[244:245], 1.0 op_sel_hi:[1,1,0] neg_lo:[1,0,0] neg_hi:[1,0,0]
	v_pk_fma_f32 v[252:253], v[242:243], v[250:251], 1.0 op_sel_hi:[1,1,0] neg_lo:[1,0,0] neg_hi:[1,0,0]
	v_pk_fma_f32 v[244:245], v[246:247], v[244:245], v[244:245]
	v_pk_fma_f32 v[250:251], v[252:253], v[250:251], v[250:251]
	v_pk_fma_f32 v[246:247], v[240:241], v[244:245], 1.0 op_sel_hi:[1,1,0] neg_lo:[1,0,0] neg_hi:[1,0,0]
	v_pk_fma_f32 v[252:253], v[242:243], v[250:251], 1.0 op_sel_hi:[1,1,0] neg_lo:[1,0,0] neg_hi:[1,0,0]
	v_pk_fma_f32 v[248:249], v[246:247], v[244:245], v[244:245]
	v_pk_fma_f32 v[254:255], v[252:253], v[250:251], v[250:251]
	v_pk_fma_f32 v[246:247], v[240:241], v[248:249], 1.0 op_sel_hi:[1,1,0] neg_lo:[1,0,0] neg_hi:[1,0,0]
	v_pk_fma_f32 v[252:253], v[242:243], v[254:255], 1.0 op_sel_hi:[1,1,0] neg_lo:[1,0,0] neg_hi:[1,0,0]
	v_pk_fma_f32 v[248:249], v[246:247], v[244:245], v[248:249]
	v_pk_fma_f32 v[254:255], v[252:253], v[250:251], v[254:255]
	v_div_fixup_f32 v240, v248, v240, 1.0
	v_div_fixup_f32 v241, v249, v241, 1.0
	v_div_fixup_f32 v242, v254, v242, 1.0
	v_div_fixup_f32 v243, v255, v243, 1.0
	v_mul_f32_e32 v92, v92, v236
	v_mul_f32_e32 v98, v88, v238
	v_mul_f32_e32 v88, v93, v237
	v_mul_f32_e32 v93, v89, v239
	v_mul_f32_e32 v89, v94, v240
	v_mul_f32_e32 v94, v90, v242
	v_mul_f32_e32 v90, v95, v241
	v_mul_f32_e32 v91, v91, v243
	v_cvt_pk_bf16_f32 v88, v92, v88
	v_cvt_pk_bf16_f32 v89, v89, v90
	v_cvt_pk_bf16_f32 v90, v98, v93
	v_cvt_pk_bf16_f32 v91, v94, v91
	s_waitcnt vmcnt(9)
; __device__ __forceinline__ float sigmoidf_(float x) { return 1.0f / (1.0f + __expf(-x)); }
; __device__ __forceinline__ u32x4 pack8(const f32x4 v0, const f32x4 v1) { u32x4 w; w.x = pk2(v0[0], v0[1]); w.y = pk2(v0[2], v0[3]); w.z = pk2(v1[0], v1[1]); w.w = pk2(v1[2], v1[3]); return w; }
; __device__ __forceinline__ void unpack8(const u32x4 w, f32x4& v0, f32x4& v1) { v0 = (f32x4){bflo(w.x), bfhi(w.x), bflo(w.y), bfhi(w.y)}; v1 = (f32x4){bflo(w.z), bfhi(w.z), bflo(w.w), bfhi(w.w)}; }
;     __device__ __forceinline__ void operator()(const f32x4 (&acc)[2][2][4][2], const Unit& u, int wr, int wc, int fr, int fq) const {
;     ...
;         for (int ai = 0; ai < 2; ++ai)
; #pragma unroll
;             for (int m = 0; m < 4; ++m) {
;                 bf16_t* rowp = z + (size_t)(row0 + ai * 128 + m * 16) * DIN + col0;
; #pragma unroll
;                 for (int bj = 0; bj < 2; ++bj) {
;                     const u32x4 gw = *(const u32x4*)(rowp + (MODE == 0 ? O_GB : O_GA) + bj * 128);
;                     f32x4 g0, g1; unpack8(gw, g0, g1);
;                     f32x4 v0, v1;
; #pragma unroll
;                     for (int j = 0; j < 4; ++j) { v0[j] = sigmoidf_(g0[j]) * acc[ai][bj][m][0][j]; v1[j] = sigmoidf_(g1[j]) * acc[ai][bj][m][1][j]; }
;                     if (MODE == 1) { const u32x4 mw = *(const u32x4*)(rowp + bj * 128); f32x4 m0, m1; unpack8(mw, m0, m1); v0 += m0; v1 += m1; }
;                     *(u32x4*)(rowp + bj * 128) = pack8(v0, v1); }
	v_mov_b32_e32 v92, v232
	v_mov_b32_e32 v93, v233
	v_mov_b64_e32 v[94:95], v[234:235]
	v_add_u32_e32 v198, 0x133b00, v197
	global_load_dwordx4 v[232:235], v198, s[22:23]
	s_mov_b32 s100, 0xbfb8aa3b
	v_lshlrev_b32_e32 v236, 16, v92
	v_and_b32_e32 v237, 0xffff0000, v92
	v_lshlrev_b32_e32 v238, 16, v94
	v_and_b32_e32 v239, 0xffff0000, v94
	v_lshlrev_b32_e32 v240, 16, v93
	v_and_b32_e32 v241, 0xffff0000, v93
	v_lshlrev_b32_e32 v242, 16, v95
	v_and_b32_e32 v243, 0xffff0000, v95
	v_pk_mul_f32 v[236:237], v[236:237], s[100:101] op_sel_hi:[1,0]
	v_pk_mul_f32 v[238:239], v[238:239], s[100:101] op_sel_hi:[1,0]
	v_pk_mul_f32 v[240:241], v[240:241], s[100:101] op_sel_hi:[1,0]
	v_pk_mul_f32 v[242:243], v[242:243], s[100:101] op_sel_hi:[1,0]
	v_exp_f32_e32 v236, v236
	v_exp_f32_e32 v237, v237
	v_exp_f32_e32 v238, v238
	v_exp_f32_e32 v239, v239
	v_exp_f32_e32 v240, v240
	v_exp_f32_e32 v241, v241
	v_exp_f32_e32 v242, v242
	v_exp_f32_e32 v243, v243
	s_nop 0
	v_pk_add_f32 v[236:237], v[236:237], 1.0 op_sel_hi:[1,0]
	v_pk_add_f32 v[238:239], v[238:239], 1.0 op_sel_hi:[1,0]
	v_pk_add_f32 v[240:241], v[240:241], 1.0 op_sel_hi:[1,0]
	v_pk_add_f32 v[242:243], v[242:243], 1.0 op_sel_hi:[1,0]
	v_rcp_f32_e32 v244, v236
	v_rcp_f32_e32 v245, v237
	v_rcp_f32_e32 v250, v238
	v_rcp_f32_e32 v251, v239
	v_pk_fma_f32 v[246:247], v[236:237], v[244:245], 1.0 op_sel_hi:[1,1,0] neg_lo:[1,0,0] neg_hi:[1,0,0]
	v_pk_fma_f32 v[252:253], v[238:239], v[250:251], 1.0 op_sel_hi:[1,1,0] neg_lo:[1,0,0] neg_hi:[1,0,0]
	v_pk_fma_f32 v[244:245], v[246:247], v[244:245], v[244:245]
	v_pk_fma_f32 v[250:251], v[252:253], v[250:251], v[250:251]
	v_pk_fma_f32 v[246:247], v[236:237], v[244:245], 1.0 op_sel_hi:[1,1,0] neg_lo:[1,0,0] neg_hi:[1,0,0]
	v_pk_fma_f32 v[252:253], v[238:239], v[250:251], 1.0 op_sel_hi:[1,1,0] neg_lo:[1,0,0] neg_hi:[1,0,0]
	v_pk_fma_f32 v[248:249], v[246:247], v[244:245], v[244:245]
	v_pk_fma_f32 v[254:255], v[252:253], v[250:251], v[250:251]
	v_pk_fma_f32 v[246:247], v[236:237], v[248:249], 1.0 op_sel_hi:[1,1,0] neg_lo:[1,0,0] neg_hi:[1,0,0]
	v_pk_fma_f32 v[252:253], v[238:239], v[254:255], 1.0 op_sel_hi:[1,1,0] neg_lo:[1,0,0] neg_hi:[1,0,0]
	v_pk_fma_f32 v[248:249], v[246:247], v[244:245], v[248:249]
	v_pk_fma_f32 v[254:255], v[252:253], v[250:251], v[254:255]
	v_div_fixup_f32 v236, v248, v236, 1.0
	v_div_fixup_f32 v237, v249, v237, 1.0
	v_div_fixup_f32 v238, v254, v238, 1.0
	v_div_fixup_f32 v239, v255, v239, 1.0
	v_rcp_f32_e32 v244, v240
	v_rcp_f32_e32 v245, v241
	v_rcp_f32_e32 v250, v242
	v_rcp_f32_e32 v251, v243
	v_pk_fma_f32 v[246:247], v[240:241], v[244:245], 1.0 op_sel_hi:[1,1,0] neg_lo:[1,0,0] neg_hi:[1,0,0]
	v_pk_fma_f32 v[252:253], v[242:243], v[250:251], 1.0 op_sel_hi:[1,1,0] neg_lo:[1,0,0] neg_hi:[1,0,0]
	v_pk_fma_f32 v[244:245], v[246:247], v[244:245], v[244:245]
	v_pk_fma_f32 v[250:251], v[252:253], v[250:251], v[250:251]
	v_pk_fma_f32 v[246:247], v[240:241], v[244:245], 1.0 op_sel_hi:[1,1,0] neg_lo:[1,0,0] neg_hi:[1,0,0]
	v_pk_fma_f32 v[252:253], v[242:243], v[250:251], 1.0 op_sel_hi:[1,1,0] neg_lo:[1,0,0] neg_hi:[1,0,0]
	v_pk_fma_f32 v[248:249], v[246:247], v[244:245], v[244:245]
	v_pk_fma_f32 v[254:255], v[252:253], v[250:251], v[250:251]
	v_pk_fma_f32 v[246:247], v[240:241], v[248:249], 1.0 op_sel_hi:[1,1,0] neg_lo:[1,0,0] neg_hi:[1,0,0]
	v_pk_fma_f32 v[252:253], v[242:243], v[254:255], 1.0 op_sel_hi:[1,1,0] neg_lo:[1,0,0] neg_hi:[1,0,0]
	v_pk_fma_f32 v[248:249], v[246:247], v[244:245], v[248:249]
	v_pk_fma_f32 v[254:255], v[252:253], v[250:251], v[254:255]
	v_div_fixup_f32 v240, v248, v240, 1.0
	v_div_fixup_f32 v241, v249, v241, 1.0
	v_div_fixup_f32 v242, v254, v242, 1.0
	v_div_fixup_f32 v243, v255, v243, 1.0
	global_store_dwordx4 v[96:97], v[88:91], off
	s_nop 0
	v_pk_mul_f32 v[84:85], v[84:85], v[236:237]
	v_pk_mul_f32 v[80:81], v[80:81], v[238:239]
	v_pk_mul_f32 v[86:87], v[86:87], v[240:241]
	v_pk_mul_f32 v[88:89], v[82:83], v[242:243]
	v_cvt_pk_bf16_f32 v82, v84, v85
	v_cvt_pk_bf16_f32 v83, v86, v87
	v_cvt_pk_bf16_f32 v84, v80, v81
	v_or_b32_e32 v80, 48, v160
	v_mad_i64_i32 v[80:81], s[6:7], v80, s57, v[146:147]
	v_lshl_add_u64 v[80:81], v[80:81], 0, v[148:149]
	v_add_co_u32_e32 v90, vcc, s58, v80
	v_cvt_pk_bf16_f32 v85, v88, v89
	global_store_dwordx4 v[96:97], v[82:85], off offset:256
	s_nop 0
	v_addc_co_u32_e32 v91, vcc, 0, v81, vcc
	s_waitcnt vmcnt(11)
; __device__ __forceinline__ float sigmoidf_(float x) { return 1.0f / (1.0f + __expf(-x)); }
; __device__ __forceinline__ u32x4 pack8(const f32x4 v0, const f32x4 v1) { u32x4 w; w.x = pk2(v0[0], v0[1]); w.y = pk2(v0[2], v0[3]); w.z = pk2(v1[0], v1[1]); w.w = pk2(v1[2], v1[3]); return w; }
; __device__ __forceinline__ void unpack8(const u32x4 w, f32x4& v0, f32x4& v1) { v0 = (f32x4){bflo(w.x), bfhi(w.x), bflo(w.y), bfhi(w.y)}; v1 = (f32x4){bflo(w.z), bfhi(w.z), bflo(w.w), bfhi(w.w)}; }
;     __device__ __forceinline__ void operator()(const f32x4 (&acc)[2][2][4][2], const Unit& u, int wr, int wc, int fr, int fq) const {
;     ...
;         for (int ai = 0; ai < 2; ++ai)
; #pragma unroll
;             for (int m = 0; m < 4; ++m) {
;                 bf16_t* rowp = z + (size_t)(row0 + ai * 128 + m * 16) * DIN + col0;
; #pragma unroll
;                 for (int bj = 0; bj < 2; ++bj) {
;                     const u32x4 gw = *(const u32x4*)(rowp + (MODE == 0 ? O_GB : O_GA) + bj * 128);
;                     f32x4 g0, g1; unpack8(gw, g0, g1);
;                     f32x4 v0, v1;
; #pragma unroll
;                     for (int j = 0; j < 4; ++j) { v0[j] = sigmoidf_(g0[j]) * acc[ai][bj][m][0][j]; v1[j] = sigmoidf_(g1[j]) * acc[ai][bj][m][1][j]; }
;                     if (MODE == 1) { const u32x4 mw = *(const u32x4*)(rowp + bj * 128); f32x4 m0, m1; unpack8(mw, m0, m1); v0 += m0; v1 += m1; }
;                     *(u32x4*)(rowp + bj * 128) = pack8(v0, v1); }
	v_mov_b64_e32 v[86:87], v[200:201]
	v_mov_b64_e32 v[88:89], v[202:203]
	v_add_u32_e32 v198, 0x155a00, v197
	global_load_dwordx4 v[200:203], v198, s[22:23]
	s_mov_b32 s100, 0xbfb8aa3b
	v_lshlrev_b32_e32 v236, 16, v86
	v_and_b32_e32 v237, 0xffff0000, v86
	v_lshlrev_b32_e32 v238, 16, v88
	v_and_b32_e32 v239, 0xffff0000, v88
	v_lshlrev_b32_e32 v240, 16, v87
	v_and_b32_e32 v241, 0xffff0000, v87
	v_lshlrev_b32_e32 v242, 16, v89
	v_and_b32_e32 v243, 0xffff0000, v89
	v_pk_mul_f32 v[236:237], v[236:237], s[100:101] op_sel_hi:[1,0]
	v_pk_mul_f32 v[238:239], v[238:239], s[100:101] op_sel_hi:[1,0]
	v_pk_mul_f32 v[240:241], v[240:241], s[100:101] op_sel_hi:[1,0]
	v_pk_mul_f32 v[242:243], v[242:243], s[100:101] op_sel_hi:[1,0]
	v_exp_f32_e32 v236, v236
	v_exp_f32_e32 v237, v237
	v_exp_f32_e32 v238, v238
	v_exp_f32_e32 v239, v239
	v_exp_f32_e32 v240, v240
	v_exp_f32_e32 v241, v241
	v_exp_f32_e32 v242, v242
	v_exp_f32_e32 v243, v243
	s_nop 0
	v_pk_add_f32 v[236:237], v[236:237], 1.0 op_sel_hi:[1,0]
	v_pk_add_f32 v[238:239], v[238:239], 1.0 op_sel_hi:[1,0]
	v_pk_add_f32 v[240:241], v[240:241], 1.0 op_sel_hi:[1,0]
	v_pk_add_f32 v[242:243], v[242:243], 1.0 op_sel_hi:[1,0]
	v_rcp_f32_e32 v244, v236
	v_rcp_f32_e32 v245, v237
	v_rcp_f32_e32 v250, v238
	v_rcp_f32_e32 v251, v239
	v_pk_fma_f32 v[246:247], v[236:237], v[244:245], 1.0 op_sel_hi:[1,1,0] neg_lo:[1,0,0] neg_hi:[1,0,0]
	v_pk_fma_f32 v[252:253], v[238:239], v[250:251], 1.0 op_sel_hi:[1,1,0] neg_lo:[1,0,0] neg_hi:[1,0,0]
	v_pk_fma_f32 v[244:245], v[246:247], v[244:245], v[244:245]
	v_pk_fma_f32 v[250:251], v[252:253], v[250:251], v[250:251]
	v_pk_fma_f32 v[246:247], v[236:237], v[244:245], 1.0 op_sel_hi:[1,1,0] neg_lo:[1,0,0] neg_hi:[1,0,0]
	v_pk_fma_f32 v[252:253], v[238:239], v[250:251], 1.0 op_sel_hi:[1,1,0] neg_lo:[1,0,0] neg_hi:[1,0,0]
	v_pk_fma_f32 v[248:249], v[246:247], v[244:245], v[244:245]
	v_pk_fma_f32 v[254:255], v[252:253], v[250:251], v[250:251]
	v_pk_fma_f32 v[246:247], v[236:237], v[248:249], 1.0 op_sel_hi:[1,1,0] neg_lo:[1,0,0] neg_hi:[1,0,0]
	v_pk_fma_f32 v[252:253], v[238:239], v[254:255], 1.0 op_sel_hi:[1,1,0] neg_lo:[1,0,0] neg_hi:[1,0,0]
	v_pk_fma_f32 v[248:249], v[246:247], v[244:245], v[248:249]
	v_pk_fma_f32 v[254:255], v[252:253], v[250:251], v[254:255]
	v_div_fixup_f32 v236, v248, v236, 1.0
	v_div_fixup_f32 v237, v249, v237, 1.0
	v_div_fixup_f32 v238, v254, v238, 1.0
	v_div_fixup_f32 v239, v255, v239, 1.0
	v_rcp_f32_e32 v244, v240
	v_rcp_f32_e32 v245, v241
	v_rcp_f32_e32 v250, v242
	v_rcp_f32_e32 v251, v243
	v_pk_fma_f32 v[246:247], v[240:241], v[244:245], 1.0 op_sel_hi:[1,1,0] neg_lo:[1,0,0] neg_hi:[1,0,0]
	v_pk_fma_f32 v[252:253], v[242:243], v[250:251], 1.0 op_sel_hi:[1,1,0] neg_lo:[1,0,0] neg_hi:[1,0,0]
	v_pk_fma_f32 v[244:245], v[246:247], v[244:245], v[244:245]
	v_pk_fma_f32 v[250:251], v[252:253], v[250:251], v[250:251]
	v_pk_fma_f32 v[246:247], v[240:241], v[244:245], 1.0 op_sel_hi:[1,1,0] neg_lo:[1,0,0] neg_hi:[1,0,0]
	v_pk_fma_f32 v[252:253], v[242:243], v[250:251], 1.0 op_sel_hi:[1,1,0] neg_lo:[1,0,0] neg_hi:[1,0,0]
	v_pk_fma_f32 v[248:249], v[246:247], v[244:245], v[244:245]
	v_pk_fma_f32 v[254:255], v[252:253], v[250:251], v[250:251]
	v_pk_fma_f32 v[246:247], v[240:241], v[248:249], 1.0 op_sel_hi:[1,1,0] neg_lo:[1,0,0] neg_hi:[1,0,0]
	v_pk_fma_f32 v[252:253], v[242:243], v[254:255], 1.0 op_sel_hi:[1,1,0] neg_lo:[1,0,0] neg_hi:[1,0,0]
	v_pk_fma_f32 v[248:249], v[246:247], v[244:245], v[248:249]
	v_pk_fma_f32 v[254:255], v[252:253], v[250:251], v[254:255]
	v_div_fixup_f32 v240, v248, v240, 1.0
	v_div_fixup_f32 v241, v249, v241, 1.0
	v_div_fixup_f32 v242, v254, v242, 1.0
	v_div_fixup_f32 v243, v255, v243, 1.0
	v_mul_f32_e32 v76, v76, v236
	v_mul_f32_e32 v82, v72, v238
	v_mul_f32_e32 v72, v77, v237
	v_mul_f32_e32 v77, v73, v239
	v_mul_f32_e32 v73, v78, v240
	v_mul_f32_e32 v78, v74, v242
	v_mul_f32_e32 v74, v79, v241
	v_mul_f32_e32 v75, v75, v243
	v_cvt_pk_bf16_f32 v72, v76, v72
	v_cvt_pk_bf16_f32 v73, v73, v74
	v_cvt_pk_bf16_f32 v74, v82, v77
	v_cvt_pk_bf16_f32 v75, v78, v75
	s_waitcnt vmcnt(10)
	v_mov_b32_e32 v76, v204
	v_mov_b32_e32 v77, v205
	v_mov_b64_e32 v[78:79], v[206:207]
	v_add_u32_e32 v198, 0x155b00, v197
	global_load_dwordx4 v[204:207], v198, s[22:23]
	s_mov_b32 s100, 0xbfb8aa3b
	v_lshlrev_b32_e32 v236, 16, v76
	v_and_b32_e32 v237, 0xffff0000, v76
	v_lshlrev_b32_e32 v238, 16, v78
	v_and_b32_e32 v239, 0xffff0000, v78
	v_lshlrev_b32_e32 v240, 16, v77
	v_and_b32_e32 v241, 0xffff0000, v77
	v_lshlrev_b32_e32 v242, 16, v79
	v_and_b32_e32 v243, 0xffff0000, v79
	v_pk_mul_f32 v[236:237], v[236:237], s[100:101] op_sel_hi:[1,0]
	v_pk_mul_f32 v[238:239], v[238:239], s[100:101] op_sel_hi:[1,0]
	v_pk_mul_f32 v[240:241], v[240:241], s[100:101] op_sel_hi:[1,0]
	v_pk_mul_f32 v[242:243], v[242:243], s[100:101] op_sel_hi:[1,0]
	v_exp_f32_e32 v236, v236
	v_exp_f32_e32 v237, v237
	v_exp_f32_e32 v238, v238
	v_exp_f32_e32 v239, v239
	v_exp_f32_e32 v240, v240
	v_exp_f32_e32 v241, v241
	v_exp_f32_e32 v242, v242
	v_exp_f32_e32 v243, v243
	s_nop 0
	v_pk_add_f32 v[236:237], v[236:237], 1.0 op_sel_hi:[1,0]
	v_pk_add_f32 v[238:239], v[238:239], 1.0 op_sel_hi:[1,0]
	v_pk_add_f32 v[240:241], v[240:241], 1.0 op_sel_hi:[1,0]
	v_pk_add_f32 v[242:243], v[242:243], 1.0 op_sel_hi:[1,0]
	v_rcp_f32_e32 v244, v236
	v_rcp_f32_e32 v245, v237
	v_rcp_f32_e32 v250, v238
	v_rcp_f32_e32 v251, v239
	v_pk_fma_f32 v[246:247], v[236:237], v[244:245], 1.0 op_sel_hi:[1,1,0] neg_lo:[1,0,0] neg_hi:[1,0,0]
	v_pk_fma_f32 v[252:253], v[238:239], v[250:251], 1.0 op_sel_hi:[1,1,0] neg_lo:[1,0,0] neg_hi:[1,0,0]
	v_pk_fma_f32 v[244:245], v[246:247], v[244:245], v[244:245]
	v_pk_fma_f32 v[250:251], v[252:253], v[250:251], v[250:251]
; __device__ __forceinline__ float sigmoidf_(float x) { return 1.0f / (1.0f + __expf(-x)); }
; __device__ __forceinline__ u32x4 pack8(const f32x4 v0, const f32x4 v1) { u32x4 w; w.x = pk2(v0[0], v0[1]); w.y = pk2(v0[2], v0[3]); w.z = pk2(v1[0], v1[1]); w.w = pk2(v1[2], v1[3]); return w; }
; __device__ __forceinline__ void unpack8(const u32x4 w, f32x4& v0, f32x4& v1) { v0 = (f32x4){bflo(w.x), bfhi(w.x), bflo(w.y), bfhi(w.y)}; v1 = (f32x4){bflo(w.z), bfhi(w.z), bflo(w.w), bfhi(w.w)}; }
;     __device__ __forceinline__ void operator()(const f32x4 (&acc)[2][2][4][2], const Unit& u, int wr, int wc, int fr, int fq) const {
;     ...
;         for (int ai = 0; ai < 2; ++ai)
; #pragma unroll
;             for (int m = 0; m < 4; ++m) {
;                 bf16_t* rowp = z + (size_t)(row0 + ai * 128 + m * 16) * DIN + col0;
; #pragma unroll
;                 for (int bj = 0; bj < 2; ++bj) {
;                     const u32x4 gw = *(const u32x4*)(rowp + (MODE == 0 ? O_GB : O_GA) + bj * 128);
;                     f32x4 g0, g1; unpack8(gw, g0, g1);
;                     f32x4 v0, v1;
; #pragma unroll
;                     for (int j = 0; j < 4; ++j) { v0[j] = sigmoidf_(g0[j]) * acc[ai][bj][m][0][j]; v1[j] = sigmoidf_(g1[j]) * acc[ai][bj][m][1][j]; }
;                     if (MODE == 1) { const u32x4 mw = *(const u32x4*)(rowp + bj * 128); f32x4 m0, m1; unpack8(mw, m0, m1); v0 += m0; v1 += m1; }
;                     *(u32x4*)(rowp + bj * 128) = pack8(v0, v1); }
	v_pk_fma_f32 v[246:247], v[236:237], v[244:245], 1.0 op_sel_hi:[1,1,0] neg_lo:[1,0,0] neg_hi:[1,0,0]
	v_pk_fma_f32 v[252:253], v[238:239], v[250:251], 1.0 op_sel_hi:[1,1,0] neg_lo:[1,0,0] neg_hi:[1,0,0]
	v_pk_fma_f32 v[248:249], v[246:247], v[244:245], v[244:245]
	v_pk_fma_f32 v[254:255], v[252:253], v[250:251], v[250:251]
	v_pk_fma_f32 v[246:247], v[236:237], v[248:249], 1.0 op_sel_hi:[1,1,0] neg_lo:[1,0,0] neg_hi:[1,0,0]
	v_pk_fma_f32 v[252:253], v[238:239], v[254:255], 1.0 op_sel_hi:[1,1,0] neg_lo:[1,0,0] neg_hi:[1,0,0]
	v_pk_fma_f32 v[248:249], v[246:247], v[244:245], v[248:249]
	v_pk_fma_f32 v[254:255], v[252:253], v[250:251], v[254:255]
	v_div_fixup_f32 v236, v248, v236, 1.0
	v_div_fixup_f32 v237, v249, v237, 1.0
	v_div_fixup_f32 v238, v254, v238, 1.0
	v_div_fixup_f32 v239, v255, v239, 1.0
	v_rcp_f32_e32 v244, v240
	v_rcp_f32_e32 v245, v241
	v_rcp_f32_e32 v250, v242
	v_rcp_f32_e32 v251, v243
	v_pk_fma_f32 v[246:247], v[240:241], v[244:245], 1.0 op_sel_hi:[1,1,0] neg_lo:[1,0,0] neg_hi:[1,0,0]
	v_pk_fma_f32 v[252:253], v[242:243], v[250:251], 1.0 op_sel_hi:[1,1,0] neg_lo:[1,0,0] neg_hi:[1,0,0]
	v_pk_fma_f32 v[244:245], v[246:247], v[244:245], v[244:245]
	v_pk_fma_f32 v[250:251], v[252:253], v[250:251], v[250:251]
	v_pk_fma_f32 v[246:247], v[240:241], v[244:245], 1.0 op_sel_hi:[1,1,0] neg_lo:[1,0,0] neg_hi:[1,0,0]
	v_pk_fma_f32 v[252:253], v[242:243], v[250:251], 1.0 op_sel_hi:[1,1,0] neg_lo:[1,0,0] neg_hi:[1,0,0]
	v_pk_fma_f32 v[248:249], v[246:247], v[244:245], v[244:245]
	v_pk_fma_f32 v[254:255], v[252:253], v[250:251], v[250:251]
	v_pk_fma_f32 v[246:247], v[240:241], v[248:249], 1.0 op_sel_hi:[1,1,0] neg_lo:[1,0,0] neg_hi:[1,0,0]
	v_pk_fma_f32 v[252:253], v[242:243], v[254:255], 1.0 op_sel_hi:[1,1,0] neg_lo:[1,0,0] neg_hi:[1,0,0]
	v_pk_fma_f32 v[248:249], v[246:247], v[244:245], v[248:249]
	v_pk_fma_f32 v[254:255], v[252:253], v[250:251], v[254:255]
	v_div_fixup_f32 v240, v248, v240, 1.0
	v_div_fixup_f32 v241, v249, v241, 1.0
	v_div_fixup_f32 v242, v254, v242, 1.0
	v_div_fixup_f32 v243, v255, v243, 1.0
	global_store_dwordx4 v[80:81], v[72:75], off
	s_nop 0
	v_pk_mul_f32 v[68:69], v[68:69], v[236:237]
	v_pk_mul_f32 v[64:65], v[64:65], v[238:239]
	v_pk_mul_f32 v[70:71], v[70:71], v[240:241]
	v_pk_mul_f32 v[72:73], v[66:67], v[242:243]
	v_cvt_pk_bf16_f32 v66, v68, v69
	v_cvt_pk_bf16_f32 v67, v70, v71
	v_cvt_pk_bf16_f32 v68, v64, v65
	v_add_u32_e32 v64, 0x80, v160
	v_mad_i64_i32 v[64:65], s[6:7], v64, s57, v[146:147]
	v_lshl_add_u64 v[64:65], v[64:65], 0, v[148:149]
	v_add_co_u32_e32 v74, vcc, s58, v64
	v_cvt_pk_bf16_f32 v69, v72, v73
	global_store_dwordx4 v[80:81], v[66:69], off offset:256
	s_nop 0
	v_addc_co_u32_e32 v75, vcc, 0, v65, vcc
	s_waitcnt vmcnt(11)
	v_mov_b64_e32 v[70:71], v[208:209]
	v_mov_b64_e32 v[72:73], v[210:211]
	v_add_u32_e32 v198, 0x177a00, v197
	global_load_dwordx4 v[208:211], v198, s[22:23]
	s_mov_b32 s100, 0xbfb8aa3b
	v_lshlrev_b32_e32 v236, 16, v70
	v_and_b32_e32 v237, 0xffff0000, v70
	v_lshlrev_b32_e32 v238, 16, v72
	v_and_b32_e32 v239, 0xffff0000, v72
	v_lshlrev_b32_e32 v240, 16, v71
	v_and_b32_e32 v241, 0xffff0000, v71
	v_lshlrev_b32_e32 v242, 16, v73
	v_and_b32_e32 v243, 0xffff0000, v73
	v_pk_mul_f32 v[236:237], v[236:237], s[100:101] op_sel_hi:[1,0]
	v_pk_mul_f32 v[238:239], v[238:239], s[100:101] op_sel_hi:[1,0]
	v_pk_mul_f32 v[240:241], v[240:241], s[100:101] op_sel_hi:[1,0]
	v_pk_mul_f32 v[242:243], v[242:243], s[100:101] op_sel_hi:[1,0]
	v_exp_f32_e32 v236, v236
	v_exp_f32_e32 v237, v237
	v_exp_f32_e32 v238, v238
	v_exp_f32_e32 v239, v239
	v_exp_f32_e32 v240, v240
	v_exp_f32_e32 v241, v241
	v_exp_f32_e32 v242, v242
	v_exp_f32_e32 v243, v243
	s_nop 0
	v_pk_add_f32 v[236:237], v[236:237], 1.0 op_sel_hi:[1,0]
	v_pk_add_f32 v[238:239], v[238:239], 1.0 op_sel_hi:[1,0]
	v_pk_add_f32 v[240:241], v[240:241], 1.0 op_sel_hi:[1,0]
	v_pk_add_f32 v[242:243], v[242:243], 1.0 op_sel_hi:[1,0]
	v_rcp_f32_e32 v244, v236
	v_rcp_f32_e32 v245, v237
	v_rcp_f32_e32 v250, v238
	v_rcp_f32_e32 v251, v239
	v_pk_fma_f32 v[246:247], v[236:237], v[244:245], 1.0 op_sel_hi:[1,1,0] neg_lo:[1,0,0] neg_hi:[1,0,0]
	v_pk_fma_f32 v[252:253], v[238:239], v[250:251], 1.0 op_sel_hi:[1,1,0] neg_lo:[1,0,0] neg_hi:[1,0,0]
	v_pk_fma_f32 v[244:245], v[246:247], v[244:245], v[244:245]
	v_pk_fma_f32 v[250:251], v[252:253], v[250:251], v[250:251]
	v_pk_fma_f32 v[246:247], v[236:237], v[244:245], 1.0 op_sel_hi:[1,1,0] neg_lo:[1,0,0] neg_hi:[1,0,0]
	v_pk_fma_f32 v[252:253], v[238:239], v[250:251], 1.0 op_sel_hi:[1,1,0] neg_lo:[1,0,0] neg_hi:[1,0,0]
	v_pk_fma_f32 v[248:249], v[246:247], v[244:245], v[244:245]
	v_pk_fma_f32 v[254:255], v[252:253], v[250:251], v[250:251]
	v_pk_fma_f32 v[246:247], v[236:237], v[248:249], 1.0 op_sel_hi:[1,1,0] neg_lo:[1,0,0] neg_hi:[1,0,0]
	v_pk_fma_f32 v[252:253], v[238:239], v[254:255], 1.0 op_sel_hi:[1,1,0] neg_lo:[1,0,0] neg_hi:[1,0,0]
	v_pk_fma_f32 v[248:249], v[246:247], v[244:245], v[248:249]
	v_pk_fma_f32 v[254:255], v[252:253], v[250:251], v[254:255]
	v_div_fixup_f32 v236, v248, v236, 1.0
	v_div_fixup_f32 v237, v249, v237, 1.0
	v_div_fixup_f32 v238, v254, v238, 1.0
	v_div_fixup_f32 v239, v255, v239, 1.0
	v_rcp_f32_e32 v244, v240
	v_rcp_f32_e32 v245, v241
	v_rcp_f32_e32 v250, v242
	v_rcp_f32_e32 v251, v243
	v_pk_fma_f32 v[246:247], v[240:241], v[244:245], 1.0 op_sel_hi:[1,1,0] neg_lo:[1,0,0] neg_hi:[1,0,0]
	v_pk_fma_f32 v[252:253], v[242:243], v[250:251], 1.0 op_sel_hi:[1,1,0] neg_lo:[1,0,0] neg_hi:[1,0,0]
	v_pk_fma_f32 v[244:245], v[246:247], v[244:245], v[244:245]
	v_pk_fma_f32 v[250:251], v[252:253], v[250:251], v[250:251]
	v_pk_fma_f32 v[246:247], v[240:241], v[244:245], 1.0 op_sel_hi:[1,1,0] neg_lo:[1,0,0] neg_hi:[1,0,0]
	v_pk_fma_f32 v[252:253], v[242:243], v[250:251], 1.0 op_sel_hi:[1,1,0] neg_lo:[1,0,0] neg_hi:[1,0,0]
	v_pk_fma_f32 v[248:249], v[246:247], v[244:245], v[244:245]
	v_pk_fma_f32 v[254:255], v[252:253], v[250:251], v[250:251]
	v_pk_fma_f32 v[246:247], v[240:241], v[248:249], 1.0 op_sel_hi:[1,1,0] neg_lo:[1,0,0] neg_hi:[1,0,0]
	v_pk_fma_f32 v[252:253], v[242:243], v[254:255], 1.0 op_sel_hi:[1,1,0] neg_lo:[1,0,0] neg_hi:[1,0,0]
	v_pk_fma_f32 v[248:249], v[246:247], v[244:245], v[248:249]
	v_pk_fma_f32 v[254:255], v[252:253], v[250:251], v[254:255]
	v_div_fixup_f32 v240, v248, v240, 1.0
	v_div_fixup_f32 v241, v249, v241, 1.0
	v_div_fixup_f32 v242, v254, v242, 1.0
	v_div_fixup_f32 v243, v255, v243, 1.0
	v_mul_f32_e32 v60, v60, v236
	v_mul_f32_e32 v66, v56, v238
	v_mul_f32_e32 v56, v61, v237
	v_mul_f32_e32 v61, v57, v239
	v_mul_f32_e32 v57, v62, v240
	v_mul_f32_e32 v62, v58, v242
	v_mul_f32_e32 v58, v63, v241
	v_mul_f32_e32 v59, v59, v243
	v_cvt_pk_bf16_f32 v56, v60, v56
	v_cvt_pk_bf16_f32 v57, v57, v58
	v_cvt_pk_bf16_f32 v58, v66, v61
	v_cvt_pk_bf16_f32 v59, v62, v59
	s_waitcnt vmcnt(11)
; __device__ __forceinline__ float sigmoidf_(float x) { return 1.0f / (1.0f + __expf(-x)); }
; __device__ __forceinline__ u32x4 pack8(const f32x4 v0, const f32x4 v1) { u32x4 w; w.x = pk2(v0[0], v0[1]); w.y = pk2(v0[2], v0[3]); w.z = pk2(v1[0], v1[1]); w.w = pk2(v1[2], v1[3]); return w; }
; __device__ __forceinline__ void unpack8(const u32x4 w, f32x4& v0, f32x4& v1) { v0 = (f32x4){bflo(w.x), bfhi(w.x), bflo(w.y), bfhi(w.y)}; v1 = (f32x4){bflo(w.z), bfhi(w.z), bflo(w.w), bfhi(w.w)}; }
;     __device__ __forceinline__ void operator()(const f32x4 (&acc)[2][2][4][2], const Unit& u, int wr, int wc, int fr, int fq) const {
;     ...
;         for (int ai = 0; ai < 2; ++ai)
; #pragma unroll
;             for (int m = 0; m < 4; ++m) {
;                 bf16_t* rowp = z + (size_t)(row0 + ai * 128 + m * 16) * DIN + col0;
; #pragma unroll
;                 for (int bj = 0; bj < 2; ++bj) {
;                     const u32x4 gw = *(const u32x4*)(rowp + (MODE == 0 ? O_GB : O_GA) + bj * 128);
;                     f32x4 g0, g1; unpack8(gw, g0, g1);
;                     f32x4 v0, v1;
; #pragma unroll
;                     for (int j = 0; j < 4; ++j) { v0[j] = sigmoidf_(g0[j]) * acc[ai][bj][m][0][j]; v1[j] = sigmoidf_(g1[j]) * acc[ai][bj][m][1][j]; }
;                     if (MODE == 1) { const u32x4 mw = *(const u32x4*)(rowp + bj * 128); f32x4 m0, m1; unpack8(mw, m0, m1); v0 += m0; v1 += m1; }
;                     *(u32x4*)(rowp + bj * 128) = pack8(v0, v1); }
	v_mov_b32_e32 v60, v212
	v_mov_b32_e32 v61, v213
	v_mov_b64_e32 v[62:63], v[214:215]
	v_add_u32_e32 v198, 0x177b00, v197
	global_load_dwordx4 v[212:215], v198, s[22:23]
	s_mov_b32 s100, 0xbfb8aa3b
	v_lshlrev_b32_e32 v236, 16, v60
	v_and_b32_e32 v237, 0xffff0000, v60
	v_lshlrev_b32_e32 v238, 16, v62
	v_and_b32_e32 v239, 0xffff0000, v62
	v_lshlrev_b32_e32 v240, 16, v61
	v_and_b32_e32 v241, 0xffff0000, v61
	v_lshlrev_b32_e32 v242, 16, v63
	v_and_b32_e32 v243, 0xffff0000, v63
	v_pk_mul_f32 v[236:237], v[236:237], s[100:101] op_sel_hi:[1,0]
	v_pk_mul_f32 v[238:239], v[238:239], s[100:101] op_sel_hi:[1,0]
	v_pk_mul_f32 v[240:241], v[240:241], s[100:101] op_sel_hi:[1,0]
	v_pk_mul_f32 v[242:243], v[242:243], s[100:101] op_sel_hi:[1,0]
	v_exp_f32_e32 v236, v236
	v_exp_f32_e32 v237, v237
	v_exp_f32_e32 v238, v238
	v_exp_f32_e32 v239, v239
	v_exp_f32_e32 v240, v240
	v_exp_f32_e32 v241, v241
	v_exp_f32_e32 v242, v242
	v_exp_f32_e32 v243, v243
	s_nop 0
	v_pk_add_f32 v[236:237], v[236:237], 1.0 op_sel_hi:[1,0]
	v_pk_add_f32 v[238:239], v[238:239], 1.0 op_sel_hi:[1,0]
	v_pk_add_f32 v[240:241], v[240:241], 1.0 op_sel_hi:[1,0]
	v_pk_add_f32 v[242:243], v[242:243], 1.0 op_sel_hi:[1,0]
	v_rcp_f32_e32 v244, v236
	v_rcp_f32_e32 v245, v237
	v_rcp_f32_e32 v250, v238
	v_rcp_f32_e32 v251, v239
	v_pk_fma_f32 v[246:247], v[236:237], v[244:245], 1.0 op_sel_hi:[1,1,0] neg_lo:[1,0,0] neg_hi:[1,0,0]
	v_pk_fma_f32 v[252:253], v[238:239], v[250:251], 1.0 op_sel_hi:[1,1,0] neg_lo:[1,0,0] neg_hi:[1,0,0]
	v_pk_fma_f32 v[244:245], v[246:247], v[244:245], v[244:245]
	v_pk_fma_f32 v[250:251], v[252:253], v[250:251], v[250:251]
	v_pk_fma_f32 v[246:247], v[236:237], v[244:245], 1.0 op_sel_hi:[1,1,0] neg_lo:[1,0,0] neg_hi:[1,0,0]
	v_pk_fma_f32 v[252:253], v[238:239], v[250:251], 1.0 op_sel_hi:[1,1,0] neg_lo:[1,0,0] neg_hi:[1,0,0]
	v_pk_fma_f32 v[248:249], v[246:247], v[244:245], v[244:245]
	v_pk_fma_f32 v[254:255], v[252:253], v[250:251], v[250:251]
	v_pk_fma_f32 v[246:247], v[236:237], v[248:249], 1.0 op_sel_hi:[1,1,0] neg_lo:[1,0,0] neg_hi:[1,0,0]
	v_pk_fma_f32 v[252:253], v[238:239], v[254:255], 1.0 op_sel_hi:[1,1,0] neg_lo:[1,0,0] neg_hi:[1,0,0]
	v_pk_fma_f32 v[248:249], v[246:247], v[244:245], v[248:249]
	v_pk_fma_f32 v[254:255], v[252:253], v[250:251], v[254:255]
	v_div_fixup_f32 v236, v248, v236, 1.0
	v_div_fixup_f32 v237, v249, v237, 1.0
	v_div_fixup_f32 v238, v254, v238, 1.0
	v_div_fixup_f32 v239, v255, v239, 1.0
	v_rcp_f32_e32 v244, v240
	v_rcp_f32_e32 v245, v241
	v_rcp_f32_e32 v250, v242
	v_rcp_f32_e32 v251, v243
	v_pk_fma_f32 v[246:247], v[240:241], v[244:245], 1.0 op_sel_hi:[1,1,0] neg_lo:[1,0,0] neg_hi:[1,0,0]
	v_pk_fma_f32 v[252:253], v[242:243], v[250:251], 1.0 op_sel_hi:[1,1,0] neg_lo:[1,0,0] neg_hi:[1,0,0]
	v_pk_fma_f32 v[244:245], v[246:247], v[244:245], v[244:245]
	v_pk_fma_f32 v[250:251], v[252:253], v[250:251], v[250:251]
	v_pk_fma_f32 v[246:247], v[240:241], v[244:245], 1.0 op_sel_hi:[1,1,0] neg_lo:[1,0,0] neg_hi:[1,0,0]
	v_pk_fma_f32 v[252:253], v[242:243], v[250:251], 1.0 op_sel_hi:[1,1,0] neg_lo:[1,0,0] neg_hi:[1,0,0]
	v_pk_fma_f32 v[248:249], v[246:247], v[244:245], v[244:245]
	v_pk_fma_f32 v[254:255], v[252:253], v[250:251], v[250:251]
	v_pk_fma_f32 v[246:247], v[240:241], v[248:249], 1.0 op_sel_hi:[1,1,0] neg_lo:[1,0,0] neg_hi:[1,0,0]
	v_pk_fma_f32 v[252:253], v[242:243], v[254:255], 1.0 op_sel_hi:[1,1,0] neg_lo:[1,0,0] neg_hi:[1,0,0]
	v_pk_fma_f32 v[248:249], v[246:247], v[244:245], v[248:249]
	v_pk_fma_f32 v[254:255], v[252:253], v[250:251], v[254:255]
	v_div_fixup_f32 v240, v248, v240, 1.0
	v_div_fixup_f32 v241, v249, v241, 1.0
	v_div_fixup_f32 v242, v254, v242, 1.0
	v_div_fixup_f32 v243, v255, v243, 1.0
	global_store_dwordx4 v[64:65], v[56:59], off
	s_nop 0
	v_pk_mul_f32 v[52:53], v[52:53], v[236:237]
	v_pk_mul_f32 v[48:49], v[48:49], v[238:239]
	v_pk_mul_f32 v[54:55], v[54:55], v[240:241]
	v_pk_mul_f32 v[56:57], v[50:51], v[242:243]
	v_cvt_pk_bf16_f32 v50, v52, v53
	v_cvt_pk_bf16_f32 v51, v54, v55
	v_cvt_pk_bf16_f32 v52, v48, v49
	v_add_u32_e32 v48, 0x90, v160
	v_mad_i64_i32 v[48:49], s[6:7], v48, s57, v[146:147]
	v_lshl_add_u64 v[48:49], v[48:49], 0, v[148:149]
	v_add_co_u32_e32 v58, vcc, s58, v48
	v_cvt_pk_bf16_f32 v53, v56, v57
	global_store_dwordx4 v[64:65], v[50:53], off offset:256
	s_nop 0
	v_addc_co_u32_e32 v59, vcc, 0, v49, vcc
	s_waitcnt vmcnt(11)
; __device__ __forceinline__ float sigmoidf_(float x) { return 1.0f / (1.0f + __expf(-x)); }
; __device__ __forceinline__ u32x4 pack8(const f32x4 v0, const f32x4 v1) { u32x4 w; w.x = pk2(v0[0], v0[1]); w.y = pk2(v0[2], v0[3]); w.z = pk2(v1[0], v1[1]); w.w = pk2(v1[2], v1[3]); return w; }
; __device__ __forceinline__ void unpack8(const u32x4 w, f32x4& v0, f32x4& v1) { v0 = (f32x4){bflo(w.x), bfhi(w.x), bflo(w.y), bfhi(w.y)}; v1 = (f32x4){bflo(w.z), bfhi(w.z), bflo(w.w), bfhi(w.w)}; }
;     __device__ __forceinline__ void operator()(const f32x4 (&acc)[2][2][4][2], const Unit& u, int wr, int wc, int fr, int fq) const {
;     ...
;         for (int ai = 0; ai < 2; ++ai)
; #pragma unroll
;             for (int m = 0; m < 4; ++m) {
;                 bf16_t* rowp = z + (size_t)(row0 + ai * 128 + m * 16) * DIN + col0;
; #pragma unroll
;                 for (int bj = 0; bj < 2; ++bj) {
;                     const u32x4 gw = *(const u32x4*)(rowp + (MODE == 0 ? O_GB : O_GA) + bj * 128);
;                     f32x4 g0, g1; unpack8(gw, g0, g1);
;                     f32x4 v0, v1;
; #pragma unroll
;                     for (int j = 0; j < 4; ++j) { v0[j] = sigmoidf_(g0[j]) * acc[ai][bj][m][0][j]; v1[j] = sigmoidf_(g1[j]) * acc[ai][bj][m][1][j]; }
;                     if (MODE == 1) { const u32x4 mw = *(const u32x4*)(rowp + bj * 128); f32x4 m0, m1; unpack8(mw, m0, m1); v0 += m0; v1 += m1; }
;                     *(u32x4*)(rowp + bj * 128) = pack8(v0, v1); }
	v_mov_b64_e32 v[54:55], v[216:217]
	v_mov_b64_e32 v[56:57], v[218:219]
	s_mov_b32 s100, 0xbfb8aa3b
	v_lshlrev_b32_e32 v236, 16, v54
	v_and_b32_e32 v237, 0xffff0000, v54
	v_lshlrev_b32_e32 v238, 16, v56
	v_and_b32_e32 v239, 0xffff0000, v56
	v_lshlrev_b32_e32 v240, 16, v55
	v_and_b32_e32 v241, 0xffff0000, v55
	v_lshlrev_b32_e32 v242, 16, v57
	v_and_b32_e32 v243, 0xffff0000, v57
	v_pk_mul_f32 v[236:237], v[236:237], s[100:101] op_sel_hi:[1,0]
	v_pk_mul_f32 v[238:239], v[238:239], s[100:101] op_sel_hi:[1,0]
	v_pk_mul_f32 v[240:241], v[240:241], s[100:101] op_sel_hi:[1,0]
	v_pk_mul_f32 v[242:243], v[242:243], s[100:101] op_sel_hi:[1,0]
	v_exp_f32_e32 v236, v236
	v_exp_f32_e32 v237, v237
	v_exp_f32_e32 v238, v238
	v_exp_f32_e32 v239, v239
	v_exp_f32_e32 v240, v240
	v_exp_f32_e32 v241, v241
	v_exp_f32_e32 v242, v242
	v_exp_f32_e32 v243, v243
	s_nop 0
	v_pk_add_f32 v[236:237], v[236:237], 1.0 op_sel_hi:[1,0]
	v_pk_add_f32 v[238:239], v[238:239], 1.0 op_sel_hi:[1,0]
	v_pk_add_f32 v[240:241], v[240:241], 1.0 op_sel_hi:[1,0]
	v_pk_add_f32 v[242:243], v[242:243], 1.0 op_sel_hi:[1,0]
	v_rcp_f32_e32 v244, v236
	v_rcp_f32_e32 v245, v237
	v_rcp_f32_e32 v250, v238
	v_rcp_f32_e32 v251, v239
	v_pk_fma_f32 v[246:247], v[236:237], v[244:245], 1.0 op_sel_hi:[1,1,0] neg_lo:[1,0,0] neg_hi:[1,0,0]
	v_pk_fma_f32 v[252:253], v[238:239], v[250:251], 1.0 op_sel_hi:[1,1,0] neg_lo:[1,0,0] neg_hi:[1,0,0]
	v_pk_fma_f32 v[244:245], v[246:247], v[244:245], v[244:245]
	v_pk_fma_f32 v[250:251], v[252:253], v[250:251], v[250:251]
	v_pk_fma_f32 v[246:247], v[236:237], v[244:245], 1.0 op_sel_hi:[1,1,0] neg_lo:[1,0,0] neg_hi:[1,0,0]
	v_pk_fma_f32 v[252:253], v[238:239], v[250:251], 1.0 op_sel_hi:[1,1,0] neg_lo:[1,0,0] neg_hi:[1,0,0]
	v_pk_fma_f32 v[248:249], v[246:247], v[244:245], v[244:245]
	v_pk_fma_f32 v[254:255], v[252:253], v[250:251], v[250:251]
	v_pk_fma_f32 v[246:247], v[236:237], v[248:249], 1.0 op_sel_hi:[1,1,0] neg_lo:[1,0,0] neg_hi:[1,0,0]
	v_pk_fma_f32 v[252:253], v[238:239], v[254:255], 1.0 op_sel_hi:[1,1,0] neg_lo:[1,0,0] neg_hi:[1,0,0]
	v_pk_fma_f32 v[248:249], v[246:247], v[244:245], v[248:249]
	v_pk_fma_f32 v[254:255], v[252:253], v[250:251], v[254:255]
	v_div_fixup_f32 v236, v248, v236, 1.0
	v_div_fixup_f32 v237, v249, v237, 1.0
	v_div_fixup_f32 v238, v254, v238, 1.0
	v_div_fixup_f32 v239, v255, v239, 1.0
	v_rcp_f32_e32 v244, v240
	v_rcp_f32_e32 v245, v241
	v_rcp_f32_e32 v250, v242
	v_rcp_f32_e32 v251, v243
	v_pk_fma_f32 v[246:247], v[240:241], v[244:245], 1.0 op_sel_hi:[1,1,0] neg_lo:[1,0,0] neg_hi:[1,0,0]
	v_pk_fma_f32 v[252:253], v[242:243], v[250:251], 1.0 op_sel_hi:[1,1,0] neg_lo:[1,0,0] neg_hi:[1,0,0]
	v_pk_fma_f32 v[244:245], v[246:247], v[244:245], v[244:245]
	v_pk_fma_f32 v[250:251], v[252:253], v[250:251], v[250:251]
	v_pk_fma_f32 v[246:247], v[240:241], v[244:245], 1.0 op_sel_hi:[1,1,0] neg_lo:[1,0,0] neg_hi:[1,0,0]
	v_pk_fma_f32 v[252:253], v[242:243], v[250:251], 1.0 op_sel_hi:[1,1,0] neg_lo:[1,0,0] neg_hi:[1,0,0]
	v_pk_fma_f32 v[248:249], v[246:247], v[244:245], v[244:245]
	v_pk_fma_f32 v[254:255], v[252:253], v[250:251], v[250:251]
	v_pk_fma_f32 v[246:247], v[240:241], v[248:249], 1.0 op_sel_hi:[1,1,0] neg_lo:[1,0,0] neg_hi:[1,0,0]
	v_pk_fma_f32 v[252:253], v[242:243], v[254:255], 1.0 op_sel_hi:[1,1,0] neg_lo:[1,0,0] neg_hi:[1,0,0]
	v_pk_fma_f32 v[248:249], v[246:247], v[244:245], v[248:249]
	v_pk_fma_f32 v[254:255], v[252:253], v[250:251], v[254:255]
	v_div_fixup_f32 v240, v248, v240, 1.0
	v_div_fixup_f32 v241, v249, v241, 1.0
	v_div_fixup_f32 v242, v254, v242, 1.0
	v_div_fixup_f32 v243, v255, v243, 1.0
	v_mul_f32_e32 v44, v44, v236
	v_mul_f32_e32 v50, v40, v238
	v_mul_f32_e32 v40, v45, v237
	v_mul_f32_e32 v45, v41, v239
	v_mul_f32_e32 v41, v46, v240
	v_mul_f32_e32 v46, v42, v242
	v_mul_f32_e32 v42, v47, v241
	v_mul_f32_e32 v43, v43, v243
	v_cvt_pk_bf16_f32 v40, v44, v40
	v_cvt_pk_bf16_f32 v41, v41, v42
	v_cvt_pk_bf16_f32 v42, v50, v45
	v_cvt_pk_bf16_f32 v43, v46, v43
	s_waitcnt vmcnt(10)
	v_mov_b32_e32 v44, v232
	v_mov_b32_e32 v45, v233
	v_mov_b64_e32 v[46:47], v[234:235]
	s_mov_b32 s100, 0xbfb8aa3b
	v_lshlrev_b32_e32 v236, 16, v44
	v_and_b32_e32 v237, 0xffff0000, v44
	v_lshlrev_b32_e32 v238, 16, v46
	v_and_b32_e32 v239, 0xffff0000, v46
	v_lshlrev_b32_e32 v240, 16, v45
	v_and_b32_e32 v241, 0xffff0000, v45
	v_lshlrev_b32_e32 v242, 16, v47
	v_and_b32_e32 v243, 0xffff0000, v47
	v_pk_mul_f32 v[236:237], v[236:237], s[100:101] op_sel_hi:[1,0]
	v_pk_mul_f32 v[238:239], v[238:239], s[100:101] op_sel_hi:[1,0]
	v_pk_mul_f32 v[240:241], v[240:241], s[100:101] op_sel_hi:[1,0]
	v_pk_mul_f32 v[242:243], v[242:243], s[100:101] op_sel_hi:[1,0]
	v_exp_f32_e32 v236, v236
	v_exp_f32_e32 v237, v237
	v_exp_f32_e32 v238, v238
	v_exp_f32_e32 v239, v239
	v_exp_f32_e32 v240, v240
	v_exp_f32_e32 v241, v241
	v_exp_f32_e32 v242, v242
	v_exp_f32_e32 v243, v243
	s_nop 0
	v_pk_add_f32 v[236:237], v[236:237], 1.0 op_sel_hi:[1,0]
	v_pk_add_f32 v[238:239], v[238:239], 1.0 op_sel_hi:[1,0]
	v_pk_add_f32 v[240:241], v[240:241], 1.0 op_sel_hi:[1,0]
	v_pk_add_f32 v[242:243], v[242:243], 1.0 op_sel_hi:[1,0]
	v_rcp_f32_e32 v244, v236
	v_rcp_f32_e32 v245, v237
	v_rcp_f32_e32 v250, v238
	v_rcp_f32_e32 v251, v239
	v_pk_fma_f32 v[246:247], v[236:237], v[244:245], 1.0 op_sel_hi:[1,1,0] neg_lo:[1,0,0] neg_hi:[1,0,0]
	v_pk_fma_f32 v[252:253], v[238:239], v[250:251], 1.0 op_sel_hi:[1,1,0] neg_lo:[1,0,0] neg_hi:[1,0,0]
	v_pk_fma_f32 v[244:245], v[246:247], v[244:245], v[244:245]
	v_pk_fma_f32 v[250:251], v[252:253], v[250:251], v[250:251]
	v_pk_fma_f32 v[246:247], v[236:237], v[244:245], 1.0 op_sel_hi:[1,1,0] neg_lo:[1,0,0] neg_hi:[1,0,0]
; __device__ __forceinline__ float sigmoidf_(float x) { return 1.0f / (1.0f + __expf(-x)); }
; __device__ __forceinline__ u32x4 pack8(const f32x4 v0, const f32x4 v1) { u32x4 w; w.x = pk2(v0[0], v0[1]); w.y = pk2(v0[2], v0[3]); w.z = pk2(v1[0], v1[1]); w.w = pk2(v1[2], v1[3]); return w; }
; __device__ __forceinline__ void unpack8(const u32x4 w, f32x4& v0, f32x4& v1) { v0 = (f32x4){bflo(w.x), bfhi(w.x), bflo(w.y), bfhi(w.y)}; v1 = (f32x4){bflo(w.z), bfhi(w.z), bflo(w.w), bfhi(w.w)}; }
;     __device__ __forceinline__ void operator()(const f32x4 (&acc)[2][2][4][2], const Unit& u, int wr, int wc, int fr, int fq) const {
;     ...
;         for (int ai = 0; ai < 2; ++ai)
; #pragma unroll
;             for (int m = 0; m < 4; ++m) {
;                 bf16_t* rowp = z + (size_t)(row0 + ai * 128 + m * 16) * DIN + col0;
; #pragma unroll
;                 for (int bj = 0; bj < 2; ++bj) {
;                     const u32x4 gw = *(const u32x4*)(rowp + (MODE == 0 ? O_GB : O_GA) + bj * 128);
;                     f32x4 g0, g1; unpack8(gw, g0, g1);
;                     f32x4 v0, v1;
; #pragma unroll
;                     for (int j = 0; j < 4; ++j) { v0[j] = sigmoidf_(g0[j]) * acc[ai][bj][m][0][j]; v1[j] = sigmoidf_(g1[j]) * acc[ai][bj][m][1][j]; }
;                     if (MODE == 1) { const u32x4 mw = *(const u32x4*)(rowp + bj * 128); f32x4 m0, m1; unpack8(mw, m0, m1); v0 += m0; v1 += m1; }
;                     *(u32x4*)(rowp + bj * 128) = pack8(v0, v1); }
	v_pk_fma_f32 v[252:253], v[238:239], v[250:251], 1.0 op_sel_hi:[1,1,0] neg_lo:[1,0,0] neg_hi:[1,0,0]
	v_pk_fma_f32 v[248:249], v[246:247], v[244:245], v[244:245]
	v_pk_fma_f32 v[254:255], v[252:253], v[250:251], v[250:251]
	v_pk_fma_f32 v[246:247], v[236:237], v[248:249], 1.0 op_sel_hi:[1,1,0] neg_lo:[1,0,0] neg_hi:[1,0,0]
	v_pk_fma_f32 v[252:253], v[238:239], v[254:255], 1.0 op_sel_hi:[1,1,0] neg_lo:[1,0,0] neg_hi:[1,0,0]
	v_pk_fma_f32 v[248:249], v[246:247], v[244:245], v[248:249]
	v_pk_fma_f32 v[254:255], v[252:253], v[250:251], v[254:255]
	v_div_fixup_f32 v236, v248, v236, 1.0
	v_div_fixup_f32 v237, v249, v237, 1.0
	v_div_fixup_f32 v238, v254, v238, 1.0
	v_div_fixup_f32 v239, v255, v239, 1.0
	v_rcp_f32_e32 v244, v240
	v_rcp_f32_e32 v245, v241
	v_rcp_f32_e32 v250, v242
	v_rcp_f32_e32 v251, v243
	v_pk_fma_f32 v[246:247], v[240:241], v[244:245], 1.0 op_sel_hi:[1,1,0] neg_lo:[1,0,0] neg_hi:[1,0,0]
	v_pk_fma_f32 v[252:253], v[242:243], v[250:251], 1.0 op_sel_hi:[1,1,0] neg_lo:[1,0,0] neg_hi:[1,0,0]
	v_pk_fma_f32 v[244:245], v[246:247], v[244:245], v[244:245]
	v_pk_fma_f32 v[250:251], v[252:253], v[250:251], v[250:251]
	v_pk_fma_f32 v[246:247], v[240:241], v[244:245], 1.0 op_sel_hi:[1,1,0] neg_lo:[1,0,0] neg_hi:[1,0,0]
	v_pk_fma_f32 v[252:253], v[242:243], v[250:251], 1.0 op_sel_hi:[1,1,0] neg_lo:[1,0,0] neg_hi:[1,0,0]
	v_pk_fma_f32 v[248:249], v[246:247], v[244:245], v[244:245]
	v_pk_fma_f32 v[254:255], v[252:253], v[250:251], v[250:251]
	v_pk_fma_f32 v[246:247], v[240:241], v[248:249], 1.0 op_sel_hi:[1,1,0] neg_lo:[1,0,0] neg_hi:[1,0,0]
	v_pk_fma_f32 v[252:253], v[242:243], v[254:255], 1.0 op_sel_hi:[1,1,0] neg_lo:[1,0,0] neg_hi:[1,0,0]
	v_pk_fma_f32 v[248:249], v[246:247], v[244:245], v[248:249]
	v_pk_fma_f32 v[254:255], v[252:253], v[250:251], v[254:255]
	v_div_fixup_f32 v240, v248, v240, 1.0
	v_div_fixup_f32 v241, v249, v241, 1.0
	v_div_fixup_f32 v242, v254, v242, 1.0
	v_div_fixup_f32 v243, v255, v243, 1.0
	global_store_dwordx4 v[48:49], v[40:43], off
	s_nop 0
	v_pk_mul_f32 v[36:37], v[36:37], v[236:237]
	v_pk_mul_f32 v[32:33], v[32:33], v[238:239]
	v_pk_mul_f32 v[38:39], v[38:39], v[240:241]
	v_pk_mul_f32 v[40:41], v[34:35], v[242:243]
	v_cvt_pk_bf16_f32 v34, v36, v37
	v_cvt_pk_bf16_f32 v35, v38, v39
	v_cvt_pk_bf16_f32 v36, v32, v33
	v_add_u32_e32 v32, 0xa0, v160
	v_mad_i64_i32 v[32:33], s[6:7], v32, s57, v[146:147]
	v_lshl_add_u64 v[32:33], v[32:33], 0, v[148:149]
	v_add_co_u32_e32 v42, vcc, s58, v32
	v_cvt_pk_bf16_f32 v37, v40, v41
	global_store_dwordx4 v[48:49], v[34:37], off offset:256
	s_nop 0
	v_addc_co_u32_e32 v43, vcc, 0, v33, vcc
	s_waitcnt vmcnt(9)
	v_mov_b64_e32 v[38:39], v[200:201]
	v_mov_b64_e32 v[40:41], v[202:203]
	s_mov_b32 s100, 0xbfb8aa3b
	v_lshlrev_b32_e32 v236, 16, v38
	v_and_b32_e32 v237, 0xffff0000, v38
	v_lshlrev_b32_e32 v238, 16, v40
	v_and_b32_e32 v239, 0xffff0000, v40
	v_lshlrev_b32_e32 v240, 16, v39
	v_and_b32_e32 v241, 0xffff0000, v39
	v_lshlrev_b32_e32 v242, 16, v41
	v_and_b32_e32 v243, 0xffff0000, v41
	v_pk_mul_f32 v[236:237], v[236:237], s[100:101] op_sel_hi:[1,0]
	v_pk_mul_f32 v[238:239], v[238:239], s[100:101] op_sel_hi:[1,0]
	v_pk_mul_f32 v[240:241], v[240:241], s[100:101] op_sel_hi:[1,0]
	v_pk_mul_f32 v[242:243], v[242:243], s[100:101] op_sel_hi:[1,0]
	v_exp_f32_e32 v236, v236
	v_exp_f32_e32 v237, v237
	v_exp_f32_e32 v238, v238
	v_exp_f32_e32 v239, v239
	v_exp_f32_e32 v240, v240
	v_exp_f32_e32 v241, v241
	v_exp_f32_e32 v242, v242
	v_exp_f32_e32 v243, v243
	s_nop 0
	v_pk_add_f32 v[236:237], v[236:237], 1.0 op_sel_hi:[1,0]
	v_pk_add_f32 v[238:239], v[238:239], 1.0 op_sel_hi:[1,0]
	v_pk_add_f32 v[240:241], v[240:241], 1.0 op_sel_hi:[1,0]
	v_pk_add_f32 v[242:243], v[242:243], 1.0 op_sel_hi:[1,0]
	v_rcp_f32_e32 v244, v236
	v_rcp_f32_e32 v245, v237
	v_rcp_f32_e32 v250, v238
	v_rcp_f32_e32 v251, v239
	v_pk_fma_f32 v[246:247], v[236:237], v[244:245], 1.0 op_sel_hi:[1,1,0] neg_lo:[1,0,0] neg_hi:[1,0,0]
	v_pk_fma_f32 v[252:253], v[238:239], v[250:251], 1.0 op_sel_hi:[1,1,0] neg_lo:[1,0,0] neg_hi:[1,0,0]
	v_pk_fma_f32 v[244:245], v[246:247], v[244:245], v[244:245]
	v_pk_fma_f32 v[250:251], v[252:253], v[250:251], v[250:251]
	v_pk_fma_f32 v[246:247], v[236:237], v[244:245], 1.0 op_sel_hi:[1,1,0] neg_lo:[1,0,0] neg_hi:[1,0,0]
	v_pk_fma_f32 v[252:253], v[238:239], v[250:251], 1.0 op_sel_hi:[1,1,0] neg_lo:[1,0,0] neg_hi:[1,0,0]
	v_pk_fma_f32 v[248:249], v[246:247], v[244:245], v[244:245]
	v_pk_fma_f32 v[254:255], v[252:253], v[250:251], v[250:251]
	v_pk_fma_f32 v[246:247], v[236:237], v[248:249], 1.0 op_sel_hi:[1,1,0] neg_lo:[1,0,0] neg_hi:[1,0,0]
	v_pk_fma_f32 v[252:253], v[238:239], v[254:255], 1.0 op_sel_hi:[1,1,0] neg_lo:[1,0,0] neg_hi:[1,0,0]
	v_pk_fma_f32 v[248:249], v[246:247], v[244:245], v[248:249]
	v_pk_fma_f32 v[254:255], v[252:253], v[250:251], v[254:255]
	v_div_fixup_f32 v236, v248, v236, 1.0
	v_div_fixup_f32 v237, v249, v237, 1.0
	v_div_fixup_f32 v238, v254, v238, 1.0
	v_div_fixup_f32 v239, v255, v239, 1.0
	v_rcp_f32_e32 v244, v240
	v_rcp_f32_e32 v245, v241
	v_rcp_f32_e32 v250, v242
	v_rcp_f32_e32 v251, v243
	v_pk_fma_f32 v[246:247], v[240:241], v[244:245], 1.0 op_sel_hi:[1,1,0] neg_lo:[1,0,0] neg_hi:[1,0,0]
	v_pk_fma_f32 v[252:253], v[242:243], v[250:251], 1.0 op_sel_hi:[1,1,0] neg_lo:[1,0,0] neg_hi:[1,0,0]
	v_pk_fma_f32 v[244:245], v[246:247], v[244:245], v[244:245]
	v_pk_fma_f32 v[250:251], v[252:253], v[250:251], v[250:251]
	v_pk_fma_f32 v[246:247], v[240:241], v[244:245], 1.0 op_sel_hi:[1,1,0] neg_lo:[1,0,0] neg_hi:[1,0,0]
	v_pk_fma_f32 v[252:253], v[242:243], v[250:251], 1.0 op_sel_hi:[1,1,0] neg_lo:[1,0,0] neg_hi:[1,0,0]
	v_pk_fma_f32 v[248:249], v[246:247], v[244:245], v[244:245]
	v_pk_fma_f32 v[254:255], v[252:253], v[250:251], v[250:251]
	v_pk_fma_f32 v[246:247], v[240:241], v[248:249], 1.0 op_sel_hi:[1,1,0] neg_lo:[1,0,0] neg_hi:[1,0,0]
	v_pk_fma_f32 v[252:253], v[242:243], v[254:255], 1.0 op_sel_hi:[1,1,0] neg_lo:[1,0,0] neg_hi:[1,0,0]
	v_pk_fma_f32 v[248:249], v[246:247], v[244:245], v[248:249]
	v_pk_fma_f32 v[254:255], v[252:253], v[250:251], v[254:255]
	v_div_fixup_f32 v240, v248, v240, 1.0
	v_div_fixup_f32 v241, v249, v241, 1.0
	v_div_fixup_f32 v242, v254, v242, 1.0
	v_div_fixup_f32 v243, v255, v243, 1.0
	v_mul_f32_e32 v28, v28, v236
	v_mul_f32_e32 v34, v24, v238
	v_mul_f32_e32 v24, v29, v237
	v_mul_f32_e32 v29, v25, v239
	v_mul_f32_e32 v25, v30, v240
	v_mul_f32_e32 v30, v26, v242
	v_mul_f32_e32 v26, v31, v241
	v_mul_f32_e32 v27, v27, v243
	v_cvt_pk_bf16_f32 v24, v28, v24
	v_cvt_pk_bf16_f32 v25, v25, v26
	v_cvt_pk_bf16_f32 v26, v34, v29
	v_cvt_pk_bf16_f32 v27, v30, v27
	s_waitcnt vmcnt(8)
; __device__ __forceinline__ float sigmoidf_(float x) { return 1.0f / (1.0f + __expf(-x)); }
; __device__ __forceinline__ u32x4 pack8(const f32x4 v0, const f32x4 v1) { u32x4 w; w.x = pk2(v0[0], v0[1]); w.y = pk2(v0[2], v0[3]); w.z = pk2(v1[0], v1[1]); w.w = pk2(v1[2], v1[3]); return w; }
; __device__ __forceinline__ void unpack8(const u32x4 w, f32x4& v0, f32x4& v1) { v0 = (f32x4){bflo(w.x), bfhi(w.x), bflo(w.y), bfhi(w.y)}; v1 = (f32x4){bflo(w.z), bfhi(w.z), bflo(w.w), bfhi(w.w)}; }
;     __device__ __forceinline__ void operator()(const f32x4 (&acc)[2][2][4][2], const Unit& u, int wr, int wc, int fr, int fq) const {
;     ...
;         for (int ai = 0; ai < 2; ++ai)
; #pragma unroll
;             for (int m = 0; m < 4; ++m) {
;                 bf16_t* rowp = z + (size_t)(row0 + ai * 128 + m * 16) * DIN + col0;
; #pragma unroll
;                 for (int bj = 0; bj < 2; ++bj) {
;                     const u32x4 gw = *(const u32x4*)(rowp + (MODE == 0 ? O_GB : O_GA) + bj * 128);
;                     f32x4 g0, g1; unpack8(gw, g0, g1);
;                     f32x4 v0, v1;
; #pragma unroll
;                     for (int j = 0; j < 4; ++j) { v0[j] = sigmoidf_(g0[j]) * acc[ai][bj][m][0][j]; v1[j] = sigmoidf_(g1[j]) * acc[ai][bj][m][1][j]; }
;                     if (MODE == 1) { const u32x4 mw = *(const u32x4*)(rowp + bj * 128); f32x4 m0, m1; unpack8(mw, m0, m1); v0 += m0; v1 += m1; }
;                     *(u32x4*)(rowp + bj * 128) = pack8(v0, v1); }
	v_mov_b32_e32 v28, v204
	v_mov_b32_e32 v29, v205
	v_mov_b64_e32 v[30:31], v[206:207]
	s_mov_b32 s100, 0xbfb8aa3b
	v_lshlrev_b32_e32 v236, 16, v28
	v_and_b32_e32 v237, 0xffff0000, v28
	v_lshlrev_b32_e32 v238, 16, v30
	v_and_b32_e32 v239, 0xffff0000, v30
	v_lshlrev_b32_e32 v240, 16, v29
	v_and_b32_e32 v241, 0xffff0000, v29
	v_lshlrev_b32_e32 v242, 16, v31
	v_and_b32_e32 v243, 0xffff0000, v31
	v_pk_mul_f32 v[236:237], v[236:237], s[100:101] op_sel_hi:[1,0]
	v_pk_mul_f32 v[238:239], v[238:239], s[100:101] op_sel_hi:[1,0]
	v_pk_mul_f32 v[240:241], v[240:241], s[100:101] op_sel_hi:[1,0]
	v_pk_mul_f32 v[242:243], v[242:243], s[100:101] op_sel_hi:[1,0]
	v_exp_f32_e32 v236, v236
	v_exp_f32_e32 v237, v237
	v_exp_f32_e32 v238, v238
	v_exp_f32_e32 v239, v239
	v_exp_f32_e32 v240, v240
	v_exp_f32_e32 v241, v241
	v_exp_f32_e32 v242, v242
	v_exp_f32_e32 v243, v243
	s_nop 0
	v_pk_add_f32 v[236:237], v[236:237], 1.0 op_sel_hi:[1,0]
	v_pk_add_f32 v[238:239], v[238:239], 1.0 op_sel_hi:[1,0]
	v_pk_add_f32 v[240:241], v[240:241], 1.0 op_sel_hi:[1,0]
	v_pk_add_f32 v[242:243], v[242:243], 1.0 op_sel_hi:[1,0]
	v_rcp_f32_e32 v244, v236
	v_rcp_f32_e32 v245, v237
	v_rcp_f32_e32 v250, v238
	v_rcp_f32_e32 v251, v239
	v_pk_fma_f32 v[246:247], v[236:237], v[244:245], 1.0 op_sel_hi:[1,1,0] neg_lo:[1,0,0] neg_hi:[1,0,0]
	v_pk_fma_f32 v[252:253], v[238:239], v[250:251], 1.0 op_sel_hi:[1,1,0] neg_lo:[1,0,0] neg_hi:[1,0,0]
	v_pk_fma_f32 v[244:245], v[246:247], v[244:245], v[244:245]
	v_pk_fma_f32 v[250:251], v[252:253], v[250:251], v[250:251]
	v_pk_fma_f32 v[246:247], v[236:237], v[244:245], 1.0 op_sel_hi:[1,1,0] neg_lo:[1,0,0] neg_hi:[1,0,0]
	v_pk_fma_f32 v[252:253], v[238:239], v[250:251], 1.0 op_sel_hi:[1,1,0] neg_lo:[1,0,0] neg_hi:[1,0,0]
	v_pk_fma_f32 v[248:249], v[246:247], v[244:245], v[244:245]
	v_pk_fma_f32 v[254:255], v[252:253], v[250:251], v[250:251]
	v_pk_fma_f32 v[246:247], v[236:237], v[248:249], 1.0 op_sel_hi:[1,1,0] neg_lo:[1,0,0] neg_hi:[1,0,0]
	v_pk_fma_f32 v[252:253], v[238:239], v[254:255], 1.0 op_sel_hi:[1,1,0] neg_lo:[1,0,0] neg_hi:[1,0,0]
	v_pk_fma_f32 v[248:249], v[246:247], v[244:245], v[248:249]
	v_pk_fma_f32 v[254:255], v[252:253], v[250:251], v[254:255]
	v_div_fixup_f32 v236, v248, v236, 1.0
	v_div_fixup_f32 v237, v249, v237, 1.0
	v_div_fixup_f32 v238, v254, v238, 1.0
	v_div_fixup_f32 v239, v255, v239, 1.0
	v_rcp_f32_e32 v244, v240
	v_rcp_f32_e32 v245, v241
	v_rcp_f32_e32 v250, v242
	v_rcp_f32_e32 v251, v243
	v_pk_fma_f32 v[246:247], v[240:241], v[244:245], 1.0 op_sel_hi:[1,1,0] neg_lo:[1,0,0] neg_hi:[1,0,0]
	v_pk_fma_f32 v[252:253], v[242:243], v[250:251], 1.0 op_sel_hi:[1,1,0] neg_lo:[1,0,0] neg_hi:[1,0,0]
	v_pk_fma_f32 v[244:245], v[246:247], v[244:245], v[244:245]
	v_pk_fma_f32 v[250:251], v[252:253], v[250:251], v[250:251]
	v_pk_fma_f32 v[246:247], v[240:241], v[244:245], 1.0 op_sel_hi:[1,1,0] neg_lo:[1,0,0] neg_hi:[1,0,0]
	v_pk_fma_f32 v[252:253], v[242:243], v[250:251], 1.0 op_sel_hi:[1,1,0] neg_lo:[1,0,0] neg_hi:[1,0,0]
	v_pk_fma_f32 v[248:249], v[246:247], v[244:245], v[244:245]
	v_pk_fma_f32 v[254:255], v[252:253], v[250:251], v[250:251]
	v_pk_fma_f32 v[246:247], v[240:241], v[248:249], 1.0 op_sel_hi:[1,1,0] neg_lo:[1,0,0] neg_hi:[1,0,0]
	v_pk_fma_f32 v[252:253], v[242:243], v[254:255], 1.0 op_sel_hi:[1,1,0] neg_lo:[1,0,0] neg_hi:[1,0,0]
	v_pk_fma_f32 v[248:249], v[246:247], v[244:245], v[248:249]
	v_pk_fma_f32 v[254:255], v[252:253], v[250:251], v[254:255]
	v_div_fixup_f32 v240, v248, v240, 1.0
	v_div_fixup_f32 v241, v249, v241, 1.0
	v_div_fixup_f32 v242, v254, v242, 1.0
	v_div_fixup_f32 v243, v255, v243, 1.0
	global_store_dwordx4 v[32:33], v[24:27], off
	s_nop 0
	v_pk_mul_f32 v[20:21], v[20:21], v[236:237]
	v_pk_mul_f32 v[16:17], v[16:17], v[238:239]
	v_pk_mul_f32 v[22:23], v[22:23], v[240:241]
	v_pk_mul_f32 v[24:25], v[18:19], v[242:243]
	v_cvt_pk_bf16_f32 v18, v20, v21
	v_cvt_pk_bf16_f32 v19, v22, v23
	v_cvt_pk_bf16_f32 v20, v16, v17
	v_add_u32_e32 v16, 0xb0, v160
	v_mad_i64_i32 v[16:17], s[6:7], v16, s57, v[146:147]
	v_lshl_add_u64 v[16:17], v[16:17], 0, v[148:149]
	v_add_co_u32_e32 v26, vcc, s58, v16
	v_cvt_pk_bf16_f32 v21, v24, v25
	global_store_dwordx4 v[32:33], v[18:21], off offset:256
	s_nop 0
	v_addc_co_u32_e32 v27, vcc, 0, v17, vcc
	s_waitcnt vmcnt(7)
; __device__ __forceinline__ float sigmoidf_(float x) { return 1.0f / (1.0f + __expf(-x)); }
; __device__ __forceinline__ u32x4 pack8(const f32x4 v0, const f32x4 v1) { u32x4 w; w.x = pk2(v0[0], v0[1]); w.y = pk2(v0[2], v0[3]); w.z = pk2(v1[0], v1[1]); w.w = pk2(v1[2], v1[3]); return w; }
; __device__ __forceinline__ void unpack8(const u32x4 w, f32x4& v0, f32x4& v1) { v0 = (f32x4){bflo(w.x), bfhi(w.x), bflo(w.y), bfhi(w.y)}; v1 = (f32x4){bflo(w.z), bfhi(w.z), bflo(w.w), bfhi(w.w)}; }
;     __device__ __forceinline__ void operator()(const f32x4 (&acc)[2][2][4][2], const Unit& u, int wr, int wc, int fr, int fq) const {
;     ...
;         for (int ai = 0; ai < 2; ++ai)
; #pragma unroll
;             for (int m = 0; m < 4; ++m) {
;                 bf16_t* rowp = z + (size_t)(row0 + ai * 128 + m * 16) * DIN + col0;
; #pragma unroll
;                 for (int bj = 0; bj < 2; ++bj) {
;                     const u32x4 gw = *(const u32x4*)(rowp + (MODE == 0 ? O_GB : O_GA) + bj * 128);
;                     f32x4 g0, g1; unpack8(gw, g0, g1);
;                     f32x4 v0, v1;
; #pragma unroll
;                     for (int j = 0; j < 4; ++j) { v0[j] = sigmoidf_(g0[j]) * acc[ai][bj][m][0][j]; v1[j] = sigmoidf_(g1[j]) * acc[ai][bj][m][1][j]; }
;                     if (MODE == 1) { const u32x4 mw = *(const u32x4*)(rowp + bj * 128); f32x4 m0, m1; unpack8(mw, m0, m1); v0 += m0; v1 += m1; }
;                     *(u32x4*)(rowp + bj * 128) = pack8(v0, v1); }
	v_mov_b64_e32 v[22:23], v[208:209]
	v_mov_b64_e32 v[24:25], v[210:211]
	s_mov_b32 s100, 0xbfb8aa3b
	v_lshlrev_b32_e32 v236, 16, v22
	v_and_b32_e32 v237, 0xffff0000, v22
	v_lshlrev_b32_e32 v238, 16, v24
	v_and_b32_e32 v239, 0xffff0000, v24
	v_lshlrev_b32_e32 v240, 16, v23
	v_and_b32_e32 v241, 0xffff0000, v23
	v_lshlrev_b32_e32 v242, 16, v25
	v_and_b32_e32 v243, 0xffff0000, v25
	v_pk_mul_f32 v[236:237], v[236:237], s[100:101] op_sel_hi:[1,0]
	v_pk_mul_f32 v[238:239], v[238:239], s[100:101] op_sel_hi:[1,0]
	v_pk_mul_f32 v[240:241], v[240:241], s[100:101] op_sel_hi:[1,0]
	v_pk_mul_f32 v[242:243], v[242:243], s[100:101] op_sel_hi:[1,0]
	v_exp_f32_e32 v236, v236
	v_exp_f32_e32 v237, v237
	v_exp_f32_e32 v238, v238
	v_exp_f32_e32 v239, v239
	v_exp_f32_e32 v240, v240
	v_exp_f32_e32 v241, v241
	v_exp_f32_e32 v242, v242
	v_exp_f32_e32 v243, v243
	s_nop 0
	v_pk_add_f32 v[236:237], v[236:237], 1.0 op_sel_hi:[1,0]
	v_pk_add_f32 v[238:239], v[238:239], 1.0 op_sel_hi:[1,0]
	v_pk_add_f32 v[240:241], v[240:241], 1.0 op_sel_hi:[1,0]
	v_pk_add_f32 v[242:243], v[242:243], 1.0 op_sel_hi:[1,0]
	v_rcp_f32_e32 v244, v236
	v_rcp_f32_e32 v245, v237
	v_rcp_f32_e32 v250, v238
	v_rcp_f32_e32 v251, v239
	v_pk_fma_f32 v[246:247], v[236:237], v[244:245], 1.0 op_sel_hi:[1,1,0] neg_lo:[1,0,0] neg_hi:[1,0,0]
	v_pk_fma_f32 v[252:253], v[238:239], v[250:251], 1.0 op_sel_hi:[1,1,0] neg_lo:[1,0,0] neg_hi:[1,0,0]
	v_pk_fma_f32 v[244:245], v[246:247], v[244:245], v[244:245]
	v_pk_fma_f32 v[250:251], v[252:253], v[250:251], v[250:251]
	v_pk_fma_f32 v[246:247], v[236:237], v[244:245], 1.0 op_sel_hi:[1,1,0] neg_lo:[1,0,0] neg_hi:[1,0,0]
	v_pk_fma_f32 v[252:253], v[238:239], v[250:251], 1.0 op_sel_hi:[1,1,0] neg_lo:[1,0,0] neg_hi:[1,0,0]
	v_pk_fma_f32 v[248:249], v[246:247], v[244:245], v[244:245]
	v_pk_fma_f32 v[254:255], v[252:253], v[250:251], v[250:251]
	v_pk_fma_f32 v[246:247], v[236:237], v[248:249], 1.0 op_sel_hi:[1,1,0] neg_lo:[1,0,0] neg_hi:[1,0,0]
	v_pk_fma_f32 v[252:253], v[238:239], v[254:255], 1.0 op_sel_hi:[1,1,0] neg_lo:[1,0,0] neg_hi:[1,0,0]
	v_pk_fma_f32 v[248:249], v[246:247], v[244:245], v[248:249]
	v_pk_fma_f32 v[254:255], v[252:253], v[250:251], v[254:255]
	v_div_fixup_f32 v236, v248, v236, 1.0
	v_div_fixup_f32 v237, v249, v237, 1.0
	v_div_fixup_f32 v238, v254, v238, 1.0
	v_div_fixup_f32 v239, v255, v239, 1.0
	v_rcp_f32_e32 v244, v240
	v_rcp_f32_e32 v245, v241
	v_rcp_f32_e32 v250, v242
	v_rcp_f32_e32 v251, v243
	v_pk_fma_f32 v[246:247], v[240:241], v[244:245], 1.0 op_sel_hi:[1,1,0] neg_lo:[1,0,0] neg_hi:[1,0,0]
	v_pk_fma_f32 v[252:253], v[242:243], v[250:251], 1.0 op_sel_hi:[1,1,0] neg_lo:[1,0,0] neg_hi:[1,0,0]
	v_pk_fma_f32 v[244:245], v[246:247], v[244:245], v[244:245]
	v_pk_fma_f32 v[250:251], v[252:253], v[250:251], v[250:251]
	v_pk_fma_f32 v[246:247], v[240:241], v[244:245], 1.0 op_sel_hi:[1,1,0] neg_lo:[1,0,0] neg_hi:[1,0,0]
	v_pk_fma_f32 v[252:253], v[242:243], v[250:251], 1.0 op_sel_hi:[1,1,0] neg_lo:[1,0,0] neg_hi:[1,0,0]
	v_pk_fma_f32 v[248:249], v[246:247], v[244:245], v[244:245]
	v_pk_fma_f32 v[254:255], v[252:253], v[250:251], v[250:251]
	v_pk_fma_f32 v[246:247], v[240:241], v[248:249], 1.0 op_sel_hi:[1,1,0] neg_lo:[1,0,0] neg_hi:[1,0,0]
	v_pk_fma_f32 v[252:253], v[242:243], v[254:255], 1.0 op_sel_hi:[1,1,0] neg_lo:[1,0,0] neg_hi:[1,0,0]
	v_pk_fma_f32 v[248:249], v[246:247], v[244:245], v[248:249]
	v_pk_fma_f32 v[254:255], v[252:253], v[250:251], v[254:255]
	v_div_fixup_f32 v240, v248, v240, 1.0
	v_div_fixup_f32 v241, v249, v241, 1.0
	v_div_fixup_f32 v242, v254, v242, 1.0
	v_div_fixup_f32 v243, v255, v243, 1.0
	v_mul_f32_e32 v12, v12, v236
	v_mul_f32_e32 v18, v8, v238
	v_mul_f32_e32 v8, v13, v237
	v_mul_f32_e32 v13, v9, v239
	v_mul_f32_e32 v9, v14, v240
	v_mul_f32_e32 v14, v10, v242
	v_mul_f32_e32 v10, v15, v241
	v_mul_f32_e32 v11, v11, v243
	v_cvt_pk_bf16_f32 v8, v12, v8
	v_cvt_pk_bf16_f32 v9, v9, v10
	v_cvt_pk_bf16_f32 v10, v18, v13
	v_cvt_pk_bf16_f32 v11, v14, v11
	s_waitcnt vmcnt(6)
; __device__ __forceinline__ float sigmoidf_(float x) { return 1.0f / (1.0f + __expf(-x)); }
; #define PG8_WAIT_V(n) asm volatile("s_waitcnt vmcnt(" #n ")" ::: "memory")
; #define PG8_BAR __builtin_amdgcn_s_barrier()
; __device__ __forceinline__ u32x4 pack8(const f32x4 v0, const f32x4 v1) { u32x4 w; w.x = pk2(v0[0], v0[1]); w.y = pk2(v0[2], v0[3]); w.z = pk2(v1[0], v1[1]); w.w = pk2(v1[2], v1[3]); return w; }
; __device__ __forceinline__ void unpack8(const u32x4 w, f32x4& v0, f32x4& v1) { v0 = (f32x4){bflo(w.x), bfhi(w.x), bflo(w.y), bfhi(w.y)}; v1 = (f32x4){bflo(w.z), bfhi(w.z), bflo(w.w), bfhi(w.w)}; }
;     ...
;         if (!has_next) break;
; #pragma unroll
;         for (int a = 0; a < 2; ++a)
; #pragma unroll
;             for (int b = 0; b < 2; ++b)
; #pragma unroll
;                 for (int m = 0; m < 4; ++m)
; #pragma unroll
;                     for (int n = 0; n < 2; ++n) acc[a][b][m][n] = (f32x4){0.f, 0.f, 0.f, 0.f};
;         cur = nxt; cA = nA; cB = nB; ++ui;
;     }
;     PG8_WAIT_V(0);
;     if (wr == 0) PG8_BAR;
;     PG8_BAR;
;     __device__ __forceinline__ void operator()(const f32x4 (&acc)[2][2][4][2], const Unit& u, int wr, int wc, int fr, int fq) const {
;     ...
;         for (int ai = 0; ai < 2; ++ai)
; #pragma unroll
;             for (int m = 0; m < 4; ++m) {
;                 bf16_t* rowp = z + (size_t)(row0 + ai * 128 + m * 16) * DIN + col0;
; #pragma unroll
;                 for (int bj = 0; bj < 2; ++bj) {
;                     const u32x4 gw = *(const u32x4*)(rowp + (MODE == 0 ? O_GB : O_GA) + bj * 128);
;                     f32x4 g0, g1; unpack8(gw, g0, g1);
;                     f32x4 v0, v1;
; #pragma unroll
;                     for (int j = 0; j < 4; ++j) { v0[j] = sigmoidf_(g0[j]) * acc[ai][bj][m][0][j]; v1[j] = sigmoidf_(g1[j]) * acc[ai][bj][m][1][j]; }
;                     if (MODE == 1) { const u32x4 mw = *(const u32x4*)(rowp + bj * 128); f32x4 m0, m1; unpack8(mw, m0, m1); v0 += m0; v1 += m1; }
;                     *(u32x4*)(rowp + bj * 128) = pack8(v0, v1); }
	v_mov_b32_e32 v12, v212
	v_mov_b32_e32 v13, v213
	v_mov_b64_e32 v[14:15], v[214:215]
	s_mov_b32 s100, 0xbfb8aa3b
	v_lshlrev_b32_e32 v236, 16, v12
	v_and_b32_e32 v237, 0xffff0000, v12
	v_lshlrev_b32_e32 v238, 16, v14
	v_and_b32_e32 v239, 0xffff0000, v14
	v_lshlrev_b32_e32 v240, 16, v13
	v_and_b32_e32 v241, 0xffff0000, v13
	v_lshlrev_b32_e32 v242, 16, v15
	v_and_b32_e32 v243, 0xffff0000, v15
	v_pk_mul_f32 v[236:237], v[236:237], s[100:101] op_sel_hi:[1,0]
	v_pk_mul_f32 v[238:239], v[238:239], s[100:101] op_sel_hi:[1,0]
	v_pk_mul_f32 v[240:241], v[240:241], s[100:101] op_sel_hi:[1,0]
	v_pk_mul_f32 v[242:243], v[242:243], s[100:101] op_sel_hi:[1,0]
	v_exp_f32_e32 v236, v236
	v_exp_f32_e32 v237, v237
	v_exp_f32_e32 v238, v238
	v_exp_f32_e32 v239, v239
	v_exp_f32_e32 v240, v240
	v_exp_f32_e32 v241, v241
	v_exp_f32_e32 v242, v242
	v_exp_f32_e32 v243, v243
	s_nop 0
	v_pk_add_f32 v[236:237], v[236:237], 1.0 op_sel_hi:[1,0]
	v_pk_add_f32 v[238:239], v[238:239], 1.0 op_sel_hi:[1,0]
	v_pk_add_f32 v[240:241], v[240:241], 1.0 op_sel_hi:[1,0]
	v_pk_add_f32 v[242:243], v[242:243], 1.0 op_sel_hi:[1,0]
	v_rcp_f32_e32 v244, v236
	v_rcp_f32_e32 v245, v237
	v_rcp_f32_e32 v250, v238
	v_rcp_f32_e32 v251, v239
	v_pk_fma_f32 v[246:247], v[236:237], v[244:245], 1.0 op_sel_hi:[1,1,0] neg_lo:[1,0,0] neg_hi:[1,0,0]
	v_pk_fma_f32 v[252:253], v[238:239], v[250:251], 1.0 op_sel_hi:[1,1,0] neg_lo:[1,0,0] neg_hi:[1,0,0]
	v_pk_fma_f32 v[244:245], v[246:247], v[244:245], v[244:245]
	v_pk_fma_f32 v[250:251], v[252:253], v[250:251], v[250:251]
	v_pk_fma_f32 v[246:247], v[236:237], v[244:245], 1.0 op_sel_hi:[1,1,0] neg_lo:[1,0,0] neg_hi:[1,0,0]
	v_pk_fma_f32 v[252:253], v[238:239], v[250:251], 1.0 op_sel_hi:[1,1,0] neg_lo:[1,0,0] neg_hi:[1,0,0]
	v_pk_fma_f32 v[248:249], v[246:247], v[244:245], v[244:245]
	v_pk_fma_f32 v[254:255], v[252:253], v[250:251], v[250:251]
	v_pk_fma_f32 v[246:247], v[236:237], v[248:249], 1.0 op_sel_hi:[1,1,0] neg_lo:[1,0,0] neg_hi:[1,0,0]
	v_pk_fma_f32 v[252:253], v[238:239], v[254:255], 1.0 op_sel_hi:[1,1,0] neg_lo:[1,0,0] neg_hi:[1,0,0]
	v_pk_fma_f32 v[248:249], v[246:247], v[244:245], v[248:249]
	v_pk_fma_f32 v[254:255], v[252:253], v[250:251], v[254:255]
	v_div_fixup_f32 v236, v248, v236, 1.0
	v_div_fixup_f32 v237, v249, v237, 1.0
	v_div_fixup_f32 v238, v254, v238, 1.0
	v_div_fixup_f32 v239, v255, v239, 1.0
	v_rcp_f32_e32 v244, v240
	v_rcp_f32_e32 v245, v241
	v_rcp_f32_e32 v250, v242
	v_rcp_f32_e32 v251, v243
	v_pk_fma_f32 v[246:247], v[240:241], v[244:245], 1.0 op_sel_hi:[1,1,0] neg_lo:[1,0,0] neg_hi:[1,0,0]
	v_pk_fma_f32 v[252:253], v[242:243], v[250:251], 1.0 op_sel_hi:[1,1,0] neg_lo:[1,0,0] neg_hi:[1,0,0]
	v_pk_fma_f32 v[244:245], v[246:247], v[244:245], v[244:245]
	v_pk_fma_f32 v[250:251], v[252:253], v[250:251], v[250:251]
	v_pk_fma_f32 v[246:247], v[240:241], v[244:245], 1.0 op_sel_hi:[1,1,0] neg_lo:[1,0,0] neg_hi:[1,0,0]
	v_pk_fma_f32 v[252:253], v[242:243], v[250:251], 1.0 op_sel_hi:[1,1,0] neg_lo:[1,0,0] neg_hi:[1,0,0]
	v_pk_fma_f32 v[248:249], v[246:247], v[244:245], v[244:245]
	v_pk_fma_f32 v[254:255], v[252:253], v[250:251], v[250:251]
	v_pk_fma_f32 v[246:247], v[240:241], v[248:249], 1.0 op_sel_hi:[1,1,0] neg_lo:[1,0,0] neg_hi:[1,0,0]
	v_pk_fma_f32 v[252:253], v[242:243], v[254:255], 1.0 op_sel_hi:[1,1,0] neg_lo:[1,0,0] neg_hi:[1,0,0]
	v_pk_fma_f32 v[248:249], v[246:247], v[244:245], v[248:249]
	v_pk_fma_f32 v[254:255], v[252:253], v[250:251], v[254:255]
	v_div_fixup_f32 v240, v248, v240, 1.0
	v_div_fixup_f32 v241, v249, v241, 1.0
	v_div_fixup_f32 v242, v254, v242, 1.0
	v_div_fixup_f32 v243, v255, v243, 1.0
	global_store_dwordx4 v[16:17], v[8:11], off
	s_nop 0
	v_mul_f32_e32 v4, v4, v236
	v_mul_f32_e32 v8, v0, v238
	v_mul_f32_e32 v0, v5, v237
	v_mul_f32_e32 v5, v1, v239
	v_mul_f32_e32 v1, v6, v240
	v_mul_f32_e32 v6, v2, v242
	v_mul_f32_e32 v2, v7, v241
	v_mul_f32_e32 v3, v3, v243
	s_and_b64 vcc, exec, s[8:9]
	s_mov_b32 s7, s26
	s_mov_b32 s6, s59
	v_cvt_pk_bf16_f32 v0, v4, v0
	v_cvt_pk_bf16_f32 v1, v1, v2
	v_cvt_pk_bf16_f32 v2, v8, v5
	v_cvt_pk_bf16_f32 v3, v6, v3
	global_store_dwordx4 v[16:17], v[0:3], off offset:256
	s_cbranch_vccz .LBB0_1763
	s_waitcnt vmcnt(0)
	s_cmpk_gt_u32 s34, 0xff
	s_cbranch_scc1 .LBB0_1772
	s_barrier

; #define PG8_STAGE(bufoff, gbase, voff) do { _Pragma("unroll") for (int _i = 0; _i < 2; ++_i) \
;         __builtin_amdgcn_global_load_lds((const unsigned*)((const char*)(gbase) + (voff)[_i]), (LAS unsigned*)(lds + (bufoff) + ldsw + _i * 8192), 16, 0, 0); } while (0)
; #define PG8_LDA(dst, b, h) do { _Pragma("unroll") for (int m = 0; m < 4; ++m) _Pragma("unroll") for (int k = 0; k < 2; ++k) dst[m][k] = *(const LAS bf16x8*)(lds + PG8_SA(b, h) + aoff + m * 2048 + k * 1024); } while (0)
; #define PG8_LDB(dst, b, h) do { _Pragma("unroll") for (int n = 0; n < 2; ++n) _Pragma("unroll") for (int k = 0; k < 2; ++k) dst[n][k] = *(const LAS bf16x8*)(lds + PG8_SB(b, h) + boff + n * 2048 + k * 1024); } while (0)
; #define PG8_MMA(ai, bj, At, Bt) do { __builtin_amdgcn_s_setprio(1); _Pragma("unroll") for (int m = 0; m < 4; ++m) _Pragma("unroll") for (int n = 0; n < 2; ++n) _Pragma("unroll") for (int k = 0; k < 2; ++k) \
;         acc[ai][bj][m][n] = __builtin_amdgcn_mfma_f32_16x16x32_bf16(Bt[n][k], At[m][k], acc[ai][bj][m][n], 0, 0, 0); __builtin_amdgcn_s_setprio(0); } while (0)
; #define PG8_WAIT_V(n) asm volatile("s_waitcnt vmcnt(" #n ")" ::: "memory")
; #define PG8_WAIT_L(n) asm volatile("s_waitcnt lgkmcnt(" #n ")" ::: "memory")
; #define PG8_BAR __builtin_amdgcn_s_barrier()
; #define PG8_SCHED __builtin_amdgcn_sched_barrier(0)
;     ...
;             PG8_LDB(B0, 0, 0); PG8_SCHED; PG8_LDA(At, 0, 0); PG8_STAGE(PG8_SA(1, 1), a1 + hA, voffA);
;             PG8_WAIT_L(8); PG8_BAR; PG8_WAIT_L(0); PG8_MMA(0, 0, At, B0); PG8_BAR; PG8_SCHED;
;             PG8_LDB(B1, 0, 1); PG8_STAGE(PG8_SB(0, 0), b2, voffB);
;             PG8_BAR; PG8_WAIT_L(0); PG8_MMA(0, 1, At, B1); PG8_BAR;
;             PG8_LDA(At, 0, 1); PG8_STAGE(PG8_SA(0, 0), a2, voffA);
;             PG8_BAR; PG8_WAIT_L(0); PG8_MMA(1, 0, At, B0); PG8_BAR; PG8_SCHED;
;             PG8_STAGE(PG8_SB(0, 1), b2 + hB, voffB);
;             PG8_WAIT_V(6); PG8_BAR; PG8_MMA(1, 1, At, B1); PG8_BAR;
.LBB0_1841:
	ds_read_b128 v[146:149], v159
	ds_read_b128 v[150:153], v159 offset:1024
	ds_read_b128 v[162:165], v159 offset:2048
	ds_read_b128 v[170:173], v159 offset:3072
	s_add_u32 s14, s12, 0xfffe0080
	s_addc_u32 s15, s13, -1
	s_cmp_eq_u32 s45, 4
	s_cselect_b32 s17, s7, s15
	s_cselect_b32 s16, s18, s14
	s_cselect_b32 s15, s19, s44
	s_cselect_b32 s14, s33, s39
	v_lshl_add_u64 v[154:155], s[12:13], 0, v[138:139]
	s_add_i32 m0, s62, 0xc000
	ds_read_b128 v[174:177], v160
	ds_read_b128 v[178:181], v160 offset:1024
	ds_read_b128 v[182:185], v160 offset:2048
	ds_read_b128 v[186:189], v160 offset:3072
	ds_read_b128 v[190:193], v160 offset:4096
	ds_read_b128 v[194:197], v160 offset:5120
	ds_read_b128 v[198:201], v160 offset:6144
	ds_read_b128 v[202:205], v160 offset:7168
	global_load_lds_dwordx4 v[154:155], off
	v_lshl_add_u64 v[154:155], s[12:13], 0, v[136:137]
	s_add_i32 m0, s62, 0xe000
	s_nop 0
	global_load_lds_dwordx4 v[154:155], off
	s_waitcnt lgkmcnt(8)
	s_barrier
	s_waitcnt lgkmcnt(0)
	s_setprio 1
	s_waitcnt lgkmcnt(0)
	v_mfma_f32_16x16x32_bf16 v[124:127], v[146:149], v[174:177], v[124:127]
	v_mfma_f32_16x16x32_bf16 v[120:123], v[162:165], v[174:177], v[120:123]
	v_mfma_f32_16x16x32_bf16 v[108:111], v[146:149], v[182:185], v[108:111]
	v_mfma_f32_16x16x32_bf16 v[104:107], v[162:165], v[182:185], v[104:107]
	v_mfma_f32_16x16x32_bf16 v[92:95], v[146:149], v[190:193], v[92:95]
	v_mfma_f32_16x16x32_bf16 v[88:91], v[162:165], v[190:193], v[88:91]
	v_mfma_f32_16x16x32_bf16 v[76:79], v[146:149], v[198:201], v[76:79]
	v_mfma_f32_16x16x32_bf16 v[72:75], v[162:165], v[198:201], v[72:75]
	v_mfma_f32_16x16x32_bf16 v[124:127], v[150:153], v[178:181], v[124:127]
	v_mfma_f32_16x16x32_bf16 v[120:123], v[170:173], v[178:181], v[120:123]
	v_mfma_f32_16x16x32_bf16 v[108:111], v[150:153], v[186:189], v[108:111]
	v_mfma_f32_16x16x32_bf16 v[104:107], v[170:173], v[186:189], v[104:107]
	v_mfma_f32_16x16x32_bf16 v[92:95], v[150:153], v[194:197], v[92:95]
	v_mfma_f32_16x16x32_bf16 v[88:91], v[170:173], v[194:197], v[88:91]
	v_mfma_f32_16x16x32_bf16 v[76:79], v[150:153], v[202:205], v[76:79]
	v_mfma_f32_16x16x32_bf16 v[72:75], v[170:173], v[202:205], v[72:75]
	s_setprio 0
	s_barrier
	s_add_i32 s55, s71, s61
	v_lshl_add_u64 v[154:155], s[14:15], 0, v[130:131]
	s_mov_b32 m0, s55
	ds_read_b128 v[206:209], v161
	ds_read_b128 v[210:213], v161 offset:1024
	ds_read_b128 v[214:217], v161 offset:2048
	ds_read_b128 v[218:221], v161 offset:3072
	global_load_lds_dwordx4 v[154:155], off
	v_lshl_add_u64 v[222:223], s[14:15], 0, v[134:135]
	s_add_i32 m0, s55, 0x2000
	s_nop 0
	global_load_lds_dwordx4 v[222:223], off
	s_barrier
	s_waitcnt lgkmcnt(0)
	s_setprio 1
	s_waitcnt lgkmcnt(0)
	v_mfma_f32_16x16x32_bf16 v[116:119], v[206:209], v[174:177], v[116:119]
	v_mfma_f32_16x16x32_bf16 v[112:115], v[214:217], v[174:177], v[112:115]
	v_mfma_f32_16x16x32_bf16 v[100:103], v[206:209], v[182:185], v[100:103]
	v_mfma_f32_16x16x32_bf16 v[96:99], v[214:217], v[182:185], v[96:99]
	v_mfma_f32_16x16x32_bf16 v[84:87], v[206:209], v[190:193], v[84:87]
	v_mfma_f32_16x16x32_bf16 v[80:83], v[214:217], v[190:193], v[80:83]
	v_mfma_f32_16x16x32_bf16 v[68:71], v[206:209], v[198:201], v[68:71]
	v_mfma_f32_16x16x32_bf16 v[64:67], v[214:217], v[198:201], v[64:67]
	v_mfma_f32_16x16x32_bf16 v[116:119], v[210:213], v[178:181], v[116:119]
	v_mfma_f32_16x16x32_bf16 v[112:115], v[218:221], v[178:181], v[112:115]
	v_mfma_f32_16x16x32_bf16 v[100:103], v[210:213], v[186:189], v[100:103]
	v_mfma_f32_16x16x32_bf16 v[96:99], v[218:221], v[186:189], v[96:99]
	v_mfma_f32_16x16x32_bf16 v[84:87], v[210:213], v[194:197], v[84:87]
	v_mfma_f32_16x16x32_bf16 v[80:83], v[218:221], v[194:197], v[80:83]
	v_mfma_f32_16x16x32_bf16 v[68:71], v[210:213], v[202:205], v[68:71]
	v_mfma_f32_16x16x32_bf16 v[64:67], v[218:221], v[202:205], v[64:67]
	s_setprio 0
	s_mov_b32 m0, s62
	v_lshl_add_u64 v[224:225], s[16:17], 0, v[128:129]
	s_barrier
	ds_read_b128 v[174:177], v160 offset:16384
	ds_read_b128 v[178:181], v160 offset:17408
	ds_read_b128 v[182:185], v160 offset:18432
	ds_read_b128 v[186:189], v160 offset:19456
	ds_read_b128 v[190:193], v160 offset:20480
	ds_read_b128 v[194:197], v160 offset:21504
	ds_read_b128 v[198:201], v160 offset:22528
	ds_read_b128 v[202:205], v160 offset:23552
	global_load_lds_dwordx4 v[224:225], off
	v_lshl_add_u64 v[226:227], s[16:17], 0, v[132:133]
	s_mov_b32 m0, s63
	s_nop 0
	global_load_lds_dwordx4 v[226:227], off
	s_barrier
	s_waitcnt lgkmcnt(0)
	s_setprio 1
	s_waitcnt lgkmcnt(0)
	v_mfma_f32_16x16x32_bf16 v[60:63], v[146:149], v[174:177], v[60:63]
	v_mfma_f32_16x16x32_bf16 v[56:59], v[162:165], v[174:177], v[56:59]
	v_mfma_f32_16x16x32_bf16 v[44:47], v[146:149], v[182:185], v[44:47]
	v_mfma_f32_16x16x32_bf16 v[40:43], v[162:165], v[182:185], v[40:43]
	v_mfma_f32_16x16x32_bf16 v[28:31], v[146:149], v[190:193], v[28:31]
	v_mfma_f32_16x16x32_bf16 v[24:27], v[162:165], v[190:193], v[24:27]
	v_mfma_f32_16x16x32_bf16 v[12:15], v[146:149], v[198:201], v[12:15]
	v_mfma_f32_16x16x32_bf16 v[8:11], v[162:165], v[198:201], v[8:11]
	v_mfma_f32_16x16x32_bf16 v[60:63], v[150:153], v[178:181], v[60:63]
	v_mfma_f32_16x16x32_bf16 v[56:59], v[170:173], v[178:181], v[56:59]
	v_mfma_f32_16x16x32_bf16 v[44:47], v[150:153], v[186:189], v[44:47]
	v_mfma_f32_16x16x32_bf16 v[40:43], v[170:173], v[186:189], v[40:43]
	v_mfma_f32_16x16x32_bf16 v[28:31], v[150:153], v[194:197], v[28:31]
	v_mfma_f32_16x16x32_bf16 v[24:27], v[170:173], v[194:197], v[24:27]
	v_mfma_f32_16x16x32_bf16 v[12:15], v[150:153], v[202:205], v[12:15]
	v_mfma_f32_16x16x32_bf16 v[8:11], v[170:173], v[202:205], v[8:11]
	s_setprio 0
	s_barrier
; #define PG8_STAGE(bufoff, gbase, voff) do { _Pragma("unroll") for (int _i = 0; _i < 2; ++_i) \
;         __builtin_amdgcn_global_load_lds((const unsigned*)((const char*)(gbase) + (voff)[_i]), (LAS unsigned*)(lds + (bufoff) + ldsw + _i * 8192), 16, 0, 0); } while (0)
; #define PG8_LDA(dst, b, h) do { _Pragma("unroll") for (int m = 0; m < 4; ++m) _Pragma("unroll") for (int k = 0; k < 2; ++k) dst[m][k] = *(const LAS bf16x8*)(lds + PG8_SA(b, h) + aoff + m * 2048 + k * 1024); } while (0)
; #define PG8_LDB(dst, b, h) do { _Pragma("unroll") for (int n = 0; n < 2; ++n) _Pragma("unroll") for (int k = 0; k < 2; ++k) dst[n][k] = *(const LAS bf16x8*)(lds + PG8_SB(b, h) + boff + n * 2048 + k * 1024); } while (0)
; #define PG8_MMA(ai, bj, At, Bt) do { __builtin_amdgcn_s_setprio(1); _Pragma("unroll") for (int m = 0; m < 4; ++m) _Pragma("unroll") for (int n = 0; n < 2; ++n) _Pragma("unroll") for (int k = 0; k < 2; ++k) \
;         acc[ai][bj][m][n] = __builtin_amdgcn_mfma_f32_16x16x32_bf16(Bt[n][k], At[m][k], acc[ai][bj][m][n], 0, 0, 0); __builtin_amdgcn_s_setprio(0); } while (0)
; #define PG8_WAIT_V(n) asm volatile("s_waitcnt vmcnt(" #n ")" ::: "memory")
; #define PG8_WAIT_L(n) asm volatile("s_waitcnt lgkmcnt(" #n ")" ::: "memory")
; #define PG8_BAR __builtin_amdgcn_s_barrier()
; #define PG8_SCHED __builtin_amdgcn_sched_barrier(0)
;     ...
;             PG8_WAIT_V(6); PG8_BAR; PG8_MMA(1, 1, At, B1); PG8_BAR;
;             PG8_LDB(B0, 1, 0); PG8_SCHED; PG8_LDA(At, 1, 0); PG8_STAGE(PG8_SA(0, 1), a2 + hA, voffA);
;             PG8_WAIT_L(8); PG8_BAR; PG8_WAIT_L(0); PG8_MMA(0, 0, At, B0); PG8_BAR; PG8_SCHED;
;             PG8_LDB(B1, 1, 1); PG8_STAGE(PG8_SB(1, 0), b3, voffB);
;             PG8_BAR; PG8_WAIT_L(0); PG8_MMA(0, 1, At, B1); PG8_BAR;
;             PG8_LDA(At, 1, 1); PG8_STAGE(PG8_SA(1, 0), a3, voffA);
;             PG8_BAR; PG8_WAIT_L(0); PG8_MMA(1, 0, At, B0); PG8_BAR; PG8_SCHED;
	s_add_u32 s76, s14, 0x20000
	s_addc_u32 s77, s15, 0
	s_add_i32 s55, s72, s61
	v_lshl_add_u64 v[146:147], s[76:77], 0, v[130:131]
	s_mov_b32 m0, s55
	s_nop 0
	global_load_lds_dwordx4 v[146:147], off
	v_lshl_add_u64 v[146:147], s[76:77], 0, v[134:135]
	s_add_i32 m0, s55, 0x2000
	s_nop 0
	global_load_lds_dwordx4 v[146:147], off
	s_waitcnt vmcnt(6)
	s_barrier
	s_setprio 1
	v_mfma_f32_16x16x32_bf16 v[52:55], v[206:209], v[174:177], v[52:55]
	v_mfma_f32_16x16x32_bf16 v[48:51], v[214:217], v[174:177], v[48:51]
	v_mfma_f32_16x16x32_bf16 v[36:39], v[206:209], v[182:185], v[36:39]
	v_mfma_f32_16x16x32_bf16 v[32:35], v[214:217], v[182:185], v[32:35]
	v_mfma_f32_16x16x32_bf16 v[20:23], v[206:209], v[190:193], v[20:23]
	v_mfma_f32_16x16x32_bf16 v[16:19], v[214:217], v[190:193], v[16:19]
	v_mfma_f32_16x16x32_bf16 v[4:7], v[206:209], v[198:201], v[4:7]
	v_mfma_f32_16x16x32_bf16 v[0:3], v[214:217], v[198:201], v[0:3]
	v_mfma_f32_16x16x32_bf16 v[52:55], v[210:213], v[178:181], v[52:55]
	v_mfma_f32_16x16x32_bf16 v[48:51], v[218:221], v[178:181], v[48:51]
	v_mfma_f32_16x16x32_bf16 v[36:39], v[210:213], v[186:189], v[36:39]
	v_mfma_f32_16x16x32_bf16 v[32:35], v[218:221], v[186:189], v[32:35]
	v_mfma_f32_16x16x32_bf16 v[20:23], v[210:213], v[194:197], v[20:23]
	v_mfma_f32_16x16x32_bf16 v[16:19], v[218:221], v[194:197], v[16:19]
	v_mfma_f32_16x16x32_bf16 v[4:7], v[210:213], v[202:205], v[4:7]
	v_mfma_f32_16x16x32_bf16 v[0:3], v[218:221], v[202:205], v[0:3]
	s_setprio 0
	s_add_i32 s55, 0, 0x18000
	v_add_u32_e32 v169, s55, v157
	s_barrier
	ds_read_b128 v[146:149], v169
	ds_read_b128 v[150:153], v169 offset:1024
	ds_read_b128 v[162:165], v169 offset:2048
	ds_read_b128 v[170:173], v169 offset:3072
	s_add_u32 s16, s16, 0x20000
	s_addc_u32 s17, s17, 0
	s_mov_b32 m0, s64
	v_lshl_add_u64 v[206:207], s[16:17], 0, v[128:129]
	ds_read_b128 v[174:177], v160 offset:32768
	ds_read_b128 v[178:181], v160 offset:33792
	ds_read_b128 v[182:185], v160 offset:34816
	ds_read_b128 v[186:189], v160 offset:35840
	ds_read_b128 v[190:193], v160 offset:36864
	ds_read_b128 v[194:197], v160 offset:37888
	ds_read_b128 v[198:201], v160 offset:38912
	ds_read_b128 v[202:205], v160 offset:39936
	global_load_lds_dwordx4 v[206:207], off
	v_lshl_add_u64 v[206:207], s[16:17], 0, v[132:133]
	s_mov_b32 m0, s65
	s_nop 0
	global_load_lds_dwordx4 v[206:207], off
	s_waitcnt lgkmcnt(8)
	s_barrier
	s_waitcnt lgkmcnt(0)
	s_setprio 1
	s_waitcnt lgkmcnt(0)
	v_mfma_f32_16x16x32_bf16 v[124:127], v[146:149], v[174:177], v[124:127]
	v_mfma_f32_16x16x32_bf16 v[120:123], v[162:165], v[174:177], v[120:123]
	v_mfma_f32_16x16x32_bf16 v[108:111], v[146:149], v[182:185], v[108:111]
	v_mfma_f32_16x16x32_bf16 v[104:107], v[162:165], v[182:185], v[104:107]
	v_mfma_f32_16x16x32_bf16 v[92:95], v[146:149], v[190:193], v[92:95]
	v_mfma_f32_16x16x32_bf16 v[88:91], v[162:165], v[190:193], v[88:91]
	v_mfma_f32_16x16x32_bf16 v[76:79], v[146:149], v[198:201], v[76:79]
	v_mfma_f32_16x16x32_bf16 v[72:75], v[162:165], v[198:201], v[72:75]
	v_mfma_f32_16x16x32_bf16 v[124:127], v[150:153], v[178:181], v[124:127]
	v_mfma_f32_16x16x32_bf16 v[120:123], v[170:173], v[178:181], v[120:123]
	v_mfma_f32_16x16x32_bf16 v[108:111], v[150:153], v[186:189], v[108:111]
	v_mfma_f32_16x16x32_bf16 v[104:107], v[170:173], v[186:189], v[104:107]
	v_mfma_f32_16x16x32_bf16 v[92:95], v[150:153], v[194:197], v[92:95]
	v_mfma_f32_16x16x32_bf16 v[88:91], v[170:173], v[194:197], v[88:91]
	v_mfma_f32_16x16x32_bf16 v[76:79], v[150:153], v[202:205], v[76:79]
	v_mfma_f32_16x16x32_bf16 v[72:75], v[170:173], v[202:205], v[72:75]
	s_setprio 0
	s_barrier
	s_add_i32 s16, 0, 0x1c000
	s_add_i32 s17, s55, s61
	v_add_u32_e32 v169, s16, v157
	v_lshl_add_u64 v[154:155], v[154:155], 0, s[40:41]
	s_mov_b32 m0, s17
	ds_read_b128 v[206:209], v169
	ds_read_b128 v[210:213], v169 offset:1024
	ds_read_b128 v[214:217], v169 offset:2048
	ds_read_b128 v[218:221], v169 offset:3072
	global_load_lds_dwordx4 v[154:155], off
	v_lshl_add_u64 v[154:155], v[222:223], 0, s[40:41]
	s_add_i32 m0, s17, 0x2000
	s_nop 0
	global_load_lds_dwordx4 v[154:155], off
	s_barrier
	s_waitcnt lgkmcnt(0)
	s_setprio 1
	s_waitcnt lgkmcnt(0)
	v_mfma_f32_16x16x32_bf16 v[116:119], v[206:209], v[174:177], v[116:119]
	v_mfma_f32_16x16x32_bf16 v[112:115], v[214:217], v[174:177], v[112:115]
	v_mfma_f32_16x16x32_bf16 v[100:103], v[206:209], v[182:185], v[100:103]
	v_mfma_f32_16x16x32_bf16 v[96:99], v[214:217], v[182:185], v[96:99]
	v_mfma_f32_16x16x32_bf16 v[84:87], v[206:209], v[190:193], v[84:87]
	v_mfma_f32_16x16x32_bf16 v[80:83], v[214:217], v[190:193], v[80:83]
	v_mfma_f32_16x16x32_bf16 v[68:71], v[206:209], v[198:201], v[68:71]
	v_mfma_f32_16x16x32_bf16 v[64:67], v[214:217], v[198:201], v[64:67]
	v_mfma_f32_16x16x32_bf16 v[116:119], v[210:213], v[178:181], v[116:119]
	v_mfma_f32_16x16x32_bf16 v[112:115], v[218:221], v[178:181], v[112:115]
	v_mfma_f32_16x16x32_bf16 v[100:103], v[210:213], v[186:189], v[100:103]
	v_mfma_f32_16x16x32_bf16 v[96:99], v[218:221], v[186:189], v[96:99]
	v_mfma_f32_16x16x32_bf16 v[84:87], v[210:213], v[194:197], v[84:87]
	v_mfma_f32_16x16x32_bf16 v[80:83], v[218:221], v[194:197], v[80:83]
	v_mfma_f32_16x16x32_bf16 v[68:71], v[210:213], v[202:205], v[68:71]
	v_mfma_f32_16x16x32_bf16 v[64:67], v[218:221], v[202:205], v[64:67]
	s_setprio 0
	s_mov_b32 m0, s67
	v_lshl_add_u64 v[154:155], v[224:225], 0, s[40:41]
	s_barrier
	ds_read_b128 v[174:177], v160 offset:49152
	ds_read_b128 v[178:181], v160 offset:50176
	ds_read_b128 v[182:185], v160 offset:51200
	ds_read_b128 v[186:189], v160 offset:52224
	ds_read_b128 v[190:193], v160 offset:53248
	ds_read_b128 v[194:197], v160 offset:54272
	ds_read_b128 v[198:201], v160 offset:55296
	ds_read_b128 v[202:205], v160 offset:56320
	global_load_lds_dwordx4 v[154:155], off
	v_lshl_add_u64 v[154:155], v[226:227], 0, s[40:41]
	s_mov_b32 m0, s68
	s_nop 0
	global_load_lds_dwordx4 v[154:155], off
	s_barrier
; __device__ __forceinline__ float sigmoidf_(float x) { return 1.0f / (1.0f + __expf(-x)); }
; #define PG8_STAGE(bufoff, gbase, voff) do { _Pragma("unroll") for (int _i = 0; _i < 2; ++_i) \
;         __builtin_amdgcn_global_load_lds((const unsigned*)((const char*)(gbase) + (voff)[_i]), (LAS unsigned*)(lds + (bufoff) + ldsw + _i * 8192), 16, 0, 0); } while (0)
; #define PG8_MMA(ai, bj, At, Bt) do { __builtin_amdgcn_s_setprio(1); _Pragma("unroll") for (int m = 0; m < 4; ++m) _Pragma("unroll") for (int n = 0; n < 2; ++n) _Pragma("unroll") for (int k = 0; k < 2; ++k) \
;         acc[ai][bj][m][n] = __builtin_amdgcn_mfma_f32_16x16x32_bf16(Bt[n][k], At[m][k], acc[ai][bj][m][n], 0, 0, 0); __builtin_amdgcn_s_setprio(0); } while (0)
; #define PG8_WAIT_V(n) asm volatile("s_waitcnt vmcnt(" #n ")" ::: "memory")
; #define PG8_BAR __builtin_amdgcn_s_barrier()
; __device__ __forceinline__ u32x4 pack8(const f32x4 v0, const f32x4 v1) { u32x4 w; w.x = pk2(v0[0], v0[1]); w.y = pk2(v0[2], v0[3]); w.z = pk2(v1[0], v1[1]); w.w = pk2(v1[2], v1[3]); return w; }
;     ...
;             PG8_STAGE(PG8_SB(1, 1), b3 + hB, voffB);
;             PG8_WAIT_V(6); PG8_BAR; PG8_MMA(1, 1, At, B1); PG8_BAR;
;     __device__ __forceinline__ void operator()(const f32x4 (&acc)[2][2][4][2], const Unit& u, int wr, int wc, int fr, int fq) const {
;     ...
;         for (int ai = 0; ai < 2; ++ai)
; #pragma unroll
;             for (int m = 0; m < 4; ++m) {
;                 const int row = row0 + ai * 128 + m * 16;
;                 const bf16_t* rowp = z + (size_t)row * DIN + col0;
; #pragma unroll
;                 for (int bj = 0; bj < 2; ++bj) {
;                     const u32x4 gw = *(const u32x4*)(rowp + O_GA + bj * 128);
;                     f32x4 g0, g1; unpack8(gw, g0, g1);
;                     f32x4 v0, v1;
; #pragma unroll
;                     for (int j = 0; j < 4; ++j) { v0[j] = sigmoidf_(g0[j]) * acc[ai][bj][m][0][j]; v1[j] = sigmoidf_(g1[j]) * acc[ai][bj][m][1][j]; }
;                     const u32x4 mw = *(const u32x4*)(rowp + bj * 128); f32x4 m0, m1; unpack8(mw, m0, m1); v0 += m0; v1 += m1;
;                     __builtin_amdgcn_raw_buffer_store_b128(pack8(v0, v1), rsrc, (unsigned)(((size_t)row * DIN + col0 + bj * 128) * 2), 0, 16  ); }
	s_waitcnt lgkmcnt(0)
	s_setprio 1
	s_waitcnt lgkmcnt(0)
	v_mfma_f32_16x16x32_bf16 v[60:63], v[146:149], v[174:177], v[60:63]
	v_mfma_f32_16x16x32_bf16 v[56:59], v[162:165], v[174:177], v[56:59]
	v_mfma_f32_16x16x32_bf16 v[44:47], v[146:149], v[182:185], v[44:47]
	v_mfma_f32_16x16x32_bf16 v[40:43], v[162:165], v[182:185], v[40:43]
	v_mfma_f32_16x16x32_bf16 v[28:31], v[146:149], v[190:193], v[28:31]
	v_mfma_f32_16x16x32_bf16 v[24:27], v[162:165], v[190:193], v[24:27]
	v_mfma_f32_16x16x32_bf16 v[12:15], v[146:149], v[198:201], v[12:15]
	v_mfma_f32_16x16x32_bf16 v[8:11], v[162:165], v[198:201], v[8:11]
	v_mfma_f32_16x16x32_bf16 v[60:63], v[150:153], v[178:181], v[60:63]
	v_mfma_f32_16x16x32_bf16 v[56:59], v[170:173], v[178:181], v[56:59]
	v_mfma_f32_16x16x32_bf16 v[44:47], v[150:153], v[186:189], v[44:47]
	v_mfma_f32_16x16x32_bf16 v[40:43], v[170:173], v[186:189], v[40:43]
	v_mfma_f32_16x16x32_bf16 v[28:31], v[150:153], v[194:197], v[28:31]
	v_mfma_f32_16x16x32_bf16 v[24:27], v[170:173], v[194:197], v[24:27]
	v_mfma_f32_16x16x32_bf16 v[12:15], v[150:153], v[202:205], v[12:15]
	v_mfma_f32_16x16x32_bf16 v[8:11], v[170:173], v[202:205], v[8:11]
	s_setprio 0
	s_barrier
	s_add_u32 s14, s14, 0x20080
	s_addc_u32 s15, s15, 0
	s_add_i32 s16, s16, s61
	v_lshl_add_u64 v[146:147], s[14:15], 0, v[130:131]
	s_mov_b32 m0, s16
	s_nop 0
	global_load_lds_dwordx4 v[146:147], off
	v_lshl_add_u64 v[146:147], s[14:15], 0, v[134:135]
	s_add_i32 m0, s16, 0x2000
	s_nop 0
	global_load_lds_dwordx4 v[146:147], off
	s_waitcnt vmcnt(6)
	s_barrier
	s_setprio 1
	v_mfma_f32_16x16x32_bf16 v[52:55], v[206:209], v[174:177], v[52:55]
	v_mfma_f32_16x16x32_bf16 v[48:51], v[214:217], v[174:177], v[48:51]
	v_mfma_f32_16x16x32_bf16 v[36:39], v[206:209], v[182:185], v[36:39]
	v_mfma_f32_16x16x32_bf16 v[32:35], v[214:217], v[182:185], v[32:35]
	v_mfma_f32_16x16x32_bf16 v[20:23], v[206:209], v[190:193], v[20:23]
	v_mfma_f32_16x16x32_bf16 v[16:19], v[214:217], v[190:193], v[16:19]
	v_mfma_f32_16x16x32_bf16 v[4:7], v[206:209], v[198:201], v[4:7]
	v_mfma_f32_16x16x32_bf16 v[0:3], v[214:217], v[198:201], v[0:3]
	v_mfma_f32_16x16x32_bf16 v[52:55], v[210:213], v[178:181], v[52:55]
	v_mfma_f32_16x16x32_bf16 v[48:51], v[218:221], v[178:181], v[48:51]
	v_mfma_f32_16x16x32_bf16 v[36:39], v[210:213], v[186:189], v[36:39]
	v_mfma_f32_16x16x32_bf16 v[32:35], v[218:221], v[186:189], v[32:35]
	v_mfma_f32_16x16x32_bf16 v[20:23], v[210:213], v[194:197], v[20:23]
	v_mfma_f32_16x16x32_bf16 v[16:19], v[218:221], v[194:197], v[16:19]
	v_mfma_f32_16x16x32_bf16 v[4:7], v[210:213], v[202:205], v[4:7]
	v_mfma_f32_16x16x32_bf16 v[0:3], v[218:221], v[202:205], v[0:3]
	s_setprio 0
	s_add_i32 s45, s45, 2
	s_add_u32 s39, s39, 0x100
	s_addc_u32 s44, s44, 0
	s_add_u32 s12, s12, 0x100
	s_addc_u32 s13, s13, 0
	s_cmp_gt_u32 s45, 5
	s_barrier
	s_cbranch_scc0 .LBB0_1841
	v_lshl_or_b32 v146, s6, 8, v158
	v_lshl_add_u32 v162, s75, 8, v156
	v_ashrrev_i32_e32 v147, 31, v146
	v_mad_i64_i32 v[154:155], s[6:7], v162, s73, 0
	v_lshl_add_u64 v[150:151], v[154:155], 1, s[36:37]
	v_lshlrev_b64 v[148:149], 1, v[146:147]
	v_lshl_add_u64 v[150:151], v[150:151], 0, v[148:149]
	v_add_co_u32_e32 v152, vcc, 0x1000, v150
	s_nop 1
	v_addc_co_u32_e32 v153, vcc, 0, v151, vcc
	v_subrev_u32_e32 v201, s36, v150
	v_add_u32_e32 v202, 0x1200, v201
	global_load_dwordx4 v[204:207], v202, s[36:37]
	v_add_u32_e32 v202, 0x0, v201
	global_load_dwordx4 v[208:211], v202, s[36:37]
	v_add_u32_e32 v202, 0x1300, v201
	global_load_dwordx4 v[212:215], v202, s[36:37]
	v_add_u32_e32 v202, 0x100, v201
	global_load_dwordx4 v[216:219], v202, s[36:37]
	v_add_u32_e32 v202, 0x23200, v201
	global_load_dwordx4 v[232:235], v202, s[36:37]
	v_add_u32_e32 v202, 0x22000, v201
	global_load_dwordx4 v[236:239], v202, s[36:37]
	s_waitcnt vmcnt(4)
	v_mov_b64_e32 v[170:171], v[204:205]
	v_mov_b64_e32 v[172:173], v[206:207]
	v_mov_b64_e32 v[174:175], v[208:209]
	v_mov_b64_e32 v[176:177], v[210:211]
	v_add_u32_e32 v202, 0x23300, v201
	global_load_dwordx4 v[204:207], v202, s[36:37]
	v_add_u32_e32 v202, 0x22100, v201
	global_load_dwordx4 v[208:211], v202, s[36:37]
	s_mov_b32 s100, 0xbfb8aa3b
	v_lshlrev_b32_e32 v242, 16, v170
	v_and_b32_e32 v243, 0xffff0000, v170
	v_lshlrev_b32_e32 v244, 16, v172
	v_and_b32_e32 v245, 0xffff0000, v172
	v_lshlrev_b32_e32 v246, 16, v173
	v_and_b32_e32 v247, 0xffff0000, v173
	v_lshlrev_b32_e32 v248, 16, v171
	v_and_b32_e32 v249, 0xffff0000, v171
	v_pk_mul_f32 v[242:243], v[242:243], s[100:101] op_sel_hi:[1,0]
	v_pk_mul_f32 v[244:245], v[244:245], s[100:101] op_sel_hi:[1,0]
	v_pk_mul_f32 v[246:247], v[246:247], s[100:101] op_sel_hi:[1,0]
	v_pk_mul_f32 v[248:249], v[248:249], s[100:101] op_sel_hi:[1,0]
	v_exp_f32_e32 v242, v242
	v_exp_f32_e32 v243, v243
	v_exp_f32_e32 v244, v244
	v_exp_f32_e32 v245, v245
	v_exp_f32_e32 v246, v246
	v_exp_f32_e32 v247, v247
	v_exp_f32_e32 v248, v248
	v_exp_f32_e32 v249, v249
	s_nop 0
	v_pk_add_f32 v[242:243], v[242:243], 1.0 op_sel_hi:[1,0]
	v_pk_add_f32 v[244:245], v[244:245], 1.0 op_sel_hi:[1,0]
	v_pk_add_f32 v[246:247], v[246:247], 1.0 op_sel_hi:[1,0]
	v_pk_add_f32 v[248:249], v[248:249], 1.0 op_sel_hi:[1,0]
	v_rcp_f32_e32 v250, v242
	v_rcp_f32_e32 v251, v243
	s_nop 0
	v_pk_fma_f32 v[252:253], v[242:243], v[250:251], 1.0 op_sel_hi:[1,1,0] neg_lo:[1,0,0] neg_hi:[1,0,0]
	v_pk_fma_f32 v[250:251], v[252:253], v[250:251], v[250:251]
	v_pk_fma_f32 v[252:253], v[242:243], v[250:251], 1.0 op_sel_hi:[1,1,0] neg_lo:[1,0,0] neg_hi:[1,0,0]
	v_pk_fma_f32 v[254:255], v[252:253], v[250:251], v[250:251]
	v_pk_fma_f32 v[252:253], v[242:243], v[254:255], 1.0 op_sel_hi:[1,1,0] neg_lo:[1,0,0] neg_hi:[1,0,0]
	v_pk_fma_f32 v[254:255], v[252:253], v[250:251], v[254:255]
; __device__ __forceinline__ float sigmoidf_(float x) { return 1.0f / (1.0f + __expf(-x)); }
; __device__ __forceinline__ u32x4 pack8(const f32x4 v0, const f32x4 v1) { u32x4 w; w.x = pk2(v0[0], v0[1]); w.y = pk2(v0[2], v0[3]); w.z = pk2(v1[0], v1[1]); w.w = pk2(v1[2], v1[3]); return w; }
; __device__ __forceinline__ void unpack8(const u32x4 w, f32x4& v0, f32x4& v1) { v0 = (f32x4){bflo(w.x), bfhi(w.x), bflo(w.y), bfhi(w.y)}; v1 = (f32x4){bflo(w.z), bfhi(w.z), bflo(w.w), bfhi(w.w)}; }
;     __device__ __forceinline__ void operator()(const f32x4 (&acc)[2][2][4][2], const Unit& u, int wr, int wc, int fr, int fq) const {
;     ...
;         for (int ai = 0; ai < 2; ++ai)
; #pragma unroll
;             for (int m = 0; m < 4; ++m) {
;                 const int row = row0 + ai * 128 + m * 16;
;                 const bf16_t* rowp = z + (size_t)row * DIN + col0;
; #pragma unroll
;                 for (int bj = 0; bj < 2; ++bj) {
;                     const u32x4 gw = *(const u32x4*)(rowp + O_GA + bj * 128);
;                     f32x4 g0, g1; unpack8(gw, g0, g1);
;                     f32x4 v0, v1;
; #pragma unroll
;                     for (int j = 0; j < 4; ++j) { v0[j] = sigmoidf_(g0[j]) * acc[ai][bj][m][0][j]; v1[j] = sigmoidf_(g1[j]) * acc[ai][bj][m][1][j]; }
;                     const u32x4 mw = *(const u32x4*)(rowp + bj * 128); f32x4 m0, m1; unpack8(mw, m0, m1); v0 += m0; v1 += m1;
;                     __builtin_amdgcn_raw_buffer_store_b128(pack8(v0, v1), rsrc, (unsigned)(((size_t)row * DIN + col0 + bj * 128) * 2), 0, 16  ); }
	v_div_fixup_f32 v242, v254, v242, 1.0
	v_div_fixup_f32 v243, v255, v243, 1.0
	v_rcp_f32_e32 v250, v244
	v_rcp_f32_e32 v251, v245
	s_nop 0
	v_pk_fma_f32 v[252:253], v[244:245], v[250:251], 1.0 op_sel_hi:[1,1,0] neg_lo:[1,0,0] neg_hi:[1,0,0]
	v_pk_fma_f32 v[250:251], v[252:253], v[250:251], v[250:251]
	v_pk_fma_f32 v[252:253], v[244:245], v[250:251], 1.0 op_sel_hi:[1,1,0] neg_lo:[1,0,0] neg_hi:[1,0,0]
	v_pk_fma_f32 v[254:255], v[252:253], v[250:251], v[250:251]
	v_pk_fma_f32 v[252:253], v[244:245], v[254:255], 1.0 op_sel_hi:[1,1,0] neg_lo:[1,0,0] neg_hi:[1,0,0]
	v_pk_fma_f32 v[254:255], v[252:253], v[250:251], v[254:255]
	v_div_fixup_f32 v244, v254, v244, 1.0
	v_div_fixup_f32 v245, v255, v245, 1.0
	v_rcp_f32_e32 v250, v246
	v_rcp_f32_e32 v251, v247
	s_nop 0
	v_pk_fma_f32 v[252:253], v[246:247], v[250:251], 1.0 op_sel_hi:[1,1,0] neg_lo:[1,0,0] neg_hi:[1,0,0]
	v_pk_fma_f32 v[250:251], v[252:253], v[250:251], v[250:251]
	v_pk_fma_f32 v[252:253], v[246:247], v[250:251], 1.0 op_sel_hi:[1,1,0] neg_lo:[1,0,0] neg_hi:[1,0,0]
	v_pk_fma_f32 v[254:255], v[252:253], v[250:251], v[250:251]
	v_pk_fma_f32 v[252:253], v[246:247], v[254:255], 1.0 op_sel_hi:[1,1,0] neg_lo:[1,0,0] neg_hi:[1,0,0]
	v_pk_fma_f32 v[254:255], v[252:253], v[250:251], v[254:255]
	v_div_fixup_f32 v246, v254, v246, 1.0
	v_div_fixup_f32 v247, v255, v247, 1.0
	v_rcp_f32_e32 v250, v248
	v_rcp_f32_e32 v251, v249
	s_nop 0
	v_pk_fma_f32 v[252:253], v[248:249], v[250:251], 1.0 op_sel_hi:[1,1,0] neg_lo:[1,0,0] neg_hi:[1,0,0]
	v_pk_fma_f32 v[250:251], v[252:253], v[250:251], v[250:251]
	v_pk_fma_f32 v[252:253], v[248:249], v[250:251], 1.0 op_sel_hi:[1,1,0] neg_lo:[1,0,0] neg_hi:[1,0,0]
	v_pk_fma_f32 v[254:255], v[252:253], v[250:251], v[250:251]
	v_pk_fma_f32 v[252:253], v[248:249], v[254:255], 1.0 op_sel_hi:[1,1,0] neg_lo:[1,0,0] neg_hi:[1,0,0]
	v_pk_fma_f32 v[254:255], v[252:253], v[250:251], v[254:255]
	v_div_fixup_f32 v248, v254, v248, 1.0
	v_div_fixup_f32 v249, v255, v249, 1.0
	s_mov_b64 vcc, s[12:13]
	s_mov_b64 vcc, s[14:15]
	s_mov_b64 vcc, s[16:17]
	s_mov_b64 vcc, s[18:19]
	v_and_b32_e32 v181, 0xffff0000, v174
	v_lshlrev_b32_e32 v182, 16, v176
	v_lshlrev_b32_e32 v180, 16, v174
	v_and_b32_e32 v183, 0xffff0000, v176
	v_lshlrev_b32_e32 v176, 16, v177
	v_and_b32_e32 v177, 0xffff0000, v177
	v_lshlrev_b32_e32 v174, 16, v175
	v_and_b32_e32 v175, 0xffff0000, v175
	v_pk_fma_f32 v[124:125], v[124:125], v[242:243], v[180:181]
	v_pk_fma_f32 v[164:165], v[122:123], v[246:247], v[176:177]
	v_pk_fma_f32 v[122:123], v[120:121], v[244:245], v[182:183]
	v_add_lshl_u32 v147, v146, v154, 1
	v_pk_fma_f32 v[126:127], v[126:127], v[248:249], v[174:175]
	v_cvt_pk_bf16_f32 v120, v124, v125
	s_nop 0
	v_cvt_pk_bf16_f32 v121, v126, v127
	v_cvt_pk_bf16_f32 v122, v122, v123
	v_cvt_pk_bf16_f32 v123, v164, v165
	buffer_store_dwordx4 v[120:123], v147, s[20:23], 0 offen sc1
	s_nop 0
	s_waitcnt vmcnt(5)
	v_mov_b64_e32 v[120:121], v[212:213]
	v_mov_b64_e32 v[122:123], v[214:215]
	v_mov_b64_e32 v[124:125], v[216:217]
	v_mov_b64_e32 v[126:127], v[218:219]
	v_add_u32_e32 v202, 0x45200, v201
	global_load_dwordx4 v[212:215], v202, s[36:37]
	v_add_u32_e32 v202, 0x44000, v201
	global_load_dwordx4 v[216:219], v202, s[36:37]
	s_mov_b32 s100, 0xbfb8aa3b
	v_lshlrev_b32_e32 v242, 16, v120
	v_and_b32_e32 v243, 0xffff0000, v120
	v_lshlrev_b32_e32 v244, 16, v122
	v_and_b32_e32 v245, 0xffff0000, v122
	v_lshlrev_b32_e32 v246, 16, v121
	v_and_b32_e32 v247, 0xffff0000, v121
	v_lshlrev_b32_e32 v248, 16, v123
	v_and_b32_e32 v249, 0xffff0000, v123
	v_pk_mul_f32 v[242:243], v[242:243], s[100:101] op_sel_hi:[1,0]
	v_pk_mul_f32 v[244:245], v[244:245], s[100:101] op_sel_hi:[1,0]
	v_pk_mul_f32 v[246:247], v[246:247], s[100:101] op_sel_hi:[1,0]
	v_pk_mul_f32 v[248:249], v[248:249], s[100:101] op_sel_hi:[1,0]
	v_exp_f32_e32 v242, v242
	v_exp_f32_e32 v243, v243
	v_exp_f32_e32 v244, v244
	v_exp_f32_e32 v245, v245
	v_exp_f32_e32 v246, v246
	v_exp_f32_e32 v247, v247
	v_exp_f32_e32 v248, v248
	v_exp_f32_e32 v249, v249
	s_nop 0
	v_pk_add_f32 v[242:243], v[242:243], 1.0 op_sel_hi:[1,0]
	v_pk_add_f32 v[244:245], v[244:245], 1.0 op_sel_hi:[1,0]
	v_pk_add_f32 v[246:247], v[246:247], 1.0 op_sel_hi:[1,0]
	v_pk_add_f32 v[248:249], v[248:249], 1.0 op_sel_hi:[1,0]
	v_rcp_f32_e32 v250, v242
	v_rcp_f32_e32 v251, v243
	s_nop 0
	v_pk_fma_f32 v[252:253], v[242:243], v[250:251], 1.0 op_sel_hi:[1,1,0] neg_lo:[1,0,0] neg_hi:[1,0,0]
	v_pk_fma_f32 v[250:251], v[252:253], v[250:251], v[250:251]
	v_pk_fma_f32 v[252:253], v[242:243], v[250:251], 1.0 op_sel_hi:[1,1,0] neg_lo:[1,0,0] neg_hi:[1,0,0]
	v_pk_fma_f32 v[254:255], v[252:253], v[250:251], v[250:251]
	v_pk_fma_f32 v[252:253], v[242:243], v[254:255], 1.0 op_sel_hi:[1,1,0] neg_lo:[1,0,0] neg_hi:[1,0,0]
	v_pk_fma_f32 v[254:255], v[252:253], v[250:251], v[254:255]
	v_div_fixup_f32 v242, v254, v242, 1.0
	v_div_fixup_f32 v243, v255, v243, 1.0
	v_rcp_f32_e32 v250, v244
	v_rcp_f32_e32 v251, v245
	s_nop 0
	v_pk_fma_f32 v[252:253], v[244:245], v[250:251], 1.0 op_sel_hi:[1,1,0] neg_lo:[1,0,0] neg_hi:[1,0,0]
	v_pk_fma_f32 v[250:251], v[252:253], v[250:251], v[250:251]
	v_pk_fma_f32 v[252:253], v[244:245], v[250:251], 1.0 op_sel_hi:[1,1,0] neg_lo:[1,0,0] neg_hi:[1,0,0]
	v_pk_fma_f32 v[254:255], v[252:253], v[250:251], v[250:251]
	v_pk_fma_f32 v[252:253], v[244:245], v[254:255], 1.0 op_sel_hi:[1,1,0] neg_lo:[1,0,0] neg_hi:[1,0,0]
	v_pk_fma_f32 v[254:255], v[252:253], v[250:251], v[254:255]
	v_div_fixup_f32 v244, v254, v244, 1.0
	v_div_fixup_f32 v245, v255, v245, 1.0
	v_rcp_f32_e32 v250, v246
	v_rcp_f32_e32 v251, v247
	s_nop 0
	v_pk_fma_f32 v[252:253], v[246:247], v[250:251], 1.0 op_sel_hi:[1,1,0] neg_lo:[1,0,0] neg_hi:[1,0,0]
; __device__ __forceinline__ float sigmoidf_(float x) { return 1.0f / (1.0f + __expf(-x)); }
; __device__ __forceinline__ u32x4 pack8(const f32x4 v0, const f32x4 v1) { u32x4 w; w.x = pk2(v0[0], v0[1]); w.y = pk2(v0[2], v0[3]); w.z = pk2(v1[0], v1[1]); w.w = pk2(v1[2], v1[3]); return w; }
; __device__ __forceinline__ void unpack8(const u32x4 w, f32x4& v0, f32x4& v1) { v0 = (f32x4){bflo(w.x), bfhi(w.x), bflo(w.y), bfhi(w.y)}; v1 = (f32x4){bflo(w.z), bfhi(w.z), bflo(w.w), bfhi(w.w)}; }
;     __device__ __forceinline__ void operator()(const f32x4 (&acc)[2][2][4][2], const Unit& u, int wr, int wc, int fr, int fq) const {
;     ...
;         for (int ai = 0; ai < 2; ++ai)
; #pragma unroll
;             for (int m = 0; m < 4; ++m) {
;                 const int row = row0 + ai * 128 + m * 16;
;                 const bf16_t* rowp = z + (size_t)row * DIN + col0;
; #pragma unroll
;                 for (int bj = 0; bj < 2; ++bj) {
;                     const u32x4 gw = *(const u32x4*)(rowp + O_GA + bj * 128);
;                     f32x4 g0, g1; unpack8(gw, g0, g1);
;                     f32x4 v0, v1;
; #pragma unroll
;                     for (int j = 0; j < 4; ++j) { v0[j] = sigmoidf_(g0[j]) * acc[ai][bj][m][0][j]; v1[j] = sigmoidf_(g1[j]) * acc[ai][bj][m][1][j]; }
;                     const u32x4 mw = *(const u32x4*)(rowp + bj * 128); f32x4 m0, m1; unpack8(mw, m0, m1); v0 += m0; v1 += m1;
;                     __builtin_amdgcn_raw_buffer_store_b128(pack8(v0, v1), rsrc, (unsigned)(((size_t)row * DIN + col0 + bj * 128) * 2), 0, 16  ); }
	v_pk_fma_f32 v[250:251], v[252:253], v[250:251], v[250:251]
	v_pk_fma_f32 v[252:253], v[246:247], v[250:251], 1.0 op_sel_hi:[1,1,0] neg_lo:[1,0,0] neg_hi:[1,0,0]
	v_pk_fma_f32 v[254:255], v[252:253], v[250:251], v[250:251]
	v_pk_fma_f32 v[252:253], v[246:247], v[254:255], 1.0 op_sel_hi:[1,1,0] neg_lo:[1,0,0] neg_hi:[1,0,0]
	v_pk_fma_f32 v[254:255], v[252:253], v[250:251], v[254:255]
	v_div_fixup_f32 v246, v254, v246, 1.0
	v_div_fixup_f32 v247, v255, v247, 1.0
	v_rcp_f32_e32 v250, v248
	v_rcp_f32_e32 v251, v249
	s_nop 0
	v_pk_fma_f32 v[252:253], v[248:249], v[250:251], 1.0 op_sel_hi:[1,1,0] neg_lo:[1,0,0] neg_hi:[1,0,0]
	v_pk_fma_f32 v[250:251], v[252:253], v[250:251], v[250:251]
	v_pk_fma_f32 v[252:253], v[248:249], v[250:251], 1.0 op_sel_hi:[1,1,0] neg_lo:[1,0,0] neg_hi:[1,0,0]
	v_pk_fma_f32 v[254:255], v[252:253], v[250:251], v[250:251]
	v_pk_fma_f32 v[252:253], v[248:249], v[254:255], 1.0 op_sel_hi:[1,1,0] neg_lo:[1,0,0] neg_hi:[1,0,0]
	v_pk_fma_f32 v[254:255], v[252:253], v[250:251], v[254:255]
	v_div_fixup_f32 v248, v254, v248, 1.0
	v_div_fixup_f32 v249, v255, v249, 1.0
	v_lshlrev_b32_e32 v154, 16, v124
	v_and_b32_e32 v155, 0xffff0000, v124
	v_lshlrev_b32_e32 v164, 16, v126
	v_and_b32_e32 v165, 0xffff0000, v126
	v_lshlrev_b32_e32 v126, 16, v127
	v_and_b32_e32 v127, 0xffff0000, v127
	v_lshlrev_b32_e32 v124, 16, v125
	v_and_b32_e32 v125, 0xffff0000, v125
	v_pk_fma_f32 v[116:117], v[116:117], v[242:243], v[154:155]
	v_pk_fma_f32 v[120:121], v[114:115], v[248:249], v[126:127]
	v_pk_fma_f32 v[114:115], v[112:113], v[244:245], v[164:165]
	v_cvt_pk_bf16_f32 v112, v116, v117
	v_pk_fma_f32 v[118:119], v[118:119], v[246:247], v[124:125]
	s_nop 0
	v_cvt_pk_bf16_f32 v113, v118, v119
	v_cvt_pk_bf16_f32 v114, v114, v115
	v_cvt_pk_bf16_f32 v115, v120, v121
	buffer_store_dwordx4 v[112:115], v147, s[20:23], 0 offen offset:256 sc1
	s_nop 1
	v_or_b32_e32 v112, 16, v162
	v_mad_i64_i32 v[114:115], s[6:7], v112, s73, 0
	v_lshl_add_u64 v[112:113], v[114:115], 1, s[36:37]
	v_lshl_add_u64 v[112:113], v[112:113], 0, v[148:149]
	v_add_co_u32_e32 v116, vcc, s74, v112
	s_nop 1
	v_addc_co_u32_e32 v117, vcc, 0, v113, vcc
	s_waitcnt vmcnt(6)
	v_mov_b64_e32 v[118:119], v[232:233]
	v_mov_b64_e32 v[120:121], v[234:235]
	v_mov_b64_e32 v[122:123], v[236:237]
	v_mov_b64_e32 v[124:125], v[238:239]
	v_add_u32_e32 v202, 0x45300, v201
	global_load_dwordx4 v[232:235], v202, s[36:37]
	v_add_u32_e32 v202, 0x44100, v201
	global_load_dwordx4 v[236:239], v202, s[36:37]
	s_mov_b32 s100, 0xbfb8aa3b
	v_lshlrev_b32_e32 v242, 16, v118
	v_and_b32_e32 v243, 0xffff0000, v118
	v_lshlrev_b32_e32 v244, 16, v120
	v_and_b32_e32 v245, 0xffff0000, v120
	v_lshlrev_b32_e32 v246, 16, v119
	v_and_b32_e32 v247, 0xffff0000, v119
	v_lshlrev_b32_e32 v248, 16, v121
	v_and_b32_e32 v249, 0xffff0000, v121
	v_pk_mul_f32 v[242:243], v[242:243], s[100:101] op_sel_hi:[1,0]
	v_pk_mul_f32 v[244:245], v[244:245], s[100:101] op_sel_hi:[1,0]
	v_pk_mul_f32 v[246:247], v[246:247], s[100:101] op_sel_hi:[1,0]
	v_pk_mul_f32 v[248:249], v[248:249], s[100:101] op_sel_hi:[1,0]
	v_exp_f32_e32 v242, v242
	v_exp_f32_e32 v243, v243
	v_exp_f32_e32 v244, v244
	v_exp_f32_e32 v245, v245
	v_exp_f32_e32 v246, v246
	v_exp_f32_e32 v247, v247
	v_exp_f32_e32 v248, v248
	v_exp_f32_e32 v249, v249
	s_nop 0
	v_pk_add_f32 v[242:243], v[242:243], 1.0 op_sel_hi:[1,0]
	v_pk_add_f32 v[244:245], v[244:245], 1.0 op_sel_hi:[1,0]
	v_pk_add_f32 v[246:247], v[246:247], 1.0 op_sel_hi:[1,0]
	v_pk_add_f32 v[248:249], v[248:249], 1.0 op_sel_hi:[1,0]
	v_rcp_f32_e32 v250, v242
	v_rcp_f32_e32 v251, v243
	s_nop 0
	v_pk_fma_f32 v[252:253], v[242:243], v[250:251], 1.0 op_sel_hi:[1,1,0] neg_lo:[1,0,0] neg_hi:[1,0,0]
	v_pk_fma_f32 v[250:251], v[252:253], v[250:251], v[250:251]
	v_pk_fma_f32 v[252:253], v[242:243], v[250:251], 1.0 op_sel_hi:[1,1,0] neg_lo:[1,0,0] neg_hi:[1,0,0]
	v_pk_fma_f32 v[254:255], v[252:253], v[250:251], v[250:251]
	v_pk_fma_f32 v[252:253], v[242:243], v[254:255], 1.0 op_sel_hi:[1,1,0] neg_lo:[1,0,0] neg_hi:[1,0,0]
	v_pk_fma_f32 v[254:255], v[252:253], v[250:251], v[254:255]
	v_div_fixup_f32 v242, v254, v242, 1.0
	v_div_fixup_f32 v243, v255, v243, 1.0
	v_rcp_f32_e32 v250, v244
	v_rcp_f32_e32 v251, v245
	s_nop 0
	v_pk_fma_f32 v[252:253], v[244:245], v[250:251], 1.0 op_sel_hi:[1,1,0] neg_lo:[1,0,0] neg_hi:[1,0,0]
	v_pk_fma_f32 v[250:251], v[252:253], v[250:251], v[250:251]
	v_pk_fma_f32 v[252:253], v[244:245], v[250:251], 1.0 op_sel_hi:[1,1,0] neg_lo:[1,0,0] neg_hi:[1,0,0]
	v_pk_fma_f32 v[254:255], v[252:253], v[250:251], v[250:251]
	v_pk_fma_f32 v[252:253], v[244:245], v[254:255], 1.0 op_sel_hi:[1,1,0] neg_lo:[1,0,0] neg_hi:[1,0,0]
	v_pk_fma_f32 v[254:255], v[252:253], v[250:251], v[254:255]
	v_div_fixup_f32 v244, v254, v244, 1.0
	v_div_fixup_f32 v245, v255, v245, 1.0
	v_rcp_f32_e32 v250, v246
	v_rcp_f32_e32 v251, v247
	s_nop 0
	v_pk_fma_f32 v[252:253], v[246:247], v[250:251], 1.0 op_sel_hi:[1,1,0] neg_lo:[1,0,0] neg_hi:[1,0,0]
	v_pk_fma_f32 v[250:251], v[252:253], v[250:251], v[250:251]
	v_pk_fma_f32 v[252:253], v[246:247], v[250:251], 1.0 op_sel_hi:[1,1,0] neg_lo:[1,0,0] neg_hi:[1,0,0]
	v_pk_fma_f32 v[254:255], v[252:253], v[250:251], v[250:251]
	v_pk_fma_f32 v[252:253], v[246:247], v[254:255], 1.0 op_sel_hi:[1,1,0] neg_lo:[1,0,0] neg_hi:[1,0,0]
	v_pk_fma_f32 v[254:255], v[252:253], v[250:251], v[254:255]
	v_div_fixup_f32 v246, v254, v246, 1.0
	v_div_fixup_f32 v247, v255, v247, 1.0
	v_rcp_f32_e32 v250, v248
	v_rcp_f32_e32 v251, v249
	s_nop 0
	v_pk_fma_f32 v[252:253], v[248:249], v[250:251], 1.0 op_sel_hi:[1,1,0] neg_lo:[1,0,0] neg_hi:[1,0,0]
	v_pk_fma_f32 v[250:251], v[252:253], v[250:251], v[250:251]
	v_pk_fma_f32 v[252:253], v[248:249], v[250:251], 1.0 op_sel_hi:[1,1,0] neg_lo:[1,0,0] neg_hi:[1,0,0]
	v_pk_fma_f32 v[254:255], v[252:253], v[250:251], v[250:251]
	v_pk_fma_f32 v[252:253], v[248:249], v[254:255], 1.0 op_sel_hi:[1,1,0] neg_lo:[1,0,0] neg_hi:[1,0,0]
	v_pk_fma_f32 v[254:255], v[252:253], v[250:251], v[254:255]
	v_div_fixup_f32 v248, v254, v248, 1.0
	v_div_fixup_f32 v249, v255, v249, 1.0
	v_and_b32_e32 v155, 0xffff0000, v124
	v_lshlrev_b32_e32 v152, 16, v122
	v_and_b32_e32 v153, 0xffff0000, v122
	v_lshlrev_b32_e32 v154, 16, v124
	v_lshlrev_b32_e32 v124, 16, v125
	v_and_b32_e32 v125, 0xffff0000, v125
	v_lshlrev_b32_e32 v122, 16, v123
	v_and_b32_e32 v123, 0xffff0000, v123
	v_pk_fma_f32 v[108:109], v[108:109], v[242:243], v[152:153]
	v_pk_fma_f32 v[118:119], v[106:107], v[248:249], v[124:125]
	v_pk_fma_f32 v[106:107], v[104:105], v[244:245], v[154:155]
	v_add_lshl_u32 v120, v146, v114, 1
	v_pk_fma_f32 v[110:111], v[110:111], v[246:247], v[122:123]
	v_cvt_pk_bf16_f32 v104, v108, v109
	s_nop 0
	v_cvt_pk_bf16_f32 v105, v110, v111
	v_cvt_pk_bf16_f32 v106, v106, v107
	v_cvt_pk_bf16_f32 v107, v118, v119
	buffer_store_dwordx4 v[104:107], v120, s[20:23], 0 offen sc1
	s_nop 0
	s_waitcnt vmcnt(7)
; __device__ __forceinline__ float sigmoidf_(float x) { return 1.0f / (1.0f + __expf(-x)); }
; __device__ __forceinline__ u32x4 pack8(const f32x4 v0, const f32x4 v1) { u32x4 w; w.x = pk2(v0[0], v0[1]); w.y = pk2(v0[2], v0[3]); w.z = pk2(v1[0], v1[1]); w.w = pk2(v1[2], v1[3]); return w; }
; __device__ __forceinline__ void unpack8(const u32x4 w, f32x4& v0, f32x4& v1) { v0 = (f32x4){bflo(w.x), bfhi(w.x), bflo(w.y), bfhi(w.y)}; v1 = (f32x4){bflo(w.z), bfhi(w.z), bflo(w.w), bfhi(w.w)}; }
;     __device__ __forceinline__ void operator()(const f32x4 (&acc)[2][2][4][2], const Unit& u, int wr, int wc, int fr, int fq) const {
;     ...
;         for (int ai = 0; ai < 2; ++ai)
; #pragma unroll
;             for (int m = 0; m < 4; ++m) {
;                 const int row = row0 + ai * 128 + m * 16;
;                 const bf16_t* rowp = z + (size_t)row * DIN + col0;
; #pragma unroll
;                 for (int bj = 0; bj < 2; ++bj) {
;                     const u32x4 gw = *(const u32x4*)(rowp + O_GA + bj * 128);
;                     f32x4 g0, g1; unpack8(gw, g0, g1);
;                     f32x4 v0, v1;
; #pragma unroll
;                     for (int j = 0; j < 4; ++j) { v0[j] = sigmoidf_(g0[j]) * acc[ai][bj][m][0][j]; v1[j] = sigmoidf_(g1[j]) * acc[ai][bj][m][1][j]; }
;                     const u32x4 mw = *(const u32x4*)(rowp + bj * 128); f32x4 m0, m1; unpack8(mw, m0, m1); v0 += m0; v1 += m1;
;                     __builtin_amdgcn_raw_buffer_store_b128(pack8(v0, v1), rsrc, (unsigned)(((size_t)row * DIN + col0 + bj * 128) * 2), 0, 16  ); }
	v_mov_b64_e32 v[104:105], v[204:205]
	v_mov_b64_e32 v[106:107], v[206:207]
	v_mov_b64_e32 v[108:109], v[208:209]
	v_mov_b64_e32 v[110:111], v[210:211]
	v_add_u32_e32 v202, 0x67200, v201
	global_load_dwordx4 v[204:207], v202, s[36:37]
	v_add_u32_e32 v202, 0x66000, v201
	global_load_dwordx4 v[208:211], v202, s[36:37]
	s_mov_b32 s100, 0xbfb8aa3b
	v_lshlrev_b32_e32 v242, 16, v106
	v_and_b32_e32 v243, 0xffff0000, v106
	v_lshlrev_b32_e32 v244, 16, v104
	v_and_b32_e32 v245, 0xffff0000, v104
	v_lshlrev_b32_e32 v246, 16, v105
	v_and_b32_e32 v247, 0xffff0000, v105
	v_lshlrev_b32_e32 v248, 16, v107
	v_and_b32_e32 v249, 0xffff0000, v107
	v_pk_mul_f32 v[242:243], v[242:243], s[100:101] op_sel_hi:[1,0]
	v_pk_mul_f32 v[244:245], v[244:245], s[100:101] op_sel_hi:[1,0]
	v_pk_mul_f32 v[246:247], v[246:247], s[100:101] op_sel_hi:[1,0]
	v_pk_mul_f32 v[248:249], v[248:249], s[100:101] op_sel_hi:[1,0]
	v_exp_f32_e32 v242, v242
	v_exp_f32_e32 v243, v243
	v_exp_f32_e32 v244, v244
	v_exp_f32_e32 v245, v245
	v_exp_f32_e32 v246, v246
	v_exp_f32_e32 v247, v247
	v_exp_f32_e32 v248, v248
	v_exp_f32_e32 v249, v249
	s_nop 0
	v_pk_add_f32 v[242:243], v[242:243], 1.0 op_sel_hi:[1,0]
	v_pk_add_f32 v[244:245], v[244:245], 1.0 op_sel_hi:[1,0]
	v_pk_add_f32 v[246:247], v[246:247], 1.0 op_sel_hi:[1,0]
	v_pk_add_f32 v[248:249], v[248:249], 1.0 op_sel_hi:[1,0]
	v_rcp_f32_e32 v250, v242
	v_rcp_f32_e32 v251, v243
	s_nop 0
	v_pk_fma_f32 v[252:253], v[242:243], v[250:251], 1.0 op_sel_hi:[1,1,0] neg_lo:[1,0,0] neg_hi:[1,0,0]
	v_pk_fma_f32 v[250:251], v[252:253], v[250:251], v[250:251]
	v_pk_fma_f32 v[252:253], v[242:243], v[250:251], 1.0 op_sel_hi:[1,1,0] neg_lo:[1,0,0] neg_hi:[1,0,0]
	v_pk_fma_f32 v[254:255], v[252:253], v[250:251], v[250:251]
	v_pk_fma_f32 v[252:253], v[242:243], v[254:255], 1.0 op_sel_hi:[1,1,0] neg_lo:[1,0,0] neg_hi:[1,0,0]
	v_pk_fma_f32 v[254:255], v[252:253], v[250:251], v[254:255]
	v_div_fixup_f32 v242, v254, v242, 1.0
	v_div_fixup_f32 v243, v255, v243, 1.0
	v_rcp_f32_e32 v250, v244
	v_rcp_f32_e32 v251, v245
	s_nop 0
	v_pk_fma_f32 v[252:253], v[244:245], v[250:251], 1.0 op_sel_hi:[1,1,0] neg_lo:[1,0,0] neg_hi:[1,0,0]
	v_pk_fma_f32 v[250:251], v[252:253], v[250:251], v[250:251]
	v_pk_fma_f32 v[252:253], v[244:245], v[250:251], 1.0 op_sel_hi:[1,1,0] neg_lo:[1,0,0] neg_hi:[1,0,0]
	v_pk_fma_f32 v[254:255], v[252:253], v[250:251], v[250:251]
	v_pk_fma_f32 v[252:253], v[244:245], v[254:255], 1.0 op_sel_hi:[1,1,0] neg_lo:[1,0,0] neg_hi:[1,0,0]
	v_pk_fma_f32 v[254:255], v[252:253], v[250:251], v[254:255]
	v_div_fixup_f32 v244, v254, v244, 1.0
	v_div_fixup_f32 v245, v255, v245, 1.0
	v_rcp_f32_e32 v250, v246
	v_rcp_f32_e32 v251, v247
	s_nop 0
	v_pk_fma_f32 v[252:253], v[246:247], v[250:251], 1.0 op_sel_hi:[1,1,0] neg_lo:[1,0,0] neg_hi:[1,0,0]
	v_pk_fma_f32 v[250:251], v[252:253], v[250:251], v[250:251]
	v_pk_fma_f32 v[252:253], v[246:247], v[250:251], 1.0 op_sel_hi:[1,1,0] neg_lo:[1,0,0] neg_hi:[1,0,0]
	v_pk_fma_f32 v[254:255], v[252:253], v[250:251], v[250:251]
	v_pk_fma_f32 v[252:253], v[246:247], v[254:255], 1.0 op_sel_hi:[1,1,0] neg_lo:[1,0,0] neg_hi:[1,0,0]
	v_pk_fma_f32 v[254:255], v[252:253], v[250:251], v[254:255]
	v_div_fixup_f32 v246, v254, v246, 1.0
	v_div_fixup_f32 v247, v255, v247, 1.0
	v_rcp_f32_e32 v250, v248
	v_rcp_f32_e32 v251, v249
	s_nop 0
	v_pk_fma_f32 v[252:253], v[248:249], v[250:251], 1.0 op_sel_hi:[1,1,0] neg_lo:[1,0,0] neg_hi:[1,0,0]
	v_pk_fma_f32 v[250:251], v[252:253], v[250:251], v[250:251]
	v_pk_fma_f32 v[252:253], v[248:249], v[250:251], 1.0 op_sel_hi:[1,1,0] neg_lo:[1,0,0] neg_hi:[1,0,0]
	v_pk_fma_f32 v[254:255], v[252:253], v[250:251], v[250:251]
	v_pk_fma_f32 v[252:253], v[248:249], v[254:255], 1.0 op_sel_hi:[1,1,0] neg_lo:[1,0,0] neg_hi:[1,0,0]
	v_pk_fma_f32 v[254:255], v[252:253], v[250:251], v[254:255]
	v_div_fixup_f32 v248, v254, v248, 1.0
	v_div_fixup_f32 v249, v255, v249, 1.0
	v_lshlrev_b32_e32 v116, 16, v108
	v_and_b32_e32 v117, 0xffff0000, v108
	v_lshlrev_b32_e32 v118, 16, v110
	v_and_b32_e32 v119, 0xffff0000, v110
	v_lshlrev_b32_e32 v110, 16, v111
	v_and_b32_e32 v111, 0xffff0000, v111
	v_lshlrev_b32_e32 v108, 16, v109
	v_and_b32_e32 v109, 0xffff0000, v109
	v_pk_fma_f32 v[100:101], v[100:101], v[244:245], v[116:117]
	v_pk_fma_f32 v[104:105], v[98:99], v[248:249], v[110:111]
	v_pk_fma_f32 v[98:99], v[96:97], v[242:243], v[118:119]
	v_cvt_pk_bf16_f32 v96, v100, v101
	v_pk_fma_f32 v[102:103], v[102:103], v[246:247], v[108:109]
	s_nop 0
	v_cvt_pk_bf16_f32 v97, v102, v103
	v_cvt_pk_bf16_f32 v98, v98, v99
	v_cvt_pk_bf16_f32 v99, v104, v105
	buffer_store_dwordx4 v[96:99], v120, s[20:23], 0 offen offset:256 sc1
	s_nop 1
	v_or_b32_e32 v96, 32, v162
	v_mad_i64_i32 v[98:99], s[6:7], v96, s73, 0
	v_lshl_add_u64 v[96:97], v[98:99], 1, s[36:37]
	v_lshl_add_u64 v[96:97], v[96:97], 0, v[148:149]
	v_add_co_u32_e32 v100, vcc, s74, v96
	s_nop 1
	v_addc_co_u32_e32 v101, vcc, 0, v97, vcc
	s_waitcnt vmcnt(7)
; __device__ __forceinline__ float sigmoidf_(float x) { return 1.0f / (1.0f + __expf(-x)); }
; __device__ __forceinline__ u32x4 pack8(const f32x4 v0, const f32x4 v1) { u32x4 w; w.x = pk2(v0[0], v0[1]); w.y = pk2(v0[2], v0[3]); w.z = pk2(v1[0], v1[1]); w.w = pk2(v1[2], v1[3]); return w; }
; __device__ __forceinline__ void unpack8(const u32x4 w, f32x4& v0, f32x4& v1) { v0 = (f32x4){bflo(w.x), bfhi(w.x), bflo(w.y), bfhi(w.y)}; v1 = (f32x4){bflo(w.z), bfhi(w.z), bflo(w.w), bfhi(w.w)}; }
;     __device__ __forceinline__ void operator()(const f32x4 (&acc)[2][2][4][2], const Unit& u, int wr, int wc, int fr, int fq) const {
;     ...
;         for (int ai = 0; ai < 2; ++ai)
; #pragma unroll
;             for (int m = 0; m < 4; ++m) {
;                 const int row = row0 + ai * 128 + m * 16;
;                 const bf16_t* rowp = z + (size_t)row * DIN + col0;
; #pragma unroll
;                 for (int bj = 0; bj < 2; ++bj) {
;                     const u32x4 gw = *(const u32x4*)(rowp + O_GA + bj * 128);
;                     f32x4 g0, g1; unpack8(gw, g0, g1);
;                     f32x4 v0, v1;
; #pragma unroll
;                     for (int j = 0; j < 4; ++j) { v0[j] = sigmoidf_(g0[j]) * acc[ai][bj][m][0][j]; v1[j] = sigmoidf_(g1[j]) * acc[ai][bj][m][1][j]; }
;                     const u32x4 mw = *(const u32x4*)(rowp + bj * 128); f32x4 m0, m1; unpack8(mw, m0, m1); v0 += m0; v1 += m1;
;                     __builtin_amdgcn_raw_buffer_store_b128(pack8(v0, v1), rsrc, (unsigned)(((size_t)row * DIN + col0 + bj * 128) * 2), 0, 16  ); }
	v_mov_b64_e32 v[102:103], v[212:213]
	v_mov_b64_e32 v[104:105], v[214:215]
	v_mov_b64_e32 v[106:107], v[216:217]
	v_mov_b64_e32 v[108:109], v[218:219]
	v_add_u32_e32 v202, 0x67300, v201
	global_load_dwordx4 v[212:215], v202, s[36:37]
	v_add_u32_e32 v202, 0x66100, v201
	global_load_dwordx4 v[216:219], v202, s[36:37]
	s_mov_b32 s100, 0xbfb8aa3b
	v_lshlrev_b32_e32 v242, 16, v102
	v_and_b32_e32 v243, 0xffff0000, v102
	v_lshlrev_b32_e32 v244, 16, v104
	v_and_b32_e32 v245, 0xffff0000, v104
	v_lshlrev_b32_e32 v246, 16, v103
	v_and_b32_e32 v247, 0xffff0000, v103
	v_lshlrev_b32_e32 v248, 16, v105
	v_and_b32_e32 v249, 0xffff0000, v105
	v_pk_mul_f32 v[242:243], v[242:243], s[100:101] op_sel_hi:[1,0]
	v_pk_mul_f32 v[244:245], v[244:245], s[100:101] op_sel_hi:[1,0]
	v_pk_mul_f32 v[246:247], v[246:247], s[100:101] op_sel_hi:[1,0]
	v_pk_mul_f32 v[248:249], v[248:249], s[100:101] op_sel_hi:[1,0]
	v_exp_f32_e32 v242, v242
	v_exp_f32_e32 v243, v243
	v_exp_f32_e32 v244, v244
	v_exp_f32_e32 v245, v245
	v_exp_f32_e32 v246, v246
	v_exp_f32_e32 v247, v247
	v_exp_f32_e32 v248, v248
	v_exp_f32_e32 v249, v249
	s_nop 0
	v_pk_add_f32 v[242:243], v[242:243], 1.0 op_sel_hi:[1,0]
	v_pk_add_f32 v[244:245], v[244:245], 1.0 op_sel_hi:[1,0]
	v_pk_add_f32 v[246:247], v[246:247], 1.0 op_sel_hi:[1,0]
	v_pk_add_f32 v[248:249], v[248:249], 1.0 op_sel_hi:[1,0]
	v_rcp_f32_e32 v250, v242
	v_rcp_f32_e32 v251, v243
	s_nop 0
	v_pk_fma_f32 v[252:253], v[242:243], v[250:251], 1.0 op_sel_hi:[1,1,0] neg_lo:[1,0,0] neg_hi:[1,0,0]
	v_pk_fma_f32 v[250:251], v[252:253], v[250:251], v[250:251]
	v_pk_fma_f32 v[252:253], v[242:243], v[250:251], 1.0 op_sel_hi:[1,1,0] neg_lo:[1,0,0] neg_hi:[1,0,0]
	v_pk_fma_f32 v[254:255], v[252:253], v[250:251], v[250:251]
	v_pk_fma_f32 v[252:253], v[242:243], v[254:255], 1.0 op_sel_hi:[1,1,0] neg_lo:[1,0,0] neg_hi:[1,0,0]
	v_pk_fma_f32 v[254:255], v[252:253], v[250:251], v[254:255]
	v_div_fixup_f32 v242, v254, v242, 1.0
	v_div_fixup_f32 v243, v255, v243, 1.0
	v_rcp_f32_e32 v250, v244
	v_rcp_f32_e32 v251, v245
	s_nop 0
	v_pk_fma_f32 v[252:253], v[244:245], v[250:251], 1.0 op_sel_hi:[1,1,0] neg_lo:[1,0,0] neg_hi:[1,0,0]
	v_pk_fma_f32 v[250:251], v[252:253], v[250:251], v[250:251]
	v_pk_fma_f32 v[252:253], v[244:245], v[250:251], 1.0 op_sel_hi:[1,1,0] neg_lo:[1,0,0] neg_hi:[1,0,0]
	v_pk_fma_f32 v[254:255], v[252:253], v[250:251], v[250:251]
	v_pk_fma_f32 v[252:253], v[244:245], v[254:255], 1.0 op_sel_hi:[1,1,0] neg_lo:[1,0,0] neg_hi:[1,0,0]
	v_pk_fma_f32 v[254:255], v[252:253], v[250:251], v[254:255]
	v_div_fixup_f32 v244, v254, v244, 1.0
	v_div_fixup_f32 v245, v255, v245, 1.0
	v_rcp_f32_e32 v250, v246
	v_rcp_f32_e32 v251, v247
	s_nop 0
	v_pk_fma_f32 v[252:253], v[246:247], v[250:251], 1.0 op_sel_hi:[1,1,0] neg_lo:[1,0,0] neg_hi:[1,0,0]
	v_pk_fma_f32 v[250:251], v[252:253], v[250:251], v[250:251]
	v_pk_fma_f32 v[252:253], v[246:247], v[250:251], 1.0 op_sel_hi:[1,1,0] neg_lo:[1,0,0] neg_hi:[1,0,0]
	v_pk_fma_f32 v[254:255], v[252:253], v[250:251], v[250:251]
	v_pk_fma_f32 v[252:253], v[246:247], v[254:255], 1.0 op_sel_hi:[1,1,0] neg_lo:[1,0,0] neg_hi:[1,0,0]
	v_pk_fma_f32 v[254:255], v[252:253], v[250:251], v[254:255]
	v_div_fixup_f32 v246, v254, v246, 1.0
	v_div_fixup_f32 v247, v255, v247, 1.0
	v_rcp_f32_e32 v250, v248
	v_rcp_f32_e32 v251, v249
	s_nop 0
	v_pk_fma_f32 v[252:253], v[248:249], v[250:251], 1.0 op_sel_hi:[1,1,0] neg_lo:[1,0,0] neg_hi:[1,0,0]
	v_pk_fma_f32 v[250:251], v[252:253], v[250:251], v[250:251]
	v_pk_fma_f32 v[252:253], v[248:249], v[250:251], 1.0 op_sel_hi:[1,1,0] neg_lo:[1,0,0] neg_hi:[1,0,0]
	v_pk_fma_f32 v[254:255], v[252:253], v[250:251], v[250:251]
	v_pk_fma_f32 v[252:253], v[248:249], v[254:255], 1.0 op_sel_hi:[1,1,0] neg_lo:[1,0,0] neg_hi:[1,0,0]
	v_pk_fma_f32 v[254:255], v[252:253], v[250:251], v[254:255]
	v_div_fixup_f32 v248, v254, v248, 1.0
	v_div_fixup_f32 v249, v255, v249, 1.0
	v_lshlrev_b32_e32 v114, 16, v106
	v_and_b32_e32 v115, 0xffff0000, v106
	v_lshlrev_b32_e32 v116, 16, v108
	v_and_b32_e32 v117, 0xffff0000, v108
	v_lshlrev_b32_e32 v108, 16, v109
	v_and_b32_e32 v109, 0xffff0000, v109
	v_lshlrev_b32_e32 v106, 16, v107
	v_and_b32_e32 v107, 0xffff0000, v107
	v_pk_fma_f32 v[92:93], v[92:93], v[242:243], v[114:115]
	v_pk_fma_f32 v[102:103], v[90:91], v[248:249], v[108:109]
	v_pk_fma_f32 v[90:91], v[88:89], v[244:245], v[116:117]
	v_add_lshl_u32 v104, v146, v98, 1
	v_pk_fma_f32 v[94:95], v[94:95], v[246:247], v[106:107]
	v_cvt_pk_bf16_f32 v88, v92, v93
	s_nop 0
	v_cvt_pk_bf16_f32 v89, v94, v95
	v_cvt_pk_bf16_f32 v90, v90, v91
	v_cvt_pk_bf16_f32 v91, v102, v103
	buffer_store_dwordx4 v[88:91], v104, s[20:23], 0 offen sc1
	s_nop 0
	s_waitcnt vmcnt(7)
; __device__ __forceinline__ float sigmoidf_(float x) { return 1.0f / (1.0f + __expf(-x)); }
; __device__ __forceinline__ u32x4 pack8(const f32x4 v0, const f32x4 v1) { u32x4 w; w.x = pk2(v0[0], v0[1]); w.y = pk2(v0[2], v0[3]); w.z = pk2(v1[0], v1[1]); w.w = pk2(v1[2], v1[3]); return w; }
; __device__ __forceinline__ void unpack8(const u32x4 w, f32x4& v0, f32x4& v1) { v0 = (f32x4){bflo(w.x), bfhi(w.x), bflo(w.y), bfhi(w.y)}; v1 = (f32x4){bflo(w.z), bfhi(w.z), bflo(w.w), bfhi(w.w)}; }
;     __device__ __forceinline__ void operator()(const f32x4 (&acc)[2][2][4][2], const Unit& u, int wr, int wc, int fr, int fq) const {
;     ...
;                 const int row = row0 + ai * 128 + m * 16;
;                 const bf16_t* rowp = z + (size_t)row * DIN + col0;
; #pragma unroll
;                 for (int bj = 0; bj < 2; ++bj) {
;                     const u32x4 gw = *(const u32x4*)(rowp + O_GA + bj * 128);
;                     f32x4 g0, g1; unpack8(gw, g0, g1);
;                     f32x4 v0, v1;
; #pragma unroll
;                     for (int j = 0; j < 4; ++j) { v0[j] = sigmoidf_(g0[j]) * acc[ai][bj][m][0][j]; v1[j] = sigmoidf_(g1[j]) * acc[ai][bj][m][1][j]; }
;                     const u32x4 mw = *(const u32x4*)(rowp + bj * 128); f32x4 m0, m1; unpack8(mw, m0, m1); v0 += m0; v1 += m1;
;                     __builtin_amdgcn_raw_buffer_store_b128(pack8(v0, v1), rsrc, (unsigned)(((size_t)row * DIN + col0 + bj * 128) * 2), 0, 16  ); }
	v_mov_b64_e32 v[88:89], v[232:233]
	v_mov_b64_e32 v[90:91], v[234:235]
	v_mov_b64_e32 v[92:93], v[236:237]
	v_mov_b64_e32 v[94:95], v[238:239]
	v_add_u32_e32 v202, 0x111200, v201
	global_load_dwordx4 v[232:235], v202, s[36:37]
	v_add_u32_e32 v202, 0x110000, v201
	global_load_dwordx4 v[236:239], v202, s[36:37]
	s_mov_b32 s100, 0xbfb8aa3b
	v_lshlrev_b32_e32 v242, 16, v90
	v_and_b32_e32 v243, 0xffff0000, v90
	v_lshlrev_b32_e32 v244, 16, v88
	v_and_b32_e32 v245, 0xffff0000, v88
	v_lshlrev_b32_e32 v246, 16, v89
	v_and_b32_e32 v247, 0xffff0000, v89
	v_lshlrev_b32_e32 v248, 16, v91
	v_and_b32_e32 v249, 0xffff0000, v91
	v_pk_mul_f32 v[242:243], v[242:243], s[100:101] op_sel_hi:[1,0]
	v_pk_mul_f32 v[244:245], v[244:245], s[100:101] op_sel_hi:[1,0]
	v_pk_mul_f32 v[246:247], v[246:247], s[100:101] op_sel_hi:[1,0]
	v_pk_mul_f32 v[248:249], v[248:249], s[100:101] op_sel_hi:[1,0]
	v_exp_f32_e32 v242, v242
	v_exp_f32_e32 v243, v243
	v_exp_f32_e32 v244, v244
	v_exp_f32_e32 v245, v245
	v_exp_f32_e32 v246, v246
	v_exp_f32_e32 v247, v247
	v_exp_f32_e32 v248, v248
	v_exp_f32_e32 v249, v249
	s_nop 0
	v_pk_add_f32 v[242:243], v[242:243], 1.0 op_sel_hi:[1,0]
	v_pk_add_f32 v[244:245], v[244:245], 1.0 op_sel_hi:[1,0]
	v_pk_add_f32 v[246:247], v[246:247], 1.0 op_sel_hi:[1,0]
	v_pk_add_f32 v[248:249], v[248:249], 1.0 op_sel_hi:[1,0]
	v_rcp_f32_e32 v250, v242
	v_rcp_f32_e32 v251, v243
	s_nop 0
	v_pk_fma_f32 v[252:253], v[242:243], v[250:251], 1.0 op_sel_hi:[1,1,0] neg_lo:[1,0,0] neg_hi:[1,0,0]
	v_pk_fma_f32 v[250:251], v[252:253], v[250:251], v[250:251]
	v_pk_fma_f32 v[252:253], v[242:243], v[250:251], 1.0 op_sel_hi:[1,1,0] neg_lo:[1,0,0] neg_hi:[1,0,0]
	v_pk_fma_f32 v[254:255], v[252:253], v[250:251], v[250:251]
	v_pk_fma_f32 v[252:253], v[242:243], v[254:255], 1.0 op_sel_hi:[1,1,0] neg_lo:[1,0,0] neg_hi:[1,0,0]
	v_pk_fma_f32 v[254:255], v[252:253], v[250:251], v[254:255]
	v_div_fixup_f32 v242, v254, v242, 1.0
	v_div_fixup_f32 v243, v255, v243, 1.0
	v_rcp_f32_e32 v250, v244
	v_rcp_f32_e32 v251, v245
	s_nop 0
	v_pk_fma_f32 v[252:253], v[244:245], v[250:251], 1.0 op_sel_hi:[1,1,0] neg_lo:[1,0,0] neg_hi:[1,0,0]
	v_pk_fma_f32 v[250:251], v[252:253], v[250:251], v[250:251]
	v_pk_fma_f32 v[252:253], v[244:245], v[250:251], 1.0 op_sel_hi:[1,1,0] neg_lo:[1,0,0] neg_hi:[1,0,0]
	v_pk_fma_f32 v[254:255], v[252:253], v[250:251], v[250:251]
	v_pk_fma_f32 v[252:253], v[244:245], v[254:255], 1.0 op_sel_hi:[1,1,0] neg_lo:[1,0,0] neg_hi:[1,0,0]
	v_pk_fma_f32 v[254:255], v[252:253], v[250:251], v[254:255]
	v_div_fixup_f32 v244, v254, v244, 1.0
	v_div_fixup_f32 v245, v255, v245, 1.0
	v_rcp_f32_e32 v250, v246
	v_rcp_f32_e32 v251, v247
	s_nop 0
	v_pk_fma_f32 v[252:253], v[246:247], v[250:251], 1.0 op_sel_hi:[1,1,0] neg_lo:[1,0,0] neg_hi:[1,0,0]
	v_pk_fma_f32 v[250:251], v[252:253], v[250:251], v[250:251]
	v_pk_fma_f32 v[252:253], v[246:247], v[250:251], 1.0 op_sel_hi:[1,1,0] neg_lo:[1,0,0] neg_hi:[1,0,0]
	v_pk_fma_f32 v[254:255], v[252:253], v[250:251], v[250:251]
	v_pk_fma_f32 v[252:253], v[246:247], v[254:255], 1.0 op_sel_hi:[1,1,0] neg_lo:[1,0,0] neg_hi:[1,0,0]
	v_pk_fma_f32 v[254:255], v[252:253], v[250:251], v[254:255]
	v_div_fixup_f32 v246, v254, v246, 1.0
	v_div_fixup_f32 v247, v255, v247, 1.0
	v_rcp_f32_e32 v250, v248
	v_rcp_f32_e32 v251, v249
	s_nop 0
	v_pk_fma_f32 v[252:253], v[248:249], v[250:251], 1.0 op_sel_hi:[1,1,0] neg_lo:[1,0,0] neg_hi:[1,0,0]
	v_pk_fma_f32 v[250:251], v[252:253], v[250:251], v[250:251]
	v_pk_fma_f32 v[252:253], v[248:249], v[250:251], 1.0 op_sel_hi:[1,1,0] neg_lo:[1,0,0] neg_hi:[1,0,0]
	v_pk_fma_f32 v[254:255], v[252:253], v[250:251], v[250:251]
	v_pk_fma_f32 v[252:253], v[248:249], v[254:255], 1.0 op_sel_hi:[1,1,0] neg_lo:[1,0,0] neg_hi:[1,0,0]
	v_pk_fma_f32 v[254:255], v[252:253], v[250:251], v[254:255]
	v_div_fixup_f32 v248, v254, v248, 1.0
	v_div_fixup_f32 v249, v255, v249, 1.0
	v_lshlrev_b32_e32 v100, 16, v92
	v_and_b32_e32 v101, 0xffff0000, v92
	v_lshlrev_b32_e32 v102, 16, v94
	v_and_b32_e32 v103, 0xffff0000, v94
	v_lshlrev_b32_e32 v94, 16, v95
	v_and_b32_e32 v95, 0xffff0000, v95
	v_lshlrev_b32_e32 v92, 16, v93
	v_and_b32_e32 v93, 0xffff0000, v93
	v_pk_fma_f32 v[84:85], v[84:85], v[244:245], v[100:101]
	v_pk_fma_f32 v[88:89], v[82:83], v[248:249], v[94:95]
	v_pk_fma_f32 v[82:83], v[80:81], v[242:243], v[102:103]
	v_cvt_pk_bf16_f32 v80, v84, v85
	v_pk_fma_f32 v[86:87], v[86:87], v[246:247], v[92:93]
	s_nop 0
	v_cvt_pk_bf16_f32 v81, v86, v87
	v_cvt_pk_bf16_f32 v82, v82, v83
	v_cvt_pk_bf16_f32 v83, v88, v89
	buffer_store_dwordx4 v[80:83], v104, s[20:23], 0 offen offset:256 sc1
	s_nop 1
	v_or_b32_e32 v80, 48, v162
	v_mad_i64_i32 v[82:83], s[6:7], v80, s73, 0
	v_lshl_add_u64 v[80:81], v[82:83], 1, s[36:37]
	v_lshl_add_u64 v[80:81], v[80:81], 0, v[148:149]
	v_add_co_u32_e32 v84, vcc, s74, v80
	s_nop 1
	v_addc_co_u32_e32 v85, vcc, 0, v81, vcc
	s_waitcnt vmcnt(7)
; __device__ __forceinline__ float sigmoidf_(float x) { return 1.0f / (1.0f + __expf(-x)); }
; __device__ __forceinline__ u32x4 pack8(const f32x4 v0, const f32x4 v1) { u32x4 w; w.x = pk2(v0[0], v0[1]); w.y = pk2(v0[2], v0[3]); w.z = pk2(v1[0], v1[1]); w.w = pk2(v1[2], v1[3]); return w; }
; __device__ __forceinline__ void unpack8(const u32x4 w, f32x4& v0, f32x4& v1) { v0 = (f32x4){bflo(w.x), bfhi(w.x), bflo(w.y), bfhi(w.y)}; v1 = (f32x4){bflo(w.z), bfhi(w.z), bflo(w.w), bfhi(w.w)}; }
;     __device__ __forceinline__ void operator()(const f32x4 (&acc)[2][2][4][2], const Unit& u, int wr, int wc, int fr, int fq) const {
;     ...
;                 const int row = row0 + ai * 128 + m * 16;
;                 const bf16_t* rowp = z + (size_t)row * DIN + col0;
; #pragma unroll
;                 for (int bj = 0; bj < 2; ++bj) {
;                     const u32x4 gw = *(const u32x4*)(rowp + O_GA + bj * 128);
;                     f32x4 g0, g1; unpack8(gw, g0, g1);
;                     f32x4 v0, v1;
; #pragma unroll
;                     for (int j = 0; j < 4; ++j) { v0[j] = sigmoidf_(g0[j]) * acc[ai][bj][m][0][j]; v1[j] = sigmoidf_(g1[j]) * acc[ai][bj][m][1][j]; }
;                     const u32x4 mw = *(const u32x4*)(rowp + bj * 128); f32x4 m0, m1; unpack8(mw, m0, m1); v0 += m0; v1 += m1;
;                     __builtin_amdgcn_raw_buffer_store_b128(pack8(v0, v1), rsrc, (unsigned)(((size_t)row * DIN + col0 + bj * 128) * 2), 0, 16  ); }
	v_mov_b64_e32 v[86:87], v[204:205]
	v_mov_b64_e32 v[88:89], v[206:207]
	v_mov_b64_e32 v[90:91], v[208:209]
	v_mov_b64_e32 v[92:93], v[210:211]
	v_add_u32_e32 v202, 0x111300, v201
	global_load_dwordx4 v[204:207], v202, s[36:37]
	v_add_u32_e32 v202, 0x110100, v201
	global_load_dwordx4 v[208:211], v202, s[36:37]
	s_mov_b32 s100, 0xbfb8aa3b
	v_lshlrev_b32_e32 v242, 16, v86
	v_and_b32_e32 v243, 0xffff0000, v86
	v_lshlrev_b32_e32 v244, 16, v88
	v_and_b32_e32 v245, 0xffff0000, v88
	v_lshlrev_b32_e32 v246, 16, v87
	v_and_b32_e32 v247, 0xffff0000, v87
	v_lshlrev_b32_e32 v248, 16, v89
	v_and_b32_e32 v249, 0xffff0000, v89
	v_pk_mul_f32 v[242:243], v[242:243], s[100:101] op_sel_hi:[1,0]
	v_pk_mul_f32 v[244:245], v[244:245], s[100:101] op_sel_hi:[1,0]
	v_pk_mul_f32 v[246:247], v[246:247], s[100:101] op_sel_hi:[1,0]
	v_pk_mul_f32 v[248:249], v[248:249], s[100:101] op_sel_hi:[1,0]
	v_exp_f32_e32 v242, v242
	v_exp_f32_e32 v243, v243
	v_exp_f32_e32 v244, v244
	v_exp_f32_e32 v245, v245
	v_exp_f32_e32 v246, v246
	v_exp_f32_e32 v247, v247
	v_exp_f32_e32 v248, v248
	v_exp_f32_e32 v249, v249
	s_nop 0
	v_pk_add_f32 v[242:243], v[242:243], 1.0 op_sel_hi:[1,0]
	v_pk_add_f32 v[244:245], v[244:245], 1.0 op_sel_hi:[1,0]
	v_pk_add_f32 v[246:247], v[246:247], 1.0 op_sel_hi:[1,0]
	v_pk_add_f32 v[248:249], v[248:249], 1.0 op_sel_hi:[1,0]
	v_rcp_f32_e32 v250, v242
	v_rcp_f32_e32 v251, v243
	s_nop 0
	v_pk_fma_f32 v[252:253], v[242:243], v[250:251], 1.0 op_sel_hi:[1,1,0] neg_lo:[1,0,0] neg_hi:[1,0,0]
	v_pk_fma_f32 v[250:251], v[252:253], v[250:251], v[250:251]
	v_pk_fma_f32 v[252:253], v[242:243], v[250:251], 1.0 op_sel_hi:[1,1,0] neg_lo:[1,0,0] neg_hi:[1,0,0]
	v_pk_fma_f32 v[254:255], v[252:253], v[250:251], v[250:251]
	v_pk_fma_f32 v[252:253], v[242:243], v[254:255], 1.0 op_sel_hi:[1,1,0] neg_lo:[1,0,0] neg_hi:[1,0,0]
	v_pk_fma_f32 v[254:255], v[252:253], v[250:251], v[254:255]
	v_div_fixup_f32 v242, v254, v242, 1.0
	v_div_fixup_f32 v243, v255, v243, 1.0
	v_rcp_f32_e32 v250, v244
	v_rcp_f32_e32 v251, v245
	s_nop 0
	v_pk_fma_f32 v[252:253], v[244:245], v[250:251], 1.0 op_sel_hi:[1,1,0] neg_lo:[1,0,0] neg_hi:[1,0,0]
	v_pk_fma_f32 v[250:251], v[252:253], v[250:251], v[250:251]
	v_pk_fma_f32 v[252:253], v[244:245], v[250:251], 1.0 op_sel_hi:[1,1,0] neg_lo:[1,0,0] neg_hi:[1,0,0]
	v_pk_fma_f32 v[254:255], v[252:253], v[250:251], v[250:251]
	v_pk_fma_f32 v[252:253], v[244:245], v[254:255], 1.0 op_sel_hi:[1,1,0] neg_lo:[1,0,0] neg_hi:[1,0,0]
	v_pk_fma_f32 v[254:255], v[252:253], v[250:251], v[254:255]
	v_div_fixup_f32 v244, v254, v244, 1.0
	v_div_fixup_f32 v245, v255, v245, 1.0
	v_rcp_f32_e32 v250, v246
	v_rcp_f32_e32 v251, v247
	s_nop 0
	v_pk_fma_f32 v[252:253], v[246:247], v[250:251], 1.0 op_sel_hi:[1,1,0] neg_lo:[1,0,0] neg_hi:[1,0,0]
	v_pk_fma_f32 v[250:251], v[252:253], v[250:251], v[250:251]
	v_pk_fma_f32 v[252:253], v[246:247], v[250:251], 1.0 op_sel_hi:[1,1,0] neg_lo:[1,0,0] neg_hi:[1,0,0]
	v_pk_fma_f32 v[254:255], v[252:253], v[250:251], v[250:251]
	v_pk_fma_f32 v[252:253], v[246:247], v[254:255], 1.0 op_sel_hi:[1,1,0] neg_lo:[1,0,0] neg_hi:[1,0,0]
	v_pk_fma_f32 v[254:255], v[252:253], v[250:251], v[254:255]
	v_div_fixup_f32 v246, v254, v246, 1.0
	v_div_fixup_f32 v247, v255, v247, 1.0
	v_rcp_f32_e32 v250, v248
	v_rcp_f32_e32 v251, v249
	s_nop 0
	v_pk_fma_f32 v[252:253], v[248:249], v[250:251], 1.0 op_sel_hi:[1,1,0] neg_lo:[1,0,0] neg_hi:[1,0,0]
	v_pk_fma_f32 v[250:251], v[252:253], v[250:251], v[250:251]
	v_pk_fma_f32 v[252:253], v[248:249], v[250:251], 1.0 op_sel_hi:[1,1,0] neg_lo:[1,0,0] neg_hi:[1,0,0]
	v_pk_fma_f32 v[254:255], v[252:253], v[250:251], v[250:251]
	v_pk_fma_f32 v[252:253], v[248:249], v[254:255], 1.0 op_sel_hi:[1,1,0] neg_lo:[1,0,0] neg_hi:[1,0,0]
	v_pk_fma_f32 v[254:255], v[252:253], v[250:251], v[254:255]
	v_div_fixup_f32 v248, v254, v248, 1.0
	v_div_fixup_f32 v249, v255, v249, 1.0
	v_lshlrev_b32_e32 v98, 16, v90
	v_and_b32_e32 v99, 0xffff0000, v90
	v_lshlrev_b32_e32 v100, 16, v92
	v_and_b32_e32 v101, 0xffff0000, v92
	v_lshlrev_b32_e32 v92, 16, v93
	v_and_b32_e32 v93, 0xffff0000, v93
	v_lshlrev_b32_e32 v90, 16, v91
	v_and_b32_e32 v91, 0xffff0000, v91
	v_pk_fma_f32 v[76:77], v[76:77], v[242:243], v[98:99]
	v_pk_fma_f32 v[86:87], v[74:75], v[248:249], v[92:93]
	v_pk_fma_f32 v[74:75], v[72:73], v[244:245], v[100:101]
	v_add_lshl_u32 v88, v146, v82, 1
	v_pk_fma_f32 v[78:79], v[78:79], v[246:247], v[90:91]
	v_cvt_pk_bf16_f32 v72, v76, v77
	s_nop 0
	v_cvt_pk_bf16_f32 v73, v78, v79
	v_cvt_pk_bf16_f32 v74, v74, v75
	v_cvt_pk_bf16_f32 v75, v86, v87
	buffer_store_dwordx4 v[72:75], v88, s[20:23], 0 offen sc1
	s_nop 0
	s_waitcnt vmcnt(7)
; __device__ __forceinline__ float sigmoidf_(float x) { return 1.0f / (1.0f + __expf(-x)); }
; __device__ __forceinline__ u32x4 pack8(const f32x4 v0, const f32x4 v1) { u32x4 w; w.x = pk2(v0[0], v0[1]); w.y = pk2(v0[2], v0[3]); w.z = pk2(v1[0], v1[1]); w.w = pk2(v1[2], v1[3]); return w; }
; __device__ __forceinline__ void unpack8(const u32x4 w, f32x4& v0, f32x4& v1) { v0 = (f32x4){bflo(w.x), bfhi(w.x), bflo(w.y), bfhi(w.y)}; v1 = (f32x4){bflo(w.z), bfhi(w.z), bflo(w.w), bfhi(w.w)}; }
;     __device__ __forceinline__ void operator()(const f32x4 (&acc)[2][2][4][2], const Unit& u, int wr, int wc, int fr, int fq) const {
;     ...
;                 const int row = row0 + ai * 128 + m * 16;
;                 const bf16_t* rowp = z + (size_t)row * DIN + col0;
; #pragma unroll
;                 for (int bj = 0; bj < 2; ++bj) {
;                     const u32x4 gw = *(const u32x4*)(rowp + O_GA + bj * 128);
;                     f32x4 g0, g1; unpack8(gw, g0, g1);
;                     f32x4 v0, v1;
; #pragma unroll
;                     for (int j = 0; j < 4; ++j) { v0[j] = sigmoidf_(g0[j]) * acc[ai][bj][m][0][j]; v1[j] = sigmoidf_(g1[j]) * acc[ai][bj][m][1][j]; }
;                     const u32x4 mw = *(const u32x4*)(rowp + bj * 128); f32x4 m0, m1; unpack8(mw, m0, m1); v0 += m0; v1 += m1;
;                     __builtin_amdgcn_raw_buffer_store_b128(pack8(v0, v1), rsrc, (unsigned)(((size_t)row * DIN + col0 + bj * 128) * 2), 0, 16  ); }
	v_mov_b64_e32 v[72:73], v[212:213]
	v_mov_b64_e32 v[74:75], v[214:215]
	v_mov_b64_e32 v[76:77], v[216:217]
	v_mov_b64_e32 v[78:79], v[218:219]
	v_add_u32_e32 v202, 0x133200, v201
	global_load_dwordx4 v[212:215], v202, s[36:37]
	v_add_u32_e32 v202, 0x132000, v201
	global_load_dwordx4 v[216:219], v202, s[36:37]
	s_mov_b32 s100, 0xbfb8aa3b
	v_lshlrev_b32_e32 v242, 16, v74
	v_and_b32_e32 v243, 0xffff0000, v74
	v_lshlrev_b32_e32 v244, 16, v72
	v_and_b32_e32 v245, 0xffff0000, v72
	v_lshlrev_b32_e32 v246, 16, v73
	v_and_b32_e32 v247, 0xffff0000, v73
	v_lshlrev_b32_e32 v248, 16, v75
	v_and_b32_e32 v249, 0xffff0000, v75
	v_pk_mul_f32 v[242:243], v[242:243], s[100:101] op_sel_hi:[1,0]
	v_pk_mul_f32 v[244:245], v[244:245], s[100:101] op_sel_hi:[1,0]
	v_pk_mul_f32 v[246:247], v[246:247], s[100:101] op_sel_hi:[1,0]
	v_pk_mul_f32 v[248:249], v[248:249], s[100:101] op_sel_hi:[1,0]
	v_exp_f32_e32 v242, v242
	v_exp_f32_e32 v243, v243
	v_exp_f32_e32 v244, v244
	v_exp_f32_e32 v245, v245
	v_exp_f32_e32 v246, v246
	v_exp_f32_e32 v247, v247
	v_exp_f32_e32 v248, v248
	v_exp_f32_e32 v249, v249
	s_nop 0
	v_pk_add_f32 v[242:243], v[242:243], 1.0 op_sel_hi:[1,0]
	v_pk_add_f32 v[244:245], v[244:245], 1.0 op_sel_hi:[1,0]
	v_pk_add_f32 v[246:247], v[246:247], 1.0 op_sel_hi:[1,0]
	v_pk_add_f32 v[248:249], v[248:249], 1.0 op_sel_hi:[1,0]
	v_rcp_f32_e32 v250, v242
	v_rcp_f32_e32 v251, v243
	s_nop 0
	v_pk_fma_f32 v[252:253], v[242:243], v[250:251], 1.0 op_sel_hi:[1,1,0] neg_lo:[1,0,0] neg_hi:[1,0,0]
	v_pk_fma_f32 v[250:251], v[252:253], v[250:251], v[250:251]
	v_pk_fma_f32 v[252:253], v[242:243], v[250:251], 1.0 op_sel_hi:[1,1,0] neg_lo:[1,0,0] neg_hi:[1,0,0]
	v_pk_fma_f32 v[254:255], v[252:253], v[250:251], v[250:251]
	v_pk_fma_f32 v[252:253], v[242:243], v[254:255], 1.0 op_sel_hi:[1,1,0] neg_lo:[1,0,0] neg_hi:[1,0,0]
	v_pk_fma_f32 v[254:255], v[252:253], v[250:251], v[254:255]
	v_div_fixup_f32 v242, v254, v242, 1.0
	v_div_fixup_f32 v243, v255, v243, 1.0
	v_rcp_f32_e32 v250, v244
	v_rcp_f32_e32 v251, v245
	s_nop 0
	v_pk_fma_f32 v[252:253], v[244:245], v[250:251], 1.0 op_sel_hi:[1,1,0] neg_lo:[1,0,0] neg_hi:[1,0,0]
	v_pk_fma_f32 v[250:251], v[252:253], v[250:251], v[250:251]
	v_pk_fma_f32 v[252:253], v[244:245], v[250:251], 1.0 op_sel_hi:[1,1,0] neg_lo:[1,0,0] neg_hi:[1,0,0]
	v_pk_fma_f32 v[254:255], v[252:253], v[250:251], v[250:251]
	v_pk_fma_f32 v[252:253], v[244:245], v[254:255], 1.0 op_sel_hi:[1,1,0] neg_lo:[1,0,0] neg_hi:[1,0,0]
	v_pk_fma_f32 v[254:255], v[252:253], v[250:251], v[254:255]
	v_div_fixup_f32 v244, v254, v244, 1.0
	v_div_fixup_f32 v245, v255, v245, 1.0
	v_rcp_f32_e32 v250, v246
	v_rcp_f32_e32 v251, v247
	s_nop 0
	v_pk_fma_f32 v[252:253], v[246:247], v[250:251], 1.0 op_sel_hi:[1,1,0] neg_lo:[1,0,0] neg_hi:[1,0,0]
	v_pk_fma_f32 v[250:251], v[252:253], v[250:251], v[250:251]
	v_pk_fma_f32 v[252:253], v[246:247], v[250:251], 1.0 op_sel_hi:[1,1,0] neg_lo:[1,0,0] neg_hi:[1,0,0]
	v_pk_fma_f32 v[254:255], v[252:253], v[250:251], v[250:251]
	v_pk_fma_f32 v[252:253], v[246:247], v[254:255], 1.0 op_sel_hi:[1,1,0] neg_lo:[1,0,0] neg_hi:[1,0,0]
	v_pk_fma_f32 v[254:255], v[252:253], v[250:251], v[254:255]
	v_div_fixup_f32 v246, v254, v246, 1.0
	v_div_fixup_f32 v247, v255, v247, 1.0
	v_rcp_f32_e32 v250, v248
	v_rcp_f32_e32 v251, v249
	s_nop 0
	v_pk_fma_f32 v[252:253], v[248:249], v[250:251], 1.0 op_sel_hi:[1,1,0] neg_lo:[1,0,0] neg_hi:[1,0,0]
	v_pk_fma_f32 v[250:251], v[252:253], v[250:251], v[250:251]
	v_pk_fma_f32 v[252:253], v[248:249], v[250:251], 1.0 op_sel_hi:[1,1,0] neg_lo:[1,0,0] neg_hi:[1,0,0]
	v_pk_fma_f32 v[254:255], v[252:253], v[250:251], v[250:251]
	v_pk_fma_f32 v[252:253], v[248:249], v[254:255], 1.0 op_sel_hi:[1,1,0] neg_lo:[1,0,0] neg_hi:[1,0,0]
	v_pk_fma_f32 v[254:255], v[252:253], v[250:251], v[254:255]
	v_div_fixup_f32 v248, v254, v248, 1.0
	v_div_fixup_f32 v249, v255, v249, 1.0
	v_lshlrev_b32_e32 v84, 16, v76
	v_and_b32_e32 v85, 0xffff0000, v76
	v_lshlrev_b32_e32 v86, 16, v78
	v_and_b32_e32 v87, 0xffff0000, v78
	v_lshlrev_b32_e32 v78, 16, v79
	v_and_b32_e32 v79, 0xffff0000, v79
	v_lshlrev_b32_e32 v76, 16, v77
	v_and_b32_e32 v77, 0xffff0000, v77
	v_pk_fma_f32 v[68:69], v[68:69], v[244:245], v[84:85]
	v_pk_fma_f32 v[72:73], v[66:67], v[248:249], v[78:79]
	v_pk_fma_f32 v[66:67], v[64:65], v[242:243], v[86:87]
	v_cvt_pk_bf16_f32 v64, v68, v69
	v_pk_fma_f32 v[70:71], v[70:71], v[246:247], v[76:77]
	s_nop 0
	v_cvt_pk_bf16_f32 v65, v70, v71
	v_cvt_pk_bf16_f32 v66, v66, v67
	v_cvt_pk_bf16_f32 v67, v72, v73
	buffer_store_dwordx4 v[64:67], v88, s[20:23], 0 offen offset:256 sc1
	s_nop 1
	v_add_u32_e32 v64, 0x80, v162
	v_mad_i64_i32 v[66:67], s[6:7], v64, s73, 0
	v_lshl_add_u64 v[64:65], v[66:67], 1, s[36:37]
	v_lshl_add_u64 v[64:65], v[64:65], 0, v[148:149]
	v_add_co_u32_e32 v68, vcc, s74, v64
	s_nop 1
	v_addc_co_u32_e32 v69, vcc, 0, v65, vcc
	s_waitcnt vmcnt(7)
; __device__ __forceinline__ float sigmoidf_(float x) { return 1.0f / (1.0f + __expf(-x)); }
; __device__ __forceinline__ u32x4 pack8(const f32x4 v0, const f32x4 v1) { u32x4 w; w.x = pk2(v0[0], v0[1]); w.y = pk2(v0[2], v0[3]); w.z = pk2(v1[0], v1[1]); w.w = pk2(v1[2], v1[3]); return w; }
; __device__ __forceinline__ void unpack8(const u32x4 w, f32x4& v0, f32x4& v1) { v0 = (f32x4){bflo(w.x), bfhi(w.x), bflo(w.y), bfhi(w.y)}; v1 = (f32x4){bflo(w.z), bfhi(w.z), bflo(w.w), bfhi(w.w)}; }
;     __device__ __forceinline__ void operator()(const f32x4 (&acc)[2][2][4][2], const Unit& u, int wr, int wc, int fr, int fq) const {
;     ...
;                 const int row = row0 + ai * 128 + m * 16;
;                 const bf16_t* rowp = z + (size_t)row * DIN + col0;
; #pragma unroll
;                 for (int bj = 0; bj < 2; ++bj) {
;                     const u32x4 gw = *(const u32x4*)(rowp + O_GA + bj * 128);
;                     f32x4 g0, g1; unpack8(gw, g0, g1);
;                     f32x4 v0, v1;
; #pragma unroll
;                     for (int j = 0; j < 4; ++j) { v0[j] = sigmoidf_(g0[j]) * acc[ai][bj][m][0][j]; v1[j] = sigmoidf_(g1[j]) * acc[ai][bj][m][1][j]; }
;                     const u32x4 mw = *(const u32x4*)(rowp + bj * 128); f32x4 m0, m1; unpack8(mw, m0, m1); v0 += m0; v1 += m1;
;                     __builtin_amdgcn_raw_buffer_store_b128(pack8(v0, v1), rsrc, (unsigned)(((size_t)row * DIN + col0 + bj * 128) * 2), 0, 16  ); }
	v_mov_b64_e32 v[70:71], v[232:233]
	v_mov_b64_e32 v[72:73], v[234:235]
	v_mov_b64_e32 v[74:75], v[236:237]
	v_mov_b64_e32 v[76:77], v[238:239]
	v_add_u32_e32 v202, 0x133300, v201
	global_load_dwordx4 v[232:235], v202, s[36:37]
	v_add_u32_e32 v202, 0x132100, v201
	global_load_dwordx4 v[236:239], v202, s[36:37]
	s_mov_b32 s100, 0xbfb8aa3b
	v_lshlrev_b32_e32 v242, 16, v70
	v_and_b32_e32 v243, 0xffff0000, v70
	v_lshlrev_b32_e32 v244, 16, v72
	v_and_b32_e32 v245, 0xffff0000, v72
	v_lshlrev_b32_e32 v246, 16, v71
	v_and_b32_e32 v247, 0xffff0000, v71
	v_lshlrev_b32_e32 v248, 16, v73
	v_and_b32_e32 v249, 0xffff0000, v73
	v_pk_mul_f32 v[242:243], v[242:243], s[100:101] op_sel_hi:[1,0]
	v_pk_mul_f32 v[244:245], v[244:245], s[100:101] op_sel_hi:[1,0]
	v_pk_mul_f32 v[246:247], v[246:247], s[100:101] op_sel_hi:[1,0]
	v_pk_mul_f32 v[248:249], v[248:249], s[100:101] op_sel_hi:[1,0]
	v_exp_f32_e32 v242, v242
	v_exp_f32_e32 v243, v243
	v_exp_f32_e32 v244, v244
	v_exp_f32_e32 v245, v245
	v_exp_f32_e32 v246, v246
	v_exp_f32_e32 v247, v247
	v_exp_f32_e32 v248, v248
	v_exp_f32_e32 v249, v249
	s_nop 0
	v_pk_add_f32 v[242:243], v[242:243], 1.0 op_sel_hi:[1,0]
	v_pk_add_f32 v[244:245], v[244:245], 1.0 op_sel_hi:[1,0]
	v_pk_add_f32 v[246:247], v[246:247], 1.0 op_sel_hi:[1,0]
	v_pk_add_f32 v[248:249], v[248:249], 1.0 op_sel_hi:[1,0]
	v_rcp_f32_e32 v250, v242
	v_rcp_f32_e32 v251, v243
	s_nop 0
	v_pk_fma_f32 v[252:253], v[242:243], v[250:251], 1.0 op_sel_hi:[1,1,0] neg_lo:[1,0,0] neg_hi:[1,0,0]
	v_pk_fma_f32 v[250:251], v[252:253], v[250:251], v[250:251]
	v_pk_fma_f32 v[252:253], v[242:243], v[250:251], 1.0 op_sel_hi:[1,1,0] neg_lo:[1,0,0] neg_hi:[1,0,0]
	v_pk_fma_f32 v[254:255], v[252:253], v[250:251], v[250:251]
	v_pk_fma_f32 v[252:253], v[242:243], v[254:255], 1.0 op_sel_hi:[1,1,0] neg_lo:[1,0,0] neg_hi:[1,0,0]
	v_pk_fma_f32 v[254:255], v[252:253], v[250:251], v[254:255]
	v_div_fixup_f32 v242, v254, v242, 1.0
	v_div_fixup_f32 v243, v255, v243, 1.0
	v_rcp_f32_e32 v250, v244
	v_rcp_f32_e32 v251, v245
	s_nop 0
	v_pk_fma_f32 v[252:253], v[244:245], v[250:251], 1.0 op_sel_hi:[1,1,0] neg_lo:[1,0,0] neg_hi:[1,0,0]
	v_pk_fma_f32 v[250:251], v[252:253], v[250:251], v[250:251]
	v_pk_fma_f32 v[252:253], v[244:245], v[250:251], 1.0 op_sel_hi:[1,1,0] neg_lo:[1,0,0] neg_hi:[1,0,0]
	v_pk_fma_f32 v[254:255], v[252:253], v[250:251], v[250:251]
	v_pk_fma_f32 v[252:253], v[244:245], v[254:255], 1.0 op_sel_hi:[1,1,0] neg_lo:[1,0,0] neg_hi:[1,0,0]
	v_pk_fma_f32 v[254:255], v[252:253], v[250:251], v[254:255]
	v_div_fixup_f32 v244, v254, v244, 1.0
	v_div_fixup_f32 v245, v255, v245, 1.0
	v_rcp_f32_e32 v250, v246
	v_rcp_f32_e32 v251, v247
	s_nop 0
	v_pk_fma_f32 v[252:253], v[246:247], v[250:251], 1.0 op_sel_hi:[1,1,0] neg_lo:[1,0,0] neg_hi:[1,0,0]
	v_pk_fma_f32 v[250:251], v[252:253], v[250:251], v[250:251]
	v_pk_fma_f32 v[252:253], v[246:247], v[250:251], 1.0 op_sel_hi:[1,1,0] neg_lo:[1,0,0] neg_hi:[1,0,0]
	v_pk_fma_f32 v[254:255], v[252:253], v[250:251], v[250:251]
	v_pk_fma_f32 v[252:253], v[246:247], v[254:255], 1.0 op_sel_hi:[1,1,0] neg_lo:[1,0,0] neg_hi:[1,0,0]
	v_pk_fma_f32 v[254:255], v[252:253], v[250:251], v[254:255]
	v_div_fixup_f32 v246, v254, v246, 1.0
	v_div_fixup_f32 v247, v255, v247, 1.0
	v_rcp_f32_e32 v250, v248
	v_rcp_f32_e32 v251, v249
	s_nop 0
	v_pk_fma_f32 v[252:253], v[248:249], v[250:251], 1.0 op_sel_hi:[1,1,0] neg_lo:[1,0,0] neg_hi:[1,0,0]
	v_pk_fma_f32 v[250:251], v[252:253], v[250:251], v[250:251]
	v_pk_fma_f32 v[252:253], v[248:249], v[250:251], 1.0 op_sel_hi:[1,1,0] neg_lo:[1,0,0] neg_hi:[1,0,0]
	v_pk_fma_f32 v[254:255], v[252:253], v[250:251], v[250:251]
	v_pk_fma_f32 v[252:253], v[248:249], v[254:255], 1.0 op_sel_hi:[1,1,0] neg_lo:[1,0,0] neg_hi:[1,0,0]
	v_pk_fma_f32 v[254:255], v[252:253], v[250:251], v[254:255]
	v_div_fixup_f32 v248, v254, v248, 1.0
	v_div_fixup_f32 v249, v255, v249, 1.0
	v_lshlrev_b32_e32 v82, 16, v74
	v_and_b32_e32 v83, 0xffff0000, v74
	v_lshlrev_b32_e32 v84, 16, v76
	v_and_b32_e32 v85, 0xffff0000, v76
	v_lshlrev_b32_e32 v76, 16, v77
	v_and_b32_e32 v77, 0xffff0000, v77
	v_lshlrev_b32_e32 v74, 16, v75
	v_and_b32_e32 v75, 0xffff0000, v75
	v_pk_fma_f32 v[60:61], v[60:61], v[242:243], v[82:83]
	v_pk_fma_f32 v[70:71], v[58:59], v[248:249], v[76:77]
	v_pk_fma_f32 v[58:59], v[56:57], v[244:245], v[84:85]
	v_add_lshl_u32 v72, v146, v66, 1
	v_pk_fma_f32 v[62:63], v[62:63], v[246:247], v[74:75]
	v_cvt_pk_bf16_f32 v56, v60, v61
	s_nop 0
	v_cvt_pk_bf16_f32 v57, v62, v63
	v_cvt_pk_bf16_f32 v58, v58, v59
	v_cvt_pk_bf16_f32 v59, v70, v71
	buffer_store_dwordx4 v[56:59], v72, s[20:23], 0 offen sc1
	s_nop 0
	s_waitcnt vmcnt(7)
; __device__ __forceinline__ float sigmoidf_(float x) { return 1.0f / (1.0f + __expf(-x)); }
; __device__ __forceinline__ u32x4 pack8(const f32x4 v0, const f32x4 v1) { u32x4 w; w.x = pk2(v0[0], v0[1]); w.y = pk2(v0[2], v0[3]); w.z = pk2(v1[0], v1[1]); w.w = pk2(v1[2], v1[3]); return w; }
; __device__ __forceinline__ void unpack8(const u32x4 w, f32x4& v0, f32x4& v1) { v0 = (f32x4){bflo(w.x), bfhi(w.x), bflo(w.y), bfhi(w.y)}; v1 = (f32x4){bflo(w.z), bfhi(w.z), bflo(w.w), bfhi(w.w)}; }
;     __device__ __forceinline__ void operator()(const f32x4 (&acc)[2][2][4][2], const Unit& u, int wr, int wc, int fr, int fq) const {
;     ...
;                 const int row = row0 + ai * 128 + m * 16;
;                 const bf16_t* rowp = z + (size_t)row * DIN + col0;
; #pragma unroll
;                 for (int bj = 0; bj < 2; ++bj) {
;                     const u32x4 gw = *(const u32x4*)(rowp + O_GA + bj * 128);
;                     f32x4 g0, g1; unpack8(gw, g0, g1);
;                     f32x4 v0, v1;
; #pragma unroll
;                     for (int j = 0; j < 4; ++j) { v0[j] = sigmoidf_(g0[j]) * acc[ai][bj][m][0][j]; v1[j] = sigmoidf_(g1[j]) * acc[ai][bj][m][1][j]; }
;                     const u32x4 mw = *(const u32x4*)(rowp + bj * 128); f32x4 m0, m1; unpack8(mw, m0, m1); v0 += m0; v1 += m1;
;                     __builtin_amdgcn_raw_buffer_store_b128(pack8(v0, v1), rsrc, (unsigned)(((size_t)row * DIN + col0 + bj * 128) * 2), 0, 16  ); }
	v_mov_b64_e32 v[56:57], v[204:205]
	v_mov_b64_e32 v[58:59], v[206:207]
	v_mov_b64_e32 v[60:61], v[208:209]
	v_mov_b64_e32 v[62:63], v[210:211]
	v_add_u32_e32 v202, 0x155200, v201
	global_load_dwordx4 v[204:207], v202, s[36:37]
	v_add_u32_e32 v202, 0x154000, v201
	global_load_dwordx4 v[208:211], v202, s[36:37]
	s_mov_b32 s100, 0xbfb8aa3b
	v_lshlrev_b32_e32 v242, 16, v58
	v_and_b32_e32 v243, 0xffff0000, v58
	v_lshlrev_b32_e32 v244, 16, v56
	v_and_b32_e32 v245, 0xffff0000, v56
	v_lshlrev_b32_e32 v246, 16, v57
	v_and_b32_e32 v247, 0xffff0000, v57
	v_lshlrev_b32_e32 v248, 16, v59
	v_and_b32_e32 v249, 0xffff0000, v59
	v_pk_mul_f32 v[242:243], v[242:243], s[100:101] op_sel_hi:[1,0]
	v_pk_mul_f32 v[244:245], v[244:245], s[100:101] op_sel_hi:[1,0]
	v_pk_mul_f32 v[246:247], v[246:247], s[100:101] op_sel_hi:[1,0]
	v_pk_mul_f32 v[248:249], v[248:249], s[100:101] op_sel_hi:[1,0]
	v_exp_f32_e32 v242, v242
	v_exp_f32_e32 v243, v243
	v_exp_f32_e32 v244, v244
	v_exp_f32_e32 v245, v245
	v_exp_f32_e32 v246, v246
	v_exp_f32_e32 v247, v247
	v_exp_f32_e32 v248, v248
	v_exp_f32_e32 v249, v249
	s_nop 0
	v_pk_add_f32 v[242:243], v[242:243], 1.0 op_sel_hi:[1,0]
	v_pk_add_f32 v[244:245], v[244:245], 1.0 op_sel_hi:[1,0]
	v_pk_add_f32 v[246:247], v[246:247], 1.0 op_sel_hi:[1,0]
	v_pk_add_f32 v[248:249], v[248:249], 1.0 op_sel_hi:[1,0]
	v_rcp_f32_e32 v250, v242
	v_rcp_f32_e32 v251, v243
	s_nop 0
	v_pk_fma_f32 v[252:253], v[242:243], v[250:251], 1.0 op_sel_hi:[1,1,0] neg_lo:[1,0,0] neg_hi:[1,0,0]
	v_pk_fma_f32 v[250:251], v[252:253], v[250:251], v[250:251]
	v_pk_fma_f32 v[252:253], v[242:243], v[250:251], 1.0 op_sel_hi:[1,1,0] neg_lo:[1,0,0] neg_hi:[1,0,0]
	v_pk_fma_f32 v[254:255], v[252:253], v[250:251], v[250:251]
	v_pk_fma_f32 v[252:253], v[242:243], v[254:255], 1.0 op_sel_hi:[1,1,0] neg_lo:[1,0,0] neg_hi:[1,0,0]
	v_pk_fma_f32 v[254:255], v[252:253], v[250:251], v[254:255]
	v_div_fixup_f32 v242, v254, v242, 1.0
	v_div_fixup_f32 v243, v255, v243, 1.0
	v_rcp_f32_e32 v250, v244
	v_rcp_f32_e32 v251, v245
	s_nop 0
	v_pk_fma_f32 v[252:253], v[244:245], v[250:251], 1.0 op_sel_hi:[1,1,0] neg_lo:[1,0,0] neg_hi:[1,0,0]
	v_pk_fma_f32 v[250:251], v[252:253], v[250:251], v[250:251]
	v_pk_fma_f32 v[252:253], v[244:245], v[250:251], 1.0 op_sel_hi:[1,1,0] neg_lo:[1,0,0] neg_hi:[1,0,0]
	v_pk_fma_f32 v[254:255], v[252:253], v[250:251], v[250:251]
	v_pk_fma_f32 v[252:253], v[244:245], v[254:255], 1.0 op_sel_hi:[1,1,0] neg_lo:[1,0,0] neg_hi:[1,0,0]
	v_pk_fma_f32 v[254:255], v[252:253], v[250:251], v[254:255]
	v_div_fixup_f32 v244, v254, v244, 1.0
	v_div_fixup_f32 v245, v255, v245, 1.0
	v_rcp_f32_e32 v250, v246
	v_rcp_f32_e32 v251, v247
	s_nop 0
	v_pk_fma_f32 v[252:253], v[246:247], v[250:251], 1.0 op_sel_hi:[1,1,0] neg_lo:[1,0,0] neg_hi:[1,0,0]
	v_pk_fma_f32 v[250:251], v[252:253], v[250:251], v[250:251]
	v_pk_fma_f32 v[252:253], v[246:247], v[250:251], 1.0 op_sel_hi:[1,1,0] neg_lo:[1,0,0] neg_hi:[1,0,0]
	v_pk_fma_f32 v[254:255], v[252:253], v[250:251], v[250:251]
	v_pk_fma_f32 v[252:253], v[246:247], v[254:255], 1.0 op_sel_hi:[1,1,0] neg_lo:[1,0,0] neg_hi:[1,0,0]
	v_pk_fma_f32 v[254:255], v[252:253], v[250:251], v[254:255]
	v_div_fixup_f32 v246, v254, v246, 1.0
	v_div_fixup_f32 v247, v255, v247, 1.0
	v_rcp_f32_e32 v250, v248
	v_rcp_f32_e32 v251, v249
	s_nop 0
	v_pk_fma_f32 v[252:253], v[248:249], v[250:251], 1.0 op_sel_hi:[1,1,0] neg_lo:[1,0,0] neg_hi:[1,0,0]
	v_pk_fma_f32 v[250:251], v[252:253], v[250:251], v[250:251]
	v_pk_fma_f32 v[252:253], v[248:249], v[250:251], 1.0 op_sel_hi:[1,1,0] neg_lo:[1,0,0] neg_hi:[1,0,0]
	v_pk_fma_f32 v[254:255], v[252:253], v[250:251], v[250:251]
	v_pk_fma_f32 v[252:253], v[248:249], v[254:255], 1.0 op_sel_hi:[1,1,0] neg_lo:[1,0,0] neg_hi:[1,0,0]
	v_pk_fma_f32 v[254:255], v[252:253], v[250:251], v[254:255]
	v_div_fixup_f32 v248, v254, v248, 1.0
	v_div_fixup_f32 v249, v255, v249, 1.0
	v_lshlrev_b32_e32 v68, 16, v60
	v_and_b32_e32 v69, 0xffff0000, v60
	v_lshlrev_b32_e32 v70, 16, v62
	v_and_b32_e32 v71, 0xffff0000, v62
	v_lshlrev_b32_e32 v62, 16, v63
	v_and_b32_e32 v63, 0xffff0000, v63
	v_lshlrev_b32_e32 v60, 16, v61
	v_and_b32_e32 v61, 0xffff0000, v61
	v_pk_fma_f32 v[52:53], v[52:53], v[244:245], v[68:69]
	v_pk_fma_f32 v[56:57], v[50:51], v[248:249], v[62:63]
	v_pk_fma_f32 v[50:51], v[48:49], v[242:243], v[70:71]
	v_cvt_pk_bf16_f32 v48, v52, v53
	v_pk_fma_f32 v[54:55], v[54:55], v[246:247], v[60:61]
	s_nop 0
	v_cvt_pk_bf16_f32 v49, v54, v55
	v_cvt_pk_bf16_f32 v50, v50, v51
	v_cvt_pk_bf16_f32 v51, v56, v57
	buffer_store_dwordx4 v[48:51], v72, s[20:23], 0 offen offset:256 sc1
	s_nop 1
	v_add_u32_e32 v48, 0x90, v162
	v_mad_i64_i32 v[50:51], s[6:7], v48, s73, 0
	v_lshl_add_u64 v[48:49], v[50:51], 1, s[36:37]
	v_lshl_add_u64 v[48:49], v[48:49], 0, v[148:149]
	v_add_co_u32_e32 v52, vcc, s74, v48
	s_nop 1
	v_addc_co_u32_e32 v53, vcc, 0, v49, vcc
	s_waitcnt vmcnt(7)
; __device__ __forceinline__ float sigmoidf_(float x) { return 1.0f / (1.0f + __expf(-x)); }
; __device__ __forceinline__ u32x4 pack8(const f32x4 v0, const f32x4 v1) { u32x4 w; w.x = pk2(v0[0], v0[1]); w.y = pk2(v0[2], v0[3]); w.z = pk2(v1[0], v1[1]); w.w = pk2(v1[2], v1[3]); return w; }
; __device__ __forceinline__ void unpack8(const u32x4 w, f32x4& v0, f32x4& v1) { v0 = (f32x4){bflo(w.x), bfhi(w.x), bflo(w.y), bfhi(w.y)}; v1 = (f32x4){bflo(w.z), bfhi(w.z), bflo(w.w), bfhi(w.w)}; }
;     __device__ __forceinline__ void operator()(const f32x4 (&acc)[2][2][4][2], const Unit& u, int wr, int wc, int fr, int fq) const {
;     ...
;                 const int row = row0 + ai * 128 + m * 16;
;                 const bf16_t* rowp = z + (size_t)row * DIN + col0;
; #pragma unroll
;                 for (int bj = 0; bj < 2; ++bj) {
;                     const u32x4 gw = *(const u32x4*)(rowp + O_GA + bj * 128);
;                     f32x4 g0, g1; unpack8(gw, g0, g1);
;                     f32x4 v0, v1;
; #pragma unroll
;                     for (int j = 0; j < 4; ++j) { v0[j] = sigmoidf_(g0[j]) * acc[ai][bj][m][0][j]; v1[j] = sigmoidf_(g1[j]) * acc[ai][bj][m][1][j]; }
;                     const u32x4 mw = *(const u32x4*)(rowp + bj * 128); f32x4 m0, m1; unpack8(mw, m0, m1); v0 += m0; v1 += m1;
;                     __builtin_amdgcn_raw_buffer_store_b128(pack8(v0, v1), rsrc, (unsigned)(((size_t)row * DIN + col0 + bj * 128) * 2), 0, 16  ); }
	v_mov_b64_e32 v[54:55], v[212:213]
	v_mov_b64_e32 v[56:57], v[214:215]
	v_mov_b64_e32 v[58:59], v[216:217]
	v_mov_b64_e32 v[60:61], v[218:219]
	v_add_u32_e32 v202, 0x155300, v201
	global_load_dwordx4 v[212:215], v202, s[36:37]
	v_add_u32_e32 v202, 0x154100, v201
	global_load_dwordx4 v[216:219], v202, s[36:37]
	s_mov_b32 s100, 0xbfb8aa3b
	v_lshlrev_b32_e32 v242, 16, v54
	v_and_b32_e32 v243, 0xffff0000, v54
	v_lshlrev_b32_e32 v244, 16, v56
	v_and_b32_e32 v245, 0xffff0000, v56
	v_lshlrev_b32_e32 v246, 16, v55
	v_and_b32_e32 v247, 0xffff0000, v55
	v_lshlrev_b32_e32 v248, 16, v57
	v_and_b32_e32 v249, 0xffff0000, v57
	v_pk_mul_f32 v[242:243], v[242:243], s[100:101] op_sel_hi:[1,0]
	v_pk_mul_f32 v[244:245], v[244:245], s[100:101] op_sel_hi:[1,0]
	v_pk_mul_f32 v[246:247], v[246:247], s[100:101] op_sel_hi:[1,0]
	v_pk_mul_f32 v[248:249], v[248:249], s[100:101] op_sel_hi:[1,0]
	v_exp_f32_e32 v242, v242
	v_exp_f32_e32 v243, v243
	v_exp_f32_e32 v244, v244
	v_exp_f32_e32 v245, v245
	v_exp_f32_e32 v246, v246
	v_exp_f32_e32 v247, v247
	v_exp_f32_e32 v248, v248
	v_exp_f32_e32 v249, v249
	s_nop 0
	v_pk_add_f32 v[242:243], v[242:243], 1.0 op_sel_hi:[1,0]
	v_pk_add_f32 v[244:245], v[244:245], 1.0 op_sel_hi:[1,0]
	v_pk_add_f32 v[246:247], v[246:247], 1.0 op_sel_hi:[1,0]
	v_pk_add_f32 v[248:249], v[248:249], 1.0 op_sel_hi:[1,0]
	v_rcp_f32_e32 v250, v242
	v_rcp_f32_e32 v251, v243
	s_nop 0
	v_pk_fma_f32 v[252:253], v[242:243], v[250:251], 1.0 op_sel_hi:[1,1,0] neg_lo:[1,0,0] neg_hi:[1,0,0]
	v_pk_fma_f32 v[250:251], v[252:253], v[250:251], v[250:251]
	v_pk_fma_f32 v[252:253], v[242:243], v[250:251], 1.0 op_sel_hi:[1,1,0] neg_lo:[1,0,0] neg_hi:[1,0,0]
	v_pk_fma_f32 v[254:255], v[252:253], v[250:251], v[250:251]
	v_pk_fma_f32 v[252:253], v[242:243], v[254:255], 1.0 op_sel_hi:[1,1,0] neg_lo:[1,0,0] neg_hi:[1,0,0]
	v_pk_fma_f32 v[254:255], v[252:253], v[250:251], v[254:255]
	v_div_fixup_f32 v242, v254, v242, 1.0
	v_div_fixup_f32 v243, v255, v243, 1.0
	v_rcp_f32_e32 v250, v244
	v_rcp_f32_e32 v251, v245
	s_nop 0
	v_pk_fma_f32 v[252:253], v[244:245], v[250:251], 1.0 op_sel_hi:[1,1,0] neg_lo:[1,0,0] neg_hi:[1,0,0]
	v_pk_fma_f32 v[250:251], v[252:253], v[250:251], v[250:251]
	v_pk_fma_f32 v[252:253], v[244:245], v[250:251], 1.0 op_sel_hi:[1,1,0] neg_lo:[1,0,0] neg_hi:[1,0,0]
	v_pk_fma_f32 v[254:255], v[252:253], v[250:251], v[250:251]
	v_pk_fma_f32 v[252:253], v[244:245], v[254:255], 1.0 op_sel_hi:[1,1,0] neg_lo:[1,0,0] neg_hi:[1,0,0]
	v_pk_fma_f32 v[254:255], v[252:253], v[250:251], v[254:255]
	v_div_fixup_f32 v244, v254, v244, 1.0
	v_div_fixup_f32 v245, v255, v245, 1.0
	v_rcp_f32_e32 v250, v246
	v_rcp_f32_e32 v251, v247
	s_nop 0
	v_pk_fma_f32 v[252:253], v[246:247], v[250:251], 1.0 op_sel_hi:[1,1,0] neg_lo:[1,0,0] neg_hi:[1,0,0]
	v_pk_fma_f32 v[250:251], v[252:253], v[250:251], v[250:251]
	v_pk_fma_f32 v[252:253], v[246:247], v[250:251], 1.0 op_sel_hi:[1,1,0] neg_lo:[1,0,0] neg_hi:[1,0,0]
	v_pk_fma_f32 v[254:255], v[252:253], v[250:251], v[250:251]
	v_pk_fma_f32 v[252:253], v[246:247], v[254:255], 1.0 op_sel_hi:[1,1,0] neg_lo:[1,0,0] neg_hi:[1,0,0]
	v_pk_fma_f32 v[254:255], v[252:253], v[250:251], v[254:255]
	v_div_fixup_f32 v246, v254, v246, 1.0
	v_div_fixup_f32 v247, v255, v247, 1.0
	v_rcp_f32_e32 v250, v248
	v_rcp_f32_e32 v251, v249
	s_nop 0
	v_pk_fma_f32 v[252:253], v[248:249], v[250:251], 1.0 op_sel_hi:[1,1,0] neg_lo:[1,0,0] neg_hi:[1,0,0]
	v_pk_fma_f32 v[250:251], v[252:253], v[250:251], v[250:251]
	v_pk_fma_f32 v[252:253], v[248:249], v[250:251], 1.0 op_sel_hi:[1,1,0] neg_lo:[1,0,0] neg_hi:[1,0,0]
	v_pk_fma_f32 v[254:255], v[252:253], v[250:251], v[250:251]
	v_pk_fma_f32 v[252:253], v[248:249], v[254:255], 1.0 op_sel_hi:[1,1,0] neg_lo:[1,0,0] neg_hi:[1,0,0]
	v_pk_fma_f32 v[254:255], v[252:253], v[250:251], v[254:255]
	v_div_fixup_f32 v248, v254, v248, 1.0
	v_div_fixup_f32 v249, v255, v249, 1.0
	v_lshlrev_b32_e32 v66, 16, v58
	v_and_b32_e32 v67, 0xffff0000, v58
	v_lshlrev_b32_e32 v68, 16, v60
	v_and_b32_e32 v69, 0xffff0000, v60
	v_lshlrev_b32_e32 v60, 16, v61
	v_and_b32_e32 v61, 0xffff0000, v61
	v_lshlrev_b32_e32 v58, 16, v59
	v_and_b32_e32 v59, 0xffff0000, v59
	v_pk_fma_f32 v[44:45], v[44:45], v[242:243], v[66:67]
	v_pk_fma_f32 v[54:55], v[42:43], v[248:249], v[60:61]
	v_pk_fma_f32 v[42:43], v[40:41], v[244:245], v[68:69]
	v_add_lshl_u32 v56, v146, v50, 1
	v_pk_fma_f32 v[46:47], v[46:47], v[246:247], v[58:59]
	v_cvt_pk_bf16_f32 v40, v44, v45
	s_nop 0
	v_cvt_pk_bf16_f32 v41, v46, v47
	v_cvt_pk_bf16_f32 v42, v42, v43
	v_cvt_pk_bf16_f32 v43, v54, v55
	buffer_store_dwordx4 v[40:43], v56, s[20:23], 0 offen sc1
	s_nop 0
	s_waitcnt vmcnt(7)
; __device__ __forceinline__ float sigmoidf_(float x) { return 1.0f / (1.0f + __expf(-x)); }
; __device__ __forceinline__ u32x4 pack8(const f32x4 v0, const f32x4 v1) { u32x4 w; w.x = pk2(v0[0], v0[1]); w.y = pk2(v0[2], v0[3]); w.z = pk2(v1[0], v1[1]); w.w = pk2(v1[2], v1[3]); return w; }
; __device__ __forceinline__ void unpack8(const u32x4 w, f32x4& v0, f32x4& v1) { v0 = (f32x4){bflo(w.x), bfhi(w.x), bflo(w.y), bfhi(w.y)}; v1 = (f32x4){bflo(w.z), bfhi(w.z), bflo(w.w), bfhi(w.w)}; }
;     __device__ __forceinline__ void operator()(const f32x4 (&acc)[2][2][4][2], const Unit& u, int wr, int wc, int fr, int fq) const {
;     ...
;                 const int row = row0 + ai * 128 + m * 16;
;                 const bf16_t* rowp = z + (size_t)row * DIN + col0;
; #pragma unroll
;                 for (int bj = 0; bj < 2; ++bj) {
;                     const u32x4 gw = *(const u32x4*)(rowp + O_GA + bj * 128);
;                     f32x4 g0, g1; unpack8(gw, g0, g1);
;                     f32x4 v0, v1;
; #pragma unroll
;                     for (int j = 0; j < 4; ++j) { v0[j] = sigmoidf_(g0[j]) * acc[ai][bj][m][0][j]; v1[j] = sigmoidf_(g1[j]) * acc[ai][bj][m][1][j]; }
;                     const u32x4 mw = *(const u32x4*)(rowp + bj * 128); f32x4 m0, m1; unpack8(mw, m0, m1); v0 += m0; v1 += m1;
;                     __builtin_amdgcn_raw_buffer_store_b128(pack8(v0, v1), rsrc, (unsigned)(((size_t)row * DIN + col0 + bj * 128) * 2), 0, 16  ); }
	v_mov_b64_e32 v[40:41], v[232:233]
	v_mov_b64_e32 v[42:43], v[234:235]
	v_mov_b64_e32 v[44:45], v[236:237]
	v_mov_b64_e32 v[46:47], v[238:239]
	v_add_u32_e32 v202, 0x177200, v201
	global_load_dwordx4 v[232:235], v202, s[36:37]
	v_add_u32_e32 v202, 0x176000, v201
	global_load_dwordx4 v[236:239], v202, s[36:37]
	s_mov_b32 s100, 0xbfb8aa3b
	v_lshlrev_b32_e32 v242, 16, v42
	v_and_b32_e32 v243, 0xffff0000, v42
	v_lshlrev_b32_e32 v244, 16, v40
	v_and_b32_e32 v245, 0xffff0000, v40
	v_lshlrev_b32_e32 v246, 16, v41
	v_and_b32_e32 v247, 0xffff0000, v41
	v_lshlrev_b32_e32 v248, 16, v43
	v_and_b32_e32 v249, 0xffff0000, v43
	v_pk_mul_f32 v[242:243], v[242:243], s[100:101] op_sel_hi:[1,0]
	v_pk_mul_f32 v[244:245], v[244:245], s[100:101] op_sel_hi:[1,0]
	v_pk_mul_f32 v[246:247], v[246:247], s[100:101] op_sel_hi:[1,0]
	v_pk_mul_f32 v[248:249], v[248:249], s[100:101] op_sel_hi:[1,0]
	v_exp_f32_e32 v242, v242
	v_exp_f32_e32 v243, v243
	v_exp_f32_e32 v244, v244
	v_exp_f32_e32 v245, v245
	v_exp_f32_e32 v246, v246
	v_exp_f32_e32 v247, v247
	v_exp_f32_e32 v248, v248
	v_exp_f32_e32 v249, v249
	s_nop 0
	v_pk_add_f32 v[242:243], v[242:243], 1.0 op_sel_hi:[1,0]
	v_pk_add_f32 v[244:245], v[244:245], 1.0 op_sel_hi:[1,0]
	v_pk_add_f32 v[246:247], v[246:247], 1.0 op_sel_hi:[1,0]
	v_pk_add_f32 v[248:249], v[248:249], 1.0 op_sel_hi:[1,0]
	v_rcp_f32_e32 v250, v242
	v_rcp_f32_e32 v251, v243
	s_nop 0
	v_pk_fma_f32 v[252:253], v[242:243], v[250:251], 1.0 op_sel_hi:[1,1,0] neg_lo:[1,0,0] neg_hi:[1,0,0]
	v_pk_fma_f32 v[250:251], v[252:253], v[250:251], v[250:251]
	v_pk_fma_f32 v[252:253], v[242:243], v[250:251], 1.0 op_sel_hi:[1,1,0] neg_lo:[1,0,0] neg_hi:[1,0,0]
	v_pk_fma_f32 v[254:255], v[252:253], v[250:251], v[250:251]
	v_pk_fma_f32 v[252:253], v[242:243], v[254:255], 1.0 op_sel_hi:[1,1,0] neg_lo:[1,0,0] neg_hi:[1,0,0]
	v_pk_fma_f32 v[254:255], v[252:253], v[250:251], v[254:255]
	v_div_fixup_f32 v242, v254, v242, 1.0
	v_div_fixup_f32 v243, v255, v243, 1.0
	v_rcp_f32_e32 v250, v244
	v_rcp_f32_e32 v251, v245
	s_nop 0
	v_pk_fma_f32 v[252:253], v[244:245], v[250:251], 1.0 op_sel_hi:[1,1,0] neg_lo:[1,0,0] neg_hi:[1,0,0]
	v_pk_fma_f32 v[250:251], v[252:253], v[250:251], v[250:251]
	v_pk_fma_f32 v[252:253], v[244:245], v[250:251], 1.0 op_sel_hi:[1,1,0] neg_lo:[1,0,0] neg_hi:[1,0,0]
	v_pk_fma_f32 v[254:255], v[252:253], v[250:251], v[250:251]
	v_pk_fma_f32 v[252:253], v[244:245], v[254:255], 1.0 op_sel_hi:[1,1,0] neg_lo:[1,0,0] neg_hi:[1,0,0]
	v_pk_fma_f32 v[254:255], v[252:253], v[250:251], v[254:255]
	v_div_fixup_f32 v244, v254, v244, 1.0
	v_div_fixup_f32 v245, v255, v245, 1.0
	v_rcp_f32_e32 v250, v246
	v_rcp_f32_e32 v251, v247
	s_nop 0
	v_pk_fma_f32 v[252:253], v[246:247], v[250:251], 1.0 op_sel_hi:[1,1,0] neg_lo:[1,0,0] neg_hi:[1,0,0]
	v_pk_fma_f32 v[250:251], v[252:253], v[250:251], v[250:251]
	v_pk_fma_f32 v[252:253], v[246:247], v[250:251], 1.0 op_sel_hi:[1,1,0] neg_lo:[1,0,0] neg_hi:[1,0,0]
	v_pk_fma_f32 v[254:255], v[252:253], v[250:251], v[250:251]
	v_pk_fma_f32 v[252:253], v[246:247], v[254:255], 1.0 op_sel_hi:[1,1,0] neg_lo:[1,0,0] neg_hi:[1,0,0]
	v_pk_fma_f32 v[254:255], v[252:253], v[250:251], v[254:255]
	v_div_fixup_f32 v246, v254, v246, 1.0
	v_div_fixup_f32 v247, v255, v247, 1.0
	v_rcp_f32_e32 v250, v248
	v_rcp_f32_e32 v251, v249
	s_nop 0
	v_pk_fma_f32 v[252:253], v[248:249], v[250:251], 1.0 op_sel_hi:[1,1,0] neg_lo:[1,0,0] neg_hi:[1,0,0]
	v_pk_fma_f32 v[250:251], v[252:253], v[250:251], v[250:251]
	v_pk_fma_f32 v[252:253], v[248:249], v[250:251], 1.0 op_sel_hi:[1,1,0] neg_lo:[1,0,0] neg_hi:[1,0,0]
	v_pk_fma_f32 v[254:255], v[252:253], v[250:251], v[250:251]
	v_pk_fma_f32 v[252:253], v[248:249], v[254:255], 1.0 op_sel_hi:[1,1,0] neg_lo:[1,0,0] neg_hi:[1,0,0]
	v_pk_fma_f32 v[254:255], v[252:253], v[250:251], v[254:255]
	v_div_fixup_f32 v248, v254, v248, 1.0
	v_div_fixup_f32 v249, v255, v249, 1.0
	v_lshlrev_b32_e32 v52, 16, v44
	v_and_b32_e32 v53, 0xffff0000, v44
	v_lshlrev_b32_e32 v54, 16, v46
	v_and_b32_e32 v55, 0xffff0000, v46
	v_lshlrev_b32_e32 v46, 16, v47
	v_and_b32_e32 v47, 0xffff0000, v47
	v_lshlrev_b32_e32 v44, 16, v45
	v_and_b32_e32 v45, 0xffff0000, v45
	v_pk_fma_f32 v[36:37], v[36:37], v[244:245], v[52:53]
	v_pk_fma_f32 v[40:41], v[34:35], v[248:249], v[46:47]
	v_pk_fma_f32 v[34:35], v[32:33], v[242:243], v[54:55]
	v_cvt_pk_bf16_f32 v32, v36, v37
	v_pk_fma_f32 v[38:39], v[38:39], v[246:247], v[44:45]
	s_nop 0
	v_cvt_pk_bf16_f32 v33, v38, v39
	v_cvt_pk_bf16_f32 v34, v34, v35
	v_cvt_pk_bf16_f32 v35, v40, v41
	buffer_store_dwordx4 v[32:35], v56, s[20:23], 0 offen offset:256 sc1
	s_nop 1
	v_add_u32_e32 v32, 0xa0, v162
	v_mad_i64_i32 v[34:35], s[6:7], v32, s73, 0
	v_lshl_add_u64 v[32:33], v[34:35], 1, s[36:37]
	v_lshl_add_u64 v[32:33], v[32:33], 0, v[148:149]
	v_add_co_u32_e32 v36, vcc, s74, v32
	s_nop 1
	v_addc_co_u32_e32 v37, vcc, 0, v33, vcc
	s_waitcnt vmcnt(7)
; __device__ __forceinline__ float sigmoidf_(float x) { return 1.0f / (1.0f + __expf(-x)); }
; __device__ __forceinline__ u32x4 pack8(const f32x4 v0, const f32x4 v1) { u32x4 w; w.x = pk2(v0[0], v0[1]); w.y = pk2(v0[2], v0[3]); w.z = pk2(v1[0], v1[1]); w.w = pk2(v1[2], v1[3]); return w; }
; __device__ __forceinline__ void unpack8(const u32x4 w, f32x4& v0, f32x4& v1) { v0 = (f32x4){bflo(w.x), bfhi(w.x), bflo(w.y), bfhi(w.y)}; v1 = (f32x4){bflo(w.z), bfhi(w.z), bflo(w.w), bfhi(w.w)}; }
;     __device__ __forceinline__ void operator()(const f32x4 (&acc)[2][2][4][2], const Unit& u, int wr, int wc, int fr, int fq) const {
;     ...
;                 const int row = row0 + ai * 128 + m * 16;
;                 const bf16_t* rowp = z + (size_t)row * DIN + col0;
; #pragma unroll
;                 for (int bj = 0; bj < 2; ++bj) {
;                     const u32x4 gw = *(const u32x4*)(rowp + O_GA + bj * 128);
;                     f32x4 g0, g1; unpack8(gw, g0, g1);
;                     f32x4 v0, v1;
; #pragma unroll
;                     for (int j = 0; j < 4; ++j) { v0[j] = sigmoidf_(g0[j]) * acc[ai][bj][m][0][j]; v1[j] = sigmoidf_(g1[j]) * acc[ai][bj][m][1][j]; }
;                     const u32x4 mw = *(const u32x4*)(rowp + bj * 128); f32x4 m0, m1; unpack8(mw, m0, m1); v0 += m0; v1 += m1;
;                     __builtin_amdgcn_raw_buffer_store_b128(pack8(v0, v1), rsrc, (unsigned)(((size_t)row * DIN + col0 + bj * 128) * 2), 0, 16  ); }
	v_mov_b64_e32 v[38:39], v[204:205]
	v_mov_b64_e32 v[40:41], v[206:207]
	v_mov_b64_e32 v[42:43], v[208:209]
	v_mov_b64_e32 v[44:45], v[210:211]
	v_add_u32_e32 v202, 0x177300, v201
	global_load_dwordx4 v[204:207], v202, s[36:37]
	v_add_u32_e32 v202, 0x176100, v201
	global_load_dwordx4 v[208:211], v202, s[36:37]
	s_mov_b32 s100, 0xbfb8aa3b
	v_lshlrev_b32_e32 v242, 16, v38
	v_and_b32_e32 v243, 0xffff0000, v38
	v_lshlrev_b32_e32 v244, 16, v40
	v_and_b32_e32 v245, 0xffff0000, v40
	v_lshlrev_b32_e32 v246, 16, v39
	v_and_b32_e32 v247, 0xffff0000, v39
	v_lshlrev_b32_e32 v248, 16, v41
	v_and_b32_e32 v249, 0xffff0000, v41
	v_pk_mul_f32 v[242:243], v[242:243], s[100:101] op_sel_hi:[1,0]
	v_pk_mul_f32 v[244:245], v[244:245], s[100:101] op_sel_hi:[1,0]
	v_pk_mul_f32 v[246:247], v[246:247], s[100:101] op_sel_hi:[1,0]
	v_pk_mul_f32 v[248:249], v[248:249], s[100:101] op_sel_hi:[1,0]
	v_exp_f32_e32 v242, v242
	v_exp_f32_e32 v243, v243
	v_exp_f32_e32 v244, v244
	v_exp_f32_e32 v245, v245
	v_exp_f32_e32 v246, v246
	v_exp_f32_e32 v247, v247
	v_exp_f32_e32 v248, v248
	v_exp_f32_e32 v249, v249
	s_nop 0
	v_pk_add_f32 v[242:243], v[242:243], 1.0 op_sel_hi:[1,0]
	v_pk_add_f32 v[244:245], v[244:245], 1.0 op_sel_hi:[1,0]
	v_pk_add_f32 v[246:247], v[246:247], 1.0 op_sel_hi:[1,0]
	v_pk_add_f32 v[248:249], v[248:249], 1.0 op_sel_hi:[1,0]
	v_rcp_f32_e32 v250, v242
	v_rcp_f32_e32 v251, v243
	s_nop 0
	v_pk_fma_f32 v[252:253], v[242:243], v[250:251], 1.0 op_sel_hi:[1,1,0] neg_lo:[1,0,0] neg_hi:[1,0,0]
	v_pk_fma_f32 v[250:251], v[252:253], v[250:251], v[250:251]
	v_pk_fma_f32 v[252:253], v[242:243], v[250:251], 1.0 op_sel_hi:[1,1,0] neg_lo:[1,0,0] neg_hi:[1,0,0]
	v_pk_fma_f32 v[254:255], v[252:253], v[250:251], v[250:251]
	v_pk_fma_f32 v[252:253], v[242:243], v[254:255], 1.0 op_sel_hi:[1,1,0] neg_lo:[1,0,0] neg_hi:[1,0,0]
	v_pk_fma_f32 v[254:255], v[252:253], v[250:251], v[254:255]
	v_div_fixup_f32 v242, v254, v242, 1.0
	v_div_fixup_f32 v243, v255, v243, 1.0
	v_rcp_f32_e32 v250, v244
	v_rcp_f32_e32 v251, v245
	s_nop 0
	v_pk_fma_f32 v[252:253], v[244:245], v[250:251], 1.0 op_sel_hi:[1,1,0] neg_lo:[1,0,0] neg_hi:[1,0,0]
	v_pk_fma_f32 v[250:251], v[252:253], v[250:251], v[250:251]
	v_pk_fma_f32 v[252:253], v[244:245], v[250:251], 1.0 op_sel_hi:[1,1,0] neg_lo:[1,0,0] neg_hi:[1,0,0]
	v_pk_fma_f32 v[254:255], v[252:253], v[250:251], v[250:251]
	v_pk_fma_f32 v[252:253], v[244:245], v[254:255], 1.0 op_sel_hi:[1,1,0] neg_lo:[1,0,0] neg_hi:[1,0,0]
	v_pk_fma_f32 v[254:255], v[252:253], v[250:251], v[254:255]
	v_div_fixup_f32 v244, v254, v244, 1.0
	v_div_fixup_f32 v245, v255, v245, 1.0
	v_rcp_f32_e32 v250, v246
	v_rcp_f32_e32 v251, v247
	s_nop 0
	v_pk_fma_f32 v[252:253], v[246:247], v[250:251], 1.0 op_sel_hi:[1,1,0] neg_lo:[1,0,0] neg_hi:[1,0,0]
	v_pk_fma_f32 v[250:251], v[252:253], v[250:251], v[250:251]
	v_pk_fma_f32 v[252:253], v[246:247], v[250:251], 1.0 op_sel_hi:[1,1,0] neg_lo:[1,0,0] neg_hi:[1,0,0]
	v_pk_fma_f32 v[254:255], v[252:253], v[250:251], v[250:251]
	v_pk_fma_f32 v[252:253], v[246:247], v[254:255], 1.0 op_sel_hi:[1,1,0] neg_lo:[1,0,0] neg_hi:[1,0,0]
	v_pk_fma_f32 v[254:255], v[252:253], v[250:251], v[254:255]
	v_div_fixup_f32 v246, v254, v246, 1.0
	v_div_fixup_f32 v247, v255, v247, 1.0
	v_rcp_f32_e32 v250, v248
	v_rcp_f32_e32 v251, v249
	s_nop 0
	v_pk_fma_f32 v[252:253], v[248:249], v[250:251], 1.0 op_sel_hi:[1,1,0] neg_lo:[1,0,0] neg_hi:[1,0,0]
	v_pk_fma_f32 v[250:251], v[252:253], v[250:251], v[250:251]
	v_pk_fma_f32 v[252:253], v[248:249], v[250:251], 1.0 op_sel_hi:[1,1,0] neg_lo:[1,0,0] neg_hi:[1,0,0]
	v_pk_fma_f32 v[254:255], v[252:253], v[250:251], v[250:251]
	v_pk_fma_f32 v[252:253], v[248:249], v[254:255], 1.0 op_sel_hi:[1,1,0] neg_lo:[1,0,0] neg_hi:[1,0,0]
	v_pk_fma_f32 v[254:255], v[252:253], v[250:251], v[254:255]
	v_div_fixup_f32 v248, v254, v248, 1.0
	v_div_fixup_f32 v249, v255, v249, 1.0
	v_lshlrev_b32_e32 v50, 16, v42
	v_and_b32_e32 v51, 0xffff0000, v42
	v_lshlrev_b32_e32 v52, 16, v44
	v_and_b32_e32 v53, 0xffff0000, v44
	v_lshlrev_b32_e32 v44, 16, v45
	v_and_b32_e32 v45, 0xffff0000, v45
	v_lshlrev_b32_e32 v42, 16, v43
	v_and_b32_e32 v43, 0xffff0000, v43
	v_pk_fma_f32 v[28:29], v[28:29], v[242:243], v[50:51]
	v_pk_fma_f32 v[38:39], v[26:27], v[248:249], v[44:45]
	v_pk_fma_f32 v[26:27], v[24:25], v[244:245], v[52:53]
	v_add_lshl_u32 v40, v146, v34, 1
	v_pk_fma_f32 v[30:31], v[30:31], v[246:247], v[42:43]
	v_cvt_pk_bf16_f32 v24, v28, v29
	s_nop 0
	v_cvt_pk_bf16_f32 v25, v30, v31
	v_cvt_pk_bf16_f32 v26, v26, v27
	v_cvt_pk_bf16_f32 v27, v38, v39
	buffer_store_dwordx4 v[24:27], v40, s[20:23], 0 offen sc1
	s_nop 0
	s_waitcnt vmcnt(7)
; __device__ __forceinline__ float sigmoidf_(float x) { return 1.0f / (1.0f + __expf(-x)); }
; __device__ __forceinline__ u32x4 pack8(const f32x4 v0, const f32x4 v1) { u32x4 w; w.x = pk2(v0[0], v0[1]); w.y = pk2(v0[2], v0[3]); w.z = pk2(v1[0], v1[1]); w.w = pk2(v1[2], v1[3]); return w; }
; __device__ __forceinline__ void unpack8(const u32x4 w, f32x4& v0, f32x4& v1) { v0 = (f32x4){bflo(w.x), bfhi(w.x), bflo(w.y), bfhi(w.y)}; v1 = (f32x4){bflo(w.z), bfhi(w.z), bflo(w.w), bfhi(w.w)}; }
;     __device__ __forceinline__ void operator()(const f32x4 (&acc)[2][2][4][2], const Unit& u, int wr, int wc, int fr, int fq) const {
;     ...
;                 const int row = row0 + ai * 128 + m * 16;
;                 const bf16_t* rowp = z + (size_t)row * DIN + col0;
; #pragma unroll
;                 for (int bj = 0; bj < 2; ++bj) {
;                     const u32x4 gw = *(const u32x4*)(rowp + O_GA + bj * 128);
;                     f32x4 g0, g1; unpack8(gw, g0, g1);
;                     f32x4 v0, v1;
; #pragma unroll
;                     for (int j = 0; j < 4; ++j) { v0[j] = sigmoidf_(g0[j]) * acc[ai][bj][m][0][j]; v1[j] = sigmoidf_(g1[j]) * acc[ai][bj][m][1][j]; }
;                     const u32x4 mw = *(const u32x4*)(rowp + bj * 128); f32x4 m0, m1; unpack8(mw, m0, m1); v0 += m0; v1 += m1;
;                     __builtin_amdgcn_raw_buffer_store_b128(pack8(v0, v1), rsrc, (unsigned)(((size_t)row * DIN + col0 + bj * 128) * 2), 0, 16  ); }
	v_mov_b64_e32 v[24:25], v[212:213]
	v_mov_b64_e32 v[26:27], v[214:215]
	v_mov_b64_e32 v[28:29], v[216:217]
	v_mov_b64_e32 v[30:31], v[218:219]
	s_mov_b32 s100, 0xbfb8aa3b
	v_lshlrev_b32_e32 v242, 16, v26
	v_and_b32_e32 v243, 0xffff0000, v26
	v_lshlrev_b32_e32 v244, 16, v24
	v_and_b32_e32 v245, 0xffff0000, v24
	v_lshlrev_b32_e32 v246, 16, v25
	v_and_b32_e32 v247, 0xffff0000, v25
	v_lshlrev_b32_e32 v248, 16, v27
	v_and_b32_e32 v249, 0xffff0000, v27
	v_pk_mul_f32 v[242:243], v[242:243], s[100:101] op_sel_hi:[1,0]
	v_pk_mul_f32 v[244:245], v[244:245], s[100:101] op_sel_hi:[1,0]
	v_pk_mul_f32 v[246:247], v[246:247], s[100:101] op_sel_hi:[1,0]
	v_pk_mul_f32 v[248:249], v[248:249], s[100:101] op_sel_hi:[1,0]
	v_exp_f32_e32 v242, v242
	v_exp_f32_e32 v243, v243
	v_exp_f32_e32 v244, v244
	v_exp_f32_e32 v245, v245
	v_exp_f32_e32 v246, v246
	v_exp_f32_e32 v247, v247
	v_exp_f32_e32 v248, v248
	v_exp_f32_e32 v249, v249
	s_nop 0
	v_pk_add_f32 v[242:243], v[242:243], 1.0 op_sel_hi:[1,0]
	v_pk_add_f32 v[244:245], v[244:245], 1.0 op_sel_hi:[1,0]
	v_pk_add_f32 v[246:247], v[246:247], 1.0 op_sel_hi:[1,0]
	v_pk_add_f32 v[248:249], v[248:249], 1.0 op_sel_hi:[1,0]
	v_rcp_f32_e32 v250, v242
	v_rcp_f32_e32 v251, v243
	s_nop 0
	v_pk_fma_f32 v[252:253], v[242:243], v[250:251], 1.0 op_sel_hi:[1,1,0] neg_lo:[1,0,0] neg_hi:[1,0,0]
	v_pk_fma_f32 v[250:251], v[252:253], v[250:251], v[250:251]
	v_pk_fma_f32 v[252:253], v[242:243], v[250:251], 1.0 op_sel_hi:[1,1,0] neg_lo:[1,0,0] neg_hi:[1,0,0]
	v_pk_fma_f32 v[254:255], v[252:253], v[250:251], v[250:251]
	v_pk_fma_f32 v[252:253], v[242:243], v[254:255], 1.0 op_sel_hi:[1,1,0] neg_lo:[1,0,0] neg_hi:[1,0,0]
	v_pk_fma_f32 v[254:255], v[252:253], v[250:251], v[254:255]
	v_div_fixup_f32 v242, v254, v242, 1.0
	v_div_fixup_f32 v243, v255, v243, 1.0
	v_rcp_f32_e32 v250, v244
	v_rcp_f32_e32 v251, v245
	s_nop 0
	v_pk_fma_f32 v[252:253], v[244:245], v[250:251], 1.0 op_sel_hi:[1,1,0] neg_lo:[1,0,0] neg_hi:[1,0,0]
	v_pk_fma_f32 v[250:251], v[252:253], v[250:251], v[250:251]
	v_pk_fma_f32 v[252:253], v[244:245], v[250:251], 1.0 op_sel_hi:[1,1,0] neg_lo:[1,0,0] neg_hi:[1,0,0]
	v_pk_fma_f32 v[254:255], v[252:253], v[250:251], v[250:251]
	v_pk_fma_f32 v[252:253], v[244:245], v[254:255], 1.0 op_sel_hi:[1,1,0] neg_lo:[1,0,0] neg_hi:[1,0,0]
	v_pk_fma_f32 v[254:255], v[252:253], v[250:251], v[254:255]
	v_div_fixup_f32 v244, v254, v244, 1.0
	v_div_fixup_f32 v245, v255, v245, 1.0
	v_rcp_f32_e32 v250, v246
	v_rcp_f32_e32 v251, v247
	s_nop 0
	v_pk_fma_f32 v[252:253], v[246:247], v[250:251], 1.0 op_sel_hi:[1,1,0] neg_lo:[1,0,0] neg_hi:[1,0,0]
	v_pk_fma_f32 v[250:251], v[252:253], v[250:251], v[250:251]
	v_pk_fma_f32 v[252:253], v[246:247], v[250:251], 1.0 op_sel_hi:[1,1,0] neg_lo:[1,0,0] neg_hi:[1,0,0]
	v_pk_fma_f32 v[254:255], v[252:253], v[250:251], v[250:251]
	v_pk_fma_f32 v[252:253], v[246:247], v[254:255], 1.0 op_sel_hi:[1,1,0] neg_lo:[1,0,0] neg_hi:[1,0,0]
	v_pk_fma_f32 v[254:255], v[252:253], v[250:251], v[254:255]
	v_div_fixup_f32 v246, v254, v246, 1.0
	v_div_fixup_f32 v247, v255, v247, 1.0
	v_rcp_f32_e32 v250, v248
	v_rcp_f32_e32 v251, v249
	s_nop 0
	v_pk_fma_f32 v[252:253], v[248:249], v[250:251], 1.0 op_sel_hi:[1,1,0] neg_lo:[1,0,0] neg_hi:[1,0,0]
	v_pk_fma_f32 v[250:251], v[252:253], v[250:251], v[250:251]
	v_pk_fma_f32 v[252:253], v[248:249], v[250:251], 1.0 op_sel_hi:[1,1,0] neg_lo:[1,0,0] neg_hi:[1,0,0]
	v_pk_fma_f32 v[254:255], v[252:253], v[250:251], v[250:251]
	v_pk_fma_f32 v[252:253], v[248:249], v[254:255], 1.0 op_sel_hi:[1,1,0] neg_lo:[1,0,0] neg_hi:[1,0,0]
	v_pk_fma_f32 v[254:255], v[252:253], v[250:251], v[254:255]
	v_div_fixup_f32 v248, v254, v248, 1.0
	v_div_fixup_f32 v249, v255, v249, 1.0
	v_lshlrev_b32_e32 v36, 16, v28
	v_and_b32_e32 v37, 0xffff0000, v28
	v_lshlrev_b32_e32 v38, 16, v30
	v_and_b32_e32 v39, 0xffff0000, v30
	v_lshlrev_b32_e32 v30, 16, v31
	v_and_b32_e32 v31, 0xffff0000, v31
	v_lshlrev_b32_e32 v28, 16, v29
	v_and_b32_e32 v29, 0xffff0000, v29
	v_pk_fma_f32 v[20:21], v[20:21], v[244:245], v[36:37]
	v_pk_fma_f32 v[24:25], v[18:19], v[248:249], v[30:31]
	v_pk_fma_f32 v[18:19], v[16:17], v[242:243], v[38:39]
	v_cvt_pk_bf16_f32 v16, v20, v21
	v_pk_fma_f32 v[22:23], v[22:23], v[246:247], v[28:29]
	s_nop 0
	v_cvt_pk_bf16_f32 v17, v22, v23
	v_cvt_pk_bf16_f32 v18, v18, v19
	v_cvt_pk_bf16_f32 v19, v24, v25
	buffer_store_dwordx4 v[16:19], v40, s[20:23], 0 offen offset:256 sc1
	s_nop 1
	v_add_u32_e32 v16, 0xb0, v162
	v_mad_i64_i32 v[18:19], s[6:7], v16, s73, 0
	v_lshl_add_u64 v[16:17], v[18:19], 1, s[36:37]
	v_lshl_add_u64 v[16:17], v[16:17], 0, v[148:149]
	v_add_co_u32_e32 v20, vcc, s74, v16
	s_nop 1
	v_addc_co_u32_e32 v21, vcc, 0, v17, vcc
	s_waitcnt vmcnt(5)
; __device__ __forceinline__ float sigmoidf_(float x) { return 1.0f / (1.0f + __expf(-x)); }
; __device__ __forceinline__ u32x4 pack8(const f32x4 v0, const f32x4 v1) { u32x4 w; w.x = pk2(v0[0], v0[1]); w.y = pk2(v0[2], v0[3]); w.z = pk2(v1[0], v1[1]); w.w = pk2(v1[2], v1[3]); return w; }
; __device__ __forceinline__ void unpack8(const u32x4 w, f32x4& v0, f32x4& v1) { v0 = (f32x4){bflo(w.x), bfhi(w.x), bflo(w.y), bfhi(w.y)}; v1 = (f32x4){bflo(w.z), bfhi(w.z), bflo(w.w), bfhi(w.w)}; }
;     __device__ __forceinline__ void operator()(const f32x4 (&acc)[2][2][4][2], const Unit& u, int wr, int wc, int fr, int fq) const {
;     ...
;                 const int row = row0 + ai * 128 + m * 16;
;                 const bf16_t* rowp = z + (size_t)row * DIN + col0;
; #pragma unroll
;                 for (int bj = 0; bj < 2; ++bj) {
;                     const u32x4 gw = *(const u32x4*)(rowp + O_GA + bj * 128);
;                     f32x4 g0, g1; unpack8(gw, g0, g1);
;                     f32x4 v0, v1;
; #pragma unroll
;                     for (int j = 0; j < 4; ++j) { v0[j] = sigmoidf_(g0[j]) * acc[ai][bj][m][0][j]; v1[j] = sigmoidf_(g1[j]) * acc[ai][bj][m][1][j]; }
;                     const u32x4 mw = *(const u32x4*)(rowp + bj * 128); f32x4 m0, m1; unpack8(mw, m0, m1); v0 += m0; v1 += m1;
;                     __builtin_amdgcn_raw_buffer_store_b128(pack8(v0, v1), rsrc, (unsigned)(((size_t)row * DIN + col0 + bj * 128) * 2), 0, 16  ); }
	v_mov_b64_e32 v[22:23], v[232:233]
	v_mov_b64_e32 v[24:25], v[234:235]
	v_mov_b64_e32 v[26:27], v[236:237]
	v_mov_b64_e32 v[28:29], v[238:239]
	s_mov_b32 s100, 0xbfb8aa3b
	v_lshlrev_b32_e32 v242, 16, v22
	v_and_b32_e32 v243, 0xffff0000, v22
	v_lshlrev_b32_e32 v244, 16, v24
	v_and_b32_e32 v245, 0xffff0000, v24
	v_lshlrev_b32_e32 v246, 16, v23
	v_and_b32_e32 v247, 0xffff0000, v23
	v_lshlrev_b32_e32 v248, 16, v25
	v_and_b32_e32 v249, 0xffff0000, v25
	v_pk_mul_f32 v[242:243], v[242:243], s[100:101] op_sel_hi:[1,0]
	v_pk_mul_f32 v[244:245], v[244:245], s[100:101] op_sel_hi:[1,0]
	v_pk_mul_f32 v[246:247], v[246:247], s[100:101] op_sel_hi:[1,0]
	v_pk_mul_f32 v[248:249], v[248:249], s[100:101] op_sel_hi:[1,0]
	v_exp_f32_e32 v242, v242
	v_exp_f32_e32 v243, v243
	v_exp_f32_e32 v244, v244
	v_exp_f32_e32 v245, v245
	v_exp_f32_e32 v246, v246
	v_exp_f32_e32 v247, v247
	v_exp_f32_e32 v248, v248
	v_exp_f32_e32 v249, v249
	s_nop 0
	v_pk_add_f32 v[242:243], v[242:243], 1.0 op_sel_hi:[1,0]
	v_pk_add_f32 v[244:245], v[244:245], 1.0 op_sel_hi:[1,0]
	v_pk_add_f32 v[246:247], v[246:247], 1.0 op_sel_hi:[1,0]
	v_pk_add_f32 v[248:249], v[248:249], 1.0 op_sel_hi:[1,0]
	v_rcp_f32_e32 v250, v242
	v_rcp_f32_e32 v251, v243
	s_nop 0
	v_pk_fma_f32 v[252:253], v[242:243], v[250:251], 1.0 op_sel_hi:[1,1,0] neg_lo:[1,0,0] neg_hi:[1,0,0]
	v_pk_fma_f32 v[250:251], v[252:253], v[250:251], v[250:251]
	v_pk_fma_f32 v[252:253], v[242:243], v[250:251], 1.0 op_sel_hi:[1,1,0] neg_lo:[1,0,0] neg_hi:[1,0,0]
	v_pk_fma_f32 v[254:255], v[252:253], v[250:251], v[250:251]
	v_pk_fma_f32 v[252:253], v[242:243], v[254:255], 1.0 op_sel_hi:[1,1,0] neg_lo:[1,0,0] neg_hi:[1,0,0]
	v_pk_fma_f32 v[254:255], v[252:253], v[250:251], v[254:255]
	v_div_fixup_f32 v242, v254, v242, 1.0
	v_div_fixup_f32 v243, v255, v243, 1.0
	v_rcp_f32_e32 v250, v244
	v_rcp_f32_e32 v251, v245
	s_nop 0
	v_pk_fma_f32 v[252:253], v[244:245], v[250:251], 1.0 op_sel_hi:[1,1,0] neg_lo:[1,0,0] neg_hi:[1,0,0]
	v_pk_fma_f32 v[250:251], v[252:253], v[250:251], v[250:251]
	v_pk_fma_f32 v[252:253], v[244:245], v[250:251], 1.0 op_sel_hi:[1,1,0] neg_lo:[1,0,0] neg_hi:[1,0,0]
	v_pk_fma_f32 v[254:255], v[252:253], v[250:251], v[250:251]
	v_pk_fma_f32 v[252:253], v[244:245], v[254:255], 1.0 op_sel_hi:[1,1,0] neg_lo:[1,0,0] neg_hi:[1,0,0]
	v_pk_fma_f32 v[254:255], v[252:253], v[250:251], v[254:255]
	v_div_fixup_f32 v244, v254, v244, 1.0
	v_div_fixup_f32 v245, v255, v245, 1.0
	v_rcp_f32_e32 v250, v246
	v_rcp_f32_e32 v251, v247
	s_nop 0
	v_pk_fma_f32 v[252:253], v[246:247], v[250:251], 1.0 op_sel_hi:[1,1,0] neg_lo:[1,0,0] neg_hi:[1,0,0]
	v_pk_fma_f32 v[250:251], v[252:253], v[250:251], v[250:251]
	v_pk_fma_f32 v[252:253], v[246:247], v[250:251], 1.0 op_sel_hi:[1,1,0] neg_lo:[1,0,0] neg_hi:[1,0,0]
	v_pk_fma_f32 v[254:255], v[252:253], v[250:251], v[250:251]
	v_pk_fma_f32 v[252:253], v[246:247], v[254:255], 1.0 op_sel_hi:[1,1,0] neg_lo:[1,0,0] neg_hi:[1,0,0]
	v_pk_fma_f32 v[254:255], v[252:253], v[250:251], v[254:255]
	v_div_fixup_f32 v246, v254, v246, 1.0
	v_div_fixup_f32 v247, v255, v247, 1.0
	v_rcp_f32_e32 v250, v248
	v_rcp_f32_e32 v251, v249
	s_nop 0
	v_pk_fma_f32 v[252:253], v[248:249], v[250:251], 1.0 op_sel_hi:[1,1,0] neg_lo:[1,0,0] neg_hi:[1,0,0]
	v_pk_fma_f32 v[250:251], v[252:253], v[250:251], v[250:251]
	v_pk_fma_f32 v[252:253], v[248:249], v[250:251], 1.0 op_sel_hi:[1,1,0] neg_lo:[1,0,0] neg_hi:[1,0,0]
	v_pk_fma_f32 v[254:255], v[252:253], v[250:251], v[250:251]
	v_pk_fma_f32 v[252:253], v[248:249], v[254:255], 1.0 op_sel_hi:[1,1,0] neg_lo:[1,0,0] neg_hi:[1,0,0]
	v_pk_fma_f32 v[254:255], v[252:253], v[250:251], v[254:255]
	v_div_fixup_f32 v248, v254, v248, 1.0
	v_div_fixup_f32 v249, v255, v249, 1.0
	v_lshlrev_b32_e32 v34, 16, v26
	v_and_b32_e32 v35, 0xffff0000, v26
	v_lshlrev_b32_e32 v36, 16, v28
	v_and_b32_e32 v37, 0xffff0000, v28
	v_lshlrev_b32_e32 v28, 16, v29
	v_and_b32_e32 v29, 0xffff0000, v29
	v_lshlrev_b32_e32 v26, 16, v27
	v_and_b32_e32 v27, 0xffff0000, v27
	v_pk_fma_f32 v[12:13], v[12:13], v[242:243], v[34:35]
	v_pk_fma_f32 v[22:23], v[10:11], v[248:249], v[28:29]
	v_pk_fma_f32 v[10:11], v[8:9], v[244:245], v[36:37]
	v_add_lshl_u32 v24, v146, v18, 1
	v_pk_fma_f32 v[14:15], v[14:15], v[246:247], v[26:27]
	v_cvt_pk_bf16_f32 v8, v12, v13
	s_nop 0
	v_cvt_pk_bf16_f32 v9, v14, v15
	v_cvt_pk_bf16_f32 v10, v10, v11
	v_cvt_pk_bf16_f32 v11, v22, v23
	buffer_store_dwordx4 v[8:11], v24, s[20:23], 0 offen sc1
	s_nop 0
	s_waitcnt vmcnt(3)
; __device__ __forceinline__ float sigmoidf_(float x) { return 1.0f / (1.0f + __expf(-x)); }
; __device__ __forceinline__ u32x4 pack8(const f32x4 v0, const f32x4 v1) { u32x4 w; w.x = pk2(v0[0], v0[1]); w.y = pk2(v0[2], v0[3]); w.z = pk2(v1[0], v1[1]); w.w = pk2(v1[2], v1[3]); return w; }
; __device__ __forceinline__ void unpack8(const u32x4 w, f32x4& v0, f32x4& v1) { v0 = (f32x4){bflo(w.x), bfhi(w.x), bflo(w.y), bfhi(w.y)}; v1 = (f32x4){bflo(w.z), bfhi(w.z), bflo(w.w), bfhi(w.w)}; }
;     __device__ __forceinline__ void operator()(const f32x4 (&acc)[2][2][4][2], const Unit& u, int wr, int wc, int fr, int fq) const {
;     ...
;                 for (int bj = 0; bj < 2; ++bj) {
;                     const u32x4 gw = *(const u32x4*)(rowp + O_GA + bj * 128);
;                     f32x4 g0, g1; unpack8(gw, g0, g1);
;                     f32x4 v0, v1;
; #pragma unroll
;                     for (int j = 0; j < 4; ++j) { v0[j] = sigmoidf_(g0[j]) * acc[ai][bj][m][0][j]; v1[j] = sigmoidf_(g1[j]) * acc[ai][bj][m][1][j]; }
;                     const u32x4 mw = *(const u32x4*)(rowp + bj * 128); f32x4 m0, m1; unpack8(mw, m0, m1); v0 += m0; v1 += m1;
;                     __builtin_amdgcn_raw_buffer_store_b128(pack8(v0, v1), rsrc, (unsigned)(((size_t)row * DIN + col0 + bj * 128) * 2), 0, 16  ); }
;             }
;         asm volatile("s_waitcnt vmcnt(0)" ::: "memory");
;         if (fr == 0 && fq == 0) (void)__hip_atomic_fetch_add(ready + 64 * (pm_off + u.pm), 1u, __ATOMIC_RELAXED, __HIP_MEMORY_SCOPE_AGENT);
	v_mov_b64_e32 v[8:9], v[204:205]
	v_mov_b64_e32 v[10:11], v[206:207]
	v_mov_b64_e32 v[12:13], v[208:209]
	v_mov_b64_e32 v[14:15], v[210:211]
	s_mov_b32 s100, 0xbfb8aa3b
	v_lshlrev_b32_e32 v242, 16, v10
	v_and_b32_e32 v243, 0xffff0000, v10
	v_lshlrev_b32_e32 v244, 16, v8
	v_and_b32_e32 v245, 0xffff0000, v8
	v_lshlrev_b32_e32 v246, 16, v9
	v_and_b32_e32 v247, 0xffff0000, v9
	v_lshlrev_b32_e32 v248, 16, v11
	v_and_b32_e32 v249, 0xffff0000, v11
	v_pk_mul_f32 v[242:243], v[242:243], s[100:101] op_sel_hi:[1,0]
	v_pk_mul_f32 v[244:245], v[244:245], s[100:101] op_sel_hi:[1,0]
	v_pk_mul_f32 v[246:247], v[246:247], s[100:101] op_sel_hi:[1,0]
	v_pk_mul_f32 v[248:249], v[248:249], s[100:101] op_sel_hi:[1,0]
	v_exp_f32_e32 v242, v242
	v_exp_f32_e32 v243, v243
	v_exp_f32_e32 v244, v244
	v_exp_f32_e32 v245, v245
	v_exp_f32_e32 v246, v246
	v_exp_f32_e32 v247, v247
	v_exp_f32_e32 v248, v248
	v_exp_f32_e32 v249, v249
	s_nop 0
	v_pk_add_f32 v[242:243], v[242:243], 1.0 op_sel_hi:[1,0]
	v_pk_add_f32 v[244:245], v[244:245], 1.0 op_sel_hi:[1,0]
	v_pk_add_f32 v[246:247], v[246:247], 1.0 op_sel_hi:[1,0]
	v_pk_add_f32 v[248:249], v[248:249], 1.0 op_sel_hi:[1,0]
	v_rcp_f32_e32 v250, v242
	v_rcp_f32_e32 v251, v243
	s_nop 0
	v_pk_fma_f32 v[252:253], v[242:243], v[250:251], 1.0 op_sel_hi:[1,1,0] neg_lo:[1,0,0] neg_hi:[1,0,0]
	v_pk_fma_f32 v[250:251], v[252:253], v[250:251], v[250:251]
	v_pk_fma_f32 v[252:253], v[242:243], v[250:251], 1.0 op_sel_hi:[1,1,0] neg_lo:[1,0,0] neg_hi:[1,0,0]
	v_pk_fma_f32 v[254:255], v[252:253], v[250:251], v[250:251]
	v_pk_fma_f32 v[252:253], v[242:243], v[254:255], 1.0 op_sel_hi:[1,1,0] neg_lo:[1,0,0] neg_hi:[1,0,0]
	v_pk_fma_f32 v[254:255], v[252:253], v[250:251], v[254:255]
	v_div_fixup_f32 v242, v254, v242, 1.0
	v_div_fixup_f32 v243, v255, v243, 1.0
	v_rcp_f32_e32 v250, v244
	v_rcp_f32_e32 v251, v245
	s_nop 0
	v_pk_fma_f32 v[252:253], v[244:245], v[250:251], 1.0 op_sel_hi:[1,1,0] neg_lo:[1,0,0] neg_hi:[1,0,0]
	v_pk_fma_f32 v[250:251], v[252:253], v[250:251], v[250:251]
	v_pk_fma_f32 v[252:253], v[244:245], v[250:251], 1.0 op_sel_hi:[1,1,0] neg_lo:[1,0,0] neg_hi:[1,0,0]
	v_pk_fma_f32 v[254:255], v[252:253], v[250:251], v[250:251]
	v_pk_fma_f32 v[252:253], v[244:245], v[254:255], 1.0 op_sel_hi:[1,1,0] neg_lo:[1,0,0] neg_hi:[1,0,0]
	v_pk_fma_f32 v[254:255], v[252:253], v[250:251], v[254:255]
	v_div_fixup_f32 v244, v254, v244, 1.0
	v_div_fixup_f32 v245, v255, v245, 1.0
	v_rcp_f32_e32 v250, v246
	v_rcp_f32_e32 v251, v247
	s_nop 0
	v_pk_fma_f32 v[252:253], v[246:247], v[250:251], 1.0 op_sel_hi:[1,1,0] neg_lo:[1,0,0] neg_hi:[1,0,0]
	v_pk_fma_f32 v[250:251], v[252:253], v[250:251], v[250:251]
	v_pk_fma_f32 v[252:253], v[246:247], v[250:251], 1.0 op_sel_hi:[1,1,0] neg_lo:[1,0,0] neg_hi:[1,0,0]
	v_pk_fma_f32 v[254:255], v[252:253], v[250:251], v[250:251]
	v_pk_fma_f32 v[252:253], v[246:247], v[254:255], 1.0 op_sel_hi:[1,1,0] neg_lo:[1,0,0] neg_hi:[1,0,0]
	v_pk_fma_f32 v[254:255], v[252:253], v[250:251], v[254:255]
	v_div_fixup_f32 v246, v254, v246, 1.0
	v_div_fixup_f32 v247, v255, v247, 1.0
	v_rcp_f32_e32 v250, v248
	v_rcp_f32_e32 v251, v249
	s_nop 0
	v_pk_fma_f32 v[252:253], v[248:249], v[250:251], 1.0 op_sel_hi:[1,1,0] neg_lo:[1,0,0] neg_hi:[1,0,0]
	v_pk_fma_f32 v[250:251], v[252:253], v[250:251], v[250:251]
	v_pk_fma_f32 v[252:253], v[248:249], v[250:251], 1.0 op_sel_hi:[1,1,0] neg_lo:[1,0,0] neg_hi:[1,0,0]
	v_pk_fma_f32 v[254:255], v[252:253], v[250:251], v[250:251]
	v_pk_fma_f32 v[252:253], v[248:249], v[254:255], 1.0 op_sel_hi:[1,1,0] neg_lo:[1,0,0] neg_hi:[1,0,0]
	v_pk_fma_f32 v[254:255], v[252:253], v[250:251], v[254:255]
	v_div_fixup_f32 v248, v254, v248, 1.0
	v_div_fixup_f32 v249, v255, v249, 1.0
	v_lshlrev_b32_e32 v20, 16, v12
	v_and_b32_e32 v21, 0xffff0000, v12
	v_lshlrev_b32_e32 v22, 16, v14
	v_and_b32_e32 v23, 0xffff0000, v14
	v_lshlrev_b32_e32 v14, 16, v15
	v_and_b32_e32 v15, 0xffff0000, v15
	v_lshlrev_b32_e32 v12, 16, v13
	v_and_b32_e32 v13, 0xffff0000, v13
	v_pk_fma_f32 v[4:5], v[4:5], v[244:245], v[20:21]
	v_pk_fma_f32 v[8:9], v[2:3], v[248:249], v[14:15]
	v_pk_fma_f32 v[2:3], v[0:1], v[242:243], v[22:23]
	v_pk_fma_f32 v[6:7], v[6:7], v[246:247], v[12:13]
	v_cvt_pk_bf16_f32 v0, v4, v5
	s_nop 0
	v_cvt_pk_bf16_f32 v1, v6, v7
	v_cvt_pk_bf16_f32 v2, v2, v3
	v_cvt_pk_bf16_f32 v3, v8, v9
	buffer_store_dwordx4 v[0:3], v24, s[20:23], 0 offen offset:256 sc1
	s_waitcnt vmcnt(0)
	s_and_saveexec_b64 s[12:13], s[8:9]
	s_cbranch_execz .LBB0_1833
	s_mov_b64 s[14:15], exec
	v_mbcnt_lo_u32_b32 v0, s14, 0
	v_mbcnt_hi_u32_b32 v0, s15, v0
	v_cmp_eq_u32_e32 vcc, 0, v0
	s_and_b64 s[6:7], exec, vcc
	s_mov_b64 exec, s[6:7]
	s_cbranch_execz .LBB0_1833
	s_lshl_b32 s6, s75, 6
	s_ashr_i32 s7, s6, 31
	s_lshl_b64 s[6:7], s[6:7], 2
	s_add_u32 s6, s28, s6
	s_addc_u32 s7, s29, s7
	s_bcnt1_i32_b64 s14, s[14:15]
	v_mov_b32_e32 v0, s14
	global_atomic_add v131, v0, s[6:7]
	s_branch .LBB0_1833

; #define PG8_STAGE(bufoff, gbase, voff) do { _Pragma("unroll") for (int _i = 0; _i < 2; ++_i) \
;         __builtin_amdgcn_global_load_lds((const unsigned*)((const char*)(gbase) + (voff)[_i]), (LAS unsigned*)(lds + (bufoff) + ldsw + _i * 8192), 16, 0, 0); } while (0)
; #define PG8_LDA(dst, b, h) do { _Pragma("unroll") for (int m = 0; m < 4; ++m) _Pragma("unroll") for (int k = 0; k < 2; ++k) dst[m][k] = *(const LAS bf16x8*)(lds + PG8_SA(b, h) + aoff + m * 2048 + k * 1024); } while (0)
; #define PG8_LDB(dst, b, h) do { _Pragma("unroll") for (int n = 0; n < 2; ++n) _Pragma("unroll") for (int k = 0; k < 2; ++k) dst[n][k] = *(const LAS bf16x8*)(lds + PG8_SB(b, h) + boff + n * 2048 + k * 1024); } while (0)
; #define PG8_MMA(ai, bj, At, Bt) do { __builtin_amdgcn_s_setprio(1); _Pragma("unroll") for (int m = 0; m < 4; ++m) _Pragma("unroll") for (int n = 0; n < 2; ++n) _Pragma("unroll") for (int k = 0; k < 2; ++k) \
;         acc[ai][bj][m][n] = __builtin_amdgcn_mfma_f32_16x16x32_bf16(Bt[n][k], At[m][k], acc[ai][bj][m][n], 0, 0, 0); __builtin_amdgcn_s_setprio(0); } while (0)
; #define PG8_WAIT_L(n) asm volatile("s_waitcnt lgkmcnt(" #n ")" ::: "memory")
; #define PG8_BAR __builtin_amdgcn_s_barrier()
; #define PG8_SCHED __builtin_amdgcn_sched_barrier(0)
;     ...
;             PG8_LDB(B0, 0, 0); PG8_SCHED; PG8_LDA(At, 0, 0); PG8_STAGE(PG8_SA(1, 1), a1 + hA, voffA);
;             PG8_WAIT_L(8); PG8_BAR; PG8_WAIT_L(0); PG8_MMA(0, 0, At, B0); PG8_BAR; PG8_SCHED;
;             PG8_LDB(B1, 0, 1); PG8_STAGE(PG8_SB(0, 0), b2, voffB);
;             PG8_BAR; PG8_WAIT_L(0); PG8_MMA(0, 1, At, B1); PG8_BAR;
;             PG8_LDA(At, 0, 1); PG8_STAGE(PG8_SA(0, 0), a2, voffA);
;             PG8_BAR; PG8_WAIT_L(0); PG8_MMA(1, 0, At, B0); PG8_BAR; PG8_SCHED;
.LBB0_1864:
	ds_read_b128 v[140:143], v155
	ds_read_b128 v[146:149], v155 offset:1024
	ds_read_b128 v[158:161], v155 offset:2048
	ds_read_b128 v[162:165], v155 offset:3072
	s_add_u32 s12, s10, 0xfffe0080
	s_addc_u32 s13, s11, -1
	s_cmp_eq_u32 s45, 4
	s_cselect_b32 s15, s7, s13
	s_cselect_b32 s14, s16, s12
	s_cselect_b32 s13, s17, s44
	s_cselect_b32 s12, s33, s37
	v_lshl_add_u64 v[150:151], s[10:11], 0, v[138:139]
	s_add_i32 m0, s62, 0xc000
	ds_read_b128 v[170:173], v156
	ds_read_b128 v[174:177], v156 offset:1024
	ds_read_b128 v[178:181], v156 offset:2048
	ds_read_b128 v[182:185], v156 offset:3072
	ds_read_b128 v[186:189], v156 offset:4096
	ds_read_b128 v[190:193], v156 offset:5120
	ds_read_b128 v[194:197], v156 offset:6144
	ds_read_b128 v[198:201], v156 offset:7168
	global_load_lds_dwordx4 v[150:151], off
	v_lshl_add_u64 v[150:151], s[10:11], 0, v[136:137]
	s_add_i32 m0, s62, 0xe000
	s_nop 0
	global_load_lds_dwordx4 v[150:151], off
	s_waitcnt lgkmcnt(8)
	s_barrier
	s_waitcnt lgkmcnt(0)
	s_setprio 1
	s_waitcnt lgkmcnt(0)
	v_mfma_f32_16x16x32_bf16 v[124:127], v[140:143], v[170:173], v[124:127]
	v_mfma_f32_16x16x32_bf16 v[120:123], v[158:161], v[170:173], v[120:123]
	v_mfma_f32_16x16x32_bf16 v[108:111], v[140:143], v[178:181], v[108:111]
	v_mfma_f32_16x16x32_bf16 v[104:107], v[158:161], v[178:181], v[104:107]
	v_mfma_f32_16x16x32_bf16 v[92:95], v[140:143], v[186:189], v[92:95]
	v_mfma_f32_16x16x32_bf16 v[88:91], v[158:161], v[186:189], v[88:91]
	v_mfma_f32_16x16x32_bf16 v[76:79], v[140:143], v[194:197], v[76:79]
	v_mfma_f32_16x16x32_bf16 v[72:75], v[158:161], v[194:197], v[72:75]
	v_mfma_f32_16x16x32_bf16 v[124:127], v[146:149], v[174:177], v[124:127]
	v_mfma_f32_16x16x32_bf16 v[120:123], v[162:165], v[174:177], v[120:123]
	v_mfma_f32_16x16x32_bf16 v[108:111], v[146:149], v[182:185], v[108:111]
	v_mfma_f32_16x16x32_bf16 v[104:107], v[162:165], v[182:185], v[104:107]
	v_mfma_f32_16x16x32_bf16 v[92:95], v[146:149], v[190:193], v[92:95]
	v_mfma_f32_16x16x32_bf16 v[88:91], v[162:165], v[190:193], v[88:91]
	v_mfma_f32_16x16x32_bf16 v[76:79], v[146:149], v[198:201], v[76:79]
	v_mfma_f32_16x16x32_bf16 v[72:75], v[162:165], v[198:201], v[72:75]
	s_setprio 0
	s_barrier
	s_add_i32 s53, s71, s61
	v_lshl_add_u64 v[150:151], s[12:13], 0, v[130:131]
	s_mov_b32 m0, s53
	ds_read_b128 v[202:205], v157
	ds_read_b128 v[206:209], v157 offset:1024
	ds_read_b128 v[210:213], v157 offset:2048
	ds_read_b128 v[214:217], v157 offset:3072
	global_load_lds_dwordx4 v[150:151], off
	v_lshl_add_u64 v[218:219], s[12:13], 0, v[134:135]
	s_add_i32 m0, s53, 0x2000
	s_nop 0
	global_load_lds_dwordx4 v[218:219], off
	s_barrier
	s_waitcnt lgkmcnt(0)
	s_setprio 1
	s_waitcnt lgkmcnt(0)
	v_mfma_f32_16x16x32_bf16 v[116:119], v[202:205], v[170:173], v[116:119]
	v_mfma_f32_16x16x32_bf16 v[112:115], v[210:213], v[170:173], v[112:115]
	v_mfma_f32_16x16x32_bf16 v[100:103], v[202:205], v[178:181], v[100:103]
	v_mfma_f32_16x16x32_bf16 v[96:99], v[210:213], v[178:181], v[96:99]
	v_mfma_f32_16x16x32_bf16 v[84:87], v[202:205], v[186:189], v[84:87]
	v_mfma_f32_16x16x32_bf16 v[80:83], v[210:213], v[186:189], v[80:83]
	v_mfma_f32_16x16x32_bf16 v[68:71], v[202:205], v[194:197], v[68:71]
	v_mfma_f32_16x16x32_bf16 v[64:67], v[210:213], v[194:197], v[64:67]
	v_mfma_f32_16x16x32_bf16 v[116:119], v[206:209], v[174:177], v[116:119]
	v_mfma_f32_16x16x32_bf16 v[112:115], v[214:217], v[174:177], v[112:115]
	v_mfma_f32_16x16x32_bf16 v[100:103], v[206:209], v[182:185], v[100:103]
	v_mfma_f32_16x16x32_bf16 v[96:99], v[214:217], v[182:185], v[96:99]
	v_mfma_f32_16x16x32_bf16 v[84:87], v[206:209], v[190:193], v[84:87]
	v_mfma_f32_16x16x32_bf16 v[80:83], v[214:217], v[190:193], v[80:83]
	v_mfma_f32_16x16x32_bf16 v[68:71], v[206:209], v[198:201], v[68:71]
	v_mfma_f32_16x16x32_bf16 v[64:67], v[214:217], v[198:201], v[64:67]
	s_setprio 0
	s_mov_b32 m0, s62
	v_lshl_add_u64 v[220:221], s[14:15], 0, v[128:129]
	s_barrier
	ds_read_b128 v[170:173], v156 offset:16384
	ds_read_b128 v[174:177], v156 offset:17408
	ds_read_b128 v[178:181], v156 offset:18432
	ds_read_b128 v[182:185], v156 offset:19456
	ds_read_b128 v[186:189], v156 offset:20480
	ds_read_b128 v[190:193], v156 offset:21504
	ds_read_b128 v[194:197], v156 offset:22528
	ds_read_b128 v[198:201], v156 offset:23552
	global_load_lds_dwordx4 v[220:221], off
	v_lshl_add_u64 v[222:223], s[14:15], 0, v[132:133]
	s_mov_b32 m0, s63
	s_nop 0
	global_load_lds_dwordx4 v[222:223], off
	s_barrier
	s_waitcnt lgkmcnt(0)
	s_setprio 1
	s_waitcnt lgkmcnt(0)
	v_mfma_f32_16x16x32_bf16 v[60:63], v[140:143], v[170:173], v[60:63]
	v_mfma_f32_16x16x32_bf16 v[56:59], v[158:161], v[170:173], v[56:59]
	v_mfma_f32_16x16x32_bf16 v[44:47], v[140:143], v[178:181], v[44:47]
	v_mfma_f32_16x16x32_bf16 v[40:43], v[158:161], v[178:181], v[40:43]
	v_mfma_f32_16x16x32_bf16 v[28:31], v[140:143], v[186:189], v[28:31]
	v_mfma_f32_16x16x32_bf16 v[24:27], v[158:161], v[186:189], v[24:27]
	v_mfma_f32_16x16x32_bf16 v[12:15], v[140:143], v[194:197], v[12:15]
	v_mfma_f32_16x16x32_bf16 v[8:11], v[158:161], v[194:197], v[8:11]
	v_mfma_f32_16x16x32_bf16 v[60:63], v[146:149], v[174:177], v[60:63]
	v_mfma_f32_16x16x32_bf16 v[56:59], v[162:165], v[174:177], v[56:59]
	v_mfma_f32_16x16x32_bf16 v[44:47], v[146:149], v[182:185], v[44:47]
	v_mfma_f32_16x16x32_bf16 v[40:43], v[162:165], v[182:185], v[40:43]
	v_mfma_f32_16x16x32_bf16 v[28:31], v[146:149], v[190:193], v[28:31]
	v_mfma_f32_16x16x32_bf16 v[24:27], v[162:165], v[190:193], v[24:27]
	v_mfma_f32_16x16x32_bf16 v[12:15], v[146:149], v[198:201], v[12:15]
	v_mfma_f32_16x16x32_bf16 v[8:11], v[162:165], v[198:201], v[8:11]
	s_setprio 0
	s_barrier
; #define PG8_STAGE(bufoff, gbase, voff) do { _Pragma("unroll") for (int _i = 0; _i < 2; ++_i) \
;         __builtin_amdgcn_global_load_lds((const unsigned*)((const char*)(gbase) + (voff)[_i]), (LAS unsigned*)(lds + (bufoff) + ldsw + _i * 8192), 16, 0, 0); } while (0)
; #define PG8_LDA(dst, b, h) do { _Pragma("unroll") for (int m = 0; m < 4; ++m) _Pragma("unroll") for (int k = 0; k < 2; ++k) dst[m][k] = *(const LAS bf16x8*)(lds + PG8_SA(b, h) + aoff + m * 2048 + k * 1024); } while (0)
; #define PG8_LDB(dst, b, h) do { _Pragma("unroll") for (int n = 0; n < 2; ++n) _Pragma("unroll") for (int k = 0; k < 2; ++k) dst[n][k] = *(const LAS bf16x8*)(lds + PG8_SB(b, h) + boff + n * 2048 + k * 1024); } while (0)
; #define PG8_MMA(ai, bj, At, Bt) do { __builtin_amdgcn_s_setprio(1); _Pragma("unroll") for (int m = 0; m < 4; ++m) _Pragma("unroll") for (int n = 0; n < 2; ++n) _Pragma("unroll") for (int k = 0; k < 2; ++k) \
;         acc[ai][bj][m][n] = __builtin_amdgcn_mfma_f32_16x16x32_bf16(Bt[n][k], At[m][k], acc[ai][bj][m][n], 0, 0, 0); __builtin_amdgcn_s_setprio(0); } while (0)
; #define PG8_WAIT_V(n) asm volatile("s_waitcnt vmcnt(" #n ")" ::: "memory")
; #define PG8_WAIT_L(n) asm volatile("s_waitcnt lgkmcnt(" #n ")" ::: "memory")
; #define PG8_BAR __builtin_amdgcn_s_barrier()
; #define PG8_SCHED __builtin_amdgcn_sched_barrier(0)
;     ...
;             PG8_STAGE(PG8_SB(0, 1), b2 + hB, voffB);
;             PG8_WAIT_V(6); PG8_BAR; PG8_MMA(1, 1, At, B1); PG8_BAR;
;             PG8_LDB(B0, 1, 0); PG8_SCHED; PG8_LDA(At, 1, 0); PG8_STAGE(PG8_SA(0, 1), a2 + hA, voffA);
;             PG8_WAIT_L(8); PG8_BAR; PG8_WAIT_L(0); PG8_MMA(0, 0, At, B0); PG8_BAR; PG8_SCHED;
;             PG8_LDB(B1, 1, 1); PG8_STAGE(PG8_SB(1, 0), b3, voffB);
;             PG8_BAR; PG8_WAIT_L(0); PG8_MMA(0, 1, At, B1); PG8_BAR;
;             PG8_LDA(At, 1, 1); PG8_STAGE(PG8_SA(1, 0), a3, voffA);
	s_add_u32 s76, s12, 0x20000
	s_addc_u32 s77, s13, 0
	s_add_i32 s53, s72, s61
	v_lshl_add_u64 v[140:141], s[76:77], 0, v[130:131]
	s_mov_b32 m0, s53
	s_nop 0
	global_load_lds_dwordx4 v[140:141], off
	v_lshl_add_u64 v[140:141], s[76:77], 0, v[134:135]
	s_add_i32 m0, s53, 0x2000
	s_nop 0
	global_load_lds_dwordx4 v[140:141], off
	s_waitcnt vmcnt(6)
	s_barrier
	s_setprio 1
	v_mfma_f32_16x16x32_bf16 v[52:55], v[202:205], v[170:173], v[52:55]
	v_mfma_f32_16x16x32_bf16 v[48:51], v[210:213], v[170:173], v[48:51]
	v_mfma_f32_16x16x32_bf16 v[36:39], v[202:205], v[178:181], v[36:39]
	v_mfma_f32_16x16x32_bf16 v[32:35], v[210:213], v[178:181], v[32:35]
	v_mfma_f32_16x16x32_bf16 v[20:23], v[202:205], v[186:189], v[20:23]
	v_mfma_f32_16x16x32_bf16 v[16:19], v[210:213], v[186:189], v[16:19]
	v_mfma_f32_16x16x32_bf16 v[4:7], v[202:205], v[194:197], v[4:7]
	v_mfma_f32_16x16x32_bf16 v[0:3], v[210:213], v[194:197], v[0:3]
	v_mfma_f32_16x16x32_bf16 v[52:55], v[206:209], v[174:177], v[52:55]
	v_mfma_f32_16x16x32_bf16 v[48:51], v[214:217], v[174:177], v[48:51]
	v_mfma_f32_16x16x32_bf16 v[36:39], v[206:209], v[182:185], v[36:39]
	v_mfma_f32_16x16x32_bf16 v[32:35], v[214:217], v[182:185], v[32:35]
	v_mfma_f32_16x16x32_bf16 v[20:23], v[206:209], v[190:193], v[20:23]
	v_mfma_f32_16x16x32_bf16 v[16:19], v[214:217], v[190:193], v[16:19]
	v_mfma_f32_16x16x32_bf16 v[4:7], v[206:209], v[198:201], v[4:7]
	v_mfma_f32_16x16x32_bf16 v[0:3], v[214:217], v[198:201], v[0:3]
	s_setprio 0
	s_add_i32 s53, 0, 0x18000
	v_add_u32_e32 v162, s53, v153
	s_barrier
	ds_read_b128 v[140:143], v162
	ds_read_b128 v[146:149], v162 offset:1024
	ds_read_b128 v[158:161], v162 offset:2048
	ds_read_b128 v[162:165], v162 offset:3072
	s_add_u32 s14, s14, 0x20000
	s_addc_u32 s15, s15, 0
	s_mov_b32 m0, s64
	v_lshl_add_u64 v[202:203], s[14:15], 0, v[128:129]
	ds_read_b128 v[170:173], v156 offset:32768
	ds_read_b128 v[174:177], v156 offset:33792
	ds_read_b128 v[178:181], v156 offset:34816
	ds_read_b128 v[182:185], v156 offset:35840
	ds_read_b128 v[186:189], v156 offset:36864
	ds_read_b128 v[190:193], v156 offset:37888
	ds_read_b128 v[194:197], v156 offset:38912
	ds_read_b128 v[198:201], v156 offset:39936
	global_load_lds_dwordx4 v[202:203], off
	v_lshl_add_u64 v[202:203], s[14:15], 0, v[132:133]
	s_mov_b32 m0, s65
	s_nop 0
	global_load_lds_dwordx4 v[202:203], off
	s_waitcnt lgkmcnt(8)
	s_barrier
	s_waitcnt lgkmcnt(0)
	s_setprio 1
	s_waitcnt lgkmcnt(0)
	v_mfma_f32_16x16x32_bf16 v[124:127], v[140:143], v[170:173], v[124:127]
	v_mfma_f32_16x16x32_bf16 v[120:123], v[158:161], v[170:173], v[120:123]
	v_mfma_f32_16x16x32_bf16 v[108:111], v[140:143], v[178:181], v[108:111]
	v_mfma_f32_16x16x32_bf16 v[104:107], v[158:161], v[178:181], v[104:107]
	v_mfma_f32_16x16x32_bf16 v[92:95], v[140:143], v[186:189], v[92:95]
	v_mfma_f32_16x16x32_bf16 v[88:91], v[158:161], v[186:189], v[88:91]
	v_mfma_f32_16x16x32_bf16 v[76:79], v[140:143], v[194:197], v[76:79]
	v_mfma_f32_16x16x32_bf16 v[72:75], v[158:161], v[194:197], v[72:75]
	v_mfma_f32_16x16x32_bf16 v[124:127], v[146:149], v[174:177], v[124:127]
	v_mfma_f32_16x16x32_bf16 v[120:123], v[162:165], v[174:177], v[120:123]
	v_mfma_f32_16x16x32_bf16 v[108:111], v[146:149], v[182:185], v[108:111]
	v_mfma_f32_16x16x32_bf16 v[104:107], v[162:165], v[182:185], v[104:107]
	v_mfma_f32_16x16x32_bf16 v[92:95], v[146:149], v[190:193], v[92:95]
	v_mfma_f32_16x16x32_bf16 v[88:91], v[162:165], v[190:193], v[88:91]
	v_mfma_f32_16x16x32_bf16 v[76:79], v[146:149], v[198:201], v[76:79]
	v_mfma_f32_16x16x32_bf16 v[72:75], v[162:165], v[198:201], v[72:75]
	s_setprio 0
	s_barrier
	s_add_i32 s14, 0, 0x1c000
	s_add_i32 s15, s53, s61
	v_add_u32_e32 v169, s14, v153
	v_lshl_add_u64 v[150:151], v[150:151], 0, s[38:39]
	s_mov_b32 m0, s15
	ds_read_b128 v[202:205], v169
	ds_read_b128 v[206:209], v169 offset:1024
	ds_read_b128 v[210:213], v169 offset:2048
	ds_read_b128 v[214:217], v169 offset:3072
	global_load_lds_dwordx4 v[150:151], off
	v_lshl_add_u64 v[150:151], v[218:219], 0, s[38:39]
	s_add_i32 m0, s15, 0x2000
	s_nop 0
	global_load_lds_dwordx4 v[150:151], off
	s_barrier
	s_waitcnt lgkmcnt(0)
	s_setprio 1
	s_waitcnt lgkmcnt(0)
	v_mfma_f32_16x16x32_bf16 v[116:119], v[202:205], v[170:173], v[116:119]
	v_mfma_f32_16x16x32_bf16 v[112:115], v[210:213], v[170:173], v[112:115]
	v_mfma_f32_16x16x32_bf16 v[100:103], v[202:205], v[178:181], v[100:103]
	v_mfma_f32_16x16x32_bf16 v[96:99], v[210:213], v[178:181], v[96:99]
	v_mfma_f32_16x16x32_bf16 v[84:87], v[202:205], v[186:189], v[84:87]
	v_mfma_f32_16x16x32_bf16 v[80:83], v[210:213], v[186:189], v[80:83]
	v_mfma_f32_16x16x32_bf16 v[68:71], v[202:205], v[194:197], v[68:71]
	v_mfma_f32_16x16x32_bf16 v[64:67], v[210:213], v[194:197], v[64:67]
	v_mfma_f32_16x16x32_bf16 v[116:119], v[206:209], v[174:177], v[116:119]
	v_mfma_f32_16x16x32_bf16 v[112:115], v[214:217], v[174:177], v[112:115]
	v_mfma_f32_16x16x32_bf16 v[100:103], v[206:209], v[182:185], v[100:103]
	v_mfma_f32_16x16x32_bf16 v[96:99], v[214:217], v[182:185], v[96:99]
	v_mfma_f32_16x16x32_bf16 v[84:87], v[206:209], v[190:193], v[84:87]
	v_mfma_f32_16x16x32_bf16 v[80:83], v[214:217], v[190:193], v[80:83]
	v_mfma_f32_16x16x32_bf16 v[68:71], v[206:209], v[198:201], v[68:71]
	v_mfma_f32_16x16x32_bf16 v[64:67], v[214:217], v[198:201], v[64:67]
	s_setprio 0
	s_mov_b32 m0, s67
	v_lshl_add_u64 v[150:151], v[220:221], 0, s[38:39]
	s_barrier
	ds_read_b128 v[170:173], v156 offset:49152
	ds_read_b128 v[174:177], v156 offset:50176
	ds_read_b128 v[178:181], v156 offset:51200
	ds_read_b128 v[182:185], v156 offset:52224
	ds_read_b128 v[186:189], v156 offset:53248
	ds_read_b128 v[190:193], v156 offset:54272
	ds_read_b128 v[194:197], v156 offset:55296
	ds_read_b128 v[198:201], v156 offset:56320
	global_load_lds_dwordx4 v[150:151], off
	v_lshl_add_u64 v[150:151], v[222:223], 0, s[38:39]
	s_mov_b32 m0, s68
	s_nop 0
	global_load_lds_dwordx4 v[150:151], off
	s_barrier
; __device__ __forceinline__ float sigmoidf_(float x) { return 1.0f / (1.0f + __expf(-x)); }
; #define PG8_STAGE(bufoff, gbase, voff) do { _Pragma("unroll") for (int _i = 0; _i < 2; ++_i) \
;         __builtin_amdgcn_global_load_lds((const unsigned*)((const char*)(gbase) + (voff)[_i]), (LAS unsigned*)(lds + (bufoff) + ldsw + _i * 8192), 16, 0, 0); } while (0)
; #define PG8_MMA(ai, bj, At, Bt) do { __builtin_amdgcn_s_setprio(1); _Pragma("unroll") for (int m = 0; m < 4; ++m) _Pragma("unroll") for (int n = 0; n < 2; ++n) _Pragma("unroll") for (int k = 0; k < 2; ++k) \
;         acc[ai][bj][m][n] = __builtin_amdgcn_mfma_f32_16x16x32_bf16(Bt[n][k], At[m][k], acc[ai][bj][m][n], 0, 0, 0); __builtin_amdgcn_s_setprio(0); } while (0)
; #define PG8_WAIT_V(n) asm volatile("s_waitcnt vmcnt(" #n ")" ::: "memory")
; #define PG8_BAR __builtin_amdgcn_s_barrier()
;     ...
;             PG8_BAR; PG8_WAIT_L(0); PG8_MMA(1, 0, At, B0); PG8_BAR; PG8_SCHED;
;             PG8_STAGE(PG8_SB(1, 1), b3 + hB, voffB);
;             PG8_WAIT_V(6); PG8_BAR; PG8_MMA(1, 1, At, B1); PG8_BAR;
;         }
;     __device__ __forceinline__ void operator()(const f32x4 (&acc)[2][2][4][2], const Unit& u, int wr, int wc, int fr, int fq) const {
;         const __amdgpu_buffer_rsrc_t rsrc = __builtin_amdgcn_make_buffer_rsrc((void*)z, 0, T_ALL * DIN * 2, 0x00020000);
;         const int row0 = row_off + u.pm * 256 + wr * 64 + fr, col0 = u.pn * 256 + wc * 32 + 8 * fq;
; #pragma unroll
;         for (int ai = 0; ai < 2; ++ai)
; #pragma unroll
;             for (int m = 0; m < 4; ++m) {
;                 const int row = row0 + ai * 128 + m * 16;
;                 const bf16_t* rowp = z + (size_t)row * DIN + col0;
; #pragma unroll
;                 for (int bj = 0; bj < 2; ++bj) {
;                     const u32x4 gw = *(const u32x4*)(rowp + O_GA + bj * 128);
;                     f32x4 g0, g1; unpack8(gw, g0, g1);
;                     f32x4 v0, v1;
; #pragma unroll
;                     for (int j = 0; j < 4; ++j) { v0[j] = sigmoidf_(g0[j]) * acc[ai][bj][m][0][j]; v1[j] = sigmoidf_(g1[j]) * acc[ai][bj][m][1][j]; }
;                     const u32x4 mw = *(const u32x4*)(rowp + bj * 128); f32x4 m0, m1; unpack8(mw, m0, m1); v0 += m0; v1 += m1;
;                     __builtin_amdgcn_raw_buffer_store_b128(pack8(v0, v1), rsrc, (unsigned)(((size_t)row * DIN + col0 + bj * 128) * 2), 0, 16  ); }
	s_waitcnt lgkmcnt(0)
	s_setprio 1
	s_waitcnt lgkmcnt(0)
	v_mfma_f32_16x16x32_bf16 v[60:63], v[140:143], v[170:173], v[60:63]
	v_mfma_f32_16x16x32_bf16 v[56:59], v[158:161], v[170:173], v[56:59]
	v_mfma_f32_16x16x32_bf16 v[44:47], v[140:143], v[178:181], v[44:47]
	v_mfma_f32_16x16x32_bf16 v[40:43], v[158:161], v[178:181], v[40:43]
	v_mfma_f32_16x16x32_bf16 v[28:31], v[140:143], v[186:189], v[28:31]
	v_mfma_f32_16x16x32_bf16 v[24:27], v[158:161], v[186:189], v[24:27]
	v_mfma_f32_16x16x32_bf16 v[12:15], v[140:143], v[194:197], v[12:15]
	v_mfma_f32_16x16x32_bf16 v[8:11], v[158:161], v[194:197], v[8:11]
	v_mfma_f32_16x16x32_bf16 v[60:63], v[146:149], v[174:177], v[60:63]
	v_mfma_f32_16x16x32_bf16 v[56:59], v[162:165], v[174:177], v[56:59]
	v_mfma_f32_16x16x32_bf16 v[44:47], v[146:149], v[182:185], v[44:47]
	v_mfma_f32_16x16x32_bf16 v[40:43], v[162:165], v[182:185], v[40:43]
	v_mfma_f32_16x16x32_bf16 v[28:31], v[146:149], v[190:193], v[28:31]
	v_mfma_f32_16x16x32_bf16 v[24:27], v[162:165], v[190:193], v[24:27]
	v_mfma_f32_16x16x32_bf16 v[12:15], v[146:149], v[198:201], v[12:15]
	v_mfma_f32_16x16x32_bf16 v[8:11], v[162:165], v[198:201], v[8:11]
	s_setprio 0
	s_barrier
	s_add_u32 s12, s12, 0x20080
	s_addc_u32 s13, s13, 0
	s_add_i32 s14, s14, s61
	v_lshl_add_u64 v[140:141], s[12:13], 0, v[130:131]
	s_mov_b32 m0, s14
	s_nop 0
	global_load_lds_dwordx4 v[140:141], off
	v_lshl_add_u64 v[140:141], s[12:13], 0, v[134:135]
	s_add_i32 m0, s14, 0x2000
	s_nop 0
	global_load_lds_dwordx4 v[140:141], off
	s_waitcnt vmcnt(6)
	s_barrier
	s_setprio 1
	v_mfma_f32_16x16x32_bf16 v[52:55], v[202:205], v[170:173], v[52:55]
	v_mfma_f32_16x16x32_bf16 v[48:51], v[210:213], v[170:173], v[48:51]
	v_mfma_f32_16x16x32_bf16 v[36:39], v[202:205], v[178:181], v[36:39]
	v_mfma_f32_16x16x32_bf16 v[32:35], v[210:213], v[178:181], v[32:35]
	v_mfma_f32_16x16x32_bf16 v[20:23], v[202:205], v[186:189], v[20:23]
	v_mfma_f32_16x16x32_bf16 v[16:19], v[210:213], v[186:189], v[16:19]
	v_mfma_f32_16x16x32_bf16 v[4:7], v[202:205], v[194:197], v[4:7]
	v_mfma_f32_16x16x32_bf16 v[0:3], v[210:213], v[194:197], v[0:3]
	v_mfma_f32_16x16x32_bf16 v[52:55], v[206:209], v[174:177], v[52:55]
	v_mfma_f32_16x16x32_bf16 v[48:51], v[214:217], v[174:177], v[48:51]
	v_mfma_f32_16x16x32_bf16 v[36:39], v[206:209], v[182:185], v[36:39]
	v_mfma_f32_16x16x32_bf16 v[32:35], v[214:217], v[182:185], v[32:35]
	v_mfma_f32_16x16x32_bf16 v[20:23], v[206:209], v[190:193], v[20:23]
	v_mfma_f32_16x16x32_bf16 v[16:19], v[214:217], v[190:193], v[16:19]
	v_mfma_f32_16x16x32_bf16 v[4:7], v[206:209], v[198:201], v[4:7]
	v_mfma_f32_16x16x32_bf16 v[0:3], v[214:217], v[198:201], v[0:3]
	s_setprio 0
	s_add_i32 s45, s45, 2
	s_add_u32 s37, s37, 0x100
	s_addc_u32 s44, s44, 0
	s_add_u32 s10, s10, 0x100
	s_addc_u32 s11, s11, 0
	s_cmp_gt_u32 s45, 5
	s_barrier
	s_cbranch_scc0 .LBB0_1864
	v_lshl_add_u32 v158, s75, 8, v152
	v_lshl_or_b32 v140, s6, 8, v154
	v_add_u32_e32 v142, 0x4000, v158
	v_ashrrev_i32_e32 v141, 31, v140
	v_mad_i64_i32 v[150:151], s[6:7], v142, s73, 0
	v_lshl_add_u64 v[146:147], v[150:151], 1, s[34:35]
	v_lshlrev_b64 v[142:143], 1, v[140:141]
	v_lshl_add_u64 v[146:147], v[146:147], 0, v[142:143]
	v_add_co_u32_e32 v148, vcc, 0x1000, v146
	s_nop 1
	v_addc_co_u32_e32 v149, vcc, 0, v147, vcc
	v_subrev_u32_e32 v197, s34, v146
	v_add_u32_e32 v198, 0x1200, v197
	global_load_dwordx4 v[200:203], v198, s[34:35]
	v_add_u32_e32 v198, 0x0, v197
	global_load_dwordx4 v[204:207], v198, s[34:35]
	v_add_u32_e32 v198, 0x1300, v197
	global_load_dwordx4 v[208:211], v198, s[34:35]
	v_add_u32_e32 v198, 0x100, v197
	global_load_dwordx4 v[212:215], v198, s[34:35]
	v_add_u32_e32 v198, 0x23200, v197
	global_load_dwordx4 v[232:235], v198, s[34:35]
	v_add_u32_e32 v198, 0x22000, v197
	global_load_dwordx4 v[236:239], v198, s[34:35]
	s_waitcnt vmcnt(4)
	v_mov_b64_e32 v[160:161], v[200:201]
	v_mov_b64_e32 v[162:163], v[202:203]
	v_mov_b64_e32 v[170:171], v[204:205]
	v_mov_b64_e32 v[172:173], v[206:207]
	v_add_u32_e32 v198, 0x23300, v197
	global_load_dwordx4 v[200:203], v198, s[34:35]
	v_add_u32_e32 v198, 0x22100, v197
	global_load_dwordx4 v[204:207], v198, s[34:35]
	s_mov_b32 s100, 0xbfb8aa3b
	v_lshlrev_b32_e32 v242, 16, v160
	v_and_b32_e32 v243, 0xffff0000, v160
	v_lshlrev_b32_e32 v244, 16, v162
	v_and_b32_e32 v245, 0xffff0000, v162
	v_lshlrev_b32_e32 v246, 16, v161
	v_and_b32_e32 v247, 0xffff0000, v161
	v_lshlrev_b32_e32 v248, 16, v163
	v_and_b32_e32 v249, 0xffff0000, v163
	v_pk_mul_f32 v[242:243], v[242:243], s[100:101] op_sel_hi:[1,0]
	v_pk_mul_f32 v[244:245], v[244:245], s[100:101] op_sel_hi:[1,0]
	v_pk_mul_f32 v[246:247], v[246:247], s[100:101] op_sel_hi:[1,0]
	v_pk_mul_f32 v[248:249], v[248:249], s[100:101] op_sel_hi:[1,0]
	v_exp_f32_e32 v242, v242
	v_exp_f32_e32 v243, v243
	v_exp_f32_e32 v244, v244
	v_exp_f32_e32 v245, v245
	v_exp_f32_e32 v246, v246
	v_exp_f32_e32 v247, v247
	v_exp_f32_e32 v248, v248
	v_exp_f32_e32 v249, v249
	s_nop 0
	v_pk_add_f32 v[242:243], v[242:243], 1.0 op_sel_hi:[1,0]
	v_pk_add_f32 v[244:245], v[244:245], 1.0 op_sel_hi:[1,0]
	v_pk_add_f32 v[246:247], v[246:247], 1.0 op_sel_hi:[1,0]
	v_pk_add_f32 v[248:249], v[248:249], 1.0 op_sel_hi:[1,0]
	v_rcp_f32_e32 v250, v242
	v_rcp_f32_e32 v251, v243
	s_nop 0
	v_pk_fma_f32 v[252:253], v[242:243], v[250:251], 1.0 op_sel_hi:[1,1,0] neg_lo:[1,0,0] neg_hi:[1,0,0]
	v_pk_fma_f32 v[250:251], v[252:253], v[250:251], v[250:251]
	v_pk_fma_f32 v[252:253], v[242:243], v[250:251], 1.0 op_sel_hi:[1,1,0] neg_lo:[1,0,0] neg_hi:[1,0,0]
	v_pk_fma_f32 v[254:255], v[252:253], v[250:251], v[250:251]
	v_pk_fma_f32 v[252:253], v[242:243], v[254:255], 1.0 op_sel_hi:[1,1,0] neg_lo:[1,0,0] neg_hi:[1,0,0]
; __device__ __forceinline__ float sigmoidf_(float x) { return 1.0f / (1.0f + __expf(-x)); }
; __device__ __forceinline__ u32x4 pack8(const f32x4 v0, const f32x4 v1) { u32x4 w; w.x = pk2(v0[0], v0[1]); w.y = pk2(v0[2], v0[3]); w.z = pk2(v1[0], v1[1]); w.w = pk2(v1[2], v1[3]); return w; }
; __device__ __forceinline__ void unpack8(const u32x4 w, f32x4& v0, f32x4& v1) { v0 = (f32x4){bflo(w.x), bfhi(w.x), bflo(w.y), bfhi(w.y)}; v1 = (f32x4){bflo(w.z), bfhi(w.z), bflo(w.w), bfhi(w.w)}; }
;     __device__ __forceinline__ void operator()(const f32x4 (&acc)[2][2][4][2], const Unit& u, int wr, int wc, int fr, int fq) const {
;     ...
;                 for (int bj = 0; bj < 2; ++bj) {
;                     const u32x4 gw = *(const u32x4*)(rowp + O_GA + bj * 128);
;                     f32x4 g0, g1; unpack8(gw, g0, g1);
;                     f32x4 v0, v1;
; #pragma unroll
;                     for (int j = 0; j < 4; ++j) { v0[j] = sigmoidf_(g0[j]) * acc[ai][bj][m][0][j]; v1[j] = sigmoidf_(g1[j]) * acc[ai][bj][m][1][j]; }
;                     const u32x4 mw = *(const u32x4*)(rowp + bj * 128); f32x4 m0, m1; unpack8(mw, m0, m1); v0 += m0; v1 += m1;
;                     __builtin_amdgcn_raw_buffer_store_b128(pack8(v0, v1), rsrc, (unsigned)(((size_t)row * DIN + col0 + bj * 128) * 2), 0, 16  ); }
	v_pk_fma_f32 v[254:255], v[252:253], v[250:251], v[254:255]
	v_div_fixup_f32 v242, v254, v242, 1.0
	v_div_fixup_f32 v243, v255, v243, 1.0
	v_rcp_f32_e32 v250, v244
	v_rcp_f32_e32 v251, v245
	s_nop 0
	v_pk_fma_f32 v[252:253], v[244:245], v[250:251], 1.0 op_sel_hi:[1,1,0] neg_lo:[1,0,0] neg_hi:[1,0,0]
	v_pk_fma_f32 v[250:251], v[252:253], v[250:251], v[250:251]
	v_pk_fma_f32 v[252:253], v[244:245], v[250:251], 1.0 op_sel_hi:[1,1,0] neg_lo:[1,0,0] neg_hi:[1,0,0]
	v_pk_fma_f32 v[254:255], v[252:253], v[250:251], v[250:251]
	v_pk_fma_f32 v[252:253], v[244:245], v[254:255], 1.0 op_sel_hi:[1,1,0] neg_lo:[1,0,0] neg_hi:[1,0,0]
	v_pk_fma_f32 v[254:255], v[252:253], v[250:251], v[254:255]
	v_div_fixup_f32 v244, v254, v244, 1.0
	v_div_fixup_f32 v245, v255, v245, 1.0
	v_rcp_f32_e32 v250, v246
	v_rcp_f32_e32 v251, v247
	s_nop 0
	v_pk_fma_f32 v[252:253], v[246:247], v[250:251], 1.0 op_sel_hi:[1,1,0] neg_lo:[1,0,0] neg_hi:[1,0,0]
	v_pk_fma_f32 v[250:251], v[252:253], v[250:251], v[250:251]
	v_pk_fma_f32 v[252:253], v[246:247], v[250:251], 1.0 op_sel_hi:[1,1,0] neg_lo:[1,0,0] neg_hi:[1,0,0]
	v_pk_fma_f32 v[254:255], v[252:253], v[250:251], v[250:251]
	v_pk_fma_f32 v[252:253], v[246:247], v[254:255], 1.0 op_sel_hi:[1,1,0] neg_lo:[1,0,0] neg_hi:[1,0,0]
	v_pk_fma_f32 v[254:255], v[252:253], v[250:251], v[254:255]
	v_div_fixup_f32 v246, v254, v246, 1.0
	v_div_fixup_f32 v247, v255, v247, 1.0
	v_rcp_f32_e32 v250, v248
	v_rcp_f32_e32 v251, v249
	s_nop 0
	v_pk_fma_f32 v[252:253], v[248:249], v[250:251], 1.0 op_sel_hi:[1,1,0] neg_lo:[1,0,0] neg_hi:[1,0,0]
	v_pk_fma_f32 v[250:251], v[252:253], v[250:251], v[250:251]
	v_pk_fma_f32 v[252:253], v[248:249], v[250:251], 1.0 op_sel_hi:[1,1,0] neg_lo:[1,0,0] neg_hi:[1,0,0]
	v_pk_fma_f32 v[254:255], v[252:253], v[250:251], v[250:251]
	v_pk_fma_f32 v[252:253], v[248:249], v[254:255], 1.0 op_sel_hi:[1,1,0] neg_lo:[1,0,0] neg_hi:[1,0,0]
	v_pk_fma_f32 v[254:255], v[252:253], v[250:251], v[254:255]
	v_div_fixup_f32 v248, v254, v248, 1.0
	v_div_fixup_f32 v249, v255, v249, 1.0
	s_mov_b64 vcc, s[10:11]
	s_mov_b64 vcc, s[12:13]
	s_mov_b64 vcc, s[14:15]
	s_mov_b64 vcc, s[16:17]
	v_and_b32_e32 v177, 0xffff0000, v170
	v_lshlrev_b32_e32 v178, 16, v172
	v_lshlrev_b32_e32 v176, 16, v170
	v_and_b32_e32 v179, 0xffff0000, v172
	v_lshlrev_b32_e32 v172, 16, v173
	v_and_b32_e32 v173, 0xffff0000, v173
	v_lshlrev_b32_e32 v170, 16, v171
	v_and_b32_e32 v171, 0xffff0000, v171
	v_pk_fma_f32 v[124:125], v[124:125], v[242:243], v[176:177]
	v_pk_fma_f32 v[160:161], v[122:123], v[248:249], v[172:173]
	v_pk_fma_f32 v[122:123], v[120:121], v[244:245], v[178:179]
	v_add_lshl_u32 v141, v140, v150, 1
	v_pk_fma_f32 v[126:127], v[126:127], v[246:247], v[170:171]
	v_cvt_pk_bf16_f32 v120, v124, v125
	s_nop 0
	v_cvt_pk_bf16_f32 v121, v126, v127
	v_cvt_pk_bf16_f32 v122, v122, v123
	v_cvt_pk_bf16_f32 v123, v160, v161
	buffer_store_dwordx4 v[120:123], v141, s[20:23], 0 offen sc1
	s_nop 0
	s_waitcnt vmcnt(5)
	v_mov_b64_e32 v[120:121], v[208:209]
	v_mov_b64_e32 v[122:123], v[210:211]
	v_mov_b64_e32 v[124:125], v[212:213]
	v_mov_b64_e32 v[126:127], v[214:215]
	v_add_u32_e32 v198, 0x45200, v197
	global_load_dwordx4 v[208:211], v198, s[34:35]
	v_add_u32_e32 v198, 0x44000, v197
	global_load_dwordx4 v[212:215], v198, s[34:35]
	s_mov_b32 s100, 0xbfb8aa3b
	v_lshlrev_b32_e32 v242, 16, v120
	v_and_b32_e32 v243, 0xffff0000, v120
	v_lshlrev_b32_e32 v244, 16, v122
	v_and_b32_e32 v245, 0xffff0000, v122
	v_lshlrev_b32_e32 v246, 16, v121
	v_and_b32_e32 v247, 0xffff0000, v121
	v_lshlrev_b32_e32 v248, 16, v123
	v_and_b32_e32 v249, 0xffff0000, v123
	v_pk_mul_f32 v[242:243], v[242:243], s[100:101] op_sel_hi:[1,0]
	v_pk_mul_f32 v[244:245], v[244:245], s[100:101] op_sel_hi:[1,0]
	v_pk_mul_f32 v[246:247], v[246:247], s[100:101] op_sel_hi:[1,0]
	v_pk_mul_f32 v[248:249], v[248:249], s[100:101] op_sel_hi:[1,0]
	v_exp_f32_e32 v242, v242
	v_exp_f32_e32 v243, v243
	v_exp_f32_e32 v244, v244
	v_exp_f32_e32 v245, v245
	v_exp_f32_e32 v246, v246
	v_exp_f32_e32 v247, v247
	v_exp_f32_e32 v248, v248
	v_exp_f32_e32 v249, v249
	s_nop 0
	v_pk_add_f32 v[242:243], v[242:243], 1.0 op_sel_hi:[1,0]
	v_pk_add_f32 v[244:245], v[244:245], 1.0 op_sel_hi:[1,0]
	v_pk_add_f32 v[246:247], v[246:247], 1.0 op_sel_hi:[1,0]
	v_pk_add_f32 v[248:249], v[248:249], 1.0 op_sel_hi:[1,0]
	v_rcp_f32_e32 v250, v242
	v_rcp_f32_e32 v251, v243
	s_nop 0
	v_pk_fma_f32 v[252:253], v[242:243], v[250:251], 1.0 op_sel_hi:[1,1,0] neg_lo:[1,0,0] neg_hi:[1,0,0]
	v_pk_fma_f32 v[250:251], v[252:253], v[250:251], v[250:251]
	v_pk_fma_f32 v[252:253], v[242:243], v[250:251], 1.0 op_sel_hi:[1,1,0] neg_lo:[1,0,0] neg_hi:[1,0,0]
	v_pk_fma_f32 v[254:255], v[252:253], v[250:251], v[250:251]
	v_pk_fma_f32 v[252:253], v[242:243], v[254:255], 1.0 op_sel_hi:[1,1,0] neg_lo:[1,0,0] neg_hi:[1,0,0]
	v_pk_fma_f32 v[254:255], v[252:253], v[250:251], v[254:255]
	v_div_fixup_f32 v242, v254, v242, 1.0
	v_div_fixup_f32 v243, v255, v243, 1.0
	v_rcp_f32_e32 v250, v244
	v_rcp_f32_e32 v251, v245
	s_nop 0
	v_pk_fma_f32 v[252:253], v[244:245], v[250:251], 1.0 op_sel_hi:[1,1,0] neg_lo:[1,0,0] neg_hi:[1,0,0]
	v_pk_fma_f32 v[250:251], v[252:253], v[250:251], v[250:251]
	v_pk_fma_f32 v[252:253], v[244:245], v[250:251], 1.0 op_sel_hi:[1,1,0] neg_lo:[1,0,0] neg_hi:[1,0,0]
	v_pk_fma_f32 v[254:255], v[252:253], v[250:251], v[250:251]
	v_pk_fma_f32 v[252:253], v[244:245], v[254:255], 1.0 op_sel_hi:[1,1,0] neg_lo:[1,0,0] neg_hi:[1,0,0]
	v_pk_fma_f32 v[254:255], v[252:253], v[250:251], v[254:255]
	v_div_fixup_f32 v244, v254, v244, 1.0
	v_div_fixup_f32 v245, v255, v245, 1.0
	v_rcp_f32_e32 v250, v246
	v_rcp_f32_e32 v251, v247
	s_nop 0
; __device__ __forceinline__ float sigmoidf_(float x) { return 1.0f / (1.0f + __expf(-x)); }
; __device__ __forceinline__ u32x4 pack8(const f32x4 v0, const f32x4 v1) { u32x4 w; w.x = pk2(v0[0], v0[1]); w.y = pk2(v0[2], v0[3]); w.z = pk2(v1[0], v1[1]); w.w = pk2(v1[2], v1[3]); return w; }
; __device__ __forceinline__ void unpack8(const u32x4 w, f32x4& v0, f32x4& v1) { v0 = (f32x4){bflo(w.x), bfhi(w.x), bflo(w.y), bfhi(w.y)}; v1 = (f32x4){bflo(w.z), bfhi(w.z), bflo(w.w), bfhi(w.w)}; }
;     __device__ __forceinline__ void operator()(const f32x4 (&acc)[2][2][4][2], const Unit& u, int wr, int wc, int fr, int fq) const {
;     ...
;                 for (int bj = 0; bj < 2; ++bj) {
;                     const u32x4 gw = *(const u32x4*)(rowp + O_GA + bj * 128);
;                     f32x4 g0, g1; unpack8(gw, g0, g1);
;                     f32x4 v0, v1;
; #pragma unroll
;                     for (int j = 0; j < 4; ++j) { v0[j] = sigmoidf_(g0[j]) * acc[ai][bj][m][0][j]; v1[j] = sigmoidf_(g1[j]) * acc[ai][bj][m][1][j]; }
;                     const u32x4 mw = *(const u32x4*)(rowp + bj * 128); f32x4 m0, m1; unpack8(mw, m0, m1); v0 += m0; v1 += m1;
;                     __builtin_amdgcn_raw_buffer_store_b128(pack8(v0, v1), rsrc, (unsigned)(((size_t)row * DIN + col0 + bj * 128) * 2), 0, 16  ); }
	v_pk_fma_f32 v[252:253], v[246:247], v[250:251], 1.0 op_sel_hi:[1,1,0] neg_lo:[1,0,0] neg_hi:[1,0,0]
	v_pk_fma_f32 v[250:251], v[252:253], v[250:251], v[250:251]
	v_pk_fma_f32 v[252:253], v[246:247], v[250:251], 1.0 op_sel_hi:[1,1,0] neg_lo:[1,0,0] neg_hi:[1,0,0]
	v_pk_fma_f32 v[254:255], v[252:253], v[250:251], v[250:251]
	v_pk_fma_f32 v[252:253], v[246:247], v[254:255], 1.0 op_sel_hi:[1,1,0] neg_lo:[1,0,0] neg_hi:[1,0,0]
	v_pk_fma_f32 v[254:255], v[252:253], v[250:251], v[254:255]
	v_div_fixup_f32 v246, v254, v246, 1.0
	v_div_fixup_f32 v247, v255, v247, 1.0
	v_rcp_f32_e32 v250, v248
	v_rcp_f32_e32 v251, v249
	s_nop 0
	v_pk_fma_f32 v[252:253], v[248:249], v[250:251], 1.0 op_sel_hi:[1,1,0] neg_lo:[1,0,0] neg_hi:[1,0,0]
	v_pk_fma_f32 v[250:251], v[252:253], v[250:251], v[250:251]
	v_pk_fma_f32 v[252:253], v[248:249], v[250:251], 1.0 op_sel_hi:[1,1,0] neg_lo:[1,0,0] neg_hi:[1,0,0]
	v_pk_fma_f32 v[254:255], v[252:253], v[250:251], v[250:251]
	v_pk_fma_f32 v[252:253], v[248:249], v[254:255], 1.0 op_sel_hi:[1,1,0] neg_lo:[1,0,0] neg_hi:[1,0,0]
	v_pk_fma_f32 v[254:255], v[252:253], v[250:251], v[254:255]
	v_div_fixup_f32 v248, v254, v248, 1.0
	v_div_fixup_f32 v249, v255, v249, 1.0
	v_lshlrev_b32_e32 v150, 16, v124
	v_and_b32_e32 v151, 0xffff0000, v124
	v_lshlrev_b32_e32 v160, 16, v126
	v_and_b32_e32 v161, 0xffff0000, v126
	v_lshlrev_b32_e32 v126, 16, v127
	v_and_b32_e32 v127, 0xffff0000, v127
	v_lshlrev_b32_e32 v124, 16, v125
	v_and_b32_e32 v125, 0xffff0000, v125
	v_pk_fma_f32 v[116:117], v[116:117], v[242:243], v[150:151]
	v_pk_fma_f32 v[120:121], v[114:115], v[248:249], v[126:127]
	v_pk_fma_f32 v[114:115], v[112:113], v[244:245], v[160:161]
	v_cvt_pk_bf16_f32 v112, v116, v117
	v_pk_fma_f32 v[118:119], v[118:119], v[246:247], v[124:125]
	s_nop 0
	v_cvt_pk_bf16_f32 v113, v118, v119
	v_cvt_pk_bf16_f32 v114, v114, v115
	v_cvt_pk_bf16_f32 v115, v120, v121
	buffer_store_dwordx4 v[112:115], v141, s[20:23], 0 offen offset:256 sc1
	s_nop 1
	v_add_u32_e32 v112, 0x4010, v158
	v_mad_i64_i32 v[114:115], s[6:7], v112, s73, 0
	v_lshl_add_u64 v[112:113], v[114:115], 1, s[34:35]
	v_lshl_add_u64 v[112:113], v[112:113], 0, v[142:143]
	v_add_co_u32_e32 v116, vcc, s74, v112
	s_nop 1
	v_addc_co_u32_e32 v117, vcc, 0, v113, vcc
	s_waitcnt vmcnt(6)
	v_mov_b64_e32 v[118:119], v[232:233]
	v_mov_b64_e32 v[120:121], v[234:235]
	v_mov_b64_e32 v[122:123], v[236:237]
	v_mov_b64_e32 v[124:125], v[238:239]
	v_add_u32_e32 v198, 0x45300, v197
	global_load_dwordx4 v[232:235], v198, s[34:35]
	v_add_u32_e32 v198, 0x44100, v197
	global_load_dwordx4 v[236:239], v198, s[34:35]
	s_mov_b32 s100, 0xbfb8aa3b
	v_lshlrev_b32_e32 v242, 16, v118
	v_and_b32_e32 v243, 0xffff0000, v118
	v_lshlrev_b32_e32 v244, 16, v120
	v_and_b32_e32 v245, 0xffff0000, v120
	v_lshlrev_b32_e32 v246, 16, v119
	v_and_b32_e32 v247, 0xffff0000, v119
	v_lshlrev_b32_e32 v248, 16, v121
	v_and_b32_e32 v249, 0xffff0000, v121
	v_pk_mul_f32 v[242:243], v[242:243], s[100:101] op_sel_hi:[1,0]
	v_pk_mul_f32 v[244:245], v[244:245], s[100:101] op_sel_hi:[1,0]
	v_pk_mul_f32 v[246:247], v[246:247], s[100:101] op_sel_hi:[1,0]
	v_pk_mul_f32 v[248:249], v[248:249], s[100:101] op_sel_hi:[1,0]
	v_exp_f32_e32 v242, v242
	v_exp_f32_e32 v243, v243
	v_exp_f32_e32 v244, v244
	v_exp_f32_e32 v245, v245
	v_exp_f32_e32 v246, v246
	v_exp_f32_e32 v247, v247
	v_exp_f32_e32 v248, v248
	v_exp_f32_e32 v249, v249
	s_nop 0
	v_pk_add_f32 v[242:243], v[242:243], 1.0 op_sel_hi:[1,0]
	v_pk_add_f32 v[244:245], v[244:245], 1.0 op_sel_hi:[1,0]
	v_pk_add_f32 v[246:247], v[246:247], 1.0 op_sel_hi:[1,0]
	v_pk_add_f32 v[248:249], v[248:249], 1.0 op_sel_hi:[1,0]
	v_rcp_f32_e32 v250, v242
	v_rcp_f32_e32 v251, v243
	s_nop 0
	v_pk_fma_f32 v[252:253], v[242:243], v[250:251], 1.0 op_sel_hi:[1,1,0] neg_lo:[1,0,0] neg_hi:[1,0,0]
	v_pk_fma_f32 v[250:251], v[252:253], v[250:251], v[250:251]
	v_pk_fma_f32 v[252:253], v[242:243], v[250:251], 1.0 op_sel_hi:[1,1,0] neg_lo:[1,0,0] neg_hi:[1,0,0]
	v_pk_fma_f32 v[254:255], v[252:253], v[250:251], v[250:251]
	v_pk_fma_f32 v[252:253], v[242:243], v[254:255], 1.0 op_sel_hi:[1,1,0] neg_lo:[1,0,0] neg_hi:[1,0,0]
	v_pk_fma_f32 v[254:255], v[252:253], v[250:251], v[254:255]
	v_div_fixup_f32 v242, v254, v242, 1.0
	v_div_fixup_f32 v243, v255, v243, 1.0
	v_rcp_f32_e32 v250, v244
	v_rcp_f32_e32 v251, v245
	s_nop 0
	v_pk_fma_f32 v[252:253], v[244:245], v[250:251], 1.0 op_sel_hi:[1,1,0] neg_lo:[1,0,0] neg_hi:[1,0,0]
	v_pk_fma_f32 v[250:251], v[252:253], v[250:251], v[250:251]
	v_pk_fma_f32 v[252:253], v[244:245], v[250:251], 1.0 op_sel_hi:[1,1,0] neg_lo:[1,0,0] neg_hi:[1,0,0]
	v_pk_fma_f32 v[254:255], v[252:253], v[250:251], v[250:251]
	v_pk_fma_f32 v[252:253], v[244:245], v[254:255], 1.0 op_sel_hi:[1,1,0] neg_lo:[1,0,0] neg_hi:[1,0,0]
	v_pk_fma_f32 v[254:255], v[252:253], v[250:251], v[254:255]
	v_div_fixup_f32 v244, v254, v244, 1.0
	v_div_fixup_f32 v245, v255, v245, 1.0
	v_rcp_f32_e32 v250, v246
	v_rcp_f32_e32 v251, v247
	s_nop 0
	v_pk_fma_f32 v[252:253], v[246:247], v[250:251], 1.0 op_sel_hi:[1,1,0] neg_lo:[1,0,0] neg_hi:[1,0,0]
	v_pk_fma_f32 v[250:251], v[252:253], v[250:251], v[250:251]
	v_pk_fma_f32 v[252:253], v[246:247], v[250:251], 1.0 op_sel_hi:[1,1,0] neg_lo:[1,0,0] neg_hi:[1,0,0]
	v_pk_fma_f32 v[254:255], v[252:253], v[250:251], v[250:251]
	v_pk_fma_f32 v[252:253], v[246:247], v[254:255], 1.0 op_sel_hi:[1,1,0] neg_lo:[1,0,0] neg_hi:[1,0,0]
	v_pk_fma_f32 v[254:255], v[252:253], v[250:251], v[254:255]
	v_div_fixup_f32 v246, v254, v246, 1.0
	v_div_fixup_f32 v247, v255, v247, 1.0
	v_rcp_f32_e32 v250, v248
	v_rcp_f32_e32 v251, v249
	s_nop 0
	v_pk_fma_f32 v[252:253], v[248:249], v[250:251], 1.0 op_sel_hi:[1,1,0] neg_lo:[1,0,0] neg_hi:[1,0,0]
	v_pk_fma_f32 v[250:251], v[252:253], v[250:251], v[250:251]
	v_pk_fma_f32 v[252:253], v[248:249], v[250:251], 1.0 op_sel_hi:[1,1,0] neg_lo:[1,0,0] neg_hi:[1,0,0]
	v_pk_fma_f32 v[254:255], v[252:253], v[250:251], v[250:251]
	v_pk_fma_f32 v[252:253], v[248:249], v[254:255], 1.0 op_sel_hi:[1,1,0] neg_lo:[1,0,0] neg_hi:[1,0,0]
	v_pk_fma_f32 v[254:255], v[252:253], v[250:251], v[254:255]
	v_div_fixup_f32 v248, v254, v248, 1.0
	v_div_fixup_f32 v249, v255, v249, 1.0
	v_and_b32_e32 v151, 0xffff0000, v124
	v_lshlrev_b32_e32 v148, 16, v122
	v_and_b32_e32 v149, 0xffff0000, v122
	v_lshlrev_b32_e32 v150, 16, v124
	v_lshlrev_b32_e32 v124, 16, v125
	v_and_b32_e32 v125, 0xffff0000, v125
	v_lshlrev_b32_e32 v122, 16, v123
	v_and_b32_e32 v123, 0xffff0000, v123
	v_pk_fma_f32 v[108:109], v[108:109], v[242:243], v[148:149]
	v_pk_fma_f32 v[118:119], v[106:107], v[248:249], v[124:125]
	v_pk_fma_f32 v[106:107], v[104:105], v[244:245], v[150:151]
	v_add_lshl_u32 v120, v140, v114, 1
	v_pk_fma_f32 v[110:111], v[110:111], v[246:247], v[122:123]
	v_cvt_pk_bf16_f32 v104, v108, v109
	s_nop 0
	v_cvt_pk_bf16_f32 v105, v110, v111
	v_cvt_pk_bf16_f32 v106, v106, v107
	v_cvt_pk_bf16_f32 v107, v118, v119
	buffer_store_dwordx4 v[104:107], v120, s[20:23], 0 offen sc1
	s_nop 0
	s_waitcnt vmcnt(7)
; __device__ __forceinline__ float sigmoidf_(float x) { return 1.0f / (1.0f + __expf(-x)); }
; __device__ __forceinline__ u32x4 pack8(const f32x4 v0, const f32x4 v1) { u32x4 w; w.x = pk2(v0[0], v0[1]); w.y = pk2(v0[2], v0[3]); w.z = pk2(v1[0], v1[1]); w.w = pk2(v1[2], v1[3]); return w; }
; __device__ __forceinline__ void unpack8(const u32x4 w, f32x4& v0, f32x4& v1) { v0 = (f32x4){bflo(w.x), bfhi(w.x), bflo(w.y), bfhi(w.y)}; v1 = (f32x4){bflo(w.z), bfhi(w.z), bflo(w.w), bfhi(w.w)}; }
;     __device__ __forceinline__ void operator()(const f32x4 (&acc)[2][2][4][2], const Unit& u, int wr, int wc, int fr, int fq) const {
;     ...
;                 const int row = row0 + ai * 128 + m * 16;
;                 const bf16_t* rowp = z + (size_t)row * DIN + col0;
; #pragma unroll
;                 for (int bj = 0; bj < 2; ++bj) {
;                     const u32x4 gw = *(const u32x4*)(rowp + O_GA + bj * 128);
;                     f32x4 g0, g1; unpack8(gw, g0, g1);
;                     f32x4 v0, v1;
; #pragma unroll
;                     for (int j = 0; j < 4; ++j) { v0[j] = sigmoidf_(g0[j]) * acc[ai][bj][m][0][j]; v1[j] = sigmoidf_(g1[j]) * acc[ai][bj][m][1][j]; }
;                     const u32x4 mw = *(const u32x4*)(rowp + bj * 128); f32x4 m0, m1; unpack8(mw, m0, m1); v0 += m0; v1 += m1;
;                     __builtin_amdgcn_raw_buffer_store_b128(pack8(v0, v1), rsrc, (unsigned)(((size_t)row * DIN + col0 + bj * 128) * 2), 0, 16  ); }
	v_mov_b64_e32 v[104:105], v[200:201]
	v_mov_b64_e32 v[106:107], v[202:203]
	v_mov_b64_e32 v[108:109], v[204:205]
	v_mov_b64_e32 v[110:111], v[206:207]
	v_add_u32_e32 v198, 0x67200, v197
	global_load_dwordx4 v[200:203], v198, s[34:35]
	v_add_u32_e32 v198, 0x66000, v197
	global_load_dwordx4 v[204:207], v198, s[34:35]
	s_mov_b32 s100, 0xbfb8aa3b
	v_lshlrev_b32_e32 v242, 16, v106
	v_and_b32_e32 v243, 0xffff0000, v106
	v_lshlrev_b32_e32 v244, 16, v104
	v_and_b32_e32 v245, 0xffff0000, v104
	v_lshlrev_b32_e32 v246, 16, v105
	v_and_b32_e32 v247, 0xffff0000, v105
	v_lshlrev_b32_e32 v248, 16, v107
	v_and_b32_e32 v249, 0xffff0000, v107
	v_pk_mul_f32 v[242:243], v[242:243], s[100:101] op_sel_hi:[1,0]
	v_pk_mul_f32 v[244:245], v[244:245], s[100:101] op_sel_hi:[1,0]
	v_pk_mul_f32 v[246:247], v[246:247], s[100:101] op_sel_hi:[1,0]
	v_pk_mul_f32 v[248:249], v[248:249], s[100:101] op_sel_hi:[1,0]
	v_exp_f32_e32 v242, v242
	v_exp_f32_e32 v243, v243
	v_exp_f32_e32 v244, v244
	v_exp_f32_e32 v245, v245
	v_exp_f32_e32 v246, v246
	v_exp_f32_e32 v247, v247
	v_exp_f32_e32 v248, v248
	v_exp_f32_e32 v249, v249
	s_nop 0
	v_pk_add_f32 v[242:243], v[242:243], 1.0 op_sel_hi:[1,0]
	v_pk_add_f32 v[244:245], v[244:245], 1.0 op_sel_hi:[1,0]
	v_pk_add_f32 v[246:247], v[246:247], 1.0 op_sel_hi:[1,0]
	v_pk_add_f32 v[248:249], v[248:249], 1.0 op_sel_hi:[1,0]
	v_rcp_f32_e32 v250, v242
	v_rcp_f32_e32 v251, v243
	s_nop 0
	v_pk_fma_f32 v[252:253], v[242:243], v[250:251], 1.0 op_sel_hi:[1,1,0] neg_lo:[1,0,0] neg_hi:[1,0,0]
	v_pk_fma_f32 v[250:251], v[252:253], v[250:251], v[250:251]
	v_pk_fma_f32 v[252:253], v[242:243], v[250:251], 1.0 op_sel_hi:[1,1,0] neg_lo:[1,0,0] neg_hi:[1,0,0]
	v_pk_fma_f32 v[254:255], v[252:253], v[250:251], v[250:251]
	v_pk_fma_f32 v[252:253], v[242:243], v[254:255], 1.0 op_sel_hi:[1,1,0] neg_lo:[1,0,0] neg_hi:[1,0,0]
	v_pk_fma_f32 v[254:255], v[252:253], v[250:251], v[254:255]
	v_div_fixup_f32 v242, v254, v242, 1.0
	v_div_fixup_f32 v243, v255, v243, 1.0
	v_rcp_f32_e32 v250, v244
	v_rcp_f32_e32 v251, v245
	s_nop 0
	v_pk_fma_f32 v[252:253], v[244:245], v[250:251], 1.0 op_sel_hi:[1,1,0] neg_lo:[1,0,0] neg_hi:[1,0,0]
	v_pk_fma_f32 v[250:251], v[252:253], v[250:251], v[250:251]
	v_pk_fma_f32 v[252:253], v[244:245], v[250:251], 1.0 op_sel_hi:[1,1,0] neg_lo:[1,0,0] neg_hi:[1,0,0]
	v_pk_fma_f32 v[254:255], v[252:253], v[250:251], v[250:251]
	v_pk_fma_f32 v[252:253], v[244:245], v[254:255], 1.0 op_sel_hi:[1,1,0] neg_lo:[1,0,0] neg_hi:[1,0,0]
	v_pk_fma_f32 v[254:255], v[252:253], v[250:251], v[254:255]
	v_div_fixup_f32 v244, v254, v244, 1.0
	v_div_fixup_f32 v245, v255, v245, 1.0
	v_rcp_f32_e32 v250, v246
	v_rcp_f32_e32 v251, v247
	s_nop 0
	v_pk_fma_f32 v[252:253], v[246:247], v[250:251], 1.0 op_sel_hi:[1,1,0] neg_lo:[1,0,0] neg_hi:[1,0,0]
	v_pk_fma_f32 v[250:251], v[252:253], v[250:251], v[250:251]
	v_pk_fma_f32 v[252:253], v[246:247], v[250:251], 1.0 op_sel_hi:[1,1,0] neg_lo:[1,0,0] neg_hi:[1,0,0]
	v_pk_fma_f32 v[254:255], v[252:253], v[250:251], v[250:251]
	v_pk_fma_f32 v[252:253], v[246:247], v[254:255], 1.0 op_sel_hi:[1,1,0] neg_lo:[1,0,0] neg_hi:[1,0,0]
	v_pk_fma_f32 v[254:255], v[252:253], v[250:251], v[254:255]
	v_div_fixup_f32 v246, v254, v246, 1.0
	v_div_fixup_f32 v247, v255, v247, 1.0
	v_rcp_f32_e32 v250, v248
	v_rcp_f32_e32 v251, v249
	s_nop 0
	v_pk_fma_f32 v[252:253], v[248:249], v[250:251], 1.0 op_sel_hi:[1,1,0] neg_lo:[1,0,0] neg_hi:[1,0,0]
	v_pk_fma_f32 v[250:251], v[252:253], v[250:251], v[250:251]
	v_pk_fma_f32 v[252:253], v[248:249], v[250:251], 1.0 op_sel_hi:[1,1,0] neg_lo:[1,0,0] neg_hi:[1,0,0]
	v_pk_fma_f32 v[254:255], v[252:253], v[250:251], v[250:251]
	v_pk_fma_f32 v[252:253], v[248:249], v[254:255], 1.0 op_sel_hi:[1,1,0] neg_lo:[1,0,0] neg_hi:[1,0,0]
	v_pk_fma_f32 v[254:255], v[252:253], v[250:251], v[254:255]
	v_div_fixup_f32 v248, v254, v248, 1.0
	v_div_fixup_f32 v249, v255, v249, 1.0
	v_lshlrev_b32_e32 v116, 16, v108
	v_and_b32_e32 v117, 0xffff0000, v108
	v_lshlrev_b32_e32 v118, 16, v110
	v_and_b32_e32 v119, 0xffff0000, v110
	v_lshlrev_b32_e32 v110, 16, v111
	v_and_b32_e32 v111, 0xffff0000, v111
	v_lshlrev_b32_e32 v108, 16, v109
	v_and_b32_e32 v109, 0xffff0000, v109
	v_pk_fma_f32 v[100:101], v[100:101], v[244:245], v[116:117]
	v_pk_fma_f32 v[104:105], v[98:99], v[248:249], v[110:111]
	v_pk_fma_f32 v[98:99], v[96:97], v[242:243], v[118:119]
	v_cvt_pk_bf16_f32 v96, v100, v101
	v_pk_fma_f32 v[102:103], v[102:103], v[246:247], v[108:109]
	s_nop 0
	v_cvt_pk_bf16_f32 v97, v102, v103
	v_cvt_pk_bf16_f32 v98, v98, v99
	v_cvt_pk_bf16_f32 v99, v104, v105
	buffer_store_dwordx4 v[96:99], v120, s[20:23], 0 offen offset:256 sc1
	s_nop 1
	v_add_u32_e32 v96, 0x4020, v158
	v_mad_i64_i32 v[98:99], s[6:7], v96, s73, 0
	v_lshl_add_u64 v[96:97], v[98:99], 1, s[34:35]
	v_lshl_add_u64 v[96:97], v[96:97], 0, v[142:143]
	v_add_co_u32_e32 v100, vcc, s74, v96
	s_nop 1
	v_addc_co_u32_e32 v101, vcc, 0, v97, vcc
	s_waitcnt vmcnt(7)
; __device__ __forceinline__ float sigmoidf_(float x) { return 1.0f / (1.0f + __expf(-x)); }
; __device__ __forceinline__ u32x4 pack8(const f32x4 v0, const f32x4 v1) { u32x4 w; w.x = pk2(v0[0], v0[1]); w.y = pk2(v0[2], v0[3]); w.z = pk2(v1[0], v1[1]); w.w = pk2(v1[2], v1[3]); return w; }
; __device__ __forceinline__ void unpack8(const u32x4 w, f32x4& v0, f32x4& v1) { v0 = (f32x4){bflo(w.x), bfhi(w.x), bflo(w.y), bfhi(w.y)}; v1 = (f32x4){bflo(w.z), bfhi(w.z), bflo(w.w), bfhi(w.w)}; }
;     __device__ __forceinline__ void operator()(const f32x4 (&acc)[2][2][4][2], const Unit& u, int wr, int wc, int fr, int fq) const {
;     ...
;                 const int row = row0 + ai * 128 + m * 16;
;                 const bf16_t* rowp = z + (size_t)row * DIN + col0;
; #pragma unroll
;                 for (int bj = 0; bj < 2; ++bj) {
;                     const u32x4 gw = *(const u32x4*)(rowp + O_GA + bj * 128);
;                     f32x4 g0, g1; unpack8(gw, g0, g1);
;                     f32x4 v0, v1;
; #pragma unroll
;                     for (int j = 0; j < 4; ++j) { v0[j] = sigmoidf_(g0[j]) * acc[ai][bj][m][0][j]; v1[j] = sigmoidf_(g1[j]) * acc[ai][bj][m][1][j]; }
;                     const u32x4 mw = *(const u32x4*)(rowp + bj * 128); f32x4 m0, m1; unpack8(mw, m0, m1); v0 += m0; v1 += m1;
;                     __builtin_amdgcn_raw_buffer_store_b128(pack8(v0, v1), rsrc, (unsigned)(((size_t)row * DIN + col0 + bj * 128) * 2), 0, 16  ); }
	v_mov_b64_e32 v[102:103], v[208:209]
	v_mov_b64_e32 v[104:105], v[210:211]
	v_mov_b64_e32 v[106:107], v[212:213]
	v_mov_b64_e32 v[108:109], v[214:215]
	v_add_u32_e32 v198, 0x67300, v197
	global_load_dwordx4 v[208:211], v198, s[34:35]
	v_add_u32_e32 v198, 0x66100, v197
	global_load_dwordx4 v[212:215], v198, s[34:35]
	s_mov_b32 s100, 0xbfb8aa3b
	v_lshlrev_b32_e32 v242, 16, v102
	v_and_b32_e32 v243, 0xffff0000, v102
	v_lshlrev_b32_e32 v244, 16, v104
	v_and_b32_e32 v245, 0xffff0000, v104
	v_lshlrev_b32_e32 v246, 16, v103
	v_and_b32_e32 v247, 0xffff0000, v103
	v_lshlrev_b32_e32 v248, 16, v105
	v_and_b32_e32 v249, 0xffff0000, v105
	v_pk_mul_f32 v[242:243], v[242:243], s[100:101] op_sel_hi:[1,0]
	v_pk_mul_f32 v[244:245], v[244:245], s[100:101] op_sel_hi:[1,0]
	v_pk_mul_f32 v[246:247], v[246:247], s[100:101] op_sel_hi:[1,0]
	v_pk_mul_f32 v[248:249], v[248:249], s[100:101] op_sel_hi:[1,0]
	v_exp_f32_e32 v242, v242
	v_exp_f32_e32 v243, v243
	v_exp_f32_e32 v244, v244
	v_exp_f32_e32 v245, v245
	v_exp_f32_e32 v246, v246
	v_exp_f32_e32 v247, v247
	v_exp_f32_e32 v248, v248
	v_exp_f32_e32 v249, v249
	s_nop 0
	v_pk_add_f32 v[242:243], v[242:243], 1.0 op_sel_hi:[1,0]
	v_pk_add_f32 v[244:245], v[244:245], 1.0 op_sel_hi:[1,0]
	v_pk_add_f32 v[246:247], v[246:247], 1.0 op_sel_hi:[1,0]
	v_pk_add_f32 v[248:249], v[248:249], 1.0 op_sel_hi:[1,0]
	v_rcp_f32_e32 v250, v242
	v_rcp_f32_e32 v251, v243
	s_nop 0
	v_pk_fma_f32 v[252:253], v[242:243], v[250:251], 1.0 op_sel_hi:[1,1,0] neg_lo:[1,0,0] neg_hi:[1,0,0]
	v_pk_fma_f32 v[250:251], v[252:253], v[250:251], v[250:251]
	v_pk_fma_f32 v[252:253], v[242:243], v[250:251], 1.0 op_sel_hi:[1,1,0] neg_lo:[1,0,0] neg_hi:[1,0,0]
	v_pk_fma_f32 v[254:255], v[252:253], v[250:251], v[250:251]
	v_pk_fma_f32 v[252:253], v[242:243], v[254:255], 1.0 op_sel_hi:[1,1,0] neg_lo:[1,0,0] neg_hi:[1,0,0]
	v_pk_fma_f32 v[254:255], v[252:253], v[250:251], v[254:255]
	v_div_fixup_f32 v242, v254, v242, 1.0
	v_div_fixup_f32 v243, v255, v243, 1.0
	v_rcp_f32_e32 v250, v244
	v_rcp_f32_e32 v251, v245
	s_nop 0
	v_pk_fma_f32 v[252:253], v[244:245], v[250:251], 1.0 op_sel_hi:[1,1,0] neg_lo:[1,0,0] neg_hi:[1,0,0]
	v_pk_fma_f32 v[250:251], v[252:253], v[250:251], v[250:251]
	v_pk_fma_f32 v[252:253], v[244:245], v[250:251], 1.0 op_sel_hi:[1,1,0] neg_lo:[1,0,0] neg_hi:[1,0,0]
	v_pk_fma_f32 v[254:255], v[252:253], v[250:251], v[250:251]
	v_pk_fma_f32 v[252:253], v[244:245], v[254:255], 1.0 op_sel_hi:[1,1,0] neg_lo:[1,0,0] neg_hi:[1,0,0]
	v_pk_fma_f32 v[254:255], v[252:253], v[250:251], v[254:255]
	v_div_fixup_f32 v244, v254, v244, 1.0
	v_div_fixup_f32 v245, v255, v245, 1.0
	v_rcp_f32_e32 v250, v246
	v_rcp_f32_e32 v251, v247
	s_nop 0
	v_pk_fma_f32 v[252:253], v[246:247], v[250:251], 1.0 op_sel_hi:[1,1,0] neg_lo:[1,0,0] neg_hi:[1,0,0]
	v_pk_fma_f32 v[250:251], v[252:253], v[250:251], v[250:251]
	v_pk_fma_f32 v[252:253], v[246:247], v[250:251], 1.0 op_sel_hi:[1,1,0] neg_lo:[1,0,0] neg_hi:[1,0,0]
	v_pk_fma_f32 v[254:255], v[252:253], v[250:251], v[250:251]
	v_pk_fma_f32 v[252:253], v[246:247], v[254:255], 1.0 op_sel_hi:[1,1,0] neg_lo:[1,0,0] neg_hi:[1,0,0]
	v_pk_fma_f32 v[254:255], v[252:253], v[250:251], v[254:255]
	v_div_fixup_f32 v246, v254, v246, 1.0
	v_div_fixup_f32 v247, v255, v247, 1.0
	v_rcp_f32_e32 v250, v248
	v_rcp_f32_e32 v251, v249
	s_nop 0
	v_pk_fma_f32 v[252:253], v[248:249], v[250:251], 1.0 op_sel_hi:[1,1,0] neg_lo:[1,0,0] neg_hi:[1,0,0]
	v_pk_fma_f32 v[250:251], v[252:253], v[250:251], v[250:251]
	v_pk_fma_f32 v[252:253], v[248:249], v[250:251], 1.0 op_sel_hi:[1,1,0] neg_lo:[1,0,0] neg_hi:[1,0,0]
	v_pk_fma_f32 v[254:255], v[252:253], v[250:251], v[250:251]
	v_pk_fma_f32 v[252:253], v[248:249], v[254:255], 1.0 op_sel_hi:[1,1,0] neg_lo:[1,0,0] neg_hi:[1,0,0]
	v_pk_fma_f32 v[254:255], v[252:253], v[250:251], v[254:255]
	v_div_fixup_f32 v248, v254, v248, 1.0
	v_div_fixup_f32 v249, v255, v249, 1.0
	v_lshlrev_b32_e32 v114, 16, v106
	v_and_b32_e32 v115, 0xffff0000, v106
	v_lshlrev_b32_e32 v116, 16, v108
	v_and_b32_e32 v117, 0xffff0000, v108
	v_lshlrev_b32_e32 v108, 16, v109
	v_and_b32_e32 v109, 0xffff0000, v109
	v_lshlrev_b32_e32 v106, 16, v107
	v_and_b32_e32 v107, 0xffff0000, v107
	v_pk_fma_f32 v[92:93], v[92:93], v[242:243], v[114:115]
	v_pk_fma_f32 v[102:103], v[90:91], v[248:249], v[108:109]
	v_pk_fma_f32 v[90:91], v[88:89], v[244:245], v[116:117]
	v_add_lshl_u32 v104, v140, v98, 1
	v_pk_fma_f32 v[94:95], v[94:95], v[246:247], v[106:107]
	v_cvt_pk_bf16_f32 v88, v92, v93
	s_nop 0
	v_cvt_pk_bf16_f32 v89, v94, v95
	v_cvt_pk_bf16_f32 v90, v90, v91
	v_cvt_pk_bf16_f32 v91, v102, v103
	buffer_store_dwordx4 v[88:91], v104, s[20:23], 0 offen sc1
	s_nop 0
	s_waitcnt vmcnt(7)
; __device__ __forceinline__ float sigmoidf_(float x) { return 1.0f / (1.0f + __expf(-x)); }
; __device__ __forceinline__ u32x4 pack8(const f32x4 v0, const f32x4 v1) { u32x4 w; w.x = pk2(v0[0], v0[1]); w.y = pk2(v0[2], v0[3]); w.z = pk2(v1[0], v1[1]); w.w = pk2(v1[2], v1[3]); return w; }
; __device__ __forceinline__ void unpack8(const u32x4 w, f32x4& v0, f32x4& v1) { v0 = (f32x4){bflo(w.x), bfhi(w.x), bflo(w.y), bfhi(w.y)}; v1 = (f32x4){bflo(w.z), bfhi(w.z), bflo(w.w), bfhi(w.w)}; }
;     __device__ __forceinline__ void operator()(const f32x4 (&acc)[2][2][4][2], const Unit& u, int wr, int wc, int fr, int fq) const {
;     ...
;                 const int row = row0 + ai * 128 + m * 16;
;                 const bf16_t* rowp = z + (size_t)row * DIN + col0;
; #pragma unroll
;                 for (int bj = 0; bj < 2; ++bj) {
;                     const u32x4 gw = *(const u32x4*)(rowp + O_GA + bj * 128);
;                     f32x4 g0, g1; unpack8(gw, g0, g1);
;                     f32x4 v0, v1;
; #pragma unroll
;                     for (int j = 0; j < 4; ++j) { v0[j] = sigmoidf_(g0[j]) * acc[ai][bj][m][0][j]; v1[j] = sigmoidf_(g1[j]) * acc[ai][bj][m][1][j]; }
;                     const u32x4 mw = *(const u32x4*)(rowp + bj * 128); f32x4 m0, m1; unpack8(mw, m0, m1); v0 += m0; v1 += m1;
;                     __builtin_amdgcn_raw_buffer_store_b128(pack8(v0, v1), rsrc, (unsigned)(((size_t)row * DIN + col0 + bj * 128) * 2), 0, 16  ); }
	v_mov_b64_e32 v[88:89], v[232:233]
	v_mov_b64_e32 v[90:91], v[234:235]
	v_mov_b64_e32 v[92:93], v[236:237]
	v_mov_b64_e32 v[94:95], v[238:239]
	v_add_u32_e32 v198, 0x111200, v197
	global_load_dwordx4 v[232:235], v198, s[34:35]
	v_add_u32_e32 v198, 0x110000, v197
	global_load_dwordx4 v[236:239], v198, s[34:35]
	s_mov_b32 s100, 0xbfb8aa3b
	v_lshlrev_b32_e32 v242, 16, v90
	v_and_b32_e32 v243, 0xffff0000, v90
	v_lshlrev_b32_e32 v244, 16, v88
	v_and_b32_e32 v245, 0xffff0000, v88
	v_lshlrev_b32_e32 v246, 16, v89
	v_and_b32_e32 v247, 0xffff0000, v89
	v_lshlrev_b32_e32 v248, 16, v91
	v_and_b32_e32 v249, 0xffff0000, v91
	v_pk_mul_f32 v[242:243], v[242:243], s[100:101] op_sel_hi:[1,0]
	v_pk_mul_f32 v[244:245], v[244:245], s[100:101] op_sel_hi:[1,0]
	v_pk_mul_f32 v[246:247], v[246:247], s[100:101] op_sel_hi:[1,0]
	v_pk_mul_f32 v[248:249], v[248:249], s[100:101] op_sel_hi:[1,0]
	v_exp_f32_e32 v242, v242
	v_exp_f32_e32 v243, v243
	v_exp_f32_e32 v244, v244
	v_exp_f32_e32 v245, v245
	v_exp_f32_e32 v246, v246
	v_exp_f32_e32 v247, v247
	v_exp_f32_e32 v248, v248
	v_exp_f32_e32 v249, v249
	s_nop 0
	v_pk_add_f32 v[242:243], v[242:243], 1.0 op_sel_hi:[1,0]
	v_pk_add_f32 v[244:245], v[244:245], 1.0 op_sel_hi:[1,0]
	v_pk_add_f32 v[246:247], v[246:247], 1.0 op_sel_hi:[1,0]
	v_pk_add_f32 v[248:249], v[248:249], 1.0 op_sel_hi:[1,0]
	v_rcp_f32_e32 v250, v242
	v_rcp_f32_e32 v251, v243
	s_nop 0
	v_pk_fma_f32 v[252:253], v[242:243], v[250:251], 1.0 op_sel_hi:[1,1,0] neg_lo:[1,0,0] neg_hi:[1,0,0]
	v_pk_fma_f32 v[250:251], v[252:253], v[250:251], v[250:251]
	v_pk_fma_f32 v[252:253], v[242:243], v[250:251], 1.0 op_sel_hi:[1,1,0] neg_lo:[1,0,0] neg_hi:[1,0,0]
	v_pk_fma_f32 v[254:255], v[252:253], v[250:251], v[250:251]
	v_pk_fma_f32 v[252:253], v[242:243], v[254:255], 1.0 op_sel_hi:[1,1,0] neg_lo:[1,0,0] neg_hi:[1,0,0]
	v_pk_fma_f32 v[254:255], v[252:253], v[250:251], v[254:255]
	v_div_fixup_f32 v242, v254, v242, 1.0
	v_div_fixup_f32 v243, v255, v243, 1.0
	v_rcp_f32_e32 v250, v244
	v_rcp_f32_e32 v251, v245
	s_nop 0
	v_pk_fma_f32 v[252:253], v[244:245], v[250:251], 1.0 op_sel_hi:[1,1,0] neg_lo:[1,0,0] neg_hi:[1,0,0]
	v_pk_fma_f32 v[250:251], v[252:253], v[250:251], v[250:251]
	v_pk_fma_f32 v[252:253], v[244:245], v[250:251], 1.0 op_sel_hi:[1,1,0] neg_lo:[1,0,0] neg_hi:[1,0,0]
	v_pk_fma_f32 v[254:255], v[252:253], v[250:251], v[250:251]
	v_pk_fma_f32 v[252:253], v[244:245], v[254:255], 1.0 op_sel_hi:[1,1,0] neg_lo:[1,0,0] neg_hi:[1,0,0]
	v_pk_fma_f32 v[254:255], v[252:253], v[250:251], v[254:255]
	v_div_fixup_f32 v244, v254, v244, 1.0
	v_div_fixup_f32 v245, v255, v245, 1.0
	v_rcp_f32_e32 v250, v246
	v_rcp_f32_e32 v251, v247
	s_nop 0
	v_pk_fma_f32 v[252:253], v[246:247], v[250:251], 1.0 op_sel_hi:[1,1,0] neg_lo:[1,0,0] neg_hi:[1,0,0]
	v_pk_fma_f32 v[250:251], v[252:253], v[250:251], v[250:251]
	v_pk_fma_f32 v[252:253], v[246:247], v[250:251], 1.0 op_sel_hi:[1,1,0] neg_lo:[1,0,0] neg_hi:[1,0,0]
	v_pk_fma_f32 v[254:255], v[252:253], v[250:251], v[250:251]
	v_pk_fma_f32 v[252:253], v[246:247], v[254:255], 1.0 op_sel_hi:[1,1,0] neg_lo:[1,0,0] neg_hi:[1,0,0]
	v_pk_fma_f32 v[254:255], v[252:253], v[250:251], v[254:255]
	v_div_fixup_f32 v246, v254, v246, 1.0
	v_div_fixup_f32 v247, v255, v247, 1.0
	v_rcp_f32_e32 v250, v248
	v_rcp_f32_e32 v251, v249
	s_nop 0
	v_pk_fma_f32 v[252:253], v[248:249], v[250:251], 1.0 op_sel_hi:[1,1,0] neg_lo:[1,0,0] neg_hi:[1,0,0]
	v_pk_fma_f32 v[250:251], v[252:253], v[250:251], v[250:251]
	v_pk_fma_f32 v[252:253], v[248:249], v[250:251], 1.0 op_sel_hi:[1,1,0] neg_lo:[1,0,0] neg_hi:[1,0,0]
	v_pk_fma_f32 v[254:255], v[252:253], v[250:251], v[250:251]
	v_pk_fma_f32 v[252:253], v[248:249], v[254:255], 1.0 op_sel_hi:[1,1,0] neg_lo:[1,0,0] neg_hi:[1,0,0]
	v_pk_fma_f32 v[254:255], v[252:253], v[250:251], v[254:255]
	v_div_fixup_f32 v248, v254, v248, 1.0
	v_div_fixup_f32 v249, v255, v249, 1.0
	v_lshlrev_b32_e32 v100, 16, v92
	v_and_b32_e32 v101, 0xffff0000, v92
	v_lshlrev_b32_e32 v102, 16, v94
	v_and_b32_e32 v103, 0xffff0000, v94
	v_lshlrev_b32_e32 v94, 16, v95
	v_and_b32_e32 v95, 0xffff0000, v95
	v_lshlrev_b32_e32 v92, 16, v93
	v_and_b32_e32 v93, 0xffff0000, v93
	v_pk_fma_f32 v[84:85], v[84:85], v[244:245], v[100:101]
	v_pk_fma_f32 v[88:89], v[82:83], v[248:249], v[94:95]
	v_pk_fma_f32 v[82:83], v[80:81], v[242:243], v[102:103]
	v_cvt_pk_bf16_f32 v80, v84, v85
	v_pk_fma_f32 v[86:87], v[86:87], v[246:247], v[92:93]
	s_nop 0
	v_cvt_pk_bf16_f32 v81, v86, v87
	v_cvt_pk_bf16_f32 v82, v82, v83
	v_cvt_pk_bf16_f32 v83, v88, v89
	buffer_store_dwordx4 v[80:83], v104, s[20:23], 0 offen offset:256 sc1
	s_nop 1
	v_add_u32_e32 v80, 0x4030, v158
	v_mad_i64_i32 v[82:83], s[6:7], v80, s73, 0
	v_lshl_add_u64 v[80:81], v[82:83], 1, s[34:35]
	v_lshl_add_u64 v[80:81], v[80:81], 0, v[142:143]
	v_add_co_u32_e32 v84, vcc, s74, v80
	s_nop 1
	v_addc_co_u32_e32 v85, vcc, 0, v81, vcc
	s_waitcnt vmcnt(7)
; __device__ __forceinline__ float sigmoidf_(float x) { return 1.0f / (1.0f + __expf(-x)); }
; __device__ __forceinline__ u32x4 pack8(const f32x4 v0, const f32x4 v1) { u32x4 w; w.x = pk2(v0[0], v0[1]); w.y = pk2(v0[2], v0[3]); w.z = pk2(v1[0], v1[1]); w.w = pk2(v1[2], v1[3]); return w; }
; __device__ __forceinline__ void unpack8(const u32x4 w, f32x4& v0, f32x4& v1) { v0 = (f32x4){bflo(w.x), bfhi(w.x), bflo(w.y), bfhi(w.y)}; v1 = (f32x4){bflo(w.z), bfhi(w.z), bflo(w.w), bfhi(w.w)}; }
;     __device__ __forceinline__ void operator()(const f32x4 (&acc)[2][2][4][2], const Unit& u, int wr, int wc, int fr, int fq) const {
;     ...
;                 const int row = row0 + ai * 128 + m * 16;
;                 const bf16_t* rowp = z + (size_t)row * DIN + col0;
; #pragma unroll
;                 for (int bj = 0; bj < 2; ++bj) {
;                     const u32x4 gw = *(const u32x4*)(rowp + O_GA + bj * 128);
;                     f32x4 g0, g1; unpack8(gw, g0, g1);
;                     f32x4 v0, v1;
; #pragma unroll
;                     for (int j = 0; j < 4; ++j) { v0[j] = sigmoidf_(g0[j]) * acc[ai][bj][m][0][j]; v1[j] = sigmoidf_(g1[j]) * acc[ai][bj][m][1][j]; }
;                     const u32x4 mw = *(const u32x4*)(rowp + bj * 128); f32x4 m0, m1; unpack8(mw, m0, m1); v0 += m0; v1 += m1;
;                     __builtin_amdgcn_raw_buffer_store_b128(pack8(v0, v1), rsrc, (unsigned)(((size_t)row * DIN + col0 + bj * 128) * 2), 0, 16  ); }
	v_mov_b64_e32 v[86:87], v[200:201]
	v_mov_b64_e32 v[88:89], v[202:203]
	v_mov_b64_e32 v[90:91], v[204:205]
	v_mov_b64_e32 v[92:93], v[206:207]
	v_add_u32_e32 v198, 0x111300, v197
	global_load_dwordx4 v[200:203], v198, s[34:35]
	v_add_u32_e32 v198, 0x110100, v197
	global_load_dwordx4 v[204:207], v198, s[34:35]
	s_mov_b32 s100, 0xbfb8aa3b
	v_lshlrev_b32_e32 v242, 16, v86
	v_and_b32_e32 v243, 0xffff0000, v86
	v_lshlrev_b32_e32 v244, 16, v88
	v_and_b32_e32 v245, 0xffff0000, v88
	v_lshlrev_b32_e32 v246, 16, v87
	v_and_b32_e32 v247, 0xffff0000, v87
	v_lshlrev_b32_e32 v248, 16, v89
	v_and_b32_e32 v249, 0xffff0000, v89
	v_pk_mul_f32 v[242:243], v[242:243], s[100:101] op_sel_hi:[1,0]
	v_pk_mul_f32 v[244:245], v[244:245], s[100:101] op_sel_hi:[1,0]
	v_pk_mul_f32 v[246:247], v[246:247], s[100:101] op_sel_hi:[1,0]
	v_pk_mul_f32 v[248:249], v[248:249], s[100:101] op_sel_hi:[1,0]
	v_exp_f32_e32 v242, v242
	v_exp_f32_e32 v243, v243
	v_exp_f32_e32 v244, v244
	v_exp_f32_e32 v245, v245
	v_exp_f32_e32 v246, v246
	v_exp_f32_e32 v247, v247
	v_exp_f32_e32 v248, v248
	v_exp_f32_e32 v249, v249
	s_nop 0
	v_pk_add_f32 v[242:243], v[242:243], 1.0 op_sel_hi:[1,0]
	v_pk_add_f32 v[244:245], v[244:245], 1.0 op_sel_hi:[1,0]
	v_pk_add_f32 v[246:247], v[246:247], 1.0 op_sel_hi:[1,0]
	v_pk_add_f32 v[248:249], v[248:249], 1.0 op_sel_hi:[1,0]
	v_rcp_f32_e32 v250, v242
	v_rcp_f32_e32 v251, v243
	s_nop 0
	v_pk_fma_f32 v[252:253], v[242:243], v[250:251], 1.0 op_sel_hi:[1,1,0] neg_lo:[1,0,0] neg_hi:[1,0,0]
	v_pk_fma_f32 v[250:251], v[252:253], v[250:251], v[250:251]
	v_pk_fma_f32 v[252:253], v[242:243], v[250:251], 1.0 op_sel_hi:[1,1,0] neg_lo:[1,0,0] neg_hi:[1,0,0]
	v_pk_fma_f32 v[254:255], v[252:253], v[250:251], v[250:251]
	v_pk_fma_f32 v[252:253], v[242:243], v[254:255], 1.0 op_sel_hi:[1,1,0] neg_lo:[1,0,0] neg_hi:[1,0,0]
	v_pk_fma_f32 v[254:255], v[252:253], v[250:251], v[254:255]
	v_div_fixup_f32 v242, v254, v242, 1.0
	v_div_fixup_f32 v243, v255, v243, 1.0
	v_rcp_f32_e32 v250, v244
	v_rcp_f32_e32 v251, v245
	s_nop 0
	v_pk_fma_f32 v[252:253], v[244:245], v[250:251], 1.0 op_sel_hi:[1,1,0] neg_lo:[1,0,0] neg_hi:[1,0,0]
	v_pk_fma_f32 v[250:251], v[252:253], v[250:251], v[250:251]
	v_pk_fma_f32 v[252:253], v[244:245], v[250:251], 1.0 op_sel_hi:[1,1,0] neg_lo:[1,0,0] neg_hi:[1,0,0]
	v_pk_fma_f32 v[254:255], v[252:253], v[250:251], v[250:251]
	v_pk_fma_f32 v[252:253], v[244:245], v[254:255], 1.0 op_sel_hi:[1,1,0] neg_lo:[1,0,0] neg_hi:[1,0,0]
	v_pk_fma_f32 v[254:255], v[252:253], v[250:251], v[254:255]
	v_div_fixup_f32 v244, v254, v244, 1.0
	v_div_fixup_f32 v245, v255, v245, 1.0
	v_rcp_f32_e32 v250, v246
	v_rcp_f32_e32 v251, v247
	s_nop 0
	v_pk_fma_f32 v[252:253], v[246:247], v[250:251], 1.0 op_sel_hi:[1,1,0] neg_lo:[1,0,0] neg_hi:[1,0,0]
	v_pk_fma_f32 v[250:251], v[252:253], v[250:251], v[250:251]
	v_pk_fma_f32 v[252:253], v[246:247], v[250:251], 1.0 op_sel_hi:[1,1,0] neg_lo:[1,0,0] neg_hi:[1,0,0]
	v_pk_fma_f32 v[254:255], v[252:253], v[250:251], v[250:251]
	v_pk_fma_f32 v[252:253], v[246:247], v[254:255], 1.0 op_sel_hi:[1,1,0] neg_lo:[1,0,0] neg_hi:[1,0,0]
	v_pk_fma_f32 v[254:255], v[252:253], v[250:251], v[254:255]
	v_div_fixup_f32 v246, v254, v246, 1.0
	v_div_fixup_f32 v247, v255, v247, 1.0
	v_rcp_f32_e32 v250, v248
	v_rcp_f32_e32 v251, v249
	s_nop 0
	v_pk_fma_f32 v[252:253], v[248:249], v[250:251], 1.0 op_sel_hi:[1,1,0] neg_lo:[1,0,0] neg_hi:[1,0,0]
	v_pk_fma_f32 v[250:251], v[252:253], v[250:251], v[250:251]
	v_pk_fma_f32 v[252:253], v[248:249], v[250:251], 1.0 op_sel_hi:[1,1,0] neg_lo:[1,0,0] neg_hi:[1,0,0]
	v_pk_fma_f32 v[254:255], v[252:253], v[250:251], v[250:251]
	v_pk_fma_f32 v[252:253], v[248:249], v[254:255], 1.0 op_sel_hi:[1,1,0] neg_lo:[1,0,0] neg_hi:[1,0,0]
	v_pk_fma_f32 v[254:255], v[252:253], v[250:251], v[254:255]
	v_div_fixup_f32 v248, v254, v248, 1.0
	v_div_fixup_f32 v249, v255, v249, 1.0
	v_lshlrev_b32_e32 v98, 16, v90
	v_and_b32_e32 v99, 0xffff0000, v90
	v_lshlrev_b32_e32 v100, 16, v92
	v_and_b32_e32 v101, 0xffff0000, v92
	v_lshlrev_b32_e32 v92, 16, v93
	v_and_b32_e32 v93, 0xffff0000, v93
	v_lshlrev_b32_e32 v90, 16, v91
	v_and_b32_e32 v91, 0xffff0000, v91
	v_pk_fma_f32 v[76:77], v[76:77], v[242:243], v[98:99]
	v_pk_fma_f32 v[86:87], v[74:75], v[248:249], v[92:93]
	v_pk_fma_f32 v[74:75], v[72:73], v[244:245], v[100:101]
	v_add_lshl_u32 v88, v140, v82, 1
	v_pk_fma_f32 v[78:79], v[78:79], v[246:247], v[90:91]
	v_cvt_pk_bf16_f32 v72, v76, v77
	s_nop 0
	v_cvt_pk_bf16_f32 v73, v78, v79
	v_cvt_pk_bf16_f32 v74, v74, v75
	v_cvt_pk_bf16_f32 v75, v86, v87
	buffer_store_dwordx4 v[72:75], v88, s[20:23], 0 offen sc1
	s_nop 0
	s_waitcnt vmcnt(7)
; __device__ __forceinline__ float sigmoidf_(float x) { return 1.0f / (1.0f + __expf(-x)); }
; __device__ __forceinline__ u32x4 pack8(const f32x4 v0, const f32x4 v1) { u32x4 w; w.x = pk2(v0[0], v0[1]); w.y = pk2(v0[2], v0[3]); w.z = pk2(v1[0], v1[1]); w.w = pk2(v1[2], v1[3]); return w; }
; __device__ __forceinline__ void unpack8(const u32x4 w, f32x4& v0, f32x4& v1) { v0 = (f32x4){bflo(w.x), bfhi(w.x), bflo(w.y), bfhi(w.y)}; v1 = (f32x4){bflo(w.z), bfhi(w.z), bflo(w.w), bfhi(w.w)}; }
;     __device__ __forceinline__ void operator()(const f32x4 (&acc)[2][2][4][2], const Unit& u, int wr, int wc, int fr, int fq) const {
;     ...
;                 const int row = row0 + ai * 128 + m * 16;
;                 const bf16_t* rowp = z + (size_t)row * DIN + col0;
; #pragma unroll
;                 for (int bj = 0; bj < 2; ++bj) {
;                     const u32x4 gw = *(const u32x4*)(rowp + O_GA + bj * 128);
;                     f32x4 g0, g1; unpack8(gw, g0, g1);
;                     f32x4 v0, v1;
; #pragma unroll
;                     for (int j = 0; j < 4; ++j) { v0[j] = sigmoidf_(g0[j]) * acc[ai][bj][m][0][j]; v1[j] = sigmoidf_(g1[j]) * acc[ai][bj][m][1][j]; }
;                     const u32x4 mw = *(const u32x4*)(rowp + bj * 128); f32x4 m0, m1; unpack8(mw, m0, m1); v0 += m0; v1 += m1;
;                     __builtin_amdgcn_raw_buffer_store_b128(pack8(v0, v1), rsrc, (unsigned)(((size_t)row * DIN + col0 + bj * 128) * 2), 0, 16  ); }
	v_mov_b64_e32 v[72:73], v[208:209]
	v_mov_b64_e32 v[74:75], v[210:211]
	v_mov_b64_e32 v[76:77], v[212:213]
	v_mov_b64_e32 v[78:79], v[214:215]
	v_add_u32_e32 v198, 0x133200, v197
	global_load_dwordx4 v[208:211], v198, s[34:35]
	v_add_u32_e32 v198, 0x132000, v197
	global_load_dwordx4 v[212:215], v198, s[34:35]
	s_mov_b32 s100, 0xbfb8aa3b
	v_lshlrev_b32_e32 v242, 16, v74
	v_and_b32_e32 v243, 0xffff0000, v74
	v_lshlrev_b32_e32 v244, 16, v72
	v_and_b32_e32 v245, 0xffff0000, v72
	v_lshlrev_b32_e32 v246, 16, v73
	v_and_b32_e32 v247, 0xffff0000, v73
	v_lshlrev_b32_e32 v248, 16, v75
	v_and_b32_e32 v249, 0xffff0000, v75
	v_pk_mul_f32 v[242:243], v[242:243], s[100:101] op_sel_hi:[1,0]
	v_pk_mul_f32 v[244:245], v[244:245], s[100:101] op_sel_hi:[1,0]
	v_pk_mul_f32 v[246:247], v[246:247], s[100:101] op_sel_hi:[1,0]
	v_pk_mul_f32 v[248:249], v[248:249], s[100:101] op_sel_hi:[1,0]
	v_exp_f32_e32 v242, v242
	v_exp_f32_e32 v243, v243
	v_exp_f32_e32 v244, v244
	v_exp_f32_e32 v245, v245
	v_exp_f32_e32 v246, v246
	v_exp_f32_e32 v247, v247
	v_exp_f32_e32 v248, v248
	v_exp_f32_e32 v249, v249
	s_nop 0
	v_pk_add_f32 v[242:243], v[242:243], 1.0 op_sel_hi:[1,0]
	v_pk_add_f32 v[244:245], v[244:245], 1.0 op_sel_hi:[1,0]
	v_pk_add_f32 v[246:247], v[246:247], 1.0 op_sel_hi:[1,0]
	v_pk_add_f32 v[248:249], v[248:249], 1.0 op_sel_hi:[1,0]
	v_rcp_f32_e32 v250, v242
	v_rcp_f32_e32 v251, v243
	s_nop 0
	v_pk_fma_f32 v[252:253], v[242:243], v[250:251], 1.0 op_sel_hi:[1,1,0] neg_lo:[1,0,0] neg_hi:[1,0,0]
	v_pk_fma_f32 v[250:251], v[252:253], v[250:251], v[250:251]
	v_pk_fma_f32 v[252:253], v[242:243], v[250:251], 1.0 op_sel_hi:[1,1,0] neg_lo:[1,0,0] neg_hi:[1,0,0]
	v_pk_fma_f32 v[254:255], v[252:253], v[250:251], v[250:251]
	v_pk_fma_f32 v[252:253], v[242:243], v[254:255], 1.0 op_sel_hi:[1,1,0] neg_lo:[1,0,0] neg_hi:[1,0,0]
	v_pk_fma_f32 v[254:255], v[252:253], v[250:251], v[254:255]
	v_div_fixup_f32 v242, v254, v242, 1.0
	v_div_fixup_f32 v243, v255, v243, 1.0
	v_rcp_f32_e32 v250, v244
	v_rcp_f32_e32 v251, v245
	s_nop 0
	v_pk_fma_f32 v[252:253], v[244:245], v[250:251], 1.0 op_sel_hi:[1,1,0] neg_lo:[1,0,0] neg_hi:[1,0,0]
	v_pk_fma_f32 v[250:251], v[252:253], v[250:251], v[250:251]
	v_pk_fma_f32 v[252:253], v[244:245], v[250:251], 1.0 op_sel_hi:[1,1,0] neg_lo:[1,0,0] neg_hi:[1,0,0]
	v_pk_fma_f32 v[254:255], v[252:253], v[250:251], v[250:251]
	v_pk_fma_f32 v[252:253], v[244:245], v[254:255], 1.0 op_sel_hi:[1,1,0] neg_lo:[1,0,0] neg_hi:[1,0,0]
	v_pk_fma_f32 v[254:255], v[252:253], v[250:251], v[254:255]
	v_div_fixup_f32 v244, v254, v244, 1.0
	v_div_fixup_f32 v245, v255, v245, 1.0
	v_rcp_f32_e32 v250, v246
	v_rcp_f32_e32 v251, v247
	s_nop 0
	v_pk_fma_f32 v[252:253], v[246:247], v[250:251], 1.0 op_sel_hi:[1,1,0] neg_lo:[1,0,0] neg_hi:[1,0,0]
	v_pk_fma_f32 v[250:251], v[252:253], v[250:251], v[250:251]
	v_pk_fma_f32 v[252:253], v[246:247], v[250:251], 1.0 op_sel_hi:[1,1,0] neg_lo:[1,0,0] neg_hi:[1,0,0]
	v_pk_fma_f32 v[254:255], v[252:253], v[250:251], v[250:251]
	v_pk_fma_f32 v[252:253], v[246:247], v[254:255], 1.0 op_sel_hi:[1,1,0] neg_lo:[1,0,0] neg_hi:[1,0,0]
	v_pk_fma_f32 v[254:255], v[252:253], v[250:251], v[254:255]
	v_div_fixup_f32 v246, v254, v246, 1.0
	v_div_fixup_f32 v247, v255, v247, 1.0
	v_rcp_f32_e32 v250, v248
	v_rcp_f32_e32 v251, v249
	s_nop 0
	v_pk_fma_f32 v[252:253], v[248:249], v[250:251], 1.0 op_sel_hi:[1,1,0] neg_lo:[1,0,0] neg_hi:[1,0,0]
	v_pk_fma_f32 v[250:251], v[252:253], v[250:251], v[250:251]
	v_pk_fma_f32 v[252:253], v[248:249], v[250:251], 1.0 op_sel_hi:[1,1,0] neg_lo:[1,0,0] neg_hi:[1,0,0]
	v_pk_fma_f32 v[254:255], v[252:253], v[250:251], v[250:251]
	v_pk_fma_f32 v[252:253], v[248:249], v[254:255], 1.0 op_sel_hi:[1,1,0] neg_lo:[1,0,0] neg_hi:[1,0,0]
	v_pk_fma_f32 v[254:255], v[252:253], v[250:251], v[254:255]
	v_div_fixup_f32 v248, v254, v248, 1.0
	v_div_fixup_f32 v249, v255, v249, 1.0
	v_lshlrev_b32_e32 v84, 16, v76
	v_and_b32_e32 v85, 0xffff0000, v76
	v_lshlrev_b32_e32 v86, 16, v78
	v_and_b32_e32 v87, 0xffff0000, v78
	v_lshlrev_b32_e32 v78, 16, v79
	v_and_b32_e32 v79, 0xffff0000, v79
	v_lshlrev_b32_e32 v76, 16, v77
	v_and_b32_e32 v77, 0xffff0000, v77
	v_pk_fma_f32 v[68:69], v[68:69], v[244:245], v[84:85]
	v_pk_fma_f32 v[72:73], v[66:67], v[248:249], v[78:79]
	v_pk_fma_f32 v[66:67], v[64:65], v[242:243], v[86:87]
	v_cvt_pk_bf16_f32 v64, v68, v69
	v_pk_fma_f32 v[70:71], v[70:71], v[246:247], v[76:77]
	s_nop 0
	v_cvt_pk_bf16_f32 v65, v70, v71
	v_cvt_pk_bf16_f32 v66, v66, v67
	v_cvt_pk_bf16_f32 v67, v72, v73
	buffer_store_dwordx4 v[64:67], v88, s[20:23], 0 offen offset:256 sc1
	s_nop 1
	v_add_u32_e32 v64, 0x4080, v158
	v_mad_i64_i32 v[66:67], s[6:7], v64, s73, 0
	v_lshl_add_u64 v[64:65], v[66:67], 1, s[34:35]
	v_lshl_add_u64 v[64:65], v[64:65], 0, v[142:143]
	v_add_co_u32_e32 v68, vcc, s74, v64
	s_nop 1
	v_addc_co_u32_e32 v69, vcc, 0, v65, vcc
	s_waitcnt vmcnt(7)
; __device__ __forceinline__ float sigmoidf_(float x) { return 1.0f / (1.0f + __expf(-x)); }
; __device__ __forceinline__ u32x4 pack8(const f32x4 v0, const f32x4 v1) { u32x4 w; w.x = pk2(v0[0], v0[1]); w.y = pk2(v0[2], v0[3]); w.z = pk2(v1[0], v1[1]); w.w = pk2(v1[2], v1[3]); return w; }
; __device__ __forceinline__ void unpack8(const u32x4 w, f32x4& v0, f32x4& v1) { v0 = (f32x4){bflo(w.x), bfhi(w.x), bflo(w.y), bfhi(w.y)}; v1 = (f32x4){bflo(w.z), bfhi(w.z), bflo(w.w), bfhi(w.w)}; }
;     __device__ __forceinline__ void operator()(const f32x4 (&acc)[2][2][4][2], const Unit& u, int wr, int wc, int fr, int fq) const {
;     ...
;                 const int row = row0 + ai * 128 + m * 16;
;                 const bf16_t* rowp = z + (size_t)row * DIN + col0;
; #pragma unroll
;                 for (int bj = 0; bj < 2; ++bj) {
;                     const u32x4 gw = *(const u32x4*)(rowp + O_GA + bj * 128);
;                     f32x4 g0, g1; unpack8(gw, g0, g1);
;                     f32x4 v0, v1;
; #pragma unroll
;                     for (int j = 0; j < 4; ++j) { v0[j] = sigmoidf_(g0[j]) * acc[ai][bj][m][0][j]; v1[j] = sigmoidf_(g1[j]) * acc[ai][bj][m][1][j]; }
;                     const u32x4 mw = *(const u32x4*)(rowp + bj * 128); f32x4 m0, m1; unpack8(mw, m0, m1); v0 += m0; v1 += m1;
;                     __builtin_amdgcn_raw_buffer_store_b128(pack8(v0, v1), rsrc, (unsigned)(((size_t)row * DIN + col0 + bj * 128) * 2), 0, 16  ); }
	v_mov_b64_e32 v[70:71], v[232:233]
	v_mov_b64_e32 v[72:73], v[234:235]
	v_mov_b64_e32 v[74:75], v[236:237]
	v_mov_b64_e32 v[76:77], v[238:239]
	v_add_u32_e32 v198, 0x133300, v197
	global_load_dwordx4 v[232:235], v198, s[34:35]
	v_add_u32_e32 v198, 0x132100, v197
	global_load_dwordx4 v[236:239], v198, s[34:35]
	s_mov_b32 s100, 0xbfb8aa3b
	v_lshlrev_b32_e32 v242, 16, v70
	v_and_b32_e32 v243, 0xffff0000, v70
	v_lshlrev_b32_e32 v244, 16, v72
	v_and_b32_e32 v245, 0xffff0000, v72
	v_lshlrev_b32_e32 v246, 16, v71
	v_and_b32_e32 v247, 0xffff0000, v71
	v_lshlrev_b32_e32 v248, 16, v73
	v_and_b32_e32 v249, 0xffff0000, v73
	v_pk_mul_f32 v[242:243], v[242:243], s[100:101] op_sel_hi:[1,0]
	v_pk_mul_f32 v[244:245], v[244:245], s[100:101] op_sel_hi:[1,0]
	v_pk_mul_f32 v[246:247], v[246:247], s[100:101] op_sel_hi:[1,0]
	v_pk_mul_f32 v[248:249], v[248:249], s[100:101] op_sel_hi:[1,0]
	v_exp_f32_e32 v242, v242
	v_exp_f32_e32 v243, v243
	v_exp_f32_e32 v244, v244
	v_exp_f32_e32 v245, v245
	v_exp_f32_e32 v246, v246
	v_exp_f32_e32 v247, v247
	v_exp_f32_e32 v248, v248
	v_exp_f32_e32 v249, v249
	s_nop 0
	v_pk_add_f32 v[242:243], v[242:243], 1.0 op_sel_hi:[1,0]
	v_pk_add_f32 v[244:245], v[244:245], 1.0 op_sel_hi:[1,0]
	v_pk_add_f32 v[246:247], v[246:247], 1.0 op_sel_hi:[1,0]
	v_pk_add_f32 v[248:249], v[248:249], 1.0 op_sel_hi:[1,0]
	v_rcp_f32_e32 v250, v242
	v_rcp_f32_e32 v251, v243
	s_nop 0
	v_pk_fma_f32 v[252:253], v[242:243], v[250:251], 1.0 op_sel_hi:[1,1,0] neg_lo:[1,0,0] neg_hi:[1,0,0]
	v_pk_fma_f32 v[250:251], v[252:253], v[250:251], v[250:251]
	v_pk_fma_f32 v[252:253], v[242:243], v[250:251], 1.0 op_sel_hi:[1,1,0] neg_lo:[1,0,0] neg_hi:[1,0,0]
	v_pk_fma_f32 v[254:255], v[252:253], v[250:251], v[250:251]
	v_pk_fma_f32 v[252:253], v[242:243], v[254:255], 1.0 op_sel_hi:[1,1,0] neg_lo:[1,0,0] neg_hi:[1,0,0]
	v_pk_fma_f32 v[254:255], v[252:253], v[250:251], v[254:255]
	v_div_fixup_f32 v242, v254, v242, 1.0
	v_div_fixup_f32 v243, v255, v243, 1.0
	v_rcp_f32_e32 v250, v244
	v_rcp_f32_e32 v251, v245
	s_nop 0
	v_pk_fma_f32 v[252:253], v[244:245], v[250:251], 1.0 op_sel_hi:[1,1,0] neg_lo:[1,0,0] neg_hi:[1,0,0]
	v_pk_fma_f32 v[250:251], v[252:253], v[250:251], v[250:251]
	v_pk_fma_f32 v[252:253], v[244:245], v[250:251], 1.0 op_sel_hi:[1,1,0] neg_lo:[1,0,0] neg_hi:[1,0,0]
	v_pk_fma_f32 v[254:255], v[252:253], v[250:251], v[250:251]
	v_pk_fma_f32 v[252:253], v[244:245], v[254:255], 1.0 op_sel_hi:[1,1,0] neg_lo:[1,0,0] neg_hi:[1,0,0]
	v_pk_fma_f32 v[254:255], v[252:253], v[250:251], v[254:255]
	v_div_fixup_f32 v244, v254, v244, 1.0
	v_div_fixup_f32 v245, v255, v245, 1.0
	v_rcp_f32_e32 v250, v246
	v_rcp_f32_e32 v251, v247
	s_nop 0
	v_pk_fma_f32 v[252:253], v[246:247], v[250:251], 1.0 op_sel_hi:[1,1,0] neg_lo:[1,0,0] neg_hi:[1,0,0]
	v_pk_fma_f32 v[250:251], v[252:253], v[250:251], v[250:251]
	v_pk_fma_f32 v[252:253], v[246:247], v[250:251], 1.0 op_sel_hi:[1,1,0] neg_lo:[1,0,0] neg_hi:[1,0,0]
	v_pk_fma_f32 v[254:255], v[252:253], v[250:251], v[250:251]
	v_pk_fma_f32 v[252:253], v[246:247], v[254:255], 1.0 op_sel_hi:[1,1,0] neg_lo:[1,0,0] neg_hi:[1,0,0]
	v_pk_fma_f32 v[254:255], v[252:253], v[250:251], v[254:255]
	v_div_fixup_f32 v246, v254, v246, 1.0
	v_div_fixup_f32 v247, v255, v247, 1.0
	v_rcp_f32_e32 v250, v248
	v_rcp_f32_e32 v251, v249
	s_nop 0
	v_pk_fma_f32 v[252:253], v[248:249], v[250:251], 1.0 op_sel_hi:[1,1,0] neg_lo:[1,0,0] neg_hi:[1,0,0]
	v_pk_fma_f32 v[250:251], v[252:253], v[250:251], v[250:251]
	v_pk_fma_f32 v[252:253], v[248:249], v[250:251], 1.0 op_sel_hi:[1,1,0] neg_lo:[1,0,0] neg_hi:[1,0,0]
	v_pk_fma_f32 v[254:255], v[252:253], v[250:251], v[250:251]
	v_pk_fma_f32 v[252:253], v[248:249], v[254:255], 1.0 op_sel_hi:[1,1,0] neg_lo:[1,0,0] neg_hi:[1,0,0]
	v_pk_fma_f32 v[254:255], v[252:253], v[250:251], v[254:255]
	v_div_fixup_f32 v248, v254, v248, 1.0
	v_div_fixup_f32 v249, v255, v249, 1.0
	v_lshlrev_b32_e32 v82, 16, v74
	v_and_b32_e32 v83, 0xffff0000, v74
	v_lshlrev_b32_e32 v84, 16, v76
	v_and_b32_e32 v85, 0xffff0000, v76
	v_lshlrev_b32_e32 v76, 16, v77
	v_and_b32_e32 v77, 0xffff0000, v77
	v_lshlrev_b32_e32 v74, 16, v75
	v_and_b32_e32 v75, 0xffff0000, v75
	v_pk_fma_f32 v[60:61], v[60:61], v[242:243], v[82:83]
	v_pk_fma_f32 v[70:71], v[58:59], v[248:249], v[76:77]
	v_pk_fma_f32 v[58:59], v[56:57], v[244:245], v[84:85]
	v_add_lshl_u32 v72, v140, v66, 1
	v_pk_fma_f32 v[62:63], v[62:63], v[246:247], v[74:75]
	v_cvt_pk_bf16_f32 v56, v60, v61
	s_nop 0
	v_cvt_pk_bf16_f32 v57, v62, v63
	v_cvt_pk_bf16_f32 v58, v58, v59
	v_cvt_pk_bf16_f32 v59, v70, v71
	buffer_store_dwordx4 v[56:59], v72, s[20:23], 0 offen sc1
	s_nop 0
	s_waitcnt vmcnt(7)
; __device__ __forceinline__ float sigmoidf_(float x) { return 1.0f / (1.0f + __expf(-x)); }
; __device__ __forceinline__ u32x4 pack8(const f32x4 v0, const f32x4 v1) { u32x4 w; w.x = pk2(v0[0], v0[1]); w.y = pk2(v0[2], v0[3]); w.z = pk2(v1[0], v1[1]); w.w = pk2(v1[2], v1[3]); return w; }
; __device__ __forceinline__ void unpack8(const u32x4 w, f32x4& v0, f32x4& v1) { v0 = (f32x4){bflo(w.x), bfhi(w.x), bflo(w.y), bfhi(w.y)}; v1 = (f32x4){bflo(w.z), bfhi(w.z), bflo(w.w), bfhi(w.w)}; }
;     __device__ __forceinline__ void operator()(const f32x4 (&acc)[2][2][4][2], const Unit& u, int wr, int wc, int fr, int fq) const {
;     ...
;                 const int row = row0 + ai * 128 + m * 16;
;                 const bf16_t* rowp = z + (size_t)row * DIN + col0;
; #pragma unroll
;                 for (int bj = 0; bj < 2; ++bj) {
;                     const u32x4 gw = *(const u32x4*)(rowp + O_GA + bj * 128);
;                     f32x4 g0, g1; unpack8(gw, g0, g1);
;                     f32x4 v0, v1;
; #pragma unroll
;                     for (int j = 0; j < 4; ++j) { v0[j] = sigmoidf_(g0[j]) * acc[ai][bj][m][0][j]; v1[j] = sigmoidf_(g1[j]) * acc[ai][bj][m][1][j]; }
;                     const u32x4 mw = *(const u32x4*)(rowp + bj * 128); f32x4 m0, m1; unpack8(mw, m0, m1); v0 += m0; v1 += m1;
;                     __builtin_amdgcn_raw_buffer_store_b128(pack8(v0, v1), rsrc, (unsigned)(((size_t)row * DIN + col0 + bj * 128) * 2), 0, 16  ); }
	v_mov_b64_e32 v[56:57], v[200:201]
	v_mov_b64_e32 v[58:59], v[202:203]
	v_mov_b64_e32 v[60:61], v[204:205]
	v_mov_b64_e32 v[62:63], v[206:207]
	v_add_u32_e32 v198, 0x155200, v197
	global_load_dwordx4 v[200:203], v198, s[34:35]
	v_add_u32_e32 v198, 0x154000, v197
	global_load_dwordx4 v[204:207], v198, s[34:35]
	s_mov_b32 s100, 0xbfb8aa3b
	v_lshlrev_b32_e32 v242, 16, v58
	v_and_b32_e32 v243, 0xffff0000, v58
	v_lshlrev_b32_e32 v244, 16, v56
	v_and_b32_e32 v245, 0xffff0000, v56
	v_lshlrev_b32_e32 v246, 16, v57
	v_and_b32_e32 v247, 0xffff0000, v57
	v_lshlrev_b32_e32 v248, 16, v59
	v_and_b32_e32 v249, 0xffff0000, v59
	v_pk_mul_f32 v[242:243], v[242:243], s[100:101] op_sel_hi:[1,0]
	v_pk_mul_f32 v[244:245], v[244:245], s[100:101] op_sel_hi:[1,0]
	v_pk_mul_f32 v[246:247], v[246:247], s[100:101] op_sel_hi:[1,0]
	v_pk_mul_f32 v[248:249], v[248:249], s[100:101] op_sel_hi:[1,0]
	v_exp_f32_e32 v242, v242
	v_exp_f32_e32 v243, v243
	v_exp_f32_e32 v244, v244
	v_exp_f32_e32 v245, v245
	v_exp_f32_e32 v246, v246
	v_exp_f32_e32 v247, v247
	v_exp_f32_e32 v248, v248
	v_exp_f32_e32 v249, v249
	s_nop 0
	v_pk_add_f32 v[242:243], v[242:243], 1.0 op_sel_hi:[1,0]
	v_pk_add_f32 v[244:245], v[244:245], 1.0 op_sel_hi:[1,0]
	v_pk_add_f32 v[246:247], v[246:247], 1.0 op_sel_hi:[1,0]
	v_pk_add_f32 v[248:249], v[248:249], 1.0 op_sel_hi:[1,0]
	v_rcp_f32_e32 v250, v242
	v_rcp_f32_e32 v251, v243
	s_nop 0
	v_pk_fma_f32 v[252:253], v[242:243], v[250:251], 1.0 op_sel_hi:[1,1,0] neg_lo:[1,0,0] neg_hi:[1,0,0]
	v_pk_fma_f32 v[250:251], v[252:253], v[250:251], v[250:251]
	v_pk_fma_f32 v[252:253], v[242:243], v[250:251], 1.0 op_sel_hi:[1,1,0] neg_lo:[1,0,0] neg_hi:[1,0,0]
	v_pk_fma_f32 v[254:255], v[252:253], v[250:251], v[250:251]
	v_pk_fma_f32 v[252:253], v[242:243], v[254:255], 1.0 op_sel_hi:[1,1,0] neg_lo:[1,0,0] neg_hi:[1,0,0]
	v_pk_fma_f32 v[254:255], v[252:253], v[250:251], v[254:255]
	v_div_fixup_f32 v242, v254, v242, 1.0
	v_div_fixup_f32 v243, v255, v243, 1.0
	v_rcp_f32_e32 v250, v244
	v_rcp_f32_e32 v251, v245
	s_nop 0
	v_pk_fma_f32 v[252:253], v[244:245], v[250:251], 1.0 op_sel_hi:[1,1,0] neg_lo:[1,0,0] neg_hi:[1,0,0]
	v_pk_fma_f32 v[250:251], v[252:253], v[250:251], v[250:251]
	v_pk_fma_f32 v[252:253], v[244:245], v[250:251], 1.0 op_sel_hi:[1,1,0] neg_lo:[1,0,0] neg_hi:[1,0,0]
	v_pk_fma_f32 v[254:255], v[252:253], v[250:251], v[250:251]
	v_pk_fma_f32 v[252:253], v[244:245], v[254:255], 1.0 op_sel_hi:[1,1,0] neg_lo:[1,0,0] neg_hi:[1,0,0]
	v_pk_fma_f32 v[254:255], v[252:253], v[250:251], v[254:255]
	v_div_fixup_f32 v244, v254, v244, 1.0
	v_div_fixup_f32 v245, v255, v245, 1.0
	v_rcp_f32_e32 v250, v246
	v_rcp_f32_e32 v251, v247
	s_nop 0
	v_pk_fma_f32 v[252:253], v[246:247], v[250:251], 1.0 op_sel_hi:[1,1,0] neg_lo:[1,0,0] neg_hi:[1,0,0]
	v_pk_fma_f32 v[250:251], v[252:253], v[250:251], v[250:251]
	v_pk_fma_f32 v[252:253], v[246:247], v[250:251], 1.0 op_sel_hi:[1,1,0] neg_lo:[1,0,0] neg_hi:[1,0,0]
	v_pk_fma_f32 v[254:255], v[252:253], v[250:251], v[250:251]
	v_pk_fma_f32 v[252:253], v[246:247], v[254:255], 1.0 op_sel_hi:[1,1,0] neg_lo:[1,0,0] neg_hi:[1,0,0]
	v_pk_fma_f32 v[254:255], v[252:253], v[250:251], v[254:255]
	v_div_fixup_f32 v246, v254, v246, 1.0
	v_div_fixup_f32 v247, v255, v247, 1.0
	v_rcp_f32_e32 v250, v248
	v_rcp_f32_e32 v251, v249
	s_nop 0
	v_pk_fma_f32 v[252:253], v[248:249], v[250:251], 1.0 op_sel_hi:[1,1,0] neg_lo:[1,0,0] neg_hi:[1,0,0]
	v_pk_fma_f32 v[250:251], v[252:253], v[250:251], v[250:251]
	v_pk_fma_f32 v[252:253], v[248:249], v[250:251], 1.0 op_sel_hi:[1,1,0] neg_lo:[1,0,0] neg_hi:[1,0,0]
	v_pk_fma_f32 v[254:255], v[252:253], v[250:251], v[250:251]
	v_pk_fma_f32 v[252:253], v[248:249], v[254:255], 1.0 op_sel_hi:[1,1,0] neg_lo:[1,0,0] neg_hi:[1,0,0]
	v_pk_fma_f32 v[254:255], v[252:253], v[250:251], v[254:255]
	v_div_fixup_f32 v248, v254, v248, 1.0
	v_div_fixup_f32 v249, v255, v249, 1.0
	v_lshlrev_b32_e32 v68, 16, v60
	v_and_b32_e32 v69, 0xffff0000, v60
	v_lshlrev_b32_e32 v70, 16, v62
	v_and_b32_e32 v71, 0xffff0000, v62
	v_lshlrev_b32_e32 v62, 16, v63
	v_and_b32_e32 v63, 0xffff0000, v63
	v_lshlrev_b32_e32 v60, 16, v61
	v_and_b32_e32 v61, 0xffff0000, v61
	v_pk_fma_f32 v[52:53], v[52:53], v[244:245], v[68:69]
	v_pk_fma_f32 v[56:57], v[50:51], v[248:249], v[62:63]
	v_pk_fma_f32 v[50:51], v[48:49], v[242:243], v[70:71]
	v_cvt_pk_bf16_f32 v48, v52, v53
	v_pk_fma_f32 v[54:55], v[54:55], v[246:247], v[60:61]
	s_nop 0
	v_cvt_pk_bf16_f32 v49, v54, v55
	v_cvt_pk_bf16_f32 v50, v50, v51
	v_cvt_pk_bf16_f32 v51, v56, v57
	buffer_store_dwordx4 v[48:51], v72, s[20:23], 0 offen offset:256 sc1
	s_nop 1
	v_add_u32_e32 v48, 0x4090, v158
	v_mad_i64_i32 v[50:51], s[6:7], v48, s73, 0
	v_lshl_add_u64 v[48:49], v[50:51], 1, s[34:35]
	v_lshl_add_u64 v[48:49], v[48:49], 0, v[142:143]
	v_add_co_u32_e32 v52, vcc, s74, v48
	s_nop 1
	v_addc_co_u32_e32 v53, vcc, 0, v49, vcc
	s_waitcnt vmcnt(7)
; __device__ __forceinline__ float sigmoidf_(float x) { return 1.0f / (1.0f + __expf(-x)); }
; __device__ __forceinline__ u32x4 pack8(const f32x4 v0, const f32x4 v1) { u32x4 w; w.x = pk2(v0[0], v0[1]); w.y = pk2(v0[2], v0[3]); w.z = pk2(v1[0], v1[1]); w.w = pk2(v1[2], v1[3]); return w; }
; __device__ __forceinline__ void unpack8(const u32x4 w, f32x4& v0, f32x4& v1) { v0 = (f32x4){bflo(w.x), bfhi(w.x), bflo(w.y), bfhi(w.y)}; v1 = (f32x4){bflo(w.z), bfhi(w.z), bflo(w.w), bfhi(w.w)}; }
;     __device__ __forceinline__ void operator()(const f32x4 (&acc)[2][2][4][2], const Unit& u, int wr, int wc, int fr, int fq) const {
;     ...
;                 const int row = row0 + ai * 128 + m * 16;
;                 const bf16_t* rowp = z + (size_t)row * DIN + col0;
; #pragma unroll
;                 for (int bj = 0; bj < 2; ++bj) {
;                     const u32x4 gw = *(const u32x4*)(rowp + O_GA + bj * 128);
;                     f32x4 g0, g1; unpack8(gw, g0, g1);
;                     f32x4 v0, v1;
; #pragma unroll
;                     for (int j = 0; j < 4; ++j) { v0[j] = sigmoidf_(g0[j]) * acc[ai][bj][m][0][j]; v1[j] = sigmoidf_(g1[j]) * acc[ai][bj][m][1][j]; }
;                     const u32x4 mw = *(const u32x4*)(rowp + bj * 128); f32x4 m0, m1; unpack8(mw, m0, m1); v0 += m0; v1 += m1;
;                     __builtin_amdgcn_raw_buffer_store_b128(pack8(v0, v1), rsrc, (unsigned)(((size_t)row * DIN + col0 + bj * 128) * 2), 0, 16  ); }
	v_mov_b64_e32 v[54:55], v[208:209]
	v_mov_b64_e32 v[56:57], v[210:211]
	v_mov_b64_e32 v[58:59], v[212:213]
	v_mov_b64_e32 v[60:61], v[214:215]
	v_add_u32_e32 v198, 0x155300, v197
	global_load_dwordx4 v[208:211], v198, s[34:35]
	v_add_u32_e32 v198, 0x154100, v197
	global_load_dwordx4 v[212:215], v198, s[34:35]
	s_mov_b32 s100, 0xbfb8aa3b
	v_lshlrev_b32_e32 v242, 16, v54
	v_and_b32_e32 v243, 0xffff0000, v54
	v_lshlrev_b32_e32 v244, 16, v56
	v_and_b32_e32 v245, 0xffff0000, v56
	v_lshlrev_b32_e32 v246, 16, v55
	v_and_b32_e32 v247, 0xffff0000, v55
	v_lshlrev_b32_e32 v248, 16, v57
	v_and_b32_e32 v249, 0xffff0000, v57
	v_pk_mul_f32 v[242:243], v[242:243], s[100:101] op_sel_hi:[1,0]
	v_pk_mul_f32 v[244:245], v[244:245], s[100:101] op_sel_hi:[1,0]
	v_pk_mul_f32 v[246:247], v[246:247], s[100:101] op_sel_hi:[1,0]
	v_pk_mul_f32 v[248:249], v[248:249], s[100:101] op_sel_hi:[1,0]
	v_exp_f32_e32 v242, v242
	v_exp_f32_e32 v243, v243
	v_exp_f32_e32 v244, v244
	v_exp_f32_e32 v245, v245
	v_exp_f32_e32 v246, v246
	v_exp_f32_e32 v247, v247
	v_exp_f32_e32 v248, v248
	v_exp_f32_e32 v249, v249
	s_nop 0
	v_pk_add_f32 v[242:243], v[242:243], 1.0 op_sel_hi:[1,0]
	v_pk_add_f32 v[244:245], v[244:245], 1.0 op_sel_hi:[1,0]
	v_pk_add_f32 v[246:247], v[246:247], 1.0 op_sel_hi:[1,0]
	v_pk_add_f32 v[248:249], v[248:249], 1.0 op_sel_hi:[1,0]
	v_rcp_f32_e32 v250, v242
	v_rcp_f32_e32 v251, v243
	s_nop 0
	v_pk_fma_f32 v[252:253], v[242:243], v[250:251], 1.0 op_sel_hi:[1,1,0] neg_lo:[1,0,0] neg_hi:[1,0,0]
	v_pk_fma_f32 v[250:251], v[252:253], v[250:251], v[250:251]
	v_pk_fma_f32 v[252:253], v[242:243], v[250:251], 1.0 op_sel_hi:[1,1,0] neg_lo:[1,0,0] neg_hi:[1,0,0]
	v_pk_fma_f32 v[254:255], v[252:253], v[250:251], v[250:251]
	v_pk_fma_f32 v[252:253], v[242:243], v[254:255], 1.0 op_sel_hi:[1,1,0] neg_lo:[1,0,0] neg_hi:[1,0,0]
	v_pk_fma_f32 v[254:255], v[252:253], v[250:251], v[254:255]
	v_div_fixup_f32 v242, v254, v242, 1.0
	v_div_fixup_f32 v243, v255, v243, 1.0
	v_rcp_f32_e32 v250, v244
	v_rcp_f32_e32 v251, v245
	s_nop 0
	v_pk_fma_f32 v[252:253], v[244:245], v[250:251], 1.0 op_sel_hi:[1,1,0] neg_lo:[1,0,0] neg_hi:[1,0,0]
	v_pk_fma_f32 v[250:251], v[252:253], v[250:251], v[250:251]
	v_pk_fma_f32 v[252:253], v[244:245], v[250:251], 1.0 op_sel_hi:[1,1,0] neg_lo:[1,0,0] neg_hi:[1,0,0]
	v_pk_fma_f32 v[254:255], v[252:253], v[250:251], v[250:251]
	v_pk_fma_f32 v[252:253], v[244:245], v[254:255], 1.0 op_sel_hi:[1,1,0] neg_lo:[1,0,0] neg_hi:[1,0,0]
	v_pk_fma_f32 v[254:255], v[252:253], v[250:251], v[254:255]
	v_div_fixup_f32 v244, v254, v244, 1.0
	v_div_fixup_f32 v245, v255, v245, 1.0
	v_rcp_f32_e32 v250, v246
	v_rcp_f32_e32 v251, v247
	s_nop 0
	v_pk_fma_f32 v[252:253], v[246:247], v[250:251], 1.0 op_sel_hi:[1,1,0] neg_lo:[1,0,0] neg_hi:[1,0,0]
	v_pk_fma_f32 v[250:251], v[252:253], v[250:251], v[250:251]
	v_pk_fma_f32 v[252:253], v[246:247], v[250:251], 1.0 op_sel_hi:[1,1,0] neg_lo:[1,0,0] neg_hi:[1,0,0]
	v_pk_fma_f32 v[254:255], v[252:253], v[250:251], v[250:251]
	v_pk_fma_f32 v[252:253], v[246:247], v[254:255], 1.0 op_sel_hi:[1,1,0] neg_lo:[1,0,0] neg_hi:[1,0,0]
	v_pk_fma_f32 v[254:255], v[252:253], v[250:251], v[254:255]
	v_div_fixup_f32 v246, v254, v246, 1.0
	v_div_fixup_f32 v247, v255, v247, 1.0
	v_rcp_f32_e32 v250, v248
	v_rcp_f32_e32 v251, v249
	s_nop 0
	v_pk_fma_f32 v[252:253], v[248:249], v[250:251], 1.0 op_sel_hi:[1,1,0] neg_lo:[1,0,0] neg_hi:[1,0,0]
	v_pk_fma_f32 v[250:251], v[252:253], v[250:251], v[250:251]
	v_pk_fma_f32 v[252:253], v[248:249], v[250:251], 1.0 op_sel_hi:[1,1,0] neg_lo:[1,0,0] neg_hi:[1,0,0]
	v_pk_fma_f32 v[254:255], v[252:253], v[250:251], v[250:251]
	v_pk_fma_f32 v[252:253], v[248:249], v[254:255], 1.0 op_sel_hi:[1,1,0] neg_lo:[1,0,0] neg_hi:[1,0,0]
	v_pk_fma_f32 v[254:255], v[252:253], v[250:251], v[254:255]
	v_div_fixup_f32 v248, v254, v248, 1.0
	v_div_fixup_f32 v249, v255, v249, 1.0
	v_lshlrev_b32_e32 v66, 16, v58
	v_and_b32_e32 v67, 0xffff0000, v58
	v_lshlrev_b32_e32 v68, 16, v60
	v_and_b32_e32 v69, 0xffff0000, v60
	v_lshlrev_b32_e32 v60, 16, v61
	v_and_b32_e32 v61, 0xffff0000, v61
	v_lshlrev_b32_e32 v58, 16, v59
	v_and_b32_e32 v59, 0xffff0000, v59
	v_pk_fma_f32 v[44:45], v[44:45], v[242:243], v[66:67]
	v_pk_fma_f32 v[54:55], v[42:43], v[248:249], v[60:61]
	v_pk_fma_f32 v[42:43], v[40:41], v[244:245], v[68:69]
	v_add_lshl_u32 v56, v140, v50, 1
	v_pk_fma_f32 v[46:47], v[46:47], v[246:247], v[58:59]
	v_cvt_pk_bf16_f32 v40, v44, v45
	s_nop 0
	v_cvt_pk_bf16_f32 v41, v46, v47
	v_cvt_pk_bf16_f32 v42, v42, v43
	v_cvt_pk_bf16_f32 v43, v54, v55
	buffer_store_dwordx4 v[40:43], v56, s[20:23], 0 offen sc1
	s_nop 0
	s_waitcnt vmcnt(7)
; __device__ __forceinline__ float sigmoidf_(float x) { return 1.0f / (1.0f + __expf(-x)); }
; __device__ __forceinline__ u32x4 pack8(const f32x4 v0, const f32x4 v1) { u32x4 w; w.x = pk2(v0[0], v0[1]); w.y = pk2(v0[2], v0[3]); w.z = pk2(v1[0], v1[1]); w.w = pk2(v1[2], v1[3]); return w; }
; __device__ __forceinline__ void unpack8(const u32x4 w, f32x4& v0, f32x4& v1) { v0 = (f32x4){bflo(w.x), bfhi(w.x), bflo(w.y), bfhi(w.y)}; v1 = (f32x4){bflo(w.z), bfhi(w.z), bflo(w.w), bfhi(w.w)}; }
;     __device__ __forceinline__ void operator()(const f32x4 (&acc)[2][2][4][2], const Unit& u, int wr, int wc, int fr, int fq) const {
;     ...
;                 const int row = row0 + ai * 128 + m * 16;
;                 const bf16_t* rowp = z + (size_t)row * DIN + col0;
; #pragma unroll
;                 for (int bj = 0; bj < 2; ++bj) {
;                     const u32x4 gw = *(const u32x4*)(rowp + O_GA + bj * 128);
;                     f32x4 g0, g1; unpack8(gw, g0, g1);
;                     f32x4 v0, v1;
; #pragma unroll
;                     for (int j = 0; j < 4; ++j) { v0[j] = sigmoidf_(g0[j]) * acc[ai][bj][m][0][j]; v1[j] = sigmoidf_(g1[j]) * acc[ai][bj][m][1][j]; }
;                     const u32x4 mw = *(const u32x4*)(rowp + bj * 128); f32x4 m0, m1; unpack8(mw, m0, m1); v0 += m0; v1 += m1;
;                     __builtin_amdgcn_raw_buffer_store_b128(pack8(v0, v1), rsrc, (unsigned)(((size_t)row * DIN + col0 + bj * 128) * 2), 0, 16  ); }
	v_mov_b64_e32 v[40:41], v[232:233]
	v_mov_b64_e32 v[42:43], v[234:235]
	v_mov_b64_e32 v[44:45], v[236:237]
	v_mov_b64_e32 v[46:47], v[238:239]
	v_add_u32_e32 v198, 0x177200, v197
	global_load_dwordx4 v[232:235], v198, s[34:35]
	v_add_u32_e32 v198, 0x176000, v197
	global_load_dwordx4 v[236:239], v198, s[34:35]
	s_mov_b32 s100, 0xbfb8aa3b
	v_lshlrev_b32_e32 v242, 16, v42
	v_and_b32_e32 v243, 0xffff0000, v42
	v_lshlrev_b32_e32 v244, 16, v40
	v_and_b32_e32 v245, 0xffff0000, v40
	v_lshlrev_b32_e32 v246, 16, v41
	v_and_b32_e32 v247, 0xffff0000, v41
	v_lshlrev_b32_e32 v248, 16, v43
	v_and_b32_e32 v249, 0xffff0000, v43
	v_pk_mul_f32 v[242:243], v[242:243], s[100:101] op_sel_hi:[1,0]
	v_pk_mul_f32 v[244:245], v[244:245], s[100:101] op_sel_hi:[1,0]
	v_pk_mul_f32 v[246:247], v[246:247], s[100:101] op_sel_hi:[1,0]
	v_pk_mul_f32 v[248:249], v[248:249], s[100:101] op_sel_hi:[1,0]
	v_exp_f32_e32 v242, v242
	v_exp_f32_e32 v243, v243
	v_exp_f32_e32 v244, v244
	v_exp_f32_e32 v245, v245
	v_exp_f32_e32 v246, v246
	v_exp_f32_e32 v247, v247
	v_exp_f32_e32 v248, v248
	v_exp_f32_e32 v249, v249
	s_nop 0
	v_pk_add_f32 v[242:243], v[242:243], 1.0 op_sel_hi:[1,0]
	v_pk_add_f32 v[244:245], v[244:245], 1.0 op_sel_hi:[1,0]
	v_pk_add_f32 v[246:247], v[246:247], 1.0 op_sel_hi:[1,0]
	v_pk_add_f32 v[248:249], v[248:249], 1.0 op_sel_hi:[1,0]
	v_rcp_f32_e32 v250, v242
	v_rcp_f32_e32 v251, v243
	s_nop 0
	v_pk_fma_f32 v[252:253], v[242:243], v[250:251], 1.0 op_sel_hi:[1,1,0] neg_lo:[1,0,0] neg_hi:[1,0,0]
	v_pk_fma_f32 v[250:251], v[252:253], v[250:251], v[250:251]
	v_pk_fma_f32 v[252:253], v[242:243], v[250:251], 1.0 op_sel_hi:[1,1,0] neg_lo:[1,0,0] neg_hi:[1,0,0]
	v_pk_fma_f32 v[254:255], v[252:253], v[250:251], v[250:251]
	v_pk_fma_f32 v[252:253], v[242:243], v[254:255], 1.0 op_sel_hi:[1,1,0] neg_lo:[1,0,0] neg_hi:[1,0,0]
	v_pk_fma_f32 v[254:255], v[252:253], v[250:251], v[254:255]
	v_div_fixup_f32 v242, v254, v242, 1.0
	v_div_fixup_f32 v243, v255, v243, 1.0
	v_rcp_f32_e32 v250, v244
	v_rcp_f32_e32 v251, v245
	s_nop 0
	v_pk_fma_f32 v[252:253], v[244:245], v[250:251], 1.0 op_sel_hi:[1,1,0] neg_lo:[1,0,0] neg_hi:[1,0,0]
	v_pk_fma_f32 v[250:251], v[252:253], v[250:251], v[250:251]
	v_pk_fma_f32 v[252:253], v[244:245], v[250:251], 1.0 op_sel_hi:[1,1,0] neg_lo:[1,0,0] neg_hi:[1,0,0]
	v_pk_fma_f32 v[254:255], v[252:253], v[250:251], v[250:251]
	v_pk_fma_f32 v[252:253], v[244:245], v[254:255], 1.0 op_sel_hi:[1,1,0] neg_lo:[1,0,0] neg_hi:[1,0,0]
	v_pk_fma_f32 v[254:255], v[252:253], v[250:251], v[254:255]
	v_div_fixup_f32 v244, v254, v244, 1.0
	v_div_fixup_f32 v245, v255, v245, 1.0
	v_rcp_f32_e32 v250, v246
	v_rcp_f32_e32 v251, v247
	s_nop 0
	v_pk_fma_f32 v[252:253], v[246:247], v[250:251], 1.0 op_sel_hi:[1,1,0] neg_lo:[1,0,0] neg_hi:[1,0,0]
	v_pk_fma_f32 v[250:251], v[252:253], v[250:251], v[250:251]
	v_pk_fma_f32 v[252:253], v[246:247], v[250:251], 1.0 op_sel_hi:[1,1,0] neg_lo:[1,0,0] neg_hi:[1,0,0]
	v_pk_fma_f32 v[254:255], v[252:253], v[250:251], v[250:251]
	v_pk_fma_f32 v[252:253], v[246:247], v[254:255], 1.0 op_sel_hi:[1,1,0] neg_lo:[1,0,0] neg_hi:[1,0,0]
	v_pk_fma_f32 v[254:255], v[252:253], v[250:251], v[254:255]
	v_div_fixup_f32 v246, v254, v246, 1.0
	v_div_fixup_f32 v247, v255, v247, 1.0
	v_rcp_f32_e32 v250, v248
	v_rcp_f32_e32 v251, v249
	s_nop 0
	v_pk_fma_f32 v[252:253], v[248:249], v[250:251], 1.0 op_sel_hi:[1,1,0] neg_lo:[1,0,0] neg_hi:[1,0,0]
	v_pk_fma_f32 v[250:251], v[252:253], v[250:251], v[250:251]
	v_pk_fma_f32 v[252:253], v[248:249], v[250:251], 1.0 op_sel_hi:[1,1,0] neg_lo:[1,0,0] neg_hi:[1,0,0]
	v_pk_fma_f32 v[254:255], v[252:253], v[250:251], v[250:251]
	v_pk_fma_f32 v[252:253], v[248:249], v[254:255], 1.0 op_sel_hi:[1,1,0] neg_lo:[1,0,0] neg_hi:[1,0,0]
	v_pk_fma_f32 v[254:255], v[252:253], v[250:251], v[254:255]
	v_div_fixup_f32 v248, v254, v248, 1.0
	v_div_fixup_f32 v249, v255, v249, 1.0
	v_lshlrev_b32_e32 v52, 16, v44
	v_and_b32_e32 v53, 0xffff0000, v44
	v_lshlrev_b32_e32 v54, 16, v46
	v_and_b32_e32 v55, 0xffff0000, v46
	v_lshlrev_b32_e32 v46, 16, v47
	v_and_b32_e32 v47, 0xffff0000, v47
	v_lshlrev_b32_e32 v44, 16, v45
	v_and_b32_e32 v45, 0xffff0000, v45
	v_pk_fma_f32 v[36:37], v[36:37], v[244:245], v[52:53]
	v_pk_fma_f32 v[40:41], v[34:35], v[248:249], v[46:47]
	v_pk_fma_f32 v[34:35], v[32:33], v[242:243], v[54:55]
	v_cvt_pk_bf16_f32 v32, v36, v37
	v_pk_fma_f32 v[38:39], v[38:39], v[246:247], v[44:45]
	s_nop 0
	v_cvt_pk_bf16_f32 v33, v38, v39
	v_cvt_pk_bf16_f32 v34, v34, v35
	v_cvt_pk_bf16_f32 v35, v40, v41
	buffer_store_dwordx4 v[32:35], v56, s[20:23], 0 offen offset:256 sc1
	s_nop 1
	v_add_u32_e32 v32, 0x40a0, v158
	v_mad_i64_i32 v[34:35], s[6:7], v32, s73, 0
	v_lshl_add_u64 v[32:33], v[34:35], 1, s[34:35]
	v_lshl_add_u64 v[32:33], v[32:33], 0, v[142:143]
	v_add_co_u32_e32 v36, vcc, s74, v32
	s_nop 1
	v_addc_co_u32_e32 v37, vcc, 0, v33, vcc
	s_waitcnt vmcnt(7)
; __device__ __forceinline__ float sigmoidf_(float x) { return 1.0f / (1.0f + __expf(-x)); }
; __device__ __forceinline__ u32x4 pack8(const f32x4 v0, const f32x4 v1) { u32x4 w; w.x = pk2(v0[0], v0[1]); w.y = pk2(v0[2], v0[3]); w.z = pk2(v1[0], v1[1]); w.w = pk2(v1[2], v1[3]); return w; }
; __device__ __forceinline__ void unpack8(const u32x4 w, f32x4& v0, f32x4& v1) { v0 = (f32x4){bflo(w.x), bfhi(w.x), bflo(w.y), bfhi(w.y)}; v1 = (f32x4){bflo(w.z), bfhi(w.z), bflo(w.w), bfhi(w.w)}; }
;     __device__ __forceinline__ void operator()(const f32x4 (&acc)[2][2][4][2], const Unit& u, int wr, int wc, int fr, int fq) const {
;     ...
;                 const int row = row0 + ai * 128 + m * 16;
;                 const bf16_t* rowp = z + (size_t)row * DIN + col0;
; #pragma unroll
;                 for (int bj = 0; bj < 2; ++bj) {
;                     const u32x4 gw = *(const u32x4*)(rowp + O_GA + bj * 128);
;                     f32x4 g0, g1; unpack8(gw, g0, g1);
;                     f32x4 v0, v1;
; #pragma unroll
;                     for (int j = 0; j < 4; ++j) { v0[j] = sigmoidf_(g0[j]) * acc[ai][bj][m][0][j]; v1[j] = sigmoidf_(g1[j]) * acc[ai][bj][m][1][j]; }
;                     const u32x4 mw = *(const u32x4*)(rowp + bj * 128); f32x4 m0, m1; unpack8(mw, m0, m1); v0 += m0; v1 += m1;
;                     __builtin_amdgcn_raw_buffer_store_b128(pack8(v0, v1), rsrc, (unsigned)(((size_t)row * DIN + col0 + bj * 128) * 2), 0, 16  ); }
	v_mov_b64_e32 v[38:39], v[200:201]
	v_mov_b64_e32 v[40:41], v[202:203]
	v_mov_b64_e32 v[42:43], v[204:205]
	v_mov_b64_e32 v[44:45], v[206:207]
	v_add_u32_e32 v198, 0x177300, v197
	global_load_dwordx4 v[200:203], v198, s[34:35]
	v_add_u32_e32 v198, 0x176100, v197
	global_load_dwordx4 v[204:207], v198, s[34:35]
	s_mov_b32 s100, 0xbfb8aa3b
	v_lshlrev_b32_e32 v242, 16, v38
	v_and_b32_e32 v243, 0xffff0000, v38
	v_lshlrev_b32_e32 v244, 16, v40
	v_and_b32_e32 v245, 0xffff0000, v40
	v_lshlrev_b32_e32 v246, 16, v39
	v_and_b32_e32 v247, 0xffff0000, v39
	v_lshlrev_b32_e32 v248, 16, v41
	v_and_b32_e32 v249, 0xffff0000, v41
	v_pk_mul_f32 v[242:243], v[242:243], s[100:101] op_sel_hi:[1,0]
	v_pk_mul_f32 v[244:245], v[244:245], s[100:101] op_sel_hi:[1,0]
	v_pk_mul_f32 v[246:247], v[246:247], s[100:101] op_sel_hi:[1,0]
	v_pk_mul_f32 v[248:249], v[248:249], s[100:101] op_sel_hi:[1,0]
	v_exp_f32_e32 v242, v242
	v_exp_f32_e32 v243, v243
	v_exp_f32_e32 v244, v244
	v_exp_f32_e32 v245, v245
	v_exp_f32_e32 v246, v246
	v_exp_f32_e32 v247, v247
	v_exp_f32_e32 v248, v248
	v_exp_f32_e32 v249, v249
	s_nop 0
	v_pk_add_f32 v[242:243], v[242:243], 1.0 op_sel_hi:[1,0]
	v_pk_add_f32 v[244:245], v[244:245], 1.0 op_sel_hi:[1,0]
	v_pk_add_f32 v[246:247], v[246:247], 1.0 op_sel_hi:[1,0]
	v_pk_add_f32 v[248:249], v[248:249], 1.0 op_sel_hi:[1,0]
	v_rcp_f32_e32 v250, v242
	v_rcp_f32_e32 v251, v243
	s_nop 0
	v_pk_fma_f32 v[252:253], v[242:243], v[250:251], 1.0 op_sel_hi:[1,1,0] neg_lo:[1,0,0] neg_hi:[1,0,0]
	v_pk_fma_f32 v[250:251], v[252:253], v[250:251], v[250:251]
	v_pk_fma_f32 v[252:253], v[242:243], v[250:251], 1.0 op_sel_hi:[1,1,0] neg_lo:[1,0,0] neg_hi:[1,0,0]
	v_pk_fma_f32 v[254:255], v[252:253], v[250:251], v[250:251]
	v_pk_fma_f32 v[252:253], v[242:243], v[254:255], 1.0 op_sel_hi:[1,1,0] neg_lo:[1,0,0] neg_hi:[1,0,0]
	v_pk_fma_f32 v[254:255], v[252:253], v[250:251], v[254:255]
	v_div_fixup_f32 v242, v254, v242, 1.0
	v_div_fixup_f32 v243, v255, v243, 1.0
	v_rcp_f32_e32 v250, v244
	v_rcp_f32_e32 v251, v245
	s_nop 0
	v_pk_fma_f32 v[252:253], v[244:245], v[250:251], 1.0 op_sel_hi:[1,1,0] neg_lo:[1,0,0] neg_hi:[1,0,0]
	v_pk_fma_f32 v[250:251], v[252:253], v[250:251], v[250:251]
	v_pk_fma_f32 v[252:253], v[244:245], v[250:251], 1.0 op_sel_hi:[1,1,0] neg_lo:[1,0,0] neg_hi:[1,0,0]
	v_pk_fma_f32 v[254:255], v[252:253], v[250:251], v[250:251]
	v_pk_fma_f32 v[252:253], v[244:245], v[254:255], 1.0 op_sel_hi:[1,1,0] neg_lo:[1,0,0] neg_hi:[1,0,0]
	v_pk_fma_f32 v[254:255], v[252:253], v[250:251], v[254:255]
	v_div_fixup_f32 v244, v254, v244, 1.0
	v_div_fixup_f32 v245, v255, v245, 1.0
	v_rcp_f32_e32 v250, v246
	v_rcp_f32_e32 v251, v247
	s_nop 0
	v_pk_fma_f32 v[252:253], v[246:247], v[250:251], 1.0 op_sel_hi:[1,1,0] neg_lo:[1,0,0] neg_hi:[1,0,0]
	v_pk_fma_f32 v[250:251], v[252:253], v[250:251], v[250:251]
	v_pk_fma_f32 v[252:253], v[246:247], v[250:251], 1.0 op_sel_hi:[1,1,0] neg_lo:[1,0,0] neg_hi:[1,0,0]
	v_pk_fma_f32 v[254:255], v[252:253], v[250:251], v[250:251]
	v_pk_fma_f32 v[252:253], v[246:247], v[254:255], 1.0 op_sel_hi:[1,1,0] neg_lo:[1,0,0] neg_hi:[1,0,0]
	v_pk_fma_f32 v[254:255], v[252:253], v[250:251], v[254:255]
	v_div_fixup_f32 v246, v254, v246, 1.0
	v_div_fixup_f32 v247, v255, v247, 1.0
	v_rcp_f32_e32 v250, v248
	v_rcp_f32_e32 v251, v249
	s_nop 0
	v_pk_fma_f32 v[252:253], v[248:249], v[250:251], 1.0 op_sel_hi:[1,1,0] neg_lo:[1,0,0] neg_hi:[1,0,0]
	v_pk_fma_f32 v[250:251], v[252:253], v[250:251], v[250:251]
	v_pk_fma_f32 v[252:253], v[248:249], v[250:251], 1.0 op_sel_hi:[1,1,0] neg_lo:[1,0,0] neg_hi:[1,0,0]
	v_pk_fma_f32 v[254:255], v[252:253], v[250:251], v[250:251]
	v_pk_fma_f32 v[252:253], v[248:249], v[254:255], 1.0 op_sel_hi:[1,1,0] neg_lo:[1,0,0] neg_hi:[1,0,0]
	v_pk_fma_f32 v[254:255], v[252:253], v[250:251], v[254:255]
	v_div_fixup_f32 v248, v254, v248, 1.0
	v_div_fixup_f32 v249, v255, v249, 1.0
	v_lshlrev_b32_e32 v50, 16, v42
	v_and_b32_e32 v51, 0xffff0000, v42
	v_lshlrev_b32_e32 v52, 16, v44
	v_and_b32_e32 v53, 0xffff0000, v44
	v_lshlrev_b32_e32 v44, 16, v45
	v_and_b32_e32 v45, 0xffff0000, v45
	v_lshlrev_b32_e32 v42, 16, v43
	v_and_b32_e32 v43, 0xffff0000, v43
	v_pk_fma_f32 v[28:29], v[28:29], v[242:243], v[50:51]
	v_pk_fma_f32 v[38:39], v[26:27], v[248:249], v[44:45]
	v_pk_fma_f32 v[26:27], v[24:25], v[244:245], v[52:53]
	v_add_lshl_u32 v40, v140, v34, 1
	v_pk_fma_f32 v[30:31], v[30:31], v[246:247], v[42:43]
	v_cvt_pk_bf16_f32 v24, v28, v29
	s_nop 0
	v_cvt_pk_bf16_f32 v25, v30, v31
	v_cvt_pk_bf16_f32 v26, v26, v27
	v_cvt_pk_bf16_f32 v27, v38, v39
	buffer_store_dwordx4 v[24:27], v40, s[20:23], 0 offen sc1
	s_nop 0
	s_waitcnt vmcnt(7)
; __device__ __forceinline__ float sigmoidf_(float x) { return 1.0f / (1.0f + __expf(-x)); }
; __device__ __forceinline__ u32x4 pack8(const f32x4 v0, const f32x4 v1) { u32x4 w; w.x = pk2(v0[0], v0[1]); w.y = pk2(v0[2], v0[3]); w.z = pk2(v1[0], v1[1]); w.w = pk2(v1[2], v1[3]); return w; }
; __device__ __forceinline__ void unpack8(const u32x4 w, f32x4& v0, f32x4& v1) { v0 = (f32x4){bflo(w.x), bfhi(w.x), bflo(w.y), bfhi(w.y)}; v1 = (f32x4){bflo(w.z), bfhi(w.z), bflo(w.w), bfhi(w.w)}; }
;     __device__ __forceinline__ void operator()(const f32x4 (&acc)[2][2][4][2], const Unit& u, int wr, int wc, int fr, int fq) const {
;     ...
;                 const int row = row0 + ai * 128 + m * 16;
;                 const bf16_t* rowp = z + (size_t)row * DIN + col0;
; #pragma unroll
;                 for (int bj = 0; bj < 2; ++bj) {
;                     const u32x4 gw = *(const u32x4*)(rowp + O_GA + bj * 128);
;                     f32x4 g0, g1; unpack8(gw, g0, g1);
;                     f32x4 v0, v1;
; #pragma unroll
;                     for (int j = 0; j < 4; ++j) { v0[j] = sigmoidf_(g0[j]) * acc[ai][bj][m][0][j]; v1[j] = sigmoidf_(g1[j]) * acc[ai][bj][m][1][j]; }
;                     const u32x4 mw = *(const u32x4*)(rowp + bj * 128); f32x4 m0, m1; unpack8(mw, m0, m1); v0 += m0; v1 += m1;
;                     __builtin_amdgcn_raw_buffer_store_b128(pack8(v0, v1), rsrc, (unsigned)(((size_t)row * DIN + col0 + bj * 128) * 2), 0, 16  ); }
	v_mov_b64_e32 v[24:25], v[208:209]
	v_mov_b64_e32 v[26:27], v[210:211]
	v_mov_b64_e32 v[28:29], v[212:213]
	v_mov_b64_e32 v[30:31], v[214:215]
	s_mov_b32 s100, 0xbfb8aa3b
	v_lshlrev_b32_e32 v242, 16, v26
	v_and_b32_e32 v243, 0xffff0000, v26
	v_lshlrev_b32_e32 v244, 16, v24
	v_and_b32_e32 v245, 0xffff0000, v24
	v_lshlrev_b32_e32 v246, 16, v25
	v_and_b32_e32 v247, 0xffff0000, v25
	v_lshlrev_b32_e32 v248, 16, v27
	v_and_b32_e32 v249, 0xffff0000, v27
	v_pk_mul_f32 v[242:243], v[242:243], s[100:101] op_sel_hi:[1,0]
	v_pk_mul_f32 v[244:245], v[244:245], s[100:101] op_sel_hi:[1,0]
	v_pk_mul_f32 v[246:247], v[246:247], s[100:101] op_sel_hi:[1,0]
	v_pk_mul_f32 v[248:249], v[248:249], s[100:101] op_sel_hi:[1,0]
	v_exp_f32_e32 v242, v242
	v_exp_f32_e32 v243, v243
	v_exp_f32_e32 v244, v244
	v_exp_f32_e32 v245, v245
	v_exp_f32_e32 v246, v246
	v_exp_f32_e32 v247, v247
	v_exp_f32_e32 v248, v248
	v_exp_f32_e32 v249, v249
	s_nop 0
	v_pk_add_f32 v[242:243], v[242:243], 1.0 op_sel_hi:[1,0]
	v_pk_add_f32 v[244:245], v[244:245], 1.0 op_sel_hi:[1,0]
	v_pk_add_f32 v[246:247], v[246:247], 1.0 op_sel_hi:[1,0]
	v_pk_add_f32 v[248:249], v[248:249], 1.0 op_sel_hi:[1,0]
	v_rcp_f32_e32 v250, v242
	v_rcp_f32_e32 v251, v243
	s_nop 0
	v_pk_fma_f32 v[252:253], v[242:243], v[250:251], 1.0 op_sel_hi:[1,1,0] neg_lo:[1,0,0] neg_hi:[1,0,0]
	v_pk_fma_f32 v[250:251], v[252:253], v[250:251], v[250:251]
	v_pk_fma_f32 v[252:253], v[242:243], v[250:251], 1.0 op_sel_hi:[1,1,0] neg_lo:[1,0,0] neg_hi:[1,0,0]
	v_pk_fma_f32 v[254:255], v[252:253], v[250:251], v[250:251]
	v_pk_fma_f32 v[252:253], v[242:243], v[254:255], 1.0 op_sel_hi:[1,1,0] neg_lo:[1,0,0] neg_hi:[1,0,0]
	v_pk_fma_f32 v[254:255], v[252:253], v[250:251], v[254:255]
	v_div_fixup_f32 v242, v254, v242, 1.0
	v_div_fixup_f32 v243, v255, v243, 1.0
	v_rcp_f32_e32 v250, v244
	v_rcp_f32_e32 v251, v245
	s_nop 0
	v_pk_fma_f32 v[252:253], v[244:245], v[250:251], 1.0 op_sel_hi:[1,1,0] neg_lo:[1,0,0] neg_hi:[1,0,0]
	v_pk_fma_f32 v[250:251], v[252:253], v[250:251], v[250:251]
	v_pk_fma_f32 v[252:253], v[244:245], v[250:251], 1.0 op_sel_hi:[1,1,0] neg_lo:[1,0,0] neg_hi:[1,0,0]
	v_pk_fma_f32 v[254:255], v[252:253], v[250:251], v[250:251]
	v_pk_fma_f32 v[252:253], v[244:245], v[254:255], 1.0 op_sel_hi:[1,1,0] neg_lo:[1,0,0] neg_hi:[1,0,0]
	v_pk_fma_f32 v[254:255], v[252:253], v[250:251], v[254:255]
	v_div_fixup_f32 v244, v254, v244, 1.0
	v_div_fixup_f32 v245, v255, v245, 1.0
	v_rcp_f32_e32 v250, v246
	v_rcp_f32_e32 v251, v247
	s_nop 0
	v_pk_fma_f32 v[252:253], v[246:247], v[250:251], 1.0 op_sel_hi:[1,1,0] neg_lo:[1,0,0] neg_hi:[1,0,0]
	v_pk_fma_f32 v[250:251], v[252:253], v[250:251], v[250:251]
	v_pk_fma_f32 v[252:253], v[246:247], v[250:251], 1.0 op_sel_hi:[1,1,0] neg_lo:[1,0,0] neg_hi:[1,0,0]
	v_pk_fma_f32 v[254:255], v[252:253], v[250:251], v[250:251]
	v_pk_fma_f32 v[252:253], v[246:247], v[254:255], 1.0 op_sel_hi:[1,1,0] neg_lo:[1,0,0] neg_hi:[1,0,0]
	v_pk_fma_f32 v[254:255], v[252:253], v[250:251], v[254:255]
	v_div_fixup_f32 v246, v254, v246, 1.0
	v_div_fixup_f32 v247, v255, v247, 1.0
	v_rcp_f32_e32 v250, v248
	v_rcp_f32_e32 v251, v249
	s_nop 0
	v_pk_fma_f32 v[252:253], v[248:249], v[250:251], 1.0 op_sel_hi:[1,1,0] neg_lo:[1,0,0] neg_hi:[1,0,0]
	v_pk_fma_f32 v[250:251], v[252:253], v[250:251], v[250:251]
	v_pk_fma_f32 v[252:253], v[248:249], v[250:251], 1.0 op_sel_hi:[1,1,0] neg_lo:[1,0,0] neg_hi:[1,0,0]
	v_pk_fma_f32 v[254:255], v[252:253], v[250:251], v[250:251]
	v_pk_fma_f32 v[252:253], v[248:249], v[254:255], 1.0 op_sel_hi:[1,1,0] neg_lo:[1,0,0] neg_hi:[1,0,0]
	v_pk_fma_f32 v[254:255], v[252:253], v[250:251], v[254:255]
	v_div_fixup_f32 v248, v254, v248, 1.0
	v_div_fixup_f32 v249, v255, v249, 1.0
	v_lshlrev_b32_e32 v36, 16, v28
	v_and_b32_e32 v37, 0xffff0000, v28
	v_lshlrev_b32_e32 v38, 16, v30
	v_and_b32_e32 v39, 0xffff0000, v30
	v_lshlrev_b32_e32 v30, 16, v31
	v_and_b32_e32 v31, 0xffff0000, v31
	v_lshlrev_b32_e32 v28, 16, v29
	v_and_b32_e32 v29, 0xffff0000, v29
	v_pk_fma_f32 v[20:21], v[20:21], v[244:245], v[36:37]
	v_pk_fma_f32 v[24:25], v[18:19], v[248:249], v[30:31]
	v_pk_fma_f32 v[18:19], v[16:17], v[242:243], v[38:39]
	v_cvt_pk_bf16_f32 v16, v20, v21
	v_pk_fma_f32 v[22:23], v[22:23], v[246:247], v[28:29]
	s_nop 0
	v_cvt_pk_bf16_f32 v17, v22, v23
	v_cvt_pk_bf16_f32 v18, v18, v19
	v_cvt_pk_bf16_f32 v19, v24, v25
	buffer_store_dwordx4 v[16:19], v40, s[20:23], 0 offen offset:256 sc1
	s_nop 1
	v_add_u32_e32 v16, 0x40b0, v158
	v_mad_i64_i32 v[18:19], s[6:7], v16, s73, 0
	v_lshl_add_u64 v[16:17], v[18:19], 1, s[34:35]
	v_lshl_add_u64 v[16:17], v[16:17], 0, v[142:143]
	v_add_co_u32_e32 v20, vcc, s74, v16
	s_nop 1
	v_addc_co_u32_e32 v21, vcc, 0, v17, vcc
	s_waitcnt vmcnt(5)
; __device__ __forceinline__ float sigmoidf_(float x) { return 1.0f / (1.0f + __expf(-x)); }
; __device__ __forceinline__ u32x4 pack8(const f32x4 v0, const f32x4 v1) { u32x4 w; w.x = pk2(v0[0], v0[1]); w.y = pk2(v0[2], v0[3]); w.z = pk2(v1[0], v1[1]); w.w = pk2(v1[2], v1[3]); return w; }
; __device__ __forceinline__ void unpack8(const u32x4 w, f32x4& v0, f32x4& v1) { v0 = (f32x4){bflo(w.x), bfhi(w.x), bflo(w.y), bfhi(w.y)}; v1 = (f32x4){bflo(w.z), bfhi(w.z), bflo(w.w), bfhi(w.w)}; }
;     __device__ __forceinline__ void operator()(const f32x4 (&acc)[2][2][4][2], const Unit& u, int wr, int wc, int fr, int fq) const {
;     ...
;                 const int row = row0 + ai * 128 + m * 16;
;                 const bf16_t* rowp = z + (size_t)row * DIN + col0;
; #pragma unroll
;                 for (int bj = 0; bj < 2; ++bj) {
;                     const u32x4 gw = *(const u32x4*)(rowp + O_GA + bj * 128);
;                     f32x4 g0, g1; unpack8(gw, g0, g1);
;                     f32x4 v0, v1;
; #pragma unroll
;                     for (int j = 0; j < 4; ++j) { v0[j] = sigmoidf_(g0[j]) * acc[ai][bj][m][0][j]; v1[j] = sigmoidf_(g1[j]) * acc[ai][bj][m][1][j]; }
;                     const u32x4 mw = *(const u32x4*)(rowp + bj * 128); f32x4 m0, m1; unpack8(mw, m0, m1); v0 += m0; v1 += m1;
;                     __builtin_amdgcn_raw_buffer_store_b128(pack8(v0, v1), rsrc, (unsigned)(((size_t)row * DIN + col0 + bj * 128) * 2), 0, 16  ); }
	v_mov_b64_e32 v[22:23], v[232:233]
	v_mov_b64_e32 v[24:25], v[234:235]
	v_mov_b64_e32 v[26:27], v[236:237]
	v_mov_b64_e32 v[28:29], v[238:239]
	s_mov_b32 s100, 0xbfb8aa3b
	v_lshlrev_b32_e32 v242, 16, v22
	v_and_b32_e32 v243, 0xffff0000, v22
	v_lshlrev_b32_e32 v244, 16, v24
	v_and_b32_e32 v245, 0xffff0000, v24
	v_lshlrev_b32_e32 v246, 16, v23
	v_and_b32_e32 v247, 0xffff0000, v23
	v_lshlrev_b32_e32 v248, 16, v25
	v_and_b32_e32 v249, 0xffff0000, v25
	v_pk_mul_f32 v[242:243], v[242:243], s[100:101] op_sel_hi:[1,0]
	v_pk_mul_f32 v[244:245], v[244:245], s[100:101] op_sel_hi:[1,0]
	v_pk_mul_f32 v[246:247], v[246:247], s[100:101] op_sel_hi:[1,0]
	v_pk_mul_f32 v[248:249], v[248:249], s[100:101] op_sel_hi:[1,0]
	v_exp_f32_e32 v242, v242
	v_exp_f32_e32 v243, v243
	v_exp_f32_e32 v244, v244
	v_exp_f32_e32 v245, v245
	v_exp_f32_e32 v246, v246
	v_exp_f32_e32 v247, v247
	v_exp_f32_e32 v248, v248
	v_exp_f32_e32 v249, v249
	s_nop 0
	v_pk_add_f32 v[242:243], v[242:243], 1.0 op_sel_hi:[1,0]
	v_pk_add_f32 v[244:245], v[244:245], 1.0 op_sel_hi:[1,0]
	v_pk_add_f32 v[246:247], v[246:247], 1.0 op_sel_hi:[1,0]
	v_pk_add_f32 v[248:249], v[248:249], 1.0 op_sel_hi:[1,0]
	v_rcp_f32_e32 v250, v242
	v_rcp_f32_e32 v251, v243
	s_nop 0
	v_pk_fma_f32 v[252:253], v[242:243], v[250:251], 1.0 op_sel_hi:[1,1,0] neg_lo:[1,0,0] neg_hi:[1,0,0]
	v_pk_fma_f32 v[250:251], v[252:253], v[250:251], v[250:251]
	v_pk_fma_f32 v[252:253], v[242:243], v[250:251], 1.0 op_sel_hi:[1,1,0] neg_lo:[1,0,0] neg_hi:[1,0,0]
	v_pk_fma_f32 v[254:255], v[252:253], v[250:251], v[250:251]
	v_pk_fma_f32 v[252:253], v[242:243], v[254:255], 1.0 op_sel_hi:[1,1,0] neg_lo:[1,0,0] neg_hi:[1,0,0]
	v_pk_fma_f32 v[254:255], v[252:253], v[250:251], v[254:255]
	v_div_fixup_f32 v242, v254, v242, 1.0
	v_div_fixup_f32 v243, v255, v243, 1.0
	v_rcp_f32_e32 v250, v244
	v_rcp_f32_e32 v251, v245
	s_nop 0
	v_pk_fma_f32 v[252:253], v[244:245], v[250:251], 1.0 op_sel_hi:[1,1,0] neg_lo:[1,0,0] neg_hi:[1,0,0]
	v_pk_fma_f32 v[250:251], v[252:253], v[250:251], v[250:251]
	v_pk_fma_f32 v[252:253], v[244:245], v[250:251], 1.0 op_sel_hi:[1,1,0] neg_lo:[1,0,0] neg_hi:[1,0,0]
	v_pk_fma_f32 v[254:255], v[252:253], v[250:251], v[250:251]
	v_pk_fma_f32 v[252:253], v[244:245], v[254:255], 1.0 op_sel_hi:[1,1,0] neg_lo:[1,0,0] neg_hi:[1,0,0]
	v_pk_fma_f32 v[254:255], v[252:253], v[250:251], v[254:255]
	v_div_fixup_f32 v244, v254, v244, 1.0
	v_div_fixup_f32 v245, v255, v245, 1.0
	v_rcp_f32_e32 v250, v246
	v_rcp_f32_e32 v251, v247
	s_nop 0
	v_pk_fma_f32 v[252:253], v[246:247], v[250:251], 1.0 op_sel_hi:[1,1,0] neg_lo:[1,0,0] neg_hi:[1,0,0]
	v_pk_fma_f32 v[250:251], v[252:253], v[250:251], v[250:251]
	v_pk_fma_f32 v[252:253], v[246:247], v[250:251], 1.0 op_sel_hi:[1,1,0] neg_lo:[1,0,0] neg_hi:[1,0,0]
	v_pk_fma_f32 v[254:255], v[252:253], v[250:251], v[250:251]
	v_pk_fma_f32 v[252:253], v[246:247], v[254:255], 1.0 op_sel_hi:[1,1,0] neg_lo:[1,0,0] neg_hi:[1,0,0]
	v_pk_fma_f32 v[254:255], v[252:253], v[250:251], v[254:255]
	v_div_fixup_f32 v246, v254, v246, 1.0
	v_div_fixup_f32 v247, v255, v247, 1.0
	v_rcp_f32_e32 v250, v248
	v_rcp_f32_e32 v251, v249
	s_nop 0
	v_pk_fma_f32 v[252:253], v[248:249], v[250:251], 1.0 op_sel_hi:[1,1,0] neg_lo:[1,0,0] neg_hi:[1,0,0]
	v_pk_fma_f32 v[250:251], v[252:253], v[250:251], v[250:251]
	v_pk_fma_f32 v[252:253], v[248:249], v[250:251], 1.0 op_sel_hi:[1,1,0] neg_lo:[1,0,0] neg_hi:[1,0,0]
	v_pk_fma_f32 v[254:255], v[252:253], v[250:251], v[250:251]
	v_pk_fma_f32 v[252:253], v[248:249], v[254:255], 1.0 op_sel_hi:[1,1,0] neg_lo:[1,0,0] neg_hi:[1,0,0]
	v_pk_fma_f32 v[254:255], v[252:253], v[250:251], v[254:255]
	v_div_fixup_f32 v248, v254, v248, 1.0
	v_div_fixup_f32 v249, v255, v249, 1.0
	v_lshlrev_b32_e32 v34, 16, v26
	v_and_b32_e32 v35, 0xffff0000, v26
	v_lshlrev_b32_e32 v36, 16, v28
	v_and_b32_e32 v37, 0xffff0000, v28
	v_lshlrev_b32_e32 v28, 16, v29
	v_and_b32_e32 v29, 0xffff0000, v29
	v_lshlrev_b32_e32 v26, 16, v27
	v_and_b32_e32 v27, 0xffff0000, v27
	v_pk_fma_f32 v[12:13], v[12:13], v[242:243], v[34:35]
	v_pk_fma_f32 v[22:23], v[10:11], v[248:249], v[28:29]
	v_pk_fma_f32 v[10:11], v[8:9], v[244:245], v[36:37]
	v_add_lshl_u32 v24, v140, v18, 1
	v_pk_fma_f32 v[14:15], v[14:15], v[246:247], v[26:27]
	v_cvt_pk_bf16_f32 v8, v12, v13
	s_nop 0
	v_cvt_pk_bf16_f32 v9, v14, v15
	v_cvt_pk_bf16_f32 v10, v10, v11
	v_cvt_pk_bf16_f32 v11, v22, v23
	buffer_store_dwordx4 v[8:11], v24, s[20:23], 0 offen sc1
	s_nop 0
	s_waitcnt vmcnt(3)
; __device__ __forceinline__ float sigmoidf_(float x) { return 1.0f / (1.0f + __expf(-x)); }
; __device__ __forceinline__ u32x4 pack8(const f32x4 v0, const f32x4 v1) { u32x4 w; w.x = pk2(v0[0], v0[1]); w.y = pk2(v0[2], v0[3]); w.z = pk2(v1[0], v1[1]); w.w = pk2(v1[2], v1[3]); return w; }
; __device__ __forceinline__ void unpack8(const u32x4 w, f32x4& v0, f32x4& v1) { v0 = (f32x4){bflo(w.x), bfhi(w.x), bflo(w.y), bfhi(w.y)}; v1 = (f32x4){bflo(w.z), bfhi(w.z), bflo(w.w), bfhi(w.w)}; }
;     __device__ __forceinline__ void operator()(const f32x4 (&acc)[2][2][4][2], const Unit& u, int wr, int wc, int fr, int fq) const {
;     ...
;                 const int row = row0 + ai * 128 + m * 16;
;                 const bf16_t* rowp = z + (size_t)row * DIN + col0;
; #pragma unroll
;                 for (int bj = 0; bj < 2; ++bj) {
;                     const u32x4 gw = *(const u32x4*)(rowp + O_GA + bj * 128);
;                     f32x4 g0, g1; unpack8(gw, g0, g1);
;                     f32x4 v0, v1;
; #pragma unroll
;                     for (int j = 0; j < 4; ++j) { v0[j] = sigmoidf_(g0[j]) * acc[ai][bj][m][0][j]; v1[j] = sigmoidf_(g1[j]) * acc[ai][bj][m][1][j]; }
;                     const u32x4 mw = *(const u32x4*)(rowp + bj * 128); f32x4 m0, m1; unpack8(mw, m0, m1); v0 += m0; v1 += m1;
;                     __builtin_amdgcn_raw_buffer_store_b128(pack8(v0, v1), rsrc, (unsigned)(((size_t)row * DIN + col0 + bj * 128) * 2), 0, 16  ); }
;             }
;         asm volatile("s_waitcnt vmcnt(0)" ::: "memory");
;         if (fr == 0 && fq == 0) (void)__hip_atomic_fetch_add(ready + 64 * (pm_off + u.pm), 1u, __ATOMIC_RELAXED, __HIP_MEMORY_SCOPE_AGENT);
	v_mov_b64_e32 v[8:9], v[200:201]
	v_mov_b64_e32 v[10:11], v[202:203]
	v_mov_b64_e32 v[12:13], v[204:205]
	v_mov_b64_e32 v[14:15], v[206:207]
	s_mov_b32 s100, 0xbfb8aa3b
	v_lshlrev_b32_e32 v242, 16, v10
	v_and_b32_e32 v243, 0xffff0000, v10
	v_lshlrev_b32_e32 v244, 16, v8
	v_and_b32_e32 v245, 0xffff0000, v8
	v_lshlrev_b32_e32 v246, 16, v9
	v_and_b32_e32 v247, 0xffff0000, v9
	v_lshlrev_b32_e32 v248, 16, v11
	v_and_b32_e32 v249, 0xffff0000, v11
	v_pk_mul_f32 v[242:243], v[242:243], s[100:101] op_sel_hi:[1,0]
	v_pk_mul_f32 v[244:245], v[244:245], s[100:101] op_sel_hi:[1,0]
	v_pk_mul_f32 v[246:247], v[246:247], s[100:101] op_sel_hi:[1,0]
	v_pk_mul_f32 v[248:249], v[248:249], s[100:101] op_sel_hi:[1,0]
	v_exp_f32_e32 v242, v242
	v_exp_f32_e32 v243, v243
	v_exp_f32_e32 v244, v244
	v_exp_f32_e32 v245, v245
	v_exp_f32_e32 v246, v246
	v_exp_f32_e32 v247, v247
	v_exp_f32_e32 v248, v248
	v_exp_f32_e32 v249, v249
	s_nop 0
	v_pk_add_f32 v[242:243], v[242:243], 1.0 op_sel_hi:[1,0]
	v_pk_add_f32 v[244:245], v[244:245], 1.0 op_sel_hi:[1,0]
	v_pk_add_f32 v[246:247], v[246:247], 1.0 op_sel_hi:[1,0]
	v_pk_add_f32 v[248:249], v[248:249], 1.0 op_sel_hi:[1,0]
	v_rcp_f32_e32 v250, v242
	v_rcp_f32_e32 v251, v243
	s_nop 0
	v_pk_fma_f32 v[252:253], v[242:243], v[250:251], 1.0 op_sel_hi:[1,1,0] neg_lo:[1,0,0] neg_hi:[1,0,0]
	v_pk_fma_f32 v[250:251], v[252:253], v[250:251], v[250:251]
	v_pk_fma_f32 v[252:253], v[242:243], v[250:251], 1.0 op_sel_hi:[1,1,0] neg_lo:[1,0,0] neg_hi:[1,0,0]
	v_pk_fma_f32 v[254:255], v[252:253], v[250:251], v[250:251]
	v_pk_fma_f32 v[252:253], v[242:243], v[254:255], 1.0 op_sel_hi:[1,1,0] neg_lo:[1,0,0] neg_hi:[1,0,0]
	v_pk_fma_f32 v[254:255], v[252:253], v[250:251], v[254:255]
	v_div_fixup_f32 v242, v254, v242, 1.0
	v_div_fixup_f32 v243, v255, v243, 1.0
	v_rcp_f32_e32 v250, v244
	v_rcp_f32_e32 v251, v245
	s_nop 0
	v_pk_fma_f32 v[252:253], v[244:245], v[250:251], 1.0 op_sel_hi:[1,1,0] neg_lo:[1,0,0] neg_hi:[1,0,0]
	v_pk_fma_f32 v[250:251], v[252:253], v[250:251], v[250:251]
	v_pk_fma_f32 v[252:253], v[244:245], v[250:251], 1.0 op_sel_hi:[1,1,0] neg_lo:[1,0,0] neg_hi:[1,0,0]
	v_pk_fma_f32 v[254:255], v[252:253], v[250:251], v[250:251]
	v_pk_fma_f32 v[252:253], v[244:245], v[254:255], 1.0 op_sel_hi:[1,1,0] neg_lo:[1,0,0] neg_hi:[1,0,0]
	v_pk_fma_f32 v[254:255], v[252:253], v[250:251], v[254:255]
	v_div_fixup_f32 v244, v254, v244, 1.0
	v_div_fixup_f32 v245, v255, v245, 1.0
	v_rcp_f32_e32 v250, v246
	v_rcp_f32_e32 v251, v247
	s_nop 0
	v_pk_fma_f32 v[252:253], v[246:247], v[250:251], 1.0 op_sel_hi:[1,1,0] neg_lo:[1,0,0] neg_hi:[1,0,0]
	v_pk_fma_f32 v[250:251], v[252:253], v[250:251], v[250:251]
	v_pk_fma_f32 v[252:253], v[246:247], v[250:251], 1.0 op_sel_hi:[1,1,0] neg_lo:[1,0,0] neg_hi:[1,0,0]
	v_pk_fma_f32 v[254:255], v[252:253], v[250:251], v[250:251]
	v_pk_fma_f32 v[252:253], v[246:247], v[254:255], 1.0 op_sel_hi:[1,1,0] neg_lo:[1,0,0] neg_hi:[1,0,0]
	v_pk_fma_f32 v[254:255], v[252:253], v[250:251], v[254:255]
	v_div_fixup_f32 v246, v254, v246, 1.0
	v_div_fixup_f32 v247, v255, v247, 1.0
	v_rcp_f32_e32 v250, v248
	v_rcp_f32_e32 v251, v249
	s_nop 0
	v_pk_fma_f32 v[252:253], v[248:249], v[250:251], 1.0 op_sel_hi:[1,1,0] neg_lo:[1,0,0] neg_hi:[1,0,0]
	v_pk_fma_f32 v[250:251], v[252:253], v[250:251], v[250:251]
	v_pk_fma_f32 v[252:253], v[248:249], v[250:251], 1.0 op_sel_hi:[1,1,0] neg_lo:[1,0,0] neg_hi:[1,0,0]
	v_pk_fma_f32 v[254:255], v[252:253], v[250:251], v[250:251]
	v_pk_fma_f32 v[252:253], v[248:249], v[254:255], 1.0 op_sel_hi:[1,1,0] neg_lo:[1,0,0] neg_hi:[1,0,0]
	v_pk_fma_f32 v[254:255], v[252:253], v[250:251], v[254:255]
	v_div_fixup_f32 v248, v254, v248, 1.0
	v_div_fixup_f32 v249, v255, v249, 1.0
	v_lshlrev_b32_e32 v20, 16, v12
	v_and_b32_e32 v21, 0xffff0000, v12
	v_lshlrev_b32_e32 v22, 16, v14
	v_and_b32_e32 v23, 0xffff0000, v14
	v_lshlrev_b32_e32 v14, 16, v15
	v_and_b32_e32 v15, 0xffff0000, v15
	v_lshlrev_b32_e32 v12, 16, v13
	v_and_b32_e32 v13, 0xffff0000, v13
	v_pk_fma_f32 v[4:5], v[4:5], v[244:245], v[20:21]
	v_pk_fma_f32 v[8:9], v[2:3], v[248:249], v[14:15]
	v_pk_fma_f32 v[2:3], v[0:1], v[242:243], v[22:23]
	v_pk_fma_f32 v[6:7], v[6:7], v[246:247], v[12:13]
	v_cvt_pk_bf16_f32 v0, v4, v5
	s_nop 0
	v_cvt_pk_bf16_f32 v1, v6, v7
	v_cvt_pk_bf16_f32 v2, v2, v3
	v_cvt_pk_bf16_f32 v3, v8, v9
	buffer_store_dwordx4 v[0:3], v24, s[20:23], 0 offen offset:256 sc1
	s_waitcnt vmcnt(0)
	s_and_saveexec_b64 s[10:11], s[8:9]
	s_cbranch_execz .LBB0_1856
	s_mov_b64 s[12:13], exec
	v_mbcnt_lo_u32_b32 v0, s12, 0
	v_mbcnt_hi_u32_b32 v0, s13, v0
	v_cmp_eq_u32_e32 vcc, 0, v0
	s_and_b64 s[6:7], exec, vcc
	s_mov_b64 exec, s[6:7]
	s_cbranch_execz .LBB0_1856
	s_lshl_b32 s6, s75, 6
	s_addk_i32 s6, 0x1000
	s_ashr_i32 s7, s6, 31
	s_lshl_b64 s[6:7], s[6:7], 2
	s_add_u32 s6, s28, s6
	s_addc_u32 s7, s29, s7
	s_bcnt1_i32_b64 s12, s[12:13]
	v_mov_b32_e32 v0, s12
	global_atomic_add v131, v0, s[6:7]
	s_branch .LBB0_1856

; __device__ __forceinline__ unsigned pk2(float lo, float hi) { unsigned r; asm volatile("v_cvt_pk_bf16_f32 %0, %1, %2" : "=v"(r) : "v"(lo), "v"(hi)); return r; }
;     __device__ __forceinline__ void operator()(const f32x4 (&acc)[2][2][4][2], const Unit& u, int wr, int wc, int fr, int fq) const {
;         const int row0 = u.pm * 256 + wr * 64 + fr, col0 = u.pn * 256 + wc * 32 + 4 * fq;
;         const float* xo = (u.pm < 64) ? xoldA : (xoldB - (size_t)T_P * DM);
; #pragma unroll
;         for (int ai = 0; ai < 2; ++ai)
; #pragma unroll
;             for (int m = 0; m < 4; ++m) {
;                 const int row = row0 + ai * 128 + m * 16; const size_t ro = (size_t)row * DM + col0;
;                 float s = 0.f;
; #pragma unroll
;                 for (int bj = 0; bj < 2; ++bj)
; #pragma unroll
;                     for (int n = 0; n < 2; ++n) {
;                         const size_t o = ro + bj * 128 + n * 16;
;                         const f32x4 xn = *(const f32x4*)(xo + o) + acc[ai][bj][m][n];
;                         *(f32x4*)(xf + o) = xn;
;                         u32x2 w; w.x = pk2(xn[0], xn[1]); w.y = pk2(xn[2], xn[3]); *(u32x2*)(xb + o) = w;
;                         s += (xn[0] * xn[0] + xn[1] * xn[1]) + (xn[2] * xn[2] + xn[3] * xn[3]);
;                     }
;                 s += __shfl_xor(s, 16); s += __shfl_xor(s, 32);
;                 if (fq == 0) ssq[(size_t)row * 16 + u.pn * 4 + wc] = s;
.LBB0_1922:
	v_lshl_add_u32 v146, s77, 8, v148
	v_lshl_or_b32 v142, s40, 8, v150
	v_ashrrev_i32_e32 v147, 31, v146
	v_ashrrev_i32_e32 v143, 31, v142
	v_lshlrev_b64 v[154:155], 10, v[146:147]
	s_cmp_lt_i32 s77, 64
	v_lshl_add_u64 v[158:159], v[154:155], 0, v[142:143]
	s_cselect_b32 s15, s25, -1
	s_cselect_b32 s14, s24, 0xfc000000
	v_lshlrev_b64 v[160:161], 2, v[158:159]
	v_lshl_add_u64 v[162:163], s[14:15], 0, v[160:161]
	v_subrev_u32_e32 v172, s14, v162
	v_add_u32_e32 v173, 0x0, v172
	global_load_dwordx4 v[174:177], v173, s[14:15]
	v_add_u32_e32 v173, 0x40, v172
	global_load_dwordx4 v[178:181], v173, s[14:15]
	v_add_u32_e32 v173, 0x200, v172
	global_load_dwordx4 v[182:185], v173, s[14:15]
	v_add_u32_e32 v173, 0x240, v172
	global_load_dwordx4 v[186:189], v173, s[14:15]
	v_add_u32_e32 v173, 0x10000, v172
	global_load_dwordx4 v[190:193], v173, s[14:15]
	v_add_u32_e32 v173, 0x10040, v172
	global_load_dwordx4 v[194:197], v173, s[14:15]
	v_add_u32_e32 v173, 0x10200, v172
	global_load_dwordx4 v[198:201], v173, s[14:15]
	v_add_u32_e32 v173, 0x10240, v172
	global_load_dwordx4 v[202:205], v173, s[14:15]
	v_add_u32_e32 v173, 0x20000, v172
	global_load_dwordx4 v[206:209], v173, s[14:15]
	v_add_u32_e32 v173, 0x20040, v172
	global_load_dwordx4 v[210:213], v173, s[14:15]
	v_add_u32_e32 v173, 0x20200, v172
	global_load_dwordx4 v[214:217], v173, s[14:15]
	v_add_u32_e32 v173, 0x20240, v172
	global_load_dwordx4 v[218:221], v173, s[14:15]
	v_add_u32_e32 v173, 0x30000, v172
	global_load_dwordx4 v[232:235], v173, s[14:15]
	v_add_u32_e32 v173, 0x30040, v172
	global_load_dwordx4 v[236:239], v173, s[14:15]
	v_add_u32_e32 v173, 0x30200, v172
	global_load_dwordx4 v[240:243], v173, s[14:15]
	v_add_u32_e32 v173, 0x30240, v172
	global_load_dwordx4 v[244:247], v173, s[14:15]
	v_add_u32_e32 v173, 0x80000, v172
	global_load_dwordx4 v[248:251], v173, s[14:15]
	v_add_u32_e32 v173, 0x80040, v172
	global_load_dwordx4 v[252:255], v173, s[14:15]
	v_lshl_add_u64 v[164:165], v[158:159], 1, s[20:21]
	v_lshl_add_u64 v[170:171], s[24:25], 0, v[160:161]
	v_xor_b32_e32 v153, 32, v152
	s_lshl_b32 s40, s40, 2
	s_ashr_i32 s41, s40, 31
	s_waitcnt vmcnt(17)
	v_mov_b64_e32 v[154:155], v[174:175]
	v_mov_b64_e32 v[156:157], v[176:177]
	v_add_u32_e32 v173, 0x80200, v172
	global_load_dwordx4 v[174:177], v173, s[14:15]
	v_pk_add_f32 v[126:127], v[126:127], v[156:157]
	v_pk_add_f32 v[124:125], v[124:125], v[154:155]
	global_store_dwordx4 v[170:171], v[124:127], off
	v_cvt_pk_bf16_f32 v154, v124, v125
	v_cvt_pk_bf16_f32 v155, v126, v127
	global_store_dwordx2 v[164:165], v[154:155], off
	s_waitcnt vmcnt(19)
	v_mov_b64_e32 v[154:155], v[178:179]
	v_mov_b64_e32 v[156:157], v[180:181]
	v_add_u32_e32 v173, 0x80240, v172
	global_load_dwordx4 v[178:181], v173, s[14:15]
	v_pk_add_f32 v[122:123], v[122:123], v[156:157]
	v_pk_add_f32 v[120:121], v[120:121], v[154:155]
	global_store_dwordx4 v[170:171], v[120:123], off offset:64
	v_cvt_pk_bf16_f32 v154, v120, v121
	v_cvt_pk_bf16_f32 v155, v122, v123
	global_store_dwordx2 v[164:165], v[154:155], off offset:32
	s_waitcnt vmcnt(21)
	v_mov_b64_e32 v[154:155], v[182:183]
	v_mov_b64_e32 v[156:157], v[184:185]
	v_add_u32_e32 v173, 0x90000, v172
	global_load_dwordx4 v[182:185], v173, s[14:15]
	v_pk_add_f32 v[156:157], v[118:119], v[156:157]
	v_pk_add_f32 v[154:155], v[116:117], v[154:155]
	global_store_dwordx4 v[170:171], v[154:157], off offset:512
	v_cvt_pk_bf16_f32 v116, v154, v155
	v_cvt_pk_bf16_f32 v117, v156, v157
	global_store_dwordx2 v[164:165], v[116:117], off offset:256
	v_mul_f32_e32 v118, v125, v125
	v_mul_f32_e32 v119, v127, v127
	v_fmac_f32_e32 v118, v124, v124
	v_fmac_f32_e32 v119, v126, v126
	v_add_f32_e32 v118, v118, v119
	v_mul_f32_e32 v119, v121, v121
	v_mul_f32_e32 v121, v123, v123
	v_fmac_f32_e32 v119, v120, v120
	v_fmac_f32_e32 v121, v122, v122
	v_add_f32_e32 v119, v119, v121
	v_add_f32_e32 v118, v118, v119
	v_mul_f32_e32 v119, v155, v155
	v_mul_f32_e32 v120, v157, v157
	v_fmac_f32_e32 v119, v154, v154
	v_fmac_f32_e32 v120, v156, v156
	v_add_f32_e32 v119, v119, v120
	v_and_b32_e32 v117, 64, v152
	v_add_f32_e32 v122, v118, v119
	v_xor_b32_e32 v116, 16, v152
	v_add_u32_e32 v117, 64, v117
	v_cmp_lt_i32_e32 vcc, v116, v117
	s_waitcnt vmcnt(23)
	v_mov_b64_e32 v[158:159], v[186:187]
	v_mov_b64_e32 v[160:161], v[188:189]
	v_add_u32_e32 v173, 0x90040, v172
	global_load_dwordx4 v[186:189], v173, s[14:15]
	v_pk_add_f32 v[120:121], v[114:115], v[160:161]
	v_pk_add_f32 v[118:119], v[112:113], v[158:159]
	v_mul_f32_e32 v113, v121, v121
	v_mul_f32_e32 v112, v119, v119
	v_fmac_f32_e32 v112, v118, v118
	v_fmac_f32_e32 v113, v120, v120
	v_cndmask_b32_e32 v116, v152, v116, vcc
	v_add_f32_e32 v112, v112, v113
	v_lshlrev_b32_e32 v116, 2, v116
	v_add_f32_e32 v112, v122, v112
	ds_bpermute_b32 v113, v116, v112
	v_cmp_lt_i32_e32 vcc, v153, v117
	global_store_dwordx4 v[170:171], v[118:121], off offset:576
	s_waitcnt lgkmcnt(0)
	v_add_f32_e32 v112, v112, v113
	v_cndmask_b32_e32 v114, v152, v153, vcc
	v_lshlrev_b32_e32 v114, 2, v114
	ds_bpermute_b32 v113, v114, v112
	v_cvt_pk_bf16_f32 v118, v118, v119
	v_cvt_pk_bf16_f32 v119, v120, v121
	global_store_dwordx2 v[164:165], v[118:119], off offset:288
	s_and_saveexec_b64 s[42:43], s[10:11]
	s_cbranch_execz .LBB0_1924
	s_waitcnt lgkmcnt(0)
	v_add_f32_e32 v115, v112, v113
	v_lshlrev_b64 v[112:113], 6, v[146:147]
	v_lshl_add_u64 v[112:113], s[22:23], 0, v[112:113]
	v_lshl_add_u64 v[112:113], s[40:41], 2, v[112:113]
	s_lshl_b32 s30, s67, 2
	v_lshl_add_u64 v[112:113], v[112:113], 0, s[30:31]
	global_store_dword v[112:113], v115, off
; __device__ __forceinline__ unsigned pk2(float lo, float hi) { unsigned r; asm volatile("v_cvt_pk_bf16_f32 %0, %1, %2" : "=v"(r) : "v"(lo), "v"(hi)); return r; }
;     __device__ __forceinline__ void operator()(const f32x4 (&acc)[2][2][4][2], const Unit& u, int wr, int wc, int fr, int fq) const {
;     ...
;                 const int row = row0 + ai * 128 + m * 16; const size_t ro = (size_t)row * DM + col0;
;                 float s = 0.f;
; #pragma unroll
;                 for (int bj = 0; bj < 2; ++bj)
; #pragma unroll
;                     for (int n = 0; n < 2; ++n) {
;                         const size_t o = ro + bj * 128 + n * 16;
;                         const f32x4 xn = *(const f32x4*)(xo + o) + acc[ai][bj][m][n];
;                         *(f32x4*)(xf + o) = xn;
;                         u32x2 w; w.x = pk2(xn[0], xn[1]); w.y = pk2(xn[2], xn[3]); *(u32x2*)(xb + o) = w;
;                         s += (xn[0] * xn[0] + xn[1] * xn[1]) + (xn[2] * xn[2] + xn[3] * xn[3]);
;                     }
;                 s += __shfl_xor(s, 16); s += __shfl_xor(s, 32);
;                 if (fq == 0) ssq[(size_t)row * 16 + u.pn * 4 + wc] = s;
.LBB0_1924:
	s_or_b64 exec, exec, s[42:43]
	v_or_b32_e32 v112, 16, v146
	s_waitcnt lgkmcnt(0)
	v_ashrrev_i32_e32 v113, 31, v112
	v_lshlrev_b64 v[118:119], 10, v[112:113]
	v_lshl_add_u64 v[122:123], v[118:119], 0, v[142:143]
	v_lshlrev_b64 v[124:125], 2, v[122:123]
	v_lshl_add_u64 v[126:127], s[14:15], 0, v[124:125]
	v_lshl_add_u64 v[122:123], v[122:123], 1, s[20:21]
	v_lshl_add_u64 v[124:125], s[24:25], 0, v[124:125]
	s_waitcnt vmcnt(25)
	v_mov_b64_e32 v[118:119], v[190:191]
	v_mov_b64_e32 v[120:121], v[192:193]
	v_add_u32_e32 v173, 0x90200, v172
	global_load_dwordx4 v[190:193], v173, s[14:15]
	v_pk_add_f32 v[110:111], v[110:111], v[120:121]
	v_pk_add_f32 v[108:109], v[108:109], v[118:119]
	global_store_dwordx4 v[124:125], v[108:111], off
	v_cvt_pk_bf16_f32 v118, v108, v109
	v_cvt_pk_bf16_f32 v119, v110, v111
	global_store_dwordx2 v[122:123], v[118:119], off
	v_mul_f32_e32 v109, v109, v109
	v_mul_f32_e32 v111, v111, v111
	v_fmac_f32_e32 v109, v108, v108
	v_fmac_f32_e32 v111, v110, v110
	v_add_f32_e32 v108, v109, v111
	s_waitcnt vmcnt(27)
	v_mov_b64_e32 v[118:119], v[194:195]
	v_mov_b64_e32 v[120:121], v[196:197]
	v_add_u32_e32 v173, 0x90240, v172
	global_load_dwordx4 v[194:197], v173, s[14:15]
	v_pk_add_f32 v[106:107], v[106:107], v[120:121]
	v_pk_add_f32 v[104:105], v[104:105], v[118:119]
	global_store_dwordx4 v[124:125], v[104:107], off offset:64
	v_cvt_pk_bf16_f32 v118, v104, v105
	v_cvt_pk_bf16_f32 v119, v106, v107
	global_store_dwordx2 v[122:123], v[118:119], off offset:32
	v_mul_f32_e32 v105, v105, v105
	v_mul_f32_e32 v107, v107, v107
	v_fmac_f32_e32 v105, v104, v104
	v_fmac_f32_e32 v107, v106, v106
	v_add_f32_e32 v104, v105, v107
	v_add_f32_e32 v104, v108, v104
	s_waitcnt vmcnt(29)
	v_mov_b64_e32 v[118:119], v[198:199]
	v_mov_b64_e32 v[120:121], v[200:201]
	v_add_u32_e32 v173, 0xa0000, v172
	global_load_dwordx4 v[198:201], v173, s[14:15]
	v_pk_add_f32 v[102:103], v[102:103], v[120:121]
	v_pk_add_f32 v[100:101], v[100:101], v[118:119]
	global_store_dwordx4 v[124:125], v[100:103], off offset:512
	v_cvt_pk_bf16_f32 v118, v100, v101
	v_cvt_pk_bf16_f32 v119, v102, v103
	global_store_dwordx2 v[122:123], v[118:119], off offset:256
	v_mul_f32_e32 v101, v101, v101
	v_mul_f32_e32 v103, v103, v103
	v_fmac_f32_e32 v101, v100, v100
	v_fmac_f32_e32 v103, v102, v102
	v_add_f32_e32 v100, v101, v103
	v_add_f32_e32 v102, v104, v100
	s_waitcnt vmcnt(31)
	v_mov_b64_e32 v[118:119], v[202:203]
	v_mov_b64_e32 v[120:121], v[204:205]
	v_add_u32_e32 v173, 0xa0040, v172
	global_load_dwordx4 v[202:205], v173, s[14:15]
	v_pk_add_f32 v[100:101], v[98:99], v[120:121]
	v_pk_add_f32 v[98:99], v[96:97], v[118:119]
	v_mul_f32_e32 v97, v101, v101
	v_mul_f32_e32 v96, v99, v99
	v_fmac_f32_e32 v96, v98, v98
	v_fmac_f32_e32 v97, v100, v100
	v_add_f32_e32 v96, v96, v97
	v_add_f32_e32 v96, v102, v96
	ds_bpermute_b32 v97, v116, v96
	global_store_dwordx4 v[124:125], v[98:101], off offset:576
	s_waitcnt lgkmcnt(0)
	v_add_f32_e32 v96, v96, v97
	ds_bpermute_b32 v97, v114, v96
	v_cvt_pk_bf16_f32 v98, v98, v99
	v_cvt_pk_bf16_f32 v99, v100, v101
	global_store_dwordx2 v[122:123], v[98:99], off offset:288
	s_and_saveexec_b64 s[42:43], s[10:11]
	s_cbranch_execz .LBB0_1926
	s_waitcnt lgkmcnt(0)
	v_add_f32_e32 v98, v96, v97
	v_lshlrev_b64 v[96:97], 6, v[112:113]
	v_lshl_add_u64 v[96:97], s[22:23], 0, v[96:97]
	v_lshl_add_u64 v[96:97], s[40:41], 2, v[96:97]
	s_lshl_b32 s30, s67, 2
	v_lshl_add_u64 v[96:97], v[96:97], 0, s[30:31]
	global_store_dword v[96:97], v98, off
.LBB0_1926:
	s_or_b64 exec, exec, s[42:43]
	v_or_b32_e32 v96, 32, v146
	s_waitcnt lgkmcnt(0)
	v_ashrrev_i32_e32 v97, 31, v96
	v_lshlrev_b64 v[98:99], 10, v[96:97]
	v_lshl_add_u64 v[102:103], v[98:99], 0, v[142:143]
	v_lshlrev_b64 v[104:105], 2, v[102:103]
	v_lshl_add_u64 v[106:107], s[14:15], 0, v[104:105]
	v_lshl_add_u64 v[102:103], v[102:103], 1, s[20:21]
	v_lshl_add_u64 v[104:105], s[24:25], 0, v[104:105]
	s_waitcnt vmcnt(33)
	v_mov_b64_e32 v[98:99], v[206:207]
	v_mov_b64_e32 v[100:101], v[208:209]
	v_add_u32_e32 v173, 0xa0200, v172
	global_load_dwordx4 v[206:209], v173, s[14:15]
	v_pk_add_f32 v[94:95], v[94:95], v[100:101]
	v_pk_add_f32 v[92:93], v[92:93], v[98:99]
	global_store_dwordx4 v[104:105], v[92:95], off
	v_cvt_pk_bf16_f32 v98, v92, v93
	v_cvt_pk_bf16_f32 v99, v94, v95
	global_store_dwordx2 v[102:103], v[98:99], off
	v_mul_f32_e32 v93, v93, v93
	v_mul_f32_e32 v95, v95, v95
	v_fmac_f32_e32 v93, v92, v92
	v_fmac_f32_e32 v95, v94, v94
	v_add_f32_e32 v92, v93, v95
	s_waitcnt vmcnt(35)
	v_mov_b64_e32 v[98:99], v[210:211]
	v_mov_b64_e32 v[100:101], v[212:213]
	v_add_u32_e32 v173, 0xa0240, v172
	global_load_dwordx4 v[210:213], v173, s[14:15]
	v_pk_add_f32 v[90:91], v[90:91], v[100:101]
	v_pk_add_f32 v[88:89], v[88:89], v[98:99]
	global_store_dwordx4 v[104:105], v[88:91], off offset:64
	v_cvt_pk_bf16_f32 v98, v88, v89
	v_cvt_pk_bf16_f32 v99, v90, v91
	global_store_dwordx2 v[102:103], v[98:99], off offset:32
	v_mul_f32_e32 v89, v89, v89
	v_mul_f32_e32 v91, v91, v91
	v_fmac_f32_e32 v89, v88, v88
	v_fmac_f32_e32 v91, v90, v90
	v_add_f32_e32 v88, v89, v91
	v_add_f32_e32 v88, v92, v88
	s_waitcnt vmcnt(37)
	v_mov_b64_e32 v[98:99], v[214:215]
	v_mov_b64_e32 v[100:101], v[216:217]
	v_add_u32_e32 v173, 0xb0000, v172
	global_load_dwordx4 v[214:217], v173, s[14:15]
	v_pk_add_f32 v[86:87], v[86:87], v[100:101]
	v_pk_add_f32 v[84:85], v[84:85], v[98:99]
	global_store_dwordx4 v[104:105], v[84:87], off offset:512
	v_cvt_pk_bf16_f32 v98, v84, v85
	v_cvt_pk_bf16_f32 v99, v86, v87
	global_store_dwordx2 v[102:103], v[98:99], off offset:256
	v_mul_f32_e32 v85, v85, v85
	v_mul_f32_e32 v87, v87, v87
	v_fmac_f32_e32 v85, v84, v84
	v_fmac_f32_e32 v87, v86, v86
	v_add_f32_e32 v84, v85, v87
	v_add_f32_e32 v86, v88, v84
	s_waitcnt vmcnt(39)
	v_mov_b64_e32 v[98:99], v[218:219]
	v_mov_b64_e32 v[100:101], v[220:221]
	v_add_u32_e32 v173, 0xb0040, v172
	global_load_dwordx4 v[218:221], v173, s[14:15]
	v_pk_add_f32 v[84:85], v[82:83], v[100:101]
	v_pk_add_f32 v[82:83], v[80:81], v[98:99]
	v_mul_f32_e32 v81, v85, v85
	v_mul_f32_e32 v80, v83, v83
	v_fmac_f32_e32 v80, v82, v82
	v_fmac_f32_e32 v81, v84, v84
	v_add_f32_e32 v80, v80, v81
	v_add_f32_e32 v80, v86, v80
	ds_bpermute_b32 v81, v116, v80
	global_store_dwordx4 v[104:105], v[82:85], off offset:576
	s_waitcnt lgkmcnt(0)
	v_add_f32_e32 v80, v80, v81
	ds_bpermute_b32 v81, v114, v80
	v_cvt_pk_bf16_f32 v82, v82, v83
	v_cvt_pk_bf16_f32 v83, v84, v85
	global_store_dwordx2 v[102:103], v[82:83], off offset:288
	s_and_saveexec_b64 s[42:43], s[10:11]
	s_cbranch_execz .LBB0_1928
	s_waitcnt lgkmcnt(0)
	v_add_f32_e32 v82, v80, v81
	v_lshlrev_b64 v[80:81], 6, v[96:97]
	v_lshl_add_u64 v[80:81], s[22:23], 0, v[80:81]
	v_lshl_add_u64 v[80:81], s[40:41], 2, v[80:81]
	s_lshl_b32 s30, s67, 2
	v_lshl_add_u64 v[80:81], v[80:81], 0, s[30:31]
	global_store_dword v[80:81], v82, off
; __device__ __forceinline__ unsigned pk2(float lo, float hi) { unsigned r; asm volatile("v_cvt_pk_bf16_f32 %0, %1, %2" : "=v"(r) : "v"(lo), "v"(hi)); return r; }
;     __device__ __forceinline__ void operator()(const f32x4 (&acc)[2][2][4][2], const Unit& u, int wr, int wc, int fr, int fq) const {
;     ...
;                 const int row = row0 + ai * 128 + m * 16; const size_t ro = (size_t)row * DM + col0;
;                 float s = 0.f;
; #pragma unroll
;                 for (int bj = 0; bj < 2; ++bj)
; #pragma unroll
;                     for (int n = 0; n < 2; ++n) {
;                         const size_t o = ro + bj * 128 + n * 16;
;                         const f32x4 xn = *(const f32x4*)(xo + o) + acc[ai][bj][m][n];
;                         *(f32x4*)(xf + o) = xn;
;                         u32x2 w; w.x = pk2(xn[0], xn[1]); w.y = pk2(xn[2], xn[3]); *(u32x2*)(xb + o) = w;
;                         s += (xn[0] * xn[0] + xn[1] * xn[1]) + (xn[2] * xn[2] + xn[3] * xn[3]);
;                     }
;                 s += __shfl_xor(s, 16); s += __shfl_xor(s, 32);
;                 if (fq == 0) ssq[(size_t)row * 16 + u.pn * 4 + wc] = s;
.LBB0_1928:
	s_or_b64 exec, exec, s[42:43]
	v_or_b32_e32 v80, 48, v146
	s_waitcnt lgkmcnt(0)
	v_ashrrev_i32_e32 v81, 31, v80
	v_lshlrev_b64 v[82:83], 10, v[80:81]
	v_lshl_add_u64 v[86:87], v[82:83], 0, v[142:143]
	v_lshlrev_b64 v[88:89], 2, v[86:87]
	v_lshl_add_u64 v[90:91], s[14:15], 0, v[88:89]
	v_lshl_add_u64 v[86:87], v[86:87], 1, s[20:21]
	v_lshl_add_u64 v[88:89], s[24:25], 0, v[88:89]
	s_waitcnt vmcnt(41)
	v_mov_b64_e32 v[82:83], v[232:233]
	v_mov_b64_e32 v[84:85], v[234:235]
	v_add_u32_e32 v173, 0xb0200, v172
	global_load_dwordx4 v[232:235], v173, s[14:15]
	v_pk_add_f32 v[78:79], v[78:79], v[84:85]
	v_pk_add_f32 v[76:77], v[76:77], v[82:83]
	global_store_dwordx4 v[88:89], v[76:79], off
	v_cvt_pk_bf16_f32 v82, v76, v77
	v_cvt_pk_bf16_f32 v83, v78, v79
	global_store_dwordx2 v[86:87], v[82:83], off
	v_mul_f32_e32 v77, v77, v77
	v_mul_f32_e32 v79, v79, v79
	v_fmac_f32_e32 v77, v76, v76
	v_fmac_f32_e32 v79, v78, v78
	v_add_f32_e32 v76, v77, v79
	s_waitcnt vmcnt(43)
	v_mov_b64_e32 v[82:83], v[236:237]
	v_mov_b64_e32 v[84:85], v[238:239]
	v_add_u32_e32 v173, 0xb0240, v172
	global_load_dwordx4 v[236:239], v173, s[14:15]
	v_pk_add_f32 v[74:75], v[74:75], v[84:85]
	v_pk_add_f32 v[72:73], v[72:73], v[82:83]
	global_store_dwordx4 v[88:89], v[72:75], off offset:64
	v_cvt_pk_bf16_f32 v82, v72, v73
	v_cvt_pk_bf16_f32 v83, v74, v75
	global_store_dwordx2 v[86:87], v[82:83], off offset:32
	v_mul_f32_e32 v73, v73, v73
	v_mul_f32_e32 v75, v75, v75
	v_fmac_f32_e32 v73, v72, v72
	v_fmac_f32_e32 v75, v74, v74
	v_add_f32_e32 v72, v73, v75
	v_add_f32_e32 v72, v76, v72
	s_waitcnt vmcnt(45)
	v_mov_b64_e32 v[82:83], v[240:241]
	v_mov_b64_e32 v[84:85], v[242:243]
	v_pk_add_f32 v[70:71], v[70:71], v[84:85]
	v_pk_add_f32 v[68:69], v[68:69], v[82:83]
	global_store_dwordx4 v[88:89], v[68:71], off offset:512
	v_cvt_pk_bf16_f32 v82, v68, v69
	v_cvt_pk_bf16_f32 v83, v70, v71
	global_store_dwordx2 v[86:87], v[82:83], off offset:256
	v_mul_f32_e32 v69, v69, v69
	v_mul_f32_e32 v71, v71, v71
	v_fmac_f32_e32 v69, v68, v68
	v_fmac_f32_e32 v71, v70, v70
	v_add_f32_e32 v68, v69, v71
	v_add_f32_e32 v70, v72, v68
	s_waitcnt vmcnt(46)
	v_mov_b64_e32 v[82:83], v[244:245]
	v_mov_b64_e32 v[84:85], v[246:247]
	v_pk_add_f32 v[68:69], v[66:67], v[84:85]
	v_pk_add_f32 v[66:67], v[64:65], v[82:83]
	v_mul_f32_e32 v65, v69, v69
	v_mul_f32_e32 v64, v67, v67
	v_fmac_f32_e32 v64, v66, v66
	v_fmac_f32_e32 v65, v68, v68
	v_add_f32_e32 v64, v64, v65
	v_add_f32_e32 v64, v70, v64
	ds_bpermute_b32 v65, v116, v64
	global_store_dwordx4 v[88:89], v[66:69], off offset:576
	s_waitcnt lgkmcnt(0)
	v_add_f32_e32 v64, v64, v65
	ds_bpermute_b32 v65, v114, v64
	v_cvt_pk_bf16_f32 v66, v66, v67
	v_cvt_pk_bf16_f32 v67, v68, v69
	global_store_dwordx2 v[86:87], v[66:67], off offset:288
	s_and_saveexec_b64 s[42:43], s[10:11]
	s_cbranch_execz .LBB0_1930
	s_waitcnt lgkmcnt(0)
	v_add_f32_e32 v66, v64, v65
	v_lshlrev_b64 v[64:65], 6, v[80:81]
	v_lshl_add_u64 v[64:65], s[22:23], 0, v[64:65]
	v_lshl_add_u64 v[64:65], s[40:41], 2, v[64:65]
	s_lshl_b32 s30, s67, 2
	v_lshl_add_u64 v[64:65], v[64:65], 0, s[30:31]
	global_store_dword v[64:65], v66, off
.LBB0_1930:
	s_or_b64 exec, exec, s[42:43]
	v_add_u32_e32 v64, 0x80, v146
	s_waitcnt lgkmcnt(0)
	v_ashrrev_i32_e32 v65, 31, v64
	v_lshlrev_b64 v[66:67], 10, v[64:65]
	v_lshl_add_u64 v[70:71], v[66:67], 0, v[142:143]
	v_lshlrev_b64 v[72:73], 2, v[70:71]
	v_lshl_add_u64 v[74:75], s[14:15], 0, v[72:73]
	v_lshl_add_u64 v[70:71], v[70:71], 1, s[20:21]
	v_lshl_add_u64 v[72:73], s[24:25], 0, v[72:73]
	s_waitcnt vmcnt(47)
	v_mov_b64_e32 v[66:67], v[248:249]
	v_mov_b64_e32 v[68:69], v[250:251]
	v_pk_add_f32 v[62:63], v[62:63], v[68:69]
	v_pk_add_f32 v[60:61], v[60:61], v[66:67]
	global_store_dwordx4 v[72:73], v[60:63], off
	v_cvt_pk_bf16_f32 v66, v60, v61
	v_cvt_pk_bf16_f32 v67, v62, v63
	global_store_dwordx2 v[70:71], v[66:67], off
	v_mul_f32_e32 v61, v61, v61
	v_mul_f32_e32 v63, v63, v63
	v_fmac_f32_e32 v61, v60, v60
	v_fmac_f32_e32 v63, v62, v62
	v_add_f32_e32 v60, v61, v63
	s_waitcnt vmcnt(48)
	v_mov_b64_e32 v[66:67], v[252:253]
	v_mov_b64_e32 v[68:69], v[254:255]
	v_pk_add_f32 v[58:59], v[58:59], v[68:69]
	v_pk_add_f32 v[56:57], v[56:57], v[66:67]
	global_store_dwordx4 v[72:73], v[56:59], off offset:64
	v_cvt_pk_bf16_f32 v66, v56, v57
	v_cvt_pk_bf16_f32 v67, v58, v59
	global_store_dwordx2 v[70:71], v[66:67], off offset:32
	v_mul_f32_e32 v57, v57, v57
	v_mul_f32_e32 v59, v59, v59
	v_fmac_f32_e32 v57, v56, v56
	v_fmac_f32_e32 v59, v58, v58
	v_add_f32_e32 v56, v57, v59
	v_add_f32_e32 v56, v60, v56
	s_waitcnt vmcnt(49)
	v_mov_b64_e32 v[66:67], v[174:175]
	v_mov_b64_e32 v[68:69], v[176:177]
	v_pk_add_f32 v[54:55], v[54:55], v[68:69]
	v_pk_add_f32 v[52:53], v[52:53], v[66:67]
	global_store_dwordx4 v[72:73], v[52:55], off offset:512
	v_cvt_pk_bf16_f32 v66, v52, v53
	v_cvt_pk_bf16_f32 v67, v54, v55
	global_store_dwordx2 v[70:71], v[66:67], off offset:256
	v_mul_f32_e32 v53, v53, v53
	v_mul_f32_e32 v55, v55, v55
	v_fmac_f32_e32 v53, v52, v52
	v_fmac_f32_e32 v55, v54, v54
	v_add_f32_e32 v52, v53, v55
	v_add_f32_e32 v54, v56, v52
	s_waitcnt vmcnt(48)
	v_mov_b64_e32 v[66:67], v[178:179]
	v_mov_b64_e32 v[68:69], v[180:181]
	v_pk_add_f32 v[52:53], v[50:51], v[68:69]
	v_pk_add_f32 v[50:51], v[48:49], v[66:67]
	v_mul_f32_e32 v49, v53, v53
	v_mul_f32_e32 v48, v51, v51
	v_fmac_f32_e32 v48, v50, v50
	v_fmac_f32_e32 v49, v52, v52
	v_add_f32_e32 v48, v48, v49
	v_add_f32_e32 v48, v54, v48
	ds_bpermute_b32 v49, v116, v48
	global_store_dwordx4 v[72:73], v[50:53], off offset:576
	s_waitcnt lgkmcnt(0)
	v_add_f32_e32 v48, v48, v49
	ds_bpermute_b32 v49, v114, v48
	v_cvt_pk_bf16_f32 v50, v50, v51
	v_cvt_pk_bf16_f32 v51, v52, v53
	global_store_dwordx2 v[70:71], v[50:51], off offset:288
	s_and_saveexec_b64 s[42:43], s[10:11]
	s_cbranch_execz .LBB0_1932
	s_waitcnt lgkmcnt(0)
	v_add_f32_e32 v50, v48, v49
	v_lshlrev_b64 v[48:49], 6, v[64:65]
	v_lshl_add_u64 v[48:49], s[22:23], 0, v[48:49]
	v_lshl_add_u64 v[48:49], s[40:41], 2, v[48:49]
	s_lshl_b32 s30, s67, 2
	v_lshl_add_u64 v[48:49], v[48:49], 0, s[30:31]
	global_store_dword v[48:49], v50, off
; __device__ __forceinline__ unsigned pk2(float lo, float hi) { unsigned r; asm volatile("v_cvt_pk_bf16_f32 %0, %1, %2" : "=v"(r) : "v"(lo), "v"(hi)); return r; }
;     __device__ __forceinline__ void operator()(const f32x4 (&acc)[2][2][4][2], const Unit& u, int wr, int wc, int fr, int fq) const {
;     ...
;                 const int row = row0 + ai * 128 + m * 16; const size_t ro = (size_t)row * DM + col0;
;                 float s = 0.f;
; #pragma unroll
;                 for (int bj = 0; bj < 2; ++bj)
; #pragma unroll
;                     for (int n = 0; n < 2; ++n) {
;                         const size_t o = ro + bj * 128 + n * 16;
;                         const f32x4 xn = *(const f32x4*)(xo + o) + acc[ai][bj][m][n];
;                         *(f32x4*)(xf + o) = xn;
;                         u32x2 w; w.x = pk2(xn[0], xn[1]); w.y = pk2(xn[2], xn[3]); *(u32x2*)(xb + o) = w;
;                         s += (xn[0] * xn[0] + xn[1] * xn[1]) + (xn[2] * xn[2] + xn[3] * xn[3]);
;                     }
;                 s += __shfl_xor(s, 16); s += __shfl_xor(s, 32);
;                 if (fq == 0) ssq[(size_t)row * 16 + u.pn * 4 + wc] = s;
.LBB0_1932:
	s_or_b64 exec, exec, s[42:43]
	v_add_u32_e32 v48, 0x90, v146
	s_waitcnt lgkmcnt(0)
	v_ashrrev_i32_e32 v49, 31, v48
	v_lshlrev_b64 v[50:51], 10, v[48:49]
	v_lshl_add_u64 v[54:55], v[50:51], 0, v[142:143]
	v_lshlrev_b64 v[56:57], 2, v[54:55]
	v_lshl_add_u64 v[58:59], s[14:15], 0, v[56:57]
	v_lshl_add_u64 v[54:55], v[54:55], 1, s[20:21]
	v_lshl_add_u64 v[56:57], s[24:25], 0, v[56:57]
	s_waitcnt vmcnt(47)
	v_mov_b64_e32 v[50:51], v[182:183]
	v_mov_b64_e32 v[52:53], v[184:185]
	v_pk_add_f32 v[46:47], v[46:47], v[52:53]
	v_pk_add_f32 v[44:45], v[44:45], v[50:51]
	global_store_dwordx4 v[56:57], v[44:47], off
	v_cvt_pk_bf16_f32 v50, v44, v45
	v_cvt_pk_bf16_f32 v51, v46, v47
	global_store_dwordx2 v[54:55], v[50:51], off
	v_mul_f32_e32 v45, v45, v45
	v_mul_f32_e32 v47, v47, v47
	v_fmac_f32_e32 v45, v44, v44
	v_fmac_f32_e32 v47, v46, v46
	v_add_f32_e32 v44, v45, v47
	s_waitcnt vmcnt(46)
	v_mov_b64_e32 v[50:51], v[186:187]
	v_mov_b64_e32 v[52:53], v[188:189]
	v_pk_add_f32 v[42:43], v[42:43], v[52:53]
	v_pk_add_f32 v[40:41], v[40:41], v[50:51]
	global_store_dwordx4 v[56:57], v[40:43], off offset:64
	v_cvt_pk_bf16_f32 v50, v40, v41
	v_cvt_pk_bf16_f32 v51, v42, v43
	global_store_dwordx2 v[54:55], v[50:51], off offset:32
	v_mul_f32_e32 v41, v41, v41
	v_mul_f32_e32 v43, v43, v43
	v_fmac_f32_e32 v41, v40, v40
	v_fmac_f32_e32 v43, v42, v42
	v_add_f32_e32 v40, v41, v43
	v_add_f32_e32 v40, v44, v40
	s_waitcnt vmcnt(45)
	v_mov_b64_e32 v[50:51], v[190:191]
	v_mov_b64_e32 v[52:53], v[192:193]
	v_pk_add_f32 v[38:39], v[38:39], v[52:53]
	v_pk_add_f32 v[36:37], v[36:37], v[50:51]
	global_store_dwordx4 v[56:57], v[36:39], off offset:512
	v_cvt_pk_bf16_f32 v50, v36, v37
	v_cvt_pk_bf16_f32 v51, v38, v39
	global_store_dwordx2 v[54:55], v[50:51], off offset:256
	v_mul_f32_e32 v37, v37, v37
	v_mul_f32_e32 v39, v39, v39
	v_fmac_f32_e32 v37, v36, v36
	v_fmac_f32_e32 v39, v38, v38
	v_add_f32_e32 v36, v37, v39
	v_add_f32_e32 v38, v40, v36
	s_waitcnt vmcnt(44)
	v_mov_b64_e32 v[50:51], v[194:195]
	v_mov_b64_e32 v[52:53], v[196:197]
	v_pk_add_f32 v[36:37], v[34:35], v[52:53]
	v_pk_add_f32 v[34:35], v[32:33], v[50:51]
	v_mul_f32_e32 v33, v37, v37
	v_mul_f32_e32 v32, v35, v35
	v_fmac_f32_e32 v32, v34, v34
	v_fmac_f32_e32 v33, v36, v36
	v_add_f32_e32 v32, v32, v33
	v_add_f32_e32 v32, v38, v32
	ds_bpermute_b32 v33, v116, v32
	global_store_dwordx4 v[56:57], v[34:37], off offset:576
	s_waitcnt lgkmcnt(0)
	v_add_f32_e32 v32, v32, v33
	ds_bpermute_b32 v33, v114, v32
	v_cvt_pk_bf16_f32 v34, v34, v35
	v_cvt_pk_bf16_f32 v35, v36, v37
	global_store_dwordx2 v[54:55], v[34:35], off offset:288
	s_and_saveexec_b64 s[42:43], s[10:11]
	s_cbranch_execz .LBB0_1934
	s_waitcnt lgkmcnt(0)
	v_add_f32_e32 v34, v32, v33
	v_lshlrev_b64 v[32:33], 6, v[48:49]
	v_lshl_add_u64 v[32:33], s[22:23], 0, v[32:33]
	v_lshl_add_u64 v[32:33], s[40:41], 2, v[32:33]
	s_lshl_b32 s30, s67, 2
	v_lshl_add_u64 v[32:33], v[32:33], 0, s[30:31]
	global_store_dword v[32:33], v34, off
; __device__ __forceinline__ unsigned pk2(float lo, float hi) { unsigned r; asm volatile("v_cvt_pk_bf16_f32 %0, %1, %2" : "=v"(r) : "v"(lo), "v"(hi)); return r; }
;     __device__ __forceinline__ void operator()(const f32x4 (&acc)[2][2][4][2], const Unit& u, int wr, int wc, int fr, int fq) const {
;     ...
;                 const int row = row0 + ai * 128 + m * 16; const size_t ro = (size_t)row * DM + col0;
;                 float s = 0.f;
; #pragma unroll
;                 for (int bj = 0; bj < 2; ++bj)
; #pragma unroll
;                     for (int n = 0; n < 2; ++n) {
;                         const size_t o = ro + bj * 128 + n * 16;
;                         const f32x4 xn = *(const f32x4*)(xo + o) + acc[ai][bj][m][n];
;                         *(f32x4*)(xf + o) = xn;
;                         u32x2 w; w.x = pk2(xn[0], xn[1]); w.y = pk2(xn[2], xn[3]); *(u32x2*)(xb + o) = w;
;                         s += (xn[0] * xn[0] + xn[1] * xn[1]) + (xn[2] * xn[2] + xn[3] * xn[3]);
;                     }
;                 s += __shfl_xor(s, 16); s += __shfl_xor(s, 32);
;                 if (fq == 0) ssq[(size_t)row * 16 + u.pn * 4 + wc] = s;
.LBB0_1934:
	s_or_b64 exec, exec, s[42:43]
	v_add_u32_e32 v32, 0xa0, v146
	s_waitcnt lgkmcnt(0)
	v_ashrrev_i32_e32 v33, 31, v32
	v_lshlrev_b64 v[34:35], 10, v[32:33]
	v_lshl_add_u64 v[38:39], v[34:35], 0, v[142:143]
	v_lshlrev_b64 v[40:41], 2, v[38:39]
	v_lshl_add_u64 v[42:43], s[14:15], 0, v[40:41]
	v_lshl_add_u64 v[38:39], v[38:39], 1, s[20:21]
	v_lshl_add_u64 v[40:41], s[24:25], 0, v[40:41]
	s_waitcnt vmcnt(43)
	v_mov_b64_e32 v[34:35], v[198:199]
	v_mov_b64_e32 v[36:37], v[200:201]
	v_pk_add_f32 v[30:31], v[30:31], v[36:37]
	v_pk_add_f32 v[28:29], v[28:29], v[34:35]
	global_store_dwordx4 v[40:41], v[28:31], off
	v_cvt_pk_bf16_f32 v34, v28, v29
	v_cvt_pk_bf16_f32 v35, v30, v31
	global_store_dwordx2 v[38:39], v[34:35], off
	v_mul_f32_e32 v29, v29, v29
	v_mul_f32_e32 v31, v31, v31
	v_fmac_f32_e32 v29, v28, v28
	v_fmac_f32_e32 v31, v30, v30
	v_add_f32_e32 v28, v29, v31
	s_waitcnt vmcnt(42)
	v_mov_b64_e32 v[34:35], v[202:203]
	v_mov_b64_e32 v[36:37], v[204:205]
	v_pk_add_f32 v[26:27], v[26:27], v[36:37]
	v_pk_add_f32 v[24:25], v[24:25], v[34:35]
	global_store_dwordx4 v[40:41], v[24:27], off offset:64
	v_cvt_pk_bf16_f32 v34, v24, v25
	v_cvt_pk_bf16_f32 v35, v26, v27
	global_store_dwordx2 v[38:39], v[34:35], off offset:32
	v_mul_f32_e32 v25, v25, v25
	v_mul_f32_e32 v27, v27, v27
	v_fmac_f32_e32 v25, v24, v24
	v_fmac_f32_e32 v27, v26, v26
	v_add_f32_e32 v24, v25, v27
	v_add_f32_e32 v24, v28, v24
	s_waitcnt vmcnt(41)
	v_mov_b64_e32 v[34:35], v[206:207]
	v_mov_b64_e32 v[36:37], v[208:209]
	v_pk_add_f32 v[22:23], v[22:23], v[36:37]
	v_pk_add_f32 v[20:21], v[20:21], v[34:35]
	global_store_dwordx4 v[40:41], v[20:23], off offset:512
	v_cvt_pk_bf16_f32 v34, v20, v21
	v_cvt_pk_bf16_f32 v35, v22, v23
	global_store_dwordx2 v[38:39], v[34:35], off offset:256
	v_mul_f32_e32 v21, v21, v21
	v_mul_f32_e32 v23, v23, v23
	v_fmac_f32_e32 v21, v20, v20
	v_fmac_f32_e32 v23, v22, v22
	v_add_f32_e32 v20, v21, v23
	v_add_f32_e32 v22, v24, v20
	s_waitcnt vmcnt(40)
	v_mov_b64_e32 v[34:35], v[210:211]
	v_mov_b64_e32 v[36:37], v[212:213]
	v_pk_add_f32 v[20:21], v[18:19], v[36:37]
	v_pk_add_f32 v[18:19], v[16:17], v[34:35]
	v_mul_f32_e32 v17, v21, v21
	v_mul_f32_e32 v16, v19, v19
	v_fmac_f32_e32 v16, v18, v18
	v_fmac_f32_e32 v17, v20, v20
	v_add_f32_e32 v16, v16, v17
	v_add_f32_e32 v16, v22, v16
	ds_bpermute_b32 v17, v116, v16
	global_store_dwordx4 v[40:41], v[18:21], off offset:576
	s_waitcnt lgkmcnt(0)
	v_add_f32_e32 v16, v16, v17
	ds_bpermute_b32 v17, v114, v16
	v_cvt_pk_bf16_f32 v18, v18, v19
	v_cvt_pk_bf16_f32 v19, v20, v21
	global_store_dwordx2 v[38:39], v[18:19], off offset:288
	s_and_saveexec_b64 s[42:43], s[10:11]
	s_cbranch_execz .LBB0_1936
	s_waitcnt lgkmcnt(0)
	v_add_f32_e32 v18, v16, v17
	v_lshlrev_b64 v[16:17], 6, v[32:33]
	v_lshl_add_u64 v[16:17], s[22:23], 0, v[16:17]
	v_lshl_add_u64 v[16:17], s[40:41], 2, v[16:17]
	s_lshl_b32 s30, s67, 2
	v_lshl_add_u64 v[16:17], v[16:17], 0, s[30:31]
	global_store_dword v[16:17], v18, off
.LBB0_1936:
	s_or_b64 exec, exec, s[42:43]
	v_add_u32_e32 v16, 0xb0, v146
	s_waitcnt lgkmcnt(0)
	v_ashrrev_i32_e32 v17, 31, v16
	v_lshlrev_b64 v[18:19], 10, v[16:17]
	v_lshl_add_u64 v[22:23], v[18:19], 0, v[142:143]
	v_lshlrev_b64 v[24:25], 2, v[22:23]
	v_lshl_add_u64 v[26:27], s[14:15], 0, v[24:25]
	v_lshl_add_u64 v[22:23], v[22:23], 1, s[20:21]
	v_lshl_add_u64 v[24:25], s[24:25], 0, v[24:25]
	s_waitcnt vmcnt(39)
	v_mov_b64_e32 v[18:19], v[214:215]
	v_mov_b64_e32 v[20:21], v[216:217]
	v_pk_add_f32 v[14:15], v[14:15], v[20:21]
	v_pk_add_f32 v[12:13], v[12:13], v[18:19]
	global_store_dwordx4 v[24:25], v[12:15], off
	v_cvt_pk_bf16_f32 v18, v12, v13
	v_cvt_pk_bf16_f32 v19, v14, v15
	global_store_dwordx2 v[22:23], v[18:19], off
	v_mul_f32_e32 v13, v13, v13
	v_mul_f32_e32 v15, v15, v15
	v_fmac_f32_e32 v13, v12, v12
	v_fmac_f32_e32 v15, v14, v14
	v_add_f32_e32 v12, v13, v15
	s_waitcnt vmcnt(38)
	v_mov_b64_e32 v[18:19], v[218:219]
	v_mov_b64_e32 v[20:21], v[220:221]
	v_pk_add_f32 v[10:11], v[10:11], v[20:21]
	v_pk_add_f32 v[8:9], v[8:9], v[18:19]
	global_store_dwordx4 v[24:25], v[8:11], off offset:64
	v_cvt_pk_bf16_f32 v18, v8, v9
	v_cvt_pk_bf16_f32 v19, v10, v11
	global_store_dwordx2 v[22:23], v[18:19], off offset:32
	v_mul_f32_e32 v9, v9, v9
	v_mul_f32_e32 v11, v11, v11
	v_fmac_f32_e32 v9, v8, v8
	v_fmac_f32_e32 v11, v10, v10
	v_add_f32_e32 v8, v9, v11
	v_add_f32_e32 v8, v12, v8
	s_waitcnt vmcnt(37)
	v_mov_b64_e32 v[18:19], v[232:233]
	v_mov_b64_e32 v[20:21], v[234:235]
	v_pk_add_f32 v[6:7], v[6:7], v[20:21]
	v_pk_add_f32 v[4:5], v[4:5], v[18:19]
	global_store_dwordx4 v[24:25], v[4:7], off offset:512
	v_cvt_pk_bf16_f32 v18, v4, v5
	v_cvt_pk_bf16_f32 v19, v6, v7
	global_store_dwordx2 v[22:23], v[18:19], off offset:256
	v_mul_f32_e32 v5, v5, v5
	v_mul_f32_e32 v7, v7, v7
	v_fmac_f32_e32 v5, v4, v4
	v_fmac_f32_e32 v7, v6, v6
	v_add_f32_e32 v4, v5, v7
	v_add_f32_e32 v6, v8, v4
	s_waitcnt vmcnt(36)
	v_mov_b64_e32 v[18:19], v[236:237]
	v_mov_b64_e32 v[20:21], v[238:239]
	v_pk_add_f32 v[4:5], v[2:3], v[20:21]
	v_pk_add_f32 v[2:3], v[0:1], v[18:19]
	v_mul_f32_e32 v1, v5, v5
	v_mul_f32_e32 v0, v3, v3
	v_fmac_f32_e32 v0, v2, v2
	v_fmac_f32_e32 v1, v4, v4
	v_add_f32_e32 v0, v0, v1
	v_add_f32_e32 v0, v6, v0
	ds_bpermute_b32 v1, v116, v0
	global_store_dwordx4 v[24:25], v[2:5], off offset:576
	s_waitcnt lgkmcnt(0)
	v_add_f32_e32 v0, v0, v1
	ds_bpermute_b32 v1, v114, v0
	v_cvt_pk_bf16_f32 v2, v2, v3
	v_cvt_pk_bf16_f32 v3, v4, v5
	global_store_dwordx2 v[22:23], v[2:3], off offset:288
	s_and_saveexec_b64 s[14:15], s[10:11]
	s_cbranch_execz .LBB0_1895
	s_waitcnt lgkmcnt(0)
	v_add_f32_e32 v2, v0, v1
	v_lshlrev_b64 v[0:1], 6, v[16:17]
	v_lshl_add_u64 v[0:1], s[22:23], 0, v[0:1]
	v_lshl_add_u64 v[0:1], s[40:41], 2, v[0:1]
	s_lshl_b32 s30, s67, 2
	v_lshl_add_u64 v[0:1], v[0:1], 0, s[30:31]
	global_store_dword v[0:1], v2, off
	s_branch .LBB0_1895

; __device__ __forceinline__ unsigned pk2(float lo, float hi) { unsigned r; asm volatile("v_cvt_pk_bf16_f32 %0, %1, %2" : "=v"(r) : "v"(lo), "v"(hi)); return r; }
;     ...
;         const int lane = threadIdx.x & 63, wv = threadIdx.x >> 6;
;         const int rbase = u.pm * 256 + (kq * 4 + u.pn) * 16 + wv * 2;
; #pragma unroll
;         for (int rr = 0; rr < 2; ++rr) {
;             const int row = rbase + rr; float sq = 0.f;
; #pragma unroll
;             for (int i = 0; i < 4; ++i) {
;                 const size_t o = (size_t)row * DM + i * 256 + lane * 4;
;                 f32x4 v = *(const f32x4*)(xold + o);
; #pragma unroll
;                 for (int q = 0; q < 4; ++q) v += *(const f32x4*)(part + (size_t)q * 1024 * DM + o);
;                 *(f32x4*)(xf_s + o) = v;
;                 u32x2 w; w.x = pk2(v[0], v[1]); w.y = pk2(v[2], v[3]); *(u32x2*)(xb_s + o) = w;
;                 sq += (v[0] * v[0] + v[1] * v[1]) + (v[2] * v[2] + v[3] * v[3]);
;             }
; #pragma unroll
;             for (int o = 32; o >= 1; o >>= 1) sq += __shfl_xor(sq, o);
;             if (lane < 16) ssq_s[(size_t)row * 16 + lane] = lane == 0 ? sq : 0.f;
;         }
.LBB0_2020:
	s_or_b64 exec, exec, s[8:9]
	s_add_u32 s18, s24, 0x4000000
	s_addc_u32 s19, s25, 0
	s_add_u32 s16, s16, 0x2000000
	s_addc_u32 s17, s17, 0
	s_lshr_b32 s8, s71, 2
	v_lshrrev_b32_e32 v0, 5, v166
	s_and_b32 s8, s8, 0xffffffc
	v_and_b32_e32 v0, 30, v0
	s_add_i32 s6, s6, s8
	v_lshl_or_b32 v0, s7, 8, v0
	v_lshl_add_u32 v2, s6, 4, v0
	v_ashrrev_i32_e32 v3, 31, v2
	v_lshlrev_b32_e32 v0, 2, v167
	v_lshlrev_b64 v[4:5], 10, v[2:3]
	v_or_b32_e32 v4, v4, v0
	v_lshlrev_b64 v[10:11], 2, v[4:5]
	v_lshl_add_u64 v[38:39], s[12:13], 0, v[10:11]
	s_mov_b32 s6, 0x400000
	v_add_co_u32_e32 v40, vcc, s6, v38
	s_mov_b32 s7, 0x800000
	s_nop 0
	v_addc_co_u32_e32 v41, vcc, 0, v39, vcc
	v_lshl_add_u64 v[26:27], s[18:19], 0, v[10:11]
	v_add_co_u32_e32 v42, vcc, s7, v38
	s_barrier
	global_load_dwordx4 v[6:9], v[26:27], off
	v_addc_co_u32_e32 v43, vcc, 0, v39, vcc
	s_mov_b32 s22, 0xc00000
	global_load_dwordx4 v[10:13], v[38:39], off
	global_load_dwordx4 v[14:17], v[40:41], off
	v_add_co_u32_e32 v44, vcc, s22, v38
	global_load_dwordx4 v[18:21], v[42:43], off
	s_nop 0
	v_addc_co_u32_e32 v45, vcc, 0, v39, vcc
	global_load_dwordx4 v[22:25], v[44:45], off
	v_mov_b32_e32 v31, v5
	v_lshl_add_u64 v[28:29], v[4:5], 1, s[16:17]
	v_or_b32_e32 v30, 0x100, v4
	v_lshl_add_u64 v[32:33], v[30:31], 2, s[18:19]
	v_mov_b32_e32 v35, v5
	v_or_b32_e32 v34, 0x200, v4
	v_lshl_add_u64 v[30:31], v[30:31], 1, s[16:17]
	v_lshl_add_u64 v[36:37], v[34:35], 2, s[18:19]
	v_or_b32_e32 v4, 0x300, v4
	v_lshl_add_u64 v[34:35], v[34:35], 1, s[16:17]
	v_lshl_add_u64 v[46:47], v[4:5], 2, s[18:19]
	v_mov_b32_e32 v1, 0
	s_mov_b64 s[20:21], 0x100000
	v_cmp_gt_u32_e64 s[8:9], 16, v167
	v_cmp_eq_u32_e32 vcc, 0, v167
	v_lshl_add_u64 v[4:5], v[4:5], 1, s[16:17]
	global_load_dwordx4 v[186:189], v[32:33], off
	global_load_dwordx4 v[190:193], v[38:39], off offset:1024
	global_load_dwordx4 v[194:197], v[40:41], off offset:1024
	global_load_dwordx4 v[198:201], v[42:43], off offset:1024
	global_load_dwordx4 v[202:205], v[44:45], off offset:1024
	global_load_dwordx4 v[206:209], v[36:37], off
	global_load_dwordx4 v[210:213], v[38:39], off offset:2048
	global_load_dwordx4 v[214:217], v[40:41], off offset:2048
	global_load_dwordx4 v[218:221], v[42:43], off offset:2048
	global_load_dwordx4 v[222:225], v[44:45], off offset:2048
	global_load_dwordx4 v[226:229], v[46:47], off
	global_load_dwordx4 v[232:235], v[38:39], off offset:3072
	global_load_dwordx4 v[236:239], v[40:41], off offset:3072
	global_load_dwordx4 v[240:243], v[42:43], off offset:3072
	global_load_dwordx4 v[244:247], v[44:45], off offset:3072
	s_waitcnt vmcnt(18)
	v_pk_add_f32 v[8:9], v[8:9], v[12:13]
	v_pk_add_f32 v[6:7], v[6:7], v[10:11]
	s_waitcnt vmcnt(17)
	v_pk_add_f32 v[8:9], v[8:9], v[16:17]
	v_pk_add_f32 v[6:7], v[6:7], v[14:15]
	s_waitcnt vmcnt(16)
	v_pk_add_f32 v[8:9], v[8:9], v[20:21]
	v_pk_add_f32 v[6:7], v[6:7], v[18:19]
	s_waitcnt vmcnt(15)
	v_pk_add_f32 v[8:9], v[8:9], v[24:25]
	v_pk_add_f32 v[6:7], v[6:7], v[22:23]
	global_store_dwordx4 v[26:27], v[6:9], off
	v_cvt_pk_bf16_f32 v10, v6, v7
	v_cvt_pk_bf16_f32 v11, v8, v9
	global_store_dwordx2 v[28:29], v[10:11], off
	s_nop 0
	v_mul_f32_e32 v7, v7, v7
	v_mul_f32_e32 v9, v9, v9
	v_fmac_f32_e32 v7, v6, v6
	v_fmac_f32_e32 v9, v8, v8
	v_add_f32_e32 v6, v7, v9
	s_waitcnt vmcnt(12)
	v_mov_b64_e32 v[10:11], v[186:187]
	v_mov_b64_e32 v[12:13], v[188:189]
	v_mov_b64_e32 v[14:15], v[190:191]
	v_mov_b64_e32 v[16:17], v[192:193]
	v_mov_b64_e32 v[18:19], v[194:195]
	v_mov_b64_e32 v[20:21], v[196:197]
	v_mov_b64_e32 v[22:23], v[198:199]
	v_mov_b64_e32 v[24:25], v[200:201]
	v_mov_b64_e32 v[26:27], v[202:203]
	v_mov_b64_e32 v[28:29], v[204:205]
	v_pk_add_f32 v[12:13], v[12:13], v[16:17]
	v_pk_add_f32 v[10:11], v[10:11], v[14:15]
	v_pk_add_f32 v[12:13], v[12:13], v[20:21]
	v_pk_add_f32 v[10:11], v[10:11], v[18:19]
	v_pk_add_f32 v[12:13], v[12:13], v[24:25]
	v_pk_add_f32 v[10:11], v[10:11], v[22:23]
	v_pk_add_f32 v[12:13], v[12:13], v[28:29]
	v_pk_add_f32 v[10:11], v[10:11], v[26:27]
	global_store_dwordx4 v[32:33], v[10:13], off
	v_cvt_pk_bf16_f32 v14, v10, v11
	v_cvt_pk_bf16_f32 v15, v12, v13
	global_store_dwordx2 v[30:31], v[14:15], off
	s_nop 0
	v_mul_f32_e32 v7, v11, v11
	v_mul_f32_e32 v8, v13, v13
	v_fmac_f32_e32 v7, v10, v10
	v_fmac_f32_e32 v8, v12, v12
	v_add_f32_e32 v7, v7, v8
	v_add_f32_e32 v6, v6, v7
	s_waitcnt vmcnt(9)
	v_mov_b64_e32 v[14:15], v[206:207]
	v_mov_b64_e32 v[16:17], v[208:209]
	v_mov_b64_e32 v[18:19], v[210:211]
	v_mov_b64_e32 v[20:21], v[212:213]
	v_mov_b64_e32 v[22:23], v[214:215]
	v_mov_b64_e32 v[24:25], v[216:217]
	v_mov_b64_e32 v[26:27], v[218:219]
	v_mov_b64_e32 v[28:29], v[220:221]
	v_mov_b64_e32 v[30:31], v[222:223]
	v_mov_b64_e32 v[32:33], v[224:225]
	v_pk_add_f32 v[16:17], v[16:17], v[20:21]
	v_pk_add_f32 v[14:15], v[14:15], v[18:19]
	v_pk_add_f32 v[16:17], v[16:17], v[24:25]
	v_pk_add_f32 v[14:15], v[14:15], v[22:23]
	v_pk_add_f32 v[16:17], v[16:17], v[28:29]
	v_pk_add_f32 v[14:15], v[14:15], v[26:27]
	v_pk_add_f32 v[16:17], v[16:17], v[32:33]
	v_pk_add_f32 v[14:15], v[14:15], v[30:31]
	global_store_dwordx4 v[36:37], v[14:17], off
	v_cvt_pk_bf16_f32 v18, v14, v15
	v_cvt_pk_bf16_f32 v19, v16, v17
	global_store_dwordx2 v[34:35], v[18:19], off
	s_nop 0
	v_mul_f32_e32 v7, v15, v15
	v_mul_f32_e32 v8, v17, v17
	v_fmac_f32_e32 v7, v14, v14
	v_fmac_f32_e32 v8, v16, v16
	v_add_f32_e32 v7, v7, v8
	v_add_f32_e32 v10, v6, v7
	v_mbcnt_hi_u32_b32 v40, -1, v168
	v_lshl_add_u64 v[38:39], s[14:15], 0, v[0:1]
	v_and_b32_e32 v1, 64, v40
	v_xor_b32_e32 v41, 32, v40
	v_add_u32_e32 v43, 64, v1
	v_cmp_lt_i32_e64 s[10:11], v41, v43
	v_xor_b32_e32 v42, 16, v40
	v_xor_b32_e32 v11, 2, v40
	v_cndmask_b32_e64 v1, v40, v41, s[10:11]
	v_lshlrev_b32_e32 v1, 2, v1
	v_cmp_lt_i32_e64 s[10:11], v42, v43
	v_xor_b32_e32 v12, 1, v40
	s_waitcnt vmcnt(6)
; __device__ __forceinline__ unsigned pk2(float lo, float hi) { unsigned r; asm volatile("v_cvt_pk_bf16_f32 %0, %1, %2" : "=v"(r) : "v"(lo), "v"(hi)); return r; }
;     ...
; #pragma unroll
;                 for (int q = 0; q < 4; ++q) v += *(const f32x4*)(part + (size_t)q * 1024 * DM + o);
;                 *(f32x4*)(xf_s + o) = v;
;                 u32x2 w; w.x = pk2(v[0], v[1]); w.y = pk2(v[2], v[3]); *(u32x2*)(xb_s + o) = w;
;                 sq += (v[0] * v[0] + v[1] * v[1]) + (v[2] * v[2] + v[3] * v[3]);
;             }
; #pragma unroll
;             for (int o = 32; o >= 1; o >>= 1) sq += __shfl_xor(sq, o);
;             if (lane < 16) ssq_s[(size_t)row * 16 + lane] = lane == 0 ? sq : 0.f;
	v_mov_b64_e32 v[18:19], v[226:227]
	v_mov_b64_e32 v[20:21], v[228:229]
	v_mov_b64_e32 v[22:23], v[232:233]
	v_mov_b64_e32 v[24:25], v[234:235]
	v_mov_b64_e32 v[26:27], v[236:237]
	v_mov_b64_e32 v[28:29], v[238:239]
	v_mov_b64_e32 v[30:31], v[240:241]
	v_mov_b64_e32 v[32:33], v[242:243]
	v_mov_b64_e32 v[34:35], v[244:245]
	v_mov_b64_e32 v[36:37], v[246:247]
	v_pk_add_f32 v[6:7], v[20:21], v[24:25]
	v_pk_add_f32 v[8:9], v[18:19], v[22:23]
	v_pk_add_f32 v[6:7], v[6:7], v[28:29]
	v_pk_add_f32 v[8:9], v[8:9], v[26:27]
	v_pk_add_f32 v[6:7], v[6:7], v[32:33]
	v_pk_add_f32 v[8:9], v[8:9], v[30:31]
	v_pk_add_f32 v[18:19], v[6:7], v[36:37]
	v_pk_add_f32 v[16:17], v[8:9], v[34:35]
	v_mul_f32_e32 v7, v19, v19
	v_mul_f32_e32 v6, v17, v17
	v_fmac_f32_e32 v6, v16, v16
	v_fmac_f32_e32 v7, v18, v18
	v_add_f32_e32 v6, v6, v7
	v_add_f32_e32 v6, v10, v6
	ds_bpermute_b32 v7, v1, v6
	v_cndmask_b32_e64 v8, v40, v42, s[10:11]
	v_lshlrev_b32_e32 v8, 2, v8
	v_xor_b32_e32 v9, 8, v40
	v_cmp_lt_i32_e64 s[10:11], v9, v43
	s_waitcnt lgkmcnt(0)
	v_add_f32_e32 v6, v6, v7
	ds_bpermute_b32 v7, v8, v6
	v_cndmask_b32_e64 v9, v40, v9, s[10:11]
	v_lshlrev_b32_e32 v9, 2, v9
	v_xor_b32_e32 v10, 4, v40
	v_cmp_lt_i32_e64 s[10:11], v10, v43
	s_waitcnt lgkmcnt(0)
	v_add_f32_e32 v6, v6, v7
	ds_bpermute_b32 v7, v9, v6
	v_cndmask_b32_e64 v10, v40, v10, s[10:11]
	v_lshlrev_b32_e32 v10, 2, v10
	v_cmp_lt_i32_e64 s[10:11], v11, v43
	global_store_dwordx4 v[46:47], v[16:19], off
	s_waitcnt lgkmcnt(0)
	v_add_f32_e32 v6, v6, v7
	ds_bpermute_b32 v7, v10, v6
	v_cndmask_b32_e64 v11, v40, v11, s[10:11]
	v_lshlrev_b32_e32 v11, 2, v11
	v_cmp_lt_i32_e64 s[10:11], v12, v43
	v_cvt_pk_bf16_f32 v16, v16, v17
	s_waitcnt lgkmcnt(0)
	v_add_f32_e32 v13, v6, v7
	ds_bpermute_b32 v14, v11, v13
	v_cndmask_b32_e64 v12, v40, v12, s[10:11]
	v_lshlrev_b32_e32 v12, 2, v12
	v_lshl_add_u64 v[6:7], v[38:39], 0, s[20:21]
	v_cvt_pk_bf16_f32 v17, v18, v19
	s_waitcnt lgkmcnt(0)
	v_add_f32_e32 v13, v13, v14
	ds_bpermute_b32 v14, v12, v13
	global_store_dwordx2 v[4:5], v[16:17], off
	s_and_saveexec_b64 s[10:11], s[8:9]
	s_cbranch_execz .LBB0_2022
	v_lshlrev_b64 v[4:5], 6, v[2:3]
	s_waitcnt lgkmcnt(0)
	v_add_f32_e32 v3, v13, v14
	v_lshl_add_u64 v[4:5], v[6:7], 0, v[4:5]
	v_cndmask_b32_e32 v3, 0, v3, vcc
	global_store_dword v[4:5], v3, off
; __device__ __forceinline__ unsigned pk2(float lo, float hi) { unsigned r; asm volatile("v_cvt_pk_bf16_f32 %0, %1, %2" : "=v"(r) : "v"(lo), "v"(hi)); return r; }
;     ...
;         for (int rr = 0; rr < 2; ++rr) {
;             const int row = rbase + rr; float sq = 0.f;
; #pragma unroll
;             for (int i = 0; i < 4; ++i) {
;                 const size_t o = (size_t)row * DM + i * 256 + lane * 4;
;                 f32x4 v = *(const f32x4*)(xold + o);
; #pragma unroll
;                 for (int q = 0; q < 4; ++q) v += *(const f32x4*)(part + (size_t)q * 1024 * DM + o);
;                 *(f32x4*)(xf_s + o) = v;
;                 u32x2 w; w.x = pk2(v[0], v[1]); w.y = pk2(v[2], v[3]); *(u32x2*)(xb_s + o) = w;
;                 sq += (v[0] * v[0] + v[1] * v[1]) + (v[2] * v[2] + v[3] * v[3]);
;             }
; #pragma unroll
;             for (int o = 32; o >= 1; o >>= 1) sq += __shfl_xor(sq, o);
;             if (lane < 16) ssq_s[(size_t)row * 16 + lane] = lane == 0 ? sq : 0.f;
;         }
.LBB0_2022:
	s_or_b64 exec, exec, s[10:11]
	v_or_b32_e32 v2, 1, v2
	v_ashrrev_i32_e32 v3, 31, v2
	v_lshlrev_b64 v[4:5], 10, v[2:3]
	v_or_b32_e32 v4, v4, v0
	v_lshlrev_b64 v[18:19], 2, v[4:5]
	v_lshl_add_u64 v[46:47], s[12:13], 0, v[18:19]
	v_add_co_u32_e64 v48, s[10:11], s6, v46
	v_lshl_add_u64 v[34:35], s[18:19], 0, v[18:19]
	s_nop 0
	v_addc_co_u32_e64 v49, s[10:11], 0, v47, s[10:11]
	v_add_co_u32_e64 v50, s[10:11], s7, v46
	s_waitcnt lgkmcnt(0)
	global_load_dwordx4 v[14:17], v[34:35], off
	v_addc_co_u32_e64 v51, s[10:11], 0, v47, s[10:11]
	global_load_dwordx4 v[18:21], v[46:47], off
	global_load_dwordx4 v[22:25], v[48:49], off
	v_add_co_u32_e64 v52, s[10:11], s22, v46
	global_load_dwordx4 v[26:29], v[50:51], off
	s_nop 0
	v_addc_co_u32_e64 v53, s[10:11], 0, v47, s[10:11]
	global_load_dwordx4 v[30:33], v[52:53], off
	v_mov_b32_e32 v39, v5
	v_lshl_add_u64 v[36:37], v[4:5], 1, s[16:17]
	v_or_b32_e32 v38, 0x100, v4
	v_lshl_add_u64 v[40:41], v[38:39], 2, s[18:19]
	v_mov_b32_e32 v43, v5
	v_or_b32_e32 v42, 0x200, v4
	v_lshl_add_u64 v[38:39], v[38:39], 1, s[16:17]
	v_lshl_add_u64 v[44:45], v[42:43], 2, s[18:19]
	v_or_b32_e32 v4, 0x300, v4
	v_lshl_add_u64 v[42:43], v[42:43], 1, s[16:17]
	v_lshl_add_u64 v[54:55], v[4:5], 2, s[18:19]
	v_lshl_add_u64 v[4:5], v[4:5], 1, s[16:17]
	global_load_dwordx4 v[186:189], v[40:41], off
	global_load_dwordx4 v[190:193], v[46:47], off offset:1024
	global_load_dwordx4 v[194:197], v[48:49], off offset:1024
	global_load_dwordx4 v[198:201], v[50:51], off offset:1024
	global_load_dwordx4 v[202:205], v[52:53], off offset:1024
	global_load_dwordx4 v[206:209], v[44:45], off
	global_load_dwordx4 v[210:213], v[46:47], off offset:2048
	global_load_dwordx4 v[214:217], v[48:49], off offset:2048
	global_load_dwordx4 v[218:221], v[50:51], off offset:2048
	global_load_dwordx4 v[222:225], v[52:53], off offset:2048
	global_load_dwordx4 v[226:229], v[54:55], off
	global_load_dwordx4 v[232:235], v[46:47], off offset:3072
	global_load_dwordx4 v[236:239], v[48:49], off offset:3072
	global_load_dwordx4 v[240:243], v[50:51], off offset:3072
	global_load_dwordx4 v[244:247], v[52:53], off offset:3072
	s_waitcnt vmcnt(18)
	v_pk_add_f32 v[16:17], v[16:17], v[20:21]
	v_pk_add_f32 v[14:15], v[14:15], v[18:19]
	s_waitcnt vmcnt(17)
	v_pk_add_f32 v[16:17], v[16:17], v[24:25]
	v_pk_add_f32 v[14:15], v[14:15], v[22:23]
	s_waitcnt vmcnt(16)
	v_pk_add_f32 v[16:17], v[16:17], v[28:29]
	v_pk_add_f32 v[14:15], v[14:15], v[26:27]
	s_waitcnt vmcnt(15)
	v_pk_add_f32 v[16:17], v[16:17], v[32:33]
	v_pk_add_f32 v[14:15], v[14:15], v[30:31]
	global_store_dwordx4 v[34:35], v[14:17], off
	v_cvt_pk_bf16_f32 v18, v14, v15
	v_cvt_pk_bf16_f32 v19, v16, v17
	global_store_dwordx2 v[36:37], v[18:19], off
	s_nop 0
	v_mul_f32_e32 v0, v15, v15
	v_mul_f32_e32 v13, v17, v17
	v_fmac_f32_e32 v0, v14, v14
	v_fmac_f32_e32 v13, v16, v16
	v_add_f32_e32 v0, v0, v13
	s_waitcnt vmcnt(12)
	v_mov_b64_e32 v[18:19], v[186:187]
	v_mov_b64_e32 v[20:21], v[188:189]
	v_mov_b64_e32 v[22:23], v[190:191]
	v_mov_b64_e32 v[24:25], v[192:193]
	v_mov_b64_e32 v[26:27], v[194:195]
	v_mov_b64_e32 v[28:29], v[196:197]
	v_mov_b64_e32 v[30:31], v[198:199]
	v_mov_b64_e32 v[32:33], v[200:201]
	v_mov_b64_e32 v[34:35], v[202:203]
	v_mov_b64_e32 v[36:37], v[204:205]
	v_pk_add_f32 v[20:21], v[20:21], v[24:25]
	v_pk_add_f32 v[18:19], v[18:19], v[22:23]
	v_pk_add_f32 v[20:21], v[20:21], v[28:29]
	v_pk_add_f32 v[18:19], v[18:19], v[26:27]
	v_pk_add_f32 v[20:21], v[20:21], v[32:33]
	v_pk_add_f32 v[18:19], v[18:19], v[30:31]
	v_pk_add_f32 v[20:21], v[20:21], v[36:37]
	v_pk_add_f32 v[18:19], v[18:19], v[34:35]
	global_store_dwordx4 v[40:41], v[18:21], off
	v_cvt_pk_bf16_f32 v22, v18, v19
	v_cvt_pk_bf16_f32 v23, v20, v21
	global_store_dwordx2 v[38:39], v[22:23], off
	s_nop 0
	v_mul_f32_e32 v13, v19, v19
	v_mul_f32_e32 v14, v21, v21
	v_fmac_f32_e32 v13, v18, v18
	v_fmac_f32_e32 v14, v20, v20
	v_add_f32_e32 v13, v13, v14
	v_add_f32_e32 v0, v0, v13
	s_waitcnt vmcnt(9)
	v_mov_b64_e32 v[22:23], v[206:207]
	v_mov_b64_e32 v[24:25], v[208:209]
	v_mov_b64_e32 v[26:27], v[210:211]
	v_mov_b64_e32 v[28:29], v[212:213]
	v_mov_b64_e32 v[30:31], v[214:215]
	v_mov_b64_e32 v[32:33], v[216:217]
	v_mov_b64_e32 v[34:35], v[218:219]
	v_mov_b64_e32 v[36:37], v[220:221]
	v_mov_b64_e32 v[38:39], v[222:223]
	v_mov_b64_e32 v[40:41], v[224:225]
	v_pk_add_f32 v[24:25], v[24:25], v[28:29]
	v_pk_add_f32 v[22:23], v[22:23], v[26:27]
	v_pk_add_f32 v[24:25], v[24:25], v[32:33]
	v_pk_add_f32 v[22:23], v[22:23], v[30:31]
	v_pk_add_f32 v[24:25], v[24:25], v[36:37]
	v_pk_add_f32 v[22:23], v[22:23], v[34:35]
	v_pk_add_f32 v[24:25], v[24:25], v[40:41]
	v_pk_add_f32 v[22:23], v[22:23], v[38:39]
	global_store_dwordx4 v[44:45], v[22:25], off
	v_cvt_pk_bf16_f32 v26, v22, v23
	v_cvt_pk_bf16_f32 v27, v24, v25
	global_store_dwordx2 v[42:43], v[26:27], off
	s_nop 0
	v_mul_f32_e32 v13, v23, v23
	v_mul_f32_e32 v14, v25, v25
	v_fmac_f32_e32 v13, v22, v22
	v_fmac_f32_e32 v14, v24, v24
	v_add_f32_e32 v13, v13, v14
	v_add_f32_e32 v0, v0, v13
	s_waitcnt vmcnt(6)
	v_mov_b64_e32 v[26:27], v[226:227]
	v_mov_b64_e32 v[28:29], v[228:229]
	v_mov_b64_e32 v[30:31], v[232:233]
	v_mov_b64_e32 v[32:33], v[234:235]
	v_mov_b64_e32 v[34:35], v[236:237]
	v_mov_b64_e32 v[36:37], v[238:239]
	v_mov_b64_e32 v[38:39], v[240:241]
	v_mov_b64_e32 v[40:41], v[242:243]
	v_mov_b64_e32 v[42:43], v[244:245]
	v_mov_b64_e32 v[44:45], v[246:247]
	v_pk_add_f32 v[14:15], v[28:29], v[32:33]
	v_pk_add_f32 v[16:17], v[26:27], v[30:31]
	v_pk_add_f32 v[14:15], v[14:15], v[36:37]
	v_pk_add_f32 v[16:17], v[16:17], v[34:35]
	v_pk_add_f32 v[14:15], v[14:15], v[40:41]
	v_pk_add_f32 v[18:19], v[16:17], v[38:39]
	v_pk_add_f32 v[16:17], v[14:15], v[44:45]
	v_pk_add_f32 v[14:15], v[18:19], v[42:43]
	v_mul_f32_e32 v18, v17, v17
	v_mul_f32_e32 v13, v15, v15
	v_fmac_f32_e32 v13, v14, v14
	v_fmac_f32_e32 v18, v16, v16
	v_add_f32_e32 v13, v13, v18
	v_add_f32_e32 v0, v0, v13
	ds_bpermute_b32 v1, v1, v0
	global_store_dwordx4 v[54:55], v[14:17], off
	s_waitcnt lgkmcnt(0)
	v_add_f32_e32 v0, v0, v1
	ds_bpermute_b32 v1, v8, v0
	v_cvt_pk_bf16_f32 v8, v14, v15
	s_waitcnt lgkmcnt(0)
	v_add_f32_e32 v0, v0, v1
	ds_bpermute_b32 v1, v9, v0
	v_cvt_pk_bf16_f32 v9, v16, v17
	global_store_dwordx2 v[4:5], v[8:9], off
	s_waitcnt lgkmcnt(0)
	v_add_f32_e32 v0, v0, v1
	ds_bpermute_b32 v1, v10, v0
	s_waitcnt lgkmcnt(0)
	v_add_f32_e32 v0, v0, v1
	ds_bpermute_b32 v1, v11, v0
	s_waitcnt lgkmcnt(0)
	v_add_f32_e32 v0, v0, v1
	ds_bpermute_b32 v1, v12, v0
	s_and_saveexec_b64 s[10:11], s[8:9]
	s_cbranch_execz .LBB0_2024
	v_lshlrev_b64 v[2:3], 6, v[2:3]
	s_waitcnt lgkmcnt(0)
	v_add_f32_e32 v0, v0, v1
	v_lshl_add_u64 v[2:3], v[6:7], 0, v[2:3]
	v_cndmask_b32_e32 v0, 0, v0, vcc
	global_store_dword v[2:3], v0, off

; __device__ __forceinline__ unsigned pk2(float lo, float hi) { unsigned r; asm volatile("v_cvt_pk_bf16_f32 %0, %1, %2" : "=v"(r) : "v"(lo), "v"(hi)); return r; }
;     __device__ __forceinline__ void operator()(const f32x4 (&acc)[2][2][4][2], const Unit& u, int wr, int wc, int fr, int fq) const {
;         const int row0 = u.pm * 256 + wr * 64 + fr, col0 = u.pn * 256 + wc * 32 + 4 * fq;
;         const float* xo = (u.pm < 64) ? xoldA : (xoldB - (size_t)T_P * DM);
; #pragma unroll
;         for (int ai = 0; ai < 2; ++ai)
; #pragma unroll
;             for (int m = 0; m < 4; ++m) {
;                 const int row = row0 + ai * 128 + m * 16; const size_t ro = (size_t)row * DM + col0;
;                 float s = 0.f;
; #pragma unroll
;                 for (int bj = 0; bj < 2; ++bj)
; #pragma unroll
;                     for (int n = 0; n < 2; ++n) {
;                         const size_t o = ro + bj * 128 + n * 16;
;                         const f32x4 xn = *(const f32x4*)(xo + o) + acc[ai][bj][m][n];
;                         *(f32x4*)(xf + o) = xn;
;                         u32x2 w; w.x = pk2(xn[0], xn[1]); w.y = pk2(xn[2], xn[3]); *(u32x2*)(xb + o) = w;
;                         s += (xn[0] * xn[0] + xn[1] * xn[1]) + (xn[2] * xn[2] + xn[3] * xn[3]);
;                     }
;                 s += __shfl_xor(s, 16); s += __shfl_xor(s, 32);
;                 if (fq == 0) ssq[(size_t)row * 16 + u.pn * 4 + wc] = s;
.LBB0_2178:
	v_lshl_add_u32 v138, s42, 8, v140
	v_lshl_or_b32 v136, s40, 8, v142
	v_ashrrev_i32_e32 v139, 31, v138
	v_ashrrev_i32_e32 v137, 31, v136
	v_lshlrev_b64 v[148:149], 10, v[138:139]
	s_cmp_lt_i32 s42, 64
	v_lshl_add_u64 v[152:153], v[148:149], 0, v[136:137]
	s_cselect_b32 s13, s17, -1
	s_cselect_b32 s12, s16, 0xfc000000
	v_lshlrev_b64 v[154:155], 2, v[152:153]
	v_lshl_add_u64 v[156:157], s[12:13], 0, v[154:155]
	v_subrev_u32_e32 v162, s12, v156
	v_add_u32_e32 v163, 0x0, v162
	global_load_dwordx4 v[170:173], v163, s[12:13]
	v_add_u32_e32 v163, 0x40, v162
	global_load_dwordx4 v[174:177], v163, s[12:13]
	v_add_u32_e32 v163, 0x200, v162
	global_load_dwordx4 v[178:181], v163, s[12:13]
	v_add_u32_e32 v163, 0x240, v162
	global_load_dwordx4 v[182:185], v163, s[12:13]
	v_add_u32_e32 v163, 0x10000, v162
	global_load_dwordx4 v[186:189], v163, s[12:13]
	v_add_u32_e32 v163, 0x10040, v162
	global_load_dwordx4 v[190:193], v163, s[12:13]
	v_add_u32_e32 v163, 0x10200, v162
	global_load_dwordx4 v[194:197], v163, s[12:13]
	v_add_u32_e32 v163, 0x10240, v162
	global_load_dwordx4 v[198:201], v163, s[12:13]
	v_add_u32_e32 v163, 0x20000, v162
	global_load_dwordx4 v[202:205], v163, s[12:13]
	v_add_u32_e32 v163, 0x20040, v162
	global_load_dwordx4 v[206:209], v163, s[12:13]
	v_add_u32_e32 v163, 0x20200, v162
	global_load_dwordx4 v[210:213], v163, s[12:13]
	v_add_u32_e32 v163, 0x20240, v162
	global_load_dwordx4 v[232:235], v163, s[12:13]
	v_add_u32_e32 v163, 0x30000, v162
	global_load_dwordx4 v[236:239], v163, s[12:13]
	v_add_u32_e32 v163, 0x30040, v162
	global_load_dwordx4 v[240:243], v163, s[12:13]
	v_add_u32_e32 v163, 0x30200, v162
	global_load_dwordx4 v[244:247], v163, s[12:13]
	v_add_u32_e32 v163, 0x30240, v162
	global_load_dwordx4 v[248:251], v163, s[12:13]
	v_add_u32_e32 v163, 0x80000, v162
	global_load_dwordx4 v[252:255], v163, s[12:13]
	v_lshl_add_u64 v[158:159], v[152:153], 1, s[22:23]
	v_lshl_add_u64 v[160:161], s[16:17], 0, v[154:155]
	v_xor_b32_e32 v147, 32, v146
	s_lshl_b32 s40, s40, 2
	s_ashr_i32 s41, s40, 31
	s_waitcnt vmcnt(16)
	v_mov_b64_e32 v[148:149], v[170:171]
	v_mov_b64_e32 v[150:151], v[172:173]
	v_add_u32_e32 v163, 0x80040, v162
	global_load_dwordx4 v[170:173], v163, s[12:13]
	v_pk_add_f32 v[126:127], v[126:127], v[150:151]
	v_pk_add_f32 v[124:125], v[124:125], v[148:149]
	global_store_dwordx4 v[160:161], v[124:127], off
	v_cvt_pk_bf16_f32 v148, v124, v125
	v_cvt_pk_bf16_f32 v149, v126, v127
	s_waitcnt vmcnt(17)
	v_mov_b32_e32 v148, v174
	v_mov_b32_e32 v149, v175
	v_mov_b64_e32 v[150:151], v[176:177]
	v_add_u32_e32 v163, 0x80200, v162
	global_load_dwordx4 v[174:177], v163, s[12:13]
	v_pk_add_f32 v[122:123], v[122:123], v[150:151]
	v_pk_add_f32 v[120:121], v[120:121], v[148:149]
	global_store_dwordx4 v[160:161], v[120:123], off offset:64
	v_cvt_pk_bf16_f32 v148, v120, v121
	v_cvt_pk_bf16_f32 v149, v122, v123
	s_waitcnt vmcnt(18)
	v_mov_b32_e32 v148, v178
	v_mov_b32_e32 v149, v179
	v_mov_b64_e32 v[150:151], v[180:181]
	v_add_u32_e32 v163, 0x80240, v162
	global_load_dwordx4 v[178:181], v163, s[12:13]
	v_pk_add_f32 v[150:151], v[118:119], v[150:151]
	v_pk_add_f32 v[148:149], v[116:117], v[148:149]
	global_store_dwordx4 v[160:161], v[148:151], off offset:512
	v_cvt_pk_bf16_f32 v116, v148, v149
	v_cvt_pk_bf16_f32 v117, v150, v151
	v_mul_f32_e32 v118, v125, v125
	v_mul_f32_e32 v119, v127, v127
	v_fmac_f32_e32 v118, v124, v124
	v_fmac_f32_e32 v119, v126, v126
	v_add_f32_e32 v118, v118, v119
	v_mul_f32_e32 v119, v121, v121
	v_mul_f32_e32 v121, v123, v123
	v_fmac_f32_e32 v119, v120, v120
	v_fmac_f32_e32 v121, v122, v122
	v_add_f32_e32 v119, v119, v121
	v_add_f32_e32 v118, v118, v119
	v_mul_f32_e32 v119, v149, v149
	v_mul_f32_e32 v120, v151, v151
	v_fmac_f32_e32 v119, v148, v148
	v_fmac_f32_e32 v120, v150, v150
	v_add_f32_e32 v119, v119, v120
	v_and_b32_e32 v117, 64, v146
	v_add_f32_e32 v122, v118, v119
	v_xor_b32_e32 v116, 16, v146
	v_add_u32_e32 v117, 64, v117
	v_cmp_lt_i32_e32 vcc, v116, v117
	s_waitcnt vmcnt(19)
	v_mov_b64_e32 v[152:153], v[182:183]
	v_mov_b64_e32 v[154:155], v[184:185]
	v_add_u32_e32 v163, 0x90000, v162
	global_load_dwordx4 v[182:185], v163, s[12:13]
	v_pk_add_f32 v[120:121], v[114:115], v[154:155]
	v_pk_add_f32 v[118:119], v[112:113], v[152:153]
	v_mul_f32_e32 v113, v121, v121
	v_mul_f32_e32 v112, v119, v119
	v_fmac_f32_e32 v112, v118, v118
	v_fmac_f32_e32 v113, v120, v120
	v_cndmask_b32_e32 v116, v146, v116, vcc
	v_add_f32_e32 v112, v112, v113
	v_lshlrev_b32_e32 v116, 2, v116
	v_add_f32_e32 v112, v122, v112
	ds_bpermute_b32 v113, v116, v112
	v_cmp_lt_i32_e32 vcc, v147, v117
	global_store_dwordx4 v[160:161], v[118:121], off offset:576
	s_waitcnt lgkmcnt(0)
	v_add_f32_e32 v112, v112, v113
	v_cndmask_b32_e32 v114, v146, v147, vcc
	v_lshlrev_b32_e32 v114, 2, v114
	ds_bpermute_b32 v113, v114, v112
	v_cvt_pk_bf16_f32 v118, v118, v119
	v_cvt_pk_bf16_f32 v119, v120, v121
	s_and_saveexec_b64 s[42:43], s[8:9]
	s_cbranch_execz .LBB0_2180
	s_waitcnt lgkmcnt(0)
	v_add_f32_e32 v115, v112, v113
	v_lshlrev_b64 v[112:113], 6, v[138:139]
	v_lshl_add_u64 v[112:113], s[24:25], 0, v[112:113]
	v_lshl_add_u64 v[112:113], s[40:41], 2, v[112:113]
	s_lshl_b32 s26, s74, 2
	v_lshl_add_u64 v[112:113], v[112:113], 0, s[26:27]
	global_store_dword v[112:113], v115, off
; __device__ __forceinline__ unsigned pk2(float lo, float hi) { unsigned r; asm volatile("v_cvt_pk_bf16_f32 %0, %1, %2" : "=v"(r) : "v"(lo), "v"(hi)); return r; }
;     __device__ __forceinline__ void operator()(const f32x4 (&acc)[2][2][4][2], const Unit& u, int wr, int wc, int fr, int fq) const {
;     ...
;                 const int row = row0 + ai * 128 + m * 16; const size_t ro = (size_t)row * DM + col0;
;                 float s = 0.f;
; #pragma unroll
;                 for (int bj = 0; bj < 2; ++bj)
; #pragma unroll
;                     for (int n = 0; n < 2; ++n) {
;                         const size_t o = ro + bj * 128 + n * 16;
;                         const f32x4 xn = *(const f32x4*)(xo + o) + acc[ai][bj][m][n];
;                         *(f32x4*)(xf + o) = xn;
;                         u32x2 w; w.x = pk2(xn[0], xn[1]); w.y = pk2(xn[2], xn[3]); *(u32x2*)(xb + o) = w;
;                         s += (xn[0] * xn[0] + xn[1] * xn[1]) + (xn[2] * xn[2] + xn[3] * xn[3]);
;                     }
;                 s += __shfl_xor(s, 16); s += __shfl_xor(s, 32);
;                 if (fq == 0) ssq[(size_t)row * 16 + u.pn * 4 + wc] = s;
.LBB0_2180:
	s_or_b64 exec, exec, s[42:43]
	v_or_b32_e32 v112, 16, v138
	s_waitcnt lgkmcnt(0)
	v_ashrrev_i32_e32 v113, 31, v112
	v_lshlrev_b64 v[118:119], 10, v[112:113]
	v_lshl_add_u64 v[122:123], v[118:119], 0, v[136:137]
	v_lshlrev_b64 v[124:125], 2, v[122:123]
	v_lshl_add_u64 v[126:127], s[12:13], 0, v[124:125]
	v_lshl_add_u64 v[122:123], v[122:123], 1, s[22:23]
	v_lshl_add_u64 v[124:125], s[16:17], 0, v[124:125]
	s_waitcnt vmcnt(20)
	v_mov_b64_e32 v[118:119], v[186:187]
	v_mov_b64_e32 v[120:121], v[188:189]
	v_add_u32_e32 v163, 0x90040, v162
	global_load_dwordx4 v[186:189], v163, s[12:13]
	v_pk_add_f32 v[110:111], v[110:111], v[120:121]
	v_pk_add_f32 v[108:109], v[108:109], v[118:119]
	global_store_dwordx4 v[124:125], v[108:111], off
	v_cvt_pk_bf16_f32 v118, v108, v109
	v_cvt_pk_bf16_f32 v119, v110, v111
	v_mul_f32_e32 v109, v109, v109
	v_mul_f32_e32 v111, v111, v111
	v_fmac_f32_e32 v109, v108, v108
	v_fmac_f32_e32 v111, v110, v110
	v_add_f32_e32 v108, v109, v111
	s_waitcnt vmcnt(21)
	v_mov_b64_e32 v[118:119], v[190:191]
	v_mov_b64_e32 v[120:121], v[192:193]
	v_add_u32_e32 v163, 0x90200, v162
	global_load_dwordx4 v[190:193], v163, s[12:13]
	v_pk_add_f32 v[106:107], v[106:107], v[120:121]
	v_pk_add_f32 v[104:105], v[104:105], v[118:119]
	global_store_dwordx4 v[124:125], v[104:107], off offset:64
	v_cvt_pk_bf16_f32 v118, v104, v105
	v_cvt_pk_bf16_f32 v119, v106, v107
	v_mul_f32_e32 v105, v105, v105
	v_mul_f32_e32 v107, v107, v107
	v_fmac_f32_e32 v105, v104, v104
	v_fmac_f32_e32 v107, v106, v106
	v_add_f32_e32 v104, v105, v107
	v_add_f32_e32 v104, v108, v104
	s_waitcnt vmcnt(22)
	v_mov_b64_e32 v[118:119], v[194:195]
	v_mov_b64_e32 v[120:121], v[196:197]
	v_add_u32_e32 v163, 0x90240, v162
	global_load_dwordx4 v[194:197], v163, s[12:13]
	v_pk_add_f32 v[102:103], v[102:103], v[120:121]
	v_pk_add_f32 v[100:101], v[100:101], v[118:119]
	global_store_dwordx4 v[124:125], v[100:103], off offset:512
	v_cvt_pk_bf16_f32 v118, v100, v101
	v_cvt_pk_bf16_f32 v119, v102, v103
	v_mul_f32_e32 v101, v101, v101
	v_mul_f32_e32 v103, v103, v103
	v_fmac_f32_e32 v101, v100, v100
	v_fmac_f32_e32 v103, v102, v102
	v_add_f32_e32 v100, v101, v103
	v_add_f32_e32 v102, v104, v100
	s_waitcnt vmcnt(23)
	v_mov_b64_e32 v[118:119], v[198:199]
	v_mov_b64_e32 v[120:121], v[200:201]
	v_add_u32_e32 v163, 0xa0000, v162
	global_load_dwordx4 v[198:201], v163, s[12:13]
	v_pk_add_f32 v[100:101], v[98:99], v[120:121]
	v_pk_add_f32 v[98:99], v[96:97], v[118:119]
	v_mul_f32_e32 v97, v101, v101
	v_mul_f32_e32 v96, v99, v99
	v_fmac_f32_e32 v96, v98, v98
	v_fmac_f32_e32 v97, v100, v100
	v_add_f32_e32 v96, v96, v97
	v_add_f32_e32 v96, v102, v96
	ds_bpermute_b32 v97, v116, v96
	global_store_dwordx4 v[124:125], v[98:101], off offset:576
	s_waitcnt lgkmcnt(0)
	v_add_f32_e32 v96, v96, v97
	ds_bpermute_b32 v97, v114, v96
	v_cvt_pk_bf16_f32 v98, v98, v99
	v_cvt_pk_bf16_f32 v99, v100, v101
	s_and_saveexec_b64 s[42:43], s[8:9]
	s_cbranch_execz .LBB0_2182
	s_waitcnt lgkmcnt(0)
	v_add_f32_e32 v98, v96, v97
	v_lshlrev_b64 v[96:97], 6, v[112:113]
	v_lshl_add_u64 v[96:97], s[24:25], 0, v[96:97]
	v_lshl_add_u64 v[96:97], s[40:41], 2, v[96:97]
	s_lshl_b32 s26, s74, 2
	v_lshl_add_u64 v[96:97], v[96:97], 0, s[26:27]
	global_store_dword v[96:97], v98, off
.LBB0_2182:
	s_or_b64 exec, exec, s[42:43]
	v_or_b32_e32 v96, 32, v138
	s_waitcnt lgkmcnt(0)
	v_ashrrev_i32_e32 v97, 31, v96
	v_lshlrev_b64 v[98:99], 10, v[96:97]
	v_lshl_add_u64 v[102:103], v[98:99], 0, v[136:137]
	v_lshlrev_b64 v[104:105], 2, v[102:103]
	v_lshl_add_u64 v[106:107], s[12:13], 0, v[104:105]
	v_lshl_add_u64 v[102:103], v[102:103], 1, s[22:23]
	v_lshl_add_u64 v[104:105], s[16:17], 0, v[104:105]
	s_waitcnt vmcnt(24)
	v_mov_b64_e32 v[98:99], v[202:203]
	v_mov_b64_e32 v[100:101], v[204:205]
	v_add_u32_e32 v163, 0xa0040, v162
	global_load_dwordx4 v[202:205], v163, s[12:13]
	v_pk_add_f32 v[94:95], v[94:95], v[100:101]
	v_pk_add_f32 v[92:93], v[92:93], v[98:99]
	global_store_dwordx4 v[104:105], v[92:95], off
	v_cvt_pk_bf16_f32 v98, v92, v93
	v_cvt_pk_bf16_f32 v99, v94, v95
	v_mul_f32_e32 v93, v93, v93
	v_mul_f32_e32 v95, v95, v95
	v_fmac_f32_e32 v93, v92, v92
	v_fmac_f32_e32 v95, v94, v94
	v_add_f32_e32 v92, v93, v95
	s_waitcnt vmcnt(25)
	v_mov_b64_e32 v[98:99], v[206:207]
	v_mov_b64_e32 v[100:101], v[208:209]
	v_add_u32_e32 v163, 0xa0200, v162
	global_load_dwordx4 v[206:209], v163, s[12:13]
	v_pk_add_f32 v[90:91], v[90:91], v[100:101]
	v_pk_add_f32 v[88:89], v[88:89], v[98:99]
	global_store_dwordx4 v[104:105], v[88:91], off offset:64
	v_cvt_pk_bf16_f32 v98, v88, v89
	v_cvt_pk_bf16_f32 v99, v90, v91
	v_mul_f32_e32 v89, v89, v89
	v_mul_f32_e32 v91, v91, v91
	v_fmac_f32_e32 v89, v88, v88
	v_fmac_f32_e32 v91, v90, v90
	v_add_f32_e32 v88, v89, v91
	v_add_f32_e32 v88, v92, v88
	s_waitcnt vmcnt(26)
	v_mov_b64_e32 v[98:99], v[210:211]
	v_mov_b64_e32 v[100:101], v[212:213]
	v_add_u32_e32 v163, 0xa0240, v162
	global_load_dwordx4 v[210:213], v163, s[12:13]
	v_pk_add_f32 v[86:87], v[86:87], v[100:101]
	v_pk_add_f32 v[84:85], v[84:85], v[98:99]
	global_store_dwordx4 v[104:105], v[84:87], off offset:512
	v_cvt_pk_bf16_f32 v98, v84, v85
	v_cvt_pk_bf16_f32 v99, v86, v87
	v_mul_f32_e32 v85, v85, v85
	v_mul_f32_e32 v87, v87, v87
	v_fmac_f32_e32 v85, v84, v84
	v_fmac_f32_e32 v87, v86, v86
	v_add_f32_e32 v84, v85, v87
	v_add_f32_e32 v86, v88, v84
	s_waitcnt vmcnt(27)
	v_mov_b64_e32 v[98:99], v[232:233]
	v_mov_b64_e32 v[100:101], v[234:235]
	v_add_u32_e32 v163, 0xb0000, v162
	global_load_dwordx4 v[232:235], v163, s[12:13]
	v_pk_add_f32 v[84:85], v[82:83], v[100:101]
	v_pk_add_f32 v[82:83], v[80:81], v[98:99]
	v_mul_f32_e32 v81, v85, v85
	v_mul_f32_e32 v80, v83, v83
	v_fmac_f32_e32 v80, v82, v82
	v_fmac_f32_e32 v81, v84, v84
	v_add_f32_e32 v80, v80, v81
	v_add_f32_e32 v80, v86, v80
	ds_bpermute_b32 v81, v116, v80
	global_store_dwordx4 v[104:105], v[82:85], off offset:576
	s_waitcnt lgkmcnt(0)
	v_add_f32_e32 v80, v80, v81
	ds_bpermute_b32 v81, v114, v80
	v_cvt_pk_bf16_f32 v82, v82, v83
	v_cvt_pk_bf16_f32 v83, v84, v85
	s_and_saveexec_b64 s[42:43], s[8:9]
	s_cbranch_execz .LBB0_2184
	s_waitcnt lgkmcnt(0)
	v_add_f32_e32 v82, v80, v81
	v_lshlrev_b64 v[80:81], 6, v[96:97]
	v_lshl_add_u64 v[80:81], s[24:25], 0, v[80:81]
	v_lshl_add_u64 v[80:81], s[40:41], 2, v[80:81]
	s_lshl_b32 s26, s74, 2
	v_lshl_add_u64 v[80:81], v[80:81], 0, s[26:27]
	global_store_dword v[80:81], v82, off
; __device__ __forceinline__ unsigned pk2(float lo, float hi) { unsigned r; asm volatile("v_cvt_pk_bf16_f32 %0, %1, %2" : "=v"(r) : "v"(lo), "v"(hi)); return r; }
;     __device__ __forceinline__ void operator()(const f32x4 (&acc)[2][2][4][2], const Unit& u, int wr, int wc, int fr, int fq) const {
;     ...
;                 const int row = row0 + ai * 128 + m * 16; const size_t ro = (size_t)row * DM + col0;
;                 float s = 0.f;
; #pragma unroll
;                 for (int bj = 0; bj < 2; ++bj)
; #pragma unroll
;                     for (int n = 0; n < 2; ++n) {
;                         const size_t o = ro + bj * 128 + n * 16;
;                         const f32x4 xn = *(const f32x4*)(xo + o) + acc[ai][bj][m][n];
;                         *(f32x4*)(xf + o) = xn;
;                         u32x2 w; w.x = pk2(xn[0], xn[1]); w.y = pk2(xn[2], xn[3]); *(u32x2*)(xb + o) = w;
;                         s += (xn[0] * xn[0] + xn[1] * xn[1]) + (xn[2] * xn[2] + xn[3] * xn[3]);
;                     }
;                 s += __shfl_xor(s, 16); s += __shfl_xor(s, 32);
;                 if (fq == 0) ssq[(size_t)row * 16 + u.pn * 4 + wc] = s;
.LBB0_2184:
	s_or_b64 exec, exec, s[42:43]
	v_or_b32_e32 v80, 48, v138
	s_waitcnt lgkmcnt(0)
	v_ashrrev_i32_e32 v81, 31, v80
	v_lshlrev_b64 v[82:83], 10, v[80:81]
	v_lshl_add_u64 v[86:87], v[82:83], 0, v[136:137]
	v_lshlrev_b64 v[88:89], 2, v[86:87]
	v_lshl_add_u64 v[90:91], s[12:13], 0, v[88:89]
	v_lshl_add_u64 v[86:87], v[86:87], 1, s[22:23]
	v_lshl_add_u64 v[88:89], s[16:17], 0, v[88:89]
	s_waitcnt vmcnt(28)
	v_mov_b64_e32 v[82:83], v[236:237]
	v_mov_b64_e32 v[84:85], v[238:239]
	v_add_u32_e32 v163, 0xb0040, v162
	global_load_dwordx4 v[236:239], v163, s[12:13]
	v_pk_add_f32 v[78:79], v[78:79], v[84:85]
	v_pk_add_f32 v[76:77], v[76:77], v[82:83]
	global_store_dwordx4 v[88:89], v[76:79], off
	v_cvt_pk_bf16_f32 v82, v76, v77
	v_cvt_pk_bf16_f32 v83, v78, v79
	v_mul_f32_e32 v77, v77, v77
	v_mul_f32_e32 v79, v79, v79
	v_fmac_f32_e32 v77, v76, v76
	v_fmac_f32_e32 v79, v78, v78
	v_add_f32_e32 v76, v77, v79
	s_waitcnt vmcnt(29)
	v_mov_b64_e32 v[82:83], v[240:241]
	v_mov_b64_e32 v[84:85], v[242:243]
	v_add_u32_e32 v163, 0xb0200, v162
	global_load_dwordx4 v[240:243], v163, s[12:13]
	v_pk_add_f32 v[74:75], v[74:75], v[84:85]
	v_pk_add_f32 v[72:73], v[72:73], v[82:83]
	global_store_dwordx4 v[88:89], v[72:75], off offset:64
	v_cvt_pk_bf16_f32 v82, v72, v73
	v_cvt_pk_bf16_f32 v83, v74, v75
	v_mul_f32_e32 v73, v73, v73
	v_mul_f32_e32 v75, v75, v75
	v_fmac_f32_e32 v73, v72, v72
	v_fmac_f32_e32 v75, v74, v74
	v_add_f32_e32 v72, v73, v75
	v_add_f32_e32 v72, v76, v72
	s_waitcnt vmcnt(30)
	v_mov_b64_e32 v[82:83], v[244:245]
	v_mov_b64_e32 v[84:85], v[246:247]
	v_add_u32_e32 v163, 0xb0240, v162
	global_load_dwordx4 v[244:247], v163, s[12:13]
	v_pk_add_f32 v[70:71], v[70:71], v[84:85]
	v_pk_add_f32 v[68:69], v[68:69], v[82:83]
	global_store_dwordx4 v[88:89], v[68:71], off offset:512
	v_cvt_pk_bf16_f32 v82, v68, v69
	v_cvt_pk_bf16_f32 v83, v70, v71
	v_mul_f32_e32 v69, v69, v69
	v_mul_f32_e32 v71, v71, v71
	v_fmac_f32_e32 v69, v68, v68
	v_fmac_f32_e32 v71, v70, v70
	v_add_f32_e32 v68, v69, v71
	v_add_f32_e32 v70, v72, v68
	s_waitcnt vmcnt(31)
	v_mov_b64_e32 v[82:83], v[248:249]
	v_mov_b64_e32 v[84:85], v[250:251]
	v_pk_add_f32 v[68:69], v[66:67], v[84:85]
	v_pk_add_f32 v[66:67], v[64:65], v[82:83]
	v_mul_f32_e32 v65, v69, v69
	v_mul_f32_e32 v64, v67, v67
	v_fmac_f32_e32 v64, v66, v66
	v_fmac_f32_e32 v65, v68, v68
	v_add_f32_e32 v64, v64, v65
	v_add_f32_e32 v64, v70, v64
	ds_bpermute_b32 v65, v116, v64
	global_store_dwordx4 v[88:89], v[66:69], off offset:576
	s_waitcnt lgkmcnt(0)
	v_add_f32_e32 v64, v64, v65
	ds_bpermute_b32 v65, v114, v64
	v_cvt_pk_bf16_f32 v66, v66, v67
	v_cvt_pk_bf16_f32 v67, v68, v69
	s_and_saveexec_b64 s[42:43], s[8:9]
	s_cbranch_execz .LBB0_2186
	s_waitcnt lgkmcnt(0)
	v_add_f32_e32 v66, v64, v65
	v_lshlrev_b64 v[64:65], 6, v[80:81]
	v_lshl_add_u64 v[64:65], s[24:25], 0, v[64:65]
	v_lshl_add_u64 v[64:65], s[40:41], 2, v[64:65]
	s_lshl_b32 s26, s74, 2
	v_lshl_add_u64 v[64:65], v[64:65], 0, s[26:27]
	global_store_dword v[64:65], v66, off
.LBB0_2186:
	s_or_b64 exec, exec, s[42:43]
	v_add_u32_e32 v64, 0x80, v138
	s_waitcnt lgkmcnt(0)
	v_ashrrev_i32_e32 v65, 31, v64
	v_lshlrev_b64 v[66:67], 10, v[64:65]
	v_lshl_add_u64 v[70:71], v[66:67], 0, v[136:137]
	v_lshlrev_b64 v[72:73], 2, v[70:71]
	v_lshl_add_u64 v[74:75], s[12:13], 0, v[72:73]
	v_lshl_add_u64 v[70:71], v[70:71], 1, s[22:23]
	v_lshl_add_u64 v[72:73], s[16:17], 0, v[72:73]
	s_waitcnt vmcnt(31)
	v_mov_b64_e32 v[66:67], v[252:253]
	v_mov_b64_e32 v[68:69], v[254:255]
	v_pk_add_f32 v[62:63], v[62:63], v[68:69]
	v_pk_add_f32 v[60:61], v[60:61], v[66:67]
	global_store_dwordx4 v[72:73], v[60:63], off
	v_cvt_pk_bf16_f32 v66, v60, v61
	v_cvt_pk_bf16_f32 v67, v62, v63
	v_mul_f32_e32 v61, v61, v61
	v_mul_f32_e32 v63, v63, v63
	v_fmac_f32_e32 v61, v60, v60
	v_fmac_f32_e32 v63, v62, v62
	v_add_f32_e32 v60, v61, v63
	s_waitcnt vmcnt(31)
	v_mov_b64_e32 v[66:67], v[170:171]
	v_mov_b64_e32 v[68:69], v[172:173]
	v_pk_add_f32 v[58:59], v[58:59], v[68:69]
	v_pk_add_f32 v[56:57], v[56:57], v[66:67]
	global_store_dwordx4 v[72:73], v[56:59], off offset:64
	v_cvt_pk_bf16_f32 v66, v56, v57
	v_cvt_pk_bf16_f32 v67, v58, v59
	v_mul_f32_e32 v57, v57, v57
	v_mul_f32_e32 v59, v59, v59
	v_fmac_f32_e32 v57, v56, v56
	v_fmac_f32_e32 v59, v58, v58
	v_add_f32_e32 v56, v57, v59
	v_add_f32_e32 v56, v60, v56
	s_waitcnt vmcnt(30)
	v_mov_b64_e32 v[66:67], v[174:175]
	v_mov_b64_e32 v[68:69], v[176:177]
	v_pk_add_f32 v[54:55], v[54:55], v[68:69]
	v_pk_add_f32 v[52:53], v[52:53], v[66:67]
	global_store_dwordx4 v[72:73], v[52:55], off offset:512
	v_cvt_pk_bf16_f32 v66, v52, v53
	v_cvt_pk_bf16_f32 v67, v54, v55
	v_mul_f32_e32 v53, v53, v53
	v_mul_f32_e32 v55, v55, v55
	v_fmac_f32_e32 v53, v52, v52
	v_fmac_f32_e32 v55, v54, v54
	v_add_f32_e32 v52, v53, v55
	v_add_f32_e32 v54, v56, v52
	s_waitcnt vmcnt(29)
	v_mov_b64_e32 v[66:67], v[178:179]
	v_mov_b64_e32 v[68:69], v[180:181]
	v_pk_add_f32 v[52:53], v[50:51], v[68:69]
	v_pk_add_f32 v[50:51], v[48:49], v[66:67]
	v_mul_f32_e32 v49, v53, v53
	v_mul_f32_e32 v48, v51, v51
	v_fmac_f32_e32 v48, v50, v50
	v_fmac_f32_e32 v49, v52, v52
	v_add_f32_e32 v48, v48, v49
	v_add_f32_e32 v48, v54, v48
	ds_bpermute_b32 v49, v116, v48
	global_store_dwordx4 v[72:73], v[50:53], off offset:576
	s_waitcnt lgkmcnt(0)
	v_add_f32_e32 v48, v48, v49
	ds_bpermute_b32 v49, v114, v48
	v_cvt_pk_bf16_f32 v50, v50, v51
	v_cvt_pk_bf16_f32 v51, v52, v53
	s_and_saveexec_b64 s[42:43], s[8:9]
	s_cbranch_execz .LBB0_2188
	s_waitcnt lgkmcnt(0)
	v_add_f32_e32 v50, v48, v49
	v_lshlrev_b64 v[48:49], 6, v[64:65]
	v_lshl_add_u64 v[48:49], s[24:25], 0, v[48:49]
	v_lshl_add_u64 v[48:49], s[40:41], 2, v[48:49]
	s_lshl_b32 s26, s74, 2
	v_lshl_add_u64 v[48:49], v[48:49], 0, s[26:27]
	global_store_dword v[48:49], v50, off
; __device__ __forceinline__ unsigned pk2(float lo, float hi) { unsigned r; asm volatile("v_cvt_pk_bf16_f32 %0, %1, %2" : "=v"(r) : "v"(lo), "v"(hi)); return r; }
;     __device__ __forceinline__ void operator()(const f32x4 (&acc)[2][2][4][2], const Unit& u, int wr, int wc, int fr, int fq) const {
;     ...
;                 const int row = row0 + ai * 128 + m * 16; const size_t ro = (size_t)row * DM + col0;
;                 float s = 0.f;
; #pragma unroll
;                 for (int bj = 0; bj < 2; ++bj)
; #pragma unroll
;                     for (int n = 0; n < 2; ++n) {
;                         const size_t o = ro + bj * 128 + n * 16;
;                         const f32x4 xn = *(const f32x4*)(xo + o) + acc[ai][bj][m][n];
;                         *(f32x4*)(xf + o) = xn;
;                         u32x2 w; w.x = pk2(xn[0], xn[1]); w.y = pk2(xn[2], xn[3]); *(u32x2*)(xb + o) = w;
;                         s += (xn[0] * xn[0] + xn[1] * xn[1]) + (xn[2] * xn[2] + xn[3] * xn[3]);
;                     }
;                 s += __shfl_xor(s, 16); s += __shfl_xor(s, 32);
;                 if (fq == 0) ssq[(size_t)row * 16 + u.pn * 4 + wc] = s;
.LBB0_2188:
	s_or_b64 exec, exec, s[42:43]
	v_add_u32_e32 v48, 0x90, v138
	s_waitcnt lgkmcnt(0)
	v_ashrrev_i32_e32 v49, 31, v48
	v_lshlrev_b64 v[50:51], 10, v[48:49]
	v_lshl_add_u64 v[54:55], v[50:51], 0, v[136:137]
	v_lshlrev_b64 v[56:57], 2, v[54:55]
	v_lshl_add_u64 v[58:59], s[12:13], 0, v[56:57]
	v_lshl_add_u64 v[54:55], v[54:55], 1, s[22:23]
	v_lshl_add_u64 v[56:57], s[16:17], 0, v[56:57]
	s_waitcnt vmcnt(28)
	v_mov_b64_e32 v[50:51], v[182:183]
	v_mov_b64_e32 v[52:53], v[184:185]
	v_pk_add_f32 v[46:47], v[46:47], v[52:53]
	v_pk_add_f32 v[44:45], v[44:45], v[50:51]
	global_store_dwordx4 v[56:57], v[44:47], off
	v_cvt_pk_bf16_f32 v50, v44, v45
	v_cvt_pk_bf16_f32 v51, v46, v47
	v_mul_f32_e32 v45, v45, v45
	v_mul_f32_e32 v47, v47, v47
	v_fmac_f32_e32 v45, v44, v44
	v_fmac_f32_e32 v47, v46, v46
	v_add_f32_e32 v44, v45, v47
	s_waitcnt vmcnt(27)
	v_mov_b64_e32 v[50:51], v[186:187]
	v_mov_b64_e32 v[52:53], v[188:189]
	v_pk_add_f32 v[42:43], v[42:43], v[52:53]
	v_pk_add_f32 v[40:41], v[40:41], v[50:51]
	global_store_dwordx4 v[56:57], v[40:43], off offset:64
	v_cvt_pk_bf16_f32 v50, v40, v41
	v_cvt_pk_bf16_f32 v51, v42, v43
	v_mul_f32_e32 v41, v41, v41
	v_mul_f32_e32 v43, v43, v43
	v_fmac_f32_e32 v41, v40, v40
	v_fmac_f32_e32 v43, v42, v42
	v_add_f32_e32 v40, v41, v43
	v_add_f32_e32 v40, v44, v40
	s_waitcnt vmcnt(26)
	v_mov_b64_e32 v[50:51], v[190:191]
	v_mov_b64_e32 v[52:53], v[192:193]
	v_pk_add_f32 v[38:39], v[38:39], v[52:53]
	v_pk_add_f32 v[36:37], v[36:37], v[50:51]
	global_store_dwordx4 v[56:57], v[36:39], off offset:512
	v_cvt_pk_bf16_f32 v50, v36, v37
	v_cvt_pk_bf16_f32 v51, v38, v39
	v_mul_f32_e32 v37, v37, v37
	v_mul_f32_e32 v39, v39, v39
	v_fmac_f32_e32 v37, v36, v36
	v_fmac_f32_e32 v39, v38, v38
	v_add_f32_e32 v36, v37, v39
	v_add_f32_e32 v38, v40, v36
	s_waitcnt vmcnt(25)
	v_mov_b64_e32 v[50:51], v[194:195]
	v_mov_b64_e32 v[52:53], v[196:197]
	v_pk_add_f32 v[36:37], v[34:35], v[52:53]
	v_pk_add_f32 v[34:35], v[32:33], v[50:51]
	v_mul_f32_e32 v33, v37, v37
	v_mul_f32_e32 v32, v35, v35
	v_fmac_f32_e32 v32, v34, v34
	v_fmac_f32_e32 v33, v36, v36
	v_add_f32_e32 v32, v32, v33
	v_add_f32_e32 v32, v38, v32
	ds_bpermute_b32 v33, v116, v32
	global_store_dwordx4 v[56:57], v[34:37], off offset:576
	s_waitcnt lgkmcnt(0)
	v_add_f32_e32 v32, v32, v33
	ds_bpermute_b32 v33, v114, v32
	v_cvt_pk_bf16_f32 v34, v34, v35
	v_cvt_pk_bf16_f32 v35, v36, v37
	s_and_saveexec_b64 s[42:43], s[8:9]
	s_cbranch_execz .LBB0_2190
	s_waitcnt lgkmcnt(0)
	v_add_f32_e32 v34, v32, v33
	v_lshlrev_b64 v[32:33], 6, v[48:49]
	v_lshl_add_u64 v[32:33], s[24:25], 0, v[32:33]
	v_lshl_add_u64 v[32:33], s[40:41], 2, v[32:33]
	s_lshl_b32 s26, s74, 2
	v_lshl_add_u64 v[32:33], v[32:33], 0, s[26:27]
	global_store_dword v[32:33], v34, off
; __device__ __forceinline__ unsigned pk2(float lo, float hi) { unsigned r; asm volatile("v_cvt_pk_bf16_f32 %0, %1, %2" : "=v"(r) : "v"(lo), "v"(hi)); return r; }
;     __device__ __forceinline__ void operator()(const f32x4 (&acc)[2][2][4][2], const Unit& u, int wr, int wc, int fr, int fq) const {
;     ...
;                 const int row = row0 + ai * 128 + m * 16; const size_t ro = (size_t)row * DM + col0;
;                 float s = 0.f;
; #pragma unroll
;                 for (int bj = 0; bj < 2; ++bj)
; #pragma unroll
;                     for (int n = 0; n < 2; ++n) {
;                         const size_t o = ro + bj * 128 + n * 16;
;                         const f32x4 xn = *(const f32x4*)(xo + o) + acc[ai][bj][m][n];
;                         *(f32x4*)(xf + o) = xn;
;                         u32x2 w; w.x = pk2(xn[0], xn[1]); w.y = pk2(xn[2], xn[3]); *(u32x2*)(xb + o) = w;
;                         s += (xn[0] * xn[0] + xn[1] * xn[1]) + (xn[2] * xn[2] + xn[3] * xn[3]);
;                     }
;                 s += __shfl_xor(s, 16); s += __shfl_xor(s, 32);
;                 if (fq == 0) ssq[(size_t)row * 16 + u.pn * 4 + wc] = s;
.LBB0_2190:
	s_or_b64 exec, exec, s[42:43]
	v_add_u32_e32 v32, 0xa0, v138
	s_waitcnt lgkmcnt(0)
	v_ashrrev_i32_e32 v33, 31, v32
	v_lshlrev_b64 v[34:35], 10, v[32:33]
	v_lshl_add_u64 v[38:39], v[34:35], 0, v[136:137]
	v_lshlrev_b64 v[40:41], 2, v[38:39]
	v_lshl_add_u64 v[42:43], s[12:13], 0, v[40:41]
	v_lshl_add_u64 v[38:39], v[38:39], 1, s[22:23]
	v_lshl_add_u64 v[40:41], s[16:17], 0, v[40:41]
	s_waitcnt vmcnt(24)
	v_mov_b64_e32 v[34:35], v[198:199]
	v_mov_b64_e32 v[36:37], v[200:201]
	v_pk_add_f32 v[30:31], v[30:31], v[36:37]
	v_pk_add_f32 v[28:29], v[28:29], v[34:35]
	global_store_dwordx4 v[40:41], v[28:31], off
	v_cvt_pk_bf16_f32 v34, v28, v29
	v_cvt_pk_bf16_f32 v35, v30, v31
	v_mul_f32_e32 v29, v29, v29
	v_mul_f32_e32 v31, v31, v31
	v_fmac_f32_e32 v29, v28, v28
	v_fmac_f32_e32 v31, v30, v30
	v_add_f32_e32 v28, v29, v31
	s_waitcnt vmcnt(23)
	v_mov_b64_e32 v[34:35], v[202:203]
	v_mov_b64_e32 v[36:37], v[204:205]
	v_pk_add_f32 v[26:27], v[26:27], v[36:37]
	v_pk_add_f32 v[24:25], v[24:25], v[34:35]
	global_store_dwordx4 v[40:41], v[24:27], off offset:64
	v_cvt_pk_bf16_f32 v34, v24, v25
	v_cvt_pk_bf16_f32 v35, v26, v27
	v_mul_f32_e32 v25, v25, v25
	v_mul_f32_e32 v27, v27, v27
	v_fmac_f32_e32 v25, v24, v24
	v_fmac_f32_e32 v27, v26, v26
	v_add_f32_e32 v24, v25, v27
	v_add_f32_e32 v24, v28, v24
	s_waitcnt vmcnt(22)
	v_mov_b64_e32 v[34:35], v[206:207]
	v_mov_b64_e32 v[36:37], v[208:209]
	v_pk_add_f32 v[22:23], v[22:23], v[36:37]
	v_pk_add_f32 v[20:21], v[20:21], v[34:35]
	global_store_dwordx4 v[40:41], v[20:23], off offset:512
	v_cvt_pk_bf16_f32 v34, v20, v21
	v_cvt_pk_bf16_f32 v35, v22, v23
	v_mul_f32_e32 v21, v21, v21
	v_mul_f32_e32 v23, v23, v23
	v_fmac_f32_e32 v21, v20, v20
	v_fmac_f32_e32 v23, v22, v22
	v_add_f32_e32 v20, v21, v23
	v_add_f32_e32 v22, v24, v20
	s_waitcnt vmcnt(21)
	v_mov_b64_e32 v[34:35], v[210:211]
	v_mov_b64_e32 v[36:37], v[212:213]
	v_pk_add_f32 v[20:21], v[18:19], v[36:37]
	v_pk_add_f32 v[18:19], v[16:17], v[34:35]
	v_mul_f32_e32 v17, v21, v21
	v_mul_f32_e32 v16, v19, v19
	v_fmac_f32_e32 v16, v18, v18
	v_fmac_f32_e32 v17, v20, v20
	v_add_f32_e32 v16, v16, v17
	v_add_f32_e32 v16, v22, v16
	ds_bpermute_b32 v17, v116, v16
	global_store_dwordx4 v[40:41], v[18:21], off offset:576
	s_waitcnt lgkmcnt(0)
	v_add_f32_e32 v16, v16, v17
	ds_bpermute_b32 v17, v114, v16
	v_cvt_pk_bf16_f32 v18, v18, v19
	v_cvt_pk_bf16_f32 v19, v20, v21
	s_and_saveexec_b64 s[42:43], s[8:9]
	s_cbranch_execz .LBB0_2192
	s_waitcnt lgkmcnt(0)
	v_add_f32_e32 v18, v16, v17
	v_lshlrev_b64 v[16:17], 6, v[32:33]
	v_lshl_add_u64 v[16:17], s[24:25], 0, v[16:17]
	v_lshl_add_u64 v[16:17], s[40:41], 2, v[16:17]
	s_lshl_b32 s26, s74, 2
	v_lshl_add_u64 v[16:17], v[16:17], 0, s[26:27]
	global_store_dword v[16:17], v18, off
.LBB0_2192:
	s_or_b64 exec, exec, s[42:43]
	v_add_u32_e32 v16, 0xb0, v138
	s_waitcnt lgkmcnt(0)
	v_ashrrev_i32_e32 v17, 31, v16
	v_lshlrev_b64 v[18:19], 10, v[16:17]
	v_lshl_add_u64 v[22:23], v[18:19], 0, v[136:137]
	v_lshlrev_b64 v[24:25], 2, v[22:23]
	v_lshl_add_u64 v[26:27], s[12:13], 0, v[24:25]
	v_lshl_add_u64 v[22:23], v[22:23], 1, s[22:23]
	v_lshl_add_u64 v[24:25], s[16:17], 0, v[24:25]
	s_waitcnt vmcnt(20)
	v_mov_b64_e32 v[18:19], v[232:233]
	v_mov_b64_e32 v[20:21], v[234:235]
	v_pk_add_f32 v[14:15], v[14:15], v[20:21]
	v_pk_add_f32 v[12:13], v[12:13], v[18:19]
	global_store_dwordx4 v[24:25], v[12:15], off
	v_cvt_pk_bf16_f32 v18, v12, v13
	v_cvt_pk_bf16_f32 v19, v14, v15
	v_mul_f32_e32 v13, v13, v13
	v_mul_f32_e32 v15, v15, v15
	v_fmac_f32_e32 v13, v12, v12
	v_fmac_f32_e32 v15, v14, v14
	v_add_f32_e32 v12, v13, v15
	s_waitcnt vmcnt(19)
	v_mov_b64_e32 v[18:19], v[236:237]
	v_mov_b64_e32 v[20:21], v[238:239]
	v_pk_add_f32 v[10:11], v[10:11], v[20:21]
	v_pk_add_f32 v[8:9], v[8:9], v[18:19]
	global_store_dwordx4 v[24:25], v[8:11], off offset:64
	v_cvt_pk_bf16_f32 v18, v8, v9
	v_cvt_pk_bf16_f32 v19, v10, v11
	v_mul_f32_e32 v9, v9, v9
	v_mul_f32_e32 v11, v11, v11
	v_fmac_f32_e32 v9, v8, v8
	v_fmac_f32_e32 v11, v10, v10
	v_add_f32_e32 v8, v9, v11
	v_add_f32_e32 v8, v12, v8
	s_waitcnt vmcnt(18)
	v_mov_b64_e32 v[18:19], v[240:241]
	v_mov_b64_e32 v[20:21], v[242:243]
	v_pk_add_f32 v[6:7], v[6:7], v[20:21]
	v_pk_add_f32 v[4:5], v[4:5], v[18:19]
	global_store_dwordx4 v[24:25], v[4:7], off offset:512
	v_cvt_pk_bf16_f32 v18, v4, v5
	v_cvt_pk_bf16_f32 v19, v6, v7
	v_mul_f32_e32 v5, v5, v5
	v_mul_f32_e32 v7, v7, v7
	v_fmac_f32_e32 v5, v4, v4
	v_fmac_f32_e32 v7, v6, v6
	v_add_f32_e32 v4, v5, v7
	v_add_f32_e32 v6, v8, v4
	s_waitcnt vmcnt(17)
	v_mov_b64_e32 v[18:19], v[244:245]
	v_mov_b64_e32 v[20:21], v[246:247]
	v_pk_add_f32 v[4:5], v[2:3], v[20:21]
	v_pk_add_f32 v[2:3], v[0:1], v[18:19]
	v_mul_f32_e32 v1, v5, v5
	v_mul_f32_e32 v0, v3, v3
	v_fmac_f32_e32 v0, v2, v2
	v_fmac_f32_e32 v1, v4, v4
	v_add_f32_e32 v0, v0, v1
	v_add_f32_e32 v0, v6, v0
	ds_bpermute_b32 v1, v116, v0
	global_store_dwordx4 v[24:25], v[2:5], off offset:576
	s_waitcnt lgkmcnt(0)
	v_add_f32_e32 v0, v0, v1
	ds_bpermute_b32 v1, v114, v0
	v_cvt_pk_bf16_f32 v2, v2, v3
	v_cvt_pk_bf16_f32 v3, v4, v5
	s_and_saveexec_b64 s[12:13], s[8:9]
	s_cbranch_execz .LBB0_2153
	s_waitcnt lgkmcnt(0)
	v_add_f32_e32 v2, v0, v1
	v_lshlrev_b64 v[0:1], 6, v[16:17]
	v_lshl_add_u64 v[0:1], s[24:25], 0, v[0:1]
	v_lshl_add_u64 v[0:1], s[40:41], 2, v[0:1]
	s_lshl_b32 s26, s74, 2
	v_lshl_add_u64 v[0:1], v[0:1], 0, s[26:27]
	global_store_dword v[0:1], v2, off
	s_branch .LBB0_2153

; __device__ __forceinline__ unsigned pk2(float lo, float hi) { unsigned r; asm volatile("v_cvt_pk_bf16_f32 %0, %1, %2" : "=v"(r) : "v"(lo), "v"(hi)); return r; }
;     ...
;         const int lane = threadIdx.x & 63, wv = threadIdx.x >> 6;
;         const int rbase = u.pm * 256 + (kq * 4 + u.pn) * 16 + wv * 2;
; #pragma unroll
;         for (int rr = 0; rr < 2; ++rr) {
;             const int row = rbase + rr; float sq = 0.f;
; #pragma unroll
;             for (int i = 0; i < 4; ++i) {
;                 const size_t o = (size_t)row * DM + i * 256 + lane * 4;
;                 f32x4 v = *(const f32x4*)(xold + o);
; #pragma unroll
;                 for (int q = 0; q < 4; ++q) v += *(const f32x4*)(part + (size_t)q * 1024 * DM + o);
;                 *(f32x4*)(xf_s + o) = v;
;                 u32x2 w; w.x = pk2(v[0], v[1]); w.y = pk2(v[2], v[3]); *(u32x2*)(xb_s + o) = w;
;                 sq += (v[0] * v[0] + v[1] * v[1]) + (v[2] * v[2] + v[3] * v[3]);
;             }
; #pragma unroll
;             for (int o = 32; o >= 1; o >>= 1) sq += __shfl_xor(sq, o);
;             if (lane < 16) ssq_s[(size_t)row * 16 + lane] = lane == 0 ? sq : 0.f;
;         }
.LBB0_2262:
	s_or_b64 exec, exec, s[6:7]
	s_add_u32 s14, s16, 0x4000000
	s_addc_u32 s15, s17, 0
	s_add_u32 s12, s12, 0x2000000
	s_addc_u32 s13, s13, 0
	s_lshr_b32 s6, s51, 2
	v_lshrrev_b32_e32 v0, 5, v166
	s_and_b32 s6, s6, 0xffffffc
	v_and_b32_e32 v0, 30, v0
	s_add_i32 s22, s22, s6
	v_lshl_or_b32 v0, s23, 8, v0
	v_lshl_add_u32 v2, s22, 4, v0
	v_ashrrev_i32_e32 v3, 31, v2
	v_lshlrev_b32_e32 v0, 2, v167
	v_lshlrev_b64 v[4:5], 10, v[2:3]
	v_or_b32_e32 v4, v4, v0
	v_lshlrev_b64 v[10:11], 2, v[4:5]
	v_lshl_add_u64 v[38:39], s[10:11], 0, v[10:11]
	s_mov_b32 s18, 0x400000
	v_add_co_u32_e32 v40, vcc, s18, v38
	s_mov_b32 s19, 0x800000
	s_nop 0
	v_addc_co_u32_e32 v41, vcc, 0, v39, vcc
	v_lshl_add_u64 v[26:27], s[14:15], 0, v[10:11]
	v_add_co_u32_e32 v42, vcc, s19, v38
	s_barrier
	global_load_dwordx4 v[6:9], v[26:27], off
	v_addc_co_u32_e32 v43, vcc, 0, v39, vcc
	s_mov_b32 s20, 0xc00000
	global_load_dwordx4 v[10:13], v[38:39], off
	global_load_dwordx4 v[14:17], v[40:41], off
	v_add_co_u32_e32 v44, vcc, s20, v38
	global_load_dwordx4 v[18:21], v[42:43], off
	s_nop 0
	v_addc_co_u32_e32 v45, vcc, 0, v39, vcc
	global_load_dwordx4 v[22:25], v[44:45], off
	v_mov_b32_e32 v31, v5
	v_lshl_add_u64 v[28:29], v[4:5], 1, s[12:13]
	v_or_b32_e32 v30, 0x100, v4
	v_lshl_add_u64 v[32:33], v[30:31], 2, s[14:15]
	v_mov_b32_e32 v35, v5
	v_or_b32_e32 v34, 0x200, v4
	v_lshl_add_u64 v[30:31], v[30:31], 1, s[12:13]
	v_lshl_add_u64 v[36:37], v[34:35], 2, s[14:15]
	v_or_b32_e32 v4, 0x300, v4
	v_lshl_add_u64 v[34:35], v[34:35], 1, s[12:13]
	v_lshl_add_u64 v[46:47], v[4:5], 2, s[14:15]
	v_mov_b32_e32 v1, 0
	s_mov_b64 s[16:17], 0x100000
	v_cmp_gt_u32_e64 s[6:7], 16, v167
	v_cmp_eq_u32_e32 vcc, 0, v167
	v_lshl_add_u64 v[4:5], v[4:5], 1, s[12:13]
	global_load_dwordx4 v[186:189], v[32:33], off
	global_load_dwordx4 v[190:193], v[38:39], off offset:1024
	global_load_dwordx4 v[194:197], v[40:41], off offset:1024
	global_load_dwordx4 v[198:201], v[42:43], off offset:1024
	global_load_dwordx4 v[202:205], v[44:45], off offset:1024
	global_load_dwordx4 v[206:209], v[36:37], off
	global_load_dwordx4 v[210:213], v[38:39], off offset:2048
	global_load_dwordx4 v[214:217], v[40:41], off offset:2048
	global_load_dwordx4 v[218:221], v[42:43], off offset:2048
	global_load_dwordx4 v[222:225], v[44:45], off offset:2048
	global_load_dwordx4 v[226:229], v[46:47], off
	global_load_dwordx4 v[232:235], v[38:39], off offset:3072
	global_load_dwordx4 v[236:239], v[40:41], off offset:3072
	global_load_dwordx4 v[240:243], v[42:43], off offset:3072
	global_load_dwordx4 v[244:247], v[44:45], off offset:3072
	s_waitcnt vmcnt(18)
	v_pk_add_f32 v[8:9], v[8:9], v[12:13]
	v_pk_add_f32 v[6:7], v[6:7], v[10:11]
	s_waitcnt vmcnt(17)
	v_pk_add_f32 v[8:9], v[8:9], v[16:17]
	v_pk_add_f32 v[6:7], v[6:7], v[14:15]
	s_waitcnt vmcnt(16)
	v_pk_add_f32 v[8:9], v[8:9], v[20:21]
	v_pk_add_f32 v[6:7], v[6:7], v[18:19]
	s_waitcnt vmcnt(15)
	v_pk_add_f32 v[8:9], v[8:9], v[24:25]
	v_pk_add_f32 v[6:7], v[6:7], v[22:23]
	global_store_dwordx4 v[26:27], v[6:9], off
	v_cvt_pk_bf16_f32 v10, v6, v7
	v_cvt_pk_bf16_f32 v11, v8, v9
	global_store_dwordx2 v[28:29], v[10:11], off
	s_nop 0
	v_mul_f32_e32 v7, v7, v7
	v_mul_f32_e32 v9, v9, v9
	v_fmac_f32_e32 v7, v6, v6
	v_fmac_f32_e32 v9, v8, v8
	v_add_f32_e32 v6, v7, v9
	s_waitcnt vmcnt(12)
	v_mov_b64_e32 v[10:11], v[186:187]
	v_mov_b64_e32 v[12:13], v[188:189]
	v_mov_b64_e32 v[14:15], v[190:191]
	v_mov_b64_e32 v[16:17], v[192:193]
	v_mov_b64_e32 v[18:19], v[194:195]
	v_mov_b64_e32 v[20:21], v[196:197]
	v_mov_b64_e32 v[22:23], v[198:199]
	v_mov_b64_e32 v[24:25], v[200:201]
	v_mov_b64_e32 v[26:27], v[202:203]
	v_mov_b64_e32 v[28:29], v[204:205]
	v_pk_add_f32 v[12:13], v[12:13], v[16:17]
	v_pk_add_f32 v[10:11], v[10:11], v[14:15]
	v_pk_add_f32 v[12:13], v[12:13], v[20:21]
	v_pk_add_f32 v[10:11], v[10:11], v[18:19]
	v_pk_add_f32 v[12:13], v[12:13], v[24:25]
	v_pk_add_f32 v[10:11], v[10:11], v[22:23]
	v_pk_add_f32 v[12:13], v[12:13], v[28:29]
	v_pk_add_f32 v[10:11], v[10:11], v[26:27]
	global_store_dwordx4 v[32:33], v[10:13], off
	v_cvt_pk_bf16_f32 v14, v10, v11
	v_cvt_pk_bf16_f32 v15, v12, v13
	global_store_dwordx2 v[30:31], v[14:15], off
	s_nop 0
	v_mul_f32_e32 v7, v11, v11
	v_mul_f32_e32 v8, v13, v13
	v_fmac_f32_e32 v7, v10, v10
	v_fmac_f32_e32 v8, v12, v12
	v_add_f32_e32 v7, v7, v8
	v_add_f32_e32 v6, v6, v7
	s_waitcnt vmcnt(9)
	v_mov_b64_e32 v[14:15], v[206:207]
	v_mov_b64_e32 v[16:17], v[208:209]
	v_mov_b64_e32 v[18:19], v[210:211]
	v_mov_b64_e32 v[20:21], v[212:213]
	v_mov_b64_e32 v[22:23], v[214:215]
	v_mov_b64_e32 v[24:25], v[216:217]
	v_mov_b64_e32 v[26:27], v[218:219]
	v_mov_b64_e32 v[28:29], v[220:221]
	v_mov_b64_e32 v[30:31], v[222:223]
	v_mov_b64_e32 v[32:33], v[224:225]
	v_pk_add_f32 v[16:17], v[16:17], v[20:21]
	v_pk_add_f32 v[14:15], v[14:15], v[18:19]
	v_pk_add_f32 v[16:17], v[16:17], v[24:25]
	v_pk_add_f32 v[14:15], v[14:15], v[22:23]
	v_pk_add_f32 v[16:17], v[16:17], v[28:29]
	v_pk_add_f32 v[14:15], v[14:15], v[26:27]
	v_pk_add_f32 v[16:17], v[16:17], v[32:33]
	v_pk_add_f32 v[14:15], v[14:15], v[30:31]
	global_store_dwordx4 v[36:37], v[14:17], off
	v_cvt_pk_bf16_f32 v18, v14, v15
	v_cvt_pk_bf16_f32 v19, v16, v17
	global_store_dwordx2 v[34:35], v[18:19], off
	s_nop 0
	v_mul_f32_e32 v7, v15, v15
	v_mul_f32_e32 v8, v17, v17
	v_fmac_f32_e32 v7, v14, v14
	v_fmac_f32_e32 v8, v16, v16
	v_add_f32_e32 v7, v7, v8
	v_add_f32_e32 v10, v6, v7
	v_mbcnt_hi_u32_b32 v40, -1, v168
	v_lshl_add_u64 v[38:39], s[8:9], 0, v[0:1]
	v_and_b32_e32 v1, 64, v40
	v_xor_b32_e32 v41, 32, v40
	v_add_u32_e32 v43, 64, v1
	v_cmp_lt_i32_e64 s[8:9], v41, v43
	v_xor_b32_e32 v42, 16, v40
	v_xor_b32_e32 v11, 2, v40
	v_cndmask_b32_e64 v1, v40, v41, s[8:9]
	v_lshlrev_b32_e32 v1, 2, v1
	v_cmp_lt_i32_e64 s[8:9], v42, v43
	v_xor_b32_e32 v12, 1, v40
	s_waitcnt vmcnt(6)
; __device__ __forceinline__ unsigned pk2(float lo, float hi) { unsigned r; asm volatile("v_cvt_pk_bf16_f32 %0, %1, %2" : "=v"(r) : "v"(lo), "v"(hi)); return r; }
;     ...
; #pragma unroll
;                 for (int q = 0; q < 4; ++q) v += *(const f32x4*)(part + (size_t)q * 1024 * DM + o);
;                 *(f32x4*)(xf_s + o) = v;
;                 u32x2 w; w.x = pk2(v[0], v[1]); w.y = pk2(v[2], v[3]); *(u32x2*)(xb_s + o) = w;
;                 sq += (v[0] * v[0] + v[1] * v[1]) + (v[2] * v[2] + v[3] * v[3]);
;             }
; #pragma unroll
;             for (int o = 32; o >= 1; o >>= 1) sq += __shfl_xor(sq, o);
;             if (lane < 16) ssq_s[(size_t)row * 16 + lane] = lane == 0 ? sq : 0.f;
	v_mov_b64_e32 v[18:19], v[226:227]
	v_mov_b64_e32 v[20:21], v[228:229]
	v_mov_b64_e32 v[22:23], v[232:233]
	v_mov_b64_e32 v[24:25], v[234:235]
	v_mov_b64_e32 v[26:27], v[236:237]
	v_mov_b64_e32 v[28:29], v[238:239]
	v_mov_b64_e32 v[30:31], v[240:241]
	v_mov_b64_e32 v[32:33], v[242:243]
	v_mov_b64_e32 v[34:35], v[244:245]
	v_mov_b64_e32 v[36:37], v[246:247]
	v_pk_add_f32 v[6:7], v[20:21], v[24:25]
	v_pk_add_f32 v[8:9], v[18:19], v[22:23]
	v_pk_add_f32 v[6:7], v[6:7], v[28:29]
	v_pk_add_f32 v[8:9], v[8:9], v[26:27]
	v_pk_add_f32 v[6:7], v[6:7], v[32:33]
	v_pk_add_f32 v[8:9], v[8:9], v[30:31]
	v_pk_add_f32 v[18:19], v[6:7], v[36:37]
	v_pk_add_f32 v[16:17], v[8:9], v[34:35]
	v_mul_f32_e32 v7, v19, v19
	v_mul_f32_e32 v6, v17, v17
	v_fmac_f32_e32 v6, v16, v16
	v_fmac_f32_e32 v7, v18, v18
	v_add_f32_e32 v6, v6, v7
	v_add_f32_e32 v6, v10, v6
	ds_bpermute_b32 v7, v1, v6
	v_cndmask_b32_e64 v8, v40, v42, s[8:9]
	v_lshlrev_b32_e32 v8, 2, v8
	v_xor_b32_e32 v9, 8, v40
	v_cmp_lt_i32_e64 s[8:9], v9, v43
	s_waitcnt lgkmcnt(0)
	v_add_f32_e32 v6, v6, v7
	ds_bpermute_b32 v7, v8, v6
	v_cndmask_b32_e64 v9, v40, v9, s[8:9]
	v_lshlrev_b32_e32 v9, 2, v9
	v_xor_b32_e32 v10, 4, v40
	v_cmp_lt_i32_e64 s[8:9], v10, v43
	s_waitcnt lgkmcnt(0)
	v_add_f32_e32 v6, v6, v7
	ds_bpermute_b32 v7, v9, v6
	v_cndmask_b32_e64 v10, v40, v10, s[8:9]
	v_lshlrev_b32_e32 v10, 2, v10
	v_cmp_lt_i32_e64 s[8:9], v11, v43
	global_store_dwordx4 v[46:47], v[16:19], off
	s_waitcnt lgkmcnt(0)
	v_add_f32_e32 v6, v6, v7
	ds_bpermute_b32 v7, v10, v6
	v_cndmask_b32_e64 v11, v40, v11, s[8:9]
	v_lshlrev_b32_e32 v11, 2, v11
	v_cmp_lt_i32_e64 s[8:9], v12, v43
	v_cvt_pk_bf16_f32 v16, v16, v17
	s_waitcnt lgkmcnt(0)
	v_add_f32_e32 v13, v6, v7
	ds_bpermute_b32 v14, v11, v13
	v_cndmask_b32_e64 v12, v40, v12, s[8:9]
	v_lshlrev_b32_e32 v12, 2, v12
	v_lshl_add_u64 v[6:7], v[38:39], 0, s[16:17]
	v_cvt_pk_bf16_f32 v17, v18, v19
	s_waitcnt lgkmcnt(0)
	v_add_f32_e32 v13, v13, v14
	ds_bpermute_b32 v14, v12, v13
	global_store_dwordx2 v[4:5], v[16:17], off
	s_and_saveexec_b64 s[8:9], s[6:7]
	s_cbranch_execz .LBB0_2264
	v_lshlrev_b64 v[4:5], 6, v[2:3]
	s_waitcnt lgkmcnt(0)
	v_add_f32_e32 v3, v13, v14
	v_lshl_add_u64 v[4:5], v[6:7], 0, v[4:5]
	v_cndmask_b32_e32 v3, 0, v3, vcc
	global_store_dword v[4:5], v3, off
; __device__ __forceinline__ unsigned pk2(float lo, float hi) { unsigned r; asm volatile("v_cvt_pk_bf16_f32 %0, %1, %2" : "=v"(r) : "v"(lo), "v"(hi)); return r; }
;     ...
;         for (int rr = 0; rr < 2; ++rr) {
;             const int row = rbase + rr; float sq = 0.f;
; #pragma unroll
;             for (int i = 0; i < 4; ++i) {
;                 const size_t o = (size_t)row * DM + i * 256 + lane * 4;
;                 f32x4 v = *(const f32x4*)(xold + o);
; #pragma unroll
;                 for (int q = 0; q < 4; ++q) v += *(const f32x4*)(part + (size_t)q * 1024 * DM + o);
;                 *(f32x4*)(xf_s + o) = v;
;                 u32x2 w; w.x = pk2(v[0], v[1]); w.y = pk2(v[2], v[3]); *(u32x2*)(xb_s + o) = w;
;                 sq += (v[0] * v[0] + v[1] * v[1]) + (v[2] * v[2] + v[3] * v[3]);
;             }
; #pragma unroll
;             for (int o = 32; o >= 1; o >>= 1) sq += __shfl_xor(sq, o);
;             if (lane < 16) ssq_s[(size_t)row * 16 + lane] = lane == 0 ? sq : 0.f;
;         }
.LBB0_2264:
	s_or_b64 exec, exec, s[8:9]
	v_or_b32_e32 v2, 1, v2
	v_ashrrev_i32_e32 v3, 31, v2
	v_lshlrev_b64 v[4:5], 10, v[2:3]
	v_or_b32_e32 v4, v4, v0
	v_lshlrev_b64 v[18:19], 2, v[4:5]
	v_lshl_add_u64 v[46:47], s[10:11], 0, v[18:19]
	v_add_co_u32_e64 v48, s[8:9], s18, v46
	v_lshl_add_u64 v[34:35], s[14:15], 0, v[18:19]
	s_nop 0
	v_addc_co_u32_e64 v49, s[8:9], 0, v47, s[8:9]
	v_add_co_u32_e64 v50, s[8:9], s19, v46
	s_waitcnt lgkmcnt(0)
	global_load_dwordx4 v[14:17], v[34:35], off
	v_addc_co_u32_e64 v51, s[8:9], 0, v47, s[8:9]
	global_load_dwordx4 v[18:21], v[46:47], off
	global_load_dwordx4 v[22:25], v[48:49], off
	v_add_co_u32_e64 v52, s[8:9], s20, v46
	global_load_dwordx4 v[26:29], v[50:51], off
	s_nop 0
	v_addc_co_u32_e64 v53, s[8:9], 0, v47, s[8:9]
	global_load_dwordx4 v[30:33], v[52:53], off
	v_mov_b32_e32 v39, v5
	v_lshl_add_u64 v[36:37], v[4:5], 1, s[12:13]
	v_or_b32_e32 v38, 0x100, v4
	v_lshl_add_u64 v[40:41], v[38:39], 2, s[14:15]
	v_mov_b32_e32 v43, v5
	v_or_b32_e32 v42, 0x200, v4
	v_lshl_add_u64 v[38:39], v[38:39], 1, s[12:13]
	v_lshl_add_u64 v[44:45], v[42:43], 2, s[14:15]
	v_or_b32_e32 v4, 0x300, v4
	v_lshl_add_u64 v[42:43], v[42:43], 1, s[12:13]
	v_lshl_add_u64 v[54:55], v[4:5], 2, s[14:15]
	v_lshl_add_u64 v[4:5], v[4:5], 1, s[12:13]
	global_load_dwordx4 v[186:189], v[40:41], off
	global_load_dwordx4 v[190:193], v[46:47], off offset:1024
	global_load_dwordx4 v[194:197], v[48:49], off offset:1024
	global_load_dwordx4 v[198:201], v[50:51], off offset:1024
	global_load_dwordx4 v[202:205], v[52:53], off offset:1024
	global_load_dwordx4 v[206:209], v[44:45], off
	global_load_dwordx4 v[210:213], v[46:47], off offset:2048
	global_load_dwordx4 v[214:217], v[48:49], off offset:2048
	global_load_dwordx4 v[218:221], v[50:51], off offset:2048
	global_load_dwordx4 v[222:225], v[52:53], off offset:2048
	global_load_dwordx4 v[226:229], v[54:55], off
	global_load_dwordx4 v[232:235], v[46:47], off offset:3072
	global_load_dwordx4 v[236:239], v[48:49], off offset:3072
	global_load_dwordx4 v[240:243], v[50:51], off offset:3072
	global_load_dwordx4 v[244:247], v[52:53], off offset:3072
	s_waitcnt vmcnt(18)
	v_pk_add_f32 v[16:17], v[16:17], v[20:21]
	v_pk_add_f32 v[14:15], v[14:15], v[18:19]
	s_waitcnt vmcnt(17)
	v_pk_add_f32 v[16:17], v[16:17], v[24:25]
	v_pk_add_f32 v[14:15], v[14:15], v[22:23]
	s_waitcnt vmcnt(16)
	v_pk_add_f32 v[16:17], v[16:17], v[28:29]
	v_pk_add_f32 v[14:15], v[14:15], v[26:27]
	s_waitcnt vmcnt(15)
	v_pk_add_f32 v[16:17], v[16:17], v[32:33]
	v_pk_add_f32 v[14:15], v[14:15], v[30:31]
	global_store_dwordx4 v[34:35], v[14:17], off
	v_cvt_pk_bf16_f32 v18, v14, v15
	v_cvt_pk_bf16_f32 v19, v16, v17
	global_store_dwordx2 v[36:37], v[18:19], off
	s_nop 0
	v_mul_f32_e32 v0, v15, v15
	v_mul_f32_e32 v13, v17, v17
	v_fmac_f32_e32 v0, v14, v14
	v_fmac_f32_e32 v13, v16, v16
	v_add_f32_e32 v0, v0, v13
	s_waitcnt vmcnt(12)
	v_mov_b64_e32 v[18:19], v[186:187]
	v_mov_b64_e32 v[20:21], v[188:189]
	v_mov_b64_e32 v[22:23], v[190:191]
	v_mov_b64_e32 v[24:25], v[192:193]
	v_mov_b64_e32 v[26:27], v[194:195]
	v_mov_b64_e32 v[28:29], v[196:197]
	v_mov_b64_e32 v[30:31], v[198:199]
	v_mov_b64_e32 v[32:33], v[200:201]
	v_mov_b64_e32 v[34:35], v[202:203]
	v_mov_b64_e32 v[36:37], v[204:205]
	v_pk_add_f32 v[20:21], v[20:21], v[24:25]
	v_pk_add_f32 v[18:19], v[18:19], v[22:23]
	v_pk_add_f32 v[20:21], v[20:21], v[28:29]
	v_pk_add_f32 v[18:19], v[18:19], v[26:27]
	v_pk_add_f32 v[20:21], v[20:21], v[32:33]
	v_pk_add_f32 v[18:19], v[18:19], v[30:31]
	v_pk_add_f32 v[20:21], v[20:21], v[36:37]
	v_pk_add_f32 v[18:19], v[18:19], v[34:35]
	global_store_dwordx4 v[40:41], v[18:21], off
	v_cvt_pk_bf16_f32 v22, v18, v19
	v_cvt_pk_bf16_f32 v23, v20, v21
	global_store_dwordx2 v[38:39], v[22:23], off
	s_nop 0
	v_mul_f32_e32 v13, v19, v19
	v_mul_f32_e32 v14, v21, v21
	v_fmac_f32_e32 v13, v18, v18
	v_fmac_f32_e32 v14, v20, v20
	v_add_f32_e32 v13, v13, v14
	v_add_f32_e32 v0, v0, v13
	s_waitcnt vmcnt(9)
	v_mov_b64_e32 v[22:23], v[206:207]
	v_mov_b64_e32 v[24:25], v[208:209]
	v_mov_b64_e32 v[26:27], v[210:211]
	v_mov_b64_e32 v[28:29], v[212:213]
	v_mov_b64_e32 v[30:31], v[214:215]
	v_mov_b64_e32 v[32:33], v[216:217]
	v_mov_b64_e32 v[34:35], v[218:219]
	v_mov_b64_e32 v[36:37], v[220:221]
	v_mov_b64_e32 v[38:39], v[222:223]
	v_mov_b64_e32 v[40:41], v[224:225]
	v_pk_add_f32 v[24:25], v[24:25], v[28:29]
	v_pk_add_f32 v[22:23], v[22:23], v[26:27]
	v_pk_add_f32 v[24:25], v[24:25], v[32:33]
	v_pk_add_f32 v[22:23], v[22:23], v[30:31]
	v_pk_add_f32 v[24:25], v[24:25], v[36:37]
	v_pk_add_f32 v[22:23], v[22:23], v[34:35]
	v_pk_add_f32 v[24:25], v[24:25], v[40:41]
	v_pk_add_f32 v[22:23], v[22:23], v[38:39]
	global_store_dwordx4 v[44:45], v[22:25], off
	v_cvt_pk_bf16_f32 v26, v22, v23
	v_cvt_pk_bf16_f32 v27, v24, v25
	global_store_dwordx2 v[42:43], v[26:27], off
	s_nop 0
	v_mul_f32_e32 v13, v23, v23
	v_mul_f32_e32 v14, v25, v25
	v_fmac_f32_e32 v13, v22, v22
	v_fmac_f32_e32 v14, v24, v24
	v_add_f32_e32 v13, v13, v14
	v_add_f32_e32 v0, v0, v13
	s_waitcnt vmcnt(6)
	v_mov_b64_e32 v[26:27], v[226:227]
	v_mov_b64_e32 v[28:29], v[228:229]
	v_mov_b64_e32 v[30:31], v[232:233]
	v_mov_b64_e32 v[32:33], v[234:235]
	v_mov_b64_e32 v[34:35], v[236:237]
	v_mov_b64_e32 v[36:37], v[238:239]
	v_mov_b64_e32 v[38:39], v[240:241]
	v_mov_b64_e32 v[40:41], v[242:243]
	v_mov_b64_e32 v[42:43], v[244:245]
	v_mov_b64_e32 v[44:45], v[246:247]
	v_pk_add_f32 v[14:15], v[28:29], v[32:33]
	v_pk_add_f32 v[16:17], v[26:27], v[30:31]
	v_pk_add_f32 v[14:15], v[14:15], v[36:37]
	v_pk_add_f32 v[16:17], v[16:17], v[34:35]
	v_pk_add_f32 v[14:15], v[14:15], v[40:41]
	v_pk_add_f32 v[18:19], v[16:17], v[38:39]
	v_pk_add_f32 v[16:17], v[14:15], v[44:45]
	v_pk_add_f32 v[14:15], v[18:19], v[42:43]
	v_mul_f32_e32 v18, v17, v17
	v_mul_f32_e32 v13, v15, v15
	v_fmac_f32_e32 v13, v14, v14
	v_fmac_f32_e32 v18, v16, v16
	v_add_f32_e32 v13, v13, v18
	v_add_f32_e32 v0, v0, v13
	ds_bpermute_b32 v1, v1, v0
	global_store_dwordx4 v[54:55], v[14:17], off
	s_waitcnt lgkmcnt(0)
	v_add_f32_e32 v0, v0, v1
	ds_bpermute_b32 v1, v8, v0
	v_cvt_pk_bf16_f32 v8, v14, v15
	s_waitcnt lgkmcnt(0)
	v_add_f32_e32 v0, v0, v1
	ds_bpermute_b32 v1, v9, v0
	v_cvt_pk_bf16_f32 v9, v16, v17
	global_store_dwordx2 v[4:5], v[8:9], off
	s_waitcnt lgkmcnt(0)
	v_add_f32_e32 v0, v0, v1
	ds_bpermute_b32 v1, v10, v0
	s_waitcnt lgkmcnt(0)
	v_add_f32_e32 v0, v0, v1
	ds_bpermute_b32 v1, v11, v0
	s_waitcnt lgkmcnt(0)
	v_add_f32_e32 v0, v0, v1
	ds_bpermute_b32 v1, v12, v0
	s_and_saveexec_b64 s[8:9], s[6:7]
	s_cbranch_execz .LBB0_2266
	v_lshlrev_b64 v[2:3], 6, v[2:3]
	s_waitcnt lgkmcnt(0)
	v_add_f32_e32 v0, v0, v1
	v_lshl_add_u64 v[2:3], v[6:7], 0, v[2:3]
	v_cndmask_b32_e32 v0, 0, v0, vcc
	global_store_dword v[2:3], v0, off
